# hyena order-1 epilogue: first channel's 32 results kept packed in 16 registers, second channel pass stores both adjacent channels as one dword per position (half as many scattered y_b store pieces)
# speedup vs baseline: 1.1574x; 1.0180x over previous
.LBB0_536:
	s_nop 1
	v_lshlrev_b32_e32 v0, 2, v146
	s_add_i32 s47, 16, 0x10000
	v_add_u32_e32 v64, 16, v0
	v_add_u32_e32 v65, s47, v0
	s_waitcnt lgkmcnt(0)
	s_barrier
	ds_read2st64_b32 v[2:3], v64 offset1:8
	ds_read2st64_b32 v[4:5], v65 offset1:8
	ds_read2st64_b32 v[8:9], v64 offset0:16 offset1:24
	ds_read2st64_b32 v[10:11], v65 offset0:16 offset1:24
	ds_read2st64_b32 v[12:13], v64 offset0:32 offset1:40
	ds_read2st64_b32 v[14:15], v65 offset0:32 offset1:40
	s_mov_b32 s49, s40
	s_waitcnt lgkmcnt(5)
	v_mov_b32_e32 v6, v2
	s_waitcnt lgkmcnt(4)
	v_mov_b32_e32 v7, v4
	v_mov_b32_e32 v4, v3
	s_waitcnt lgkmcnt(3)
	v_mov_b32_e32 v2, v8
	s_waitcnt lgkmcnt(2)
	v_mov_b32_e32 v3, v10
	v_mov_b32_e32 v10, v9
	ds_read2st64_b32 v[8:9], v64 offset0:48 offset1:56
	ds_read2st64_b32 v[16:17], v65 offset0:48 offset1:56
	s_waitcnt lgkmcnt(3)
	v_mov_b32_e32 v18, v12
	s_waitcnt lgkmcnt(2)
	v_mov_b32_e32 v19, v14
	v_mov_b32_e32 v14, v13
	s_waitcnt lgkmcnt(1)
	v_mov_b32_e32 v12, v8
	s_waitcnt lgkmcnt(0)
	v_mov_b32_e32 v13, v16
	ds_read2st64_b32 v[20:21], v64 offset0:64 offset1:72
	ds_read2st64_b32 v[22:23], v65 offset0:64 offset1:72
	v_mov_b32_e32 v16, v9
	ds_read2st64_b32 v[8:9], v64 offset0:80 offset1:88
	ds_read2st64_b32 v[24:25], v65 offset0:80 offset1:88
	s_mov_b32 s41, s45
	s_waitcnt lgkmcnt(3)
	v_mov_b32_e32 v26, v20
	s_waitcnt lgkmcnt(2)
	v_mov_b32_e32 v27, v22
	v_mov_b32_e32 v22, v21
	s_waitcnt lgkmcnt(1)
	v_mov_b32_e32 v28, v8
	s_waitcnt lgkmcnt(0)
	v_mov_b32_e32 v29, v24
	ds_read2st64_b32 v[20:21], v64 offset0:96 offset1:104
	ds_read2st64_b32 v[30:31], v65 offset0:96 offset1:104
	v_mov_b32_e32 v24, v9
	ds_read2st64_b32 v[8:9], v64 offset0:112 offset1:120
	ds_read2st64_b32 v[32:33], v65 offset0:112 offset1:120
	v_and_b32_e32 v196, 63, v146
	v_lshlrev_b32_e32 v196, 2, v196
	v_and_b32_e32 v0, 0xffffffc0, v146
	v_lshl_add_u32 v0, v0, 5, v196
	v_add_u32_e32 v0, 0x400, v0
	s_waitcnt lgkmcnt(3)
	v_mov_b32_e32 v34, v20
	s_waitcnt lgkmcnt(2)
	v_mov_b32_e32 v35, v30
	v_mov_b32_e32 v30, v21
	s_waitcnt lgkmcnt(1)
	v_mov_b32_e32 v36, v8
	s_waitcnt lgkmcnt(0)
	v_mov_b32_e32 v37, v32
	ds_read2st64_b32 v[20:21], v64 offset0:128 offset1:136
	ds_read2st64_b32 v[38:39], v65 offset0:128 offset1:136
	v_mov_b32_e32 v32, v9
	ds_read2st64_b32 v[8:9], v64 offset0:144 offset1:152
	ds_read2st64_b32 v[40:41], v65 offset0:144 offset1:152
	v_readlane_b32 s0, v252, 48
	s_waitcnt lgkmcnt(3)
	v_mov_b32_e32 v42, v20
	s_waitcnt lgkmcnt(2)
	v_mov_b32_e32 v43, v38
	v_mov_b32_e32 v38, v21
	s_waitcnt lgkmcnt(1)
	v_mov_b32_e32 v44, v8
	s_waitcnt lgkmcnt(0)
	v_mov_b32_e32 v45, v40
	ds_read2st64_b32 v[20:21], v64 offset0:160 offset1:168
	ds_read2st64_b32 v[46:47], v65 offset0:160 offset1:168
	v_mov_b32_e32 v40, v9
	ds_read2st64_b32 v[8:9], v64 offset0:176 offset1:184
	ds_read2st64_b32 v[48:49], v65 offset0:176 offset1:184
	v_ashrrev_i32_e32 v1, 31, v0
	s_waitcnt lgkmcnt(3)
	v_mov_b32_e32 v50, v20
	s_waitcnt lgkmcnt(2)
	v_mov_b32_e32 v51, v46
	v_mov_b32_e32 v46, v21
	s_waitcnt lgkmcnt(1)
	v_mov_b32_e32 v52, v8
	s_waitcnt lgkmcnt(0)
	v_mov_b32_e32 v53, v48
	ds_read2st64_b32 v[20:21], v64 offset0:192 offset1:200
	ds_read2st64_b32 v[54:55], v65 offset0:192 offset1:200
	v_mov_b32_e32 v48, v9
	ds_read2st64_b32 v[8:9], v64 offset0:208 offset1:216
	ds_read2st64_b32 v[56:57], v65 offset0:208 offset1:216
	v_readlane_b32 s1, v252, 49
	s_waitcnt lgkmcnt(3)
	v_mov_b32_e32 v58, v20
	s_waitcnt lgkmcnt(2)
	v_mov_b32_e32 v59, v54
	v_mov_b32_e32 v54, v21
	s_waitcnt lgkmcnt(1)
	v_mov_b32_e32 v60, v8
	s_waitcnt lgkmcnt(0)
	v_mov_b32_e32 v61, v56
	ds_read2st64_b32 v[20:21], v64 offset0:224 offset1:232
	ds_read2st64_b32 v[62:63], v65 offset0:224 offset1:232
	v_mov_b32_e32 v56, v9
	ds_read2st64_b32 v[8:9], v64 offset0:240 offset1:248
	ds_read2st64_b32 v[64:65], v65 offset0:240 offset1:248
	s_waitcnt lgkmcnt(0)
	v_mov_b32_e32 v66, v20
	v_mov_b32_e32 v67, v62
	v_mov_b32_e32 v72, v8
	v_mov_b32_e32 v73, v64
	v_mov_b32_e32 v64, v9
	v_pk_add_f32 v[8:9], v[6:7], v[42:43]
	v_pk_add_f32 v[6:7], v[6:7], v[42:43] neg_lo:[0,1] neg_hi:[0,1]
	v_pk_add_f32 v[42:43], v[4:5], v[38:39]
	v_pk_add_f32 v[4:5], v[4:5], v[38:39] neg_lo:[0,1] neg_hi:[0,1]
	v_mov_b32_e32 v62, v21
	v_pk_mul_f32 v[38:39], v[4:5], s[58:59] op_sel:[1,0] op_sel_hi:[0,0] neg_hi:[1,0]
	v_mov_b32_e32 v21, v146
	v_pk_fma_f32 v[4:5], v[4:5], s[46:47], v[38:39] op_sel_hi:[1,0,1]
	v_pk_add_f32 v[38:39], v[2:3], v[44:45]
	v_pk_add_f32 v[2:3], v[2:3], v[44:45] neg_lo:[0,1] neg_hi:[0,1]
	s_barrier
	s_nop 0
	s_nop 0
	v_pk_mul_f32 v[44:45], v[2:3], s[62:63] op_sel:[1,0] op_sel_hi:[0,0] neg_hi:[1,0]
	s_nop 0
	v_pk_fma_f32 v[2:3], v[2:3], s[60:61], v[44:45] op_sel_hi:[1,0,1]
	v_pk_add_f32 v[44:45], v[10:11], v[40:41]
	v_pk_add_f32 v[10:11], v[10:11], v[40:41] neg_lo:[0,1] neg_hi:[0,1]
	s_lshl_b64 s[10:11], s[68:69], 2
	s_nop 0
	s_nop 0
	v_pk_mul_f32 v[40:41], v[10:11], s[66:67] op_sel:[1,0] op_sel_hi:[0,0] neg_hi:[1,0]
	s_add_u32 s90, s54, s10
	v_pk_fma_f32 v[10:11], v[10:11], s[64:65], v[40:41] op_sel_hi:[1,0,1]
	v_pk_add_f32 v[40:41], v[18:19], v[50:51]
	v_pk_add_f32 v[18:19], v[18:19], v[50:51] neg_lo:[0,1] neg_hi:[0,1]
	s_addc_u32 s91, s55, s11
	s_nop 0
	s_nop 0
	v_pk_mul_f32 v[50:51], v[18:19], s[70:71] op_sel:[1,0] op_sel_hi:[0,0] neg_hi:[1,0]
	v_add_u32_e32 v70, 0x200, v146
	v_pk_fma_f32 v[18:19], v[18:19], s[70:71], v[50:51] op_sel_hi:[1,0,1]
	v_pk_add_f32 v[50:51], v[14:15], v[46:47]
	v_pk_add_f32 v[14:15], v[14:15], v[46:47] neg_lo:[0,1] neg_hi:[0,1]
	v_ashrrev_i32_e32 v147, 31, v146
	s_nop 0
	s_nop 0
	v_pk_mul_f32 v[46:47], v[14:15], s[64:65] op_sel:[1,0] op_sel_hi:[0,0] neg_hi:[1,0]
	v_add_u32_e32 v69, 0x400, v146
	v_pk_fma_f32 v[14:15], v[14:15], s[66:67], v[46:47] op_sel_hi:[1,0,1]
	v_pk_add_f32 v[46:47], v[12:13], v[52:53]
	v_pk_add_f32 v[12:13], v[12:13], v[52:53] neg_lo:[0,1] neg_hi:[0,1]
	v_add_u32_e32 v68, 0x600, v146
	v_pk_mul_f32 v[52:53], v[12:13], s[60:61] op_sel:[1,0] op_sel_hi:[0,0] neg_hi:[1,0]
	s_mov_b32 s16, 0
	v_pk_fma_f32 v[12:13], v[12:13], s[62:63], v[52:53] op_sel_hi:[1,0,1]
	v_pk_add_f32 v[52:53], v[16:17], v[48:49]
	v_pk_add_f32 v[16:17], v[16:17], v[48:49] neg_lo:[0,1] neg_hi:[0,1]
	s_nop 0
	v_pk_mul_f32 v[48:49], v[16:17], s[46:47] op_sel:[1,0] op_sel_hi:[0,0] neg_hi:[1,0]
	s_nop 0
	v_pk_fma_f32 v[16:17], v[16:17], s[58:59], v[48:49] op_sel_hi:[1,0,1]
	v_pk_add_f32 v[48:49], v[26:27], v[58:59]
	v_pk_add_f32 v[26:27], v[26:27], v[58:59] neg_lo:[0,1] neg_hi:[0,1]
	s_nop 0
	v_xor_b32_e32 v59, 0x80000000, v26
	v_mov_b32_e32 v58, v27
	v_pk_add_f32 v[26:27], v[22:23], v[54:55]
	v_pk_add_f32 v[22:23], v[22:23], v[54:55] neg_lo:[0,1] neg_hi:[0,1]
	s_nop 0
	v_pk_mul_f32 v[54:55], v[22:23], s[58:59] op_sel_hi:[1,0]
	v_xor_b32_e32 v75, 0x80000000, v22
	v_mov_b32_e32 v74, v23
	v_pk_fma_f32 v[22:23], v[74:75], s[46:47], v[54:55] op_sel_hi:[1,0,1] neg_lo:[0,0,1] neg_hi:[0,0,1]
	v_pk_add_f32 v[54:55], v[28:29], v[60:61]
	v_pk_add_f32 v[28:29], v[28:29], v[60:61] neg_lo:[0,1] neg_hi:[0,1]
	s_nop 0
	v_pk_mul_f32 v[60:61], v[28:29], s[62:63] op_sel_hi:[1,0]
	v_xor_b32_e32 v75, 0x80000000, v28
	v_mov_b32_e32 v74, v29
	v_pk_fma_f32 v[28:29], v[74:75], s[60:61], v[60:61] op_sel_hi:[1,0,1] neg_lo:[0,0,1] neg_hi:[0,0,1]
	v_pk_add_f32 v[60:61], v[24:25], v[56:57]
	v_pk_add_f32 v[24:25], v[24:25], v[56:57] neg_lo:[0,1] neg_hi:[0,1]
	s_nop 0
	v_pk_mul_f32 v[56:57], v[24:25], s[66:67] op_sel_hi:[1,0]
	v_xor_b32_e32 v75, 0x80000000, v24
	v_mov_b32_e32 v74, v25
	v_pk_fma_f32 v[24:25], v[74:75], s[64:65], v[56:57] op_sel_hi:[1,0,1] neg_lo:[0,0,1] neg_hi:[0,0,1]
	v_pk_add_f32 v[56:57], v[34:35], v[66:67]
	v_pk_add_f32 v[34:35], v[34:35], v[66:67] neg_lo:[0,1] neg_hi:[0,1]
	s_nop 0
	v_pk_mul_f32 v[66:67], v[34:35], s[70:71] op_sel_hi:[1,0]
	v_xor_b32_e32 v75, 0x80000000, v34
	v_mov_b32_e32 v74, v35
	v_pk_fma_f32 v[34:35], v[74:75], s[70:71], v[66:67] op_sel_hi:[1,0,1] neg_lo:[0,0,1] neg_hi:[0,0,1]
	v_pk_add_f32 v[66:67], v[30:31], v[62:63]
	v_pk_add_f32 v[30:31], v[30:31], v[62:63] neg_lo:[0,1] neg_hi:[0,1]
	s_nop 0
	v_pk_mul_f32 v[62:63], v[30:31], s[64:65] op_sel_hi:[1,0]
	v_xor_b32_e32 v75, 0x80000000, v30
	v_mov_b32_e32 v74, v31
	v_pk_fma_f32 v[30:31], v[74:75], s[66:67], v[62:63] op_sel_hi:[1,0,1] neg_lo:[0,0,1] neg_hi:[0,0,1]
	v_pk_add_f32 v[62:63], v[36:37], v[72:73]
	v_pk_add_f32 v[36:37], v[36:37], v[72:73] neg_lo:[0,1] neg_hi:[0,1]
	s_nop 0
	v_pk_mul_f32 v[72:73], v[36:37], s[60:61] op_sel_hi:[1,0]
	v_xor_b32_e32 v75, 0x80000000, v36
	v_mov_b32_e32 v74, v37
	v_pk_fma_f32 v[36:37], v[74:75], s[62:63], v[72:73] op_sel_hi:[1,0,1] neg_lo:[0,0,1] neg_hi:[0,0,1]
	v_pk_add_f32 v[72:73], v[32:33], v[64:65]
	v_pk_add_f32 v[32:33], v[32:33], v[64:65] neg_lo:[0,1] neg_hi:[0,1]
	s_nop 0
	v_pk_mul_f32 v[64:65], v[32:33], s[46:47] op_sel_hi:[1,0]
	v_xor_b32_e32 v75, 0x80000000, v32
	v_mov_b32_e32 v74, v33
	v_pk_fma_f32 v[32:33], v[74:75], s[58:59], v[64:65] op_sel_hi:[1,0,1] neg_lo:[0,0,1] neg_hi:[0,0,1]
	v_pk_add_f32 v[64:65], v[8:9], v[48:49]
	v_pk_add_f32 v[8:9], v[8:9], v[48:49] neg_lo:[0,1] neg_hi:[0,1]
	v_pk_add_f32 v[48:49], v[42:43], v[26:27]
	v_pk_add_f32 v[26:27], v[42:43], v[26:27] neg_lo:[0,1] neg_hi:[0,1]
	s_nop 0
	v_pk_mul_f32 v[42:43], v[26:27], s[62:63] op_sel:[1,0] op_sel_hi:[0,0] neg_hi:[1,0]
	s_nop 0
	v_pk_fma_f32 v[26:27], v[26:27], s[60:61], v[42:43] op_sel_hi:[1,0,1]
	v_pk_add_f32 v[42:43], v[38:39], v[54:55]
	v_pk_add_f32 v[38:39], v[38:39], v[54:55] neg_lo:[0,1] neg_hi:[0,1]
	s_nop 0
	v_pk_mul_f32 v[54:55], v[38:39], s[70:71] op_sel:[1,0] op_sel_hi:[0,0] neg_hi:[1,0]
	s_nop 0
	v_pk_fma_f32 v[38:39], v[38:39], s[70:71], v[54:55] op_sel_hi:[1,0,1]
	v_pk_add_f32 v[54:55], v[44:45], v[60:61]
	v_pk_add_f32 v[44:45], v[44:45], v[60:61] neg_lo:[0,1] neg_hi:[0,1]
	s_nop 0
	v_pk_mul_f32 v[60:61], v[44:45], s[60:61] op_sel:[1,0] op_sel_hi:[0,0] neg_hi:[1,0]
	s_nop 0
	v_pk_fma_f32 v[44:45], v[44:45], s[62:63], v[60:61] op_sel_hi:[1,0,1]
	v_pk_add_f32 v[60:61], v[40:41], v[56:57]
	v_pk_add_f32 v[40:41], v[40:41], v[56:57] neg_lo:[0,1] neg_hi:[0,1]
	s_nop 0
	v_xor_b32_e32 v57, 0x80000000, v40
	v_mov_b32_e32 v56, v41
	v_pk_add_f32 v[40:41], v[50:51], v[66:67]
	v_pk_add_f32 v[50:51], v[50:51], v[66:67] neg_lo:[0,1] neg_hi:[0,1]
	s_nop 0
	v_pk_mul_f32 v[66:67], v[50:51], s[62:63] op_sel_hi:[1,0]
	v_xor_b32_e32 v75, 0x80000000, v50
	v_mov_b32_e32 v74, v51
	v_pk_fma_f32 v[50:51], v[74:75], s[60:61], v[66:67] op_sel_hi:[1,0,1] neg_lo:[0,0,1] neg_hi:[0,0,1]
	v_pk_add_f32 v[66:67], v[46:47], v[62:63]
	v_pk_add_f32 v[46:47], v[46:47], v[62:63] neg_lo:[0,1] neg_hi:[0,1]
	s_nop 0
	v_pk_mul_f32 v[62:63], v[46:47], s[70:71] op_sel_hi:[1,0]
	v_xor_b32_e32 v75, 0x80000000, v46
	v_mov_b32_e32 v74, v47
	v_pk_fma_f32 v[46:47], v[74:75], s[70:71], v[62:63] op_sel_hi:[1,0,1] neg_lo:[0,0,1] neg_hi:[0,0,1]
	v_pk_add_f32 v[62:63], v[52:53], v[72:73]
	v_pk_add_f32 v[52:53], v[52:53], v[72:73] neg_lo:[0,1] neg_hi:[0,1]
	s_nop 0
	v_pk_mul_f32 v[72:73], v[52:53], s[60:61] op_sel_hi:[1,0]
	v_xor_b32_e32 v75, 0x80000000, v52
	v_mov_b32_e32 v74, v53
	v_pk_fma_f32 v[52:53], v[74:75], s[62:63], v[72:73] op_sel_hi:[1,0,1] neg_lo:[0,0,1] neg_hi:[0,0,1]
	v_pk_add_f32 v[72:73], v[6:7], v[58:59]
	v_pk_add_f32 v[6:7], v[6:7], v[58:59] neg_lo:[0,1] neg_hi:[0,1]
	v_pk_add_f32 v[58:59], v[4:5], v[22:23]
	v_pk_add_f32 v[4:5], v[4:5], v[22:23] neg_lo:[0,1] neg_hi:[0,1]
	s_nop 0
	v_pk_mul_f32 v[22:23], v[4:5], s[62:63] op_sel:[1,0] op_sel_hi:[0,0] neg_hi:[1,0]
	s_nop 0
	v_pk_fma_f32 v[4:5], v[4:5], s[60:61], v[22:23] op_sel_hi:[1,0,1]
	v_pk_add_f32 v[22:23], v[2:3], v[28:29]
	v_pk_add_f32 v[2:3], v[2:3], v[28:29] neg_lo:[0,1] neg_hi:[0,1]
	s_nop 0
	v_pk_mul_f32 v[28:29], v[2:3], s[70:71] op_sel:[1,0] op_sel_hi:[0,0] neg_hi:[1,0]
	s_nop 0
	v_pk_fma_f32 v[2:3], v[2:3], s[70:71], v[28:29] op_sel_hi:[1,0,1]
	v_pk_add_f32 v[28:29], v[10:11], v[24:25]
	v_pk_add_f32 v[10:11], v[10:11], v[24:25] neg_lo:[0,1] neg_hi:[0,1]
	s_nop 0
	v_pk_mul_f32 v[24:25], v[10:11], s[60:61] op_sel:[1,0] op_sel_hi:[0,0] neg_hi:[1,0]
	s_nop 0
	v_pk_fma_f32 v[10:11], v[10:11], s[62:63], v[24:25] op_sel_hi:[1,0,1]
	v_pk_add_f32 v[24:25], v[18:19], v[34:35]
	v_pk_add_f32 v[18:19], v[18:19], v[34:35] neg_lo:[0,1] neg_hi:[0,1]
	s_nop 0
	v_xor_b32_e32 v35, 0x80000000, v18
	v_mov_b32_e32 v34, v19
	v_pk_add_f32 v[18:19], v[14:15], v[30:31]
	v_pk_add_f32 v[14:15], v[14:15], v[30:31] neg_lo:[0,1] neg_hi:[0,1]
	s_nop 0
	v_pk_mul_f32 v[30:31], v[14:15], s[62:63] op_sel_hi:[1,0]
	v_xor_b32_e32 v75, 0x80000000, v14
	v_mov_b32_e32 v74, v15
	v_pk_fma_f32 v[14:15], v[74:75], s[60:61], v[30:31] op_sel_hi:[1,0,1] neg_lo:[0,0,1] neg_hi:[0,0,1]
	v_pk_add_f32 v[30:31], v[12:13], v[36:37]
	v_pk_add_f32 v[12:13], v[12:13], v[36:37] neg_lo:[0,1] neg_hi:[0,1]
	s_nop 0
	v_pk_mul_f32 v[36:37], v[12:13], s[70:71] op_sel_hi:[1,0]
	v_xor_b32_e32 v75, 0x80000000, v12
	v_mov_b32_e32 v74, v13
	v_pk_fma_f32 v[12:13], v[74:75], s[70:71], v[36:37] op_sel_hi:[1,0,1] neg_lo:[0,0,1] neg_hi:[0,0,1]
	v_pk_add_f32 v[36:37], v[16:17], v[32:33]
	v_pk_add_f32 v[16:17], v[16:17], v[32:33] neg_lo:[0,1] neg_hi:[0,1]
	s_nop 0
	v_pk_mul_f32 v[32:33], v[16:17], s[60:61] op_sel_hi:[1,0]
	v_xor_b32_e32 v75, 0x80000000, v16
	v_mov_b32_e32 v74, v17
	v_pk_fma_f32 v[16:17], v[74:75], s[62:63], v[32:33] op_sel_hi:[1,0,1] neg_lo:[0,0,1] neg_hi:[0,0,1]
	v_pk_add_f32 v[32:33], v[64:65], v[60:61]
	v_pk_add_f32 v[60:61], v[64:65], v[60:61] neg_lo:[0,1] neg_hi:[0,1]
	v_pk_add_f32 v[64:65], v[48:49], v[40:41]
	v_pk_add_f32 v[40:41], v[48:49], v[40:41] neg_lo:[0,1] neg_hi:[0,1]
	s_nop 0
	v_pk_mul_f32 v[48:49], v[40:41], s[70:71] op_sel:[1,0] op_sel_hi:[0,0] neg_hi:[1,0]
	s_nop 0
	v_pk_fma_f32 v[40:41], v[40:41], s[70:71], v[48:49] op_sel_hi:[1,0,1]
	v_pk_add_f32 v[48:49], v[42:43], v[66:67]
	v_pk_add_f32 v[42:43], v[42:43], v[66:67] neg_lo:[0,1] neg_hi:[0,1]
	s_nop 0
	v_xor_b32_e32 v67, 0x80000000, v42
	v_mov_b32_e32 v66, v43
	v_pk_add_f32 v[42:43], v[54:55], v[62:63]
	v_pk_add_f32 v[54:55], v[54:55], v[62:63] neg_lo:[0,1] neg_hi:[0,1]
	s_nop 0
	v_pk_mul_f32 v[62:63], v[54:55], s[70:71] op_sel_hi:[1,0]
	v_xor_b32_e32 v75, 0x80000000, v54
	v_mov_b32_e32 v74, v55
	v_pk_fma_f32 v[54:55], v[74:75], s[70:71], v[62:63] op_sel_hi:[1,0,1] neg_lo:[0,0,1] neg_hi:[0,0,1]
	v_pk_add_f32 v[62:63], v[8:9], v[56:57]
	v_pk_add_f32 v[8:9], v[8:9], v[56:57] neg_lo:[0,1] neg_hi:[0,1]
	v_pk_add_f32 v[56:57], v[26:27], v[50:51]
	v_pk_add_f32 v[26:27], v[26:27], v[50:51] neg_lo:[0,1] neg_hi:[0,1]
	s_nop 0
	v_pk_mul_f32 v[50:51], v[26:27], s[70:71] op_sel:[1,0] op_sel_hi:[0,0] neg_hi:[1,0]
	s_nop 0
	v_pk_fma_f32 v[26:27], v[26:27], s[70:71], v[50:51] op_sel_hi:[1,0,1]
	v_pk_add_f32 v[50:51], v[38:39], v[46:47]
	v_pk_add_f32 v[38:39], v[38:39], v[46:47] neg_lo:[0,1] neg_hi:[0,1]
	s_nop 0
	v_xor_b32_e32 v47, 0x80000000, v38
	v_mov_b32_e32 v46, v39
	v_pk_add_f32 v[38:39], v[44:45], v[52:53]
	v_pk_add_f32 v[44:45], v[44:45], v[52:53] neg_lo:[0,1] neg_hi:[0,1]
	s_nop 0
	v_pk_mul_f32 v[52:53], v[44:45], s[70:71] op_sel_hi:[1,0]
	v_xor_b32_e32 v75, 0x80000000, v44
	v_mov_b32_e32 v74, v45
	v_pk_fma_f32 v[44:45], v[74:75], s[70:71], v[52:53] op_sel_hi:[1,0,1] neg_lo:[0,0,1] neg_hi:[0,0,1]
	v_pk_add_f32 v[52:53], v[72:73], v[24:25]
	v_pk_add_f32 v[24:25], v[72:73], v[24:25] neg_lo:[0,1] neg_hi:[0,1]
	v_pk_add_f32 v[72:73], v[58:59], v[18:19]
	v_pk_add_f32 v[18:19], v[58:59], v[18:19] neg_lo:[0,1] neg_hi:[0,1]
	s_nop 0
	v_pk_mul_f32 v[58:59], v[18:19], s[70:71] op_sel:[1,0] op_sel_hi:[0,0] neg_hi:[1,0]
	s_nop 0
	v_pk_fma_f32 v[18:19], v[18:19], s[70:71], v[58:59] op_sel_hi:[1,0,1]
	v_pk_add_f32 v[58:59], v[22:23], v[30:31]
	v_pk_add_f32 v[22:23], v[22:23], v[30:31] neg_lo:[0,1] neg_hi:[0,1]
	s_nop 0
	v_xor_b32_e32 v31, 0x80000000, v22
	v_mov_b32_e32 v30, v23
	v_pk_add_f32 v[22:23], v[28:29], v[36:37]
	v_pk_add_f32 v[28:29], v[28:29], v[36:37] neg_lo:[0,1] neg_hi:[0,1]
	v_pk_add_f32 v[76:77], v[24:25], v[30:31]
	v_pk_mul_f32 v[36:37], v[28:29], s[70:71] op_sel_hi:[1,0]
	v_xor_b32_e32 v75, 0x80000000, v28
	v_mov_b32_e32 v74, v29
	v_pk_fma_f32 v[28:29], v[74:75], s[70:71], v[36:37] op_sel_hi:[1,0,1] neg_lo:[0,0,1] neg_hi:[0,0,1]
	v_pk_add_f32 v[36:37], v[6:7], v[34:35]
	v_pk_add_f32 v[6:7], v[6:7], v[34:35] neg_lo:[0,1] neg_hi:[0,1]
	v_pk_add_f32 v[34:35], v[4:5], v[14:15]
	v_pk_add_f32 v[4:5], v[4:5], v[14:15] neg_lo:[0,1] neg_hi:[0,1]
	v_pk_add_f32 v[78:79], v[18:19], v[28:29]
	v_pk_mul_f32 v[14:15], v[4:5], s[70:71] op_sel:[1,0] op_sel_hi:[0,0] neg_hi:[1,0]
	v_pk_add_f32 v[18:19], v[18:19], v[28:29] neg_lo:[0,1] neg_hi:[0,1]
	v_pk_fma_f32 v[4:5], v[4:5], s[70:71], v[14:15] op_sel_hi:[1,0,1]
	v_pk_add_f32 v[14:15], v[2:3], v[12:13]
	v_pk_add_f32 v[2:3], v[2:3], v[12:13] neg_lo:[0,1] neg_hi:[0,1]
	v_xor_b32_e32 v81, 0x80000000, v18
	v_xor_b32_e32 v13, 0x80000000, v2
	v_mov_b32_e32 v12, v3
	v_pk_add_f32 v[2:3], v[10:11], v[16:17]
	v_pk_add_f32 v[10:11], v[10:11], v[16:17] neg_lo:[0,1] neg_hi:[0,1]
	v_mov_b32_e32 v80, v19
	v_pk_mul_f32 v[16:17], v[10:11], s[70:71] op_sel_hi:[1,0]
	s_nop 0
	v_pk_fma_f32 v[10:11], v[10:11], s[70:71], v[16:17] op_sel:[1,0,0] op_sel_hi:[0,0,1] neg_lo:[0,0,1] neg_hi:[1,0,1]
	v_pk_add_f32 v[74:75], v[62:63], v[50:51]
	v_pk_add_f32 v[50:51], v[62:63], v[50:51] neg_lo:[0,1] neg_hi:[0,1]
	v_pk_add_f32 v[62:63], v[56:57], v[38:39]
	v_pk_add_f32 v[38:39], v[56:57], v[38:39] neg_lo:[0,1] neg_hi:[0,1]
	v_pk_add_f32 v[16:17], v[32:33], v[48:49]
	v_pk_add_f32 v[32:33], v[32:33], v[48:49] neg_lo:[0,1] neg_hi:[0,1]
	v_pk_add_f32 v[48:49], v[64:65], v[42:43]
	v_pk_add_f32 v[42:43], v[64:65], v[42:43] neg_lo:[0,1] neg_hi:[0,1]
	v_xor_b32_e32 v57, 0x80000000, v38
	v_mov_b32_e32 v56, v39
	v_pk_add_f32 v[38:39], v[8:9], v[46:47]
	v_pk_add_f32 v[8:9], v[8:9], v[46:47] neg_lo:[0,1] neg_hi:[0,1]
	v_pk_add_f32 v[46:47], v[26:27], v[44:45]
	v_pk_add_f32 v[26:27], v[26:27], v[44:45] neg_lo:[0,1] neg_hi:[0,1]
	v_xor_b32_e32 v65, 0x80000000, v42
	v_mov_b32_e32 v64, v43
	v_pk_add_f32 v[42:43], v[60:61], v[66:67]
	v_pk_add_f32 v[60:61], v[60:61], v[66:67] neg_lo:[0,1] neg_hi:[0,1]
	v_pk_add_f32 v[66:67], v[40:41], v[54:55]
	v_pk_add_f32 v[40:41], v[40:41], v[54:55] neg_lo:[0,1] neg_hi:[0,1]
	v_xor_b32_e32 v45, 0x80000000, v26
	v_mov_b32_e32 v44, v27
	v_pk_add_f32 v[26:27], v[52:53], v[58:59]
	v_pk_add_f32 v[52:53], v[52:53], v[58:59] neg_lo:[0,1] neg_hi:[0,1]
	v_pk_add_f32 v[58:59], v[72:73], v[22:23]
	v_pk_add_f32 v[22:23], v[72:73], v[22:23] neg_lo:[0,1] neg_hi:[0,1]
	v_pk_add_f32 v[18:19], v[36:37], v[14:15]
	v_pk_add_f32 v[14:15], v[36:37], v[14:15] neg_lo:[0,1] neg_hi:[0,1]
	v_pk_add_f32 v[36:37], v[34:35], v[2:3]
	v_pk_add_f32 v[2:3], v[34:35], v[2:3] neg_lo:[0,1] neg_hi:[0,1]
	v_xor_b32_e32 v73, 0x80000000, v22
	v_mov_b32_e32 v72, v23
	v_xor_b32_e32 v35, 0x80000000, v2
	v_mov_b32_e32 v34, v3
	v_pk_add_f32 v[2:3], v[4:5], v[10:11] neg_lo:[0,1] neg_hi:[0,1]
	v_pk_add_f32 v[24:25], v[24:25], v[30:31] neg_lo:[0,1] neg_hi:[0,1]
	v_pk_add_f32 v[82:83], v[6:7], v[12:13]
	v_pk_add_f32 v[12:13], v[6:7], v[12:13] neg_lo:[0,1] neg_hi:[0,1]
	v_xor_b32_e32 v87, 0x80000000, v2
	v_mov_b32_e32 v86, v3
	v_pk_add_f32 v[2:3], v[16:17], v[48:49]
	v_pk_add_f32 v[88:89], v[16:17], v[48:49] neg_lo:[0,1] neg_hi:[0,1]
	v_pk_add_f32 v[48:49], v[32:33], v[64:65]
	v_pk_add_f32 v[28:29], v[32:33], v[64:65] neg_lo:[0,1] neg_hi:[0,1]
	v_pk_add_f32 v[64:65], v[60:61], v[40:41] op_sel:[0,1] op_sel_hi:[1,0] neg_hi:[0,1]
	v_pk_add_f32 v[6:7], v[60:61], v[40:41] op_sel:[0,1] op_sel_hi:[1,0] neg_lo:[0,1]
	v_pk_add_f32 v[60:61], v[50:51], v[56:57]
	v_pk_add_f32 v[22:23], v[50:51], v[56:57] neg_lo:[0,1] neg_hi:[0,1]
	v_pk_add_f32 v[50:51], v[52:53], v[72:73]
	v_pk_add_f32 v[30:31], v[52:53], v[72:73] neg_lo:[0,1] neg_hi:[0,1]
	v_pk_add_f32 v[52:53], v[18:19], v[36:37]
	v_pk_add_f32 v[56:57], v[18:19], v[36:37] neg_lo:[0,1] neg_hi:[0,1]
	v_mov_b32_e32 v18, v21
	v_pk_add_f32 v[84:85], v[4:5], v[10:11]
	v_cvt_f32_i32_e32 v18, v18
	v_pk_add_f32 v[32:33], v[42:43], v[66:67]
	v_pk_add_f32 v[40:41], v[42:43], v[66:67] neg_lo:[0,1] neg_hi:[0,1]
	v_pk_add_f32 v[66:67], v[24:25], v[80:81]
	v_pk_add_f32 v[10:11], v[24:25], v[80:81] neg_lo:[0,1] neg_hi:[0,1]
	v_pk_add_f32 v[72:73], v[14:15], v[34:35]
	v_pk_add_f32 v[24:25], v[14:15], v[34:35] neg_lo:[0,1] neg_hi:[0,1]
	v_mul_f32_e32 v15, 0x38800000, v18
	v_cos_f32_e32 v14, v15
	v_sin_f32_e32 v15, v15
	v_pk_add_f32 v[16:17], v[74:75], v[62:63]
	v_pk_add_f32 v[54:55], v[74:75], v[62:63] neg_lo:[0,1] neg_hi:[0,1]
	v_pk_add_f32 v[62:63], v[8:9], v[44:45]
	v_pk_add_f32 v[4:5], v[8:9], v[44:45] neg_lo:[0,1] neg_hi:[0,1]
	v_pk_add_f32 v[8:9], v[26:27], v[58:59]
	v_add_f32_e32 v20, v14, v14
	v_pk_add_f32 v[42:43], v[38:39], v[46:47]
	v_pk_add_f32 v[38:39], v[38:39], v[46:47] neg_lo:[0,1] neg_hi:[0,1]
	v_pk_add_f32 v[58:59], v[26:27], v[58:59] neg_lo:[0,1] neg_hi:[0,1]
	v_pk_add_f32 v[26:27], v[76:77], v[78:79]
	v_pk_add_f32 v[46:47], v[76:77], v[78:79] neg_lo:[0,1] neg_hi:[0,1]
	v_pk_mul_f32 v[18:19], v[14:15], v[14:15]
	v_mul_f32_e32 v20, v15, v20
	v_mov_b32_e32 v78, v15
	v_pk_add_f32 v[18:19], v[18:19], v[18:19] op_sel:[0,1] op_sel_hi:[0,1] neg_lo:[0,1] neg_hi:[0,1]
	v_pk_mul_f32 v[34:35], v[14:15], v[20:21] op_sel:[1,0] op_sel_hi:[0,0] neg_lo:[1,0]
	v_pk_mul_f32 v[36:37], v[78:79], v[8:9] op_sel:[0,1] op_sel_hi:[0,0] neg_hi:[0,1]
	v_pk_fma_f32 v[34:35], v[14:15], v[18:19], v[34:35]
	v_pk_fma_f32 v[8:9], v[14:15], v[8:9], v[36:37] op_sel_hi:[0,1,1]
	v_pk_mul_f32 v[14:15], v[20:21], s[48:49] op_sel_hi:[0,1]
	v_pk_fma_f32 v[36:37], v[18:19], s[40:41], v[14:15]
	s_nop 0
	v_pk_mul_f32 v[14:15], v[16:17], v[36:37] op_sel:[1,1] op_sel_hi:[0,1] neg_hi:[1,0]
	v_pk_add_f32 v[74:75], v[82:83], v[84:85]
	v_pk_fma_f32 v[16:17], v[16:17], v[36:37], v[14:15] op_sel_hi:[1,0,1]
	v_pk_mul_f32 v[14:15], v[20:21], v[34:35] op_sel:[0,1] op_sel_hi:[0,0] neg_lo:[0,1]
	v_pk_fma_f32 v[78:79], v[18:19], v[34:35], v[14:15]
	v_pk_mul_f32 v[14:15], v[34:35], v[52:53] op_sel:[1,1] op_sel_hi:[1,0] neg_hi:[0,1]
	v_pk_add_f32 v[76:77], v[12:13], v[86:87]
	v_pk_fma_f32 v[14:15], v[34:35], v[52:53], v[14:15] op_sel_hi:[0,1,1]
	v_pk_mul_f32 v[34:35], v[20:21], v[36:37] op_sel:[0,1] op_sel_hi:[0,0] neg_lo:[0,1]
	s_nop 0
	v_pk_fma_f32 v[36:37], v[18:19], v[36:37], v[34:35]
	v_pk_mul_f32 v[52:53], v[26:27], v[78:79] op_sel:[1,1] op_sel_hi:[0,1] neg_hi:[1,0]
	v_pk_mul_f32 v[34:35], v[32:33], v[36:37] op_sel:[1,1] op_sel_hi:[0,1] neg_hi:[1,0]
	v_pk_fma_f32 v[26:27], v[26:27], v[78:79], v[52:53] op_sel_hi:[1,0,1]
	v_pk_fma_f32 v[34:35], v[32:33], v[36:37], v[34:35] op_sel_hi:[1,0,1]
	v_pk_mul_f32 v[52:53], v[20:21], v[36:37] op_sel:[0,1] op_sel_hi:[0,0] neg_lo:[0,1]
	v_pk_mul_f32 v[32:33], v[20:21], v[78:79] op_sel:[0,1] op_sel_hi:[0,0] neg_lo:[0,1]
	v_pk_fma_f32 v[52:53], v[18:19], v[36:37], v[52:53]
	v_pk_fma_f32 v[32:33], v[18:19], v[78:79], v[32:33]
	v_pk_mul_f32 v[36:37], v[42:43], v[52:53] op_sel:[1,1] op_sel_hi:[0,1] neg_hi:[1,0]
	s_nop 0
	v_pk_fma_f32 v[36:37], v[42:43], v[52:53], v[36:37] op_sel_hi:[1,0,1]
	v_pk_mul_f32 v[42:43], v[20:21], v[32:33] op_sel:[0,1] op_sel_hi:[0,0] neg_lo:[0,1]
	v_pk_mul_f32 v[78:79], v[74:75], v[32:33] op_sel:[1,1] op_sel_hi:[0,1] neg_hi:[1,0]
	v_pk_fma_f32 v[42:43], v[18:19], v[32:33], v[42:43]
	v_pk_fma_f32 v[32:33], v[74:75], v[32:33], v[78:79] op_sel_hi:[1,0,1]
	v_pk_mul_f32 v[74:75], v[20:21], v[52:53] op_sel:[0,1] op_sel_hi:[0,0] neg_lo:[0,1]
	v_pk_fma_f32 v[52:53], v[18:19], v[52:53], v[74:75]
	s_nop 0
	v_pk_mul_f32 v[74:75], v[48:49], v[52:53] op_sel:[1,1] op_sel_hi:[0,1] neg_hi:[1,0]
	s_nop 0
	v_pk_fma_f32 v[48:49], v[48:49], v[52:53], v[74:75] op_sel_hi:[1,0,1]
	v_pk_mul_f32 v[74:75], v[20:21], v[42:43] op_sel:[0,1] op_sel_hi:[0,0] neg_lo:[0,1]
	v_pk_mul_f32 v[78:79], v[50:51], v[42:43] op_sel:[1,1] op_sel_hi:[0,1] neg_hi:[1,0]
	v_pk_fma_f32 v[74:75], v[18:19], v[42:43], v[74:75]
	v_pk_fma_f32 v[42:43], v[50:51], v[42:43], v[78:79] op_sel_hi:[1,0,1]
	v_pk_mul_f32 v[50:51], v[20:21], v[52:53] op_sel:[0,1] op_sel_hi:[0,0] neg_lo:[0,1]
	v_pk_fma_f32 v[78:79], v[18:19], v[52:53], v[50:51]
	s_nop 0
	v_pk_mul_f32 v[50:51], v[60:61], v[78:79] op_sel:[1,1] op_sel_hi:[0,1] neg_hi:[1,0]
	v_xor_b32_e32 v81, 0x80000000, v58
	v_pk_fma_f32 v[52:53], v[60:61], v[78:79], v[50:51] op_sel_hi:[1,0,1]
	v_pk_mul_f32 v[50:51], v[20:21], v[74:75] op_sel:[0,1] op_sel_hi:[0,0] neg_lo:[0,1]
	v_pk_fma_f32 v[60:61], v[18:19], v[74:75], v[50:51]
	v_pk_mul_f32 v[50:51], v[72:73], v[74:75] op_sel:[1,1] op_sel_hi:[0,1] neg_hi:[1,0]
	v_mov_b32_e32 v80, v59
	v_pk_fma_f32 v[50:51], v[72:73], v[74:75], v[50:51] op_sel_hi:[1,0,1]
	v_pk_mul_f32 v[72:73], v[20:21], v[78:79] op_sel:[0,1] op_sel_hi:[0,0] neg_lo:[0,1]
	v_pk_fma_f32 v[72:73], v[18:19], v[78:79], v[72:73]
	s_nop 0
	v_pk_mul_f32 v[74:75], v[64:65], v[72:73] op_sel:[1,1] op_sel_hi:[0,1] neg_hi:[1,0]
	s_nop 0
	v_pk_fma_f32 v[64:65], v[64:65], v[72:73], v[74:75] op_sel_hi:[1,0,1]
	v_pk_mul_f32 v[74:75], v[20:21], v[60:61] op_sel:[0,1] op_sel_hi:[0,0] neg_lo:[0,1]
	v_pk_mul_f32 v[78:79], v[66:67], v[60:61] op_sel:[1,1] op_sel_hi:[0,1] neg_hi:[1,0]
	v_pk_fma_f32 v[74:75], v[18:19], v[60:61], v[74:75]
	v_pk_fma_f32 v[60:61], v[66:67], v[60:61], v[78:79] op_sel_hi:[1,0,1]
	v_pk_mul_f32 v[66:67], v[20:21], v[72:73] op_sel:[0,1] op_sel_hi:[0,0] neg_lo:[0,1]
	v_pk_fma_f32 v[66:67], v[18:19], v[72:73], v[66:67]
	s_nop 0
	v_pk_mul_f32 v[72:73], v[62:63], v[66:67] op_sel:[1,1] op_sel_hi:[0,1] neg_hi:[1,0]
	s_nop 0
	v_pk_fma_f32 v[62:63], v[62:63], v[66:67], v[72:73] op_sel_hi:[1,0,1]
	v_pk_mul_f32 v[72:73], v[20:21], v[74:75] op_sel:[0,1] op_sel_hi:[0,0] neg_lo:[0,1]
	v_pk_mul_f32 v[78:79], v[76:77], v[74:75] op_sel:[1,1] op_sel_hi:[0,1] neg_hi:[1,0]
	v_pk_fma_f32 v[72:73], v[18:19], v[74:75], v[72:73]
	v_pk_fma_f32 v[74:75], v[76:77], v[74:75], v[78:79] op_sel_hi:[1,0,1]
	v_pk_mul_f32 v[76:77], v[20:21], v[66:67] op_sel:[0,1] op_sel_hi:[0,0] neg_lo:[0,1]
	s_nop 0
	v_pk_fma_f32 v[66:67], v[18:19], v[66:67], v[76:77]
	v_pk_mul_f32 v[78:79], v[20:21], v[72:73] op_sel:[0,1] op_sel_hi:[0,0] neg_lo:[0,1]
	v_pk_mul_f32 v[80:81], v[80:81], v[72:73] op_sel:[0,1]
	v_pk_fma_f32 v[78:79], v[18:19], v[72:73], v[78:79]
	v_pk_fma_f32 v[58:59], v[58:59], v[72:73], v[80:81] op_sel_hi:[1,0,1]
	v_pk_mul_f32 v[76:77], v[88:89], v[66:67] op_sel:[1,1] op_sel_hi:[0,1] neg_hi:[1,0]
	v_pk_mul_f32 v[72:73], v[20:21], v[66:67] op_sel:[0,1] op_sel_hi:[0,0] neg_lo:[0,1]
	v_pk_fma_f32 v[76:77], v[88:89], v[66:67], v[76:77] op_sel_hi:[1,0,1]
	v_pk_fma_f32 v[66:67], v[18:19], v[66:67], v[72:73]
	s_nop 0
	v_pk_mul_f32 v[72:73], v[54:55], v[66:67] op_sel:[1,1] op_sel_hi:[0,1] neg_hi:[1,0]
	s_nop 0
	v_pk_fma_f32 v[54:55], v[54:55], v[66:67], v[72:73] op_sel_hi:[1,0,1]
	v_pk_mul_f32 v[72:73], v[20:21], v[78:79] op_sel:[0,1] op_sel_hi:[0,0] neg_lo:[0,1]
	v_pk_mul_f32 v[80:81], v[56:57], v[78:79] op_sel:[1,1] op_sel_hi:[0,1] neg_hi:[1,0]
	v_pk_fma_f32 v[72:73], v[18:19], v[78:79], v[72:73]
	v_pk_fma_f32 v[56:57], v[56:57], v[78:79], v[80:81] op_sel_hi:[1,0,1]
	v_pk_mul_f32 v[78:79], v[20:21], v[66:67] op_sel:[0,1] op_sel_hi:[0,0] neg_lo:[0,1]
	v_pk_fma_f32 v[66:67], v[18:19], v[66:67], v[78:79]
	s_nop 0
	v_pk_mul_f32 v[78:79], v[40:41], v[66:67] op_sel:[1,1] op_sel_hi:[0,1] neg_hi:[1,0]
	s_nop 0
	v_pk_fma_f32 v[40:41], v[40:41], v[66:67], v[78:79] op_sel_hi:[1,0,1]
	v_pk_mul_f32 v[78:79], v[20:21], v[72:73] op_sel:[0,1] op_sel_hi:[0,0] neg_lo:[0,1]
	v_pk_mul_f32 v[80:81], v[46:47], v[72:73] op_sel:[1,1] op_sel_hi:[0,1] neg_hi:[1,0]
	v_pk_fma_f32 v[78:79], v[18:19], v[72:73], v[78:79]
	v_pk_fma_f32 v[46:47], v[46:47], v[72:73], v[80:81] op_sel_hi:[1,0,1]
	v_pk_mul_f32 v[72:73], v[20:21], v[66:67] op_sel:[0,1] op_sel_hi:[0,0] neg_lo:[0,1]
	v_pk_fma_f32 v[66:67], v[18:19], v[66:67], v[72:73]
	v_pk_add_f32 v[44:45], v[82:83], v[84:85] neg_lo:[0,1] neg_hi:[0,1]
	v_pk_mul_f32 v[72:73], v[38:39], v[66:67] op_sel:[1,1] op_sel_hi:[0,1] neg_hi:[1,0]
	s_nop 0
	v_pk_fma_f32 v[38:39], v[38:39], v[66:67], v[72:73] op_sel_hi:[1,0,1]
	v_pk_mul_f32 v[72:73], v[20:21], v[78:79] op_sel:[0,1] op_sel_hi:[0,0] neg_lo:[0,1]
	v_pk_mul_f32 v[80:81], v[44:45], v[78:79] op_sel:[1,1] op_sel_hi:[0,1] neg_hi:[1,0]
	v_pk_fma_f32 v[72:73], v[18:19], v[78:79], v[72:73]
	v_pk_fma_f32 v[44:45], v[44:45], v[78:79], v[80:81] op_sel_hi:[1,0,1]
	v_pk_mul_f32 v[78:79], v[20:21], v[66:67] op_sel:[0,1] op_sel_hi:[0,0] neg_lo:[0,1]
	v_pk_fma_f32 v[66:67], v[18:19], v[66:67], v[78:79]
	s_nop 0
	v_pk_mul_f32 v[78:79], v[28:29], v[66:67] op_sel:[1,1] op_sel_hi:[0,1] neg_hi:[1,0]
	s_nop 0
	v_pk_fma_f32 v[28:29], v[28:29], v[66:67], v[78:79] op_sel_hi:[1,0,1]
	v_pk_mul_f32 v[78:79], v[20:21], v[72:73] op_sel:[0,1] op_sel_hi:[0,0] neg_lo:[0,1]
	v_pk_mul_f32 v[80:81], v[30:31], v[72:73] op_sel:[1,1] op_sel_hi:[0,1] neg_hi:[1,0]
	v_pk_fma_f32 v[78:79], v[18:19], v[72:73], v[78:79]
	v_pk_fma_f32 v[30:31], v[30:31], v[72:73], v[80:81] op_sel_hi:[1,0,1]
	v_pk_mul_f32 v[72:73], v[20:21], v[66:67] op_sel:[0,1] op_sel_hi:[0,0] neg_lo:[0,1]
	v_pk_fma_f32 v[66:67], v[18:19], v[66:67], v[72:73]
	s_nop 0
	v_pk_mul_f32 v[72:73], v[22:23], v[66:67] op_sel:[1,1] op_sel_hi:[0,1] neg_hi:[1,0]
	s_nop 0
	v_pk_fma_f32 v[22:23], v[22:23], v[66:67], v[72:73] op_sel_hi:[1,0,1]
	v_pk_mul_f32 v[72:73], v[20:21], v[78:79] op_sel:[0,1] op_sel_hi:[0,0] neg_lo:[0,1]
	v_pk_mul_f32 v[80:81], v[24:25], v[78:79] op_sel:[1,1] op_sel_hi:[0,1] neg_hi:[1,0]
	v_pk_fma_f32 v[72:73], v[18:19], v[78:79], v[72:73]
	v_pk_fma_f32 v[24:25], v[24:25], v[78:79], v[80:81] op_sel_hi:[1,0,1]
	v_pk_mul_f32 v[78:79], v[20:21], v[66:67] op_sel:[0,1] op_sel_hi:[0,0] neg_lo:[0,1]
	v_pk_fma_f32 v[66:67], v[18:19], v[66:67], v[78:79]
	s_nop 0
	v_pk_mul_f32 v[78:79], v[6:7], v[66:67] op_sel:[1,1] op_sel_hi:[0,1] neg_hi:[1,0]
	s_nop 0
	v_pk_fma_f32 v[6:7], v[6:7], v[66:67], v[78:79] op_sel_hi:[1,0,1]
	v_pk_mul_f32 v[78:79], v[20:21], v[72:73] op_sel:[0,1] op_sel_hi:[0,0] neg_lo:[0,1]
	v_pk_mul_f32 v[80:81], v[10:11], v[72:73] op_sel:[1,1] op_sel_hi:[0,1] neg_hi:[1,0]
	v_pk_fma_f32 v[78:79], v[18:19], v[72:73], v[78:79]
	v_pk_fma_f32 v[10:11], v[10:11], v[72:73], v[80:81] op_sel_hi:[1,0,1]
	v_pk_mul_f32 v[72:73], v[20:21], v[66:67] op_sel:[0,1] op_sel_hi:[0,0] neg_lo:[0,1]
	v_pk_fma_f32 v[18:19], v[18:19], v[66:67], v[72:73]
	v_pk_add_f32 v[12:13], v[12:13], v[86:87] neg_lo:[0,1] neg_hi:[0,1]
	v_pk_mul_f32 v[66:67], v[4:5], v[18:19] op_sel:[1,1] op_sel_hi:[0,1] neg_hi:[1,0]
	s_nop 0
	v_pk_fma_f32 v[4:5], v[4:5], v[18:19], v[66:67] op_sel_hi:[1,0,1]
	s_nop 0
	s_nop 0
	v_pk_mul_f32 v[18:19], v[12:13], v[78:79] op_sel:[1,1] op_sel_hi:[0,1] neg_hi:[1,0]
	s_nop 0
	v_pk_fma_f32 v[12:13], v[12:13], v[78:79], v[18:19] op_sel_hi:[1,0,1]
	v_lshrrev_b32_e32 v18, 5, v21
	v_bitop3_b32 v18, v18, v21, 15 bitop3:0x6c
	v_lshlrev_b32_e32 v18, 3, v18
	v_bfe_u32 v19, v21, 5, 4
	v_add_u32_e32 v20, 16, v18
	ds_write_b64 v20, v[2:3]
	v_bitop3_b32 v2, v19, v21, 16 bitop3:0x36
	v_lshl_add_u32 v2, v2, 3, 16
	v_add_u32_e32 v3, s47, v18
	ds_write_b64 v2, v[76:77] offset:4096
	ds_write_b64 v20, v[48:49] offset:8192
	ds_write_b64 v2, v[28:29] offset:12288
	ds_write_b64 v20, v[34:35] offset:16384
	ds_write_b64 v2, v[40:41] offset:20480
	ds_write_b64 v20, v[64:65] offset:24576
	ds_write_b64 v2, v[6:7] offset:28672
	ds_write_b64 v20, v[16:17] offset:32768
	ds_write_b64 v2, v[54:55] offset:36864
	ds_write_b64 v20, v[52:53] offset:40960
	ds_write_b64 v2, v[22:23] offset:45056
	ds_write_b64 v20, v[36:37] offset:49152
	ds_write_b64 v2, v[38:39] offset:53248
	ds_write_b64 v20, v[62:63] offset:57344
	ds_write_b64 v2, v[4:5] offset:61440
	ds_write_b64 v3, v[8:9]
	v_add_u32_e32 v3, 0x11000, v2
	ds_write_b64 v3, v[58:59]
	v_add_u32_e32 v3, 0x12000, v20
	ds_write_b64 v3, v[42:43]
	v_add_u32_e32 v3, 0x13000, v2
	ds_write_b64 v3, v[30:31]
	v_add_u32_e32 v3, 0x14000, v20
	ds_write_b64 v3, v[26:27]
	v_add_u32_e32 v3, 0x15000, v2
	ds_write_b64 v3, v[46:47]
	v_add_u32_e32 v3, 0x16000, v20
	ds_write_b64 v3, v[60:61]
	v_add_u32_e32 v3, 0x17000, v2
	ds_write_b64 v3, v[10:11]
	v_add_u32_e32 v3, 0x18000, v20
	ds_write_b64 v3, v[14:15]
	v_add_u32_e32 v3, 0x19000, v2
	ds_write_b64 v3, v[56:57]
	v_add_u32_e32 v3, 0x1a000, v20
	ds_write_b64 v3, v[50:51]
	v_add_u32_e32 v3, 0x1b000, v2
	ds_write_b64 v3, v[24:25]
	v_add_u32_e32 v3, 0x1c000, v20
	ds_write_b64 v3, v[32:33]
	v_add_u32_e32 v3, 0x1d000, v2
	ds_write_b64 v3, v[44:45]
	v_add_u32_e32 v3, 0x1e000, v20
	v_add_u32_e32 v2, 0x1f000, v2
	v_mov_b32_e32 v11, v146
	ds_write_b64 v3, v[74:75]
	ds_write_b64 v2, v[12:13]
	s_waitcnt lgkmcnt(0)
	s_barrier
	s_nop 0
	v_lshlrev_b32_e32 v2, 5, v11
	v_and_b32_e32 v2, 0xfffffe00, v2
	v_and_or_b32 v3, v11, 16, v2
	v_bitop3_b32 v2, v2, 16, v11 bitop3:0x34
	v_bitop3_b32 v12, v11, 2, 15 bitop3:0x6c
	v_bitop3_b32 v22, v11, 4, 15 bitop3:0x6c
	v_bitop3_b32 v30, v11, 6, 15 bitop3:0x6c
	v_bitop3_b32 v38, v11, 8, 15 bitop3:0x6c
	v_and_b32_e32 v10, 15, v11
	v_lshl_add_u32 v18, v3, 3, 16
	v_lshl_add_u32 v87, v2, 3, 16
	v_lshlrev_b32_e32 v12, 3, v12
	v_lshlrev_b32_e32 v22, 3, v22
	v_lshlrev_b32_e32 v30, 3, v30
	v_lshlrev_b32_e32 v38, 3, v38
	v_lshlrev_b32_e32 v3, 3, v10
	v_bitop3_b32 v2, v11, 1, 15 bitop3:0x6c
	v_add_u32_e32 v57, v18, v12
	v_add_u32_e32 v58, v87, v12
	v_bitop3_b32 v12, v11, 3, 15 bitop3:0x6c
	v_add_u32_e32 v61, v18, v22
	v_add_u32_e32 v62, v87, v22
	v_bitop3_b32 v22, v11, 5, 15 bitop3:0x6c
	v_add_u32_e32 v65, v18, v30
	v_add_u32_e32 v66, v87, v30
	v_bitop3_b32 v30, v11, 7, 15 bitop3:0x6c
	v_add_u32_e32 v72, v18, v38
	v_add_u32_e32 v73, v87, v38
	v_bitop3_b32 v38, v11, 9, 15 bitop3:0x6c
	v_add_u32_e32 v19, v18, v3
	v_lshlrev_b32_e32 v2, 3, v2
	v_lshlrev_b32_e32 v12, 3, v12
	v_lshlrev_b32_e32 v22, 3, v22
	v_lshlrev_b32_e32 v30, 3, v30
	v_lshlrev_b32_e32 v38, 3, v38
	v_add_u32_e32 v54, v87, v3
	v_add_u32_e32 v55, v18, v2
	v_add_u32_e32 v56, v87, v2
	ds_read_b64 v[2:3], v19
	ds_read_b64 v[4:5], v54
	ds_read_b64 v[6:7], v55 offset:256
	ds_read_b64 v[8:9], v56 offset:256
	v_add_u32_e32 v59, v18, v12
	v_add_u32_e32 v60, v87, v12
	ds_read_b64 v[12:13], v57 offset:512
	ds_read_b64 v[14:15], v58 offset:512
	ds_read_b64 v[16:17], v59 offset:768
	ds_read_b64 v[20:21], v60 offset:768
	v_add_u32_e32 v63, v18, v22
	v_add_u32_e32 v64, v87, v22
	ds_read_b64 v[22:23], v61 offset:1024
	ds_read_b64 v[24:25], v62 offset:1024
	ds_read_b64 v[26:27], v63 offset:1280
	ds_read_b64 v[28:29], v64 offset:1280
	v_add_u32_e32 v67, v18, v30
	v_add_u32_e32 v71, v87, v30
	ds_read_b64 v[30:31], v65 offset:1536
	ds_read_b64 v[32:33], v66 offset:1536
	ds_read_b64 v[34:35], v67 offset:1792
	ds_read_b64 v[36:37], v71 offset:1792
	v_add_u32_e32 v74, v18, v38
	v_add_u32_e32 v75, v87, v38
	ds_read_b64 v[38:39], v72 offset:2048
	ds_read_b64 v[40:41], v73 offset:2048
	ds_read_b64 v[42:43], v74 offset:2304
	ds_read_b64 v[44:45], v75 offset:2304
	v_bitop3_b32 v46, v11, 10, 15 bitop3:0x6c
	s_waitcnt lgkmcnt(3)
	v_pk_add_f32 v[104:105], v[2:3], v[38:39]
	v_pk_add_f32 v[2:3], v[2:3], v[38:39] neg_lo:[0,1] neg_hi:[0,1]
	s_waitcnt lgkmcnt(2)
	v_pk_add_f32 v[38:39], v[4:5], v[40:41]
	v_pk_add_f32 v[4:5], v[4:5], v[40:41] neg_lo:[0,1] neg_hi:[0,1]
	v_lshlrev_b32_e32 v46, 3, v46
	v_pk_mul_f32 v[40:41], v[4:5], s[58:59] op_sel:[1,0] op_sel_hi:[0,0] neg_hi:[1,0]
	v_add_u32_e32 v76, v18, v46
	v_pk_fma_f32 v[4:5], v[4:5], s[46:47], v[40:41] op_sel_hi:[1,0,1]
	s_waitcnt lgkmcnt(1)
	v_pk_add_f32 v[40:41], v[6:7], v[42:43]
	v_pk_add_f32 v[6:7], v[6:7], v[42:43] neg_lo:[0,1] neg_hi:[0,1]
	v_add_u32_e32 v77, v87, v46
	v_bitop3_b32 v46, v11, 11, 15 bitop3:0x6c
	v_pk_mul_f32 v[42:43], v[6:7], s[62:63] op_sel:[1,0] op_sel_hi:[0,0] neg_hi:[1,0]
	v_lshlrev_b32_e32 v46, 3, v46
	v_pk_fma_f32 v[6:7], v[6:7], s[60:61], v[42:43] op_sel_hi:[1,0,1]
	s_waitcnt lgkmcnt(0)
	v_pk_add_f32 v[42:43], v[8:9], v[44:45]
	v_pk_add_f32 v[8:9], v[8:9], v[44:45] neg_lo:[0,1] neg_hi:[0,1]
	v_add_u32_e32 v78, v18, v46
	v_add_u32_e32 v79, v87, v46
	ds_read_b64 v[46:47], v76 offset:2560
	ds_read_b64 v[48:49], v77 offset:2560
	ds_read_b64 v[50:51], v78 offset:2816
	ds_read_b64 v[52:53], v79 offset:2816
	v_pk_mul_f32 v[44:45], v[8:9], s[66:67] op_sel:[1,0] op_sel_hi:[0,0] neg_hi:[1,0]
	v_bitop3_b32 v80, v11, 12, 15 bitop3:0x6c
	v_pk_fma_f32 v[8:9], v[8:9], s[64:65], v[44:45] op_sel_hi:[1,0,1]
	s_waitcnt lgkmcnt(3)
	v_pk_add_f32 v[44:45], v[12:13], v[46:47]
	v_pk_add_f32 v[12:13], v[12:13], v[46:47] neg_lo:[0,1] neg_hi:[0,1]
	v_lshlrev_b32_e32 v81, 3, v80
	v_pk_mul_f32 v[46:47], v[12:13], s[70:71] op_sel:[1,0] op_sel_hi:[0,0] neg_hi:[1,0]
	v_bitop3_b32 v82, v11, 13, 15 bitop3:0x6c
	v_pk_fma_f32 v[12:13], v[12:13], s[70:71], v[46:47] op_sel_hi:[1,0,1]
	s_waitcnt lgkmcnt(2)
	v_pk_add_f32 v[46:47], v[14:15], v[48:49]
	v_pk_add_f32 v[14:15], v[14:15], v[48:49] neg_lo:[0,1] neg_hi:[0,1]
	v_add_u32_e32 v80, v18, v81
	v_pk_mul_f32 v[48:49], v[14:15], s[64:65] op_sel:[1,0] op_sel_hi:[0,0] neg_hi:[1,0]
	v_lshlrev_b32_e32 v83, 3, v82
	v_pk_fma_f32 v[14:15], v[14:15], s[66:67], v[48:49] op_sel_hi:[1,0,1]
	s_waitcnt lgkmcnt(1)
	v_pk_add_f32 v[48:49], v[16:17], v[50:51]
	v_pk_add_f32 v[16:17], v[16:17], v[50:51] neg_lo:[0,1] neg_hi:[0,1]
	v_add_u32_e32 v81, v87, v81
	v_pk_mul_f32 v[50:51], v[16:17], s[60:61] op_sel:[1,0] op_sel_hi:[0,0] neg_hi:[1,0]
	v_add_u32_e32 v82, v18, v83
	v_pk_fma_f32 v[16:17], v[16:17], s[62:63], v[50:51] op_sel_hi:[1,0,1]
	s_waitcnt lgkmcnt(0)
	v_pk_add_f32 v[50:51], v[20:21], v[52:53]
	v_pk_add_f32 v[20:21], v[20:21], v[52:53] neg_lo:[0,1] neg_hi:[0,1]
	v_add_u32_e32 v83, v87, v83
	ds_read_b64 v[88:89], v80 offset:3072
	ds_read_b64 v[90:91], v81 offset:3072
	ds_read_b64 v[92:93], v82 offset:3328
	ds_read_b64 v[94:95], v83 offset:3328
	v_pk_mul_f32 v[52:53], v[20:21], s[46:47] op_sel:[1,0] op_sel_hi:[0,0] neg_hi:[1,0]
	v_bitop3_b32 v84, v11, 14, 15 bitop3:0x6c
	v_pk_fma_f32 v[20:21], v[20:21], s[58:59], v[52:53] op_sel_hi:[1,0,1]
	s_waitcnt lgkmcnt(3)
	v_pk_add_f32 v[52:53], v[22:23], v[88:89]
	v_pk_add_f32 v[22:23], v[22:23], v[88:89] neg_lo:[0,1] neg_hi:[0,1]
	v_lshlrev_b32_e32 v85, 3, v84
	v_xor_b32_e32 v89, 0x80000000, v22
	v_mov_b32_e32 v88, v23
	s_waitcnt lgkmcnt(2)
	v_pk_add_f32 v[22:23], v[24:25], v[90:91]
	v_pk_add_f32 v[24:25], v[24:25], v[90:91] neg_lo:[0,1] neg_hi:[0,1]
	v_bitop3_b32 v11, v11, 15, v11 bitop3:0xc
	v_pk_mul_f32 v[90:91], v[24:25], s[58:59] op_sel_hi:[1,0]
	v_xor_b32_e32 v107, 0x80000000, v24
	v_mov_b32_e32 v106, v25
	v_pk_fma_f32 v[24:25], v[106:107], s[46:47], v[90:91] op_sel_hi:[1,0,1] neg_lo:[0,0,1] neg_hi:[0,0,1]
	s_waitcnt lgkmcnt(1)
	v_pk_add_f32 v[90:91], v[26:27], v[92:93]
	v_pk_add_f32 v[26:27], v[26:27], v[92:93] neg_lo:[0,1] neg_hi:[0,1]
	v_add_u32_e32 v84, v18, v85
	v_lshlrev_b32_e32 v11, 3, v11
	v_pk_mul_f32 v[92:93], v[26:27], s[62:63] op_sel_hi:[1,0]
	v_xor_b32_e32 v107, 0x80000000, v26
	v_mov_b32_e32 v106, v27
	v_add_u32_e32 v85, v87, v85
	v_add_u32_e32 v86, v18, v11
	v_add_u32_e32 v87, v87, v11
	ds_read_b64 v[96:97], v84 offset:3584
	ds_read_b64 v[98:99], v85 offset:3584
	ds_read_b64 v[100:101], v86 offset:3840
	ds_read_b64 v[102:103], v87 offset:3840
	v_pk_fma_f32 v[26:27], v[106:107], s[60:61], v[92:93] op_sel_hi:[1,0,1] neg_lo:[0,0,1] neg_hi:[0,0,1]
	s_waitcnt lgkmcnt(4)
	v_pk_add_f32 v[92:93], v[28:29], v[94:95]
	v_pk_add_f32 v[28:29], v[28:29], v[94:95] neg_lo:[0,1] neg_hi:[0,1]
	s_nop 0
	v_pk_mul_f32 v[94:95], v[28:29], s[66:67] op_sel_hi:[1,0]
	v_xor_b32_e32 v107, 0x80000000, v28
	v_mov_b32_e32 v106, v29
	v_pk_fma_f32 v[28:29], v[106:107], s[64:65], v[94:95] op_sel_hi:[1,0,1] neg_lo:[0,0,1] neg_hi:[0,0,1]
	s_waitcnt lgkmcnt(3)
	v_pk_add_f32 v[94:95], v[30:31], v[96:97]
	v_pk_add_f32 v[30:31], v[30:31], v[96:97] neg_lo:[0,1] neg_hi:[0,1]
	v_cvt_f32_i32_e32 v10, v10
	v_pk_mul_f32 v[96:97], v[30:31], s[70:71] op_sel_hi:[1,0]
	v_xor_b32_e32 v107, 0x80000000, v30
	v_mov_b32_e32 v106, v31
	v_pk_fma_f32 v[30:31], v[106:107], s[70:71], v[96:97] op_sel_hi:[1,0,1] neg_lo:[0,0,1] neg_hi:[0,0,1]
	s_waitcnt lgkmcnt(2)
	v_pk_add_f32 v[96:97], v[32:33], v[98:99]
	v_pk_add_f32 v[32:33], v[32:33], v[98:99] neg_lo:[0,1] neg_hi:[0,1]
	v_mul_f32_e32 v10, 0x3b000000, v10
	v_pk_mul_f32 v[98:99], v[32:33], s[64:65] op_sel_hi:[1,0]
	v_xor_b32_e32 v107, 0x80000000, v32
	v_mov_b32_e32 v106, v33
	v_pk_fma_f32 v[32:33], v[106:107], s[66:67], v[98:99] op_sel_hi:[1,0,1] neg_lo:[0,0,1] neg_hi:[0,0,1]
	s_waitcnt lgkmcnt(1)
	v_pk_add_f32 v[98:99], v[34:35], v[100:101]
	v_pk_add_f32 v[34:35], v[34:35], v[100:101] neg_lo:[0,1] neg_hi:[0,1]
	s_nop 0
	v_pk_mul_f32 v[100:101], v[34:35], s[60:61] op_sel_hi:[1,0]
	v_xor_b32_e32 v107, 0x80000000, v34
	v_mov_b32_e32 v106, v35
	v_pk_fma_f32 v[34:35], v[106:107], s[62:63], v[100:101] op_sel_hi:[1,0,1] neg_lo:[0,0,1] neg_hi:[0,0,1]
	s_waitcnt lgkmcnt(0)
	v_pk_add_f32 v[100:101], v[36:37], v[102:103]
	v_pk_add_f32 v[36:37], v[36:37], v[102:103] neg_lo:[0,1] neg_hi:[0,1]
	s_nop 0
	v_pk_mul_f32 v[102:103], v[36:37], s[46:47] op_sel_hi:[1,0]
	v_xor_b32_e32 v107, 0x80000000, v36
	v_mov_b32_e32 v106, v37
	v_pk_fma_f32 v[36:37], v[106:107], s[58:59], v[102:103] op_sel_hi:[1,0,1] neg_lo:[0,0,1] neg_hi:[0,0,1]
	v_pk_add_f32 v[102:103], v[104:105], v[52:53]
	v_pk_add_f32 v[52:53], v[104:105], v[52:53] neg_lo:[0,1] neg_hi:[0,1]
	v_pk_add_f32 v[104:105], v[38:39], v[22:23]
	v_pk_add_f32 v[22:23], v[38:39], v[22:23] neg_lo:[0,1] neg_hi:[0,1]
	s_nop 0
	v_pk_mul_f32 v[38:39], v[22:23], s[62:63] op_sel:[1,0] op_sel_hi:[0,0] neg_hi:[1,0]
	s_nop 0
	v_pk_fma_f32 v[22:23], v[22:23], s[60:61], v[38:39] op_sel_hi:[1,0,1]
	v_pk_add_f32 v[38:39], v[40:41], v[90:91]
	v_pk_add_f32 v[40:41], v[40:41], v[90:91] neg_lo:[0,1] neg_hi:[0,1]
	s_nop 0
	v_pk_mul_f32 v[90:91], v[40:41], s[70:71] op_sel:[1,0] op_sel_hi:[0,0] neg_hi:[1,0]
	s_nop 0
	v_pk_fma_f32 v[40:41], v[40:41], s[70:71], v[90:91] op_sel_hi:[1,0,1]
	v_pk_add_f32 v[90:91], v[42:43], v[92:93]
	v_pk_add_f32 v[42:43], v[42:43], v[92:93] neg_lo:[0,1] neg_hi:[0,1]
	s_nop 0
	v_pk_mul_f32 v[92:93], v[42:43], s[60:61] op_sel:[1,0] op_sel_hi:[0,0] neg_hi:[1,0]
	s_nop 0
	v_pk_fma_f32 v[42:43], v[42:43], s[62:63], v[92:93] op_sel_hi:[1,0,1]
	v_pk_add_f32 v[92:93], v[44:45], v[94:95]
	v_pk_add_f32 v[44:45], v[44:45], v[94:95] neg_lo:[0,1] neg_hi:[0,1]
	s_nop 0
	v_xor_b32_e32 v95, 0x80000000, v44
	v_mov_b32_e32 v94, v45
	v_pk_add_f32 v[44:45], v[46:47], v[96:97]
	v_pk_add_f32 v[46:47], v[46:47], v[96:97] neg_lo:[0,1] neg_hi:[0,1]
	s_nop 0
	v_pk_mul_f32 v[96:97], v[46:47], s[62:63] op_sel_hi:[1,0]
	v_xor_b32_e32 v107, 0x80000000, v46
	v_mov_b32_e32 v106, v47
	v_pk_fma_f32 v[46:47], v[106:107], s[60:61], v[96:97] op_sel_hi:[1,0,1] neg_lo:[0,0,1] neg_hi:[0,0,1]
	v_pk_add_f32 v[96:97], v[48:49], v[98:99]
	v_pk_add_f32 v[48:49], v[48:49], v[98:99] neg_lo:[0,1] neg_hi:[0,1]
	s_nop 0
	v_pk_mul_f32 v[98:99], v[48:49], s[70:71] op_sel_hi:[1,0]
	v_xor_b32_e32 v107, 0x80000000, v48
	v_mov_b32_e32 v106, v49
	v_pk_fma_f32 v[48:49], v[106:107], s[70:71], v[98:99] op_sel_hi:[1,0,1] neg_lo:[0,0,1] neg_hi:[0,0,1]
	v_pk_add_f32 v[98:99], v[50:51], v[100:101]
	v_pk_add_f32 v[50:51], v[50:51], v[100:101] neg_lo:[0,1] neg_hi:[0,1]
	s_nop 0
	v_pk_mul_f32 v[100:101], v[50:51], s[60:61] op_sel_hi:[1,0]
	v_xor_b32_e32 v107, 0x80000000, v50
	v_mov_b32_e32 v106, v51
	v_pk_fma_f32 v[50:51], v[106:107], s[62:63], v[100:101] op_sel_hi:[1,0,1] neg_lo:[0,0,1] neg_hi:[0,0,1]
	v_pk_add_f32 v[100:101], v[2:3], v[88:89]
	v_pk_add_f32 v[2:3], v[2:3], v[88:89] neg_lo:[0,1] neg_hi:[0,1]
	v_pk_add_f32 v[88:89], v[4:5], v[24:25]
	v_pk_add_f32 v[4:5], v[4:5], v[24:25] neg_lo:[0,1] neg_hi:[0,1]
	s_nop 0
	v_pk_mul_f32 v[24:25], v[4:5], s[62:63] op_sel:[1,0] op_sel_hi:[0,0] neg_hi:[1,0]
	s_nop 0
	v_pk_fma_f32 v[4:5], v[4:5], s[60:61], v[24:25] op_sel_hi:[1,0,1]
	v_pk_add_f32 v[24:25], v[6:7], v[26:27]
	v_pk_add_f32 v[6:7], v[6:7], v[26:27] neg_lo:[0,1] neg_hi:[0,1]
	s_nop 0
	v_pk_mul_f32 v[26:27], v[6:7], s[70:71] op_sel:[1,0] op_sel_hi:[0,0] neg_hi:[1,0]
	s_nop 0
	v_pk_fma_f32 v[6:7], v[6:7], s[70:71], v[26:27] op_sel_hi:[1,0,1]
	v_pk_add_f32 v[26:27], v[8:9], v[28:29]
	v_pk_add_f32 v[8:9], v[8:9], v[28:29] neg_lo:[0,1] neg_hi:[0,1]
	s_nop 0
	v_pk_mul_f32 v[28:29], v[8:9], s[60:61] op_sel:[1,0] op_sel_hi:[0,0] neg_hi:[1,0]
	s_nop 0
	v_pk_fma_f32 v[8:9], v[8:9], s[62:63], v[28:29] op_sel_hi:[1,0,1]
	v_pk_add_f32 v[28:29], v[12:13], v[30:31]
	v_pk_add_f32 v[12:13], v[12:13], v[30:31] neg_lo:[0,1] neg_hi:[0,1]
	s_nop 0
	v_xor_b32_e32 v31, 0x80000000, v12
	v_mov_b32_e32 v30, v13
	v_pk_add_f32 v[12:13], v[14:15], v[32:33]
	v_pk_add_f32 v[14:15], v[14:15], v[32:33] neg_lo:[0,1] neg_hi:[0,1]
	s_nop 0
	v_pk_mul_f32 v[32:33], v[14:15], s[62:63] op_sel_hi:[1,0]
	v_xor_b32_e32 v107, 0x80000000, v14
	v_mov_b32_e32 v106, v15
	v_pk_fma_f32 v[14:15], v[106:107], s[60:61], v[32:33] op_sel_hi:[1,0,1] neg_lo:[0,0,1] neg_hi:[0,0,1]
	v_pk_add_f32 v[32:33], v[16:17], v[34:35]
	v_pk_add_f32 v[16:17], v[16:17], v[34:35] neg_lo:[0,1] neg_hi:[0,1]
	s_nop 0
	v_pk_mul_f32 v[34:35], v[16:17], s[70:71] op_sel_hi:[1,0]
	v_xor_b32_e32 v107, 0x80000000, v16
	v_mov_b32_e32 v106, v17
	v_pk_fma_f32 v[16:17], v[106:107], s[70:71], v[34:35] op_sel_hi:[1,0,1] neg_lo:[0,0,1] neg_hi:[0,0,1]
	v_pk_add_f32 v[34:35], v[20:21], v[36:37]
	v_pk_add_f32 v[20:21], v[20:21], v[36:37] neg_lo:[0,1] neg_hi:[0,1]
	s_nop 0
	v_pk_mul_f32 v[36:37], v[20:21], s[60:61] op_sel_hi:[1,0]
	v_xor_b32_e32 v107, 0x80000000, v20
	v_mov_b32_e32 v106, v21
	v_pk_fma_f32 v[20:21], v[106:107], s[62:63], v[36:37] op_sel_hi:[1,0,1] neg_lo:[0,0,1] neg_hi:[0,0,1]
	v_pk_add_f32 v[36:37], v[102:103], v[92:93]
	v_pk_add_f32 v[92:93], v[102:103], v[92:93] neg_lo:[0,1] neg_hi:[0,1]
	v_pk_add_f32 v[102:103], v[104:105], v[44:45]
	v_pk_add_f32 v[44:45], v[104:105], v[44:45] neg_lo:[0,1] neg_hi:[0,1]
	s_nop 0
	v_pk_mul_f32 v[104:105], v[44:45], s[70:71] op_sel:[1,0] op_sel_hi:[0,0] neg_hi:[1,0]
	s_nop 0
	v_pk_fma_f32 v[44:45], v[44:45], s[70:71], v[104:105] op_sel_hi:[1,0,1]
	v_pk_add_f32 v[104:105], v[38:39], v[96:97]
	v_pk_add_f32 v[38:39], v[38:39], v[96:97] neg_lo:[0,1] neg_hi:[0,1]
	s_nop 0
	v_xor_b32_e32 v97, 0x80000000, v38
	v_mov_b32_e32 v96, v39
	v_pk_add_f32 v[38:39], v[90:91], v[98:99]
	v_pk_add_f32 v[90:91], v[90:91], v[98:99] neg_lo:[0,1] neg_hi:[0,1]
	s_nop 0
	v_pk_mul_f32 v[98:99], v[90:91], s[70:71] op_sel_hi:[1,0]
	v_xor_b32_e32 v107, 0x80000000, v90
	v_mov_b32_e32 v106, v91
	v_pk_fma_f32 v[90:91], v[106:107], s[70:71], v[98:99] op_sel_hi:[1,0,1] neg_lo:[0,0,1] neg_hi:[0,0,1]
	v_pk_add_f32 v[98:99], v[52:53], v[94:95]
	v_pk_add_f32 v[52:53], v[52:53], v[94:95] neg_lo:[0,1] neg_hi:[0,1]
	v_pk_add_f32 v[94:95], v[22:23], v[46:47]
	v_pk_add_f32 v[22:23], v[22:23], v[46:47] neg_lo:[0,1] neg_hi:[0,1]
	s_nop 0
	v_pk_mul_f32 v[46:47], v[22:23], s[70:71] op_sel:[1,0] op_sel_hi:[0,0] neg_hi:[1,0]
	s_nop 0
	v_pk_fma_f32 v[22:23], v[22:23], s[70:71], v[46:47] op_sel_hi:[1,0,1]
	v_pk_add_f32 v[46:47], v[40:41], v[48:49]
	v_pk_add_f32 v[40:41], v[40:41], v[48:49] neg_lo:[0,1] neg_hi:[0,1]
	s_nop 0
	v_xor_b32_e32 v49, 0x80000000, v40
	v_mov_b32_e32 v48, v41
	v_pk_add_f32 v[40:41], v[42:43], v[50:51]
	v_pk_add_f32 v[42:43], v[42:43], v[50:51] neg_lo:[0,1] neg_hi:[0,1]
	s_nop 0
	v_pk_mul_f32 v[50:51], v[42:43], s[70:71] op_sel_hi:[1,0]
	v_xor_b32_e32 v107, 0x80000000, v42
	v_mov_b32_e32 v106, v43
	v_pk_fma_f32 v[42:43], v[106:107], s[70:71], v[50:51] op_sel_hi:[1,0,1] neg_lo:[0,0,1] neg_hi:[0,0,1]
	v_pk_add_f32 v[50:51], v[100:101], v[28:29]
	v_pk_add_f32 v[28:29], v[100:101], v[28:29] neg_lo:[0,1] neg_hi:[0,1]
	v_pk_add_f32 v[100:101], v[88:89], v[12:13]
	v_pk_add_f32 v[12:13], v[88:89], v[12:13] neg_lo:[0,1] neg_hi:[0,1]
	s_nop 0
	v_pk_mul_f32 v[88:89], v[12:13], s[70:71] op_sel:[1,0] op_sel_hi:[0,0] neg_hi:[1,0]
	s_nop 0
	v_pk_fma_f32 v[12:13], v[12:13], s[70:71], v[88:89] op_sel_hi:[1,0,1]
	v_pk_add_f32 v[88:89], v[24:25], v[32:33]
	v_pk_add_f32 v[24:25], v[24:25], v[32:33] neg_lo:[0,1] neg_hi:[0,1]
	v_pk_add_f32 v[108:109], v[50:51], v[88:89]
	v_xor_b32_e32 v33, 0x80000000, v24
	v_mov_b32_e32 v32, v25
	v_pk_add_f32 v[24:25], v[26:27], v[34:35]
	v_pk_add_f32 v[26:27], v[26:27], v[34:35] neg_lo:[0,1] neg_hi:[0,1]
	v_pk_add_f32 v[50:51], v[50:51], v[88:89] neg_lo:[0,1] neg_hi:[0,1]
	v_pk_mul_f32 v[34:35], v[26:27], s[70:71] op_sel_hi:[1,0]
	v_xor_b32_e32 v107, 0x80000000, v26
	v_mov_b32_e32 v106, v27
	v_pk_fma_f32 v[26:27], v[106:107], s[70:71], v[34:35] op_sel_hi:[1,0,1] neg_lo:[0,0,1] neg_hi:[0,0,1]
	v_pk_add_f32 v[34:35], v[2:3], v[30:31]
	v_pk_add_f32 v[2:3], v[2:3], v[30:31] neg_lo:[0,1] neg_hi:[0,1]
	v_pk_add_f32 v[30:31], v[4:5], v[14:15]
	v_pk_add_f32 v[4:5], v[4:5], v[14:15] neg_lo:[0,1] neg_hi:[0,1]
	v_pk_add_f32 v[110:111], v[12:13], v[26:27]
	v_pk_mul_f32 v[14:15], v[4:5], s[70:71] op_sel:[1,0] op_sel_hi:[0,0] neg_hi:[1,0]
	v_pk_add_f32 v[12:13], v[12:13], v[26:27] neg_lo:[0,1] neg_hi:[0,1]
	v_pk_fma_f32 v[4:5], v[4:5], s[70:71], v[14:15] op_sel_hi:[1,0,1]
	v_pk_add_f32 v[14:15], v[6:7], v[16:17]
	v_pk_add_f32 v[6:7], v[6:7], v[16:17] neg_lo:[0,1] neg_hi:[0,1]
	v_pk_add_f32 v[88:89], v[100:101], v[24:25]
	v_xor_b32_e32 v17, 0x80000000, v6
	v_mov_b32_e32 v16, v7
	v_pk_add_f32 v[6:7], v[8:9], v[20:21]
	v_pk_add_f32 v[8:9], v[8:9], v[20:21] neg_lo:[0,1] neg_hi:[0,1]
	v_xor_b32_e32 v113, 0x80000000, v12
	v_pk_mul_f32 v[20:21], v[8:9], s[70:71] op_sel_hi:[1,0]
	s_nop 0
	v_pk_fma_f32 v[8:9], v[8:9], s[70:71], v[20:21] op_sel:[1,0,0] op_sel_hi:[0,0,1] neg_lo:[0,0,1] neg_hi:[1,0,1]
	v_pk_add_f32 v[20:21], v[36:37], v[104:105]
	v_pk_add_f32 v[36:37], v[36:37], v[104:105] neg_lo:[0,1] neg_hi:[0,1]
	v_pk_add_f32 v[104:105], v[102:103], v[38:39]
	v_pk_add_f32 v[38:39], v[102:103], v[38:39] neg_lo:[0,1] neg_hi:[0,1]
	v_pk_add_f32 v[106:107], v[52:53], v[48:49]
	v_xor_b32_e32 v103, 0x80000000, v38
	v_mov_b32_e32 v102, v39
	v_pk_add_f32 v[38:39], v[92:93], v[96:97]
	v_pk_add_f32 v[92:93], v[92:93], v[96:97] neg_lo:[0,1] neg_hi:[0,1]
	v_pk_add_f32 v[96:97], v[44:45], v[90:91]
	v_pk_add_f32 v[44:45], v[44:45], v[90:91] neg_lo:[0,1] neg_hi:[0,1]
	v_pk_add_f32 v[48:49], v[52:53], v[48:49] neg_lo:[0,1] neg_hi:[0,1]
	v_pk_add_f32 v[52:53], v[22:23], v[42:43]
	v_pk_add_f32 v[22:23], v[22:23], v[42:43] neg_lo:[0,1] neg_hi:[0,1]
	v_xor_b32_e32 v91, 0x80000000, v44
	v_mov_b32_e32 v90, v45
	v_pk_add_f32 v[44:45], v[98:99], v[46:47]
	v_pk_add_f32 v[46:47], v[98:99], v[46:47] neg_lo:[0,1] neg_hi:[0,1]
	v_pk_add_f32 v[98:99], v[94:95], v[40:41]
	v_pk_add_f32 v[40:41], v[94:95], v[40:41] neg_lo:[0,1] neg_hi:[0,1]
	v_xor_b32_e32 v43, 0x80000000, v22
	v_mov_b32_e32 v42, v23
	v_pk_add_f32 v[22:23], v[100:101], v[24:25] neg_lo:[0,1] neg_hi:[0,1]
	v_xor_b32_e32 v95, 0x80000000, v40
	v_mov_b32_e32 v94, v41
	v_xor_b32_e32 v25, 0x80000000, v22
	v_mov_b32_e32 v24, v23
	v_pk_add_f32 v[100:101], v[28:29], v[32:33]
	v_pk_add_f32 v[32:33], v[28:29], v[32:33] neg_lo:[0,1] neg_hi:[0,1]
	v_mov_b32_e32 v112, v13
	v_pk_add_f32 v[12:13], v[34:35], v[14:15]
	v_pk_add_f32 v[14:15], v[34:35], v[14:15] neg_lo:[0,1] neg_hi:[0,1]
	v_pk_add_f32 v[34:35], v[30:31], v[6:7]
	v_pk_add_f32 v[6:7], v[30:31], v[6:7] neg_lo:[0,1] neg_hi:[0,1]
	v_pk_add_f32 v[114:115], v[2:3], v[16:17]
	v_pk_add_f32 v[16:17], v[2:3], v[16:17] neg_lo:[0,1] neg_hi:[0,1]
	v_pk_add_f32 v[2:3], v[4:5], v[8:9] neg_lo:[0,1] neg_hi:[0,1]
	v_xor_b32_e32 v31, 0x80000000, v6
	v_mov_b32_e32 v30, v7
	v_pk_add_f32 v[116:117], v[4:5], v[8:9]
	v_xor_b32_e32 v119, 0x80000000, v2
	v_mov_b32_e32 v118, v3
	v_pk_add_f32 v[2:3], v[20:21], v[104:105]
	v_pk_add_f32 v[104:105], v[20:21], v[104:105] neg_lo:[0,1] neg_hi:[0,1]
	v_pk_add_f32 v[120:121], v[36:37], v[102:103]
	v_pk_add_f32 v[26:27], v[36:37], v[102:103] neg_lo:[0,1] neg_hi:[0,1]
	v_pk_add_f32 v[36:37], v[38:39], v[96:97]
	v_pk_add_f32 v[40:41], v[38:39], v[96:97] neg_lo:[0,1] neg_hi:[0,1]
	v_pk_add_f32 v[96:97], v[92:93], v[90:91]
	v_pk_add_f32 v[6:7], v[92:93], v[90:91] neg_lo:[0,1] neg_hi:[0,1]
	v_pk_add_f32 v[20:21], v[44:45], v[98:99]
	v_pk_add_f32 v[90:91], v[44:45], v[98:99] neg_lo:[0,1] neg_hi:[0,1]
	v_pk_add_f32 v[92:93], v[46:47], v[94:95]
	v_pk_add_f32 v[22:23], v[46:47], v[94:95] neg_lo:[0,1] neg_hi:[0,1]
	v_pk_add_f32 v[46:47], v[106:107], v[52:53]
	v_pk_add_f32 v[38:39], v[106:107], v[52:53] neg_lo:[0,1] neg_hi:[0,1]
	v_pk_add_f32 v[52:53], v[50:51], v[24:25]
	v_pk_add_f32 v[28:29], v[50:51], v[24:25] neg_lo:[0,1] neg_hi:[0,1]
	v_pk_add_f32 v[50:51], v[100:101], v[110:111]
	v_pk_add_f32 v[44:45], v[100:101], v[110:111] neg_lo:[0,1] neg_hi:[0,1]
	v_pk_add_f32 v[98:99], v[32:33], v[112:113]
	v_pk_add_f32 v[8:9], v[32:33], v[112:113] neg_lo:[0,1] neg_hi:[0,1]
	v_pk_add_f32 v[32:33], v[12:13], v[34:35]
	v_pk_add_f32 v[100:101], v[12:13], v[34:35] neg_lo:[0,1] neg_hi:[0,1]
	v_cos_f32_e32 v12, v10
	v_sin_f32_e32 v13, v10
	v_pk_add_f32 v[94:95], v[48:49], v[42:43]
	v_pk_add_f32 v[4:5], v[48:49], v[42:43] neg_lo:[0,1] neg_hi:[0,1]
	v_pk_add_f32 v[48:49], v[108:109], v[88:89]
	v_pk_add_f32 v[102:103], v[14:15], v[30:31]
	v_pk_add_f32 v[24:25], v[14:15], v[30:31] neg_lo:[0,1] neg_hi:[0,1]
	v_pk_add_f32 v[106:107], v[16:17], v[118:119]
	v_pk_add_f32 v[10:11], v[16:17], v[118:119] neg_lo:[0,1] neg_hi:[0,1]
	v_pk_mul_f32 v[14:15], v[12:13], v[12:13]
	v_add_f32_e32 v16, v12, v12
	v_pk_add_f32 v[88:89], v[108:109], v[88:89] neg_lo:[0,1] neg_hi:[0,1]
	v_mul_f32_e32 v18, v13, v16
	v_pk_add_f32 v[16:17], v[14:15], v[14:15] op_sel:[0,1] op_sel_hi:[0,1] neg_lo:[0,1] neg_hi:[0,1]
	v_mov_b32_e32 v108, v13
	v_pk_mul_f32 v[14:15], v[12:13], v[18:19] op_sel:[1,0] op_sel_hi:[0,0] neg_lo:[1,0]
	v_pk_mul_f32 v[30:31], v[108:109], v[48:49] op_sel:[0,1] op_sel_hi:[0,0] neg_hi:[0,1]
	v_pk_fma_f32 v[14:15], v[12:13], v[16:17], v[14:15]
	v_pk_fma_f32 v[12:13], v[12:13], v[48:49], v[30:31] op_sel_hi:[0,1,1]
	v_pk_mul_f32 v[30:31], v[18:19], s[48:49] op_sel_hi:[0,1]
	v_pk_fma_f32 v[30:31], v[16:17], s[40:41], v[30:31]
	s_nop 0
	v_pk_mul_f32 v[48:49], v[30:31], v[20:21] op_sel:[1,1] op_sel_hi:[1,0] neg_hi:[0,1]
	s_nop 0
	v_pk_fma_f32 v[20:21], v[20:21], v[30:31], v[48:49] op_sel_hi:[1,0,1]
	v_pk_mul_f32 v[48:49], v[18:19], v[14:15] op_sel:[0,1] op_sel_hi:[0,0] neg_lo:[0,1]
	v_pk_mul_f32 v[108:109], v[14:15], v[32:33] op_sel:[1,1] op_sel_hi:[1,0] neg_hi:[0,1]
	v_pk_fma_f32 v[48:49], v[16:17], v[14:15], v[48:49]
	v_pk_fma_f32 v[14:15], v[14:15], v[32:33], v[108:109] op_sel_hi:[0,1,1]
	v_pk_mul_f32 v[32:33], v[18:19], v[30:31] op_sel:[0,1] op_sel_hi:[0,0] neg_lo:[0,1]
	v_pk_fma_f32 v[108:109], v[16:17], v[30:31], v[32:33]
	s_nop 0
	v_pk_mul_f32 v[30:31], v[36:37], v[108:109] op_sel:[1,1] op_sel_hi:[0,1] neg_hi:[1,0]
	v_pk_add_f32 v[34:35], v[114:115], v[116:117]
	v_pk_fma_f32 v[32:33], v[36:37], v[108:109], v[30:31] op_sel_hi:[1,0,1]
	v_pk_mul_f32 v[30:31], v[18:19], v[48:49] op_sel:[0,1] op_sel_hi:[0,0] neg_lo:[0,1]
	v_pk_fma_f32 v[110:111], v[16:17], v[48:49], v[30:31]
	v_pk_mul_f32 v[30:31], v[48:49], v[50:51] op_sel:[1,1] op_sel_hi:[1,0] neg_hi:[0,1]
	v_pk_mul_f32 v[36:37], v[18:19], v[108:109] op_sel:[0,1] op_sel_hi:[0,0] neg_lo:[0,1]
	v_pk_fma_f32 v[30:31], v[50:51], v[48:49], v[30:31] op_sel_hi:[1,0,1]
	v_pk_fma_f32 v[48:49], v[16:17], v[108:109], v[36:37]
	s_nop 0
	v_pk_mul_f32 v[36:37], v[46:47], v[48:49] op_sel:[1,1] op_sel_hi:[0,1] neg_hi:[1,0]
	s_nop 0
	v_pk_fma_f32 v[36:37], v[46:47], v[48:49], v[36:37] op_sel_hi:[1,0,1]
	v_pk_mul_f32 v[46:47], v[18:19], v[110:111] op_sel:[0,1] op_sel_hi:[0,0] neg_lo:[0,1]
	v_pk_mul_f32 v[50:51], v[110:111], v[34:35] op_sel:[1,1] op_sel_hi:[1,0] neg_hi:[0,1]
	v_pk_fma_f32 v[46:47], v[16:17], v[110:111], v[46:47]
	v_pk_fma_f32 v[34:35], v[34:35], v[110:111], v[50:51] op_sel_hi:[1,0,1]
	v_pk_mul_f32 v[50:51], v[18:19], v[48:49] op_sel:[0,1] op_sel_hi:[0,0] neg_lo:[0,1]
	s_nop 0
	v_pk_fma_f32 v[50:51], v[16:17], v[48:49], v[50:51]
	v_pk_mul_f32 v[108:109], v[18:19], v[46:47] op_sel:[0,1] op_sel_hi:[0,0] neg_lo:[0,1]
	v_pk_mul_f32 v[110:111], v[52:53], v[46:47] op_sel:[1,1] op_sel_hi:[0,1] neg_hi:[1,0]
	v_pk_fma_f32 v[108:109], v[16:17], v[46:47], v[108:109]
	v_pk_fma_f32 v[46:47], v[52:53], v[46:47], v[110:111] op_sel_hi:[1,0,1]
	v_pk_mul_f32 v[48:49], v[120:121], v[50:51] op_sel:[1,1] op_sel_hi:[0,1] neg_hi:[1,0]
	v_pk_mul_f32 v[52:53], v[18:19], v[50:51] op_sel:[0,1] op_sel_hi:[0,0] neg_lo:[0,1]
	v_pk_fma_f32 v[48:49], v[120:121], v[50:51], v[48:49] op_sel_hi:[1,0,1]
	v_pk_fma_f32 v[110:111], v[16:17], v[50:51], v[52:53]
	s_nop 0
	v_pk_mul_f32 v[50:51], v[92:93], v[110:111] op_sel:[1,1] op_sel_hi:[0,1] neg_hi:[1,0]
	v_pk_add_f32 v[42:43], v[114:115], v[116:117] neg_lo:[0,1] neg_hi:[0,1]
	v_pk_fma_f32 v[52:53], v[92:93], v[110:111], v[50:51] op_sel_hi:[1,0,1]
	v_pk_mul_f32 v[50:51], v[18:19], v[108:109] op_sel:[0,1] op_sel_hi:[0,0] neg_lo:[0,1]
	v_pk_fma_f32 v[92:93], v[16:17], v[108:109], v[50:51]
	v_pk_mul_f32 v[50:51], v[102:103], v[108:109] op_sel:[1,1] op_sel_hi:[0,1] neg_hi:[1,0]
	s_nop 0
	v_pk_fma_f32 v[50:51], v[102:103], v[108:109], v[50:51] op_sel_hi:[1,0,1]
	v_pk_mul_f32 v[102:103], v[18:19], v[110:111] op_sel:[0,1] op_sel_hi:[0,0] neg_lo:[0,1]
	v_pk_fma_f32 v[102:103], v[16:17], v[110:111], v[102:103]
	s_nop 0
	v_pk_mul_f32 v[108:109], v[96:97], v[102:103] op_sel:[1,1] op_sel_hi:[0,1] neg_hi:[1,0]
	s_nop 0
	v_pk_fma_f32 v[96:97], v[96:97], v[102:103], v[108:109] op_sel_hi:[1,0,1]
	v_pk_mul_f32 v[108:109], v[18:19], v[92:93] op_sel:[0,1] op_sel_hi:[0,0] neg_lo:[0,1]
	v_pk_mul_f32 v[110:111], v[98:99], v[92:93] op_sel:[1,1] op_sel_hi:[0,1] neg_hi:[1,0]
	v_pk_fma_f32 v[108:109], v[16:17], v[92:93], v[108:109]
	v_pk_fma_f32 v[92:93], v[98:99], v[92:93], v[110:111] op_sel_hi:[1,0,1]
	v_pk_mul_f32 v[98:99], v[18:19], v[102:103] op_sel:[0,1] op_sel_hi:[0,0] neg_lo:[0,1]
	v_pk_fma_f32 v[98:99], v[16:17], v[102:103], v[98:99]
	s_nop 0
	v_pk_mul_f32 v[102:103], v[94:95], v[98:99] op_sel:[1,1] op_sel_hi:[0,1] neg_hi:[1,0]
	s_nop 0
	v_pk_fma_f32 v[94:95], v[94:95], v[98:99], v[102:103] op_sel_hi:[1,0,1]
	v_pk_mul_f32 v[102:103], v[18:19], v[108:109] op_sel:[0,1] op_sel_hi:[0,0] neg_lo:[0,1]
	v_pk_mul_f32 v[110:111], v[106:107], v[108:109] op_sel:[1,1] op_sel_hi:[0,1] neg_hi:[1,0]
	v_pk_fma_f32 v[102:103], v[16:17], v[108:109], v[102:103]
	v_pk_fma_f32 v[106:107], v[106:107], v[108:109], v[110:111] op_sel_hi:[1,0,1]
	v_pk_mul_f32 v[108:109], v[18:19], v[98:99] op_sel:[0,1] op_sel_hi:[0,0] neg_lo:[0,1]
	v_pk_fma_f32 v[98:99], v[16:17], v[98:99], v[108:109]
	s_nop 0
	v_pk_mul_f32 v[108:109], v[104:105], v[98:99] op_sel:[1,1] op_sel_hi:[0,1] neg_hi:[1,0]
	s_nop 0
	v_pk_fma_f32 v[104:105], v[104:105], v[98:99], v[108:109] op_sel_hi:[1,0,1]
	v_pk_mul_f32 v[108:109], v[18:19], v[102:103] op_sel:[0,1] op_sel_hi:[0,0] neg_lo:[0,1]
	v_pk_mul_f32 v[110:111], v[88:89], v[102:103] op_sel:[1,1] op_sel_hi:[0,1] neg_hi:[1,0]
	v_pk_fma_f32 v[108:109], v[16:17], v[102:103], v[108:109]
	v_pk_fma_f32 v[88:89], v[88:89], v[102:103], v[110:111] op_sel_hi:[1,0,1]
	v_pk_mul_f32 v[102:103], v[18:19], v[98:99] op_sel:[0,1] op_sel_hi:[0,0] neg_lo:[0,1]
	v_pk_fma_f32 v[98:99], v[16:17], v[98:99], v[102:103]
	s_nop 0
	v_pk_mul_f32 v[102:103], v[90:91], v[98:99] op_sel:[1,1] op_sel_hi:[0,1] neg_hi:[1,0]
	s_nop 0
	v_pk_fma_f32 v[90:91], v[90:91], v[98:99], v[102:103] op_sel_hi:[1,0,1]
	v_pk_mul_f32 v[102:103], v[18:19], v[108:109] op_sel:[0,1] op_sel_hi:[0,0] neg_lo:[0,1]
	v_pk_mul_f32 v[110:111], v[100:101], v[108:109] op_sel:[1,1] op_sel_hi:[0,1] neg_hi:[1,0]
	v_pk_fma_f32 v[102:103], v[16:17], v[108:109], v[102:103]
	v_pk_fma_f32 v[100:101], v[100:101], v[108:109], v[110:111] op_sel_hi:[1,0,1]
	v_pk_mul_f32 v[108:109], v[18:19], v[98:99] op_sel:[0,1] op_sel_hi:[0,0] neg_lo:[0,1]
	v_pk_fma_f32 v[98:99], v[16:17], v[98:99], v[108:109]
	s_nop 0
	v_pk_mul_f32 v[108:109], v[40:41], v[98:99] op_sel:[1,1] op_sel_hi:[0,1] neg_hi:[1,0]
	s_nop 0
	v_pk_fma_f32 v[40:41], v[40:41], v[98:99], v[108:109] op_sel_hi:[1,0,1]
	v_pk_mul_f32 v[108:109], v[18:19], v[102:103] op_sel:[0,1] op_sel_hi:[0,0] neg_lo:[0,1]
	v_pk_mul_f32 v[110:111], v[44:45], v[102:103] op_sel:[1,1] op_sel_hi:[0,1] neg_hi:[1,0]
	v_pk_fma_f32 v[108:109], v[16:17], v[102:103], v[108:109]
	v_pk_fma_f32 v[44:45], v[44:45], v[102:103], v[110:111] op_sel_hi:[1,0,1]
	v_pk_mul_f32 v[102:103], v[18:19], v[98:99] op_sel:[0,1] op_sel_hi:[0,0] neg_lo:[0,1]
	v_pk_fma_f32 v[98:99], v[16:17], v[98:99], v[102:103]
	s_nop 0
	v_pk_mul_f32 v[102:103], v[38:39], v[98:99] op_sel:[1,1] op_sel_hi:[0,1] neg_hi:[1,0]
	s_nop 0
	v_pk_fma_f32 v[38:39], v[38:39], v[98:99], v[102:103] op_sel_hi:[1,0,1]
	v_pk_mul_f32 v[102:103], v[18:19], v[108:109] op_sel:[0,1] op_sel_hi:[0,0] neg_lo:[0,1]
	v_pk_mul_f32 v[110:111], v[42:43], v[108:109] op_sel:[1,1] op_sel_hi:[0,1] neg_hi:[1,0]
	v_pk_fma_f32 v[102:103], v[16:17], v[108:109], v[102:103]
	v_pk_fma_f32 v[42:43], v[42:43], v[108:109], v[110:111] op_sel_hi:[1,0,1]
	v_pk_mul_f32 v[108:109], v[18:19], v[98:99] op_sel:[0,1] op_sel_hi:[0,0] neg_lo:[0,1]
	v_pk_fma_f32 v[98:99], v[16:17], v[98:99], v[108:109]
	s_nop 0
	v_pk_mul_f32 v[108:109], v[26:27], v[98:99] op_sel:[1,1] op_sel_hi:[0,1] neg_hi:[1,0]
	s_nop 0
	v_pk_fma_f32 v[26:27], v[26:27], v[98:99], v[108:109] op_sel_hi:[1,0,1]
	v_pk_mul_f32 v[108:109], v[18:19], v[102:103] op_sel:[0,1] op_sel_hi:[0,0] neg_lo:[0,1]
	v_pk_mul_f32 v[110:111], v[28:29], v[102:103] op_sel:[1,1] op_sel_hi:[0,1] neg_hi:[1,0]
	v_pk_fma_f32 v[108:109], v[16:17], v[102:103], v[108:109]
	v_pk_fma_f32 v[28:29], v[28:29], v[102:103], v[110:111] op_sel_hi:[1,0,1]
	v_pk_mul_f32 v[102:103], v[18:19], v[98:99] op_sel:[0,1] op_sel_hi:[0,0] neg_lo:[0,1]
	v_pk_fma_f32 v[98:99], v[16:17], v[98:99], v[102:103]
	s_nop 0
	v_pk_mul_f32 v[102:103], v[22:23], v[98:99] op_sel:[1,1] op_sel_hi:[0,1] neg_hi:[1,0]
	s_nop 0
	v_pk_fma_f32 v[22:23], v[22:23], v[98:99], v[102:103] op_sel_hi:[1,0,1]
	v_pk_mul_f32 v[102:103], v[18:19], v[108:109] op_sel:[0,1] op_sel_hi:[0,0] neg_lo:[0,1]
	v_pk_mul_f32 v[110:111], v[24:25], v[108:109] op_sel:[1,1] op_sel_hi:[0,1] neg_hi:[1,0]
	v_pk_fma_f32 v[102:103], v[16:17], v[108:109], v[102:103]
	v_pk_fma_f32 v[24:25], v[24:25], v[108:109], v[110:111] op_sel_hi:[1,0,1]
	v_pk_mul_f32 v[108:109], v[18:19], v[98:99] op_sel:[0,1] op_sel_hi:[0,0] neg_lo:[0,1]
	v_pk_fma_f32 v[98:99], v[16:17], v[98:99], v[108:109]
	s_nop 0
	v_pk_mul_f32 v[108:109], v[6:7], v[98:99] op_sel:[1,1] op_sel_hi:[0,1] neg_hi:[1,0]
	s_nop 0
	v_pk_fma_f32 v[6:7], v[6:7], v[98:99], v[108:109] op_sel_hi:[1,0,1]
	v_pk_mul_f32 v[108:109], v[18:19], v[102:103] op_sel:[0,1] op_sel_hi:[0,0] neg_lo:[0,1]
	v_pk_mul_f32 v[110:111], v[8:9], v[102:103] op_sel:[1,1] op_sel_hi:[0,1] neg_hi:[1,0]
	v_pk_fma_f32 v[108:109], v[16:17], v[102:103], v[108:109]
	v_pk_fma_f32 v[8:9], v[8:9], v[102:103], v[110:111] op_sel_hi:[1,0,1]
	v_pk_mul_f32 v[102:103], v[18:19], v[98:99] op_sel:[0,1] op_sel_hi:[0,0] neg_lo:[0,1]
	v_pk_fma_f32 v[16:17], v[16:17], v[98:99], v[102:103]
	s_nop 0
	v_pk_mul_f32 v[98:99], v[4:5], v[16:17] op_sel:[1,1] op_sel_hi:[0,1] neg_hi:[1,0]
	s_nop 0
	v_pk_fma_f32 v[4:5], v[4:5], v[16:17], v[98:99] op_sel_hi:[1,0,1]
	v_pk_mul_f32 v[16:17], v[10:11], v[108:109] op_sel:[1,1] op_sel_hi:[0,1] neg_hi:[1,0]
	s_nop 0
	v_pk_fma_f32 v[10:11], v[10:11], v[108:109], v[16:17] op_sel_hi:[1,0,1]
	ds_write_b64 v19, v[2:3]
	ds_write_b64 v54, v[104:105]
	ds_write_b64 v55, v[48:49] offset:256
	ds_write_b64 v56, v[26:27] offset:256
	ds_write_b64 v57, v[32:33] offset:512
	ds_write_b64 v58, v[40:41] offset:512
	ds_write_b64 v59, v[96:97] offset:768
	ds_write_b64 v60, v[6:7] offset:768
	ds_write_b64 v61, v[20:21] offset:1024
	ds_write_b64 v62, v[90:91] offset:1024
	ds_write_b64 v63, v[52:53] offset:1280
	ds_write_b64 v64, v[22:23] offset:1280
	ds_write_b64 v65, v[36:37] offset:1536
	ds_write_b64 v66, v[38:39] offset:1536
	ds_write_b64 v67, v[94:95] offset:1792
	ds_write_b64 v71, v[4:5] offset:1792
	ds_write_b64 v72, v[12:13] offset:2048
	ds_write_b64 v73, v[88:89] offset:2048
	ds_write_b64 v74, v[46:47] offset:2304
	ds_write_b64 v75, v[28:29] offset:2304
	ds_write_b64 v76, v[30:31] offset:2560
	ds_write_b64 v77, v[44:45] offset:2560
	ds_write_b64 v78, v[92:93] offset:2816
	ds_write_b64 v79, v[8:9] offset:2816
	ds_write_b64 v80, v[14:15] offset:3072
	ds_write_b64 v81, v[100:101] offset:3072
	ds_write_b64 v82, v[50:51] offset:3328
	ds_write_b64 v83, v[24:25] offset:3328
	ds_write_b64 v84, v[34:35] offset:3584
	ds_write_b64 v85, v[42:43] offset:3584
	ds_write_b64 v86, v[106:107] offset:3840
	ds_write_b64 v87, v[10:11] offset:3840
	v_mov_b32_e32 v2, v146
	s_waitcnt lgkmcnt(0)
	s_barrier
	s_nop 0
	v_lshlrev_b32_e32 v34, 4, v2
	v_lshrrev_b32_e32 v35, 1, v2
	v_bitop3_b32 v3, v35, v34, 16 bitop3:0x6c
	v_lshl_add_u32 v26, v3, 3, 16
	v_bitop3_b32 v3, v35, 1, 15 bitop3:0x6c
	v_bitop3_b32 v11, v35, 5, 15 bitop3:0x6c
	v_bitop3_b32 v19, v35, 9, 15 bitop3:0x6c
	v_lshlrev_b32_e32 v37, 3, v3
	v_bitop3_b32 v3, v35, 2, 15 bitop3:0x6c
	v_lshlrev_b32_e32 v45, 3, v11
	v_bitop3_b32 v11, v35, 6, 15 bitop3:0x6c
	v_lshlrev_b32_e32 v49, 3, v19
	v_bitop3_b32 v19, v35, 10, 15 bitop3:0x6c
	v_bitop3_b32 v29, v35, 14, 15 bitop3:0x6c
	v_add_u32_e32 v34, 0x2000, v34
	v_bfe_u32 v2, v2, 1, 4
	v_lshlrev_b32_e32 v38, 3, v3
	v_bitop3_b32 v3, v35, 3, 15 bitop3:0x6c
	v_bitop3_b32 v10, v35, 4, 15 bitop3:0x6c
	v_lshlrev_b32_e32 v46, 3, v11
	v_bitop3_b32 v11, v35, 7, 15 bitop3:0x6c
	v_bitop3_b32 v18, v35, 8, 15 bitop3:0x6c
	v_lshlrev_b32_e32 v50, 3, v19
	v_bitop3_b32 v19, v35, 11, 15 bitop3:0x6c
	v_bitop3_b32 v27, v35, 12, 15 bitop3:0x6c
	v_bitop3_b32 v28, v35, 13, 15 bitop3:0x6c
	v_lshlrev_b32_e32 v54, 3, v29
	v_bitop3_b32 v29, v35, 15, v35 bitop3:0xc
	v_bitop3_b32 v34, v34, v35, 16 bitop3:0x78
	v_lshlrev_b32_e32 v36, 3, v2
	v_lshlrev_b32_e32 v39, 3, v3
	v_lshlrev_b32_e32 v44, 3, v10
	v_lshlrev_b32_e32 v47, 3, v11
	v_lshlrev_b32_e32 v48, 3, v18
	v_lshlrev_b32_e32 v51, 3, v19
	v_lshlrev_b32_e32 v52, 3, v27
	v_lshlrev_b32_e32 v53, 3, v28
	v_lshlrev_b32_e32 v55, 3, v29
	v_lshl_add_u32 v34, v34, 3, 16
	v_add_u32_e32 v2, v26, v36
	v_add_u32_e32 v4, v26, v37
	v_add_u32_e32 v6, v26, v38
	v_add_u32_e32 v8, v26, v39
	v_add_u32_e32 v10, v26, v44
	v_add_u32_e32 v12, v26, v45
	v_add_u32_e32 v14, v26, v46
	v_add_u32_e32 v16, v26, v47
	v_add_u32_e32 v18, v26, v48
	v_add_u32_e32 v20, v26, v49
	v_add_u32_e32 v22, v26, v50
	v_add_u32_e32 v24, v26, v51
	v_add_u32_e32 v27, v26, v52
	v_add_u32_e32 v28, v26, v53
	v_add_u32_e32 v30, v26, v54
	v_add_u32_e32 v32, v26, v55
	v_add_u32_e32 v35, v34, v36
	v_add_u32_e32 v40, v34, v37
	v_add_u32_e32 v41, v34, v38
	v_add_u32_e32 v42, v34, v39
	ds_read_b64 v[2:3], v2
	ds_read_b64 v[4:5], v4
	ds_read_b64 v[6:7], v6
	ds_read_b64 v[8:9], v8
	ds_read_b64 v[10:11], v10
	ds_read_b64 v[12:13], v12
	ds_read_b64 v[14:15], v14
	ds_read_b64 v[16:17], v16
	ds_read_b64 v[18:19], v18
	ds_read_b64 v[20:21], v20
	ds_read_b64 v[22:23], v22
	ds_read_b64 v[24:25], v24
	ds_read_b64 v[26:27], v27
	ds_read_b64 v[28:29], v28
	ds_read_b64 v[30:31], v30
	ds_read_b64 v[32:33], v32
	ds_read_b64 v[36:37], v35
	ds_read_b64 v[38:39], v40
	ds_read_b64 v[40:41], v41
	ds_read_b64 v[42:43], v42
	v_add_u32_e32 v35, v34, v44
	v_add_u32_e32 v44, v34, v45
	v_add_u32_e32 v45, v34, v46
	v_add_u32_e32 v46, v34, v47
	ds_read_b64 v[72:73], v35
	ds_read_b64 v[74:75], v44
	ds_read_b64 v[76:77], v45
	ds_read_b64 v[78:79], v46
	v_add_u32_e32 v35, v34, v48
	v_add_u32_e32 v44, v34, v49
	v_add_u32_e32 v45, v34, v50
	v_add_u32_e32 v46, v34, v51
	ds_read_b64 v[80:81], v35
	ds_read_b64 v[82:83], v44
	ds_read_b64 v[84:85], v45
	ds_read_b64 v[86:87], v46
	v_add_u32_e32 v35, v34, v52
	v_add_u32_e32 v44, v34, v53
	v_add_u32_e32 v45, v34, v54
	v_add_u32_e32 v34, v34, v55
	ds_read_b64 v[88:89], v35
	ds_read_b64 v[90:91], v44
	ds_read_b64 v[92:93], v45
	ds_read_b64 v[94:95], v34
	s_waitcnt lgkmcnt(14)
	v_pk_add_f32 v[34:35], v[2:3], v[18:19]
	v_pk_add_f32 v[2:3], v[2:3], v[18:19] neg_lo:[0,1] neg_hi:[0,1]
	v_pk_add_f32 v[18:19], v[4:5], v[20:21]
	v_pk_add_f32 v[4:5], v[4:5], v[20:21] neg_lo:[0,1] neg_hi:[0,1]
	s_nop 0
	v_pk_mul_f32 v[20:21], v[4:5], s[62:63] op_sel:[1,0] op_sel_hi:[0,0] neg_hi:[1,0]
	s_nop 0
	v_pk_fma_f32 v[4:5], v[4:5], s[60:61], v[20:21] op_sel_hi:[1,0,1]
	v_pk_add_f32 v[20:21], v[6:7], v[22:23]
	v_pk_add_f32 v[6:7], v[6:7], v[22:23] neg_lo:[0,1] neg_hi:[0,1]
	s_nop 0
	v_pk_mul_f32 v[22:23], v[6:7], s[70:71] op_sel:[1,0] op_sel_hi:[0,0] neg_hi:[1,0]
	s_nop 0
	v_pk_fma_f32 v[6:7], v[6:7], s[70:71], v[22:23] op_sel_hi:[1,0,1]
	v_pk_add_f32 v[22:23], v[8:9], v[24:25]
	v_pk_add_f32 v[8:9], v[8:9], v[24:25] neg_lo:[0,1] neg_hi:[0,1]
	s_nop 0
	v_pk_mul_f32 v[24:25], v[8:9], s[60:61] op_sel:[1,0] op_sel_hi:[0,0] neg_hi:[1,0]
	s_nop 0
	v_pk_fma_f32 v[8:9], v[8:9], s[62:63], v[24:25] op_sel_hi:[1,0,1]
	v_pk_add_f32 v[24:25], v[10:11], v[26:27]
	v_pk_add_f32 v[10:11], v[10:11], v[26:27] neg_lo:[0,1] neg_hi:[0,1]
	s_nop 0
	v_xor_b32_e32 v27, 0x80000000, v10
	v_mov_b32_e32 v26, v11
	v_pk_add_f32 v[10:11], v[12:13], v[28:29]
	v_pk_add_f32 v[12:13], v[12:13], v[28:29] neg_lo:[0,1] neg_hi:[0,1]
	s_nop 0
	v_pk_mul_f32 v[28:29], v[12:13], s[62:63] op_sel_hi:[1,0]
	v_xor_b32_e32 v45, 0x80000000, v12
	v_mov_b32_e32 v44, v13
	v_pk_fma_f32 v[12:13], v[44:45], s[60:61], v[28:29] op_sel_hi:[1,0,1] neg_lo:[0,0,1] neg_hi:[0,0,1]
	v_pk_add_f32 v[28:29], v[14:15], v[30:31]
	v_pk_add_f32 v[14:15], v[14:15], v[30:31] neg_lo:[0,1] neg_hi:[0,1]
	s_nop 0
	v_pk_mul_f32 v[30:31], v[14:15], s[70:71] op_sel_hi:[1,0]
	v_xor_b32_e32 v45, 0x80000000, v14
	v_mov_b32_e32 v44, v15
	v_pk_fma_f32 v[14:15], v[44:45], s[70:71], v[30:31] op_sel_hi:[1,0,1] neg_lo:[0,0,1] neg_hi:[0,0,1]
	v_pk_add_f32 v[30:31], v[16:17], v[32:33]
	v_pk_add_f32 v[16:17], v[16:17], v[32:33] neg_lo:[0,1] neg_hi:[0,1]
	s_nop 0
	v_pk_mul_f32 v[32:33], v[16:17], s[60:61] op_sel_hi:[1,0]
	v_xor_b32_e32 v45, 0x80000000, v16
	v_mov_b32_e32 v44, v17
	v_pk_fma_f32 v[16:17], v[44:45], s[62:63], v[32:33] op_sel_hi:[1,0,1] neg_lo:[0,0,1] neg_hi:[0,0,1]
	v_pk_add_f32 v[32:33], v[34:35], v[24:25]
	v_pk_add_f32 v[24:25], v[34:35], v[24:25] neg_lo:[0,1] neg_hi:[0,1]
	v_pk_add_f32 v[34:35], v[18:19], v[10:11]
	v_pk_add_f32 v[10:11], v[18:19], v[10:11] neg_lo:[0,1] neg_hi:[0,1]
	s_nop 0
	v_pk_mul_f32 v[18:19], v[10:11], s[70:71] op_sel:[1,0] op_sel_hi:[0,0] neg_hi:[1,0]
	s_nop 0
	v_pk_fma_f32 v[10:11], v[10:11], s[70:71], v[18:19] op_sel_hi:[1,0,1]
	v_pk_add_f32 v[18:19], v[20:21], v[28:29]
	v_pk_add_f32 v[20:21], v[20:21], v[28:29] neg_lo:[0,1] neg_hi:[0,1]
	s_nop 0
	v_xor_b32_e32 v29, 0x80000000, v20
	v_mov_b32_e32 v28, v21
	v_pk_add_f32 v[20:21], v[22:23], v[30:31]
	v_pk_add_f32 v[22:23], v[22:23], v[30:31] neg_lo:[0,1] neg_hi:[0,1]
	s_nop 0
	v_pk_mul_f32 v[30:31], v[22:23], s[70:71] op_sel_hi:[1,0]
	v_xor_b32_e32 v45, 0x80000000, v22
	v_mov_b32_e32 v44, v23
	v_pk_fma_f32 v[22:23], v[44:45], s[70:71], v[30:31] op_sel_hi:[1,0,1] neg_lo:[0,0,1] neg_hi:[0,0,1]
	v_pk_add_f32 v[30:31], v[2:3], v[26:27]
	v_pk_add_f32 v[2:3], v[2:3], v[26:27] neg_lo:[0,1] neg_hi:[0,1]
	v_pk_add_f32 v[26:27], v[4:5], v[12:13]
	v_pk_add_f32 v[4:5], v[4:5], v[12:13] neg_lo:[0,1] neg_hi:[0,1]
	s_nop 0
	v_pk_mul_f32 v[12:13], v[4:5], s[70:71] op_sel:[1,0] op_sel_hi:[0,0] neg_hi:[1,0]
	s_nop 0
	v_pk_fma_f32 v[4:5], v[4:5], s[70:71], v[12:13] op_sel_hi:[1,0,1]
	v_pk_add_f32 v[12:13], v[6:7], v[14:15]
	v_pk_add_f32 v[6:7], v[6:7], v[14:15] neg_lo:[0,1] neg_hi:[0,1]
	s_nop 0
	v_xor_b32_e32 v15, 0x80000000, v6
	v_mov_b32_e32 v14, v7
	v_pk_add_f32 v[6:7], v[8:9], v[16:17]
	v_pk_add_f32 v[8:9], v[8:9], v[16:17] neg_lo:[0,1] neg_hi:[0,1]
	s_nop 0
	v_pk_mul_f32 v[16:17], v[8:9], s[70:71] op_sel_hi:[1,0]
	s_nop 0
	v_pk_fma_f32 v[8:9], v[8:9], s[70:71], v[16:17] op_sel:[1,0,0] op_sel_hi:[0,0,1] neg_lo:[0,0,1] neg_hi:[1,0,1]
	v_pk_add_f32 v[16:17], v[32:33], v[18:19]
	v_pk_add_f32 v[18:19], v[32:33], v[18:19] neg_lo:[0,1] neg_hi:[0,1]
	v_pk_add_f32 v[32:33], v[34:35], v[20:21]
	v_pk_add_f32 v[20:21], v[34:35], v[20:21] neg_lo:[0,1] neg_hi:[0,1]
	v_pk_add_f32 v[66:67], v[16:17], v[32:33]
	v_xor_b32_e32 v35, 0x80000000, v20
	v_mov_b32_e32 v34, v21
	v_pk_add_f32 v[20:21], v[24:25], v[28:29]
	v_pk_add_f32 v[24:25], v[24:25], v[28:29] neg_lo:[0,1] neg_hi:[0,1]
	v_pk_add_f32 v[28:29], v[10:11], v[22:23]
	v_pk_add_f32 v[10:11], v[10:11], v[22:23] neg_lo:[0,1] neg_hi:[0,1]
	v_pk_add_f32 v[58:59], v[20:21], v[28:29]
	v_xor_b32_e32 v23, 0x80000000, v10
	v_mov_b32_e32 v22, v11
	v_pk_add_f32 v[10:11], v[30:31], v[12:13]
	v_pk_add_f32 v[12:13], v[30:31], v[12:13] neg_lo:[0,1] neg_hi:[0,1]
	v_pk_add_f32 v[30:31], v[26:27], v[6:7]
	v_pk_add_f32 v[6:7], v[26:27], v[6:7] neg_lo:[0,1] neg_hi:[0,1]
	v_pk_add_f32 v[54:55], v[24:25], v[22:23]
	v_xor_b32_e32 v27, 0x80000000, v6
	v_mov_b32_e32 v26, v7
	v_pk_add_f32 v[6:7], v[2:3], v[14:15]
	v_pk_add_f32 v[2:3], v[2:3], v[14:15] neg_lo:[0,1] neg_hi:[0,1]
	v_pk_add_f32 v[14:15], v[4:5], v[8:9]
	v_pk_add_f32 v[4:5], v[4:5], v[8:9] neg_lo:[0,1] neg_hi:[0,1]
	v_pk_add_f32 v[52:53], v[24:25], v[22:23] neg_lo:[0,1] neg_hi:[0,1]
	v_pk_add_f32 v[50:51], v[10:11], v[30:31]
	v_pk_add_f32 v[48:49], v[10:11], v[30:31] neg_lo:[0,1] neg_hi:[0,1]
	v_pk_add_f32 v[46:47], v[12:13], v[26:27]
	v_pk_add_f32 v[44:45], v[12:13], v[26:27] neg_lo:[0,1] neg_hi:[0,1]
	v_pk_add_f32 v[30:31], v[2:3], v[4:5] op_sel:[0,1] op_sel_hi:[1,0] neg_hi:[0,1]
	v_pk_add_f32 v[26:27], v[2:3], v[4:5] op_sel:[0,1] op_sel_hi:[1,0] neg_lo:[0,1]
	s_waitcnt lgkmcnt(6)
	v_pk_add_f32 v[8:9], v[38:39], v[82:83] neg_lo:[0,1] neg_hi:[0,1]
	s_waitcnt lgkmcnt(2)
	v_pk_add_f32 v[24:25], v[74:75], v[90:91] neg_lo:[0,1] neg_hi:[0,1]
	v_pk_add_f32 v[56:57], v[20:21], v[28:29] neg_lo:[0,1] neg_hi:[0,1]
	v_pk_add_f32 v[2:3], v[36:37], v[80:81]
	v_pk_add_f32 v[4:5], v[36:37], v[80:81] neg_lo:[0,1] neg_hi:[0,1]
	v_pk_mul_f32 v[28:29], v[24:25], s[62:63] op_sel_hi:[1,0]
	v_pk_add_f32 v[64:65], v[16:17], v[32:33] neg_lo:[0,1] neg_hi:[0,1]
	v_pk_mul_f32 v[10:11], v[8:9], s[62:63] op_sel:[1,0] op_sel_hi:[0,0] neg_hi:[1,0]
	v_pk_add_f32 v[12:13], v[40:41], v[84:85] neg_lo:[0,1] neg_hi:[0,1]
	v_pk_add_f32 v[16:17], v[42:43], v[86:87] neg_lo:[0,1] neg_hi:[0,1]
	v_pk_fma_f32 v[24:25], v[24:25], s[60:61], v[28:29] op_sel:[1,0,0] op_sel_hi:[0,0,1] neg_lo:[0,0,1] neg_hi:[1,0,1]
	s_waitcnt lgkmcnt(1)
	v_pk_add_f32 v[36:37], v[76:77], v[92:93] neg_lo:[0,1] neg_hi:[0,1]
	v_pk_add_f32 v[62:63], v[18:19], v[34:35]
	v_pk_add_f32 v[60:61], v[18:19], v[34:35] neg_lo:[0,1] neg_hi:[0,1]
	v_pk_add_f32 v[34:35], v[6:7], v[14:15]
	v_pk_add_f32 v[32:33], v[6:7], v[14:15] neg_lo:[0,1] neg_hi:[0,1]
	v_pk_add_f32 v[6:7], v[38:39], v[82:83]
	v_pk_fma_f32 v[8:9], v[8:9], s[60:61], v[10:11] op_sel_hi:[1,0,1]
	v_pk_add_f32 v[10:11], v[40:41], v[84:85]
	v_pk_mul_f32 v[38:39], v[36:37], s[70:71] op_sel_hi:[1,0]
	v_pk_mul_f32 v[14:15], v[12:13], s[70:71] op_sel:[1,0] op_sel_hi:[0,0] neg_hi:[1,0]
	v_pk_mul_f32 v[18:19], v[16:17], s[60:61] op_sel:[1,0] op_sel_hi:[0,0] neg_hi:[1,0]
	v_pk_add_f32 v[20:21], v[72:73], v[88:89] neg_lo:[0,1] neg_hi:[0,1]
	v_pk_fma_f32 v[36:37], v[36:37], s[70:71], v[38:39] op_sel:[1,0,0] op_sel_hi:[0,0,1] neg_lo:[0,0,1] neg_hi:[1,0,1]
	s_waitcnt lgkmcnt(0)
	v_pk_add_f32 v[40:41], v[78:79], v[94:95] neg_lo:[0,1] neg_hi:[0,1]
	v_pk_fma_f32 v[12:13], v[12:13], s[70:71], v[14:15] op_sel_hi:[1,0,1]
	v_pk_add_f32 v[14:15], v[42:43], v[86:87]
	v_pk_fma_f32 v[16:17], v[16:17], s[62:63], v[18:19] op_sel_hi:[1,0,1]
	v_pk_add_f32 v[18:19], v[72:73], v[88:89]
	v_xor_b32_e32 v23, 0x80000000, v20
	v_mov_b32_e32 v22, v21
	v_pk_add_f32 v[20:21], v[74:75], v[90:91]
	v_pk_mul_f32 v[42:43], v[40:41], s[60:61] op_sel_hi:[1,0]
	v_xor_b32_e32 v73, 0x80000000, v40
	v_mov_b32_e32 v72, v41
	v_pk_fma_f32 v[40:41], v[72:73], s[62:63], v[42:43] op_sel_hi:[1,0,1] neg_lo:[0,0,1] neg_hi:[0,0,1]
	v_pk_add_f32 v[42:43], v[2:3], v[18:19]
	v_pk_add_f32 v[2:3], v[2:3], v[18:19] neg_lo:[0,1] neg_hi:[0,1]
	v_pk_add_f32 v[18:19], v[6:7], v[20:21]
	v_pk_add_f32 v[6:7], v[6:7], v[20:21] neg_lo:[0,1] neg_hi:[0,1]
	v_pk_add_f32 v[28:29], v[76:77], v[92:93]
	v_pk_mul_f32 v[20:21], v[6:7], s[70:71] op_sel:[1,0] op_sel_hi:[0,0] neg_hi:[1,0]
	v_pk_add_f32 v[38:39], v[78:79], v[94:95]
	v_pk_fma_f32 v[6:7], v[6:7], s[70:71], v[20:21] op_sel_hi:[1,0,1]
	v_pk_add_f32 v[20:21], v[10:11], v[28:29]
	v_pk_add_f32 v[10:11], v[10:11], v[28:29] neg_lo:[0,1] neg_hi:[0,1]
	s_nop 0
	v_xor_b32_e32 v29, 0x80000000, v10
	v_mov_b32_e32 v28, v11
	v_pk_add_f32 v[10:11], v[14:15], v[38:39]
	v_pk_add_f32 v[14:15], v[14:15], v[38:39] neg_lo:[0,1] neg_hi:[0,1]
	s_nop 0
	v_pk_mul_f32 v[38:39], v[14:15], s[70:71] op_sel_hi:[1,0]
	v_xor_b32_e32 v73, 0x80000000, v14
	v_mov_b32_e32 v72, v15
	v_pk_fma_f32 v[14:15], v[72:73], s[70:71], v[38:39] op_sel_hi:[1,0,1] neg_lo:[0,0,1] neg_hi:[0,0,1]
	v_pk_add_f32 v[38:39], v[4:5], v[22:23]
	v_pk_add_f32 v[4:5], v[4:5], v[22:23] neg_lo:[0,1] neg_hi:[0,1]
	v_pk_add_f32 v[22:23], v[8:9], v[24:25]
	v_pk_add_f32 v[8:9], v[8:9], v[24:25] neg_lo:[0,1] neg_hi:[0,1]
	s_nop 0
	v_pk_mul_f32 v[24:25], v[8:9], s[70:71] op_sel:[1,0] op_sel_hi:[0,0] neg_hi:[1,0]
	s_nop 0
	v_pk_fma_f32 v[8:9], v[8:9], s[70:71], v[24:25] op_sel_hi:[1,0,1]
	v_pk_add_f32 v[24:25], v[12:13], v[36:37]
	v_pk_add_f32 v[12:13], v[12:13], v[36:37] neg_lo:[0,1] neg_hi:[0,1]
	v_pk_add_f32 v[74:75], v[38:39], v[24:25] neg_lo:[0,1] neg_hi:[0,1]
	v_xor_b32_e32 v37, 0x80000000, v12
	v_mov_b32_e32 v36, v13
	v_pk_add_f32 v[12:13], v[16:17], v[40:41]
	v_pk_add_f32 v[16:17], v[16:17], v[40:41] neg_lo:[0,1] neg_hi:[0,1]
	v_pk_add_f32 v[76:77], v[22:23], v[12:13]
	v_pk_mul_f32 v[40:41], v[16:17], s[70:71] op_sel_hi:[1,0]
	s_nop 0
	v_pk_fma_f32 v[16:17], v[16:17], s[70:71], v[40:41] op_sel:[1,0,0] op_sel_hi:[0,0,1] neg_lo:[0,0,1] neg_hi:[1,0,1]
	v_pk_add_f32 v[72:73], v[18:19], v[10:11]
	v_pk_add_f32 v[10:11], v[18:19], v[10:11] neg_lo:[0,1] neg_hi:[0,1]
	v_pk_add_f32 v[12:13], v[22:23], v[12:13] neg_lo:[0,1] neg_hi:[0,1]
	v_xor_b32_e32 v19, 0x80000000, v10
	v_mov_b32_e32 v18, v11
	v_pk_add_f32 v[10:11], v[2:3], v[28:29]
	v_pk_add_f32 v[2:3], v[2:3], v[28:29] neg_lo:[0,1] neg_hi:[0,1]
	v_pk_add_f32 v[28:29], v[6:7], v[14:15]
	v_pk_add_f32 v[6:7], v[6:7], v[14:15] neg_lo:[0,1] neg_hi:[0,1]
	v_pk_add_f32 v[22:23], v[10:11], v[28:29] neg_lo:[0,1] neg_hi:[0,1]
	v_xor_b32_e32 v15, 0x80000000, v6
	v_mov_b32_e32 v14, v7
	v_pk_add_f32 v[6:7], v[38:39], v[24:25]
	v_pk_add_f32 v[24:25], v[10:11], v[28:29]
	v_mov_b32_e32 v28, v146
	v_pk_add_f32 v[40:41], v[42:43], v[20:21]
	v_pk_add_f32 v[20:21], v[42:43], v[20:21] neg_lo:[0,1] neg_hi:[0,1]
	v_lshlrev_b32_e32 v71, 4, v28
	v_lshrrev_b32_e32 v29, 1, v28
	v_pk_add_f32 v[42:43], v[40:41], v[72:73]
	v_pk_add_f32 v[40:41], v[40:41], v[72:73] neg_lo:[0,1] neg_hi:[0,1]
	v_bfe_u32 v28, v28, 1, 4
	v_bitop3_b32 v72, v29, v71, 16 bitop3:0x6c
	v_lshl_add_u32 v72, v72, 3, 16
	v_lshlrev_b32_e32 v28, 3, v28
	v_add_u32_e32 v73, v72, v28
	ds_write_b64 v73, v[66:67]
	v_bitop3_b32 v73, v29, 1, 15 bitop3:0x6c
	v_xor_b32_e32 v79, 0x80000000, v12
	v_mov_b32_e32 v78, v13
	v_lshlrev_b32_e32 v73, 3, v73
	v_pk_add_f32 v[12:13], v[74:75], v[78:79]
	v_pk_add_f32 v[10:11], v[74:75], v[78:79] neg_lo:[0,1] neg_hi:[0,1]
	v_add_u32_e32 v74, v72, v73
	ds_write_b64 v74, v[64:65]
	v_bitop3_b32 v74, v29, 2, 15 bitop3:0x6c
	v_lshlrev_b32_e32 v74, 3, v74
	v_add_u32_e32 v75, v72, v74
	ds_write_b64 v75, v[62:63]
	v_bitop3_b32 v75, v29, 3, 15 bitop3:0x6c
	v_lshlrev_b32_e32 v75, 3, v75
	v_pk_add_f32 v[80:81], v[4:5], v[36:37]
	v_pk_add_f32 v[82:83], v[4:5], v[36:37] neg_lo:[0,1] neg_hi:[0,1]
	v_pk_add_f32 v[4:5], v[8:9], v[16:17]
	v_pk_add_f32 v[8:9], v[8:9], v[16:17] neg_lo:[0,1] neg_hi:[0,1]
	v_pk_add_f32 v[38:39], v[20:21], v[18:19]
	v_pk_add_f32 v[36:37], v[20:21], v[18:19] neg_lo:[0,1] neg_hi:[0,1]
	v_pk_add_f32 v[20:21], v[2:3], v[14:15]
	v_pk_add_f32 v[18:19], v[2:3], v[14:15] neg_lo:[0,1] neg_hi:[0,1]
	v_pk_add_f32 v[16:17], v[6:7], v[76:77]
	v_pk_add_f32 v[14:15], v[6:7], v[76:77] neg_lo:[0,1] neg_hi:[0,1]
	v_add_u32_e32 v76, v72, v75
	ds_write_b64 v76, v[60:61]
	v_bitop3_b32 v76, v29, 4, 15 bitop3:0x6c
	v_lshlrev_b32_e32 v76, 3, v76
	v_add_u32_e32 v77, v72, v76
	ds_write_b64 v77, v[58:59]
	v_bitop3_b32 v77, v29, 5, 15 bitop3:0x6c
	v_lshlrev_b32_e32 v77, 3, v77
	v_add_u32_e32 v78, v72, v77
	ds_write_b64 v78, v[56:57]
	v_bitop3_b32 v78, v29, 6, 15 bitop3:0x6c
	v_lshlrev_b32_e32 v78, 3, v78
	v_add_u32_e32 v79, v72, v78
	ds_write_b64 v79, v[54:55]
	v_bitop3_b32 v79, v29, 7, 15 bitop3:0x6c
	v_lshlrev_b32_e32 v79, 3, v79
	v_xor_b32_e32 v85, 0x80000000, v8
	v_mov_b32_e32 v84, v9
	v_pk_add_f32 v[8:9], v[80:81], v[4:5]
	v_pk_add_f32 v[6:7], v[80:81], v[4:5] neg_lo:[0,1] neg_hi:[0,1]
	v_add_u32_e32 v80, v72, v79
	ds_write_b64 v80, v[52:53]
	v_bitop3_b32 v80, v29, 8, 15 bitop3:0x6c
	v_lshlrev_b32_e32 v80, 3, v80
	v_add_u32_e32 v81, v72, v80
	ds_write_b64 v81, v[50:51]
	v_bitop3_b32 v81, v29, 9, 15 bitop3:0x6c
	v_lshlrev_b32_e32 v81, 3, v81
	v_pk_add_f32 v[4:5], v[82:83], v[84:85]
	v_pk_add_f32 v[2:3], v[82:83], v[84:85] neg_lo:[0,1] neg_hi:[0,1]
	v_add_u32_e32 v82, v72, v81
	ds_write_b64 v82, v[48:49]
	v_bitop3_b32 v82, v29, 10, 15 bitop3:0x6c
	v_lshlrev_b32_e32 v82, 3, v82
	v_add_u32_e32 v83, v72, v82
	ds_write_b64 v83, v[46:47]
	v_bitop3_b32 v83, v29, 11, 15 bitop3:0x6c
	v_lshlrev_b32_e32 v83, 3, v83
	v_add_u32_e32 v84, v72, v83
	ds_write_b64 v84, v[44:45]
	v_bitop3_b32 v84, v29, 12, 15 bitop3:0x6c
	v_lshlrev_b32_e32 v84, 3, v84
	v_add_u32_e32 v85, v72, v84
	ds_write_b64 v85, v[34:35]
	v_bitop3_b32 v85, v29, 13, 15 bitop3:0x6c
	v_lshlrev_b32_e32 v85, 3, v85
	v_add_u32_e32 v86, v72, v85
	ds_write_b64 v86, v[32:33]
	v_bitop3_b32 v86, v29, 14, 15 bitop3:0x6c
	v_lshlrev_b32_e32 v86, 3, v86
	v_add_u32_e32 v87, v72, v86
	v_add_u32_e32 v88, 0x2000, v71
	ds_write_b64 v87, v[30:31]
	v_bitop3_b32 v87, v29, 15, v29 bitop3:0xc
	v_bitop3_b32 v29, v88, v29, 16 bitop3:0x78
	v_lshlrev_b32_e32 v87, 3, v87
	v_lshl_add_u32 v29, v29, 3, 16
	v_add_u32_e32 v72, v72, v87
	v_add_u32_e32 v28, v29, v28
	ds_write_b64 v72, v[26:27]
	ds_write_b64 v28, v[42:43]
	v_add_u32_e32 v28, v29, v73
	ds_write_b64 v28, v[40:41]
	v_add_u32_e32 v28, v29, v74
	ds_write_b64 v28, v[38:39]
	v_add_u32_e32 v28, v29, v75
	ds_write_b64 v28, v[36:37]
	v_add_u32_e32 v28, v29, v76
	ds_write_b64 v28, v[24:25]
	v_add_u32_e32 v28, v29, v77
	ds_write_b64 v28, v[22:23]
	v_add_u32_e32 v28, v29, v78
	ds_write_b64 v28, v[20:21]
	v_add_u32_e32 v28, v29, v79
	ds_write_b64 v28, v[18:19]
	v_add_u32_e32 v28, v29, v80
	ds_write_b64 v28, v[16:17]
	v_add_u32_e32 v28, v29, v81
	ds_write_b64 v28, v[14:15]
	v_add_u32_e32 v28, v29, v82
	v_or_b32_e32 v72, 1, v71
	ds_write_b64 v28, v[12:13]
	v_add_u32_e32 v28, v29, v83
	v_bfrev_b32_e32 v72, v72
	ds_write_b64 v28, v[10:11]
	v_add_u32_e32 v28, v29, v84
	v_lshrrev_b32_e32 v72, 18, v72
	ds_write_b64 v28, v[8:9]
	v_add_u32_e32 v28, v29, v85
	v_sub_u32_e32 v72, 0, v72
	ds_write_b64 v28, v[6:7]
	v_add_u32_e32 v28, v29, v86
	v_and_b32_e32 v72, 0x3fff, v72
	ds_write_b64 v28, v[4:5]
	v_add_u32_e32 v28, v29, v87
	v_bfrev_b32_e32 v72, v72
	ds_write_b64 v28, v[2:3]
	v_lshl_add_u64 v[28:29], v[0:1], 2, s[0:1]
	v_bfrev_b32_e32 v0, v71
	v_lshrrev_b32_e32 v73, 18, v72
	v_lshrrev_b32_e32 v72, 23, v72
	v_lshrrev_b32_e32 v0, 18, v0
	v_bitop3_b32 v72, v72, v73, 31 bitop3:0x6c
	v_or_b32_e32 v73, 2, v71
	v_sub_u32_e32 v0, 0, v0
	v_bfrev_b32_e32 v73, v73
	v_and_b32_e32 v0, 0x3fff, v0
	v_lshrrev_b32_e32 v73, 18, v73
	v_bfrev_b32_e32 v0, v0
	v_sub_u32_e32 v73, 0, v73
	v_lshrrev_b32_e32 v1, 18, v0
	v_lshrrev_b32_e32 v0, 23, v0
	v_and_b32_e32 v74, 0x3fff, v73
	v_bitop3_b32 v0, v0, v1, 31 bitop3:0x6c
	v_bfrev_b32_e32 v74, v74
	v_and_b32_e32 v73, 0x1fff, v73
	v_lshl_add_u32 v0, v0, 3, 16
	v_lshrrev_b32_e32 v75, 18, v74
	v_lshrrev_b32_e32 v74, 23, v74
	v_bfrev_b32_e32 v73, v73
	s_waitcnt lgkmcnt(0)
	s_barrier
	ds_read_b64 v[0:1], v0
	v_bitop3_b32 v74, v74, v75, 31 bitop3:0x6c
	v_lshrrev_b32_e32 v75, 18, v73
	v_lshrrev_b32_e32 v73, 23, v73
	v_bitop3_b32 v73, v73, v75, 31 bitop3:0x6c
	v_lshl_add_u32 v72, v72, 3, 16
	v_lshl_add_u32 v74, v74, 3, 16
	v_lshl_add_u32 v76, v73, 3, 16
	ds_read_b64 v[72:73], v72
	ds_read_b64 v[74:75], v74
	ds_read_b64 v[76:77], v76
	s_waitcnt lgkmcnt(3)
	v_pk_add_f32 v[78:79], v[66:67], v[0:1]
	v_sub_f32_e32 v1, v67, v1
	v_sub_f32_e32 v0, v0, v66
	v_mul_f32_e32 v67, 0.5, v1
	v_mul_f32_e32 v66, 0.5, v0
	s_waitcnt lgkmcnt(2)
	v_pk_add_f32 v[0:1], v[64:65], v[72:73]
	v_mul_f32_e32 v78, 0.5, v78
	v_mul_f32_e32 v80, 0.5, v0
	v_sub_f32_e32 v0, v65, v73
	v_mul_f32_e32 v65, 0.5, v0
	v_sub_f32_e32 v0, v72, v64
	v_mul_f32_e32 v73, 0.5, v1
	v_mul_f32_e32 v64, 0.5, v0
	s_waitcnt lgkmcnt(1)
	v_pk_add_f32 v[0:1], v[62:63], v[74:75]
	s_mov_b32 s0, 0x10000
	v_mul_f32_e32 v72, 0.5, v0
	v_sub_f32_e32 v0, v63, v75
	v_mul_f32_e32 v75, 0.5, v0
	v_sub_f32_e32 v0, v74, v62
	v_mul_f32_e32 v81, 0.5, v1
	v_mul_f32_e32 v74, 0.5, v0
	s_waitcnt lgkmcnt(0)
	v_pk_add_f32 v[0:1], v[60:61], v[76:77]
	v_sub_f32_e32 v61, v61, v77
	v_mul_f32_e32 v0, 0.5, v0
	v_mul_f32_e32 v61, 0.5, v61
	v_sub_f32_e32 v60, v76, v60
	v_mul_f32_e32 v79, 0.5, v79
	v_mul_f32_e32 v1, 0.5, v1
	v_mul_f32_e32 v76, 0.5, v60
	v_cvt_pk_f16_f32 v63, v0, v61
	v_cvt_pk_f16_f32 v62, v72, v75
	v_cvt_pk_f16_f32 v61, v80, v65
	v_cvt_pk_f16_f32 v60, v78, v67
	v_add_co_u32_e32 v0, vcc, s0, v28
	global_store_dwordx4 v[28:29], v[60:63], off offset:-4096
	s_lshl_b64 s[0:1], s[68:69], 13
	s_add_u32 s92, s0, 0xc00000
	v_cvt_pk_f16_f32 v63, v1, v76
	v_cvt_pk_f16_f32 v62, v81, v74
	v_cvt_pk_f16_f32 v61, v73, v64
	v_cvt_pk_f16_f32 v60, v79, v66
	v_addc_co_u32_e32 v1, vcc, 0, v29, vcc
	global_store_dwordx4 v[0:1], v[60:63], off offset:-4096
	s_addc_u32 s93, s1, 0
	s_add_u32 s94, s56, s10
	v_or_b32_e32 v60, 4, v71
	v_bfrev_b32_e32 v60, v60
	v_lshrrev_b32_e32 v60, 18, v60
	v_sub_u32_e32 v62, 0, v60
	v_and_b32_e32 v63, 0x1fff, v62
	v_bfrev_b32_e32 v63, v63
	v_lshrrev_b32_e32 v64, 18, v63
	v_lshrrev_b32_e32 v63, 23, v63
	v_bitop3_b32 v63, v63, v64, 31 bitop3:0x6c
	v_or_b32_e32 v64, 6, v71
	v_bfrev_b32_e32 v64, v64
	v_and_b32_e32 v60, 0x3fff, v62
	v_lshrrev_b32_e32 v64, 18, v64
	v_bfrev_b32_e32 v60, v60
	v_sub_u32_e32 v64, 0, v64
	v_lshrrev_b32_e32 v61, 18, v60
	v_lshrrev_b32_e32 v60, 23, v60
	v_and_b32_e32 v64, 0x2fff, v64
	v_bitop3_b32 v60, v60, v61, 31 bitop3:0x6c
	v_bfrev_b32_e32 v64, v64
	v_and_b32_e32 v62, 0xfff, v62
	v_lshl_add_u32 v60, v60, 3, 16
	v_lshrrev_b32_e32 v65, 18, v64
	v_lshrrev_b32_e32 v64, 23, v64
	v_bfrev_b32_e32 v62, v62
	ds_read_b64 v[60:61], v60
	v_bitop3_b32 v64, v64, v65, 31 bitop3:0x6c
	v_lshrrev_b32_e32 v65, 18, v62
	v_lshrrev_b32_e32 v62, 23, v62
	v_bitop3_b32 v62, v62, v65, 31 bitop3:0x6c
	v_lshl_add_u32 v63, v63, 3, 16
	v_lshl_add_u32 v64, v64, 3, 16
	v_lshl_add_u32 v66, v62, 3, 16
	ds_read_b64 v[62:63], v63
	ds_read_b64 v[64:65], v64
	ds_read_b64 v[66:67], v66
	s_waitcnt lgkmcnt(3)
	v_pk_add_f32 v[72:73], v[58:59], v[60:61]
	v_sub_f32_e32 v59, v59, v61
	v_sub_f32_e32 v58, v60, v58
	v_mul_f32_e32 v61, 0.5, v59
	v_mul_f32_e32 v60, 0.5, v58
	s_waitcnt lgkmcnt(2)
	v_pk_add_f32 v[58:59], v[56:57], v[62:63]
	v_sub_f32_e32 v57, v57, v63
	v_sub_f32_e32 v56, v62, v56
	v_mul_f32_e32 v63, 0.5, v57
	v_mul_f32_e32 v62, 0.5, v56
	s_waitcnt lgkmcnt(1)
	v_pk_add_f32 v[56:57], v[54:55], v[64:65]
	v_sub_f32_e32 v55, v55, v65
	v_sub_f32_e32 v54, v64, v54
	v_mul_f32_e32 v65, 0.5, v55
	v_mul_f32_e32 v64, 0.5, v54
	s_waitcnt lgkmcnt(0)
	v_pk_add_f32 v[54:55], v[52:53], v[66:67]
	v_sub_f32_e32 v53, v53, v67
	v_mul_f32_e32 v72, 0.5, v72
	v_mul_f32_e32 v58, 0.5, v58
	v_mul_f32_e32 v56, 0.5, v56
	v_mul_f32_e32 v54, 0.5, v54
	v_mul_f32_e32 v53, 0.5, v53
	v_sub_f32_e32 v52, v66, v52
	v_mul_f32_e32 v73, 0.5, v73
	v_mul_f32_e32 v59, 0.5, v59
	v_mul_f32_e32 v57, 0.5, v57
	v_mul_f32_e32 v67, 0.5, v55
	v_mul_f32_e32 v66, 0.5, v52
	v_cvt_pk_f16_f32 v55, v54, v53
	v_cvt_pk_f16_f32 v54, v56, v65
	v_cvt_pk_f16_f32 v53, v58, v63
	v_cvt_pk_f16_f32 v52, v72, v61
	global_store_dwordx4 v[28:29], v[52:55], off offset:-3072
	s_addc_u32 s95, s57, s11
	s_lshl_b64 s[0:1], s[68:69], 14
	v_cvt_pk_f16_f32 v55, v67, v66
	v_cvt_pk_f16_f32 v54, v57, v64
	v_cvt_pk_f16_f32 v53, v59, v62
	v_cvt_pk_f16_f32 v52, v73, v60
	global_store_dwordx4 v[0:1], v[52:55], off offset:-3072
	s_add_u32 s12, s26, s0
	s_addc_u32 s13, s27, s1
	v_or_b32_e32 v52, 8, v71
	v_bfrev_b32_e32 v52, v52
	v_lshrrev_b32_e32 v52, 18, v52
	v_sub_u32_e32 v62, 0, v52
	v_and_b32_e32 v54, 0x1fff, v62
	v_bfrev_b32_e32 v54, v54
	v_lshrrev_b32_e32 v55, 18, v54
	v_lshrrev_b32_e32 v54, 23, v54
	v_bitop3_b32 v54, v54, v55, 31 bitop3:0x6c
	v_or_b32_e32 v55, 10, v71
	v_bfrev_b32_e32 v55, v55
	v_lshrrev_b32_e32 v55, 18, v55
	v_sub_u32_e32 v55, 0, v55
	v_and_b32_e32 v55, 0x2fff, v55
	v_and_b32_e32 v52, 0x3fff, v62
	v_bfrev_b32_e32 v55, v55
	v_bfrev_b32_e32 v52, v52
	v_lshrrev_b32_e32 v56, 18, v55
	v_lshrrev_b32_e32 v55, 23, v55
	v_lshrrev_b32_e32 v53, 18, v52
	v_lshrrev_b32_e32 v52, 23, v52
	v_bitop3_b32 v55, v55, v56, 31 bitop3:0x6c
	v_bitop3_b32 v52, v52, v53, 31 bitop3:0x6c
	v_lshl_add_u32 v56, v55, 3, 16
	v_and_b32_e32 v55, 0xfff, v62
	v_lshl_add_u32 v52, v52, 3, 16
	v_bfrev_b32_e32 v55, v55
	ds_read_b64 v[52:53], v52
	v_lshrrev_b32_e32 v57, 18, v55
	v_lshrrev_b32_e32 v55, 23, v55
	v_bitop3_b32 v55, v55, v57, 31 bitop3:0x6c
	v_lshl_add_u32 v54, v54, 3, 16
	v_lshl_add_u32 v58, v55, 3, 16
	ds_read_b64 v[54:55], v54
	ds_read_b64 v[56:57], v56
	ds_read_b64 v[58:59], v58
	s_waitcnt lgkmcnt(3)
	v_pk_add_f32 v[60:61], v[50:51], v[52:53]
	v_sub_f32_e32 v51, v51, v53
	v_sub_f32_e32 v50, v52, v50
	v_mul_f32_e32 v53, 0.5, v51
	v_mul_f32_e32 v52, 0.5, v50
	s_waitcnt lgkmcnt(2)
	v_pk_add_f32 v[50:51], v[48:49], v[54:55]
	v_sub_f32_e32 v49, v49, v55
	v_sub_f32_e32 v48, v54, v48
	v_mul_f32_e32 v55, 0.5, v49
	v_mul_f32_e32 v54, 0.5, v48
	s_waitcnt lgkmcnt(1)
	v_pk_add_f32 v[48:49], v[46:47], v[56:57]
	v_sub_f32_e32 v47, v47, v57
	v_sub_f32_e32 v46, v56, v46
	v_mul_f32_e32 v57, 0.5, v47
	v_mul_f32_e32 v56, 0.5, v46
	s_waitcnt lgkmcnt(0)
	v_pk_add_f32 v[46:47], v[44:45], v[58:59]
	v_sub_f32_e32 v45, v45, v59
	v_mul_f32_e32 v60, 0.5, v60
	v_mul_f32_e32 v50, 0.5, v50
	v_mul_f32_e32 v48, 0.5, v48
	v_mul_f32_e32 v46, 0.5, v46
	v_mul_f32_e32 v45, 0.5, v45
	v_sub_f32_e32 v44, v58, v44
	v_mul_f32_e32 v61, 0.5, v61
	v_mul_f32_e32 v51, 0.5, v51
	v_mul_f32_e32 v49, 0.5, v49
	v_mul_f32_e32 v59, 0.5, v47
	v_mul_f32_e32 v58, 0.5, v44
	v_cvt_pk_f16_f32 v47, v46, v45
	v_cvt_pk_f16_f32 v46, v48, v57
	v_cvt_pk_f16_f32 v45, v50, v55
	v_cvt_pk_f16_f32 v44, v60, v53
	global_store_dwordx4 v[28:29], v[44:47], off offset:-2048
	s_add_u32 s14, s30, s0
	s_addc_u32 s15, s31, s1
	v_cvt_pk_f16_f32 v47, v59, v58
	v_cvt_pk_f16_f32 v46, v49, v56
	v_cvt_pk_f16_f32 v45, v51, v54
	v_cvt_pk_f16_f32 v44, v61, v52
	global_store_dwordx4 v[0:1], v[44:47], off offset:-2048
	v_cmp_lt_i32_e32 vcc, s25, v146
	v_add_u32_e32 v55, 0xe00, v146
	v_or_b32_e32 v44, 12, v71
	v_bfrev_b32_e32 v44, v44
	v_lshrrev_b32_e32 v44, 18, v44
	v_sub_u32_e32 v46, 0, v44
	v_and_b32_e32 v44, 0x37ff, v46
	v_and_b32_e32 v46, 0x17ff, v46
	v_bfrev_b32_e32 v46, v46
	v_lshrrev_b32_e32 v47, 18, v46
	v_lshrrev_b32_e32 v46, 23, v46
	v_bitop3_b32 v46, v46, v47, 31 bitop3:0x6c
	v_or_b32_e32 v47, 14, v71
	v_bfrev_b32_e32 v47, v47
	v_lshrrev_b32_e32 v47, 18, v47
	v_sub_u32_e32 v47, 0, v47
	v_and_b32_e32 v47, 0x27ff, v47
	v_bfrev_b32_e32 v47, v47
	v_bfrev_b32_e32 v44, v44
	v_lshrrev_b32_e32 v48, 18, v47
	v_lshrrev_b32_e32 v47, 23, v47
	v_lshrrev_b32_e32 v45, 18, v44
	v_lshrrev_b32_e32 v44, 23, v44
	v_bitop3_b32 v47, v47, v48, 31 bitop3:0x6c
	v_bitop3_b32 v44, v44, v45, 31 bitop3:0x6c
	v_lshl_add_u32 v48, v47, 3, 16
	v_and_b32_e32 v47, 0x7ff, v62
	v_lshl_add_u32 v44, v44, 3, 16
	v_bfrev_b32_e32 v47, v47
	ds_read_b64 v[44:45], v44
	v_lshrrev_b32_e32 v49, 18, v47
	v_lshrrev_b32_e32 v47, 23, v47
	v_bitop3_b32 v47, v47, v49, 31 bitop3:0x6c
	v_lshl_add_u32 v46, v46, 3, 16
	v_lshl_add_u32 v50, v47, 3, 16
	ds_read_b64 v[46:47], v46
	ds_read_b64 v[48:49], v48
	ds_read_b64 v[50:51], v50
	s_waitcnt lgkmcnt(3)
	v_pk_add_f32 v[52:53], v[34:35], v[44:45]
	v_sub_f32_e32 v35, v35, v45
	v_sub_f32_e32 v34, v44, v34
	v_mul_f32_e32 v45, 0.5, v35
	v_mul_f32_e32 v44, 0.5, v34
	s_waitcnt lgkmcnt(2)
	v_pk_add_f32 v[34:35], v[32:33], v[46:47]
	v_sub_f32_e32 v33, v33, v47
	v_sub_f32_e32 v32, v46, v32
	v_mul_f32_e32 v47, 0.5, v33
	v_mul_f32_e32 v46, 0.5, v32
	s_waitcnt lgkmcnt(1)
	v_pk_add_f32 v[32:33], v[30:31], v[48:49]
	v_sub_f32_e32 v31, v31, v49
	v_sub_f32_e32 v30, v48, v30
	v_mul_f32_e32 v49, 0.5, v31
	v_mul_f32_e32 v48, 0.5, v30
	s_waitcnt lgkmcnt(0)
	v_pk_add_f32 v[30:31], v[26:27], v[50:51]
	v_sub_f32_e32 v27, v27, v51
	v_mul_f32_e32 v52, 0.5, v52
	v_mul_f32_e32 v34, 0.5, v34
	v_mul_f32_e32 v32, 0.5, v32
	v_mul_f32_e32 v30, 0.5, v30
	v_mul_f32_e32 v27, 0.5, v27
	v_sub_f32_e32 v26, v50, v26
	v_mul_f32_e32 v53, 0.5, v53
	v_mul_f32_e32 v35, 0.5, v35
	v_mul_f32_e32 v54, 0.5, v33
	v_mul_f32_e32 v51, 0.5, v31
	v_mul_f32_e32 v26, 0.5, v26
	v_cvt_pk_f16_f32 v33, v30, v27
	v_cvt_pk_f16_f32 v32, v32, v49
	v_cvt_pk_f16_f32 v31, v34, v47
	v_cvt_pk_f16_f32 v30, v52, v45
	global_store_dwordx4 v[28:29], v[30:33], off offset:-1024
	v_add_u32_e32 v52, 0x800, v146
	s_nop 0
	v_cvt_pk_f16_f32 v33, v51, v26
	v_cvt_pk_f16_f32 v32, v54, v48
	v_cvt_pk_f16_f32 v31, v35, v46
	v_cvt_pk_f16_f32 v30, v53, v44
	global_store_dwordx4 v[0:1], v[30:33], off offset:-1024
	v_bfrev_b32_e32 v26, v88
	v_lshrrev_b32_e32 v26, 18, v26
	v_add_u32_e32 v30, 0x2001, v71
	v_bfrev_b32_e32 v30, v30
	v_lshrrev_b32_e32 v30, 18, v30
	v_sub_u32_e32 v30, 0, v30
	v_and_b32_e32 v30, 0x3fff, v30
	v_bfrev_b32_e32 v30, v30
	v_lshrrev_b32_e32 v31, 18, v30
	v_lshrrev_b32_e32 v30, 23, v30
	v_bitop3_b32 v30, v30, v31, 31 bitop3:0x6c
	v_add_u32_e32 v31, 0x2002, v71
	v_bfrev_b32_e32 v31, v31
	v_lshrrev_b32_e32 v31, 18, v31
	v_sub_u32_e32 v31, 0, v31
	v_and_b32_e32 v31, 0x3fff, v31
	v_bfrev_b32_e32 v31, v31
	v_lshrrev_b32_e32 v32, 18, v31
	v_lshrrev_b32_e32 v31, 23, v31
	v_bitop3_b32 v31, v31, v32, 31 bitop3:0x6c
	v_sub_u32_e32 v26, 0, v26
	v_lshl_add_u32 v32, v31, 3, 16
	v_add_u32_e32 v31, 0x2003, v71
	v_and_b32_e32 v26, 0x3fff, v26
	v_bfrev_b32_e32 v31, v31
	v_bfrev_b32_e32 v26, v26
	v_lshrrev_b32_e32 v31, 18, v31
	v_lshrrev_b32_e32 v27, 18, v26
	v_lshrrev_b32_e32 v26, 23, v26
	v_sub_u32_e32 v31, 0, v31
	v_bitop3_b32 v26, v26, v27, 31 bitop3:0x6c
	v_and_b32_e32 v31, 0x1fff, v31
	v_lshl_add_u32 v26, v26, 3, 16
	v_bfrev_b32_e32 v31, v31
	ds_read_b64 v[26:27], v26
	v_lshrrev_b32_e32 v33, 18, v31
	v_lshrrev_b32_e32 v31, 23, v31
	v_bitop3_b32 v31, v31, v33, 31 bitop3:0x6c
	v_lshl_add_u32 v30, v30, 3, 16
	v_lshl_add_u32 v34, v31, 3, 16
	ds_read_b64 v[30:31], v30
	ds_read_b64 v[32:33], v32
	ds_read_b64 v[34:35], v34
	s_waitcnt lgkmcnt(3)
	v_pk_add_f32 v[44:45], v[42:43], v[26:27]
	v_sub_f32_e32 v27, v43, v27
	v_sub_f32_e32 v26, v26, v42
	v_mul_f32_e32 v43, 0.5, v27
	v_mul_f32_e32 v42, 0.5, v26
	s_waitcnt lgkmcnt(2)
	v_pk_add_f32 v[26:27], v[40:41], v[30:31]
	v_mul_f32_e32 v44, 0.5, v44
	v_mul_f32_e32 v46, 0.5, v26
	v_sub_f32_e32 v26, v41, v31
	v_mul_f32_e32 v31, 0.5, v26
	v_sub_f32_e32 v26, v30, v40
	v_mul_f32_e32 v41, 0.5, v27
	v_mul_f32_e32 v40, 0.5, v26
	s_waitcnt lgkmcnt(1)
	v_pk_add_f32 v[26:27], v[38:39], v[32:33]
	v_mul_f32_e32 v45, 0.5, v45
	v_mul_f32_e32 v30, 0.5, v26
	v_sub_f32_e32 v26, v39, v33
	v_mul_f32_e32 v39, 0.5, v26
	v_sub_f32_e32 v26, v32, v38
	v_mul_f32_e32 v47, 0.5, v27
	v_mul_f32_e32 v38, 0.5, v26
	s_waitcnt lgkmcnt(0)
	v_pk_add_f32 v[26:27], v[36:37], v[34:35]
	v_sub_f32_e32 v32, v37, v35
	v_mul_f32_e32 v26, 0.5, v26
	v_mul_f32_e32 v32, 0.5, v32
	v_sub_f32_e32 v33, v34, v36
	v_mul_f32_e32 v27, 0.5, v27
	v_mul_f32_e32 v34, 0.5, v33
	v_cvt_pk_f16_f32 v33, v26, v32
	v_cvt_pk_f16_f32 v32, v30, v39
	v_cvt_pk_f16_f32 v31, v46, v31
	v_cvt_pk_f16_f32 v30, v44, v43
	global_store_dwordx4 v[28:29], v[30:33], off
	v_add_u32_e32 v26, 0x2004, v71
	v_bfrev_b32_e32 v26, v26
	v_cvt_pk_f16_f32 v33, v27, v34
	v_cvt_pk_f16_f32 v32, v47, v38
	v_cvt_pk_f16_f32 v31, v41, v40
	v_cvt_pk_f16_f32 v30, v45, v42
	global_store_dwordx4 v[0:1], v[30:33], off
	v_lshrrev_b32_e32 v26, 18, v26
	v_sub_u32_e32 v26, 0, v26
	v_add_u32_e32 v30, 0x2005, v71
	v_bfrev_b32_e32 v30, v30
	v_lshrrev_b32_e32 v30, 18, v30
	v_sub_u32_e32 v30, 0, v30
	v_and_b32_e32 v30, 0x1fff, v30
	v_bfrev_b32_e32 v30, v30
	v_lshrrev_b32_e32 v31, 18, v30
	v_lshrrev_b32_e32 v30, 23, v30
	v_bitop3_b32 v30, v30, v31, 31 bitop3:0x6c
	v_add_u32_e32 v31, 0x2006, v71
	v_bfrev_b32_e32 v31, v31
	v_lshrrev_b32_e32 v31, 18, v31
	v_sub_u32_e32 v31, 0, v31
	v_and_b32_e32 v31, 0x2fff, v31
	v_bfrev_b32_e32 v31, v31
	v_lshrrev_b32_e32 v32, 18, v31
	v_lshrrev_b32_e32 v31, 23, v31
	v_bitop3_b32 v31, v31, v32, 31 bitop3:0x6c
	v_lshl_add_u32 v32, v31, 3, 16
	v_add_u32_e32 v31, 0x2007, v71
	v_and_b32_e32 v26, 0x3fff, v26
	v_bfrev_b32_e32 v31, v31
	v_bfrev_b32_e32 v26, v26
	v_lshrrev_b32_e32 v31, 18, v31
	v_lshrrev_b32_e32 v27, 18, v26
	v_lshrrev_b32_e32 v26, 23, v26
	v_sub_u32_e32 v31, 0, v31
	v_bitop3_b32 v26, v26, v27, 31 bitop3:0x6c
	v_and_b32_e32 v31, 0xfff, v31
	v_lshl_add_u32 v26, v26, 3, 16
	v_bfrev_b32_e32 v31, v31
	ds_read_b64 v[26:27], v26
	v_lshrrev_b32_e32 v33, 18, v31
	v_lshrrev_b32_e32 v31, 23, v31
	v_bitop3_b32 v31, v31, v33, 31 bitop3:0x6c
	v_lshl_add_u32 v30, v30, 3, 16
	v_lshl_add_u32 v34, v31, 3, 16
	ds_read_b64 v[30:31], v30
	ds_read_b64 v[32:33], v32
	ds_read_b64 v[34:35], v34
	s_waitcnt lgkmcnt(3)
	v_pk_add_f32 v[36:37], v[24:25], v[26:27]
	v_sub_f32_e32 v25, v25, v27
	v_sub_f32_e32 v24, v26, v24
	v_mul_f32_e32 v27, 0.5, v25
	v_mul_f32_e32 v26, 0.5, v24
	s_waitcnt lgkmcnt(2)
	v_pk_add_f32 v[24:25], v[22:23], v[30:31]
	v_sub_f32_e32 v23, v23, v31
	v_sub_f32_e32 v22, v30, v22
	v_mul_f32_e32 v31, 0.5, v23
	v_mul_f32_e32 v30, 0.5, v22
	s_waitcnt lgkmcnt(1)
	v_pk_add_f32 v[22:23], v[20:21], v[32:33]
	v_sub_f32_e32 v21, v21, v33
	v_sub_f32_e32 v20, v32, v20
	v_mul_f32_e32 v33, 0.5, v21
	v_mul_f32_e32 v32, 0.5, v20
	s_waitcnt lgkmcnt(0)
	v_pk_add_f32 v[20:21], v[18:19], v[34:35]
	v_sub_f32_e32 v19, v19, v35
	v_mul_f32_e32 v36, 0.5, v36
	v_mul_f32_e32 v24, 0.5, v24
	v_mul_f32_e32 v22, 0.5, v22
	v_mul_f32_e32 v20, 0.5, v20
	v_mul_f32_e32 v19, 0.5, v19
	v_sub_f32_e32 v18, v34, v18
	v_mul_f32_e32 v37, 0.5, v37
	v_mul_f32_e32 v25, 0.5, v25
	v_mul_f32_e32 v23, 0.5, v23
	v_mul_f32_e32 v35, 0.5, v21
	v_mul_f32_e32 v34, 0.5, v18
	v_cvt_pk_f16_f32 v21, v20, v19
	v_cvt_pk_f16_f32 v20, v22, v33
	v_cvt_pk_f16_f32 v19, v24, v31
	v_cvt_pk_f16_f32 v18, v36, v27
	global_store_dwordx4 v[28:29], v[18:21], off offset:1024
	v_add_u32_e32 v53, 0xa00, v146
	v_add_u32_e32 v54, 0xc00, v146
	v_cvt_pk_f16_f32 v21, v35, v34
	v_cvt_pk_f16_f32 v20, v23, v32
	v_cvt_pk_f16_f32 v19, v25, v30
	v_cvt_pk_f16_f32 v18, v37, v26
	global_store_dwordx4 v[0:1], v[18:21], off offset:1024
	v_add_u32_e32 v47, 0x1000, v146
	v_add_u32_e32 v46, 0x1200, v146
	v_add_u32_e32 v20, 0x2009, v71
	v_bfrev_b32_e32 v20, v20
	v_lshrrev_b32_e32 v20, 18, v20
	v_sub_u32_e32 v20, 0, v20
	v_and_b32_e32 v20, 0x1fff, v20
	v_bfrev_b32_e32 v20, v20
	v_lshrrev_b32_e32 v21, 18, v20
	v_lshrrev_b32_e32 v20, 23, v20
	v_bitop3_b32 v20, v20, v21, 31 bitop3:0x6c
	v_add_u32_e32 v21, 0x200a, v71
	v_bfrev_b32_e32 v21, v21
	v_lshrrev_b32_e32 v21, 18, v21
	v_sub_u32_e32 v21, 0, v21
	v_and_b32_e32 v21, 0x2fff, v21
	v_add_u32_e32 v18, 0x2008, v71
	v_bfrev_b32_e32 v21, v21
	v_bfrev_b32_e32 v18, v18
	v_lshrrev_b32_e32 v22, 18, v21
	v_lshrrev_b32_e32 v21, 23, v21
	v_lshrrev_b32_e32 v18, 18, v18
	v_bitop3_b32 v21, v21, v22, 31 bitop3:0x6c
	v_sub_u32_e32 v18, 0, v18
	v_lshl_add_u32 v22, v21, 3, 16
	v_add_u32_e32 v21, 0x200b, v71
	v_and_b32_e32 v18, 0x3fff, v18
	v_bfrev_b32_e32 v21, v21
	v_bfrev_b32_e32 v18, v18
	v_lshrrev_b32_e32 v21, 18, v21
	v_lshrrev_b32_e32 v19, 18, v18
	v_lshrrev_b32_e32 v18, 23, v18
	v_sub_u32_e32 v21, 0, v21
	v_bitop3_b32 v18, v18, v19, 31 bitop3:0x6c
	v_and_b32_e32 v21, 0xfff, v21
	v_lshl_add_u32 v18, v18, 3, 16
	v_bfrev_b32_e32 v21, v21
	ds_read_b64 v[18:19], v18
	v_lshrrev_b32_e32 v23, 18, v21
	v_lshrrev_b32_e32 v21, 23, v21
	v_bitop3_b32 v21, v21, v23, 31 bitop3:0x6c
	v_lshl_add_u32 v20, v20, 3, 16
	v_lshl_add_u32 v24, v21, 3, 16
	ds_read_b64 v[20:21], v20
	ds_read_b64 v[22:23], v22
	ds_read_b64 v[24:25], v24
	s_waitcnt lgkmcnt(3)
	v_pk_add_f32 v[26:27], v[16:17], v[18:19]
	v_sub_f32_e32 v17, v17, v19
	v_sub_f32_e32 v16, v18, v16
	v_mul_f32_e32 v19, 0.5, v17
	v_mul_f32_e32 v18, 0.5, v16
	s_waitcnt lgkmcnt(2)
	v_pk_add_f32 v[16:17], v[14:15], v[20:21]
	v_sub_f32_e32 v15, v15, v21
	v_sub_f32_e32 v14, v20, v14
	v_mul_f32_e32 v21, 0.5, v15
	v_mul_f32_e32 v20, 0.5, v14
	s_waitcnt lgkmcnt(1)
	v_pk_add_f32 v[14:15], v[12:13], v[22:23]
	v_sub_f32_e32 v13, v13, v23
	v_sub_f32_e32 v12, v22, v12
	v_mul_f32_e32 v23, 0.5, v13
	v_mul_f32_e32 v22, 0.5, v12
	s_waitcnt lgkmcnt(0)
	v_pk_add_f32 v[12:13], v[10:11], v[24:25]
	v_sub_f32_e32 v11, v11, v25
	v_mul_f32_e32 v26, 0.5, v26
	v_mul_f32_e32 v16, 0.5, v16
	v_mul_f32_e32 v14, 0.5, v14
	v_mul_f32_e32 v12, 0.5, v12
	v_mul_f32_e32 v11, 0.5, v11
	v_sub_f32_e32 v10, v24, v10
	v_mul_f32_e32 v27, 0.5, v27
	v_mul_f32_e32 v17, 0.5, v17
	v_mul_f32_e32 v15, 0.5, v15
	v_mul_f32_e32 v25, 0.5, v13
	v_mul_f32_e32 v24, 0.5, v10
	v_cvt_pk_f16_f32 v13, v12, v11
	v_cvt_pk_f16_f32 v12, v14, v23
	v_cvt_pk_f16_f32 v11, v16, v21
	v_cvt_pk_f16_f32 v10, v26, v19
	global_store_dwordx4 v[28:29], v[10:13], off offset:2048
	v_add_u32_e32 v26, 0x1600, v146
	s_nop 0
	v_cvt_pk_f16_f32 v13, v25, v24
	v_cvt_pk_f16_f32 v12, v15, v22
	v_cvt_pk_f16_f32 v11, v17, v20
	v_cvt_pk_f16_f32 v10, v27, v18
	global_store_dwordx4 v[0:1], v[10:13], off offset:2048
	v_add_u32_e32 v27, 0x1400, v146
	s_nop 0
	v_add_u32_e32 v12, 0x200d, v71
	v_bfrev_b32_e32 v12, v12
	v_lshrrev_b32_e32 v12, 18, v12
	v_sub_u32_e32 v12, 0, v12
	v_and_b32_e32 v12, 0x17ff, v12
	v_bfrev_b32_e32 v12, v12
	v_lshrrev_b32_e32 v13, 18, v12
	v_lshrrev_b32_e32 v12, 23, v12
	v_bitop3_b32 v12, v12, v13, 31 bitop3:0x6c
	v_add_u32_e32 v13, 0x200e, v71
	v_bfrev_b32_e32 v13, v13
	v_lshrrev_b32_e32 v13, 18, v13
	v_sub_u32_e32 v13, 0, v13
	v_and_b32_e32 v13, 0x27ff, v13
	v_add_u32_e32 v10, 0x200c, v71
	v_bfrev_b32_e32 v13, v13
	v_bfrev_b32_e32 v10, v10
	v_lshrrev_b32_e32 v14, 18, v13
	v_lshrrev_b32_e32 v13, 23, v13
	v_lshrrev_b32_e32 v10, 18, v10
	v_bitop3_b32 v13, v13, v14, 31 bitop3:0x6c
	v_sub_u32_e32 v10, 0, v10
	v_lshl_add_u32 v14, v13, 3, 16
	v_add_u32_e32 v13, 0x200f, v71
	v_and_b32_e32 v10, 0x37ff, v10
	v_bfrev_b32_e32 v13, v13
	v_bfrev_b32_e32 v10, v10
	v_lshrrev_b32_e32 v13, 18, v13
	v_lshrrev_b32_e32 v11, 18, v10
	v_lshrrev_b32_e32 v10, 23, v10
	v_sub_u32_e32 v13, 0, v13
	v_bitop3_b32 v10, v10, v11, 31 bitop3:0x6c
	v_and_b32_e32 v13, 0x7ff, v13
	v_lshl_add_u32 v10, v10, 3, 16
	v_bfrev_b32_e32 v13, v13
	ds_read_b64 v[10:11], v10
	v_lshrrev_b32_e32 v15, 18, v13
	v_lshrrev_b32_e32 v13, 23, v13
	v_bitop3_b32 v13, v13, v15, 31 bitop3:0x6c
	v_lshl_add_u32 v12, v12, 3, 16
	v_lshl_add_u32 v16, v13, 3, 16
	ds_read_b64 v[12:13], v12
	ds_read_b64 v[14:15], v14
	ds_read_b64 v[16:17], v16
	s_waitcnt lgkmcnt(3)
	v_pk_add_f32 v[18:19], v[8:9], v[10:11]
	v_sub_f32_e32 v9, v9, v11
	v_sub_f32_e32 v8, v10, v8
	v_mul_f32_e32 v11, 0.5, v9
	v_mul_f32_e32 v10, 0.5, v8
	s_waitcnt lgkmcnt(2)
	v_pk_add_f32 v[8:9], v[6:7], v[12:13]
	v_sub_f32_e32 v7, v7, v13
	v_sub_f32_e32 v6, v12, v6
	v_mul_f32_e32 v13, 0.5, v7
	v_mul_f32_e32 v12, 0.5, v6
	s_waitcnt lgkmcnt(1)
	v_pk_add_f32 v[6:7], v[4:5], v[14:15]
	v_sub_f32_e32 v5, v5, v15
	v_sub_f32_e32 v4, v14, v4
	v_mul_f32_e32 v15, 0.5, v5
	v_mul_f32_e32 v14, 0.5, v4
	s_waitcnt lgkmcnt(0)
	v_pk_add_f32 v[4:5], v[2:3], v[16:17]
	v_sub_f32_e32 v3, v3, v17
	v_mul_f32_e32 v18, 0.5, v18
	v_mul_f32_e32 v8, 0.5, v8
	v_mul_f32_e32 v6, 0.5, v6
	v_mul_f32_e32 v4, 0.5, v4
	v_mul_f32_e32 v3, 0.5, v3
	v_sub_f32_e32 v2, v16, v2
	v_mul_f32_e32 v19, 0.5, v19
	v_mul_f32_e32 v9, 0.5, v9
	v_mul_f32_e32 v7, 0.5, v7
	v_mul_f32_e32 v17, 0.5, v5
	v_mul_f32_e32 v16, 0.5, v2
	v_cvt_pk_f16_f32 v5, v4, v3
	v_cvt_pk_f16_f32 v4, v6, v15
	v_cvt_pk_f16_f32 v3, v8, v13
	v_cvt_pk_f16_f32 v2, v18, v11
	global_store_dwordx4 v[28:29], v[2:5], off offset:3072
	s_nop 1
	v_cvt_pk_f16_f32 v5, v17, v16
	v_cvt_pk_f16_f32 v4, v7, v14
	v_cvt_pk_f16_f32 v3, v9, v12
	v_cvt_pk_f16_f32 v2, v19, v10
	global_store_dwordx4 v[0:1], v[2:5], off offset:3072
	global_load_dword v2, v153, s[90:91] offset:2048
	global_load_dword v0, v154, s[90:91]
	global_load_dword v6, v145, s[90:91]
	global_load_dword v4, v145, s[94:95]
	v_lshlrev_b32_e32 v8, 1, v146
	v_max_i32_e32 v12, 1, v146
	v_add_u32_e32 v13, 0x1e00, v146
	v_cmp_lt_i32_e32 vcc, 0, v146
	v_add_u32_e32 v9, 0x1000, v8
	v_add_u32_e32 v10, 0x2000, v8
	v_add_u32_e32 v11, 0x3000, v8
	v_lshlrev_b32_e32 v12, 1, v12
	v_cndmask_b32_e64 v14, 0, 1.0, vcc
	v_cmp_gt_i32_e32 vcc, 0x1fff, v13
	v_min_i32_e32 v13, 0x1ffe, v13
	v_lshlrev_b32_e32 v13, 1, v13
	s_nop 0
	v_cndmask_b32_e64 v15, 0, 1.0, vcc
	global_load_ushort v163, v12, s[12:13] offset:-2
	global_load_ushort v164, v8, s[12:13]
	global_load_ushort v165, v8, s[12:13] offset:2
	global_load_ushort v166, v12, s[14:15] offset:-2
	global_load_ushort v167, v8, s[14:15]
	global_load_ushort v168, v8, s[14:15] offset:2
	global_load_ushort v169, v8, s[12:13] offset:1022
	global_load_ushort v170, v8, s[12:13] offset:1024
	global_load_ushort v171, v8, s[12:13] offset:1026
	global_load_ushort v172, v8, s[14:15] offset:1022
	global_load_ushort v173, v8, s[14:15] offset:1024
	global_load_ushort v174, v8, s[14:15] offset:1026
	global_load_ushort v175, v8, s[12:13] offset:2046
	global_load_ushort v176, v8, s[12:13] offset:2048
	global_load_ushort v177, v8, s[12:13] offset:2050
	global_load_ushort v178, v8, s[14:15] offset:2046
	global_load_ushort v179, v8, s[14:15] offset:2048
	global_load_ushort v180, v8, s[14:15] offset:2050
	global_load_ushort v181, v8, s[12:13] offset:3070
	global_load_ushort v182, v8, s[12:13] offset:3072
	global_load_ushort v183, v8, s[12:13] offset:3074
	global_load_ushort v184, v8, s[14:15] offset:3070
	global_load_ushort v185, v8, s[14:15] offset:3072
	global_load_ushort v186, v8, s[14:15] offset:3074
	global_load_ushort v187, v9, s[12:13] offset:-2
	global_load_ushort v188, v9, s[12:13]
	global_load_ushort v189, v9, s[12:13] offset:2
	global_load_ushort v190, v9, s[14:15] offset:-2
	global_load_ushort v191, v9, s[14:15]
	global_load_ushort v192, v9, s[14:15] offset:2
	global_load_ushort v193, v9, s[12:13] offset:1022
	global_load_ushort v194, v9, s[12:13] offset:1024
	global_load_ushort v195, v9, s[12:13] offset:1026
	global_load_ushort v196, v9, s[14:15] offset:1022
	global_load_ushort v197, v9, s[14:15] offset:1024
	global_load_ushort v62, v9, s[14:15] offset:1026
	global_load_ushort v63, v9, s[12:13] offset:2046
	global_load_ushort v64, v9, s[12:13] offset:2048
	global_load_ushort v65, v9, s[12:13] offset:2050
	global_load_ushort v66, v9, s[14:15] offset:2046
	global_load_ushort v67, v9, s[14:15] offset:2048
	global_load_ushort v68, v9, s[14:15] offset:2050
	global_load_ushort v69, v9, s[12:13] offset:3070
	global_load_ushort v70, v9, s[12:13] offset:3072
	global_load_ushort v71, v9, s[12:13] offset:3074
	global_load_ushort v72, v9, s[14:15] offset:3070
	global_load_ushort v73, v9, s[14:15] offset:3072
	global_load_ushort v74, v9, s[14:15] offset:3074
	global_load_ushort v75, v10, s[12:13] offset:-2
	global_load_ushort v76, v10, s[12:13]
	global_load_ushort v77, v10, s[12:13] offset:2
	global_load_ushort v221, v10, s[14:15] offset:-2
	global_load_ushort v222, v10, s[14:15]
	global_load_ushort v223, v10, s[14:15] offset:2
	global_load_ushort v224, v10, s[12:13] offset:1022
	global_load_ushort v225, v10, s[12:13] offset:1024
	global_load_ushort v226, v10, s[12:13] offset:1026
	global_load_ushort v227, v10, s[14:15] offset:1022
	global_load_ushort v228, v10, s[14:15] offset:1024
	global_load_ushort v229, v10, s[14:15] offset:1026
	global_load_ushort v230, v10, s[12:13] offset:2046
	global_load_ushort v231, v10, s[12:13] offset:2048
	global_load_ushort v232, v10, s[12:13] offset:2050
	global_load_ushort v233, v10, s[14:15] offset:2046
	global_load_ushort v234, v10, s[14:15] offset:2048
	global_load_ushort v235, v10, s[14:15] offset:2050
	global_load_ushort v236, v10, s[12:13] offset:3070
	global_load_ushort v237, v10, s[12:13] offset:3072
	global_load_ushort v238, v10, s[12:13] offset:3074
	global_load_ushort v239, v10, s[14:15] offset:3070
	global_load_ushort v240, v10, s[14:15] offset:3072
	global_load_ushort v241, v10, s[14:15] offset:3074
	global_load_ushort v242, v11, s[12:13] offset:-2
	global_load_ushort v243, v11, s[12:13]
	global_load_ushort v244, v11, s[12:13] offset:2
	global_load_ushort v245, v11, s[14:15] offset:-2
	global_load_ushort v246, v11, s[14:15]
	global_load_ushort v247, v11, s[14:15] offset:2
	global_load_ushort v248, v11, s[12:13] offset:1022
	global_load_ushort v249, v11, s[12:13] offset:1024
	global_load_ushort v250, v11, s[12:13] offset:1026
	global_load_ushort v251, v11, s[14:15] offset:1022
	global_load_ushort v253, v11, s[14:15] offset:1024
	global_load_ushort v254, v11, s[14:15] offset:1026
	global_load_ushort v255, v11, s[12:13] offset:2046
	global_load_ushort v1, v11, s[12:13] offset:2048
	global_load_ushort v3, v11, s[12:13] offset:2050
	global_load_ushort v5, v11, s[14:15] offset:2046
	global_load_ushort v7, v11, s[14:15] offset:2048
	global_load_ushort v16, v11, s[14:15] offset:2050
	global_load_ushort v17, v11, s[12:13] offset:3070
	global_load_ushort v18, v11, s[12:13] offset:3072
	global_load_ushort v19, v13, s[12:13] offset:2
	global_load_ushort v20, v11, s[14:15] offset:3070
	global_load_ushort v21, v11, s[14:15] offset:3072
	global_load_ushort v22, v13, s[14:15] offset:2
	s_waitcnt vmcnt(48)
	v_lshlrev_b32_e32 v163, 16, v163
	v_lshlrev_b32_e32 v164, 16, v164
	v_lshlrev_b32_e32 v165, 16, v165
	v_mul_f32_e32 v163, v14, v163
	v_mul_f32_e32 v163, v6, v163
	v_fmac_f32_e32 v163, v2, v164
	v_fmac_f32_e32 v163, v0, v165
	v_add_f32_e32 v32, v4, v163
	v_lshlrev_b32_e32 v166, 16, v166
	v_lshlrev_b32_e32 v167, 16, v167
	v_lshlrev_b32_e32 v168, 16, v168
	v_mul_f32_e32 v166, v14, v166
	v_mul_f32_e32 v166, v6, v166
	v_fmac_f32_e32 v166, v2, v167
	v_fmac_f32_e32 v166, v0, v168
	v_add_f32_e32 v34, v4, v166
	v_lshlrev_b32_e32 v169, 16, v169
	v_lshlrev_b32_e32 v170, 16, v170
	v_lshlrev_b32_e32 v171, 16, v171
	v_mul_f32_e32 v169, v6, v169
	v_fmac_f32_e32 v169, v2, v170
	v_fmac_f32_e32 v169, v0, v171
	v_add_f32_e32 v33, v4, v169
	v_lshlrev_b32_e32 v172, 16, v172
	v_lshlrev_b32_e32 v173, 16, v173
	v_lshlrev_b32_e32 v174, 16, v174
	v_mul_f32_e32 v172, v6, v172
	v_fmac_f32_e32 v172, v2, v173
	v_fmac_f32_e32 v172, v0, v174
	v_add_f32_e32 v35, v4, v172
	v_lshlrev_b32_e32 v175, 16, v175
	v_lshlrev_b32_e32 v176, 16, v176
	v_lshlrev_b32_e32 v177, 16, v177
	v_mul_f32_e32 v175, v6, v175
	v_fmac_f32_e32 v175, v2, v176
	v_fmac_f32_e32 v175, v0, v177
	v_add_f32_e32 v37, v4, v175
	v_lshlrev_b32_e32 v178, 16, v178
	v_lshlrev_b32_e32 v179, 16, v179
	v_lshlrev_b32_e32 v180, 16, v180
	v_mul_f32_e32 v178, v6, v178
	v_fmac_f32_e32 v178, v2, v179
	v_fmac_f32_e32 v178, v0, v180
	v_add_f32_e32 v31, v4, v178
	v_lshlrev_b32_e32 v181, 16, v181
	v_lshlrev_b32_e32 v182, 16, v182
	v_lshlrev_b32_e32 v183, 16, v183
	v_mul_f32_e32 v181, v6, v181
	v_fmac_f32_e32 v181, v2, v182
	v_fmac_f32_e32 v181, v0, v183
	v_add_f32_e32 v36, v4, v181
	v_lshlrev_b32_e32 v184, 16, v184
	v_lshlrev_b32_e32 v185, 16, v185
	v_lshlrev_b32_e32 v186, 16, v186
	v_mul_f32_e32 v184, v6, v184
	v_fmac_f32_e32 v184, v2, v185
	v_fmac_f32_e32 v184, v0, v186
	v_add_f32_e32 v30, v4, v184
	v_lshlrev_b32_e32 v187, 16, v187
	v_lshlrev_b32_e32 v188, 16, v188
	v_lshlrev_b32_e32 v189, 16, v189
	v_mul_f32_e32 v187, v6, v187
	v_fmac_f32_e32 v187, v2, v188
	v_fmac_f32_e32 v187, v0, v189
	v_add_f32_e32 v39, v4, v187
	v_lshlrev_b32_e32 v190, 16, v190
	v_lshlrev_b32_e32 v191, 16, v191
	v_lshlrev_b32_e32 v192, 16, v192
	v_mul_f32_e32 v190, v6, v190
	v_fmac_f32_e32 v190, v2, v191
	v_fmac_f32_e32 v190, v0, v192
	v_add_f32_e32 v41, v4, v190
	v_lshlrev_b32_e32 v193, 16, v193
	v_lshlrev_b32_e32 v194, 16, v194
	v_lshlrev_b32_e32 v195, 16, v195
	v_mul_f32_e32 v193, v6, v193
	v_fmac_f32_e32 v193, v2, v194
	v_fmac_f32_e32 v193, v0, v195
	v_add_f32_e32 v38, v4, v193
	v_lshlrev_b32_e32 v196, 16, v196
	v_lshlrev_b32_e32 v197, 16, v197
	v_lshlrev_b32_e32 v62, 16, v62
	v_mul_f32_e32 v196, v6, v196
	v_fmac_f32_e32 v196, v2, v197
	v_fmac_f32_e32 v196, v0, v62
	v_add_f32_e32 v40, v4, v196
	v_lshlrev_b32_e32 v63, 16, v63
	v_lshlrev_b32_e32 v64, 16, v64
	v_lshlrev_b32_e32 v65, 16, v65
	v_mul_f32_e32 v63, v6, v63
	v_fmac_f32_e32 v63, v2, v64
	v_fmac_f32_e32 v63, v0, v65
	v_add_f32_e32 v43, v4, v63
	v_lshlrev_b32_e32 v66, 16, v66
	v_lshlrev_b32_e32 v67, 16, v67
	v_lshlrev_b32_e32 v68, 16, v68
	v_mul_f32_e32 v66, v6, v66
	v_fmac_f32_e32 v66, v2, v67
	v_fmac_f32_e32 v66, v0, v68
	v_add_f32_e32 v45, v4, v66
	v_lshlrev_b32_e32 v69, 16, v69
	v_lshlrev_b32_e32 v70, 16, v70
	v_lshlrev_b32_e32 v71, 16, v71
	v_mul_f32_e32 v69, v6, v69
	v_fmac_f32_e32 v69, v2, v70
	v_fmac_f32_e32 v69, v0, v71
	v_add_f32_e32 v42, v4, v69
	v_lshlrev_b32_e32 v72, 16, v72
	v_lshlrev_b32_e32 v73, 16, v73
	v_lshlrev_b32_e32 v74, 16, v74
	v_mul_f32_e32 v72, v6, v72
	v_fmac_f32_e32 v72, v2, v73
	v_fmac_f32_e32 v72, v0, v74
	v_add_f32_e32 v44, v4, v72
	s_waitcnt vmcnt(0)
	v_lshlrev_b32_e32 v75, 16, v75
	v_lshlrev_b32_e32 v76, 16, v76
	v_lshlrev_b32_e32 v77, 16, v77
	v_mul_f32_e32 v75, v6, v75
	v_fmac_f32_e32 v75, v2, v76
	v_fmac_f32_e32 v75, v0, v77
	v_add_f32_e32 v47, v4, v75
	v_lshlrev_b32_e32 v221, 16, v221
	v_lshlrev_b32_e32 v222, 16, v222
	v_lshlrev_b32_e32 v223, 16, v223
	v_mul_f32_e32 v221, v6, v221
	v_fmac_f32_e32 v221, v2, v222
	v_fmac_f32_e32 v221, v0, v223
	v_add_f32_e32 v49, v4, v221
	v_lshlrev_b32_e32 v224, 16, v224
	v_lshlrev_b32_e32 v225, 16, v225
	v_lshlrev_b32_e32 v226, 16, v226
	v_mul_f32_e32 v224, v6, v224
	v_fmac_f32_e32 v224, v2, v225
	v_fmac_f32_e32 v224, v0, v226
	v_add_f32_e32 v46, v4, v224
	v_lshlrev_b32_e32 v227, 16, v227
	v_lshlrev_b32_e32 v228, 16, v228
	v_lshlrev_b32_e32 v229, 16, v229
	v_mul_f32_e32 v227, v6, v227
	v_fmac_f32_e32 v227, v2, v228
	v_fmac_f32_e32 v227, v0, v229
	v_add_f32_e32 v48, v4, v227
	v_lshlrev_b32_e32 v230, 16, v230
	v_lshlrev_b32_e32 v231, 16, v231
	v_lshlrev_b32_e32 v232, 16, v232
	v_mul_f32_e32 v230, v6, v230
	v_fmac_f32_e32 v230, v2, v231
	v_fmac_f32_e32 v230, v0, v232
	v_add_f32_e32 v51, v4, v230
	v_lshlrev_b32_e32 v233, 16, v233
	v_lshlrev_b32_e32 v234, 16, v234
	v_lshlrev_b32_e32 v235, 16, v235
	v_mul_f32_e32 v233, v6, v233
	v_fmac_f32_e32 v233, v2, v234
	v_fmac_f32_e32 v233, v0, v235
	v_add_f32_e32 v53, v4, v233
	v_lshlrev_b32_e32 v236, 16, v236
	v_lshlrev_b32_e32 v237, 16, v237
	v_lshlrev_b32_e32 v238, 16, v238
	v_mul_f32_e32 v236, v6, v236
	v_fmac_f32_e32 v236, v2, v237
	v_fmac_f32_e32 v236, v0, v238
	v_add_f32_e32 v50, v4, v236
	v_lshlrev_b32_e32 v239, 16, v239
	v_lshlrev_b32_e32 v240, 16, v240
	v_lshlrev_b32_e32 v241, 16, v241
	v_mul_f32_e32 v239, v6, v239
	v_fmac_f32_e32 v239, v2, v240
	v_fmac_f32_e32 v239, v0, v241
	v_add_f32_e32 v52, v4, v239
	v_lshlrev_b32_e32 v242, 16, v242
	v_lshlrev_b32_e32 v243, 16, v243
	v_lshlrev_b32_e32 v244, 16, v244
	v_mul_f32_e32 v242, v6, v242
	v_fmac_f32_e32 v242, v2, v243
	v_fmac_f32_e32 v242, v0, v244
	v_add_f32_e32 v55, v4, v242
	v_lshlrev_b32_e32 v245, 16, v245
	v_lshlrev_b32_e32 v246, 16, v246
	v_lshlrev_b32_e32 v247, 16, v247
	v_mul_f32_e32 v245, v6, v245
	v_fmac_f32_e32 v245, v2, v246
	v_fmac_f32_e32 v245, v0, v247
	v_add_f32_e32 v57, v4, v245
	v_lshlrev_b32_e32 v248, 16, v248
	v_lshlrev_b32_e32 v249, 16, v249
	v_lshlrev_b32_e32 v250, 16, v250
	v_mul_f32_e32 v248, v6, v248
	v_fmac_f32_e32 v248, v2, v249
	v_fmac_f32_e32 v248, v0, v250
	v_add_f32_e32 v54, v4, v248
	v_lshlrev_b32_e32 v251, 16, v251
	v_lshlrev_b32_e32 v253, 16, v253
	v_lshlrev_b32_e32 v254, 16, v254
	v_mul_f32_e32 v251, v6, v251
	v_fmac_f32_e32 v251, v2, v253
	v_fmac_f32_e32 v251, v0, v254
	v_add_f32_e32 v56, v4, v251
	v_lshlrev_b32_e32 v255, 16, v255
	v_lshlrev_b32_e32 v1, 16, v1
	v_lshlrev_b32_e32 v3, 16, v3
	v_mul_f32_e32 v255, v6, v255
	v_fmac_f32_e32 v255, v2, v1
	v_fmac_f32_e32 v255, v0, v3
	v_add_f32_e32 v59, v4, v255
	v_lshlrev_b32_e32 v5, 16, v5
	v_lshlrev_b32_e32 v7, 16, v7
	v_lshlrev_b32_e32 v16, 16, v16
	v_mul_f32_e32 v5, v6, v5
	v_fmac_f32_e32 v5, v2, v7
	v_fmac_f32_e32 v5, v0, v16
	v_add_f32_e32 v61, v4, v5
	v_lshlrev_b32_e32 v17, 16, v17
	v_lshlrev_b32_e32 v18, 16, v18
	v_lshlrev_b32_e32 v19, 16, v19
	v_mul_f32_e32 v19, v15, v19
	v_mul_f32_e32 v17, v6, v17
	v_fmac_f32_e32 v17, v2, v18
	v_fmac_f32_e32 v17, v0, v19
	v_add_f32_e32 v58, v4, v17
	v_lshlrev_b32_e32 v20, 16, v20
	v_lshlrev_b32_e32 v21, 16, v21
	v_lshlrev_b32_e32 v22, 16, v22
	v_mul_f32_e32 v22, v15, v22
	v_mul_f32_e32 v20, v6, v20
	v_fmac_f32_e32 v20, v2, v21
	v_fmac_f32_e32 v20, v0, v22
	v_add_f32_e32 v60, v4, v20
	v_readlane_b32 s72, v252, 22
	v_readlane_b32 s78, v252, 28
	v_readlane_b32 s79, v252, 29
	s_add_u32 s24, s78, s10
	s_addc_u32 s59, s79, s11
	s_lshl_b64 s[0:1], s[68:69], 1
	v_readlane_b32 s4, v252, 50
	v_readlane_b32 s73, v252, 23
	v_readlane_b32 s74, v252, 24
	v_readlane_b32 s75, v252, 25
	v_readlane_b32 s76, v252, 26
	v_readlane_b32 s77, v252, 27
	v_readlane_b32 s80, v252, 30
	v_readlane_b32 s81, v252, 31
	v_readlane_b32 s82, v252, 32
	v_readlane_b32 s83, v252, 33
	s_add_u32 s96, s4, s0
	v_readlane_b32 s0, v252, 51
	s_movk_i32 s83, 0xea00
	s_movk_i32 s82, 0xdff
	s_movk_i32 s81, 0xee00
	s_movk_i32 s80, 0x13ff
	s_movk_i32 s77, 0xf200
	s_movk_i32 s76, 0x7ff
	s_movk_i32 s73, 0xf000
	s_movk_i32 s72, 0x1ff
	s_movk_i32 s75, 0xfff
	s_movk_i32 s74, 0x1fff
	s_movk_i32 s78, 0xf400
	s_movk_i32 s79, 0x11ff
	s_movk_i32 s69, 0xec00
	s_addc_u32 s97, s0, s1
	s_mov_b64 s[14:15], -1
	v_readlane_b32 s84, v252, 34
	v_readlane_b32 s85, v252, 35
	v_readlane_b32 s86, v252, 36
	v_readlane_b32 s87, v252, 37
	s_branch .LBB0_538

.LBB0_538:
	s_lshl_b32 s98, s16, 16
	s_mov_b32 s99, 0
	v_lshl_add_u64 v[196:197], s[98:99], 0, v[28:29]
	global_load_dwordx4 v[164:167], v[196:197], off offset:-4096
	global_load_dwordx4 v[168:171], v[196:197], off offset:-3072
	global_load_dwordx4 v[172:175], v[196:197], off offset:-2048
	global_load_dwordx4 v[176:179], v[196:197], off offset:-1024
	global_load_dwordx4 v[180:183], v[196:197], off
	global_load_dwordx4 v[184:187], v[196:197], off offset:1024
	global_load_dwordx4 v[188:191], v[196:197], off offset:2048
	global_load_dwordx4 v[192:195], v[196:197], off offset:3072
	v_mov_b32_e32 v20, v46
	v_mov_b32_e32 v21, v48
	v_mov_b32_e32 v22, v51
	v_mov_b32_e32 v23, v53
	v_pk_add_f32 v[88:89], v[20:21], 0 op_sel_hi:[1,0]
	v_pk_mul_f32 v[20:21], v[20:21], s[58:59] op_sel_hi:[1,0]
	v_xor_b32_e32 v91, 0x80000000, v46
	v_mov_b32_e32 v90, v48
	v_pk_add_f32 v[92:93], v[50:51], 0 neg_lo:[1,1] neg_hi:[1,1]
	v_mov_b32_e32 v24, v50
	v_mov_b32_e32 v25, v52
	v_pk_fma_f32 v[20:21], v[90:91], s[46:47], v[20:21] op_sel_hi:[1,0,1] neg_lo:[0,0,1] neg_hi:[0,0,1]
	v_pk_add_f32 v[90:91], v[22:23], 0 op_sel_hi:[1,0]
	v_pk_mul_f32 v[22:23], v[22:23], s[62:63] op_sel_hi:[1,0]
	v_mov_b32_e32 v92, v53
	v_mov_b32_e32 v26, v55
	v_mov_b32_e32 v27, v57
	v_pk_fma_f32 v[22:23], v[92:93], s[60:61], v[22:23] op_sel_hi:[1,0,1] neg_lo:[0,0,1] neg_hi:[0,0,1]
	v_pk_add_f32 v[92:93], v[24:25], 0 op_sel_hi:[1,0]
	v_pk_mul_f32 v[24:25], v[24:25], s[66:67] op_sel_hi:[1,0]
	v_xor_b32_e32 v95, 0x80000000, v50
	v_mov_b32_e32 v94, v52
	v_pk_add_f32 v[96:97], v[54:55], 0 neg_lo:[1,1] neg_hi:[1,1]
	v_mov_b32_e32 v64, v54
	v_mov_b32_e32 v65, v56
	v_pk_fma_f32 v[24:25], v[94:95], s[64:65], v[24:25] op_sel_hi:[1,0,1] neg_lo:[0,0,1] neg_hi:[0,0,1]
	v_pk_add_f32 v[94:95], v[26:27], 0 op_sel_hi:[1,0]
	v_pk_mul_f32 v[26:27], v[26:27], s[70:71] op_sel_hi:[1,0]
	v_mov_b32_e32 v96, v57
	v_mov_b32_e32 v66, v59
	v_mov_b32_e32 v67, v61
	v_pk_fma_f32 v[26:27], v[96:97], s[70:71], v[26:27] op_sel_hi:[1,0,1] neg_lo:[0,0,1] neg_hi:[0,0,1]
	v_pk_add_f32 v[96:97], v[64:65], 0 op_sel_hi:[1,0]
	v_pk_mul_f32 v[64:65], v[64:65], s[64:65] op_sel_hi:[1,0]
	v_xor_b32_e32 v99, 0x80000000, v54
	v_mov_b32_e32 v98, v56
	v_pk_add_f32 v[100:101], v[58:59], 0 neg_lo:[1,1] neg_hi:[1,1]
	v_mov_b32_e32 v2, v32
	v_mov_b32_e32 v3, v34
	v_mov_b32_e32 v4, v33
	v_mov_b32_e32 v5, v35
	v_mov_b32_e32 v18, v47
	v_mov_b32_e32 v19, v49
	v_mov_b32_e32 v68, v58
	v_mov_b32_e32 v69, v60
	v_pk_fma_f32 v[64:65], v[98:99], s[66:67], v[64:65] op_sel_hi:[1,0,1] neg_lo:[0,0,1] neg_hi:[0,0,1]
	v_pk_add_f32 v[98:99], v[66:67], 0 op_sel_hi:[1,0]
	v_pk_mul_f32 v[66:67], v[66:67], s[60:61] op_sel_hi:[1,0]
	v_mov_b32_e32 v100, v61
	v_pk_add_f32 v[70:71], v[2:3], 0 op_sel_hi:[1,0]
	v_pk_add_f32 v[72:73], v[4:5], 0 op_sel_hi:[1,0]
	v_pk_add_f32 v[74:75], v[32:33], 0 neg_lo:[1,1] neg_hi:[1,1]
	v_pk_add_f32 v[18:19], v[18:19], 0 op_sel_hi:[1,0]
	v_pk_fma_f32 v[66:67], v[100:101], s[62:63], v[66:67] op_sel_hi:[1,0,1] neg_lo:[0,0,1] neg_hi:[0,0,1]
	v_pk_add_f32 v[100:101], v[68:69], 0 op_sel_hi:[1,0]
	v_pk_mul_f32 v[68:69], v[68:69], s[46:47] op_sel_hi:[1,0]
	v_xor_b32_e32 v103, 0x80000000, v58
	v_mov_b32_e32 v102, v60
	v_mov_b32_e32 v74, v35
	v_pk_fma_f32 v[68:69], v[102:103], s[58:59], v[68:69] op_sel_hi:[1,0,1] neg_lo:[0,0,1] neg_hi:[0,0,1]
	v_pk_add_f32 v[102:103], v[18:19], v[70:71]
	v_pk_add_f32 v[18:19], v[70:71], v[18:19] neg_lo:[0,1] neg_hi:[0,1]
	v_pk_add_f32 v[70:71], v[88:89], v[72:73]
	v_pk_add_f32 v[72:73], v[72:73], v[88:89] neg_lo:[0,1] neg_hi:[0,1]
	v_mov_b32_e32 v6, v37
	v_mov_b32_e32 v7, v31
	v_pk_mul_f32 v[74:75], v[74:75], s[58:59] op_sel_hi:[1,0]
	s_nop 0
	v_pk_fma_f32 v[4:5], v[4:5], s[46:47], v[74:75] op_sel_hi:[1,0,1]
	v_pk_add_f32 v[74:75], v[6:7], 0 op_sel_hi:[1,0]
	v_pk_add_f32 v[76:77], v[36:37], 0 neg_lo:[1,1] neg_hi:[1,1]
	v_pk_mul_f32 v[88:89], v[72:73], s[62:63] op_sel:[1,0] op_sel_hi:[0,0] neg_hi:[1,0]
	v_mov_b32_e32 v76, v31
	v_pk_fma_f32 v[72:73], v[72:73], s[60:61], v[88:89] op_sel_hi:[1,0,1]
	v_pk_add_f32 v[88:89], v[90:91], v[74:75]
	v_pk_add_f32 v[74:75], v[74:75], v[90:91] neg_lo:[0,1] neg_hi:[0,1]
	v_mov_b32_e32 v8, v36
	v_mov_b32_e32 v9, v30
	v_pk_mul_f32 v[76:77], v[76:77], s[62:63] op_sel_hi:[1,0]
	s_nop 0
	v_pk_fma_f32 v[6:7], v[6:7], s[60:61], v[76:77] op_sel_hi:[1,0,1]
	v_pk_add_f32 v[76:77], v[8:9], 0 op_sel_hi:[1,0]
	v_pk_mul_f32 v[90:91], v[74:75], s[70:71] op_sel:[1,0] op_sel_hi:[0,0] neg_hi:[1,0]
	v_xor_b32_e32 v79, 0x80000000, v36
	v_mov_b32_e32 v78, v30
	v_pk_add_f32 v[80:81], v[38:39], 0 neg_lo:[1,1] neg_hi:[1,1]
	v_pk_fma_f32 v[74:75], v[74:75], s[70:71], v[90:91] op_sel_hi:[1,0,1]
	v_pk_add_f32 v[90:91], v[92:93], v[76:77]
	v_pk_add_f32 v[76:77], v[76:77], v[92:93] neg_lo:[0,1] neg_hi:[0,1]
	v_mov_b32_e32 v10, v39
	v_mov_b32_e32 v11, v41
	v_pk_mul_f32 v[78:79], v[78:79], s[66:67] op_sel_hi:[1,0]
	v_mov_b32_e32 v80, v41
	v_mov_b32_e32 v12, v38
	v_mov_b32_e32 v13, v40
	v_pk_fma_f32 v[8:9], v[8:9], s[64:65], v[78:79] op_sel_hi:[1,0,1]
	v_pk_add_f32 v[78:79], v[10:11], 0 op_sel_hi:[1,0]
	v_pk_mul_f32 v[80:81], v[80:81], s[70:71] op_sel_hi:[1,0]
	v_pk_mul_f32 v[92:93], v[76:77], s[60:61] op_sel:[1,0] op_sel_hi:[0,0] neg_hi:[1,0]
	v_pk_fma_f32 v[10:11], v[10:11], s[70:71], v[80:81] op_sel_hi:[1,0,1]
	v_pk_add_f32 v[80:81], v[12:13], 0 op_sel_hi:[1,0]
	v_xor_b32_e32 v83, 0x80000000, v38
	v_mov_b32_e32 v82, v40
	v_pk_fma_f32 v[76:77], v[76:77], s[62:63], v[92:93] op_sel_hi:[1,0,1]
	v_pk_add_f32 v[92:93], v[94:95], v[78:79]
	v_pk_add_f32 v[78:79], v[78:79], v[94:95] neg_lo:[0,1] neg_hi:[0,1]
	v_mov_b32_e32 v14, v43
	v_mov_b32_e32 v15, v45
	v_pk_mul_f32 v[82:83], v[82:83], s[64:65] op_sel_hi:[1,0]
	v_pk_add_f32 v[84:85], v[42:43], 0 neg_lo:[1,1] neg_hi:[1,1]
	v_xor_b32_e32 v95, 0x80000000, v78
	v_mov_b32_e32 v94, v79
	v_pk_add_f32 v[78:79], v[96:97], v[80:81]
	v_pk_add_f32 v[80:81], v[80:81], v[96:97] neg_lo:[0,1] neg_hi:[0,1]
	v_pk_fma_f32 v[12:13], v[12:13], s[66:67], v[82:83] op_sel_hi:[1,0,1]
	v_pk_add_f32 v[82:83], v[14:15], 0 op_sel_hi:[1,0]
	v_mov_b32_e32 v84, v45
	v_pk_mul_f32 v[96:97], v[80:81], s[62:63] op_sel_hi:[1,0]
	v_xor_b32_e32 v105, 0x80000000, v80
	v_mov_b32_e32 v104, v81
	v_mov_b32_e32 v16, v42
	v_mov_b32_e32 v17, v44
	v_pk_mul_f32 v[84:85], v[84:85], s[60:61] op_sel_hi:[1,0]
	v_xor_b32_e32 v87, 0x80000000, v42
	v_mov_b32_e32 v86, v44
	v_pk_fma_f32 v[80:81], v[104:105], s[60:61], v[96:97] op_sel_hi:[1,0,1] neg_lo:[0,0,1] neg_hi:[0,0,1]
	v_pk_add_f32 v[96:97], v[98:99], v[82:83]
	v_pk_add_f32 v[82:83], v[82:83], v[98:99] neg_lo:[0,1] neg_hi:[0,1]
	v_pk_fma_f32 v[14:15], v[14:15], s[62:63], v[84:85] op_sel_hi:[1,0,1]
	v_pk_add_f32 v[84:85], v[16:17], 0 op_sel_hi:[1,0]
	v_pk_mul_f32 v[86:87], v[86:87], s[46:47] op_sel_hi:[1,0]
	v_pk_mul_f32 v[98:99], v[82:83], s[70:71] op_sel_hi:[1,0]
	v_xor_b32_e32 v105, 0x80000000, v82
	v_mov_b32_e32 v104, v83
	v_pk_fma_f32 v[16:17], v[16:17], s[58:59], v[86:87] op_sel_hi:[1,0,1]
	v_pk_add_f32 v[86:87], v[46:47], 0 neg_lo:[1,1] neg_hi:[1,1]
	v_pk_fma_f32 v[82:83], v[104:105], s[70:71], v[98:99] op_sel_hi:[1,0,1] neg_lo:[0,0,1] neg_hi:[0,0,1]
	v_pk_add_f32 v[98:99], v[100:101], v[84:85]
	v_pk_add_f32 v[84:85], v[84:85], v[100:101] neg_lo:[0,1] neg_hi:[0,1]
	v_mov_b32_e32 v86, v49
	v_pk_mul_f32 v[100:101], v[84:85], s[60:61] op_sel_hi:[1,0]
	v_xor_b32_e32 v105, 0x80000000, v84
	v_mov_b32_e32 v104, v85
	v_pk_fma_f32 v[84:85], v[104:105], s[62:63], v[100:101] op_sel_hi:[1,0,1] neg_lo:[0,0,1] neg_hi:[0,0,1]
	v_pk_add_f32 v[100:101], v[86:87], v[2:3]
	v_pk_add_f32 v[2:3], v[2:3], v[86:87] neg_lo:[0,1] neg_hi:[0,1]
	v_pk_add_f32 v[86:87], v[20:21], v[4:5]
	v_pk_add_f32 v[4:5], v[4:5], v[20:21] neg_lo:[0,1] neg_hi:[0,1]
	v_mov_b32_e32 v63, v146
	v_pk_mul_f32 v[20:21], v[4:5], s[62:63] op_sel:[1,0] op_sel_hi:[0,0] neg_hi:[1,0]
	s_nop 0
	v_pk_fma_f32 v[4:5], v[4:5], s[60:61], v[20:21] op_sel_hi:[1,0,1]
	v_pk_add_f32 v[20:21], v[22:23], v[6:7]
	v_pk_add_f32 v[6:7], v[6:7], v[22:23] neg_lo:[0,1] neg_hi:[0,1]
	s_barrier
	v_pk_mul_f32 v[22:23], v[6:7], s[70:71] op_sel:[1,0] op_sel_hi:[0,0] neg_hi:[1,0]
	s_nop 0
	v_pk_fma_f32 v[6:7], v[6:7], s[70:71], v[22:23] op_sel_hi:[1,0,1]
	v_pk_add_f32 v[22:23], v[24:25], v[8:9]
	v_pk_add_f32 v[8:9], v[8:9], v[24:25] neg_lo:[0,1] neg_hi:[0,1]
	s_add_i32 s19, 16, 0x11000
	v_pk_mul_f32 v[24:25], v[8:9], s[60:61] op_sel:[1,0] op_sel_hi:[0,0] neg_hi:[1,0]
	s_add_i32 s18, 16, 0x12000
	v_pk_fma_f32 v[8:9], v[8:9], s[62:63], v[24:25] op_sel_hi:[1,0,1]
	v_pk_add_f32 v[24:25], v[26:27], v[10:11]
	v_pk_add_f32 v[10:11], v[10:11], v[26:27] neg_lo:[0,1] neg_hi:[0,1]
	s_add_i32 s17, 16, 0x13000
	v_xor_b32_e32 v27, 0x80000000, v10
	v_mov_b32_e32 v26, v11
	v_pk_add_f32 v[10:11], v[64:65], v[12:13]
	v_pk_add_f32 v[12:13], v[12:13], v[64:65] neg_lo:[0,1] neg_hi:[0,1]
	s_add_i32 s13, 16, 0x14000
	v_pk_mul_f32 v[64:65], v[12:13], s[62:63] op_sel_hi:[1,0]
	v_xor_b32_e32 v105, 0x80000000, v12
	v_mov_b32_e32 v104, v13
	v_pk_fma_f32 v[12:13], v[104:105], s[60:61], v[64:65] op_sel_hi:[1,0,1] neg_lo:[0,0,1] neg_hi:[0,0,1]
	v_pk_add_f32 v[64:65], v[66:67], v[14:15]
	v_pk_add_f32 v[14:15], v[14:15], v[66:67] neg_lo:[0,1] neg_hi:[0,1]
	s_add_i32 s12, 16, 0x15000
	v_pk_mul_f32 v[66:67], v[14:15], s[70:71] op_sel_hi:[1,0]
	v_xor_b32_e32 v105, 0x80000000, v14
	v_mov_b32_e32 v104, v15
	v_pk_fma_f32 v[14:15], v[104:105], s[70:71], v[66:67] op_sel_hi:[1,0,1] neg_lo:[0,0,1] neg_hi:[0,0,1]
	v_pk_add_f32 v[66:67], v[68:69], v[16:17]
	v_pk_add_f32 v[16:17], v[16:17], v[68:69] neg_lo:[0,1] neg_hi:[0,1]
	s_add_i32 s11, 16, 0x16000
	v_pk_mul_f32 v[68:69], v[16:17], s[60:61] op_sel_hi:[1,0]
	v_xor_b32_e32 v105, 0x80000000, v16
	v_mov_b32_e32 v104, v17
	v_pk_fma_f32 v[16:17], v[104:105], s[62:63], v[68:69] op_sel_hi:[1,0,1] neg_lo:[0,0,1] neg_hi:[0,0,1]
	v_pk_add_f32 v[68:69], v[92:93], v[102:103]
	v_pk_add_f32 v[92:93], v[102:103], v[92:93] neg_lo:[0,1] neg_hi:[0,1]
	v_pk_add_f32 v[102:103], v[78:79], v[70:71]
	v_pk_add_f32 v[70:71], v[70:71], v[78:79] neg_lo:[0,1] neg_hi:[0,1]
	s_add_i32 s10, 16, 0x17000
	v_pk_mul_f32 v[78:79], v[70:71], s[70:71] op_sel:[1,0] op_sel_hi:[0,0] neg_hi:[1,0]
	s_add_i32 s9, 16, 0x18000
	v_pk_fma_f32 v[70:71], v[70:71], s[70:71], v[78:79] op_sel_hi:[1,0,1]
	v_pk_add_f32 v[78:79], v[96:97], v[88:89]
	v_pk_add_f32 v[88:89], v[88:89], v[96:97] neg_lo:[0,1] neg_hi:[0,1]
	s_add_i32 s8, 16, 0x19000
	v_xor_b32_e32 v97, 0x80000000, v88
	v_mov_b32_e32 v96, v89
	v_pk_add_f32 v[88:89], v[98:99], v[90:91]
	v_pk_add_f32 v[90:91], v[90:91], v[98:99] neg_lo:[0,1] neg_hi:[0,1]
	s_add_i32 s7, 16, 0x1a000
	v_pk_mul_f32 v[98:99], v[90:91], s[70:71] op_sel_hi:[1,0]
	v_xor_b32_e32 v105, 0x80000000, v90
	v_mov_b32_e32 v104, v91
	v_pk_fma_f32 v[90:91], v[104:105], s[70:71], v[98:99] op_sel_hi:[1,0,1] neg_lo:[0,0,1] neg_hi:[0,0,1]
	v_pk_add_f32 v[98:99], v[94:95], v[18:19]
	v_pk_add_f32 v[18:19], v[18:19], v[94:95] neg_lo:[0,1] neg_hi:[0,1]
	v_pk_add_f32 v[94:95], v[80:81], v[72:73]
	v_pk_add_f32 v[72:73], v[72:73], v[80:81] neg_lo:[0,1] neg_hi:[0,1]
	s_add_i32 s6, 16, 0x1b000
	v_pk_mul_f32 v[80:81], v[72:73], s[70:71] op_sel:[1,0] op_sel_hi:[0,0] neg_hi:[1,0]
	s_add_i32 s5, 16, 0x1c000
	v_pk_fma_f32 v[72:73], v[72:73], s[70:71], v[80:81] op_sel_hi:[1,0,1]
	v_pk_add_f32 v[80:81], v[82:83], v[74:75]
	v_pk_add_f32 v[74:75], v[74:75], v[82:83] neg_lo:[0,1] neg_hi:[0,1]
	s_add_i32 s4, 16, 0x1d000
	v_xor_b32_e32 v83, 0x80000000, v74
	v_mov_b32_e32 v82, v75
	v_pk_add_f32 v[74:75], v[84:85], v[76:77]
	v_pk_add_f32 v[76:77], v[76:77], v[84:85] neg_lo:[0,1] neg_hi:[0,1]
	v_pk_add_f32 v[106:107], v[18:19], v[82:83]
	v_pk_mul_f32 v[84:85], v[76:77], s[70:71] op_sel_hi:[1,0]
	v_xor_b32_e32 v105, 0x80000000, v76
	v_mov_b32_e32 v104, v77
	v_pk_fma_f32 v[76:77], v[104:105], s[70:71], v[84:85] op_sel_hi:[1,0,1] neg_lo:[0,0,1] neg_hi:[0,0,1]
	v_pk_add_f32 v[84:85], v[24:25], v[100:101]
	v_pk_add_f32 v[24:25], v[100:101], v[24:25] neg_lo:[0,1] neg_hi:[0,1]
	v_pk_add_f32 v[100:101], v[10:11], v[86:87]
	v_pk_add_f32 v[10:11], v[86:87], v[10:11] neg_lo:[0,1] neg_hi:[0,1]
	v_pk_add_f32 v[18:19], v[18:19], v[82:83] neg_lo:[0,1] neg_hi:[0,1]
	v_pk_mul_f32 v[86:87], v[10:11], s[70:71] op_sel:[1,0] op_sel_hi:[0,0] neg_hi:[1,0]
	v_pk_add_f32 v[82:83], v[76:77], v[72:73]
	v_pk_fma_f32 v[10:11], v[10:11], s[70:71], v[86:87] op_sel_hi:[1,0,1]
	v_pk_add_f32 v[86:87], v[64:65], v[20:21]
	v_pk_add_f32 v[20:21], v[20:21], v[64:65] neg_lo:[0,1] neg_hi:[0,1]
	v_pk_add_f32 v[72:73], v[72:73], v[76:77] neg_lo:[0,1] neg_hi:[0,1]
	v_xor_b32_e32 v65, 0x80000000, v20
	v_mov_b32_e32 v64, v21
	v_pk_add_f32 v[20:21], v[66:67], v[22:23]
	v_pk_add_f32 v[22:23], v[22:23], v[66:67] neg_lo:[0,1] neg_hi:[0,1]
	v_xor_b32_e32 v77, 0x80000000, v72
	v_pk_mul_f32 v[66:67], v[22:23], s[70:71] op_sel_hi:[1,0]
	v_xor_b32_e32 v105, 0x80000000, v22
	v_mov_b32_e32 v104, v23
	v_pk_fma_f32 v[22:23], v[104:105], s[70:71], v[66:67] op_sel_hi:[1,0,1] neg_lo:[0,0,1] neg_hi:[0,0,1]
	v_pk_add_f32 v[66:67], v[2:3], v[26:27]
	v_pk_add_f32 v[2:3], v[2:3], v[26:27] neg_lo:[0,1] neg_hi:[0,1]
	v_pk_add_f32 v[26:27], v[12:13], v[4:5]
	v_pk_add_f32 v[4:5], v[4:5], v[12:13] neg_lo:[0,1] neg_hi:[0,1]
	v_mov_b32_e32 v76, v73
	v_pk_mul_f32 v[12:13], v[4:5], s[70:71] op_sel:[1,0] op_sel_hi:[0,0] neg_hi:[1,0]
	v_pk_add_f32 v[72:73], v[84:85], v[86:87]
	v_pk_fma_f32 v[4:5], v[4:5], s[70:71], v[12:13] op_sel_hi:[1,0,1]
	v_pk_add_f32 v[12:13], v[14:15], v[6:7]
	v_pk_add_f32 v[6:7], v[6:7], v[14:15] neg_lo:[0,1] neg_hi:[0,1]
	v_pk_add_f32 v[84:85], v[84:85], v[86:87] neg_lo:[0,1] neg_hi:[0,1]
	v_xor_b32_e32 v15, 0x80000000, v6
	v_mov_b32_e32 v14, v7
	v_pk_add_f32 v[6:7], v[16:17], v[8:9]
	v_pk_add_f32 v[8:9], v[8:9], v[16:17] neg_lo:[0,1] neg_hi:[0,1]
	v_pk_add_f32 v[86:87], v[20:21], v[100:101]
	v_pk_mul_f32 v[16:17], v[8:9], s[70:71] op_sel_hi:[1,0]
	s_nop 0
	v_pk_fma_f32 v[8:9], v[8:9], s[70:71], v[16:17] op_sel:[1,0,0] op_sel_hi:[0,0,1] neg_lo:[0,0,1] neg_hi:[1,0,1]
	v_pk_add_f32 v[104:105], v[92:93], v[96:97]
	v_pk_add_f32 v[92:93], v[92:93], v[96:97] neg_lo:[0,1] neg_hi:[0,1]
	v_pk_add_f32 v[96:97], v[90:91], v[70:71]
	v_pk_add_f32 v[70:71], v[70:71], v[90:91] neg_lo:[0,1] neg_hi:[0,1]
	v_pk_add_f32 v[16:17], v[78:79], v[68:69]
	v_pk_add_f32 v[68:69], v[68:69], v[78:79] neg_lo:[0,1] neg_hi:[0,1]
	v_pk_add_f32 v[78:79], v[88:89], v[102:103]
	v_pk_add_f32 v[88:89], v[102:103], v[88:89] neg_lo:[0,1] neg_hi:[0,1]
	v_xor_b32_e32 v91, 0x80000000, v70
	v_mov_b32_e32 v90, v71
	v_pk_add_f32 v[70:71], v[98:99], v[80:81]
	v_pk_add_f32 v[98:99], v[98:99], v[80:81] neg_lo:[0,1] neg_hi:[0,1]
	v_pk_add_f32 v[80:81], v[74:75], v[94:95]
	v_pk_add_f32 v[74:75], v[94:95], v[74:75] neg_lo:[0,1] neg_hi:[0,1]
	v_pk_add_f32 v[20:21], v[100:101], v[20:21] neg_lo:[0,1] neg_hi:[0,1]
	v_pk_add_f32 v[108:109], v[24:25], v[64:65]
	v_pk_add_f32 v[24:25], v[24:25], v[64:65] neg_lo:[0,1] neg_hi:[0,1]
	v_pk_add_f32 v[64:65], v[22:23], v[10:11]
	v_pk_add_f32 v[10:11], v[10:11], v[22:23] neg_lo:[0,1] neg_hi:[0,1]
	v_pk_add_f32 v[114:115], v[6:7], v[26:27]
	v_pk_add_f32 v[6:7], v[26:27], v[6:7] neg_lo:[0,1] neg_hi:[0,1]
	v_xor_b32_e32 v103, 0x80000000, v88
	v_mov_b32_e32 v102, v89
	v_xor_b32_e32 v95, 0x80000000, v74
	v_mov_b32_e32 v94, v75
	v_xor_b32_e32 v101, 0x80000000, v20
	v_mov_b32_e32 v100, v21
	v_xor_b32_e32 v27, 0x80000000, v6
	v_mov_b32_e32 v26, v7
	v_pk_add_f32 v[6:7], v[2:3], v[14:15]
	v_pk_add_f32 v[116:117], v[2:3], v[14:15] neg_lo:[0,1] neg_hi:[0,1]
	v_pk_add_f32 v[2:3], v[4:5], v[8:9] neg_lo:[0,1] neg_hi:[0,1]
	v_pk_add_f32 v[112:113], v[66:67], v[12:13]
	v_pk_add_f32 v[66:67], v[66:67], v[12:13] neg_lo:[0,1] neg_hi:[0,1]
	v_pk_add_f32 v[118:119], v[8:9], v[4:5]
	v_xor_b32_e32 v121, 0x80000000, v2
	v_mov_b32_e32 v120, v3
	v_pk_add_f32 v[2:3], v[78:79], v[16:17]
	v_pk_add_f32 v[88:89], v[16:17], v[78:79] neg_lo:[0,1] neg_hi:[0,1]
	v_pk_add_f32 v[122:123], v[68:69], v[102:103]
	v_pk_add_f32 v[20:21], v[68:69], v[102:103] neg_lo:[0,1] neg_hi:[0,1]
	v_pk_add_f32 v[78:79], v[104:105], v[96:97]
	v_pk_add_f32 v[74:75], v[104:105], v[96:97] neg_lo:[0,1] neg_hi:[0,1]
	v_pk_add_f32 v[96:97], v[92:93], v[90:91]
	v_pk_add_f32 v[8:9], v[92:93], v[90:91] neg_lo:[0,1] neg_hi:[0,1]
	v_pk_add_f32 v[102:103], v[98:99], v[94:95]
	v_pk_add_f32 v[12:13], v[98:99], v[94:95] neg_lo:[0,1] neg_hi:[0,1]
	v_pk_add_f32 v[98:99], v[18:19], v[76:77]
	v_pk_add_f32 v[4:5], v[18:19], v[76:77] neg_lo:[0,1] neg_hi:[0,1]
	v_pk_add_f32 v[18:19], v[72:73], v[86:87]
	v_pk_add_f32 v[92:93], v[72:73], v[86:87] neg_lo:[0,1] neg_hi:[0,1]
	v_pk_add_f32 v[86:87], v[84:85], v[100:101]
	v_pk_add_f32 v[22:23], v[84:85], v[100:101] neg_lo:[0,1] neg_hi:[0,1]
	v_pk_add_f32 v[100:101], v[24:25], v[10:11] op_sel:[0,1] op_sel_hi:[1,0] neg_hi:[0,1]
	v_pk_add_f32 v[10:11], v[24:25], v[10:11] op_sel:[0,1] op_sel_hi:[1,0] neg_lo:[0,1]
	v_mov_b32_e32 v24, v63
	v_pk_add_f32 v[84:85], v[108:109], v[64:65]
	v_cvt_f32_i32_e32 v24, v24
	v_pk_add_f32 v[76:77], v[108:109], v[64:65] neg_lo:[0,1] neg_hi:[0,1]
	v_pk_add_f32 v[104:105], v[66:67], v[26:27]
	v_pk_add_f32 v[14:15], v[66:67], v[26:27] neg_lo:[0,1] neg_hi:[0,1]
	v_mul_f32_e32 v25, 0x38800000, v24
	v_cos_f32_e32 v24, v25
	v_sin_f32_e32 v25, v25
	s_nop 0
	s_nop 0
	v_add_f32_e32 v62, v24, v24
	v_pk_mul_f32 v[26:27], v[24:25], v[24:25]
	v_mul_f32_e32 v62, v25, v62
	s_nop 0
	s_nop 0
	v_mov_b32_e32 v108, v25
	v_pk_add_f32 v[26:27], v[26:27], v[26:27] op_sel:[0,1] op_sel_hi:[0,1] neg_lo:[0,1] neg_hi:[0,1]
	v_pk_mul_f32 v[72:73], v[24:25], v[62:63] op_sel:[1,0] op_sel_hi:[0,0] neg_lo:[1,0]
	v_pk_mul_f32 v[94:95], v[18:19], v[108:109] op_sel:[1,0] op_sel_hi:[0,0] neg_hi:[1,0]
	v_pk_add_f32 v[16:17], v[70:71], v[80:81]
	v_pk_fma_f32 v[72:73], v[24:25], v[26:27], v[72:73]
	v_pk_fma_f32 v[18:19], v[18:19], v[24:25], v[94:95] op_sel_hi:[1,0,1]
	v_pk_mul_f32 v[24:25], v[62:63], s[48:49] op_sel_hi:[0,1]
	v_pk_fma_f32 v[94:95], v[26:27], s[40:41], v[24:25]
	s_nop 0
	v_pk_mul_f32 v[24:25], v[16:17], v[94:95] op_sel:[1,1] op_sel_hi:[0,1] neg_hi:[1,0]
	v_pk_add_f32 v[64:65], v[112:113], v[114:115]
	v_pk_fma_f32 v[24:25], v[16:17], v[94:95], v[24:25] op_sel_hi:[1,0,1]
	v_pk_mul_f32 v[16:17], v[62:63], v[72:73] op_sel:[0,1] op_sel_hi:[0,0] neg_lo:[0,1]
	v_pk_fma_f32 v[108:109], v[26:27], v[72:73], v[16:17]
	v_pk_mul_f32 v[16:17], v[64:65], v[72:73] op_sel:[1,1] op_sel_hi:[0,1] neg_hi:[1,0]
	v_pk_add_f32 v[90:91], v[106:107], v[82:83]
	v_pk_fma_f32 v[16:17], v[64:65], v[72:73], v[16:17] op_sel_hi:[1,0,1]
	v_pk_mul_f32 v[64:65], v[62:63], v[94:95] op_sel:[0,1] op_sel_hi:[0,0] neg_lo:[0,1]
	v_pk_fma_f32 v[94:95], v[26:27], v[94:95], v[64:65]
	s_nop 0
	v_pk_mul_f32 v[64:65], v[78:79], v[94:95] op_sel:[1,1] op_sel_hi:[0,1] neg_hi:[1,0]
	v_pk_add_f32 v[66:67], v[6:7], v[118:119]
	v_pk_fma_f32 v[72:73], v[78:79], v[94:95], v[64:65] op_sel_hi:[1,0,1]
	v_pk_mul_f32 v[64:65], v[62:63], v[108:109] op_sel:[0,1] op_sel_hi:[0,0] neg_lo:[0,1]
	v_pk_fma_f32 v[110:111], v[26:27], v[108:109], v[64:65]
	v_pk_mul_f32 v[64:65], v[84:85], v[108:109] op_sel:[1,1] op_sel_hi:[0,1] neg_hi:[1,0]
	v_pk_mul_f32 v[78:79], v[62:63], v[94:95] op_sel:[0,1] op_sel_hi:[0,0] neg_lo:[0,1]
	v_pk_fma_f32 v[64:65], v[84:85], v[108:109], v[64:65] op_sel_hi:[1,0,1]
	v_pk_fma_f32 v[84:85], v[26:27], v[94:95], v[78:79]
	s_nop 0
	v_pk_mul_f32 v[78:79], v[90:91], v[84:85] op_sel:[1,1] op_sel_hi:[0,1] neg_hi:[1,0]
	v_pk_add_f32 v[68:69], v[106:107], v[82:83] neg_lo:[0,1] neg_hi:[0,1]
	v_pk_fma_f32 v[78:79], v[90:91], v[84:85], v[78:79] op_sel_hi:[1,0,1]
	v_pk_mul_f32 v[90:91], v[62:63], v[110:111] op_sel:[0,1] op_sel_hi:[0,0] neg_lo:[0,1]
	v_pk_fma_f32 v[94:95], v[26:27], v[110:111], v[90:91]
	v_pk_mul_f32 v[90:91], v[66:67], v[110:111] op_sel:[1,1] op_sel_hi:[0,1] neg_hi:[1,0]
	v_pk_add_f32 v[106:107], v[116:117], v[120:121]
	v_pk_fma_f32 v[66:67], v[66:67], v[110:111], v[90:91] op_sel_hi:[1,0,1]
	v_pk_mul_f32 v[90:91], v[62:63], v[84:85] op_sel:[0,1] op_sel_hi:[0,0] neg_lo:[0,1]
	v_pk_fma_f32 v[108:109], v[26:27], v[84:85], v[90:91]
	s_nop 0
	v_pk_mul_f32 v[84:85], v[122:123], v[108:109] op_sel:[1,1] op_sel_hi:[0,1] neg_hi:[1,0]
	v_pk_add_f32 v[80:81], v[70:71], v[80:81] neg_lo:[0,1] neg_hi:[0,1]
	v_pk_fma_f32 v[90:91], v[122:123], v[108:109], v[84:85] op_sel_hi:[1,0,1]
	v_pk_mul_f32 v[84:85], v[62:63], v[94:95] op_sel:[0,1] op_sel_hi:[0,0] neg_lo:[0,1]
	v_pk_fma_f32 v[110:111], v[26:27], v[94:95], v[84:85]
	v_pk_mul_f32 v[84:85], v[86:87], v[94:95] op_sel:[1,1] op_sel_hi:[0,1] neg_hi:[1,0]
	v_pk_add_f32 v[82:83], v[112:113], v[114:115] neg_lo:[0,1] neg_hi:[0,1]
	v_pk_fma_f32 v[84:85], v[86:87], v[94:95], v[84:85] op_sel_hi:[1,0,1]
	v_pk_mul_f32 v[86:87], v[62:63], v[108:109] op_sel:[0,1] op_sel_hi:[0,0] neg_lo:[0,1]
	v_pk_fma_f32 v[108:109], v[26:27], v[108:109], v[86:87]
	s_nop 0
	v_pk_mul_f32 v[86:87], v[102:103], v[108:109] op_sel:[1,1] op_sel_hi:[0,1] neg_hi:[1,0]
	v_pk_add_f32 v[70:71], v[6:7], v[118:119] neg_lo:[0,1] neg_hi:[0,1]
	v_pk_fma_f32 v[94:95], v[102:103], v[108:109], v[86:87] op_sel_hi:[1,0,1]
	v_pk_mul_f32 v[86:87], v[62:63], v[110:111] op_sel:[0,1] op_sel_hi:[0,0] neg_lo:[0,1]
	v_pk_fma_f32 v[102:103], v[26:27], v[110:111], v[86:87]
	v_pk_mul_f32 v[86:87], v[104:105], v[110:111] op_sel:[1,1] op_sel_hi:[0,1] neg_hi:[1,0]
	v_pk_add_f32 v[6:7], v[116:117], v[120:121] neg_lo:[0,1] neg_hi:[0,1]
	v_pk_fma_f32 v[86:87], v[104:105], v[110:111], v[86:87] op_sel_hi:[1,0,1]
	v_pk_mul_f32 v[104:105], v[62:63], v[108:109] op_sel:[0,1] op_sel_hi:[0,0] neg_lo:[0,1]
	v_pk_fma_f32 v[104:105], v[26:27], v[108:109], v[104:105]
	s_nop 0
	v_pk_mul_f32 v[108:109], v[96:97], v[104:105] op_sel:[1,1] op_sel_hi:[0,1] neg_hi:[1,0]
	s_nop 0
	v_pk_fma_f32 v[96:97], v[96:97], v[104:105], v[108:109] op_sel_hi:[1,0,1]
	v_pk_mul_f32 v[108:109], v[62:63], v[102:103] op_sel:[0,1] op_sel_hi:[0,0] neg_lo:[0,1]
	v_pk_mul_f32 v[110:111], v[100:101], v[102:103] op_sel:[1,1] op_sel_hi:[0,1] neg_hi:[1,0]
	v_pk_fma_f32 v[108:109], v[26:27], v[102:103], v[108:109]
	v_pk_fma_f32 v[100:101], v[100:101], v[102:103], v[110:111] op_sel_hi:[1,0,1]
	v_pk_mul_f32 v[102:103], v[62:63], v[104:105] op_sel:[0,1] op_sel_hi:[0,0] neg_lo:[0,1]
	v_pk_fma_f32 v[102:103], v[26:27], v[104:105], v[102:103]
	s_nop 0
	v_pk_mul_f32 v[104:105], v[98:99], v[102:103] op_sel:[1,1] op_sel_hi:[0,1] neg_hi:[1,0]
	s_nop 0
	v_pk_fma_f32 v[98:99], v[98:99], v[102:103], v[104:105] op_sel_hi:[1,0,1]
	v_pk_mul_f32 v[104:105], v[62:63], v[108:109] op_sel:[0,1] op_sel_hi:[0,0] neg_lo:[0,1]
	v_pk_mul_f32 v[110:111], v[106:107], v[108:109] op_sel:[1,1] op_sel_hi:[0,1] neg_hi:[1,0]
	v_pk_fma_f32 v[104:105], v[26:27], v[108:109], v[104:105]
	v_pk_fma_f32 v[106:107], v[106:107], v[108:109], v[110:111] op_sel_hi:[1,0,1]
	v_pk_mul_f32 v[108:109], v[62:63], v[102:103] op_sel:[0,1] op_sel_hi:[0,0] neg_lo:[0,1]
	v_pk_fma_f32 v[102:103], v[26:27], v[102:103], v[108:109]
	s_nop 0
	v_pk_mul_f32 v[108:109], v[88:89], v[102:103] op_sel:[1,1] op_sel_hi:[0,1] neg_hi:[1,0]
	s_nop 0
	v_pk_fma_f32 v[88:89], v[88:89], v[102:103], v[108:109] op_sel_hi:[1,0,1]
	v_pk_mul_f32 v[108:109], v[62:63], v[104:105] op_sel:[0,1] op_sel_hi:[0,0] neg_lo:[0,1]
	v_pk_mul_f32 v[110:111], v[92:93], v[104:105] op_sel:[1,1] op_sel_hi:[0,1] neg_hi:[1,0]
	v_pk_fma_f32 v[108:109], v[26:27], v[104:105], v[108:109]
	v_pk_fma_f32 v[92:93], v[92:93], v[104:105], v[110:111] op_sel_hi:[1,0,1]
	v_pk_mul_f32 v[104:105], v[62:63], v[102:103] op_sel:[0,1] op_sel_hi:[0,0] neg_lo:[0,1]
	v_pk_fma_f32 v[102:103], v[26:27], v[102:103], v[104:105]
	s_nop 0
	v_pk_mul_f32 v[104:105], v[80:81], v[102:103] op_sel:[1,1] op_sel_hi:[0,1] neg_hi:[1,0]
	s_nop 0
	v_pk_fma_f32 v[80:81], v[80:81], v[102:103], v[104:105] op_sel_hi:[1,0,1]
	v_pk_mul_f32 v[104:105], v[62:63], v[108:109] op_sel:[0,1] op_sel_hi:[0,0] neg_lo:[0,1]
	v_pk_mul_f32 v[110:111], v[82:83], v[108:109] op_sel:[1,1] op_sel_hi:[0,1] neg_hi:[1,0]
	v_pk_fma_f32 v[104:105], v[26:27], v[108:109], v[104:105]
	v_pk_fma_f32 v[82:83], v[82:83], v[108:109], v[110:111] op_sel_hi:[1,0,1]
	v_pk_mul_f32 v[108:109], v[62:63], v[102:103] op_sel:[0,1] op_sel_hi:[0,0] neg_lo:[0,1]
	v_pk_fma_f32 v[102:103], v[26:27], v[102:103], v[108:109]
	s_nop 0
	v_pk_mul_f32 v[108:109], v[74:75], v[102:103] op_sel:[1,1] op_sel_hi:[0,1] neg_hi:[1,0]
	s_nop 0
	v_pk_fma_f32 v[74:75], v[74:75], v[102:103], v[108:109] op_sel_hi:[1,0,1]
	v_pk_mul_f32 v[108:109], v[62:63], v[104:105] op_sel:[0,1] op_sel_hi:[0,0] neg_lo:[0,1]
	v_pk_mul_f32 v[110:111], v[76:77], v[104:105] op_sel:[1,1] op_sel_hi:[0,1] neg_hi:[1,0]
	v_pk_fma_f32 v[108:109], v[26:27], v[104:105], v[108:109]
	v_pk_fma_f32 v[76:77], v[76:77], v[104:105], v[110:111] op_sel_hi:[1,0,1]
	v_pk_mul_f32 v[104:105], v[62:63], v[102:103] op_sel:[0,1] op_sel_hi:[0,0] neg_lo:[0,1]
	v_pk_fma_f32 v[102:103], v[26:27], v[102:103], v[104:105]
	s_nop 0
	v_pk_mul_f32 v[104:105], v[68:69], v[102:103] op_sel:[1,1] op_sel_hi:[0,1] neg_hi:[1,0]
	s_nop 0
	v_pk_fma_f32 v[68:69], v[68:69], v[102:103], v[104:105] op_sel_hi:[1,0,1]
	v_pk_mul_f32 v[104:105], v[62:63], v[108:109] op_sel:[0,1] op_sel_hi:[0,0] neg_lo:[0,1]
	v_pk_mul_f32 v[110:111], v[70:71], v[108:109] op_sel:[1,1] op_sel_hi:[0,1] neg_hi:[1,0]
	v_pk_fma_f32 v[104:105], v[26:27], v[108:109], v[104:105]
	v_pk_fma_f32 v[70:71], v[70:71], v[108:109], v[110:111] op_sel_hi:[1,0,1]
	v_pk_mul_f32 v[108:109], v[62:63], v[102:103] op_sel:[0,1] op_sel_hi:[0,0] neg_lo:[0,1]
	v_pk_fma_f32 v[102:103], v[26:27], v[102:103], v[108:109]
	s_nop 0
	v_pk_mul_f32 v[108:109], v[20:21], v[102:103] op_sel:[1,1] op_sel_hi:[0,1] neg_hi:[1,0]
	s_nop 0
	v_pk_fma_f32 v[20:21], v[20:21], v[102:103], v[108:109] op_sel_hi:[1,0,1]
	v_pk_mul_f32 v[108:109], v[62:63], v[104:105] op_sel:[0,1] op_sel_hi:[0,0] neg_lo:[0,1]
	v_pk_mul_f32 v[110:111], v[22:23], v[104:105] op_sel:[1,1] op_sel_hi:[0,1] neg_hi:[1,0]
	v_pk_fma_f32 v[108:109], v[26:27], v[104:105], v[108:109]
	v_pk_fma_f32 v[22:23], v[22:23], v[104:105], v[110:111] op_sel_hi:[1,0,1]
	v_pk_mul_f32 v[104:105], v[62:63], v[102:103] op_sel:[0,1] op_sel_hi:[0,0] neg_lo:[0,1]
	v_pk_fma_f32 v[102:103], v[26:27], v[102:103], v[104:105]
	s_nop 0
	v_pk_mul_f32 v[104:105], v[12:13], v[102:103] op_sel:[1,1] op_sel_hi:[0,1] neg_hi:[1,0]
	s_nop 0
	v_pk_fma_f32 v[12:13], v[12:13], v[102:103], v[104:105] op_sel_hi:[1,0,1]
	v_pk_mul_f32 v[104:105], v[62:63], v[108:109] op_sel:[0,1] op_sel_hi:[0,0] neg_lo:[0,1]
	v_pk_mul_f32 v[110:111], v[14:15], v[108:109] op_sel:[1,1] op_sel_hi:[0,1] neg_hi:[1,0]
	v_pk_fma_f32 v[104:105], v[26:27], v[108:109], v[104:105]
	v_pk_fma_f32 v[14:15], v[14:15], v[108:109], v[110:111] op_sel_hi:[1,0,1]
	v_pk_mul_f32 v[108:109], v[62:63], v[102:103] op_sel:[0,1] op_sel_hi:[0,0] neg_lo:[0,1]
	v_pk_fma_f32 v[102:103], v[26:27], v[102:103], v[108:109]
	s_nop 0
	v_pk_mul_f32 v[108:109], v[8:9], v[102:103] op_sel:[1,1] op_sel_hi:[0,1] neg_hi:[1,0]
	s_nop 0
	v_pk_fma_f32 v[8:9], v[8:9], v[102:103], v[108:109] op_sel_hi:[1,0,1]
	v_pk_mul_f32 v[108:109], v[62:63], v[104:105] op_sel:[0,1] op_sel_hi:[0,0] neg_lo:[0,1]
	v_pk_mul_f32 v[110:111], v[10:11], v[104:105] op_sel:[1,1] op_sel_hi:[0,1] neg_hi:[1,0]
	v_pk_fma_f32 v[108:109], v[26:27], v[104:105], v[108:109]
	v_pk_fma_f32 v[10:11], v[10:11], v[104:105], v[110:111] op_sel_hi:[1,0,1]
	v_pk_mul_f32 v[104:105], v[62:63], v[102:103] op_sel:[0,1] op_sel_hi:[0,0] neg_lo:[0,1]
	v_pk_fma_f32 v[26:27], v[26:27], v[102:103], v[104:105]
	s_nop 0
	v_pk_mul_f32 v[102:103], v[4:5], v[26:27] op_sel:[1,1] op_sel_hi:[0,1] neg_hi:[1,0]
	s_add_i32 s1, 16, 0x1e000
	v_pk_fma_f32 v[4:5], v[4:5], v[26:27], v[102:103] op_sel_hi:[1,0,1]
	s_nop 0
	s_nop 0
	v_pk_mul_f32 v[26:27], v[6:7], v[108:109] op_sel:[1,1] op_sel_hi:[0,1] neg_hi:[1,0]
	s_add_i32 s0, 16, 0x1f000
	v_pk_fma_f32 v[6:7], v[6:7], v[108:109], v[26:27] op_sel_hi:[1,0,1]
	v_lshrrev_b32_e32 v26, 5, v63
	v_bitop3_b32 v26, v26, v63, 15 bitop3:0x6c
	v_lshlrev_b32_e32 v26, 3, v26
	v_bfe_u32 v27, v63, 5, 4
	v_add_u32_e32 v62, 16, v26
	ds_write_b64 v62, v[2:3]
	v_bitop3_b32 v2, v27, v63, 16 bitop3:0x36
	v_lshlrev_b32_e32 v2, 3, v2
	v_add_u32_e32 v3, 16, v2
	ds_write_b64 v3, v[88:89] offset:4096
	ds_write_b64 v62, v[90:91] offset:8192
	ds_write_b64 v3, v[20:21] offset:12288
	ds_write_b64 v62, v[72:73] offset:16384
	ds_write_b64 v3, v[74:75] offset:20480
	ds_write_b64 v62, v[96:97] offset:24576
	ds_write_b64 v3, v[8:9] offset:28672
	ds_write_b64 v62, v[24:25] offset:32768
	ds_write_b64 v3, v[80:81] offset:36864
	ds_write_b64 v62, v[94:95] offset:40960
	ds_write_b64 v3, v[12:13] offset:45056
	ds_write_b64 v62, v[78:79] offset:49152
	ds_write_b64 v3, v[68:69] offset:53248
	ds_write_b64 v62, v[98:99] offset:57344
	ds_write_b64 v3, v[4:5] offset:61440
	v_add_u32_e32 v3, s47, v26
	ds_write_b64 v3, v[18:19]
	v_add_u32_e32 v3, s19, v2
	ds_write_b64 v3, v[92:93]
	v_add_u32_e32 v3, s18, v26
	ds_write_b64 v3, v[84:85]
	v_add_u32_e32 v3, s17, v2
	ds_write_b64 v3, v[22:23]
	v_add_u32_e32 v3, s13, v26
	ds_write_b64 v3, v[64:65]
	v_add_u32_e32 v3, s12, v2
	ds_write_b64 v3, v[76:77]
	v_add_u32_e32 v3, s11, v26
	ds_write_b64 v3, v[100:101]
	v_add_u32_e32 v3, s10, v2
	ds_write_b64 v3, v[10:11]
	v_add_u32_e32 v3, s9, v26
	ds_write_b64 v3, v[16:17]
	v_add_u32_e32 v3, s8, v2
	ds_write_b64 v3, v[82:83]
	v_add_u32_e32 v3, s7, v26
	ds_write_b64 v3, v[86:87]
	v_add_u32_e32 v3, s6, v2
	ds_write_b64 v3, v[14:15]
	v_add_u32_e32 v3, s5, v26
	ds_write_b64 v3, v[66:67]
	v_add_u32_e32 v3, s4, v2
	ds_write_b64 v3, v[70:71]
	v_add_u32_e32 v3, s1, v26
	v_add_u32_e32 v2, s0, v2
	v_mov_b32_e32 v21, v146
	ds_write_b64 v3, v[106:107]
	ds_write_b64 v2, v[6:7]
	s_waitcnt lgkmcnt(0)
	s_barrier
	s_lshl_b32 s44, s16, 14
	v_lshlrev_b32_e32 v2, 5, v21
	v_and_b32_e32 v4, 0xfffffe00, v2
	v_and_b32_e32 v20, 15, v21
	v_and_or_b32 v2, v21, 16, v4
	v_bitop3_b32 v4, v4, 16, v21 bitop3:0x34
	v_bitop3_b32 v72, v21, 8, 15 bitop3:0x6c
	v_lshl_add_u32 v26, v2, 3, 16
	v_lshlrev_b32_e32 v5, 3, v20
	v_lshl_add_u32 v126, v4, 3, 16
	v_lshlrev_b32_e32 v74, 3, v72
	v_add_u32_e32 v27, v26, v5
	v_add_u32_e32 v96, v126, v5
	v_add_u32_e32 v111, v26, v74
	v_add_u32_e32 v112, v126, v74
	ds_read_b64 v[2:3], v27
	ds_read_b64 v[4:5], v96
	v_bitop3_b32 v6, v21, 1, 15 bitop3:0x6c
	ds_read_b64 v[72:73], v111 offset:2048
	ds_read_b64 v[74:75], v112 offset:2048
	v_bitop3_b32 v76, v21, 9, 15 bitop3:0x6c
	v_lshlrev_b32_e32 v8, 3, v6
	v_lshlrev_b32_e32 v78, 3, v76
	v_add_u32_e32 v97, v26, v8
	v_add_u32_e32 v113, v26, v78
	ds_read_b64 v[6:7], v97 offset:256
	ds_read_b64 v[76:77], v113 offset:2304
	v_add_u32_e32 v98, v126, v8
	v_add_u32_e32 v114, v126, v78
	ds_read_b64 v[8:9], v98 offset:256
	ds_read_b64 v[78:79], v114 offset:2304
	s_waitcnt lgkmcnt(5)
	v_pk_add_f32 v[136:137], v[2:3], v[72:73]
	v_pk_add_f32 v[2:3], v[2:3], v[72:73] neg_lo:[0,1] neg_hi:[0,1]
	s_waitcnt lgkmcnt(4)
	v_pk_add_f32 v[72:73], v[4:5], v[74:75]
	v_pk_add_f32 v[4:5], v[4:5], v[74:75] neg_lo:[0,1] neg_hi:[0,1]
	v_bitop3_b32 v10, v21, 2, 15 bitop3:0x6c
	v_bitop3_b32 v80, v21, 10, 15 bitop3:0x6c
	v_lshlrev_b32_e32 v12, 3, v10
	v_lshlrev_b32_e32 v82, 3, v80
	v_pk_mul_f32 v[74:75], v[4:5], s[58:59] op_sel:[1,0] op_sel_hi:[0,0] neg_hi:[1,0]
	v_add_u32_e32 v99, v26, v12
	v_add_u32_e32 v115, v26, v82
	v_pk_fma_f32 v[4:5], v[4:5], s[46:47], v[74:75] op_sel_hi:[1,0,1]
	s_waitcnt lgkmcnt(2)
	v_pk_add_f32 v[74:75], v[6:7], v[76:77]
	v_pk_add_f32 v[6:7], v[6:7], v[76:77] neg_lo:[0,1] neg_hi:[0,1]
	ds_read_b64 v[10:11], v99 offset:512
	ds_read_b64 v[80:81], v115 offset:2560
	v_pk_mul_f32 v[76:77], v[6:7], s[62:63] op_sel:[1,0] op_sel_hi:[0,0] neg_hi:[1,0]
	v_add_u32_e32 v100, v126, v12
	v_bitop3_b32 v14, v21, 3, 15 bitop3:0x6c
	v_add_u32_e32 v116, v126, v82
	v_bitop3_b32 v84, v21, 11, 15 bitop3:0x6c
	v_pk_fma_f32 v[6:7], v[6:7], s[60:61], v[76:77] op_sel_hi:[1,0,1]
	s_waitcnt lgkmcnt(2)
	v_pk_add_f32 v[76:77], v[8:9], v[78:79]
	v_pk_add_f32 v[8:9], v[8:9], v[78:79] neg_lo:[0,1] neg_hi:[0,1]
	ds_read_b64 v[12:13], v100 offset:512
	v_lshlrev_b32_e32 v16, 3, v14
	ds_read_b64 v[82:83], v116 offset:2560
	v_lshlrev_b32_e32 v86, 3, v84
	v_add_u32_e32 v101, v26, v16
	v_add_u32_e32 v102, v126, v16
	v_add_u32_e32 v117, v26, v86
	v_add_u32_e32 v118, v126, v86
	v_pk_mul_f32 v[78:79], v[8:9], s[66:67] op_sel:[1,0] op_sel_hi:[0,0] neg_hi:[1,0]
	ds_read_b64 v[14:15], v101 offset:768
	ds_read_b64 v[16:17], v102 offset:768
	ds_read_b64 v[84:85], v117 offset:2816
	ds_read_b64 v[86:87], v118 offset:2816
	v_pk_fma_f32 v[8:9], v[8:9], s[64:65], v[78:79] op_sel_hi:[1,0,1]
	s_waitcnt lgkmcnt(6)
	v_pk_add_f32 v[78:79], v[10:11], v[80:81]
	v_pk_add_f32 v[10:11], v[10:11], v[80:81] neg_lo:[0,1] neg_hi:[0,1]
	v_bitop3_b32 v18, v21, 4, 15 bitop3:0x6c
	v_pk_mul_f32 v[80:81], v[10:11], s[70:71] op_sel:[1,0] op_sel_hi:[0,0] neg_hi:[1,0]
	v_bitop3_b32 v88, v21, 12, 15 bitop3:0x6c
	v_pk_fma_f32 v[10:11], v[10:11], s[70:71], v[80:81] op_sel_hi:[1,0,1]
	s_waitcnt lgkmcnt(4)
	v_pk_add_f32 v[80:81], v[12:13], v[82:83]
	v_pk_add_f32 v[12:13], v[12:13], v[82:83] neg_lo:[0,1] neg_hi:[0,1]
	v_lshlrev_b32_e32 v22, 3, v18
	v_lshlrev_b32_e32 v90, 3, v88
	v_pk_mul_f32 v[82:83], v[12:13], s[64:65] op_sel:[1,0] op_sel_hi:[0,0] neg_hi:[1,0]
	v_add_u32_e32 v103, v26, v22
	v_add_u32_e32 v119, v26, v90
	v_pk_fma_f32 v[12:13], v[12:13], s[66:67], v[82:83] op_sel_hi:[1,0,1]
	s_waitcnt lgkmcnt(1)
	v_pk_add_f32 v[82:83], v[14:15], v[84:85]
	v_pk_add_f32 v[14:15], v[14:15], v[84:85] neg_lo:[0,1] neg_hi:[0,1]
	ds_read_b64 v[18:19], v103 offset:1024
	v_add_u32_e32 v104, v126, v22
	v_bitop3_b32 v24, v21, 5, 15 bitop3:0x6c
	ds_read_b64 v[88:89], v119 offset:3072
	v_add_u32_e32 v120, v126, v90
	v_bitop3_b32 v92, v21, 13, 15 bitop3:0x6c
	ds_read_b64 v[22:23], v104 offset:1024
	v_lshlrev_b32_e32 v62, 3, v24
	ds_read_b64 v[90:91], v120 offset:3072
	v_lshlrev_b32_e32 v94, 3, v92
	v_pk_mul_f32 v[84:85], v[14:15], s[60:61] op_sel:[1,0] op_sel_hi:[0,0] neg_hi:[1,0]
	v_add_u32_e32 v105, v26, v62
	v_add_u32_e32 v121, v26, v94
	v_pk_fma_f32 v[14:15], v[14:15], s[62:63], v[84:85] op_sel_hi:[1,0,1]
	s_waitcnt lgkmcnt(4)
	v_pk_add_f32 v[84:85], v[16:17], v[86:87]
	v_pk_add_f32 v[16:17], v[16:17], v[86:87] neg_lo:[0,1] neg_hi:[0,1]
	ds_read_b64 v[24:25], v105 offset:1280
	ds_read_b64 v[92:93], v121 offset:3328
	v_add_u32_e32 v106, v126, v62
	v_bitop3_b32 v64, v21, 6, 15 bitop3:0x6c
	v_add_u32_e32 v122, v126, v94
	v_bitop3_b32 v123, v21, 14, 15 bitop3:0x6c
	v_pk_mul_f32 v[86:87], v[16:17], s[46:47] op_sel:[1,0] op_sel_hi:[0,0] neg_hi:[1,0]
	ds_read_b64 v[62:63], v106 offset:1280
	v_lshlrev_b32_e32 v66, 3, v64
	ds_read_b64 v[94:95], v122 offset:3328
	v_lshlrev_b32_e32 v124, 3, v123
	v_pk_fma_f32 v[16:17], v[16:17], s[58:59], v[86:87] op_sel_hi:[1,0,1]
	s_waitcnt lgkmcnt(6)
	v_pk_add_f32 v[86:87], v[18:19], v[88:89]
	v_pk_add_f32 v[18:19], v[18:19], v[88:89] neg_lo:[0,1] neg_hi:[0,1]
	v_add_u32_e32 v107, v26, v66
	v_add_u32_e32 v123, v26, v124
	v_xor_b32_e32 v89, 0x80000000, v18
	v_mov_b32_e32 v88, v19
	s_waitcnt lgkmcnt(4)
	v_pk_add_f32 v[18:19], v[22:23], v[90:91]
	v_pk_add_f32 v[22:23], v[22:23], v[90:91] neg_lo:[0,1] neg_hi:[0,1]
	ds_read_b64 v[64:65], v107 offset:1536
	ds_read_b64 v[128:129], v123 offset:3584
	v_pk_mul_f32 v[90:91], v[22:23], s[58:59] op_sel_hi:[1,0]
	v_xor_b32_e32 v139, 0x80000000, v22
	v_mov_b32_e32 v138, v23
	v_add_u32_e32 v108, v126, v66
	v_bitop3_b32 v68, v21, 7, 15 bitop3:0x6c
	v_add_u32_e32 v124, v126, v124
	v_bitop3_b32 v21, v21, 15, v21 bitop3:0xc
	v_pk_fma_f32 v[22:23], v[138:139], s[46:47], v[90:91] op_sel_hi:[1,0,1] neg_lo:[0,0,1] neg_hi:[0,0,1]
	s_waitcnt lgkmcnt(4)
	v_pk_add_f32 v[90:91], v[24:25], v[92:93]
	v_pk_add_f32 v[24:25], v[24:25], v[92:93] neg_lo:[0,1] neg_hi:[0,1]
	ds_read_b64 v[66:67], v108 offset:1536
	v_lshlrev_b32_e32 v70, 3, v68
	ds_read_b64 v[130:131], v124 offset:3584
	v_lshlrev_b32_e32 v21, 3, v21
	v_pk_mul_f32 v[92:93], v[24:25], s[62:63] op_sel_hi:[1,0]
	v_xor_b32_e32 v139, 0x80000000, v24
	v_mov_b32_e32 v138, v25
	v_add_u32_e32 v109, v26, v70
	v_add_u32_e32 v125, v26, v21
	v_pk_fma_f32 v[24:25], v[138:139], s[60:61], v[92:93] op_sel_hi:[1,0,1] neg_lo:[0,0,1] neg_hi:[0,0,1]
	s_waitcnt lgkmcnt(4)
	v_pk_add_f32 v[92:93], v[62:63], v[94:95]
	v_pk_add_f32 v[62:63], v[62:63], v[94:95] neg_lo:[0,1] neg_hi:[0,1]
	ds_read_b64 v[68:69], v109 offset:1792
	v_add_u32_e32 v110, v126, v70
	ds_read_b64 v[132:133], v125 offset:3840
	v_add_u32_e32 v126, v126, v21
	v_pk_mul_f32 v[94:95], v[62:63], s[66:67] op_sel_hi:[1,0]
	v_xor_b32_e32 v139, 0x80000000, v62
	v_mov_b32_e32 v138, v63
	ds_read_b64 v[70:71], v110 offset:1792
	ds_read_b64 v[134:135], v126 offset:3840
	v_pk_fma_f32 v[62:63], v[138:139], s[64:65], v[94:95] op_sel_hi:[1,0,1] neg_lo:[0,0,1] neg_hi:[0,0,1]
	s_waitcnt lgkmcnt(6)
	v_pk_add_f32 v[94:95], v[64:65], v[128:129]
	v_pk_add_f32 v[64:65], v[64:65], v[128:129] neg_lo:[0,1] neg_hi:[0,1]
	v_lshl_add_u64 v[0:1], s[44:45], 2, v[28:29]
	v_pk_mul_f32 v[128:129], v[64:65], s[70:71] op_sel_hi:[1,0]
	v_xor_b32_e32 v139, 0x80000000, v64
	v_mov_b32_e32 v138, v65
	v_pk_fma_f32 v[64:65], v[138:139], s[70:71], v[128:129] op_sel_hi:[1,0,1] neg_lo:[0,0,1] neg_hi:[0,0,1]
	s_waitcnt lgkmcnt(4)
	v_pk_add_f32 v[128:129], v[66:67], v[130:131]
	v_pk_add_f32 v[66:67], v[66:67], v[130:131] neg_lo:[0,1] neg_hi:[0,1]
	v_cvt_f32_i32_e32 v20, v20
	v_pk_mul_f32 v[130:131], v[66:67], s[64:65] op_sel_hi:[1,0]
	v_xor_b32_e32 v139, 0x80000000, v66
	v_mov_b32_e32 v138, v67
	v_pk_fma_f32 v[66:67], v[138:139], s[66:67], v[130:131] op_sel_hi:[1,0,1] neg_lo:[0,0,1] neg_hi:[0,0,1]
	s_waitcnt lgkmcnt(2)
	v_pk_add_f32 v[130:131], v[68:69], v[132:133]
	v_pk_add_f32 v[68:69], v[68:69], v[132:133] neg_lo:[0,1] neg_hi:[0,1]
	v_mul_f32_e32 v21, 0x3b000000, v20
	v_pk_mul_f32 v[132:133], v[68:69], s[60:61] op_sel_hi:[1,0]
	v_xor_b32_e32 v139, 0x80000000, v68
	v_mov_b32_e32 v138, v69
	v_pk_fma_f32 v[68:69], v[138:139], s[62:63], v[132:133] op_sel_hi:[1,0,1] neg_lo:[0,0,1] neg_hi:[0,0,1]
	s_waitcnt lgkmcnt(0)
	v_pk_add_f32 v[132:133], v[70:71], v[134:135]
	v_pk_add_f32 v[70:71], v[70:71], v[134:135] neg_lo:[0,1] neg_hi:[0,1]
	v_cos_f32_e32 v20, v21
	v_pk_mul_f32 v[134:135], v[70:71], s[46:47] op_sel_hi:[1,0]
	v_xor_b32_e32 v139, 0x80000000, v70
	v_mov_b32_e32 v138, v71
	v_pk_fma_f32 v[70:71], v[138:139], s[58:59], v[134:135] op_sel_hi:[1,0,1] neg_lo:[0,0,1] neg_hi:[0,0,1]
	v_pk_add_f32 v[134:135], v[136:137], v[86:87]
	v_pk_add_f32 v[86:87], v[136:137], v[86:87] neg_lo:[0,1] neg_hi:[0,1]
	v_pk_add_f32 v[136:137], v[72:73], v[18:19]
	v_pk_add_f32 v[18:19], v[72:73], v[18:19] neg_lo:[0,1] neg_hi:[0,1]
	v_sin_f32_e32 v21, v21
	s_nop 0
	s_nop 0
	v_pk_mul_f32 v[72:73], v[18:19], s[62:63] op_sel:[1,0] op_sel_hi:[0,0] neg_hi:[1,0]
	v_add_f32_e32 v26, v20, v20
	v_pk_fma_f32 v[18:19], v[18:19], s[60:61], v[72:73] op_sel_hi:[1,0,1]
	v_pk_add_f32 v[72:73], v[74:75], v[90:91]
	v_pk_add_f32 v[74:75], v[74:75], v[90:91] neg_lo:[0,1] neg_hi:[0,1]
	v_mul_f32_e32 v26, v21, v26
	s_nop 0
	s_nop 0
	v_pk_mul_f32 v[90:91], v[74:75], s[70:71] op_sel:[1,0] op_sel_hi:[0,0] neg_hi:[1,0]
	s_lshl_b32 s44, s16, 9
	v_pk_fma_f32 v[74:75], v[74:75], s[70:71], v[90:91] op_sel_hi:[1,0,1]
	v_pk_add_f32 v[90:91], v[76:77], v[92:93]
	v_pk_add_f32 v[76:77], v[76:77], v[92:93] neg_lo:[0,1] neg_hi:[0,1]
	s_mov_b64 s[28:29], -1
	s_nop 0
	s_nop 0
	v_pk_mul_f32 v[92:93], v[76:77], s[60:61] op_sel:[1,0] op_sel_hi:[0,0] neg_hi:[1,0]
	s_nop 0
	v_pk_fma_f32 v[76:77], v[76:77], s[62:63], v[92:93] op_sel_hi:[1,0,1]
	v_pk_add_f32 v[92:93], v[78:79], v[94:95]
	v_pk_add_f32 v[78:79], v[78:79], v[94:95] neg_lo:[0,1] neg_hi:[0,1]
	s_nop 0
	v_xor_b32_e32 v95, 0x80000000, v78
	v_mov_b32_e32 v94, v79
	v_pk_add_f32 v[78:79], v[80:81], v[128:129]
	v_pk_add_f32 v[80:81], v[80:81], v[128:129] neg_lo:[0,1] neg_hi:[0,1]
	s_nop 0
	v_pk_mul_f32 v[128:129], v[80:81], s[62:63] op_sel_hi:[1,0]
	v_xor_b32_e32 v139, 0x80000000, v80
	v_mov_b32_e32 v138, v81
	v_pk_fma_f32 v[80:81], v[138:139], s[60:61], v[128:129] op_sel_hi:[1,0,1] neg_lo:[0,0,1] neg_hi:[0,0,1]
	v_pk_add_f32 v[128:129], v[82:83], v[130:131]
	v_pk_add_f32 v[82:83], v[82:83], v[130:131] neg_lo:[0,1] neg_hi:[0,1]
	s_nop 0
	v_pk_mul_f32 v[130:131], v[82:83], s[70:71] op_sel_hi:[1,0]
	v_xor_b32_e32 v139, 0x80000000, v82
	v_mov_b32_e32 v138, v83
	v_pk_fma_f32 v[82:83], v[138:139], s[70:71], v[130:131] op_sel_hi:[1,0,1] neg_lo:[0,0,1] neg_hi:[0,0,1]
	v_pk_add_f32 v[130:131], v[84:85], v[132:133]
	v_pk_add_f32 v[84:85], v[84:85], v[132:133] neg_lo:[0,1] neg_hi:[0,1]
	s_nop 0
	v_pk_mul_f32 v[132:133], v[84:85], s[60:61] op_sel_hi:[1,0]
	v_xor_b32_e32 v139, 0x80000000, v84
	v_mov_b32_e32 v138, v85
	v_pk_fma_f32 v[84:85], v[138:139], s[62:63], v[132:133] op_sel_hi:[1,0,1] neg_lo:[0,0,1] neg_hi:[0,0,1]
	v_pk_add_f32 v[132:133], v[2:3], v[88:89]
	v_pk_add_f32 v[2:3], v[2:3], v[88:89] neg_lo:[0,1] neg_hi:[0,1]
	v_pk_add_f32 v[88:89], v[4:5], v[22:23]
	v_pk_add_f32 v[4:5], v[4:5], v[22:23] neg_lo:[0,1] neg_hi:[0,1]
	s_nop 0
	v_pk_mul_f32 v[22:23], v[4:5], s[62:63] op_sel:[1,0] op_sel_hi:[0,0] neg_hi:[1,0]
	s_nop 0
	v_pk_fma_f32 v[4:5], v[4:5], s[60:61], v[22:23] op_sel_hi:[1,0,1]
	v_pk_add_f32 v[22:23], v[6:7], v[24:25]
	v_pk_add_f32 v[6:7], v[6:7], v[24:25] neg_lo:[0,1] neg_hi:[0,1]
	s_nop 0
	v_pk_mul_f32 v[24:25], v[6:7], s[70:71] op_sel:[1,0] op_sel_hi:[0,0] neg_hi:[1,0]
	s_nop 0
	v_pk_fma_f32 v[6:7], v[6:7], s[70:71], v[24:25] op_sel_hi:[1,0,1]
	v_pk_add_f32 v[24:25], v[8:9], v[62:63]
	v_pk_add_f32 v[8:9], v[8:9], v[62:63] neg_lo:[0,1] neg_hi:[0,1]
	s_nop 0
	v_pk_mul_f32 v[62:63], v[8:9], s[60:61] op_sel:[1,0] op_sel_hi:[0,0] neg_hi:[1,0]
	s_nop 0
	v_pk_fma_f32 v[8:9], v[8:9], s[62:63], v[62:63] op_sel_hi:[1,0,1]
	v_pk_add_f32 v[62:63], v[10:11], v[64:65]
	v_pk_add_f32 v[10:11], v[10:11], v[64:65] neg_lo:[0,1] neg_hi:[0,1]
	s_nop 0
	v_xor_b32_e32 v65, 0x80000000, v10
	v_mov_b32_e32 v64, v11
	v_pk_add_f32 v[10:11], v[12:13], v[66:67]
	v_pk_add_f32 v[12:13], v[12:13], v[66:67] neg_lo:[0,1] neg_hi:[0,1]
	s_nop 0
	v_pk_mul_f32 v[66:67], v[12:13], s[62:63] op_sel_hi:[1,0]
	v_xor_b32_e32 v139, 0x80000000, v12
	v_mov_b32_e32 v138, v13
	v_pk_fma_f32 v[12:13], v[138:139], s[60:61], v[66:67] op_sel_hi:[1,0,1] neg_lo:[0,0,1] neg_hi:[0,0,1]
	v_pk_add_f32 v[66:67], v[14:15], v[68:69]
	v_pk_add_f32 v[14:15], v[14:15], v[68:69] neg_lo:[0,1] neg_hi:[0,1]
	s_nop 0
	v_pk_mul_f32 v[68:69], v[14:15], s[70:71] op_sel_hi:[1,0]
	v_xor_b32_e32 v139, 0x80000000, v14
	v_mov_b32_e32 v138, v15
	v_pk_fma_f32 v[14:15], v[138:139], s[70:71], v[68:69] op_sel_hi:[1,0,1] neg_lo:[0,0,1] neg_hi:[0,0,1]
	v_pk_add_f32 v[68:69], v[16:17], v[70:71]
	v_pk_add_f32 v[16:17], v[16:17], v[70:71] neg_lo:[0,1] neg_hi:[0,1]
	s_nop 0
	v_pk_mul_f32 v[70:71], v[16:17], s[60:61] op_sel_hi:[1,0]
	v_xor_b32_e32 v139, 0x80000000, v16
	v_mov_b32_e32 v138, v17
	v_pk_fma_f32 v[16:17], v[138:139], s[62:63], v[70:71] op_sel_hi:[1,0,1] neg_lo:[0,0,1] neg_hi:[0,0,1]
	v_pk_add_f32 v[70:71], v[134:135], v[92:93]
	v_pk_add_f32 v[92:93], v[134:135], v[92:93] neg_lo:[0,1] neg_hi:[0,1]
	v_pk_add_f32 v[134:135], v[136:137], v[78:79]
	v_pk_add_f32 v[78:79], v[136:137], v[78:79] neg_lo:[0,1] neg_hi:[0,1]
	s_nop 0
	v_pk_mul_f32 v[136:137], v[78:79], s[70:71] op_sel:[1,0] op_sel_hi:[0,0] neg_hi:[1,0]
	s_nop 0
	v_pk_fma_f32 v[78:79], v[78:79], s[70:71], v[136:137] op_sel_hi:[1,0,1]
	v_pk_add_f32 v[136:137], v[72:73], v[128:129]
	v_pk_add_f32 v[72:73], v[72:73], v[128:129] neg_lo:[0,1] neg_hi:[0,1]
	s_nop 0
	v_xor_b32_e32 v129, 0x80000000, v72
	v_mov_b32_e32 v128, v73
	v_pk_add_f32 v[72:73], v[90:91], v[130:131]
	v_pk_add_f32 v[90:91], v[90:91], v[130:131] neg_lo:[0,1] neg_hi:[0,1]
	s_nop 0
	v_pk_mul_f32 v[130:131], v[90:91], s[70:71] op_sel_hi:[1,0]
	v_xor_b32_e32 v139, 0x80000000, v90
	v_mov_b32_e32 v138, v91
	v_pk_fma_f32 v[90:91], v[138:139], s[70:71], v[130:131] op_sel_hi:[1,0,1] neg_lo:[0,0,1] neg_hi:[0,0,1]
	v_pk_add_f32 v[130:131], v[86:87], v[94:95]
	v_pk_add_f32 v[86:87], v[86:87], v[94:95] neg_lo:[0,1] neg_hi:[0,1]
	v_pk_add_f32 v[94:95], v[18:19], v[80:81]
	v_pk_add_f32 v[18:19], v[18:19], v[80:81] neg_lo:[0,1] neg_hi:[0,1]
	s_nop 0
	v_pk_mul_f32 v[80:81], v[18:19], s[70:71] op_sel:[1,0] op_sel_hi:[0,0] neg_hi:[1,0]
	s_nop 0
	v_pk_fma_f32 v[18:19], v[18:19], s[70:71], v[80:81] op_sel_hi:[1,0,1]
	v_pk_add_f32 v[80:81], v[74:75], v[82:83]
	v_pk_add_f32 v[74:75], v[74:75], v[82:83] neg_lo:[0,1] neg_hi:[0,1]
	s_nop 0
	v_xor_b32_e32 v83, 0x80000000, v74
	v_mov_b32_e32 v82, v75
	v_pk_add_f32 v[74:75], v[76:77], v[84:85]
	v_pk_add_f32 v[76:77], v[76:77], v[84:85] neg_lo:[0,1] neg_hi:[0,1]
	s_nop 0
	v_pk_mul_f32 v[84:85], v[76:77], s[70:71] op_sel_hi:[1,0]
	v_xor_b32_e32 v139, 0x80000000, v76
	v_mov_b32_e32 v138, v77
	v_pk_fma_f32 v[76:77], v[138:139], s[70:71], v[84:85] op_sel_hi:[1,0,1] neg_lo:[0,0,1] neg_hi:[0,0,1]
	v_pk_add_f32 v[84:85], v[132:133], v[62:63]
	v_pk_add_f32 v[62:63], v[132:133], v[62:63] neg_lo:[0,1] neg_hi:[0,1]
	v_pk_add_f32 v[132:133], v[88:89], v[10:11]
	v_pk_add_f32 v[10:11], v[88:89], v[10:11] neg_lo:[0,1] neg_hi:[0,1]
	s_nop 0
	v_pk_mul_f32 v[88:89], v[10:11], s[70:71] op_sel:[1,0] op_sel_hi:[0,0] neg_hi:[1,0]
	s_nop 0
	v_pk_fma_f32 v[10:11], v[10:11], s[70:71], v[88:89] op_sel_hi:[1,0,1]
	v_pk_add_f32 v[88:89], v[22:23], v[66:67]
	v_pk_add_f32 v[22:23], v[22:23], v[66:67] neg_lo:[0,1] neg_hi:[0,1]
	s_nop 0
	v_xor_b32_e32 v67, 0x80000000, v22
	v_mov_b32_e32 v66, v23
	v_pk_add_f32 v[22:23], v[24:25], v[68:69]
	v_pk_add_f32 v[24:25], v[24:25], v[68:69] neg_lo:[0,1] neg_hi:[0,1]
	s_nop 0
	v_pk_mul_f32 v[68:69], v[24:25], s[70:71] op_sel_hi:[1,0]
	v_xor_b32_e32 v139, 0x80000000, v24
	v_mov_b32_e32 v138, v25
	v_pk_fma_f32 v[24:25], v[138:139], s[70:71], v[68:69] op_sel_hi:[1,0,1] neg_lo:[0,0,1] neg_hi:[0,0,1]
	v_pk_add_f32 v[68:69], v[2:3], v[64:65]
	v_pk_add_f32 v[2:3], v[2:3], v[64:65] neg_lo:[0,1] neg_hi:[0,1]
	v_pk_add_f32 v[64:65], v[4:5], v[12:13]
	v_pk_add_f32 v[4:5], v[4:5], v[12:13] neg_lo:[0,1] neg_hi:[0,1]
	s_nop 0
	v_pk_mul_f32 v[12:13], v[4:5], s[70:71] op_sel:[1,0] op_sel_hi:[0,0] neg_hi:[1,0]
	s_nop 0
	v_pk_fma_f32 v[4:5], v[4:5], s[70:71], v[12:13] op_sel_hi:[1,0,1]
	v_pk_add_f32 v[12:13], v[6:7], v[14:15]
	v_pk_add_f32 v[6:7], v[6:7], v[14:15] neg_lo:[0,1] neg_hi:[0,1]
	v_pk_add_f32 v[140:141], v[68:69], v[12:13]
	v_xor_b32_e32 v15, 0x80000000, v6
	v_mov_b32_e32 v14, v7
	v_pk_add_f32 v[6:7], v[8:9], v[16:17]
	v_pk_add_f32 v[8:9], v[8:9], v[16:17] neg_lo:[0,1] neg_hi:[0,1]
	v_pk_add_f32 v[142:143], v[64:65], v[6:7]
	v_pk_mul_f32 v[16:17], v[8:9], s[70:71] op_sel_hi:[1,0]
	s_nop 0
	v_pk_fma_f32 v[8:9], v[8:9], s[70:71], v[16:17] op_sel:[1,0,0] op_sel_hi:[0,0,1] neg_lo:[0,0,1] neg_hi:[1,0,1]
	v_pk_add_f32 v[16:17], v[70:71], v[136:137]
	v_pk_add_f32 v[70:71], v[70:71], v[136:137] neg_lo:[0,1] neg_hi:[0,1]
	v_pk_add_f32 v[136:137], v[134:135], v[72:73]
	v_pk_add_f32 v[72:73], v[134:135], v[72:73] neg_lo:[0,1] neg_hi:[0,1]
	v_pk_add_f32 v[138:139], v[84:85], v[88:89] neg_lo:[0,1] neg_hi:[0,1]
	v_xor_b32_e32 v135, 0x80000000, v72
	v_mov_b32_e32 v134, v73
	v_pk_add_f32 v[72:73], v[92:93], v[128:129]
	v_pk_add_f32 v[92:93], v[92:93], v[128:129] neg_lo:[0,1] neg_hi:[0,1]
	v_pk_add_f32 v[128:129], v[78:79], v[90:91]
	v_pk_add_f32 v[78:79], v[78:79], v[90:91] neg_lo:[0,1] neg_hi:[0,1]
	v_pk_add_f32 v[6:7], v[64:65], v[6:7] neg_lo:[0,1] neg_hi:[0,1]
	v_xor_b32_e32 v91, 0x80000000, v78
	v_mov_b32_e32 v90, v79
	v_pk_add_f32 v[78:79], v[130:131], v[80:81]
	v_pk_add_f32 v[130:131], v[130:131], v[80:81] neg_lo:[0,1] neg_hi:[0,1]
	v_pk_add_f32 v[80:81], v[94:95], v[74:75]
	v_pk_add_f32 v[74:75], v[94:95], v[74:75] neg_lo:[0,1] neg_hi:[0,1]
	v_xor_b32_e32 v149, 0x80000000, v6
	v_xor_b32_e32 v95, 0x80000000, v74
	v_mov_b32_e32 v94, v75
	v_pk_add_f32 v[74:75], v[86:87], v[82:83]
	v_pk_add_f32 v[82:83], v[86:87], v[82:83] neg_lo:[0,1] neg_hi:[0,1]
	v_pk_add_f32 v[86:87], v[18:19], v[76:77]
	v_pk_add_f32 v[18:19], v[18:19], v[76:77] neg_lo:[0,1] neg_hi:[0,1]
	v_mov_b32_e32 v148, v7
	v_xor_b32_e32 v77, 0x80000000, v18
	v_mov_b32_e32 v76, v19
	v_pk_add_f32 v[18:19], v[84:85], v[88:89]
	v_pk_add_f32 v[88:89], v[132:133], v[22:23]
	v_pk_add_f32 v[22:23], v[132:133], v[22:23] neg_lo:[0,1] neg_hi:[0,1]
	v_pk_add_f32 v[6:7], v[2:3], v[14:15]
	v_xor_b32_e32 v133, 0x80000000, v22
	v_mov_b32_e32 v132, v23
	v_pk_add_f32 v[22:23], v[62:63], v[66:67]
	v_pk_add_f32 v[62:63], v[62:63], v[66:67] neg_lo:[0,1] neg_hi:[0,1]
	v_pk_add_f32 v[66:67], v[10:11], v[24:25]
	v_pk_add_f32 v[10:11], v[10:11], v[24:25] neg_lo:[0,1] neg_hi:[0,1]
	v_pk_add_f32 v[150:151], v[2:3], v[14:15] neg_lo:[0,1] neg_hi:[0,1]
	v_pk_add_f32 v[2:3], v[4:5], v[8:9] neg_lo:[0,1] neg_hi:[0,1]
	v_pk_add_f32 v[68:69], v[68:69], v[12:13] neg_lo:[0,1] neg_hi:[0,1]
	v_pk_add_f32 v[156:157], v[4:5], v[8:9]
	v_xor_b32_e32 v159, 0x80000000, v2
	v_mov_b32_e32 v158, v3
	v_pk_add_f32 v[2:3], v[16:17], v[136:137]
	v_pk_add_f32 v[84:85], v[16:17], v[136:137] neg_lo:[0,1] neg_hi:[0,1]
	v_pk_add_f32 v[136:137], v[70:71], v[134:135]
	v_pk_add_f32 v[16:17], v[70:71], v[134:135] neg_lo:[0,1] neg_hi:[0,1]
	v_pk_add_f32 v[134:135], v[72:73], v[128:129]
	v_pk_add_f32 v[70:71], v[72:73], v[128:129] neg_lo:[0,1] neg_hi:[0,1]
	v_pk_add_f32 v[128:129], v[92:93], v[90:91]
	v_pk_add_f32 v[8:9], v[92:93], v[90:91] neg_lo:[0,1] neg_hi:[0,1]
	v_pk_add_f32 v[72:73], v[78:79], v[80:81]
	v_pk_add_f32 v[80:81], v[78:79], v[80:81] neg_lo:[0,1] neg_hi:[0,1]
	v_pk_add_f32 v[92:93], v[130:131], v[94:95]
	v_pk_add_f32 v[12:13], v[130:131], v[94:95] neg_lo:[0,1] neg_hi:[0,1]
	v_pk_add_f32 v[78:79], v[74:75], v[86:87]
	v_pk_add_f32 v[64:65], v[74:75], v[86:87] neg_lo:[0,1] neg_hi:[0,1]
	v_pk_add_f32 v[130:131], v[82:83], v[76:77]
	v_pk_add_f32 v[4:5], v[82:83], v[76:77] neg_lo:[0,1] neg_hi:[0,1]
	v_pk_add_f32 v[76:77], v[18:19], v[88:89]
	v_pk_add_f32 v[88:89], v[18:19], v[88:89] neg_lo:[0,1] neg_hi:[0,1]
	v_pk_add_f32 v[86:87], v[138:139], v[132:133]
	v_pk_add_f32 v[18:19], v[138:139], v[132:133] neg_lo:[0,1] neg_hi:[0,1]
	v_pk_add_f32 v[132:133], v[62:63], v[10:11] op_sel:[0,1] op_sel_hi:[1,0] neg_hi:[0,1]
	v_pk_add_f32 v[10:11], v[62:63], v[10:11] op_sel:[0,1] op_sel_hi:[1,0] neg_lo:[0,1]
	v_pk_mul_f32 v[24:25], v[20:21], v[20:21]
	s_nop 0
	v_pk_add_f32 v[24:25], v[24:25], v[24:25] op_sel:[0,1] op_sel_hi:[0,1] neg_lo:[0,1] neg_hi:[0,1]
	v_pk_mul_f32 v[62:63], v[20:21], v[26:27] op_sel:[1,0] op_sel_hi:[0,0] neg_lo:[1,0]
	v_pk_add_f32 v[90:91], v[22:23], v[66:67]
	v_pk_add_f32 v[74:75], v[22:23], v[66:67] neg_lo:[0,1] neg_hi:[0,1]
	v_pk_add_f32 v[22:23], v[140:141], v[142:143]
	v_pk_add_f32 v[82:83], v[140:141], v[142:143] neg_lo:[0,1] neg_hi:[0,1]
	v_pk_add_f32 v[138:139], v[68:69], v[148:149]
	v_pk_add_f32 v[14:15], v[68:69], v[148:149] neg_lo:[0,1] neg_hi:[0,1]
	v_pk_fma_f32 v[68:69], v[20:21], v[24:25], v[62:63]
	v_mov_b32_e32 v142, v21
	s_nop 0
	v_pk_mul_f32 v[62:63], v[142:143], v[76:77] op_sel:[0,1] op_sel_hi:[0,0] neg_hi:[0,1]
	v_pk_fma_f32 v[20:21], v[20:21], v[76:77], v[62:63] op_sel_hi:[0,1,1]
	v_pk_mul_f32 v[62:63], v[26:27], s[48:49] op_sel_hi:[0,1]
	v_pk_fma_f32 v[76:77], v[24:25], s[40:41], v[62:63]
	s_nop 0
	v_pk_mul_f32 v[62:63], v[76:77], v[72:73] op_sel:[1,1] op_sel_hi:[1,0] neg_hi:[0,1]
	v_pk_add_f32 v[94:95], v[6:7], v[156:157]
	v_pk_fma_f32 v[62:63], v[72:73], v[76:77], v[62:63] op_sel_hi:[1,0,1]
	v_pk_mul_f32 v[72:73], v[26:27], v[68:69] op_sel:[0,1] op_sel_hi:[0,0] neg_lo:[0,1]
	v_pk_fma_f32 v[142:143], v[24:25], v[68:69], v[72:73]
	v_pk_mul_f32 v[72:73], v[68:69], v[22:23] op_sel:[1,1] op_sel_hi:[1,0] neg_hi:[0,1]
	v_pk_add_f32 v[140:141], v[150:151], v[158:159]
	v_pk_fma_f32 v[22:23], v[68:69], v[22:23], v[72:73] op_sel_hi:[0,1,1]
	v_pk_mul_f32 v[68:69], v[26:27], v[76:77] op_sel:[0,1] op_sel_hi:[0,0] neg_lo:[0,1]
	v_pk_fma_f32 v[76:77], v[24:25], v[76:77], v[68:69]
	s_nop 0
	v_pk_mul_f32 v[68:69], v[134:135], v[76:77] op_sel:[1,1] op_sel_hi:[0,1] neg_hi:[1,0]
	v_pk_add_f32 v[66:67], v[6:7], v[156:157] neg_lo:[0,1] neg_hi:[0,1]
	v_pk_fma_f32 v[72:73], v[134:135], v[76:77], v[68:69] op_sel_hi:[1,0,1]
	v_pk_mul_f32 v[68:69], v[26:27], v[142:143] op_sel:[0,1] op_sel_hi:[0,0] neg_lo:[0,1]
	v_pk_fma_f32 v[134:135], v[24:25], v[142:143], v[68:69]
	v_pk_mul_f32 v[68:69], v[142:143], v[90:91] op_sel:[1,1] op_sel_hi:[1,0] neg_hi:[0,1]
	v_pk_add_f32 v[6:7], v[150:151], v[158:159] neg_lo:[0,1] neg_hi:[0,1]
	v_pk_fma_f32 v[68:69], v[90:91], v[142:143], v[68:69] op_sel_hi:[1,0,1]
	v_pk_mul_f32 v[90:91], v[26:27], v[76:77] op_sel:[0,1] op_sel_hi:[0,0] neg_lo:[0,1]
	v_pk_fma_f32 v[90:91], v[24:25], v[76:77], v[90:91]
	s_nop 0
	v_pk_mul_f32 v[76:77], v[78:79], v[90:91] op_sel:[1,1] op_sel_hi:[0,1] neg_hi:[1,0]
	s_nop 0
	v_pk_fma_f32 v[78:79], v[78:79], v[90:91], v[76:77] op_sel_hi:[1,0,1]
	v_pk_mul_f32 v[76:77], v[26:27], v[134:135] op_sel:[0,1] op_sel_hi:[0,0] neg_lo:[0,1]
	v_pk_fma_f32 v[142:143], v[24:25], v[134:135], v[76:77]
	v_pk_mul_f32 v[76:77], v[134:135], v[94:95] op_sel:[1,1] op_sel_hi:[1,0] neg_hi:[0,1]
	s_nop 0
	v_pk_fma_f32 v[76:77], v[94:95], v[134:135], v[76:77] op_sel_hi:[1,0,1]
	v_pk_mul_f32 v[94:95], v[26:27], v[90:91] op_sel:[0,1] op_sel_hi:[0,0] neg_lo:[0,1]
	v_pk_fma_f32 v[94:95], v[24:25], v[90:91], v[94:95]
	s_nop 0
	v_pk_mul_f32 v[90:91], v[136:137], v[94:95] op_sel:[1,1] op_sel_hi:[0,1] neg_hi:[1,0]
	v_xor_b32_e32 v134, 0x80000000, v143
	v_pk_fma_f32 v[90:91], v[136:137], v[94:95], v[90:91] op_sel_hi:[1,0,1]
	v_pk_mul_f32 v[136:137], v[86:87], v[142:143] op_sel:[1,1] op_sel_hi:[0,1] neg_hi:[1,0]
	v_mov_b32_e32 v135, v142
	v_pk_fma_f32 v[86:87], v[86:87], v[142:143], v[136:137] op_sel_hi:[1,0,1]
	v_pk_mul_f32 v[136:137], v[26:27], v[94:95] op_sel:[0,1] op_sel_hi:[0,0] neg_lo:[0,1]
	v_pk_mul_f32 v[134:135], v[26:27], v[134:135] op_sel_hi:[0,1]
	v_pk_fma_f32 v[136:137], v[24:25], v[94:95], v[136:137]
	v_pk_fma_f32 v[134:135], v[24:25], v[142:143], v[134:135]
	v_pk_mul_f32 v[94:95], v[92:93], v[136:137] op_sel:[1,1] op_sel_hi:[0,1] neg_hi:[1,0]
	s_nop 0
	v_pk_fma_f32 v[94:95], v[92:93], v[136:137], v[94:95] op_sel_hi:[1,0,1]
	v_pk_mul_f32 v[92:93], v[26:27], v[134:135] op_sel:[0,1] op_sel_hi:[0,0] neg_lo:[0,1]
	v_pk_fma_f32 v[142:143], v[24:25], v[134:135], v[92:93]
	v_pk_mul_f32 v[92:93], v[138:139], v[134:135] op_sel:[1,1] op_sel_hi:[0,1] neg_hi:[1,0]
	s_nop 0
	v_pk_fma_f32 v[92:93], v[138:139], v[134:135], v[92:93] op_sel_hi:[1,0,1]
	v_pk_mul_f32 v[134:135], v[26:27], v[136:137] op_sel:[0,1] op_sel_hi:[0,0] neg_lo:[0,1]
	s_nop 0
	v_pk_fma_f32 v[134:135], v[24:25], v[136:137], v[134:135]
	v_pk_mul_f32 v[138:139], v[132:133], v[142:143] op_sel:[1,1] op_sel_hi:[0,1] neg_hi:[1,0]
	v_pk_mul_f32 v[136:137], v[128:129], v[134:135] op_sel:[1,1] op_sel_hi:[0,1] neg_hi:[1,0]
	v_pk_fma_f32 v[132:133], v[132:133], v[142:143], v[138:139] op_sel_hi:[1,0,1]
	v_pk_fma_f32 v[128:129], v[128:129], v[134:135], v[136:137] op_sel_hi:[1,0,1]
	v_pk_mul_f32 v[138:139], v[26:27], v[134:135] op_sel:[0,1] op_sel_hi:[0,0] neg_lo:[0,1]
	v_pk_mul_f32 v[136:137], v[26:27], v[142:143] op_sel:[0,1] op_sel_hi:[0,0] neg_lo:[0,1]
	v_pk_fma_f32 v[134:135], v[24:25], v[134:135], v[138:139]
	v_pk_fma_f32 v[136:137], v[24:25], v[142:143], v[136:137]
	v_pk_mul_f32 v[138:139], v[130:131], v[134:135] op_sel:[1,1] op_sel_hi:[0,1] neg_hi:[1,0]
	s_nop 0
	v_pk_fma_f32 v[130:131], v[130:131], v[134:135], v[138:139] op_sel_hi:[1,0,1]
	v_pk_mul_f32 v[138:139], v[26:27], v[136:137] op_sel:[0,1] op_sel_hi:[0,0] neg_lo:[0,1]
	v_pk_mul_f32 v[142:143], v[140:141], v[136:137] op_sel:[1,1] op_sel_hi:[0,1] neg_hi:[1,0]
	v_pk_fma_f32 v[138:139], v[24:25], v[136:137], v[138:139]
	v_pk_fma_f32 v[136:137], v[140:141], v[136:137], v[142:143] op_sel_hi:[1,0,1]
	v_pk_mul_f32 v[140:141], v[26:27], v[134:135] op_sel:[0,1] op_sel_hi:[0,0] neg_lo:[0,1]
	v_pk_fma_f32 v[134:135], v[24:25], v[134:135], v[140:141]
	s_nop 0
	v_pk_mul_f32 v[140:141], v[84:85], v[134:135] op_sel:[1,1] op_sel_hi:[0,1] neg_hi:[1,0]
	s_nop 0
	v_pk_fma_f32 v[84:85], v[84:85], v[134:135], v[140:141] op_sel_hi:[1,0,1]
	v_pk_mul_f32 v[140:141], v[26:27], v[138:139] op_sel:[0,1] op_sel_hi:[0,0] neg_lo:[0,1]
	v_pk_mul_f32 v[142:143], v[88:89], v[138:139] op_sel:[1,1] op_sel_hi:[0,1] neg_hi:[1,0]
	v_pk_fma_f32 v[140:141], v[24:25], v[138:139], v[140:141]
	v_pk_fma_f32 v[88:89], v[88:89], v[138:139], v[142:143] op_sel_hi:[1,0,1]
	v_pk_mul_f32 v[138:139], v[26:27], v[134:135] op_sel:[0,1] op_sel_hi:[0,0] neg_lo:[0,1]
	v_pk_fma_f32 v[134:135], v[24:25], v[134:135], v[138:139]
	s_nop 0
	v_pk_mul_f32 v[138:139], v[80:81], v[134:135] op_sel:[1,1] op_sel_hi:[0,1] neg_hi:[1,0]
	s_nop 0
	v_pk_fma_f32 v[80:81], v[80:81], v[134:135], v[138:139] op_sel_hi:[1,0,1]
	v_pk_mul_f32 v[138:139], v[26:27], v[140:141] op_sel:[0,1] op_sel_hi:[0,0] neg_lo:[0,1]
	v_pk_mul_f32 v[142:143], v[82:83], v[140:141] op_sel:[1,1] op_sel_hi:[0,1] neg_hi:[1,0]
	v_pk_fma_f32 v[138:139], v[24:25], v[140:141], v[138:139]
	v_pk_fma_f32 v[82:83], v[82:83], v[140:141], v[142:143] op_sel_hi:[1,0,1]
	v_pk_mul_f32 v[140:141], v[26:27], v[134:135] op_sel:[0,1] op_sel_hi:[0,0] neg_lo:[0,1]
	v_pk_fma_f32 v[134:135], v[24:25], v[134:135], v[140:141]
	s_nop 0
	v_pk_mul_f32 v[140:141], v[70:71], v[134:135] op_sel:[1,1] op_sel_hi:[0,1] neg_hi:[1,0]
	s_nop 0
	v_pk_fma_f32 v[70:71], v[70:71], v[134:135], v[140:141] op_sel_hi:[1,0,1]
	v_pk_mul_f32 v[140:141], v[26:27], v[138:139] op_sel:[0,1] op_sel_hi:[0,0] neg_lo:[0,1]
	v_pk_mul_f32 v[142:143], v[74:75], v[138:139] op_sel:[1,1] op_sel_hi:[0,1] neg_hi:[1,0]
	v_pk_fma_f32 v[140:141], v[24:25], v[138:139], v[140:141]
	v_pk_fma_f32 v[74:75], v[74:75], v[138:139], v[142:143] op_sel_hi:[1,0,1]
	v_pk_mul_f32 v[138:139], v[26:27], v[134:135] op_sel:[0,1] op_sel_hi:[0,0] neg_lo:[0,1]
	v_pk_fma_f32 v[134:135], v[24:25], v[134:135], v[138:139]
	s_nop 0
	v_pk_mul_f32 v[138:139], v[64:65], v[134:135] op_sel:[1,1] op_sel_hi:[0,1] neg_hi:[1,0]
	s_nop 0
	v_pk_fma_f32 v[64:65], v[64:65], v[134:135], v[138:139] op_sel_hi:[1,0,1]
	v_pk_mul_f32 v[138:139], v[26:27], v[140:141] op_sel:[0,1] op_sel_hi:[0,0] neg_lo:[0,1]
	v_pk_mul_f32 v[142:143], v[66:67], v[140:141] op_sel:[1,1] op_sel_hi:[0,1] neg_hi:[1,0]
	v_pk_fma_f32 v[138:139], v[24:25], v[140:141], v[138:139]
	v_pk_fma_f32 v[66:67], v[66:67], v[140:141], v[142:143] op_sel_hi:[1,0,1]
	v_pk_mul_f32 v[140:141], v[26:27], v[134:135] op_sel:[0,1] op_sel_hi:[0,0] neg_lo:[0,1]
	v_pk_fma_f32 v[134:135], v[24:25], v[134:135], v[140:141]
	s_nop 0
	v_pk_mul_f32 v[140:141], v[16:17], v[134:135] op_sel:[1,1] op_sel_hi:[0,1] neg_hi:[1,0]
	s_nop 0
	v_pk_fma_f32 v[16:17], v[16:17], v[134:135], v[140:141] op_sel_hi:[1,0,1]
	v_pk_mul_f32 v[140:141], v[26:27], v[138:139] op_sel:[0,1] op_sel_hi:[0,0] neg_lo:[0,1]
	v_pk_mul_f32 v[142:143], v[18:19], v[138:139] op_sel:[1,1] op_sel_hi:[0,1] neg_hi:[1,0]
	v_pk_fma_f32 v[140:141], v[24:25], v[138:139], v[140:141]
	v_pk_fma_f32 v[18:19], v[18:19], v[138:139], v[142:143] op_sel_hi:[1,0,1]
	v_pk_mul_f32 v[138:139], v[26:27], v[134:135] op_sel:[0,1] op_sel_hi:[0,0] neg_lo:[0,1]
	v_pk_fma_f32 v[134:135], v[24:25], v[134:135], v[138:139]
	s_nop 0
	v_pk_mul_f32 v[138:139], v[12:13], v[134:135] op_sel:[1,1] op_sel_hi:[0,1] neg_hi:[1,0]
	s_nop 0
	v_pk_fma_f32 v[12:13], v[12:13], v[134:135], v[138:139] op_sel_hi:[1,0,1]
	v_pk_mul_f32 v[138:139], v[26:27], v[140:141] op_sel:[0,1] op_sel_hi:[0,0] neg_lo:[0,1]
	v_pk_mul_f32 v[142:143], v[14:15], v[140:141] op_sel:[1,1] op_sel_hi:[0,1] neg_hi:[1,0]
	v_pk_fma_f32 v[138:139], v[24:25], v[140:141], v[138:139]
	v_pk_fma_f32 v[14:15], v[14:15], v[140:141], v[142:143] op_sel_hi:[1,0,1]
	v_pk_mul_f32 v[140:141], v[26:27], v[134:135] op_sel:[0,1] op_sel_hi:[0,0] neg_lo:[0,1]
	v_pk_fma_f32 v[134:135], v[24:25], v[134:135], v[140:141]
	s_nop 0
	v_pk_mul_f32 v[140:141], v[8:9], v[134:135] op_sel:[1,1] op_sel_hi:[0,1] neg_hi:[1,0]
	s_nop 0
	v_pk_fma_f32 v[8:9], v[8:9], v[134:135], v[140:141] op_sel_hi:[1,0,1]
	v_pk_mul_f32 v[140:141], v[26:27], v[138:139] op_sel:[0,1] op_sel_hi:[0,0] neg_lo:[0,1]
	v_pk_mul_f32 v[142:143], v[10:11], v[138:139] op_sel:[1,1] op_sel_hi:[0,1] neg_hi:[1,0]
	v_pk_fma_f32 v[140:141], v[24:25], v[138:139], v[140:141]
	v_pk_fma_f32 v[10:11], v[10:11], v[138:139], v[142:143] op_sel_hi:[1,0,1]
	v_pk_mul_f32 v[138:139], v[26:27], v[134:135] op_sel:[0,1] op_sel_hi:[0,0] neg_lo:[0,1]
	v_pk_fma_f32 v[24:25], v[24:25], v[134:135], v[138:139]
	s_nop 0
	v_pk_mul_f32 v[134:135], v[4:5], v[24:25] op_sel:[1,1] op_sel_hi:[0,1] neg_hi:[1,0]
	s_nop 0
	v_pk_fma_f32 v[4:5], v[4:5], v[24:25], v[134:135] op_sel_hi:[1,0,1]
	v_pk_mul_f32 v[24:25], v[6:7], v[140:141] op_sel:[1,1] op_sel_hi:[0,1] neg_hi:[1,0]
	s_nop 0
	v_pk_fma_f32 v[6:7], v[6:7], v[140:141], v[24:25] op_sel_hi:[1,0,1]
	ds_write_b64 v27, v[2:3]
	ds_write_b64 v96, v[84:85]
	ds_write_b64 v97, v[90:91] offset:256
	ds_write_b64 v98, v[16:17] offset:256
	ds_write_b64 v99, v[72:73] offset:512
	ds_write_b64 v100, v[70:71] offset:512
	ds_write_b64 v101, v[128:129] offset:768
	ds_write_b64 v102, v[8:9] offset:768
	ds_write_b64 v103, v[62:63] offset:1024
	ds_write_b64 v104, v[80:81] offset:1024
	ds_write_b64 v105, v[94:95] offset:1280
	ds_write_b64 v106, v[12:13] offset:1280
	ds_write_b64 v107, v[78:79] offset:1536
	ds_write_b64 v108, v[64:65] offset:1536
	ds_write_b64 v109, v[130:131] offset:1792
	ds_write_b64 v110, v[4:5] offset:1792
	ds_write_b64 v111, v[20:21] offset:2048
	ds_write_b64 v112, v[88:89] offset:2048
	ds_write_b64 v113, v[86:87] offset:2304
	ds_write_b64 v114, v[18:19] offset:2304
	ds_write_b64 v115, v[68:69] offset:2560
	ds_write_b64 v116, v[74:75] offset:2560
	ds_write_b64 v117, v[132:133] offset:2816
	ds_write_b64 v118, v[10:11] offset:2816
	ds_write_b64 v119, v[22:23] offset:3072
	ds_write_b64 v120, v[82:83] offset:3072
	ds_write_b64 v121, v[92:93] offset:3328
	ds_write_b64 v122, v[14:15] offset:3328
	ds_write_b64 v123, v[76:77] offset:3584
	ds_write_b64 v124, v[66:67] offset:3584
	ds_write_b64 v125, v[136:137] offset:3840
	ds_write_b64 v126, v[6:7] offset:3840
	v_mov_b32_e32 v2, v146
	s_waitcnt lgkmcnt(0)
	s_barrier
	s_nop 0
	v_lshlrev_b32_e32 v3, 4, v2
	v_lshrrev_b32_e32 v4, 1, v2
	v_bfe_u32 v2, v2, 1, 4
	v_bitop3_b32 v5, v4, v3, 16 bitop3:0x6c
	v_lshl_add_u32 v5, v5, 3, 16
	v_lshlrev_b32_e32 v2, 3, v2
	v_add_u32_e32 v6, v5, v2
	ds_read_b64 v[12:13], v6
	v_bitop3_b32 v6, v4, 1, 15 bitop3:0x6c
	v_lshlrev_b32_e32 v8, 3, v6
	v_add_u32_e32 v6, v5, v8
	ds_read_b64 v[14:15], v6
	v_bitop3_b32 v6, v4, 2, 15 bitop3:0x6c
	v_lshlrev_b32_e32 v9, 3, v6
	v_add_u32_e32 v6, v5, v9
	ds_read_b64 v[16:17], v6
	v_bitop3_b32 v6, v4, 3, 15 bitop3:0x6c
	v_lshlrev_b32_e32 v10, 3, v6
	v_add_u32_e32 v6, v5, v10
	ds_read_b64 v[18:19], v6
	v_bitop3_b32 v6, v4, 4, 15 bitop3:0x6c
	v_lshlrev_b32_e32 v11, 3, v6
	v_add_u32_e32 v6, v5, v11
	ds_read_b64 v[20:21], v6
	v_bitop3_b32 v6, v4, 5, 15 bitop3:0x6c
	v_lshlrev_b32_e32 v82, 3, v6
	v_add_u32_e32 v6, v5, v82
	ds_read_b64 v[22:23], v6
	v_bitop3_b32 v6, v4, 6, 15 bitop3:0x6c
	v_lshlrev_b32_e32 v83, 3, v6
	v_add_u32_e32 v6, v5, v83
	ds_read_b64 v[24:25], v6
	v_bitop3_b32 v6, v4, 7, 15 bitop3:0x6c
	v_lshlrev_b32_e32 v84, 3, v6
	v_add_u32_e32 v6, v5, v84
	ds_read_b64 v[26:27], v6
	v_bitop3_b32 v6, v4, 8, 15 bitop3:0x6c
	v_lshlrev_b32_e32 v85, 3, v6
	v_add_u32_e32 v6, v5, v85
	ds_read_b64 v[62:63], v6
	v_bitop3_b32 v6, v4, 9, 15 bitop3:0x6c
	v_lshlrev_b32_e32 v86, 3, v6
	v_add_u32_e32 v6, v5, v86
	ds_read_b64 v[64:65], v6
	v_bitop3_b32 v6, v4, 10, 15 bitop3:0x6c
	v_lshlrev_b32_e32 v87, 3, v6
	v_add_u32_e32 v6, v5, v87
	ds_read_b64 v[66:67], v6
	v_bitop3_b32 v6, v4, 11, 15 bitop3:0x6c
	v_lshlrev_b32_e32 v88, 3, v6
	v_add_u32_e32 v6, v5, v88
	ds_read_b64 v[68:69], v6
	v_bitop3_b32 v6, v4, 12, 15 bitop3:0x6c
	v_lshlrev_b32_e32 v89, 3, v6
	v_add_u32_e32 v6, v5, v89
	ds_read_b64 v[70:71], v6
	v_bitop3_b32 v6, v4, 13, 15 bitop3:0x6c
	v_lshlrev_b32_e32 v90, 3, v6
	v_add_u32_e32 v6, v5, v90
	ds_read_b64 v[72:73], v6
	v_bitop3_b32 v6, v4, 14, 15 bitop3:0x6c
	v_lshlrev_b32_e32 v91, 3, v6
	v_add_u32_e32 v6, v5, v91
	v_add_u32_e32 v3, 0x2000, v3
	ds_read_b64 v[74:75], v6
	v_bitop3_b32 v6, v4, 15, v4 bitop3:0xc
	v_bitop3_b32 v3, v3, v4, 16 bitop3:0x78
	v_lshlrev_b32_e32 v106, 3, v6
	v_lshl_add_u32 v107, v3, 3, 16
	v_add_u32_e32 v5, v5, v106
	v_add_u32_e32 v2, v107, v2
	ds_read_b64 v[76:77], v5
	ds_read_b64 v[6:7], v2
	v_add_u32_e32 v2, v107, v8
	ds_read_b64 v[78:79], v2
	v_add_u32_e32 v2, v107, v9
	ds_read_b64 v[8:9], v2
	v_add_u32_e32 v2, v107, v10
	ds_read_b64 v[80:81], v2
	v_add_u32_e32 v2, v107, v11
	ds_read_b64 v[10:11], v2
	v_add_u32_e32 v2, v107, v82
	v_add_u32_e32 v82, v107, v84
	v_add_u32_e32 v84, v107, v85
	ds_read_b64 v[4:5], v2
	ds_read_b64 v[92:93], v84
	v_add_u32_e32 v2, v107, v83
	v_add_u32_e32 v84, v107, v86
	ds_read_b64 v[2:3], v2
	ds_read_b64 v[82:83], v82
	ds_read_b64 v[94:95], v84
	v_add_u32_e32 v84, v107, v87
	ds_read_b64 v[96:97], v84
	v_add_u32_e32 v84, v107, v88
	ds_read_b64 v[98:99], v84
	v_add_u32_e32 v84, v107, v89
	ds_read_b64 v[100:101], v84
	v_add_u32_e32 v84, v107, v90
	ds_read_b64 v[102:103], v84
	v_add_u32_e32 v84, v107, v91
	ds_read_b64 v[104:105], v84
	v_add_u32_e32 v84, v107, v106
	ds_read_b64 v[106:107], v84
	s_waitcnt lgkmcnt(14)
	v_pk_add_f32 v[84:85], v[12:13], v[62:63]
	v_pk_add_f32 v[12:13], v[12:13], v[62:63] neg_lo:[0,1] neg_hi:[0,1]
	v_pk_add_f32 v[62:63], v[14:15], v[64:65]
	v_pk_add_f32 v[14:15], v[14:15], v[64:65] neg_lo:[0,1] neg_hi:[0,1]
	s_nop 0
	v_pk_mul_f32 v[64:65], v[14:15], s[62:63] op_sel:[1,0] op_sel_hi:[0,0] neg_hi:[1,0]
	s_nop 0
	v_pk_fma_f32 v[14:15], v[14:15], s[60:61], v[64:65] op_sel_hi:[1,0,1]
	v_pk_add_f32 v[64:65], v[16:17], v[66:67]
	v_pk_add_f32 v[16:17], v[16:17], v[66:67] neg_lo:[0,1] neg_hi:[0,1]
	s_nop 0
	v_pk_mul_f32 v[66:67], v[16:17], s[70:71] op_sel:[1,0] op_sel_hi:[0,0] neg_hi:[1,0]
	s_nop 0
	v_pk_fma_f32 v[16:17], v[16:17], s[70:71], v[66:67] op_sel_hi:[1,0,1]
	v_pk_add_f32 v[66:67], v[18:19], v[68:69]
	v_pk_add_f32 v[18:19], v[18:19], v[68:69] neg_lo:[0,1] neg_hi:[0,1]
	s_nop 0
	v_pk_mul_f32 v[68:69], v[18:19], s[60:61] op_sel:[1,0] op_sel_hi:[0,0] neg_hi:[1,0]
	s_nop 0
	v_pk_fma_f32 v[18:19], v[18:19], s[62:63], v[68:69] op_sel_hi:[1,0,1]
	v_pk_add_f32 v[68:69], v[20:21], v[70:71]
	v_pk_add_f32 v[20:21], v[20:21], v[70:71] neg_lo:[0,1] neg_hi:[0,1]
	s_nop 0
	v_xor_b32_e32 v71, 0x80000000, v20
	v_mov_b32_e32 v70, v21
	v_pk_add_f32 v[20:21], v[22:23], v[72:73]
	v_pk_add_f32 v[22:23], v[22:23], v[72:73] neg_lo:[0,1] neg_hi:[0,1]
	s_nop 0
	v_pk_mul_f32 v[72:73], v[22:23], s[62:63] op_sel_hi:[1,0]
	v_xor_b32_e32 v87, 0x80000000, v22
	v_mov_b32_e32 v86, v23
	v_pk_fma_f32 v[22:23], v[86:87], s[60:61], v[72:73] op_sel_hi:[1,0,1] neg_lo:[0,0,1] neg_hi:[0,0,1]
	v_pk_add_f32 v[72:73], v[24:25], v[74:75]
	v_pk_add_f32 v[24:25], v[24:25], v[74:75] neg_lo:[0,1] neg_hi:[0,1]
	s_nop 0
	v_pk_mul_f32 v[74:75], v[24:25], s[70:71] op_sel_hi:[1,0]
	v_xor_b32_e32 v87, 0x80000000, v24
	v_mov_b32_e32 v86, v25
	v_pk_fma_f32 v[24:25], v[86:87], s[70:71], v[74:75] op_sel_hi:[1,0,1] neg_lo:[0,0,1] neg_hi:[0,0,1]
	v_pk_add_f32 v[74:75], v[26:27], v[76:77]
	v_pk_add_f32 v[26:27], v[26:27], v[76:77] neg_lo:[0,1] neg_hi:[0,1]
	s_nop 0
	v_pk_mul_f32 v[76:77], v[26:27], s[60:61] op_sel_hi:[1,0]
	v_xor_b32_e32 v87, 0x80000000, v26
	v_mov_b32_e32 v86, v27
	v_pk_fma_f32 v[26:27], v[86:87], s[62:63], v[76:77] op_sel_hi:[1,0,1] neg_lo:[0,0,1] neg_hi:[0,0,1]
	v_pk_add_f32 v[76:77], v[84:85], v[68:69]
	v_pk_add_f32 v[68:69], v[84:85], v[68:69] neg_lo:[0,1] neg_hi:[0,1]
	v_pk_add_f32 v[84:85], v[62:63], v[20:21]
	v_pk_add_f32 v[20:21], v[62:63], v[20:21] neg_lo:[0,1] neg_hi:[0,1]
	s_nop 0
	v_pk_mul_f32 v[62:63], v[20:21], s[70:71] op_sel:[1,0] op_sel_hi:[0,0] neg_hi:[1,0]
	s_nop 0
	v_pk_fma_f32 v[20:21], v[20:21], s[70:71], v[62:63] op_sel_hi:[1,0,1]
	v_pk_add_f32 v[62:63], v[64:65], v[72:73]
	v_pk_add_f32 v[64:65], v[64:65], v[72:73] neg_lo:[0,1] neg_hi:[0,1]
	s_nop 0
	v_xor_b32_e32 v73, 0x80000000, v64
	v_mov_b32_e32 v72, v65
	v_pk_add_f32 v[64:65], v[66:67], v[74:75]
	v_pk_add_f32 v[66:67], v[66:67], v[74:75] neg_lo:[0,1] neg_hi:[0,1]
	s_nop 0
	v_pk_mul_f32 v[74:75], v[66:67], s[70:71] op_sel_hi:[1,0]
	v_xor_b32_e32 v87, 0x80000000, v66
	v_mov_b32_e32 v86, v67
	v_pk_fma_f32 v[66:67], v[86:87], s[70:71], v[74:75] op_sel_hi:[1,0,1] neg_lo:[0,0,1] neg_hi:[0,0,1]
	v_pk_add_f32 v[74:75], v[12:13], v[70:71]
	v_pk_add_f32 v[12:13], v[12:13], v[70:71] neg_lo:[0,1] neg_hi:[0,1]
	v_pk_add_f32 v[70:71], v[14:15], v[22:23]
	v_pk_add_f32 v[14:15], v[14:15], v[22:23] neg_lo:[0,1] neg_hi:[0,1]
	s_nop 0
	v_pk_mul_f32 v[22:23], v[14:15], s[70:71] op_sel:[1,0] op_sel_hi:[0,0] neg_hi:[1,0]
	s_nop 0
	v_pk_fma_f32 v[14:15], v[14:15], s[70:71], v[22:23] op_sel_hi:[1,0,1]
	v_pk_add_f32 v[22:23], v[16:17], v[24:25]
	v_pk_add_f32 v[16:17], v[16:17], v[24:25] neg_lo:[0,1] neg_hi:[0,1]
	s_nop 0
	v_xor_b32_e32 v25, 0x80000000, v16
	v_mov_b32_e32 v24, v17
	v_pk_add_f32 v[16:17], v[18:19], v[26:27]
	v_pk_add_f32 v[18:19], v[18:19], v[26:27] neg_lo:[0,1] neg_hi:[0,1]
	v_pk_add_f32 v[108:109], v[12:13], v[24:25]
	v_pk_mul_f32 v[26:27], v[18:19], s[70:71] op_sel_hi:[1,0]
	s_nop 0
	v_pk_fma_f32 v[18:19], v[18:19], s[70:71], v[26:27] op_sel:[1,0,0] op_sel_hi:[0,0,1] neg_lo:[0,0,1] neg_hi:[1,0,1]
	v_pk_add_f32 v[26:27], v[76:77], v[62:63]
	v_pk_add_f32 v[62:63], v[76:77], v[62:63] neg_lo:[0,1] neg_hi:[0,1]
	v_pk_add_f32 v[76:77], v[84:85], v[64:65]
	v_pk_add_f32 v[64:65], v[84:85], v[64:65] neg_lo:[0,1] neg_hi:[0,1]
	v_pk_add_f32 v[110:111], v[12:13], v[24:25] neg_lo:[0,1] neg_hi:[0,1]
	v_xor_b32_e32 v85, 0x80000000, v64
	v_mov_b32_e32 v84, v65
	v_pk_add_f32 v[64:65], v[68:69], v[72:73]
	v_pk_add_f32 v[68:69], v[68:69], v[72:73] neg_lo:[0,1] neg_hi:[0,1]
	v_pk_add_f32 v[72:73], v[20:21], v[66:67]
	v_pk_add_f32 v[20:21], v[20:21], v[66:67] neg_lo:[0,1] neg_hi:[0,1]
	v_pk_add_f32 v[12:13], v[14:15], v[18:19] neg_lo:[0,1] neg_hi:[0,1]
	v_pk_add_f32 v[112:113], v[14:15], v[18:19]
	v_xor_b32_e32 v115, 0x80000000, v12
	v_mov_b32_e32 v114, v13
	v_pk_add_f32 v[12:13], v[26:27], v[76:77]
	v_pk_add_f32 v[14:15], v[26:27], v[76:77] neg_lo:[0,1] neg_hi:[0,1]
	v_pk_add_f32 v[24:25], v[68:69], v[20:21] op_sel:[0,1] op_sel_hi:[1,0] neg_hi:[0,1]
	v_pk_add_f32 v[26:27], v[68:69], v[20:21] op_sel:[0,1] op_sel_hi:[1,0] neg_lo:[0,1]
	s_waitcnt lgkmcnt(6)
	v_pk_add_f32 v[66:67], v[78:79], v[94:95] neg_lo:[0,1] neg_hi:[0,1]
	v_pk_add_f32 v[86:87], v[74:75], v[22:23]
	v_pk_mul_f32 v[76:77], v[66:67], s[62:63] op_sel:[1,0] op_sel_hi:[0,0] neg_hi:[1,0]
	v_pk_add_f32 v[74:75], v[74:75], v[22:23] neg_lo:[0,1] neg_hi:[0,1]
	v_pk_fma_f32 v[66:67], v[66:67], s[60:61], v[76:77] op_sel_hi:[1,0,1]
	s_waitcnt lgkmcnt(5)
	v_pk_add_f32 v[76:77], v[8:9], v[96:97]
	v_pk_add_f32 v[8:9], v[8:9], v[96:97] neg_lo:[0,1] neg_hi:[0,1]
	v_pk_add_f32 v[20:21], v[64:65], v[72:73]
	v_pk_add_f32 v[22:23], v[64:65], v[72:73] neg_lo:[0,1] neg_hi:[0,1]
	v_pk_add_f32 v[64:65], v[78:79], v[94:95]
	v_pk_mul_f32 v[78:79], v[8:9], s[70:71] op_sel:[1,0] op_sel_hi:[0,0] neg_hi:[1,0]
	v_pk_add_f32 v[88:89], v[70:71], v[16:17]
	v_pk_add_f32 v[16:17], v[70:71], v[16:17] neg_lo:[0,1] neg_hi:[0,1]
	v_pk_fma_f32 v[8:9], v[8:9], s[70:71], v[78:79] op_sel_hi:[1,0,1]
	s_waitcnt lgkmcnt(4)
	v_pk_add_f32 v[78:79], v[80:81], v[98:99]
	v_pk_add_f32 v[80:81], v[80:81], v[98:99] neg_lo:[0,1] neg_hi:[0,1]
	v_xor_b32_e32 v91, 0x80000000, v16
	v_mov_b32_e32 v90, v17
	v_pk_add_f32 v[16:17], v[62:63], v[84:85]
	v_pk_add_f32 v[18:19], v[62:63], v[84:85] neg_lo:[0,1] neg_hi:[0,1]
	v_pk_add_f32 v[62:63], v[6:7], v[92:93]
	v_pk_add_f32 v[6:7], v[6:7], v[92:93] neg_lo:[0,1] neg_hi:[0,1]
	v_pk_mul_f32 v[92:93], v[80:81], s[60:61] op_sel:[1,0] op_sel_hi:[0,0] neg_hi:[1,0]
	v_pk_add_f32 v[68:69], v[86:87], v[88:89]
	v_pk_fma_f32 v[80:81], v[80:81], s[62:63], v[92:93] op_sel_hi:[1,0,1]
	s_waitcnt lgkmcnt(3)
	v_pk_add_f32 v[92:93], v[10:11], v[100:101]
	v_pk_add_f32 v[10:11], v[10:11], v[100:101] neg_lo:[0,1] neg_hi:[0,1]
	v_pk_add_f32 v[70:71], v[86:87], v[88:89] neg_lo:[0,1] neg_hi:[0,1]
	v_xor_b32_e32 v95, 0x80000000, v10
	v_mov_b32_e32 v94, v11
	s_waitcnt lgkmcnt(2)
	v_pk_add_f32 v[10:11], v[4:5], v[102:103]
	v_pk_add_f32 v[4:5], v[4:5], v[102:103] neg_lo:[0,1] neg_hi:[0,1]
	v_pk_add_f32 v[84:85], v[108:109], v[112:113]
	v_pk_mul_f32 v[96:97], v[4:5], s[62:63] op_sel_hi:[1,0]
	s_nop 0
	v_pk_fma_f32 v[4:5], v[4:5], s[60:61], v[96:97] op_sel:[1,0,0] op_sel_hi:[0,0,1] neg_lo:[0,0,1] neg_hi:[1,0,1]
	s_waitcnt lgkmcnt(1)
	v_pk_add_f32 v[96:97], v[2:3], v[104:105]
	v_pk_add_f32 v[2:3], v[2:3], v[104:105] neg_lo:[0,1] neg_hi:[0,1]
	v_pk_add_f32 v[86:87], v[108:109], v[112:113] neg_lo:[0,1] neg_hi:[0,1]
	v_pk_mul_f32 v[98:99], v[2:3], s[70:71] op_sel_hi:[1,0]
	s_nop 0
	v_pk_fma_f32 v[2:3], v[2:3], s[70:71], v[98:99] op_sel:[1,0,0] op_sel_hi:[0,0,1] neg_lo:[0,0,1] neg_hi:[1,0,1]
	s_waitcnt lgkmcnt(0)
	v_pk_add_f32 v[98:99], v[82:83], v[106:107]
	v_pk_add_f32 v[82:83], v[82:83], v[106:107] neg_lo:[0,1] neg_hi:[0,1]
	v_pk_add_f32 v[72:73], v[74:75], v[90:91]
	v_pk_mul_f32 v[100:101], v[82:83], s[60:61] op_sel_hi:[1,0]
	v_xor_b32_e32 v103, 0x80000000, v82
	v_mov_b32_e32 v102, v83
	v_pk_fma_f32 v[82:83], v[102:103], s[62:63], v[100:101] op_sel_hi:[1,0,1] neg_lo:[0,0,1] neg_hi:[0,0,1]
	v_pk_add_f32 v[100:101], v[62:63], v[92:93]
	v_pk_add_f32 v[62:63], v[62:63], v[92:93] neg_lo:[0,1] neg_hi:[0,1]
	v_pk_add_f32 v[92:93], v[64:65], v[10:11]
	v_pk_add_f32 v[10:11], v[64:65], v[10:11] neg_lo:[0,1] neg_hi:[0,1]
	v_pk_add_f32 v[74:75], v[74:75], v[90:91] neg_lo:[0,1] neg_hi:[0,1]
	v_pk_mul_f32 v[64:65], v[10:11], s[70:71] op_sel:[1,0] op_sel_hi:[0,0] neg_hi:[1,0]
	v_pk_add_f32 v[88:89], v[110:111], v[114:115]
	v_pk_fma_f32 v[10:11], v[10:11], s[70:71], v[64:65] op_sel_hi:[1,0,1]
	v_pk_add_f32 v[64:65], v[76:77], v[96:97]
	v_pk_add_f32 v[76:77], v[76:77], v[96:97] neg_lo:[0,1] neg_hi:[0,1]
	v_pk_add_f32 v[90:91], v[110:111], v[114:115] neg_lo:[0,1] neg_hi:[0,1]
	v_xor_b32_e32 v97, 0x80000000, v76
	v_mov_b32_e32 v96, v77
	v_pk_add_f32 v[76:77], v[78:79], v[98:99]
	v_pk_add_f32 v[78:79], v[78:79], v[98:99] neg_lo:[0,1] neg_hi:[0,1]
	s_nop 0
	v_pk_mul_f32 v[98:99], v[78:79], s[70:71] op_sel_hi:[1,0]
	v_xor_b32_e32 v103, 0x80000000, v78
	v_mov_b32_e32 v102, v79
	v_pk_fma_f32 v[78:79], v[102:103], s[70:71], v[98:99] op_sel_hi:[1,0,1] neg_lo:[0,0,1] neg_hi:[0,0,1]
	v_pk_add_f32 v[98:99], v[6:7], v[94:95]
	v_pk_add_f32 v[6:7], v[6:7], v[94:95] neg_lo:[0,1] neg_hi:[0,1]
	v_pk_add_f32 v[94:95], v[66:67], v[4:5]
	v_pk_add_f32 v[4:5], v[66:67], v[4:5] neg_lo:[0,1] neg_hi:[0,1]
	s_nop 0
	v_pk_mul_f32 v[66:67], v[4:5], s[70:71] op_sel:[1,0] op_sel_hi:[0,0] neg_hi:[1,0]
	s_nop 0
	v_pk_fma_f32 v[4:5], v[4:5], s[70:71], v[66:67] op_sel_hi:[1,0,1]
	v_pk_add_f32 v[66:67], v[8:9], v[2:3]
	v_pk_add_f32 v[2:3], v[8:9], v[2:3] neg_lo:[0,1] neg_hi:[0,1]
	v_pk_add_f32 v[106:107], v[98:99], v[66:67] neg_lo:[0,1] neg_hi:[0,1]
	v_xor_b32_e32 v9, 0x80000000, v2
	v_mov_b32_e32 v8, v3
	v_pk_add_f32 v[2:3], v[80:81], v[82:83]
	v_pk_add_f32 v[80:81], v[80:81], v[82:83] neg_lo:[0,1] neg_hi:[0,1]
	v_pk_add_f32 v[108:109], v[94:95], v[2:3]
	v_pk_mul_f32 v[82:83], v[80:81], s[70:71] op_sel_hi:[1,0]
	s_nop 0
	v_pk_fma_f32 v[80:81], v[80:81], s[70:71], v[82:83] op_sel:[1,0,0] op_sel_hi:[0,0,1] neg_lo:[0,0,1] neg_hi:[1,0,1]
	v_pk_add_f32 v[82:83], v[100:101], v[64:65]
	v_pk_add_f32 v[64:65], v[100:101], v[64:65] neg_lo:[0,1] neg_hi:[0,1]
	v_pk_add_f32 v[100:101], v[92:93], v[76:77]
	v_pk_add_f32 v[76:77], v[92:93], v[76:77] neg_lo:[0,1] neg_hi:[0,1]
	v_pk_add_f32 v[102:103], v[10:11], v[78:79]
	v_xor_b32_e32 v93, 0x80000000, v76
	v_mov_b32_e32 v92, v77
	v_pk_add_f32 v[76:77], v[62:63], v[96:97]
	v_pk_add_f32 v[10:11], v[10:11], v[78:79] neg_lo:[0,1] neg_hi:[0,1]
	v_pk_add_f32 v[2:3], v[94:95], v[2:3] neg_lo:[0,1] neg_hi:[0,1]
	v_pk_add_f32 v[62:63], v[62:63], v[96:97] neg_lo:[0,1] neg_hi:[0,1]
	v_xor_b32_e32 v105, 0x80000000, v10
	v_mov_b32_e32 v104, v11
	v_pk_add_f32 v[10:11], v[98:99], v[66:67]
	v_xor_b32_e32 v111, 0x80000000, v2
	v_mov_b32_e32 v110, v3
	v_pk_add_f32 v[112:113], v[6:7], v[8:9]
	v_pk_add_f32 v[114:115], v[6:7], v[8:9] neg_lo:[0,1] neg_hi:[0,1]
	v_pk_add_f32 v[6:7], v[4:5], v[80:81]
	v_pk_add_f32 v[2:3], v[4:5], v[80:81] neg_lo:[0,1] neg_hi:[0,1]
	v_pk_add_f32 v[98:99], v[82:83], v[100:101]
	v_pk_add_f32 v[96:97], v[82:83], v[100:101] neg_lo:[0,1] neg_hi:[0,1]
	v_pk_add_f32 v[82:83], v[76:77], v[102:103]
	v_pk_add_f32 v[80:81], v[76:77], v[102:103] neg_lo:[0,1] neg_hi:[0,1]
	s_waitcnt vmcnt(7)
	v_mov_b64 v[100:101], v[164:165]
	v_mov_b64 v[102:103], v[166:167]
	v_pk_add_f32 v[78:79], v[62:63], v[104:105]
	v_pk_add_f32 v[76:77], v[62:63], v[104:105] neg_lo:[0,1] neg_hi:[0,1]
	v_xor_b32_e32 v5, 0x80000000, v2
	v_mov_b32_e32 v4, v3
	v_pk_add_f32 v[62:63], v[106:107], v[110:111]
	v_pk_add_f32 v[2:3], v[106:107], v[110:111] neg_lo:[0,1] neg_hi:[0,1]
	v_pk_add_f32 v[94:95], v[64:65], v[92:93]
	v_pk_add_f32 v[92:93], v[64:65], v[92:93] neg_lo:[0,1] neg_hi:[0,1]
	v_pk_add_f32 v[66:67], v[10:11], v[108:109]
	v_pk_add_f32 v[64:65], v[10:11], v[108:109] neg_lo:[0,1] neg_hi:[0,1]
	v_pk_add_f32 v[10:11], v[112:113], v[6:7]
	v_pk_add_f32 v[8:9], v[112:113], v[6:7] neg_lo:[0,1] neg_hi:[0,1]
	v_pk_add_f32 v[6:7], v[114:115], v[4:5]
	v_pk_add_f32 v[4:5], v[114:115], v[4:5] neg_lo:[0,1] neg_hi:[0,1]
	v_cvt_f32_f16_e32 v104, v100
	v_cvt_f32_f16_sdwa v100, v100 dst_sel:DWORD dst_unused:UNUSED_PAD src0_sel:WORD_1
	v_mul_f32_e32 v104, 0x38800000, v104
	v_mul_f32_e32 v100, 0x38800000, v100
	s_nop 0
	v_pk_mul_f32 v[106:107], v[12:13], v[100:101] op_sel:[1,0] op_sel_hi:[0,0] neg_lo:[1,0]
	v_cvt_f32_f16_e32 v100, v101
	v_cvt_f32_f16_sdwa v101, v101 dst_sel:DWORD dst_unused:UNUSED_PAD src0_sel:WORD_1
	v_pk_fma_f32 v[12:13], v[12:13], v[104:105], v[106:107] op_sel_hi:[1,0,1]
	v_xor_b32_e32 v106, 0x80000000, v15
	v_mov_b32_e32 v107, v14
	v_mul_f32_e32 v104, 0x38800000, v101
	v_mul_f32_e32 v100, 0x38800000, v100
	v_pk_mul_f32 v[104:105], v[106:107], v[104:105] op_sel_hi:[1,0]
	v_xor_b32_e32 v106, 0x80000000, v21
	v_pk_fma_f32 v[14:15], v[14:15], v[100:101], v[104:105] op_sel_hi:[1,0,1]
	v_cvt_f32_f16_sdwa v101, v102 dst_sel:DWORD dst_unused:UNUSED_PAD src0_sel:WORD_1
	v_cvt_f32_f16_e32 v100, v102
	s_nop 0
	s_nop 0
	v_mul_f32_e32 v102, 0x38800000, v101
	v_mul_f32_e32 v100, 0x38800000, v100
	v_pk_mul_f32 v[104:105], v[16:17], v[102:103] op_sel:[1,0] op_sel_hi:[0,0] neg_lo:[1,0]
	v_mov_b32_e32 v107, v20
	v_pk_fma_f32 v[16:17], v[16:17], v[100:101], v[104:105] op_sel_hi:[1,0,1]
	v_cvt_f32_f16_sdwa v101, v103 dst_sel:DWORD dst_unused:UNUSED_PAD src0_sel:WORD_1
	v_cvt_f32_f16_e32 v100, v103
	v_xor_b32_e32 v104, 0x80000000, v19
	v_mov_b32_e32 v105, v18
	v_mul_f32_e32 v102, 0x38800000, v101
	v_mul_f32_e32 v100, 0x38800000, v100
	v_pk_mul_f32 v[102:103], v[104:105], v[102:103] op_sel_hi:[1,0]
	s_nop 0
	v_pk_fma_f32 v[18:19], v[18:19], v[100:101], v[102:103] op_sel_hi:[1,0,1]
	s_waitcnt vmcnt(6)
	v_mov_b64 v[100:101], v[168:169]
	v_mov_b64 v[102:103], v[170:171]
	v_cvt_f32_f16_e32 v104, v100
	v_cvt_f32_f16_sdwa v100, v100 dst_sel:DWORD dst_unused:UNUSED_PAD src0_sel:WORD_1
	v_mul_f32_e32 v104, 0x38800000, v104
	v_mul_f32_e32 v100, 0x38800000, v100
	v_pk_mul_f32 v[106:107], v[106:107], v[100:101] op_sel_hi:[1,0]
	v_cvt_f32_f16_e32 v100, v101
	v_cvt_f32_f16_sdwa v101, v101 dst_sel:DWORD dst_unused:UNUSED_PAD src0_sel:WORD_1
	v_pk_fma_f32 v[20:21], v[20:21], v[104:105], v[106:107] op_sel_hi:[1,0,1]
	v_xor_b32_e32 v106, 0x80000000, v23
	v_mov_b32_e32 v107, v22
	v_mul_f32_e32 v104, 0x38800000, v101
	v_mul_f32_e32 v100, 0x38800000, v100
	v_pk_mul_f32 v[104:105], v[106:107], v[104:105] op_sel_hi:[1,0]
	v_xor_b32_e32 v106, 0x80000000, v69
	v_pk_fma_f32 v[22:23], v[22:23], v[100:101], v[104:105] op_sel_hi:[1,0,1]
	v_cvt_f32_f16_sdwa v101, v102 dst_sel:DWORD dst_unused:UNUSED_PAD src0_sel:WORD_1
	v_cvt_f32_f16_e32 v100, v102
	s_nop 0
	s_nop 0
	v_mul_f32_e32 v102, 0x38800000, v101
	v_mul_f32_e32 v100, 0x38800000, v100
	v_pk_mul_f32 v[104:105], v[24:25], v[102:103] op_sel:[1,0] op_sel_hi:[0,0] neg_lo:[1,0]
	v_mov_b32_e32 v107, v68
	v_pk_fma_f32 v[24:25], v[24:25], v[100:101], v[104:105] op_sel_hi:[1,0,1]
	v_cvt_f32_f16_sdwa v101, v103 dst_sel:DWORD dst_unused:UNUSED_PAD src0_sel:WORD_1
	v_cvt_f32_f16_e32 v100, v103
	v_xor_b32_e32 v104, 0x80000000, v27
	v_mov_b32_e32 v105, v26
	v_mul_f32_e32 v102, 0x38800000, v101
	v_mul_f32_e32 v100, 0x38800000, v100
	v_pk_mul_f32 v[102:103], v[104:105], v[102:103] op_sel_hi:[1,0]
	s_nop 0
	v_pk_fma_f32 v[26:27], v[26:27], v[100:101], v[102:103] op_sel_hi:[1,0,1]
	s_waitcnt vmcnt(5)
	v_mov_b64 v[100:101], v[172:173]
	v_mov_b64 v[102:103], v[174:175]
	v_cvt_f32_f16_e32 v104, v100
	v_cvt_f32_f16_sdwa v100, v100 dst_sel:DWORD dst_unused:UNUSED_PAD src0_sel:WORD_1
	v_mul_f32_e32 v104, 0x38800000, v104
	v_mul_f32_e32 v100, 0x38800000, v100
	v_pk_mul_f32 v[106:107], v[106:107], v[100:101] op_sel_hi:[1,0]
	v_cvt_f32_f16_e32 v100, v101
	v_cvt_f32_f16_sdwa v101, v101 dst_sel:DWORD dst_unused:UNUSED_PAD src0_sel:WORD_1
	v_pk_fma_f32 v[68:69], v[68:69], v[104:105], v[106:107] op_sel_hi:[1,0,1]
	v_xor_b32_e32 v106, 0x80000000, v71
	v_mov_b32_e32 v107, v70
	v_mul_f32_e32 v104, 0x38800000, v101
	v_mul_f32_e32 v100, 0x38800000, v100
	v_pk_mul_f32 v[104:105], v[106:107], v[104:105] op_sel_hi:[1,0]
	v_xor_b32_e32 v106, 0x80000000, v85
	v_pk_fma_f32 v[70:71], v[70:71], v[100:101], v[104:105] op_sel_hi:[1,0,1]
	v_cvt_f32_f16_sdwa v101, v102 dst_sel:DWORD dst_unused:UNUSED_PAD src0_sel:WORD_1
	v_cvt_f32_f16_e32 v100, v102
	s_nop 0
	s_nop 0
	v_mul_f32_e32 v102, 0x38800000, v101
	v_mul_f32_e32 v100, 0x38800000, v100
	v_pk_mul_f32 v[104:105], v[72:73], v[102:103] op_sel:[1,0] op_sel_hi:[0,0] neg_lo:[1,0]
	v_mov_b32_e32 v107, v84
	v_pk_fma_f32 v[72:73], v[72:73], v[100:101], v[104:105] op_sel_hi:[1,0,1]
	v_cvt_f32_f16_sdwa v101, v103 dst_sel:DWORD dst_unused:UNUSED_PAD src0_sel:WORD_1
	v_cvt_f32_f16_e32 v100, v103
	v_xor_b32_e32 v104, 0x80000000, v75
	v_mov_b32_e32 v105, v74
	v_mul_f32_e32 v102, 0x38800000, v101
	v_mul_f32_e32 v100, 0x38800000, v100
	v_pk_mul_f32 v[102:103], v[104:105], v[102:103] op_sel_hi:[1,0]
	s_nop 0
	v_pk_fma_f32 v[74:75], v[74:75], v[100:101], v[102:103] op_sel_hi:[1,0,1]
	s_waitcnt vmcnt(4)
	v_mov_b64 v[100:101], v[176:177]
	v_mov_b64 v[102:103], v[178:179]
	v_cvt_f32_f16_e32 v104, v100
	v_cvt_f32_f16_sdwa v100, v100 dst_sel:DWORD dst_unused:UNUSED_PAD src0_sel:WORD_1
	v_mul_f32_e32 v104, 0x38800000, v104
	v_mul_f32_e32 v100, 0x38800000, v100
	v_pk_mul_f32 v[106:107], v[106:107], v[100:101] op_sel_hi:[1,0]
	v_cvt_f32_f16_e32 v100, v101
	v_cvt_f32_f16_sdwa v101, v101 dst_sel:DWORD dst_unused:UNUSED_PAD src0_sel:WORD_1
	v_pk_fma_f32 v[84:85], v[84:85], v[104:105], v[106:107] op_sel_hi:[1,0,1]
	v_xor_b32_e32 v106, 0x80000000, v87
	v_mov_b32_e32 v107, v86
	v_mul_f32_e32 v104, 0x38800000, v101
	v_mul_f32_e32 v100, 0x38800000, v100
	v_pk_mul_f32 v[104:105], v[106:107], v[104:105] op_sel_hi:[1,0]
	v_xor_b32_e32 v106, 0x80000000, v99
	v_pk_fma_f32 v[86:87], v[86:87], v[100:101], v[104:105] op_sel_hi:[1,0,1]
	v_cvt_f32_f16_sdwa v101, v102 dst_sel:DWORD dst_unused:UNUSED_PAD src0_sel:WORD_1
	v_cvt_f32_f16_e32 v100, v102
	s_nop 0
	s_nop 0
	v_mul_f32_e32 v102, 0x38800000, v101
	v_mul_f32_e32 v100, 0x38800000, v100
	v_pk_mul_f32 v[104:105], v[88:89], v[102:103] op_sel:[1,0] op_sel_hi:[0,0] neg_lo:[1,0]
	v_mov_b32_e32 v107, v98
	v_pk_fma_f32 v[88:89], v[88:89], v[100:101], v[104:105] op_sel_hi:[1,0,1]
	v_cvt_f32_f16_sdwa v101, v103 dst_sel:DWORD dst_unused:UNUSED_PAD src0_sel:WORD_1
	v_cvt_f32_f16_e32 v100, v103
	v_xor_b32_e32 v104, 0x80000000, v91
	v_mov_b32_e32 v105, v90
	v_mul_f32_e32 v102, 0x38800000, v101
	v_mul_f32_e32 v100, 0x38800000, v100
	v_pk_mul_f32 v[102:103], v[104:105], v[102:103] op_sel_hi:[1,0]
	s_nop 0
	v_pk_fma_f32 v[90:91], v[90:91], v[100:101], v[102:103] op_sel_hi:[1,0,1]
	s_waitcnt vmcnt(3)
	v_mov_b64 v[100:101], v[180:181]
	v_mov_b64 v[102:103], v[182:183]
	v_cvt_f32_f16_e32 v104, v100
	v_cvt_f32_f16_sdwa v100, v100 dst_sel:DWORD dst_unused:UNUSED_PAD src0_sel:WORD_1
	v_mul_f32_e32 v104, 0x38800000, v104
	v_mul_f32_e32 v100, 0x38800000, v100
	v_pk_mul_f32 v[106:107], v[106:107], v[100:101] op_sel_hi:[1,0]
	v_cvt_f32_f16_e32 v100, v101
	v_cvt_f32_f16_sdwa v101, v101 dst_sel:DWORD dst_unused:UNUSED_PAD src0_sel:WORD_1
	v_pk_fma_f32 v[98:99], v[98:99], v[104:105], v[106:107] op_sel_hi:[1,0,1]
	v_xor_b32_e32 v106, 0x80000000, v97
	v_mov_b32_e32 v107, v96
	v_mul_f32_e32 v104, 0x38800000, v101
	v_mul_f32_e32 v100, 0x38800000, v100
	v_pk_mul_f32 v[104:105], v[106:107], v[104:105] op_sel_hi:[1,0]
	v_xor_b32_e32 v106, 0x80000000, v83
	v_pk_fma_f32 v[96:97], v[96:97], v[100:101], v[104:105] op_sel_hi:[1,0,1]
	v_cvt_f32_f16_sdwa v101, v102 dst_sel:DWORD dst_unused:UNUSED_PAD src0_sel:WORD_1
	v_cvt_f32_f16_e32 v100, v102
	s_nop 0
	s_nop 0
	v_mul_f32_e32 v102, 0x38800000, v101
	v_mul_f32_e32 v100, 0x38800000, v100
	v_pk_mul_f32 v[104:105], v[94:95], v[102:103] op_sel:[1,0] op_sel_hi:[0,0] neg_lo:[1,0]
	v_mov_b32_e32 v107, v82
	v_pk_fma_f32 v[94:95], v[94:95], v[100:101], v[104:105] op_sel_hi:[1,0,1]
	v_cvt_f32_f16_sdwa v101, v103 dst_sel:DWORD dst_unused:UNUSED_PAD src0_sel:WORD_1
	v_cvt_f32_f16_e32 v100, v103
	v_xor_b32_e32 v104, 0x80000000, v93
	v_mov_b32_e32 v105, v92
	v_mul_f32_e32 v102, 0x38800000, v101
	v_mul_f32_e32 v100, 0x38800000, v100
	v_pk_mul_f32 v[102:103], v[104:105], v[102:103] op_sel_hi:[1,0]
	s_nop 0
	v_pk_fma_f32 v[92:93], v[92:93], v[100:101], v[102:103] op_sel_hi:[1,0,1]
	s_waitcnt vmcnt(2)
	v_mov_b64 v[100:101], v[184:185]
	v_mov_b64 v[102:103], v[186:187]
	v_cvt_f32_f16_e32 v104, v100
	v_cvt_f32_f16_sdwa v100, v100 dst_sel:DWORD dst_unused:UNUSED_PAD src0_sel:WORD_1
	v_mul_f32_e32 v104, 0x38800000, v104
	v_mul_f32_e32 v100, 0x38800000, v100
	v_pk_mul_f32 v[106:107], v[106:107], v[100:101] op_sel_hi:[1,0]
	v_cvt_f32_f16_e32 v100, v101
	v_cvt_f32_f16_sdwa v101, v101 dst_sel:DWORD dst_unused:UNUSED_PAD src0_sel:WORD_1
	v_pk_fma_f32 v[82:83], v[82:83], v[104:105], v[106:107] op_sel_hi:[1,0,1]
	v_xor_b32_e32 v106, 0x80000000, v81
	v_mov_b32_e32 v107, v80
	v_mul_f32_e32 v104, 0x38800000, v101
	v_mul_f32_e32 v100, 0x38800000, v100
	v_pk_mul_f32 v[104:105], v[106:107], v[104:105] op_sel_hi:[1,0]
	v_xor_b32_e32 v106, 0x80000000, v67
	v_pk_fma_f32 v[80:81], v[80:81], v[100:101], v[104:105] op_sel_hi:[1,0,1]
	v_cvt_f32_f16_sdwa v101, v102 dst_sel:DWORD dst_unused:UNUSED_PAD src0_sel:WORD_1
	v_cvt_f32_f16_e32 v100, v102
	s_nop 0
	s_nop 0
	v_mul_f32_e32 v102, 0x38800000, v101
	v_mul_f32_e32 v100, 0x38800000, v100
	v_pk_mul_f32 v[104:105], v[78:79], v[102:103] op_sel:[1,0] op_sel_hi:[0,0] neg_lo:[1,0]
	v_mov_b32_e32 v107, v66
	v_pk_fma_f32 v[78:79], v[78:79], v[100:101], v[104:105] op_sel_hi:[1,0,1]
	v_cvt_f32_f16_sdwa v101, v103 dst_sel:DWORD dst_unused:UNUSED_PAD src0_sel:WORD_1
	v_cvt_f32_f16_e32 v100, v103
	v_xor_b32_e32 v104, 0x80000000, v77
	v_mov_b32_e32 v105, v76
	v_mul_f32_e32 v102, 0x38800000, v101
	v_mul_f32_e32 v100, 0x38800000, v100
	v_pk_mul_f32 v[102:103], v[104:105], v[102:103] op_sel_hi:[1,0]
	s_nop 0
	v_pk_fma_f32 v[76:77], v[76:77], v[100:101], v[102:103] op_sel_hi:[1,0,1]
	s_waitcnt vmcnt(1)
	v_mov_b64 v[100:101], v[188:189]
	v_mov_b64 v[102:103], v[190:191]
	v_cvt_f32_f16_e32 v104, v100
	v_cvt_f32_f16_sdwa v100, v100 dst_sel:DWORD dst_unused:UNUSED_PAD src0_sel:WORD_1
	v_mul_f32_e32 v104, 0x38800000, v104
	v_mul_f32_e32 v100, 0x38800000, v100
	v_pk_mul_f32 v[106:107], v[106:107], v[100:101] op_sel_hi:[1,0]
	v_cvt_f32_f16_e32 v100, v101
	v_cvt_f32_f16_sdwa v101, v101 dst_sel:DWORD dst_unused:UNUSED_PAD src0_sel:WORD_1
	v_pk_fma_f32 v[66:67], v[66:67], v[104:105], v[106:107] op_sel_hi:[1,0,1]
	v_xor_b32_e32 v106, 0x80000000, v65
	v_mov_b32_e32 v107, v64
	v_mul_f32_e32 v104, 0x38800000, v101
	v_mul_f32_e32 v100, 0x38800000, v100
	v_pk_mul_f32 v[104:105], v[106:107], v[104:105] op_sel_hi:[1,0]
	s_nop 0
	v_pk_fma_f32 v[64:65], v[64:65], v[100:101], v[104:105] op_sel_hi:[1,0,1]
	v_cvt_f32_f16_sdwa v101, v102 dst_sel:DWORD dst_unused:UNUSED_PAD src0_sel:WORD_1
	v_cvt_f32_f16_e32 v100, v102
	s_nop 0
	s_nop 0
	v_mul_f32_e32 v102, 0x38800000, v101
	v_mul_f32_e32 v100, 0x38800000, v100
	v_pk_mul_f32 v[104:105], v[62:63], v[102:103] op_sel:[1,0] op_sel_hi:[0,0] neg_lo:[1,0]
	s_nop 0
	v_pk_fma_f32 v[62:63], v[62:63], v[100:101], v[104:105] op_sel_hi:[1,0,1]
	v_cvt_f32_f16_sdwa v101, v103 dst_sel:DWORD dst_unused:UNUSED_PAD src0_sel:WORD_1
	v_cvt_f32_f16_e32 v100, v103
	v_xor_b32_e32 v104, 0x80000000, v3
	v_mov_b32_e32 v105, v2
	v_mul_f32_e32 v102, 0x38800000, v101
	v_mul_f32_e32 v100, 0x38800000, v100
	v_pk_mul_f32 v[102:103], v[104:105], v[102:103] op_sel_hi:[1,0]
	v_xor_b32_e32 v104, 0x80000000, v11
	v_pk_fma_f32 v[100:101], v[2:3], v[100:101], v[102:103] op_sel_hi:[1,0,1]
	s_waitcnt vmcnt(0)
	v_mov_b64 v[0:1], v[192:193]
	v_mov_b64 v[2:3], v[194:195]
	v_mov_b32_e32 v105, v10
	v_cvt_f32_f16_e32 v102, v0
	v_cvt_f32_f16_sdwa v0, v0 dst_sel:DWORD dst_unused:UNUSED_PAD src0_sel:WORD_1
	v_mul_f32_e32 v102, 0x38800000, v102
	v_mul_f32_e32 v0, 0x38800000, v0
	v_pk_mul_f32 v[104:105], v[104:105], v[0:1] op_sel_hi:[1,0]
	v_cvt_f32_f16_e32 v0, v1
	v_cvt_f32_f16_sdwa v1, v1 dst_sel:DWORD dst_unused:UNUSED_PAD src0_sel:WORD_1
	v_pk_fma_f32 v[10:11], v[10:11], v[102:103], v[104:105] op_sel_hi:[1,0,1]
	v_xor_b32_e32 v104, 0x80000000, v9
	v_mov_b32_e32 v105, v8
	v_mul_f32_e32 v102, 0x38800000, v1
	v_mul_f32_e32 v0, 0x38800000, v0
	v_pk_mul_f32 v[102:103], v[104:105], v[102:103] op_sel_hi:[1,0]
	s_nop 0
	v_pk_fma_f32 v[0:1], v[8:9], v[0:1], v[102:103] op_sel_hi:[1,0,1]
	v_cvt_f32_f16_e32 v8, v2
	v_cvt_f32_f16_sdwa v2, v2 dst_sel:DWORD dst_unused:UNUSED_PAD src0_sel:WORD_1
	s_nop 0
	s_nop 0
	v_mul_f32_e32 v8, 0x38800000, v8
	v_mul_f32_e32 v2, 0x38800000, v2
	s_nop 0
	v_pk_mul_f32 v[102:103], v[6:7], v[2:3] op_sel:[1,0] op_sel_hi:[0,0] neg_lo:[1,0]
	v_cvt_f32_f16_e32 v2, v3
	v_cvt_f32_f16_sdwa v3, v3 dst_sel:DWORD dst_unused:UNUSED_PAD src0_sel:WORD_1
	v_pk_fma_f32 v[6:7], v[6:7], v[8:9], v[102:103] op_sel_hi:[1,0,1]
	v_xor_b32_e32 v102, 0x80000000, v5
	v_mov_b32_e32 v103, v4
	v_mul_f32_e32 v8, 0x38800000, v3
	v_mul_f32_e32 v2, 0x38800000, v2
	v_pk_mul_f32 v[8:9], v[102:103], v[8:9] op_sel_hi:[1,0]
	v_mov_b32_e32 v102, v146
	v_pk_fma_f32 v[2:3], v[4:5], v[2:3], v[8:9] op_sel_hi:[1,0,1]
	v_pk_add_f32 v[4:5], v[12:13], v[14:15]
	v_pk_add_f32 v[8:9], v[12:13], v[14:15] neg_lo:[0,1] neg_hi:[0,1]
	v_pk_add_f32 v[12:13], v[16:17], v[18:19]
	v_pk_add_f32 v[14:15], v[16:17], v[18:19] neg_lo:[0,1] neg_hi:[0,1]
	v_pk_add_f32 v[16:17], v[20:21], v[22:23]
	v_pk_add_f32 v[18:19], v[20:21], v[22:23] neg_lo:[0,1] neg_hi:[0,1]
	v_pk_add_f32 v[20:21], v[24:25], v[26:27]
	v_pk_add_f32 v[22:23], v[24:25], v[26:27] neg_lo:[0,1] neg_hi:[0,1]
	v_pk_add_f32 v[24:25], v[68:69], v[70:71]
	v_pk_add_f32 v[26:27], v[68:69], v[70:71] neg_lo:[0,1] neg_hi:[0,1]
	v_pk_add_f32 v[68:69], v[72:73], v[74:75]
	v_pk_add_f32 v[70:71], v[72:73], v[74:75] neg_lo:[0,1] neg_hi:[0,1]
	v_pk_add_f32 v[72:73], v[84:85], v[86:87]
	v_pk_add_f32 v[74:75], v[84:85], v[86:87] neg_lo:[0,1] neg_hi:[0,1]
	v_pk_add_f32 v[84:85], v[88:89], v[90:91]
	v_pk_add_f32 v[86:87], v[88:89], v[90:91] neg_lo:[0,1] neg_hi:[0,1]
	v_pk_add_f32 v[88:89], v[4:5], v[12:13]
	v_pk_add_f32 v[4:5], v[4:5], v[12:13] neg_lo:[0,1] neg_hi:[0,1]
	v_xor_b32_e32 v12, 0x80000000, v15
	v_mov_b32_e32 v13, v14
	v_pk_add_f32 v[14:15], v[8:9], v[12:13]
	v_pk_add_f32 v[8:9], v[8:9], v[12:13] neg_lo:[0,1] neg_hi:[0,1]
	v_pk_add_f32 v[12:13], v[16:17], v[20:21]
	v_pk_add_f32 v[16:17], v[16:17], v[20:21] neg_lo:[0,1] neg_hi:[0,1]
	v_xor_b32_e32 v20, 0x80000000, v23
	v_mov_b32_e32 v21, v22
	v_pk_add_f32 v[22:23], v[18:19], v[20:21]
	v_pk_add_f32 v[18:19], v[18:19], v[20:21] neg_lo:[0,1] neg_hi:[0,1]
	v_pk_add_f32 v[20:21], v[24:25], v[68:69]
	v_pk_add_f32 v[24:25], v[24:25], v[68:69] neg_lo:[0,1] neg_hi:[0,1]
	v_xor_b32_e32 v68, 0x80000000, v71
	v_mov_b32_e32 v69, v70
	v_pk_add_f32 v[70:71], v[26:27], v[68:69]
	v_pk_add_f32 v[26:27], v[26:27], v[68:69] neg_lo:[0,1] neg_hi:[0,1]
	v_pk_add_f32 v[68:69], v[72:73], v[84:85]
	v_pk_add_f32 v[72:73], v[72:73], v[84:85] neg_lo:[0,1] neg_hi:[0,1]
	v_xor_b32_e32 v84, 0x80000000, v87
	v_mov_b32_e32 v85, v86
	v_pk_add_f32 v[86:87], v[74:75], v[84:85]
	v_pk_add_f32 v[74:75], v[74:75], v[84:85] neg_lo:[0,1] neg_hi:[0,1]
	v_pk_add_f32 v[84:85], v[88:89], v[12:13]
	v_pk_add_f32 v[12:13], v[88:89], v[12:13] neg_lo:[0,1] neg_hi:[0,1]
	v_pk_mul_f32 v[88:89], v[22:23], s[70:71] op_sel:[1,0] op_sel_hi:[0,0] neg_lo:[1,0]
	v_xor_b32_e32 v90, 0x80000000, v19
	v_pk_fma_f32 v[22:23], v[22:23], s[70:71], v[88:89] op_sel_hi:[1,0,1]
	v_mov_b32_e32 v91, v18
	v_pk_add_f32 v[88:89], v[14:15], v[22:23]
	v_pk_add_f32 v[14:15], v[14:15], v[22:23] neg_lo:[0,1] neg_hi:[0,1]
	v_xor_b32_e32 v22, 0x80000000, v17
	v_mov_b32_e32 v23, v16
	v_pk_add_f32 v[16:17], v[4:5], v[22:23]
	v_pk_add_f32 v[4:5], v[4:5], v[22:23] neg_lo:[0,1] neg_hi:[0,1]
	v_pk_mul_f32 v[22:23], v[18:19], s[70:71] op_sel_hi:[1,0]
	s_nop 0
	v_pk_fma_f32 v[18:19], v[90:91], s[70:71], v[22:23] op_sel_hi:[1,0,1] neg_lo:[0,0,1] neg_hi:[0,0,1]
	v_xor_b32_e32 v90, 0x80000000, v75
	v_pk_add_f32 v[22:23], v[8:9], v[18:19]
	v_pk_add_f32 v[8:9], v[8:9], v[18:19] neg_lo:[0,1] neg_hi:[0,1]
	v_pk_add_f32 v[18:19], v[20:21], v[68:69]
	v_pk_add_f32 v[20:21], v[20:21], v[68:69] neg_lo:[0,1] neg_hi:[0,1]
	v_pk_mul_f32 v[68:69], v[86:87], s[70:71] op_sel:[1,0] op_sel_hi:[0,0] neg_lo:[1,0]
	v_mov_b32_e32 v91, v74
	v_pk_fma_f32 v[68:69], v[86:87], s[70:71], v[68:69] op_sel_hi:[1,0,1]
	s_nop 0
	v_pk_add_f32 v[86:87], v[70:71], v[68:69]
	v_pk_add_f32 v[68:69], v[70:71], v[68:69] neg_lo:[0,1] neg_hi:[0,1]
	v_xor_b32_e32 v70, 0x80000000, v73
	v_mov_b32_e32 v71, v72
	v_pk_add_f32 v[72:73], v[24:25], v[70:71]
	v_pk_add_f32 v[24:25], v[24:25], v[70:71] neg_lo:[0,1] neg_hi:[0,1]
	v_pk_mul_f32 v[70:71], v[74:75], s[70:71] op_sel_hi:[1,0]
	s_nop 0
	v_pk_fma_f32 v[70:71], v[90:91], s[70:71], v[70:71] op_sel_hi:[1,0,1] neg_lo:[0,0,1] neg_hi:[0,0,1]
	v_xor_b32_e32 v90, 0x80000000, v69
	v_pk_add_f32 v[74:75], v[26:27], v[70:71]
	v_pk_add_f32 v[26:27], v[26:27], v[70:71] neg_lo:[0,1] neg_hi:[0,1]
	v_pk_add_f32 v[70:71], v[84:85], v[18:19]
	v_pk_add_f32 v[18:19], v[84:85], v[18:19] neg_lo:[0,1] neg_hi:[0,1]
	v_pk_mul_f32 v[84:85], v[86:87], s[62:63] op_sel:[1,0] op_sel_hi:[0,0] neg_lo:[1,0]
	v_mov_b32_e32 v91, v68
	v_pk_fma_f32 v[84:85], v[86:87], s[60:61], v[84:85] op_sel_hi:[1,0,1]
	s_nop 0
	v_pk_add_f32 v[86:87], v[88:89], v[84:85]
	v_pk_add_f32 v[84:85], v[88:89], v[84:85] neg_lo:[0,1] neg_hi:[0,1]
	v_pk_mul_f32 v[88:89], v[72:73], s[70:71] op_sel:[1,0] op_sel_hi:[0,0] neg_lo:[1,0]
	s_nop 0
	v_pk_fma_f32 v[72:73], v[72:73], s[70:71], v[88:89] op_sel_hi:[1,0,1]
	s_nop 0
	v_pk_add_f32 v[88:89], v[16:17], v[72:73]
	v_pk_add_f32 v[16:17], v[16:17], v[72:73] neg_lo:[0,1] neg_hi:[0,1]
	v_pk_mul_f32 v[72:73], v[74:75], s[60:61] op_sel:[1,0] op_sel_hi:[0,0] neg_lo:[1,0]
	s_nop 0
	v_pk_fma_f32 v[72:73], v[74:75], s[62:63], v[72:73] op_sel_hi:[1,0,1]
	s_nop 0
	v_pk_add_f32 v[74:75], v[22:23], v[72:73]
	v_pk_add_f32 v[22:23], v[22:23], v[72:73] neg_lo:[0,1] neg_hi:[0,1]
	v_xor_b32_e32 v72, 0x80000000, v21
	v_mov_b32_e32 v73, v20
	v_pk_add_f32 v[20:21], v[12:13], v[72:73]
	v_pk_add_f32 v[12:13], v[12:13], v[72:73] neg_lo:[0,1] neg_hi:[0,1]
	v_pk_mul_f32 v[72:73], v[68:69], s[62:63] op_sel_hi:[1,0]
	s_nop 0
	v_pk_fma_f32 v[68:69], v[90:91], s[60:61], v[72:73] op_sel_hi:[1,0,1] neg_lo:[0,0,1] neg_hi:[0,0,1]
	v_xor_b32_e32 v90, 0x80000000, v25
	v_pk_add_f32 v[72:73], v[14:15], v[68:69]
	v_pk_add_f32 v[14:15], v[14:15], v[68:69] neg_lo:[0,1] neg_hi:[0,1]
	v_pk_mul_f32 v[68:69], v[24:25], s[70:71] op_sel_hi:[1,0]
	v_mov_b32_e32 v91, v24
	v_pk_fma_f32 v[24:25], v[90:91], s[70:71], v[68:69] op_sel_hi:[1,0,1] neg_lo:[0,0,1] neg_hi:[0,0,1]
	s_nop 0
	v_pk_add_f32 v[68:69], v[4:5], v[24:25]
	v_pk_add_f32 v[4:5], v[4:5], v[24:25] neg_lo:[0,1] neg_hi:[0,1]
	v_pk_mul_f32 v[24:25], v[26:27], s[60:61] op_sel_hi:[1,0]
	s_nop 0
	v_pk_fma_f32 v[24:25], v[26:27], s[62:63], v[24:25] op_sel:[1,0,0] op_sel_hi:[0,0,1] neg_lo:[1,0,1] neg_hi:[0,0,1]
	v_pk_add_f32 v[90:91], v[98:99], v[96:97] neg_lo:[0,1] neg_hi:[0,1]
	v_pk_add_f32 v[26:27], v[8:9], v[24:25]
	v_pk_add_f32 v[8:9], v[8:9], v[24:25] neg_lo:[0,1] neg_hi:[0,1]
	v_pk_add_f32 v[24:25], v[98:99], v[96:97]
	v_pk_add_f32 v[96:97], v[94:95], v[92:93]
	v_pk_add_f32 v[92:93], v[94:95], v[92:93] neg_lo:[0,1] neg_hi:[0,1]
	v_pk_add_f32 v[94:95], v[82:83], v[80:81]
	v_pk_add_f32 v[80:81], v[82:83], v[80:81] neg_lo:[0,1] neg_hi:[0,1]
	v_pk_add_f32 v[82:83], v[78:79], v[76:77]
	v_pk_add_f32 v[76:77], v[78:79], v[76:77] neg_lo:[0,1] neg_hi:[0,1]
	v_pk_add_f32 v[98:99], v[10:11], v[0:1]
	v_pk_add_f32 v[0:1], v[10:11], v[0:1] neg_lo:[0,1] neg_hi:[0,1]
	v_pk_add_f32 v[10:11], v[6:7], v[2:3]
	v_pk_add_f32 v[2:3], v[6:7], v[2:3] neg_lo:[0,1] neg_hi:[0,1]
	v_pk_add_f32 v[6:7], v[24:25], v[96:97]
	v_pk_add_f32 v[24:25], v[24:25], v[96:97] neg_lo:[0,1] neg_hi:[0,1]
	v_xor_b32_e32 v96, 0x80000000, v93
	v_mov_b32_e32 v97, v92
	v_pk_add_f32 v[78:79], v[66:67], v[64:65]
	v_pk_add_f32 v[64:65], v[66:67], v[64:65] neg_lo:[0,1] neg_hi:[0,1]
	v_pk_add_f32 v[66:67], v[62:63], v[100:101]
	v_pk_add_f32 v[62:63], v[62:63], v[100:101] neg_lo:[0,1] neg_hi:[0,1]
	v_pk_add_f32 v[92:93], v[90:91], v[96:97]
	v_pk_add_f32 v[90:91], v[90:91], v[96:97] neg_lo:[0,1] neg_hi:[0,1]
	v_pk_add_f32 v[96:97], v[94:95], v[82:83]
	v_pk_add_f32 v[82:83], v[94:95], v[82:83] neg_lo:[0,1] neg_hi:[0,1]
	v_xor_b32_e32 v94, 0x80000000, v77
	v_mov_b32_e32 v95, v76
	v_pk_add_f32 v[76:77], v[80:81], v[94:95]
	v_pk_add_f32 v[80:81], v[80:81], v[94:95] neg_lo:[0,1] neg_hi:[0,1]
	v_pk_add_f32 v[94:95], v[78:79], v[66:67]
	v_pk_add_f32 v[66:67], v[78:79], v[66:67] neg_lo:[0,1] neg_hi:[0,1]
	v_xor_b32_e32 v78, 0x80000000, v63
	v_mov_b32_e32 v79, v62
	v_pk_add_f32 v[62:63], v[64:65], v[78:79]
	v_pk_add_f32 v[64:65], v[64:65], v[78:79] neg_lo:[0,1] neg_hi:[0,1]
	v_pk_add_f32 v[78:79], v[98:99], v[10:11]
	v_pk_add_f32 v[10:11], v[98:99], v[10:11] neg_lo:[0,1] neg_hi:[0,1]
	v_xor_b32_e32 v98, 0x80000000, v3
	v_mov_b32_e32 v99, v2
	v_pk_add_f32 v[2:3], v[0:1], v[98:99]
	v_pk_add_f32 v[0:1], v[0:1], v[98:99] neg_lo:[0,1] neg_hi:[0,1]
	v_pk_add_f32 v[98:99], v[6:7], v[96:97]
	v_pk_add_f32 v[6:7], v[6:7], v[96:97] neg_lo:[0,1] neg_hi:[0,1]
	v_pk_mul_f32 v[96:97], v[76:77], s[70:71] op_sel:[1,0] op_sel_hi:[0,0] neg_lo:[1,0]
	v_xor_b32_e32 v100, 0x80000000, v81
	v_pk_fma_f32 v[76:77], v[76:77], s[70:71], v[96:97] op_sel_hi:[1,0,1]
	v_mov_b32_e32 v101, v80
	v_pk_add_f32 v[96:97], v[92:93], v[76:77]
	v_pk_add_f32 v[76:77], v[92:93], v[76:77] neg_lo:[0,1] neg_hi:[0,1]
	v_xor_b32_e32 v92, 0x80000000, v83
	v_mov_b32_e32 v93, v82
	v_pk_add_f32 v[82:83], v[24:25], v[92:93]
	v_pk_add_f32 v[24:25], v[24:25], v[92:93] neg_lo:[0,1] neg_hi:[0,1]
	v_pk_mul_f32 v[92:93], v[80:81], s[70:71] op_sel_hi:[1,0]
	s_nop 0
	v_pk_fma_f32 v[80:81], v[100:101], s[70:71], v[92:93] op_sel_hi:[1,0,1] neg_lo:[0,0,1] neg_hi:[0,0,1]
	v_xor_b32_e32 v100, 0x80000000, v1
	v_pk_add_f32 v[92:93], v[90:91], v[80:81]
	v_pk_add_f32 v[80:81], v[90:91], v[80:81] neg_lo:[0,1] neg_hi:[0,1]
	v_pk_add_f32 v[90:91], v[94:95], v[78:79]
	v_pk_add_f32 v[78:79], v[94:95], v[78:79] neg_lo:[0,1] neg_hi:[0,1]
	v_pk_mul_f32 v[94:95], v[2:3], s[70:71] op_sel:[1,0] op_sel_hi:[0,0] neg_lo:[1,0]
	v_mov_b32_e32 v101, v0
	v_pk_fma_f32 v[2:3], v[2:3], s[70:71], v[94:95] op_sel_hi:[1,0,1]
	s_nop 0
	v_pk_add_f32 v[94:95], v[62:63], v[2:3]
	v_pk_add_f32 v[2:3], v[62:63], v[2:3] neg_lo:[0,1] neg_hi:[0,1]
	v_xor_b32_e32 v62, 0x80000000, v11
	v_mov_b32_e32 v63, v10
	v_pk_add_f32 v[10:11], v[66:67], v[62:63]
	v_pk_add_f32 v[62:63], v[66:67], v[62:63] neg_lo:[0,1] neg_hi:[0,1]
	v_pk_mul_f32 v[66:67], v[0:1], s[70:71] op_sel_hi:[1,0]
	s_nop 0
	v_pk_fma_f32 v[0:1], v[100:101], s[70:71], v[66:67] op_sel_hi:[1,0,1] neg_lo:[0,0,1] neg_hi:[0,0,1]
	v_xor_b32_e32 v100, 0x80000000, v3
	v_pk_add_f32 v[66:67], v[64:65], v[0:1]
	v_pk_add_f32 v[0:1], v[64:65], v[0:1] neg_lo:[0,1] neg_hi:[0,1]
	v_pk_add_f32 v[64:65], v[98:99], v[90:91]
	v_pk_add_f32 v[90:91], v[98:99], v[90:91] neg_lo:[0,1] neg_hi:[0,1]
	v_pk_mul_f32 v[98:99], v[94:95], s[62:63] op_sel:[1,0] op_sel_hi:[0,0] neg_lo:[1,0]
	v_mov_b32_e32 v101, v2
	v_pk_fma_f32 v[94:95], v[94:95], s[60:61], v[98:99] op_sel_hi:[1,0,1]
	s_nop 0
	v_pk_add_f32 v[98:99], v[96:97], v[94:95]
	v_pk_add_f32 v[94:95], v[96:97], v[94:95] neg_lo:[0,1] neg_hi:[0,1]
	v_pk_mul_f32 v[96:97], v[10:11], s[70:71] op_sel:[1,0] op_sel_hi:[0,0] neg_lo:[1,0]
	s_nop 0
	v_pk_fma_f32 v[10:11], v[10:11], s[70:71], v[96:97] op_sel_hi:[1,0,1]
	s_nop 0
	v_pk_add_f32 v[96:97], v[82:83], v[10:11]
	v_pk_add_f32 v[10:11], v[82:83], v[10:11] neg_lo:[0,1] neg_hi:[0,1]
	v_pk_mul_f32 v[82:83], v[66:67], s[60:61] op_sel:[1,0] op_sel_hi:[0,0] neg_lo:[1,0]
	s_nop 0
	v_pk_fma_f32 v[66:67], v[66:67], s[62:63], v[82:83] op_sel_hi:[1,0,1]
	s_nop 0
	v_pk_add_f32 v[82:83], v[92:93], v[66:67]
	v_pk_add_f32 v[66:67], v[92:93], v[66:67] neg_lo:[0,1] neg_hi:[0,1]
	v_xor_b32_e32 v92, 0x80000000, v79
	v_mov_b32_e32 v93, v78
	v_pk_add_f32 v[78:79], v[6:7], v[92:93]
	v_pk_add_f32 v[6:7], v[6:7], v[92:93] neg_lo:[0,1] neg_hi:[0,1]
	v_pk_mul_f32 v[92:93], v[2:3], s[62:63] op_sel_hi:[1,0]
	s_nop 0
	v_pk_fma_f32 v[2:3], v[100:101], s[60:61], v[92:93] op_sel_hi:[1,0,1] neg_lo:[0,0,1] neg_hi:[0,0,1]
	v_xor_b32_e32 v100, 0x80000000, v63
	v_pk_add_f32 v[92:93], v[76:77], v[2:3]
	v_pk_add_f32 v[2:3], v[76:77], v[2:3] neg_lo:[0,1] neg_hi:[0,1]
	v_pk_mul_f32 v[76:77], v[62:63], s[70:71] op_sel_hi:[1,0]
	v_mov_b32_e32 v101, v62
	v_pk_fma_f32 v[62:63], v[100:101], s[70:71], v[76:77] op_sel_hi:[1,0,1] neg_lo:[0,0,1] neg_hi:[0,0,1]
	v_xor_b32_e32 v100, 0x80000000, v1
	v_pk_add_f32 v[76:77], v[24:25], v[62:63]
	v_pk_add_f32 v[24:25], v[24:25], v[62:63] neg_lo:[0,1] neg_hi:[0,1]
	v_pk_mul_f32 v[62:63], v[0:1], s[60:61] op_sel_hi:[1,0]
	v_mov_b32_e32 v101, v0
	v_pk_fma_f32 v[0:1], v[100:101], s[62:63], v[62:63] op_sel_hi:[1,0,1] neg_lo:[0,0,1] neg_hi:[0,0,1]
	v_bfe_u32 v100, v102, 1, 4
	v_pk_add_f32 v[62:63], v[80:81], v[0:1]
	v_pk_add_f32 v[0:1], v[80:81], v[0:1] neg_lo:[0,1] neg_hi:[0,1]
	v_lshlrev_b32_e32 v80, 4, v102
	v_lshrrev_b32_e32 v81, 1, v102
	v_bitop3_b32 v101, v81, v80, 16 bitop3:0x6c
	v_lshl_add_u32 v101, v101, 3, 16
	v_lshlrev_b32_e32 v100, 3, v100
	v_add_u32_e32 v102, v101, v100
	ds_write_b64 v102, v[70:71]
	v_bitop3_b32 v70, v81, 1, 15 bitop3:0x6c
	v_lshlrev_b32_e32 v70, 3, v70
	v_add_u32_e32 v71, v101, v70
	ds_write_b64 v71, v[86:87]
	v_bitop3_b32 v71, v81, 2, 15 bitop3:0x6c
	v_lshlrev_b32_e32 v71, 3, v71
	v_add_u32_e32 v86, v101, v71
	ds_write_b64 v86, v[88:89]
	v_bitop3_b32 v86, v81, 3, 15 bitop3:0x6c
	v_lshlrev_b32_e32 v86, 3, v86
	v_add_u32_e32 v87, v101, v86
	ds_write_b64 v87, v[74:75]
	v_bitop3_b32 v74, v81, 4, 15 bitop3:0x6c
	v_lshlrev_b32_e32 v74, 3, v74
	v_add_u32_e32 v75, v101, v74
	ds_write_b64 v75, v[20:21]
	v_bitop3_b32 v20, v81, 5, 15 bitop3:0x6c
	v_lshlrev_b32_e32 v20, 3, v20
	v_add_u32_e32 v21, v101, v20
	ds_write_b64 v21, v[72:73]
	v_bitop3_b32 v21, v81, 6, 15 bitop3:0x6c
	v_lshlrev_b32_e32 v21, 3, v21
	v_add_u32_e32 v72, v101, v21
	ds_write_b64 v72, v[68:69]
	v_bitop3_b32 v68, v81, 7, 15 bitop3:0x6c
	v_lshlrev_b32_e32 v68, 3, v68
	v_add_u32_e32 v69, v101, v68
	ds_write_b64 v69, v[26:27]
	v_bitop3_b32 v26, v81, 8, 15 bitop3:0x6c
	v_lshlrev_b32_e32 v26, 3, v26
	v_add_u32_e32 v27, v101, v26
	ds_write_b64 v27, v[18:19]
	v_bitop3_b32 v18, v81, 9, 15 bitop3:0x6c
	v_lshlrev_b32_e32 v18, 3, v18
	v_add_u32_e32 v19, v101, v18
	ds_write_b64 v19, v[84:85]
	v_bitop3_b32 v19, v81, 10, 15 bitop3:0x6c
	v_lshlrev_b32_e32 v19, 3, v19
	v_add_u32_e32 v27, v101, v19
	ds_write_b64 v27, v[16:17]
	v_bitop3_b32 v16, v81, 11, 15 bitop3:0x6c
	v_lshlrev_b32_e32 v16, 3, v16
	v_add_u32_e32 v17, v101, v16
	ds_write_b64 v17, v[22:23]
	v_bitop3_b32 v17, v81, 12, 15 bitop3:0x6c
	v_lshlrev_b32_e32 v17, 3, v17
	v_add_u32_e32 v22, v101, v17
	ds_write_b64 v22, v[12:13]
	v_bitop3_b32 v12, v81, 13, 15 bitop3:0x6c
	v_lshlrev_b32_e32 v12, 3, v12
	v_add_u32_e32 v13, v101, v12
	ds_write_b64 v13, v[14:15]
	v_bitop3_b32 v13, v81, 14, 15 bitop3:0x6c
	v_lshlrev_b32_e32 v13, 3, v13
	v_add_u32_e32 v14, v101, v13
	ds_write_b64 v14, v[4:5]
	v_bitop3_b32 v4, v81, 15, v81 bitop3:0xc
	v_lshlrev_b32_e32 v4, 3, v4
	v_add_u32_e32 v5, v101, v4
	ds_write_b64 v5, v[8:9]
	v_add_u32_e32 v5, 0x2000, v80
	v_bitop3_b32 v5, v5, v81, 16 bitop3:0x78
	v_lshl_add_u32 v5, v5, 3, 16
	v_add_u32_e32 v8, v5, v100
	ds_write_b64 v8, v[64:65]
	v_add_u32_e32 v8, v5, v70
	ds_write_b64 v8, v[98:99]
	v_add_u32_e32 v8, v5, v71
	ds_write_b64 v8, v[96:97]
	v_add_u32_e32 v8, v5, v86
	ds_write_b64 v8, v[82:83]
	v_add_u32_e32 v8, v5, v74
	ds_write_b64 v8, v[78:79]
	v_add_u32_e32 v8, v5, v20
	ds_write_b64 v8, v[92:93]
	v_add_u32_e32 v8, v5, v21
	ds_write_b64 v8, v[76:77]
	v_add_u32_e32 v8, v5, v68
	ds_write_b64 v8, v[62:63]
	v_add_u32_e32 v8, v5, v26
	ds_write_b64 v8, v[90:91]
	v_add_u32_e32 v8, v5, v18
	ds_write_b64 v8, v[94:95]
	v_add_u32_e32 v8, v5, v19
	ds_write_b64 v8, v[10:11]
	v_add_u32_e32 v8, v5, v16
	ds_write_b64 v8, v[66:67]
	v_add_u32_e32 v8, v5, v17
	ds_write_b64 v8, v[6:7]
	v_add_u32_e32 v6, v5, v12
	ds_write_b64 v6, v[2:3]
	v_add_u32_e32 v2, v5, v13
	ds_write_b64 v2, v[24:25]
	v_add_u32_e32 v2, v5, v4
	v_mov_b32_e32 v22, v146
	ds_write_b64 v2, v[0:1]
	s_waitcnt lgkmcnt(0)
	s_barrier
	s_nop 0
	v_lshlrev_b32_e32 v0, 5, v22
	v_and_b32_e32 v2, 0xfffffe00, v0
	v_and_or_b32 v0, v22, 16, v2
	v_bitop3_b32 v2, v2, 16, v22 bitop3:0x34
	v_bitop3_b32 v6, v22, 4, 15 bitop3:0x6c
	v_bitop3_b32 v14, v22, 8, 15 bitop3:0x6c
	v_lshl_add_u32 v23, v0, 3, 16
	v_lshl_add_u32 v65, v2, 3, 16
	v_lshlrev_b32_e32 v6, 3, v6
	v_lshlrev_b32_e32 v14, 3, v14
	v_bitop3_b32 v2, v22, 1, 15 bitop3:0x6c
	v_add_u32_e32 v105, v23, v6
	v_add_u32_e32 v106, v65, v6
	v_bitop3_b32 v6, v22, 5, 15 bitop3:0x6c
	v_add_u32_e32 v113, v23, v14
	v_add_u32_e32 v114, v65, v14
	v_bitop3_b32 v14, v22, 9, 15 bitop3:0x6c
	v_lshlrev_b32_e32 v2, 3, v2
	v_lshlrev_b32_e32 v6, 3, v6
	v_lshlrev_b32_e32 v14, 3, v14
	v_add_u32_e32 v99, v23, v2
	v_add_u32_e32 v100, v65, v2
	v_bitop3_b32 v2, v22, 2, 15 bitop3:0x6c
	v_add_u32_e32 v107, v23, v6
	v_add_u32_e32 v108, v65, v6
	v_bitop3_b32 v6, v22, 6, 15 bitop3:0x6c
	v_add_u32_e32 v115, v23, v14
	v_add_u32_e32 v116, v65, v14
	v_bitop3_b32 v14, v22, 10, 15 bitop3:0x6c
	v_bitop3_b32 v26, v22, 12, 15 bitop3:0x6c
	v_lshlrev_b32_e32 v2, 3, v2
	v_lshlrev_b32_e32 v6, 3, v6
	v_lshlrev_b32_e32 v14, 3, v14
	v_lshlrev_b32_e32 v26, 3, v26
	v_and_b32_e32 v64, 15, v22
	v_add_u32_e32 v101, v23, v2
	v_add_u32_e32 v102, v65, v2
	v_bitop3_b32 v2, v22, 3, 15 bitop3:0x6c
	v_add_u32_e32 v109, v23, v6
	v_add_u32_e32 v110, v65, v6
	v_bitop3_b32 v6, v22, 7, 15 bitop3:0x6c
	v_add_u32_e32 v117, v23, v14
	v_add_u32_e32 v118, v65, v14
	v_bitop3_b32 v14, v22, 11, 15 bitop3:0x6c
	v_add_u32_e32 v121, v23, v26
	v_add_u32_e32 v122, v65, v26
	v_bitop3_b32 v26, v22, 13, 15 bitop3:0x6c
	v_bitop3_b32 v66, v22, 14, 15 bitop3:0x6c
	v_bitop3_b32 v22, v22, 15, v22 bitop3:0xc
	v_lshlrev_b32_e32 v3, 3, v64
	v_lshlrev_b32_e32 v2, 3, v2
	v_lshlrev_b32_e32 v6, 3, v6
	v_lshlrev_b32_e32 v14, 3, v14
	v_lshlrev_b32_e32 v26, 3, v26
	v_lshlrev_b32_e32 v66, 3, v66
	v_lshlrev_b32_e32 v22, 3, v22
	v_add_u32_e32 v67, v23, v3
	v_add_u32_e32 v98, v65, v3
	v_add_u32_e32 v103, v23, v2
	v_add_u32_e32 v104, v65, v2
	v_add_u32_e32 v111, v23, v6
	v_add_u32_e32 v112, v65, v6
	v_add_u32_e32 v119, v23, v14
	v_add_u32_e32 v120, v65, v14
	v_add_u32_e32 v123, v23, v26
	v_add_u32_e32 v124, v65, v26
	v_add_u32_e32 v125, v23, v66
	v_add_u32_e32 v126, v65, v66
	v_add_u32_e32 v127, v23, v22
	v_add_u32_e32 v128, v65, v22
	ds_read_b64 v[0:1], v67
	ds_read_b64 v[12:13], v98
	ds_read_b64 v[74:75], v99 offset:256
	ds_read_b64 v[4:5], v100 offset:256
	ds_read_b64 v[76:77], v101 offset:512
	ds_read_b64 v[10:11], v102 offset:512
	ds_read_b64 v[70:71], v103 offset:768
	ds_read_b64 v[2:3], v104 offset:768
	ds_read_b64 v[62:63], v105 offset:1024
	ds_read_b64 v[20:21], v106 offset:1024
	ds_read_b64 v[90:91], v107 offset:1280
	ds_read_b64 v[8:9], v108 offset:1280
	ds_read_b64 v[84:85], v109 offset:1536
	ds_read_b64 v[16:17], v110 offset:1536
	ds_read_b64 v[82:83], v111 offset:1792
	ds_read_b64 v[6:7], v112 offset:1792
	ds_read_b64 v[24:25], v113 offset:2048
	ds_read_b64 v[78:79], v114 offset:2048
	ds_read_b64 v[96:97], v115 offset:2304
	ds_read_b64 v[18:19], v116 offset:2304
	ds_read_b64 v[86:87], v117 offset:2560
	ds_read_b64 v[72:73], v118 offset:2560
	ds_read_b64 v[130:131], v119 offset:2816
	ds_read_b64 v[14:15], v120 offset:2816
	ds_read_b64 v[80:81], v121 offset:3072
	ds_read_b64 v[92:93], v122 offset:3072
	ds_read_b64 v[132:133], v123 offset:3328
	ds_read_b64 v[26:27], v124 offset:3328
	ds_read_b64 v[94:95], v125 offset:3584
	ds_read_b64 v[88:89], v126 offset:3584
	ds_read_b64 v[134:135], v127 offset:3840
	ds_read_b64 v[22:23], v128 offset:3840
	s_waitcnt lgkmcnt(14)
	s_nop 0
	v_cvt_f32_i32_e32 v64, v64
	s_nop 0
	v_mul_f32_e32 v64, 0x3b000000, v64
	v_cos_f32_e32 v68, v64
	v_sin_f32_e32 v69, v64
	v_add_f32_e32 v66, v68, v68
	v_pk_mul_f32 v[64:65], v[68:69], v[68:69]
	v_mul_f32_e32 v66, v69, v66
	s_nop 0
	s_nop 0
	v_mov_b32_e32 v140, v69
	v_pk_add_f32 v[64:65], v[64:65], v[64:65] op_sel:[0,1] op_sel_hi:[0,1] neg_lo:[0,1] neg_hi:[0,1]
	v_pk_mul_f32 v[136:137], v[68:69], v[66:67] op_sel:[1,0] op_sel_hi:[0,0] neg_lo:[1,0]
	v_pk_mul_f32 v[138:139], v[24:25], v[140:141] op_sel:[1,0] op_sel_hi:[0,0] neg_lo:[1,0]
	v_pk_fma_f32 v[136:137], v[68:69], v[64:65], v[136:137]
	v_pk_fma_f32 v[24:25], v[24:25], v[68:69], v[138:139] op_sel_hi:[1,0,1]
	v_pk_mul_f32 v[68:69], v[66:67], s[48:49] op_sel_hi:[0,1]
	v_pk_fma_f32 v[138:139], v[64:65], s[40:41], v[68:69]
	s_nop 0
	v_pk_mul_f32 v[68:69], v[62:63], v[138:139] op_sel:[1,1] op_sel_hi:[0,1] neg_lo:[1,0]
	s_nop 0
	v_pk_fma_f32 v[68:69], v[62:63], v[138:139], v[68:69] op_sel_hi:[1,0,1]
	v_pk_mul_f32 v[62:63], v[66:67], v[136:137] op_sel:[0,1] op_sel_hi:[0,0] neg_lo:[0,1]
	v_pk_fma_f32 v[140:141], v[64:65], v[136:137], v[62:63]
	s_waitcnt lgkmcnt(7)
	v_pk_mul_f32 v[62:63], v[80:81], v[136:137] op_sel:[1,1] op_sel_hi:[0,1] neg_lo:[1,0]
	s_nop 0
	v_pk_fma_f32 v[62:63], v[80:81], v[136:137], v[62:63] op_sel_hi:[1,0,1]
	v_pk_mul_f32 v[80:81], v[66:67], v[138:139] op_sel:[0,1] op_sel_hi:[0,0] neg_lo:[0,1]
	v_pk_fma_f32 v[136:137], v[64:65], v[138:139], v[80:81]
	s_nop 0
	v_pk_mul_f32 v[80:81], v[76:77], v[136:137] op_sel:[1,1] op_sel_hi:[0,1] neg_lo:[1,0]
	s_nop 0
	v_pk_fma_f32 v[80:81], v[76:77], v[136:137], v[80:81] op_sel_hi:[1,0,1]
	v_pk_mul_f32 v[76:77], v[66:67], v[140:141] op_sel:[0,1] op_sel_hi:[0,0] neg_lo:[0,1]
	v_pk_fma_f32 v[138:139], v[64:65], v[140:141], v[76:77]
	v_pk_mul_f32 v[76:77], v[86:87], v[140:141] op_sel:[1,1] op_sel_hi:[0,1] neg_lo:[1,0]
	s_nop 0
	v_pk_fma_f32 v[76:77], v[86:87], v[140:141], v[76:77] op_sel_hi:[1,0,1]
	v_pk_mul_f32 v[86:87], v[66:67], v[136:137] op_sel:[0,1] op_sel_hi:[0,0] neg_lo:[0,1]
	v_pk_fma_f32 v[136:137], v[64:65], v[136:137], v[86:87]
	s_nop 0
	v_pk_mul_f32 v[86:87], v[84:85], v[136:137] op_sel:[1,1] op_sel_hi:[0,1] neg_lo:[1,0]
	s_nop 0
	v_pk_fma_f32 v[86:87], v[84:85], v[136:137], v[86:87] op_sel_hi:[1,0,1]
	v_pk_mul_f32 v[84:85], v[66:67], v[138:139] op_sel:[0,1] op_sel_hi:[0,0] neg_lo:[0,1]
	v_pk_fma_f32 v[140:141], v[64:65], v[138:139], v[84:85]
	s_waitcnt lgkmcnt(3)
	v_pk_mul_f32 v[84:85], v[94:95], v[138:139] op_sel:[1,1] op_sel_hi:[0,1] neg_lo:[1,0]
	s_nop 0
	v_pk_fma_f32 v[84:85], v[94:95], v[138:139], v[84:85] op_sel_hi:[1,0,1]
	v_pk_mul_f32 v[94:95], v[66:67], v[136:137] op_sel:[0,1] op_sel_hi:[0,0] neg_lo:[0,1]
	v_pk_fma_f32 v[136:137], v[64:65], v[136:137], v[94:95]
	s_nop 0
	v_pk_mul_f32 v[94:95], v[74:75], v[136:137] op_sel:[1,1] op_sel_hi:[0,1] neg_lo:[1,0]
	s_nop 0
	v_pk_fma_f32 v[94:95], v[74:75], v[136:137], v[94:95] op_sel_hi:[1,0,1]
	v_pk_mul_f32 v[74:75], v[66:67], v[140:141] op_sel:[0,1] op_sel_hi:[0,0] neg_lo:[0,1]
	v_pk_fma_f32 v[138:139], v[64:65], v[140:141], v[74:75]
	v_pk_mul_f32 v[74:75], v[96:97], v[140:141] op_sel:[1,1] op_sel_hi:[0,1] neg_lo:[1,0]
	s_nop 0
	v_pk_fma_f32 v[74:75], v[96:97], v[140:141], v[74:75] op_sel_hi:[1,0,1]
	v_pk_mul_f32 v[96:97], v[66:67], v[136:137] op_sel:[0,1] op_sel_hi:[0,0] neg_lo:[0,1]
	v_pk_fma_f32 v[136:137], v[64:65], v[136:137], v[96:97]
	s_nop 0
	v_pk_mul_f32 v[96:97], v[90:91], v[136:137] op_sel:[1,1] op_sel_hi:[0,1] neg_lo:[1,0]
	s_nop 0
	v_pk_fma_f32 v[96:97], v[90:91], v[136:137], v[96:97] op_sel_hi:[1,0,1]
	v_pk_mul_f32 v[90:91], v[66:67], v[138:139] op_sel:[0,1] op_sel_hi:[0,0] neg_lo:[0,1]
	v_pk_fma_f32 v[140:141], v[64:65], v[138:139], v[90:91]
	v_pk_mul_f32 v[90:91], v[132:133], v[138:139] op_sel:[1,1] op_sel_hi:[0,1] neg_lo:[1,0]
	s_nop 0
	v_pk_fma_f32 v[90:91], v[132:133], v[138:139], v[90:91] op_sel_hi:[1,0,1]
	v_pk_mul_f32 v[132:133], v[66:67], v[136:137] op_sel:[0,1] op_sel_hi:[0,0] neg_lo:[0,1]
	s_nop 0
	v_pk_fma_f32 v[132:133], v[64:65], v[136:137], v[132:133]
	v_pk_mul_f32 v[138:139], v[130:131], v[140:141] op_sel:[1,1] op_sel_hi:[0,1] neg_lo:[1,0]
	v_pk_mul_f32 v[136:137], v[70:71], v[132:133] op_sel:[1,1] op_sel_hi:[0,1] neg_lo:[1,0]
	v_pk_fma_f32 v[130:131], v[130:131], v[140:141], v[138:139] op_sel_hi:[1,0,1]
	v_pk_fma_f32 v[70:71], v[70:71], v[132:133], v[136:137] op_sel_hi:[1,0,1]
	v_pk_mul_f32 v[138:139], v[66:67], v[132:133] op_sel:[0,1] op_sel_hi:[0,0] neg_lo:[0,1]
	v_pk_mul_f32 v[136:137], v[66:67], v[140:141] op_sel:[0,1] op_sel_hi:[0,0] neg_lo:[0,1]
	v_pk_fma_f32 v[132:133], v[64:65], v[132:133], v[138:139]
	v_pk_fma_f32 v[136:137], v[64:65], v[140:141], v[136:137]
	v_pk_mul_f32 v[138:139], v[82:83], v[132:133] op_sel:[1,1] op_sel_hi:[0,1] neg_lo:[1,0]
	s_waitcnt lgkmcnt(1)
	v_pk_fma_f32 v[82:83], v[82:83], v[132:133], v[138:139] op_sel_hi:[1,0,1]
	v_pk_mul_f32 v[138:139], v[66:67], v[136:137] op_sel:[0,1] op_sel_hi:[0,0] neg_lo:[0,1]
	v_pk_mul_f32 v[140:141], v[134:135], v[136:137] op_sel:[1,1] op_sel_hi:[0,1] neg_lo:[1,0]
	v_pk_fma_f32 v[138:139], v[64:65], v[136:137], v[138:139]
	v_pk_fma_f32 v[134:135], v[134:135], v[136:137], v[140:141] op_sel_hi:[1,0,1]
	v_pk_mul_f32 v[136:137], v[66:67], v[132:133] op_sel:[0,1] op_sel_hi:[0,0] neg_lo:[0,1]
	v_pk_fma_f32 v[132:133], v[64:65], v[132:133], v[136:137]
	s_nop 0
	v_pk_mul_f32 v[136:137], v[12:13], v[132:133] op_sel:[1,1] op_sel_hi:[0,1] neg_lo:[1,0]
	s_nop 0
	v_pk_fma_f32 v[12:13], v[12:13], v[132:133], v[136:137] op_sel_hi:[1,0,1]
	v_pk_mul_f32 v[136:137], v[66:67], v[138:139] op_sel:[0,1] op_sel_hi:[0,0] neg_lo:[0,1]
	v_pk_mul_f32 v[140:141], v[78:79], v[138:139] op_sel:[1,1] op_sel_hi:[0,1] neg_lo:[1,0]
	v_pk_fma_f32 v[136:137], v[64:65], v[138:139], v[136:137]
	v_pk_fma_f32 v[78:79], v[78:79], v[138:139], v[140:141] op_sel_hi:[1,0,1]
	v_pk_mul_f32 v[138:139], v[66:67], v[132:133] op_sel:[0,1] op_sel_hi:[0,0] neg_lo:[0,1]
	v_pk_fma_f32 v[132:133], v[64:65], v[132:133], v[138:139]
	s_nop 0
	v_pk_mul_f32 v[138:139], v[20:21], v[132:133] op_sel:[1,1] op_sel_hi:[0,1] neg_lo:[1,0]
	s_nop 0
	v_pk_fma_f32 v[20:21], v[20:21], v[132:133], v[138:139] op_sel_hi:[1,0,1]
	v_pk_mul_f32 v[138:139], v[66:67], v[136:137] op_sel:[0,1] op_sel_hi:[0,0] neg_lo:[0,1]
	v_pk_mul_f32 v[140:141], v[92:93], v[136:137] op_sel:[1,1] op_sel_hi:[0,1] neg_lo:[1,0]
	v_pk_fma_f32 v[138:139], v[64:65], v[136:137], v[138:139]
	v_pk_fma_f32 v[92:93], v[92:93], v[136:137], v[140:141] op_sel_hi:[1,0,1]
	v_pk_mul_f32 v[136:137], v[66:67], v[132:133] op_sel:[0,1] op_sel_hi:[0,0] neg_lo:[0,1]
	v_pk_fma_f32 v[132:133], v[64:65], v[132:133], v[136:137]
	s_nop 0
	v_pk_mul_f32 v[136:137], v[10:11], v[132:133] op_sel:[1,1] op_sel_hi:[0,1] neg_lo:[1,0]
	s_nop 0
	v_pk_fma_f32 v[10:11], v[10:11], v[132:133], v[136:137] op_sel_hi:[1,0,1]
	v_pk_mul_f32 v[136:137], v[66:67], v[138:139] op_sel:[0,1] op_sel_hi:[0,0] neg_lo:[0,1]
	v_pk_mul_f32 v[140:141], v[72:73], v[138:139] op_sel:[1,1] op_sel_hi:[0,1] neg_lo:[1,0]
	v_pk_fma_f32 v[136:137], v[64:65], v[138:139], v[136:137]
	v_pk_fma_f32 v[72:73], v[72:73], v[138:139], v[140:141] op_sel_hi:[1,0,1]
	v_pk_mul_f32 v[138:139], v[66:67], v[132:133] op_sel:[0,1] op_sel_hi:[0,0] neg_lo:[0,1]
	v_pk_fma_f32 v[132:133], v[64:65], v[132:133], v[138:139]
	s_nop 0
	v_pk_mul_f32 v[138:139], v[16:17], v[132:133] op_sel:[1,1] op_sel_hi:[0,1] neg_lo:[1,0]
	s_nop 0
	v_pk_fma_f32 v[16:17], v[16:17], v[132:133], v[138:139] op_sel_hi:[1,0,1]
	v_pk_mul_f32 v[138:139], v[66:67], v[136:137] op_sel:[0,1] op_sel_hi:[0,0] neg_lo:[0,1]
	v_pk_mul_f32 v[140:141], v[88:89], v[136:137] op_sel:[1,1] op_sel_hi:[0,1] neg_lo:[1,0]
	v_pk_fma_f32 v[138:139], v[64:65], v[136:137], v[138:139]
	v_pk_fma_f32 v[88:89], v[88:89], v[136:137], v[140:141] op_sel_hi:[1,0,1]
	v_pk_mul_f32 v[136:137], v[66:67], v[132:133] op_sel:[0,1] op_sel_hi:[0,0] neg_lo:[0,1]
	v_pk_fma_f32 v[132:133], v[64:65], v[132:133], v[136:137]
	s_nop 0
	v_pk_mul_f32 v[136:137], v[4:5], v[132:133] op_sel:[1,1] op_sel_hi:[0,1] neg_lo:[1,0]
	s_nop 0
	v_pk_fma_f32 v[4:5], v[4:5], v[132:133], v[136:137] op_sel_hi:[1,0,1]
	v_pk_mul_f32 v[136:137], v[66:67], v[138:139] op_sel:[0,1] op_sel_hi:[0,0] neg_lo:[0,1]
	v_pk_mul_f32 v[140:141], v[18:19], v[138:139] op_sel:[1,1] op_sel_hi:[0,1] neg_lo:[1,0]
	v_pk_fma_f32 v[136:137], v[64:65], v[138:139], v[136:137]
	v_pk_fma_f32 v[18:19], v[18:19], v[138:139], v[140:141] op_sel_hi:[1,0,1]
	v_pk_mul_f32 v[138:139], v[66:67], v[132:133] op_sel:[0,1] op_sel_hi:[0,0] neg_lo:[0,1]
	v_pk_fma_f32 v[132:133], v[64:65], v[132:133], v[138:139]
	s_nop 0
	v_pk_mul_f32 v[138:139], v[8:9], v[132:133] op_sel:[1,1] op_sel_hi:[0,1] neg_lo:[1,0]
	s_nop 0
	v_pk_fma_f32 v[8:9], v[8:9], v[132:133], v[138:139] op_sel_hi:[1,0,1]
	v_pk_mul_f32 v[138:139], v[66:67], v[136:137] op_sel:[0,1] op_sel_hi:[0,0] neg_lo:[0,1]
	v_pk_mul_f32 v[140:141], v[26:27], v[136:137] op_sel:[1,1] op_sel_hi:[0,1] neg_lo:[1,0]
	v_pk_fma_f32 v[138:139], v[64:65], v[136:137], v[138:139]
	v_pk_fma_f32 v[26:27], v[26:27], v[136:137], v[140:141] op_sel_hi:[1,0,1]
	v_pk_mul_f32 v[136:137], v[66:67], v[132:133] op_sel:[0,1] op_sel_hi:[0,0] neg_lo:[0,1]
	v_pk_fma_f32 v[132:133], v[64:65], v[132:133], v[136:137]
	s_nop 0
	v_pk_mul_f32 v[136:137], v[2:3], v[132:133] op_sel:[1,1] op_sel_hi:[0,1] neg_lo:[1,0]
	s_nop 0
	v_pk_fma_f32 v[2:3], v[2:3], v[132:133], v[136:137] op_sel_hi:[1,0,1]
	v_pk_mul_f32 v[136:137], v[66:67], v[138:139] op_sel:[0,1] op_sel_hi:[0,0] neg_lo:[0,1]
	v_pk_mul_f32 v[140:141], v[14:15], v[138:139] op_sel:[1,1] op_sel_hi:[0,1] neg_lo:[1,0]
	v_pk_fma_f32 v[136:137], v[64:65], v[138:139], v[136:137]
	v_pk_fma_f32 v[14:15], v[14:15], v[138:139], v[140:141] op_sel_hi:[1,0,1]
	v_pk_mul_f32 v[138:139], v[66:67], v[132:133] op_sel:[0,1] op_sel_hi:[0,0] neg_lo:[0,1]
	v_pk_fma_f32 v[64:65], v[64:65], v[132:133], v[138:139]
	s_nop 0
	v_pk_mul_f32 v[132:133], v[6:7], v[64:65] op_sel:[1,1] op_sel_hi:[0,1] neg_lo:[1,0]
	s_nop 0
	v_pk_fma_f32 v[6:7], v[6:7], v[64:65], v[132:133] op_sel_hi:[1,0,1]
	s_waitcnt lgkmcnt(0)
	v_pk_mul_f32 v[64:65], v[22:23], v[136:137] op_sel:[1,1] op_sel_hi:[0,1] neg_lo:[1,0]
	s_nop 0
	v_pk_fma_f32 v[22:23], v[22:23], v[136:137], v[64:65] op_sel_hi:[1,0,1]
	v_pk_add_f32 v[64:65], v[0:1], v[12:13]
	v_pk_add_f32 v[0:1], v[0:1], v[12:13] neg_lo:[0,1] neg_hi:[0,1]
	v_pk_add_f32 v[12:13], v[94:95], v[4:5]
	v_pk_add_f32 v[4:5], v[94:95], v[4:5] neg_lo:[0,1] neg_hi:[0,1]
	v_pk_add_f32 v[94:95], v[80:81], v[10:11]
	v_pk_add_f32 v[10:11], v[80:81], v[10:11] neg_lo:[0,1] neg_hi:[0,1]
	v_pk_add_f32 v[80:81], v[70:71], v[2:3]
	v_pk_add_f32 v[2:3], v[70:71], v[2:3] neg_lo:[0,1] neg_hi:[0,1]
	v_pk_add_f32 v[132:133], v[64:65], v[12:13]
	v_pk_add_f32 v[12:13], v[64:65], v[12:13] neg_lo:[0,1] neg_hi:[0,1]
	v_xor_b32_e32 v64, 0x80000000, v5
	v_mov_b32_e32 v65, v4
	v_pk_add_f32 v[70:71], v[68:69], v[20:21]
	v_pk_add_f32 v[20:21], v[68:69], v[20:21] neg_lo:[0,1] neg_hi:[0,1]
	v_pk_add_f32 v[68:69], v[96:97], v[8:9]
	v_pk_add_f32 v[8:9], v[96:97], v[8:9] neg_lo:[0,1] neg_hi:[0,1]
	v_pk_add_f32 v[4:5], v[0:1], v[64:65]
	v_pk_add_f32 v[0:1], v[0:1], v[64:65] neg_lo:[0,1] neg_hi:[0,1]
	v_pk_add_f32 v[64:65], v[94:95], v[80:81]
	v_pk_add_f32 v[80:81], v[94:95], v[80:81] neg_lo:[0,1] neg_hi:[0,1]
	v_xor_b32_e32 v94, 0x80000000, v3
	v_mov_b32_e32 v95, v2
	v_pk_add_f32 v[96:97], v[86:87], v[16:17]
	v_pk_add_f32 v[16:17], v[86:87], v[16:17] neg_lo:[0,1] neg_hi:[0,1]
	v_pk_add_f32 v[86:87], v[82:83], v[6:7]
	v_pk_add_f32 v[6:7], v[82:83], v[6:7] neg_lo:[0,1] neg_hi:[0,1]
	v_pk_add_f32 v[2:3], v[10:11], v[94:95]
	v_pk_add_f32 v[10:11], v[10:11], v[94:95] neg_lo:[0,1] neg_hi:[0,1]
	v_pk_add_f32 v[94:95], v[70:71], v[68:69]
	v_pk_add_f32 v[68:69], v[70:71], v[68:69] neg_lo:[0,1] neg_hi:[0,1]
	v_xor_b32_e32 v70, 0x80000000, v9
	v_mov_b32_e32 v71, v8
	v_pk_add_f32 v[82:83], v[24:25], v[78:79]
	v_pk_add_f32 v[24:25], v[24:25], v[78:79] neg_lo:[0,1] neg_hi:[0,1]
	v_pk_add_f32 v[78:79], v[74:75], v[18:19]
	v_pk_add_f32 v[18:19], v[74:75], v[18:19] neg_lo:[0,1] neg_hi:[0,1]
	v_pk_add_f32 v[8:9], v[20:21], v[70:71]
	v_pk_add_f32 v[20:21], v[20:21], v[70:71] neg_lo:[0,1] neg_hi:[0,1]
	v_pk_add_f32 v[70:71], v[96:97], v[86:87]
	v_pk_add_f32 v[86:87], v[96:97], v[86:87] neg_lo:[0,1] neg_hi:[0,1]
	v_xor_b32_e32 v96, 0x80000000, v7
	v_mov_b32_e32 v97, v6
	v_pk_add_f32 v[74:75], v[76:77], v[72:73]
	v_pk_add_f32 v[72:73], v[76:77], v[72:73] neg_lo:[0,1] neg_hi:[0,1]
	v_pk_add_f32 v[76:77], v[130:131], v[14:15]
	v_pk_add_f32 v[14:15], v[130:131], v[14:15] neg_lo:[0,1] neg_hi:[0,1]
	v_pk_add_f32 v[6:7], v[16:17], v[96:97]
	v_pk_add_f32 v[16:17], v[16:17], v[96:97] neg_lo:[0,1] neg_hi:[0,1]
	v_pk_add_f32 v[96:97], v[82:83], v[78:79]
	v_pk_add_f32 v[78:79], v[82:83], v[78:79] neg_lo:[0,1] neg_hi:[0,1]
	v_xor_b32_e32 v82, 0x80000000, v19
	v_mov_b32_e32 v83, v18
	v_pk_add_f32 v[130:131], v[62:63], v[92:93]
	v_pk_add_f32 v[62:63], v[62:63], v[92:93] neg_lo:[0,1] neg_hi:[0,1]
	v_pk_add_f32 v[92:93], v[90:91], v[26:27]
	v_pk_add_f32 v[26:27], v[90:91], v[26:27] neg_lo:[0,1] neg_hi:[0,1]
	v_pk_add_f32 v[18:19], v[24:25], v[82:83]
	v_pk_add_f32 v[24:25], v[24:25], v[82:83] neg_lo:[0,1] neg_hi:[0,1]
	v_pk_add_f32 v[82:83], v[74:75], v[76:77]
	v_pk_add_f32 v[74:75], v[74:75], v[76:77] neg_lo:[0,1] neg_hi:[0,1]
	v_xor_b32_e32 v76, 0x80000000, v15
	v_mov_b32_e32 v77, v14
	v_pk_add_f32 v[90:91], v[84:85], v[88:89]
	v_pk_add_f32 v[84:85], v[84:85], v[88:89] neg_lo:[0,1] neg_hi:[0,1]
	v_pk_add_f32 v[88:89], v[134:135], v[22:23]
	v_pk_add_f32 v[22:23], v[134:135], v[22:23] neg_lo:[0,1] neg_hi:[0,1]
	v_pk_add_f32 v[14:15], v[72:73], v[76:77]
	v_pk_add_f32 v[72:73], v[72:73], v[76:77] neg_lo:[0,1] neg_hi:[0,1]
	v_pk_add_f32 v[76:77], v[130:131], v[92:93]
	v_pk_add_f32 v[92:93], v[130:131], v[92:93] neg_lo:[0,1] neg_hi:[0,1]
	v_xor_b32_e32 v130, 0x80000000, v27
	v_mov_b32_e32 v131, v26
	v_pk_add_f32 v[26:27], v[62:63], v[130:131]
	v_pk_add_f32 v[62:63], v[62:63], v[130:131] neg_lo:[0,1] neg_hi:[0,1]
	v_pk_add_f32 v[130:131], v[90:91], v[88:89]
	v_pk_add_f32 v[88:89], v[90:91], v[88:89] neg_lo:[0,1] neg_hi:[0,1]
	v_xor_b32_e32 v90, 0x80000000, v23
	v_mov_b32_e32 v91, v22
	v_pk_add_f32 v[22:23], v[84:85], v[90:91]
	v_pk_add_f32 v[84:85], v[84:85], v[90:91] neg_lo:[0,1] neg_hi:[0,1]
	v_pk_add_f32 v[90:91], v[132:133], v[64:65]
	v_pk_add_f32 v[64:65], v[132:133], v[64:65] neg_lo:[0,1] neg_hi:[0,1]
	v_pk_mul_f32 v[132:133], v[2:3], s[70:71] op_sel:[1,0] op_sel_hi:[0,0] neg_lo:[1,0]
	v_xor_b32_e32 v134, 0x80000000, v11
	v_pk_fma_f32 v[2:3], v[2:3], s[70:71], v[132:133] op_sel_hi:[1,0,1]
	v_mov_b32_e32 v135, v10
	v_pk_add_f32 v[132:133], v[4:5], v[2:3]
	v_pk_add_f32 v[2:3], v[4:5], v[2:3] neg_lo:[0,1] neg_hi:[0,1]
	v_xor_b32_e32 v4, 0x80000000, v81
	v_mov_b32_e32 v5, v80
	v_pk_add_f32 v[80:81], v[12:13], v[4:5]
	v_pk_add_f32 v[4:5], v[12:13], v[4:5] neg_lo:[0,1] neg_hi:[0,1]
	v_pk_mul_f32 v[12:13], v[10:11], s[70:71] op_sel_hi:[1,0]
	s_nop 0
	v_pk_fma_f32 v[10:11], v[134:135], s[70:71], v[12:13] op_sel_hi:[1,0,1] neg_lo:[0,0,1] neg_hi:[0,0,1]
	v_xor_b32_e32 v134, 0x80000000, v17
	v_pk_add_f32 v[12:13], v[0:1], v[10:11]
	v_pk_add_f32 v[0:1], v[0:1], v[10:11] neg_lo:[0,1] neg_hi:[0,1]
	v_pk_add_f32 v[10:11], v[94:95], v[70:71]
	v_pk_add_f32 v[70:71], v[94:95], v[70:71] neg_lo:[0,1] neg_hi:[0,1]
	v_pk_mul_f32 v[94:95], v[6:7], s[70:71] op_sel:[1,0] op_sel_hi:[0,0] neg_lo:[1,0]
	v_mov_b32_e32 v135, v16
	v_pk_fma_f32 v[6:7], v[6:7], s[70:71], v[94:95] op_sel_hi:[1,0,1]
	s_nop 0
	v_pk_add_f32 v[94:95], v[8:9], v[6:7]
	v_pk_add_f32 v[6:7], v[8:9], v[6:7] neg_lo:[0,1] neg_hi:[0,1]
	v_xor_b32_e32 v8, 0x80000000, v87
	v_mov_b32_e32 v9, v86
	v_pk_add_f32 v[86:87], v[68:69], v[8:9]
	v_pk_add_f32 v[8:9], v[68:69], v[8:9] neg_lo:[0,1] neg_hi:[0,1]
	v_pk_mul_f32 v[68:69], v[16:17], s[70:71] op_sel_hi:[1,0]
	s_nop 0
	v_pk_fma_f32 v[16:17], v[134:135], s[70:71], v[68:69] op_sel_hi:[1,0,1] neg_lo:[0,0,1] neg_hi:[0,0,1]
	v_xor_b32_e32 v134, 0x80000000, v73
	v_pk_add_f32 v[68:69], v[20:21], v[16:17]
	v_pk_add_f32 v[16:17], v[20:21], v[16:17] neg_lo:[0,1] neg_hi:[0,1]
	v_pk_add_f32 v[20:21], v[96:97], v[82:83]
	v_pk_add_f32 v[82:83], v[96:97], v[82:83] neg_lo:[0,1] neg_hi:[0,1]
	v_pk_mul_f32 v[96:97], v[14:15], s[70:71] op_sel:[1,0] op_sel_hi:[0,0] neg_lo:[1,0]
	v_mov_b32_e32 v135, v72
	v_pk_fma_f32 v[14:15], v[14:15], s[70:71], v[96:97] op_sel_hi:[1,0,1]
	s_nop 0
	v_pk_add_f32 v[96:97], v[18:19], v[14:15]
	v_pk_add_f32 v[14:15], v[18:19], v[14:15] neg_lo:[0,1] neg_hi:[0,1]
	v_xor_b32_e32 v18, 0x80000000, v75
	v_mov_b32_e32 v19, v74
	v_pk_add_f32 v[74:75], v[78:79], v[18:19]
	v_pk_add_f32 v[18:19], v[78:79], v[18:19] neg_lo:[0,1] neg_hi:[0,1]
	v_pk_mul_f32 v[78:79], v[72:73], s[70:71] op_sel_hi:[1,0]
	s_nop 0
	v_pk_fma_f32 v[72:73], v[134:135], s[70:71], v[78:79] op_sel_hi:[1,0,1] neg_lo:[0,0,1] neg_hi:[0,0,1]
	v_xor_b32_e32 v134, 0x80000000, v85
	v_pk_add_f32 v[78:79], v[24:25], v[72:73]
	v_pk_add_f32 v[24:25], v[24:25], v[72:73] neg_lo:[0,1] neg_hi:[0,1]
	v_pk_add_f32 v[72:73], v[76:77], v[130:131]
	v_pk_add_f32 v[76:77], v[76:77], v[130:131] neg_lo:[0,1] neg_hi:[0,1]
	v_pk_mul_f32 v[130:131], v[22:23], s[70:71] op_sel:[1,0] op_sel_hi:[0,0] neg_lo:[1,0]
	v_mov_b32_e32 v135, v84
	v_pk_fma_f32 v[22:23], v[22:23], s[70:71], v[130:131] op_sel_hi:[1,0,1]
	s_nop 0
	v_pk_add_f32 v[130:131], v[26:27], v[22:23]
	v_pk_add_f32 v[22:23], v[26:27], v[22:23] neg_lo:[0,1] neg_hi:[0,1]
	v_xor_b32_e32 v26, 0x80000000, v89
	v_mov_b32_e32 v27, v88
	v_pk_add_f32 v[88:89], v[92:93], v[26:27]
	v_pk_add_f32 v[26:27], v[92:93], v[26:27] neg_lo:[0,1] neg_hi:[0,1]
	v_pk_mul_f32 v[92:93], v[84:85], s[70:71] op_sel_hi:[1,0]
	s_nop 0
	v_pk_fma_f32 v[84:85], v[134:135], s[70:71], v[92:93] op_sel_hi:[1,0,1] neg_lo:[0,0,1] neg_hi:[0,0,1]
	v_xor_b32_e32 v134, 0x80000000, v7
	v_pk_add_f32 v[92:93], v[62:63], v[84:85]
	v_pk_add_f32 v[62:63], v[62:63], v[84:85] neg_lo:[0,1] neg_hi:[0,1]
	v_pk_add_f32 v[84:85], v[90:91], v[10:11]
	v_pk_add_f32 v[10:11], v[90:91], v[10:11] neg_lo:[0,1] neg_hi:[0,1]
	v_pk_mul_f32 v[90:91], v[94:95], s[62:63] op_sel:[1,0] op_sel_hi:[0,0] neg_lo:[1,0]
	v_mov_b32_e32 v135, v6
	v_pk_fma_f32 v[90:91], v[94:95], s[60:61], v[90:91] op_sel_hi:[1,0,1]
	s_nop 0
	v_pk_add_f32 v[94:95], v[132:133], v[90:91]
	v_pk_add_f32 v[90:91], v[132:133], v[90:91] neg_lo:[0,1] neg_hi:[0,1]
	v_pk_mul_f32 v[132:133], v[86:87], s[70:71] op_sel:[1,0] op_sel_hi:[0,0] neg_lo:[1,0]
	s_nop 0
	v_pk_fma_f32 v[86:87], v[86:87], s[70:71], v[132:133] op_sel_hi:[1,0,1]
	s_nop 0
	v_pk_add_f32 v[132:133], v[80:81], v[86:87]
	v_pk_add_f32 v[80:81], v[80:81], v[86:87] neg_lo:[0,1] neg_hi:[0,1]
	v_pk_mul_f32 v[86:87], v[68:69], s[60:61] op_sel:[1,0] op_sel_hi:[0,0] neg_lo:[1,0]
	s_nop 0
	v_pk_fma_f32 v[68:69], v[68:69], s[62:63], v[86:87] op_sel_hi:[1,0,1]
	s_nop 0
	v_pk_add_f32 v[86:87], v[12:13], v[68:69]
	v_pk_add_f32 v[12:13], v[12:13], v[68:69] neg_lo:[0,1] neg_hi:[0,1]
	v_xor_b32_e32 v68, 0x80000000, v71
	v_mov_b32_e32 v69, v70
	v_pk_add_f32 v[70:71], v[64:65], v[68:69]
	v_pk_add_f32 v[64:65], v[64:65], v[68:69] neg_lo:[0,1] neg_hi:[0,1]
	v_pk_mul_f32 v[68:69], v[6:7], s[62:63] op_sel_hi:[1,0]
	s_nop 0
	v_pk_fma_f32 v[6:7], v[134:135], s[60:61], v[68:69] op_sel_hi:[1,0,1] neg_lo:[0,0,1] neg_hi:[0,0,1]
	v_xor_b32_e32 v134, 0x80000000, v9
	v_pk_add_f32 v[68:69], v[2:3], v[6:7]
	v_pk_add_f32 v[2:3], v[2:3], v[6:7] neg_lo:[0,1] neg_hi:[0,1]
	v_pk_mul_f32 v[6:7], v[8:9], s[70:71] op_sel_hi:[1,0]
	v_mov_b32_e32 v135, v8
	v_pk_fma_f32 v[6:7], v[134:135], s[70:71], v[6:7] op_sel_hi:[1,0,1] neg_lo:[0,0,1] neg_hi:[0,0,1]
	v_xor_b32_e32 v134, 0x80000000, v17
	v_pk_add_f32 v[8:9], v[4:5], v[6:7]
	v_pk_add_f32 v[4:5], v[4:5], v[6:7] neg_lo:[0,1] neg_hi:[0,1]
	v_pk_mul_f32 v[6:7], v[16:17], s[60:61] op_sel_hi:[1,0]
	v_mov_b32_e32 v135, v16
	v_pk_fma_f32 v[6:7], v[134:135], s[62:63], v[6:7] op_sel_hi:[1,0,1] neg_lo:[0,0,1] neg_hi:[0,0,1]
	v_xor_b32_e32 v134, 0x80000000, v23
	v_pk_add_f32 v[16:17], v[0:1], v[6:7]
	v_pk_add_f32 v[0:1], v[0:1], v[6:7] neg_lo:[0,1] neg_hi:[0,1]
	v_pk_add_f32 v[6:7], v[20:21], v[72:73]
	v_pk_add_f32 v[20:21], v[20:21], v[72:73] neg_lo:[0,1] neg_hi:[0,1]
	v_pk_mul_f32 v[72:73], v[130:131], s[62:63] op_sel:[1,0] op_sel_hi:[0,0] neg_lo:[1,0]
	v_mov_b32_e32 v135, v22
	v_pk_fma_f32 v[72:73], v[130:131], s[60:61], v[72:73] op_sel_hi:[1,0,1]
	s_nop 0
	v_pk_add_f32 v[130:131], v[96:97], v[72:73]
	v_pk_add_f32 v[72:73], v[96:97], v[72:73] neg_lo:[0,1] neg_hi:[0,1]
	v_pk_mul_f32 v[96:97], v[88:89], s[70:71] op_sel:[1,0] op_sel_hi:[0,0] neg_lo:[1,0]
	s_nop 0
	v_pk_fma_f32 v[88:89], v[88:89], s[70:71], v[96:97] op_sel_hi:[1,0,1]
	s_nop 0
	v_pk_add_f32 v[96:97], v[74:75], v[88:89]
	v_pk_add_f32 v[74:75], v[74:75], v[88:89] neg_lo:[0,1] neg_hi:[0,1]
	v_pk_mul_f32 v[88:89], v[92:93], s[60:61] op_sel:[1,0] op_sel_hi:[0,0] neg_lo:[1,0]
	s_nop 0
	v_pk_fma_f32 v[88:89], v[92:93], s[62:63], v[88:89] op_sel_hi:[1,0,1]
	s_nop 0
	v_pk_add_f32 v[92:93], v[78:79], v[88:89]
	v_pk_add_f32 v[78:79], v[78:79], v[88:89] neg_lo:[0,1] neg_hi:[0,1]
	v_xor_b32_e32 v88, 0x80000000, v77
	v_mov_b32_e32 v89, v76
	v_pk_add_f32 v[76:77], v[82:83], v[88:89]
	v_pk_add_f32 v[82:83], v[82:83], v[88:89] neg_lo:[0,1] neg_hi:[0,1]
	v_pk_mul_f32 v[88:89], v[22:23], s[62:63] op_sel_hi:[1,0]
	s_nop 0
	v_pk_fma_f32 v[22:23], v[134:135], s[60:61], v[88:89] op_sel_hi:[1,0,1] neg_lo:[0,0,1] neg_hi:[0,0,1]
	v_xor_b32_e32 v134, 0x80000000, v27
	v_pk_add_f32 v[88:89], v[14:15], v[22:23]
	v_pk_add_f32 v[14:15], v[14:15], v[22:23] neg_lo:[0,1] neg_hi:[0,1]
	v_pk_mul_f32 v[22:23], v[26:27], s[70:71] op_sel_hi:[1,0]
	v_mov_b32_e32 v135, v26
	v_pk_fma_f32 v[22:23], v[134:135], s[70:71], v[22:23] op_sel_hi:[1,0,1] neg_lo:[0,0,1] neg_hi:[0,0,1]
	v_xor_b32_e32 v134, 0x80000000, v63
	v_pk_add_f32 v[26:27], v[18:19], v[22:23]
	v_pk_add_f32 v[18:19], v[18:19], v[22:23] neg_lo:[0,1] neg_hi:[0,1]
	v_pk_mul_f32 v[22:23], v[62:63], s[60:61] op_sel_hi:[1,0]
	v_mov_b32_e32 v135, v62
	v_pk_fma_f32 v[22:23], v[134:135], s[62:63], v[22:23] op_sel_hi:[1,0,1] neg_lo:[0,0,1] neg_hi:[0,0,1]
	v_xor_b32_e32 v134, 0x80000000, v73
	v_pk_add_f32 v[62:63], v[24:25], v[22:23]
	v_pk_add_f32 v[22:23], v[24:25], v[22:23] neg_lo:[0,1] neg_hi:[0,1]
	v_pk_add_f32 v[24:25], v[84:85], v[6:7]
	v_pk_add_f32 v[6:7], v[84:85], v[6:7] neg_lo:[0,1] neg_hi:[0,1]
	v_pk_mul_f32 v[84:85], v[130:131], s[58:59] op_sel:[1,0] op_sel_hi:[0,0] neg_lo:[1,0]
	v_mov_b32_e32 v135, v72
	v_pk_fma_f32 v[84:85], v[130:131], s[46:47], v[84:85] op_sel_hi:[1,0,1]
	s_nop 0
	v_pk_add_f32 v[130:131], v[94:95], v[84:85]
	v_pk_add_f32 v[84:85], v[94:95], v[84:85] neg_lo:[0,1] neg_hi:[0,1]
	v_pk_mul_f32 v[94:95], v[96:97], s[62:63] op_sel:[1,0] op_sel_hi:[0,0] neg_lo:[1,0]
	s_nop 0
	v_pk_fma_f32 v[94:95], v[96:97], s[60:61], v[94:95] op_sel_hi:[1,0,1]
	s_nop 0
	v_pk_add_f32 v[96:97], v[132:133], v[94:95]
	v_pk_add_f32 v[94:95], v[132:133], v[94:95] neg_lo:[0,1] neg_hi:[0,1]
	v_pk_mul_f32 v[132:133], v[92:93], s[66:67] op_sel:[1,0] op_sel_hi:[0,0] neg_lo:[1,0]
	s_nop 0
	v_pk_fma_f32 v[92:93], v[92:93], s[64:65], v[132:133] op_sel_hi:[1,0,1]
	s_nop 0
	v_pk_add_f32 v[132:133], v[86:87], v[92:93]
	v_pk_add_f32 v[86:87], v[86:87], v[92:93] neg_lo:[0,1] neg_hi:[0,1]
	v_pk_mul_f32 v[92:93], v[76:77], s[70:71] op_sel:[1,0] op_sel_hi:[0,0] neg_lo:[1,0]
	s_nop 0
	v_pk_fma_f32 v[76:77], v[76:77], s[70:71], v[92:93] op_sel_hi:[1,0,1]
	s_nop 0
	v_pk_add_f32 v[92:93], v[70:71], v[76:77]
	v_pk_add_f32 v[70:71], v[70:71], v[76:77] neg_lo:[0,1] neg_hi:[0,1]
	v_pk_mul_f32 v[76:77], v[88:89], s[64:65] op_sel:[1,0] op_sel_hi:[0,0] neg_lo:[1,0]
	s_nop 0
	v_pk_fma_f32 v[76:77], v[88:89], s[66:67], v[76:77] op_sel_hi:[1,0,1]
	s_nop 0
	v_pk_add_f32 v[88:89], v[68:69], v[76:77]
	v_pk_add_f32 v[68:69], v[68:69], v[76:77] neg_lo:[0,1] neg_hi:[0,1]
	v_pk_mul_f32 v[76:77], v[26:27], s[60:61] op_sel:[1,0] op_sel_hi:[0,0] neg_lo:[1,0]
	s_nop 0
	v_pk_fma_f32 v[26:27], v[26:27], s[62:63], v[76:77] op_sel_hi:[1,0,1]
	s_nop 0
	v_pk_add_f32 v[76:77], v[8:9], v[26:27]
	v_pk_add_f32 v[8:9], v[8:9], v[26:27] neg_lo:[0,1] neg_hi:[0,1]
	v_pk_mul_f32 v[26:27], v[62:63], s[46:47] op_sel:[1,0] op_sel_hi:[0,0] neg_lo:[1,0]
	s_nop 0
	v_pk_fma_f32 v[26:27], v[62:63], s[58:59], v[26:27] op_sel_hi:[1,0,1]
	s_nop 0
	v_pk_add_f32 v[62:63], v[16:17], v[26:27]
	v_pk_add_f32 v[16:17], v[16:17], v[26:27] neg_lo:[0,1] neg_hi:[0,1]
	v_xor_b32_e32 v26, 0x80000000, v21
	v_mov_b32_e32 v27, v20
	v_pk_add_f32 v[20:21], v[10:11], v[26:27]
	v_pk_add_f32 v[10:11], v[10:11], v[26:27] neg_lo:[0,1] neg_hi:[0,1]
	v_pk_mul_f32 v[26:27], v[72:73], s[58:59] op_sel_hi:[1,0]
	s_nop 0
	v_pk_fma_f32 v[26:27], v[134:135], s[46:47], v[26:27] op_sel_hi:[1,0,1] neg_lo:[0,0,1] neg_hi:[0,0,1]
	v_xor_b32_e32 v134, 0x80000000, v75
	v_pk_add_f32 v[72:73], v[90:91], v[26:27]
	v_pk_add_f32 v[26:27], v[90:91], v[26:27] neg_lo:[0,1] neg_hi:[0,1]
	v_pk_mul_f32 v[90:91], v[74:75], s[62:63] op_sel_hi:[1,0]
	v_mov_b32_e32 v135, v74
	v_pk_fma_f32 v[74:75], v[134:135], s[60:61], v[90:91] op_sel_hi:[1,0,1] neg_lo:[0,0,1] neg_hi:[0,0,1]
	v_xor_b32_e32 v134, 0x80000000, v79
	v_pk_add_f32 v[90:91], v[80:81], v[74:75]
	v_pk_add_f32 v[74:75], v[80:81], v[74:75] neg_lo:[0,1] neg_hi:[0,1]
	v_pk_mul_f32 v[80:81], v[78:79], s[66:67] op_sel_hi:[1,0]
	v_mov_b32_e32 v135, v78
	v_pk_fma_f32 v[78:79], v[134:135], s[64:65], v[80:81] op_sel_hi:[1,0,1] neg_lo:[0,0,1] neg_hi:[0,0,1]
	v_xor_b32_e32 v134, 0x80000000, v83
	v_pk_add_f32 v[80:81], v[12:13], v[78:79]
	v_pk_add_f32 v[12:13], v[12:13], v[78:79] neg_lo:[0,1] neg_hi:[0,1]
	v_pk_mul_f32 v[78:79], v[82:83], s[70:71] op_sel_hi:[1,0]
	v_mov_b32_e32 v135, v82
	v_pk_fma_f32 v[78:79], v[134:135], s[70:71], v[78:79] op_sel_hi:[1,0,1] neg_lo:[0,0,1] neg_hi:[0,0,1]
	v_xor_b32_e32 v134, 0x80000000, v15
	v_pk_add_f32 v[82:83], v[64:65], v[78:79]
	v_pk_add_f32 v[64:65], v[64:65], v[78:79] neg_lo:[0,1] neg_hi:[0,1]
	v_pk_mul_f32 v[78:79], v[14:15], s[64:65] op_sel_hi:[1,0]
	v_mov_b32_e32 v135, v14
	v_pk_fma_f32 v[14:15], v[134:135], s[66:67], v[78:79] op_sel_hi:[1,0,1] neg_lo:[0,0,1] neg_hi:[0,0,1]
	v_xor_b32_e32 v134, 0x80000000, v19
	v_pk_add_f32 v[78:79], v[2:3], v[14:15]
	v_pk_add_f32 v[2:3], v[2:3], v[14:15] neg_lo:[0,1] neg_hi:[0,1]
	v_pk_mul_f32 v[14:15], v[18:19], s[60:61] op_sel_hi:[1,0]
	v_mov_b32_e32 v135, v18
	v_pk_fma_f32 v[14:15], v[134:135], s[62:63], v[14:15] op_sel_hi:[1,0,1] neg_lo:[0,0,1] neg_hi:[0,0,1]
	v_xor_b32_e32 v134, 0x80000000, v23
	v_pk_add_f32 v[18:19], v[4:5], v[14:15]
	v_pk_add_f32 v[4:5], v[4:5], v[14:15] neg_lo:[0,1] neg_hi:[0,1]
	v_pk_mul_f32 v[14:15], v[22:23], s[46:47] op_sel_hi:[1,0]
	v_mov_b32_e32 v135, v22
	v_pk_fma_f32 v[14:15], v[134:135], s[58:59], v[14:15] op_sel_hi:[1,0,1] neg_lo:[0,0,1] neg_hi:[0,0,1]
	s_nop 0
	v_pk_add_f32 v[22:23], v[0:1], v[14:15]
	v_pk_add_f32 v[0:1], v[0:1], v[14:15] neg_lo:[0,1] neg_hi:[0,1]
	ds_write_b64 v67, v[24:25]
	ds_write_b64 v98, v[130:131]
	ds_write_b64 v99, v[96:97] offset:256
	ds_write_b64 v100, v[132:133] offset:256
	ds_write_b64 v101, v[92:93] offset:512
	ds_write_b64 v102, v[88:89] offset:512
	ds_write_b64 v103, v[76:77] offset:768
	ds_write_b64 v104, v[62:63] offset:768
	ds_write_b64 v105, v[20:21] offset:1024
	ds_write_b64 v106, v[72:73] offset:1024
	ds_write_b64 v107, v[90:91] offset:1280
	ds_write_b64 v108, v[80:81] offset:1280
	ds_write_b64 v109, v[82:83] offset:1536
	ds_write_b64 v110, v[78:79] offset:1536
	ds_write_b64 v111, v[18:19] offset:1792
	ds_write_b64 v112, v[22:23] offset:1792
	ds_write_b64 v113, v[6:7] offset:2048
	ds_write_b64 v114, v[84:85] offset:2048
	ds_write_b64 v115, v[94:95] offset:2304
	ds_write_b64 v116, v[86:87] offset:2304
	ds_write_b64 v117, v[70:71] offset:2560
	ds_write_b64 v118, v[68:69] offset:2560
	ds_write_b64 v119, v[8:9] offset:2816
	ds_write_b64 v120, v[16:17] offset:2816
	ds_write_b64 v121, v[10:11] offset:3072
	ds_write_b64 v122, v[26:27] offset:3072
	ds_write_b64 v123, v[74:75] offset:3328
	ds_write_b64 v124, v[12:13] offset:3328
	ds_write_b64 v125, v[64:65] offset:3584
	ds_write_b64 v126, v[2:3] offset:3584
	ds_write_b64 v127, v[4:5] offset:3840
	ds_write_b64 v128, v[0:1] offset:3840
	v_mov_b32_e32 v74, v146
	s_waitcnt lgkmcnt(0)
	s_barrier
	s_nop 0
	v_lshrrev_b32_e32 v0, 5, v74
	v_bfe_u32 v4, v74, 5, 4
	v_bitop3_b32 v0, v0, v74, 15 bitop3:0x6c
	v_bitop3_b32 v4, v4, v74, 16 bitop3:0x36
	v_lshlrev_b32_e32 v66, 3, v0
	v_lshlrev_b32_e32 v67, 3, v4
	v_add_u32_e32 v5, 16, v66
	v_add_u32_e32 v4, 16, v67
	v_add_u32_e32 v62, s47, v66
	v_add_u32_e32 v70, s9, v66
	ds_read2st64_b64 v[0:3], v5 offset1:16
	ds_read2st64_b64 v[16:19], v4 offset0:8 offset1:24
	ds_read2st64_b64 v[24:27], v5 offset0:32 offset1:48
	ds_read2st64_b64 v[8:11], v4 offset0:40 offset1:56
	ds_read2st64_b64 v[92:95], v5 offset0:64 offset1:80
	ds_read2st64_b64 v[12:15], v4 offset0:72 offset1:88
	ds_read2st64_b64 v[20:23], v5 offset0:96 offset1:112
	ds_read2st64_b64 v[4:7], v4 offset0:104 offset1:120
	ds_read_b64 v[68:69], v62
	ds_read_b64 v[72:73], v70
	v_add_u32_e32 v62, s19, v67
	v_add_u32_e32 v70, s8, v67
	ds_read_b64 v[84:85], v62
	ds_read_b64 v[90:91], v70
	v_add_u32_e32 v62, s18, v66
	v_add_u32_e32 v70, s7, v66
	ds_read_b64 v[96:97], v62
	ds_read_b64 v[100:101], v70
	v_add_u32_e32 v62, s17, v67
	v_add_u32_e32 v70, s6, v67
	ds_read_b64 v[64:65], v62
	ds_read_b64 v[70:71], v70
	v_add_u32_e32 v62, s13, v66
	v_add_u32_e32 v75, s5, v66
	ds_read_b64 v[86:87], v62
	ds_read_b64 v[102:103], v75
	v_add_u32_e32 v62, s12, v67
	v_add_u32_e32 v75, s4, v67
	ds_read_b64 v[80:81], v62
	ds_read_b64 v[88:89], v75
	v_add_u32_e32 v62, s11, v66
	v_add_u32_e32 v66, s1, v66
	ds_read_b64 v[98:99], v62
	ds_read_b64 v[104:105], v66
	v_add_u32_e32 v62, s10, v67
	v_add_u32_e32 v66, s0, v67
	ds_read_b64 v[62:63], v62
	ds_read_b64 v[66:67], v66
	s_waitcnt lgkmcnt(14)
	s_nop 0
	v_cvt_f32_i32_e32 v74, v74
	s_nop 0
	s_lshl_b64 s[0:1], s[44:45], 2
	s_add_u32 s0, s24, s0
	v_mul_f32_e32 v74, 0x38800000, v74
	v_cos_f32_e32 v78, v74
	v_sin_f32_e32 v79, v74
	s_addc_u32 s1, s59, s1
	s_and_b64 vcc, s[14:15], exec
	v_add_f32_e32 v76, v78, v78
	v_pk_mul_f32 v[74:75], v[78:79], v[78:79]
	v_mul_f32_e32 v76, v79, v76
	s_nop 0
	s_nop 0
	v_mov_b32_e32 v108, v79
	v_pk_add_f32 v[74:75], v[74:75], v[74:75] op_sel:[0,1] op_sel_hi:[0,1] neg_lo:[0,1] neg_hi:[0,1]
	v_pk_mul_f32 v[82:83], v[78:79], v[76:77] op_sel:[1,0] op_sel_hi:[0,0] neg_lo:[1,0]
	v_pk_mul_f32 v[106:107], v[68:69], v[108:109] op_sel:[1,0] op_sel_hi:[0,0] neg_lo:[1,0]
	v_pk_fma_f32 v[82:83], v[78:79], v[74:75], v[82:83]
	v_pk_fma_f32 v[68:69], v[68:69], v[78:79], v[106:107] op_sel_hi:[1,0,1]
	v_pk_mul_f32 v[78:79], v[76:77], s[48:49] op_sel_hi:[0,1]
	v_pk_fma_f32 v[106:107], v[74:75], s[40:41], v[78:79]
	s_nop 0
	v_pk_mul_f32 v[78:79], v[92:93], v[106:107] op_sel:[1,1] op_sel_hi:[0,1] neg_lo:[1,0]
	s_nop 0
	v_pk_fma_f32 v[78:79], v[92:93], v[106:107], v[78:79] op_sel_hi:[1,0,1]
	v_pk_mul_f32 v[92:93], v[76:77], v[82:83] op_sel:[0,1] op_sel_hi:[0,0] neg_lo:[0,1]
	v_pk_mul_f32 v[108:109], v[72:73], v[82:83] op_sel:[1,1] op_sel_hi:[0,1] neg_lo:[1,0]
	v_pk_fma_f32 v[92:93], v[74:75], v[82:83], v[92:93]
	v_pk_fma_f32 v[72:73], v[72:73], v[82:83], v[108:109] op_sel_hi:[1,0,1]
	v_pk_mul_f32 v[82:83], v[76:77], v[106:107] op_sel:[0,1] op_sel_hi:[0,0] neg_lo:[0,1]
	v_pk_fma_f32 v[106:107], v[74:75], v[106:107], v[82:83]
	s_nop 0
	v_pk_mul_f32 v[82:83], v[24:25], v[106:107] op_sel:[1,1] op_sel_hi:[0,1] neg_lo:[1,0]
	s_nop 0
	v_pk_fma_f32 v[82:83], v[24:25], v[106:107], v[82:83] op_sel_hi:[1,0,1]
	v_pk_mul_f32 v[24:25], v[76:77], v[92:93] op_sel:[0,1] op_sel_hi:[0,0] neg_lo:[0,1]
	v_pk_fma_f32 v[108:109], v[74:75], v[92:93], v[24:25]
	s_waitcnt lgkmcnt(7)
	v_pk_mul_f32 v[24:25], v[86:87], v[92:93] op_sel:[1,1] op_sel_hi:[0,1] neg_lo:[1,0]
	s_nop 0
	v_pk_fma_f32 v[24:25], v[86:87], v[92:93], v[24:25] op_sel_hi:[1,0,1]
	v_pk_mul_f32 v[86:87], v[76:77], v[106:107] op_sel:[0,1] op_sel_hi:[0,0] neg_lo:[0,1]
	v_pk_fma_f32 v[92:93], v[74:75], v[106:107], v[86:87]
	s_nop 0
	v_pk_mul_f32 v[86:87], v[20:21], v[92:93] op_sel:[1,1] op_sel_hi:[0,1] neg_lo:[1,0]
	s_nop 0
	v_pk_fma_f32 v[86:87], v[20:21], v[92:93], v[86:87] op_sel_hi:[1,0,1]
	v_pk_mul_f32 v[20:21], v[76:77], v[108:109] op_sel:[0,1] op_sel_hi:[0,0] neg_lo:[0,1]
	v_pk_fma_f32 v[106:107], v[74:75], v[108:109], v[20:21]
	s_waitcnt lgkmcnt(6)
	v_pk_mul_f32 v[20:21], v[102:103], v[108:109] op_sel:[1,1] op_sel_hi:[0,1] neg_lo:[1,0]
	s_nop 0
	v_pk_fma_f32 v[20:21], v[102:103], v[108:109], v[20:21] op_sel_hi:[1,0,1]
	v_pk_mul_f32 v[102:103], v[76:77], v[92:93] op_sel:[0,1] op_sel_hi:[0,0] neg_lo:[0,1]
	v_pk_fma_f32 v[102:103], v[74:75], v[92:93], v[102:103]
	s_nop 0
	v_pk_mul_f32 v[92:93], v[2:3], v[102:103] op_sel:[1,1] op_sel_hi:[0,1] neg_lo:[1,0]
	s_nop 0
	v_pk_fma_f32 v[92:93], v[2:3], v[102:103], v[92:93] op_sel_hi:[1,0,1]
	v_pk_mul_f32 v[2:3], v[76:77], v[106:107] op_sel:[0,1] op_sel_hi:[0,0] neg_lo:[0,1]
	v_pk_fma_f32 v[108:109], v[74:75], v[106:107], v[2:3]
	v_pk_mul_f32 v[2:3], v[96:97], v[106:107] op_sel:[1,1] op_sel_hi:[0,1] neg_lo:[1,0]
	s_nop 0
	v_pk_fma_f32 v[2:3], v[96:97], v[106:107], v[2:3] op_sel_hi:[1,0,1]
	v_pk_mul_f32 v[96:97], v[76:77], v[102:103] op_sel:[0,1] op_sel_hi:[0,0] neg_lo:[0,1]
	v_pk_fma_f32 v[102:103], v[74:75], v[102:103], v[96:97]
	s_nop 0
	v_pk_mul_f32 v[96:97], v[94:95], v[102:103] op_sel:[1,1] op_sel_hi:[0,1] neg_lo:[1,0]
	s_nop 0
	v_pk_fma_f32 v[96:97], v[94:95], v[102:103], v[96:97] op_sel_hi:[1,0,1]
	v_pk_mul_f32 v[94:95], v[76:77], v[108:109] op_sel:[0,1] op_sel_hi:[0,0] neg_lo:[0,1]
	v_pk_fma_f32 v[106:107], v[74:75], v[108:109], v[94:95]
	v_pk_mul_f32 v[94:95], v[100:101], v[108:109] op_sel:[1,1] op_sel_hi:[0,1] neg_lo:[1,0]
	s_nop 0
	v_pk_fma_f32 v[94:95], v[100:101], v[108:109], v[94:95] op_sel_hi:[1,0,1]
	v_pk_mul_f32 v[100:101], v[76:77], v[102:103] op_sel:[0,1] op_sel_hi:[0,0] neg_lo:[0,1]
	v_pk_fma_f32 v[100:101], v[74:75], v[102:103], v[100:101]
	s_nop 0
	v_pk_mul_f32 v[102:103], v[26:27], v[100:101] op_sel:[1,1] op_sel_hi:[0,1] neg_lo:[1,0]
	s_waitcnt lgkmcnt(3)
	v_pk_fma_f32 v[26:27], v[26:27], v[100:101], v[102:103] op_sel_hi:[1,0,1]
	v_pk_mul_f32 v[102:103], v[76:77], v[106:107] op_sel:[0,1] op_sel_hi:[0,0] neg_lo:[0,1]
	v_pk_mul_f32 v[108:109], v[98:99], v[106:107] op_sel:[1,1] op_sel_hi:[0,1] neg_lo:[1,0]
	v_pk_fma_f32 v[102:103], v[74:75], v[106:107], v[102:103]
	v_pk_fma_f32 v[98:99], v[98:99], v[106:107], v[108:109] op_sel_hi:[1,0,1]
	v_pk_mul_f32 v[106:107], v[76:77], v[100:101] op_sel:[0,1] op_sel_hi:[0,0] neg_lo:[0,1]
	v_pk_fma_f32 v[100:101], v[74:75], v[100:101], v[106:107]
	s_nop 0
	v_pk_mul_f32 v[106:107], v[22:23], v[100:101] op_sel:[1,1] op_sel_hi:[0,1] neg_lo:[1,0]
	s_waitcnt lgkmcnt(2)
	v_pk_fma_f32 v[22:23], v[22:23], v[100:101], v[106:107] op_sel_hi:[1,0,1]
	v_pk_mul_f32 v[106:107], v[76:77], v[102:103] op_sel:[0,1] op_sel_hi:[0,0] neg_lo:[0,1]
	v_pk_mul_f32 v[108:109], v[104:105], v[102:103] op_sel:[1,1] op_sel_hi:[0,1] neg_lo:[1,0]
	v_pk_fma_f32 v[106:107], v[74:75], v[102:103], v[106:107]
	v_pk_fma_f32 v[102:103], v[104:105], v[102:103], v[108:109] op_sel_hi:[1,0,1]
	v_pk_mul_f32 v[104:105], v[76:77], v[100:101] op_sel:[0,1] op_sel_hi:[0,0] neg_lo:[0,1]
	v_pk_fma_f32 v[100:101], v[74:75], v[100:101], v[104:105]
	s_nop 0
	v_pk_mul_f32 v[104:105], v[16:17], v[100:101] op_sel:[1,1] op_sel_hi:[0,1] neg_lo:[1,0]
	s_nop 0
	v_pk_fma_f32 v[16:17], v[16:17], v[100:101], v[104:105] op_sel_hi:[1,0,1]
	v_pk_mul_f32 v[104:105], v[76:77], v[106:107] op_sel:[0,1] op_sel_hi:[0,0] neg_lo:[0,1]
	v_pk_mul_f32 v[108:109], v[84:85], v[106:107] op_sel:[1,1] op_sel_hi:[0,1] neg_lo:[1,0]
	v_pk_fma_f32 v[104:105], v[74:75], v[106:107], v[104:105]
	v_pk_fma_f32 v[84:85], v[84:85], v[106:107], v[108:109] op_sel_hi:[1,0,1]
	v_pk_mul_f32 v[106:107], v[76:77], v[100:101] op_sel:[0,1] op_sel_hi:[0,0] neg_lo:[0,1]
	v_pk_fma_f32 v[100:101], v[74:75], v[100:101], v[106:107]
	s_nop 0
	v_pk_mul_f32 v[106:107], v[12:13], v[100:101] op_sel:[1,1] op_sel_hi:[0,1] neg_lo:[1,0]
	s_nop 0
	v_pk_fma_f32 v[12:13], v[12:13], v[100:101], v[106:107] op_sel_hi:[1,0,1]
	v_pk_mul_f32 v[106:107], v[76:77], v[104:105] op_sel:[0,1] op_sel_hi:[0,0] neg_lo:[0,1]
	v_pk_mul_f32 v[108:109], v[90:91], v[104:105] op_sel:[1,1] op_sel_hi:[0,1] neg_lo:[1,0]
	v_pk_fma_f32 v[106:107], v[74:75], v[104:105], v[106:107]
	v_pk_fma_f32 v[90:91], v[90:91], v[104:105], v[108:109] op_sel_hi:[1,0,1]
	v_pk_mul_f32 v[104:105], v[76:77], v[100:101] op_sel:[0,1] op_sel_hi:[0,0] neg_lo:[0,1]
	v_pk_fma_f32 v[100:101], v[74:75], v[100:101], v[104:105]
	s_nop 0
	v_pk_mul_f32 v[104:105], v[8:9], v[100:101] op_sel:[1,1] op_sel_hi:[0,1] neg_lo:[1,0]
	s_nop 0
	v_pk_fma_f32 v[8:9], v[8:9], v[100:101], v[104:105] op_sel_hi:[1,0,1]
	v_pk_mul_f32 v[104:105], v[76:77], v[106:107] op_sel:[0,1] op_sel_hi:[0,0] neg_lo:[0,1]
	v_pk_mul_f32 v[108:109], v[80:81], v[106:107] op_sel:[1,1] op_sel_hi:[0,1] neg_lo:[1,0]
	v_pk_fma_f32 v[104:105], v[74:75], v[106:107], v[104:105]
	v_pk_fma_f32 v[80:81], v[80:81], v[106:107], v[108:109] op_sel_hi:[1,0,1]
	v_pk_mul_f32 v[106:107], v[76:77], v[100:101] op_sel:[0,1] op_sel_hi:[0,0] neg_lo:[0,1]
	v_pk_fma_f32 v[100:101], v[74:75], v[100:101], v[106:107]
	s_nop 0
	v_pk_mul_f32 v[106:107], v[4:5], v[100:101] op_sel:[1,1] op_sel_hi:[0,1] neg_lo:[1,0]
	s_nop 0
	v_pk_fma_f32 v[4:5], v[4:5], v[100:101], v[106:107] op_sel_hi:[1,0,1]
	v_pk_mul_f32 v[106:107], v[76:77], v[104:105] op_sel:[0,1] op_sel_hi:[0,0] neg_lo:[0,1]
	v_pk_mul_f32 v[108:109], v[88:89], v[104:105] op_sel:[1,1] op_sel_hi:[0,1] neg_lo:[1,0]
	v_pk_fma_f32 v[106:107], v[74:75], v[104:105], v[106:107]
	v_pk_fma_f32 v[88:89], v[88:89], v[104:105], v[108:109] op_sel_hi:[1,0,1]
	v_pk_mul_f32 v[104:105], v[76:77], v[100:101] op_sel:[0,1] op_sel_hi:[0,0] neg_lo:[0,1]
	v_pk_fma_f32 v[100:101], v[74:75], v[100:101], v[104:105]
	s_nop 0
	v_pk_mul_f32 v[104:105], v[18:19], v[100:101] op_sel:[1,1] op_sel_hi:[0,1] neg_lo:[1,0]
	s_nop 0
	v_pk_fma_f32 v[18:19], v[18:19], v[100:101], v[104:105] op_sel_hi:[1,0,1]
	v_pk_mul_f32 v[104:105], v[76:77], v[106:107] op_sel:[0,1] op_sel_hi:[0,0] neg_lo:[0,1]
	v_pk_mul_f32 v[108:109], v[64:65], v[106:107] op_sel:[1,1] op_sel_hi:[0,1] neg_lo:[1,0]
	v_pk_fma_f32 v[104:105], v[74:75], v[106:107], v[104:105]
	v_pk_fma_f32 v[64:65], v[64:65], v[106:107], v[108:109] op_sel_hi:[1,0,1]
	v_pk_mul_f32 v[106:107], v[76:77], v[100:101] op_sel:[0,1] op_sel_hi:[0,0] neg_lo:[0,1]
	v_pk_fma_f32 v[100:101], v[74:75], v[100:101], v[106:107]
	s_nop 0
	v_pk_mul_f32 v[106:107], v[14:15], v[100:101] op_sel:[1,1] op_sel_hi:[0,1] neg_lo:[1,0]
	s_nop 0
	v_pk_fma_f32 v[14:15], v[14:15], v[100:101], v[106:107] op_sel_hi:[1,0,1]
	v_pk_mul_f32 v[106:107], v[76:77], v[104:105] op_sel:[0,1] op_sel_hi:[0,0] neg_lo:[0,1]
	v_pk_mul_f32 v[108:109], v[70:71], v[104:105] op_sel:[1,1] op_sel_hi:[0,1] neg_lo:[1,0]
	v_pk_fma_f32 v[106:107], v[74:75], v[104:105], v[106:107]
	v_pk_fma_f32 v[70:71], v[70:71], v[104:105], v[108:109] op_sel_hi:[1,0,1]
	v_pk_mul_f32 v[104:105], v[76:77], v[100:101] op_sel:[0,1] op_sel_hi:[0,0] neg_lo:[0,1]
	v_pk_fma_f32 v[100:101], v[74:75], v[100:101], v[104:105]
	s_nop 0
	v_pk_mul_f32 v[104:105], v[10:11], v[100:101] op_sel:[1,1] op_sel_hi:[0,1] neg_lo:[1,0]
	s_waitcnt lgkmcnt(1)
	v_pk_fma_f32 v[10:11], v[10:11], v[100:101], v[104:105] op_sel_hi:[1,0,1]
	v_pk_mul_f32 v[104:105], v[76:77], v[106:107] op_sel:[0,1] op_sel_hi:[0,0] neg_lo:[0,1]
	v_pk_mul_f32 v[108:109], v[62:63], v[106:107] op_sel:[1,1] op_sel_hi:[0,1] neg_lo:[1,0]
	v_pk_fma_f32 v[104:105], v[74:75], v[106:107], v[104:105]
	v_pk_fma_f32 v[62:63], v[62:63], v[106:107], v[108:109] op_sel_hi:[1,0,1]
	v_pk_mul_f32 v[76:77], v[76:77], v[100:101] op_sel:[0,1] op_sel_hi:[0,0] neg_lo:[0,1]
	v_pk_fma_f32 v[74:75], v[74:75], v[100:101], v[76:77]
	s_nop 0
	v_pk_mul_f32 v[76:77], v[6:7], v[74:75] op_sel:[1,1] op_sel_hi:[0,1] neg_lo:[1,0]
	s_nop 0
	v_pk_fma_f32 v[6:7], v[6:7], v[74:75], v[76:77] op_sel_hi:[1,0,1]
	s_waitcnt lgkmcnt(0)
	v_pk_mul_f32 v[74:75], v[66:67], v[104:105] op_sel:[1,1] op_sel_hi:[0,1] neg_lo:[1,0]
	v_pk_add_f32 v[76:77], v[82:83], v[8:9]
	v_pk_fma_f32 v[66:67], v[66:67], v[104:105], v[74:75] op_sel_hi:[1,0,1]
	v_pk_add_f32 v[74:75], v[0:1], v[16:17]
	v_pk_add_f32 v[0:1], v[0:1], v[16:17] neg_lo:[0,1] neg_hi:[0,1]
	v_pk_add_f32 v[16:17], v[92:93], v[18:19]
	v_pk_add_f32 v[18:19], v[92:93], v[18:19] neg_lo:[0,1] neg_hi:[0,1]
	v_pk_add_f32 v[8:9], v[82:83], v[8:9] neg_lo:[0,1] neg_hi:[0,1]
	v_pk_add_f32 v[82:83], v[26:27], v[10:11]
	v_pk_add_f32 v[10:11], v[26:27], v[10:11] neg_lo:[0,1] neg_hi:[0,1]
	v_pk_add_f32 v[92:93], v[86:87], v[4:5]
	v_pk_add_f32 v[4:5], v[86:87], v[4:5] neg_lo:[0,1] neg_hi:[0,1]
	v_pk_add_f32 v[86:87], v[22:23], v[6:7]
	v_pk_add_f32 v[6:7], v[22:23], v[6:7] neg_lo:[0,1] neg_hi:[0,1]
	v_pk_add_f32 v[22:23], v[68:69], v[84:85]
	v_pk_add_f32 v[68:69], v[68:69], v[84:85] neg_lo:[0,1] neg_hi:[0,1]
	v_pk_add_f32 v[84:85], v[2:3], v[64:65]
	v_pk_add_f32 v[2:3], v[2:3], v[64:65] neg_lo:[0,1] neg_hi:[0,1]
	v_pk_add_f32 v[64:65], v[24:25], v[80:81]
	v_pk_add_f32 v[24:25], v[24:25], v[80:81] neg_lo:[0,1] neg_hi:[0,1]
	v_pk_add_f32 v[80:81], v[98:99], v[62:63]
	v_pk_add_f32 v[62:63], v[98:99], v[62:63] neg_lo:[0,1] neg_hi:[0,1]
	v_pk_add_f32 v[98:99], v[74:75], v[16:17]
	v_pk_add_f32 v[16:17], v[74:75], v[16:17] neg_lo:[0,1] neg_hi:[0,1]
	v_xor_b32_e32 v74, 0x80000000, v19
	v_mov_b32_e32 v75, v18
	v_pk_add_f32 v[26:27], v[78:79], v[12:13]
	v_pk_add_f32 v[12:13], v[78:79], v[12:13] neg_lo:[0,1] neg_hi:[0,1]
	v_pk_add_f32 v[78:79], v[96:97], v[14:15]
	v_pk_add_f32 v[14:15], v[96:97], v[14:15] neg_lo:[0,1] neg_hi:[0,1]
	v_pk_add_f32 v[18:19], v[0:1], v[74:75]
	v_pk_add_f32 v[0:1], v[0:1], v[74:75] neg_lo:[0,1] neg_hi:[0,1]
	v_pk_add_f32 v[74:75], v[76:77], v[82:83]
	v_pk_add_f32 v[76:77], v[76:77], v[82:83] neg_lo:[0,1] neg_hi:[0,1]
	v_xor_b32_e32 v82, 0x80000000, v11
	v_mov_b32_e32 v83, v10
	v_pk_add_f32 v[10:11], v[8:9], v[82:83]
	v_pk_add_f32 v[8:9], v[8:9], v[82:83] neg_lo:[0,1] neg_hi:[0,1]
	v_pk_add_f32 v[82:83], v[26:27], v[78:79]
	v_pk_add_f32 v[26:27], v[26:27], v[78:79] neg_lo:[0,1] neg_hi:[0,1]
	v_xor_b32_e32 v78, 0x80000000, v15
	v_mov_b32_e32 v79, v14
	v_pk_add_f32 v[14:15], v[12:13], v[78:79]
	v_pk_add_f32 v[12:13], v[12:13], v[78:79] neg_lo:[0,1] neg_hi:[0,1]
	v_pk_add_f32 v[78:79], v[92:93], v[86:87]
	v_pk_add_f32 v[86:87], v[92:93], v[86:87] neg_lo:[0,1] neg_hi:[0,1]
	v_xor_b32_e32 v92, 0x80000000, v7
	v_mov_b32_e32 v93, v6
	v_pk_add_f32 v[6:7], v[4:5], v[92:93]
	v_pk_add_f32 v[4:5], v[4:5], v[92:93] neg_lo:[0,1] neg_hi:[0,1]
	v_pk_add_f32 v[92:93], v[22:23], v[84:85]
	v_pk_add_f32 v[22:23], v[22:23], v[84:85] neg_lo:[0,1] neg_hi:[0,1]
	v_xor_b32_e32 v84, 0x80000000, v3
	v_mov_b32_e32 v85, v2
	v_pk_add_f32 v[96:97], v[72:73], v[90:91]
	v_pk_add_f32 v[72:73], v[72:73], v[90:91] neg_lo:[0,1] neg_hi:[0,1]
	v_pk_add_f32 v[90:91], v[94:95], v[70:71]
	v_pk_add_f32 v[70:71], v[94:95], v[70:71] neg_lo:[0,1] neg_hi:[0,1]
	v_pk_add_f32 v[2:3], v[68:69], v[84:85]
	v_pk_add_f32 v[68:69], v[68:69], v[84:85] neg_lo:[0,1] neg_hi:[0,1]
	v_pk_add_f32 v[84:85], v[64:65], v[80:81]
	v_pk_add_f32 v[64:65], v[64:65], v[80:81] neg_lo:[0,1] neg_hi:[0,1]
	v_xor_b32_e32 v80, 0x80000000, v63
	v_mov_b32_e32 v81, v62
	v_pk_add_f32 v[94:95], v[20:21], v[88:89]
	v_pk_add_f32 v[20:21], v[20:21], v[88:89] neg_lo:[0,1] neg_hi:[0,1]
	v_pk_add_f32 v[88:89], v[102:103], v[66:67]
	v_pk_add_f32 v[66:67], v[102:103], v[66:67] neg_lo:[0,1] neg_hi:[0,1]
	v_pk_add_f32 v[62:63], v[24:25], v[80:81]
	v_pk_add_f32 v[24:25], v[24:25], v[80:81] neg_lo:[0,1] neg_hi:[0,1]
	v_pk_add_f32 v[80:81], v[96:97], v[90:91]
	v_pk_add_f32 v[90:91], v[96:97], v[90:91] neg_lo:[0,1] neg_hi:[0,1]
	v_xor_b32_e32 v96, 0x80000000, v71
	v_mov_b32_e32 v97, v70
	v_pk_add_f32 v[70:71], v[72:73], v[96:97]
	v_pk_add_f32 v[72:73], v[72:73], v[96:97] neg_lo:[0,1] neg_hi:[0,1]
	v_pk_add_f32 v[96:97], v[94:95], v[88:89]
	v_pk_add_f32 v[88:89], v[94:95], v[88:89] neg_lo:[0,1] neg_hi:[0,1]
	v_xor_b32_e32 v94, 0x80000000, v67
	v_mov_b32_e32 v95, v66
	v_pk_add_f32 v[66:67], v[20:21], v[94:95]
	v_pk_add_f32 v[20:21], v[20:21], v[94:95] neg_lo:[0,1] neg_hi:[0,1]
	v_pk_add_f32 v[94:95], v[98:99], v[74:75]
	v_pk_add_f32 v[74:75], v[98:99], v[74:75] neg_lo:[0,1] neg_hi:[0,1]
	v_pk_mul_f32 v[98:99], v[10:11], s[70:71] op_sel:[1,0] op_sel_hi:[0,0] neg_lo:[1,0]
	v_xor_b32_e32 v100, 0x80000000, v9
	v_pk_fma_f32 v[10:11], v[10:11], s[70:71], v[98:99] op_sel_hi:[1,0,1]
	v_mov_b32_e32 v101, v8
	v_pk_add_f32 v[98:99], v[18:19], v[10:11]
	v_pk_add_f32 v[10:11], v[18:19], v[10:11] neg_lo:[0,1] neg_hi:[0,1]
	v_xor_b32_e32 v18, 0x80000000, v77
	v_mov_b32_e32 v19, v76
	v_pk_add_f32 v[76:77], v[16:17], v[18:19]
	v_pk_add_f32 v[16:17], v[16:17], v[18:19] neg_lo:[0,1] neg_hi:[0,1]
	v_pk_mul_f32 v[18:19], v[8:9], s[70:71] op_sel_hi:[1,0]
	s_nop 0
	v_pk_fma_f32 v[8:9], v[100:101], s[70:71], v[18:19] op_sel_hi:[1,0,1] neg_lo:[0,0,1] neg_hi:[0,0,1]
	v_xor_b32_e32 v100, 0x80000000, v5
	v_pk_add_f32 v[18:19], v[0:1], v[8:9]
	v_pk_add_f32 v[0:1], v[0:1], v[8:9] neg_lo:[0,1] neg_hi:[0,1]
	v_pk_add_f32 v[8:9], v[82:83], v[78:79]
	v_pk_add_f32 v[78:79], v[82:83], v[78:79] neg_lo:[0,1] neg_hi:[0,1]
	v_pk_mul_f32 v[82:83], v[6:7], s[70:71] op_sel:[1,0] op_sel_hi:[0,0] neg_lo:[1,0]
	v_mov_b32_e32 v101, v4
	v_pk_fma_f32 v[6:7], v[6:7], s[70:71], v[82:83] op_sel_hi:[1,0,1]
	s_nop 0
	v_pk_add_f32 v[82:83], v[14:15], v[6:7]
	v_pk_add_f32 v[6:7], v[14:15], v[6:7] neg_lo:[0,1] neg_hi:[0,1]
	v_xor_b32_e32 v14, 0x80000000, v87
	v_mov_b32_e32 v15, v86
	v_pk_add_f32 v[86:87], v[26:27], v[14:15]
	v_pk_add_f32 v[14:15], v[26:27], v[14:15] neg_lo:[0,1] neg_hi:[0,1]
	v_pk_mul_f32 v[26:27], v[4:5], s[70:71] op_sel_hi:[1,0]
	s_nop 0
	v_pk_fma_f32 v[4:5], v[100:101], s[70:71], v[26:27] op_sel_hi:[1,0,1] neg_lo:[0,0,1] neg_hi:[0,0,1]
	v_xor_b32_e32 v100, 0x80000000, v25
	v_pk_add_f32 v[26:27], v[12:13], v[4:5]
	v_pk_add_f32 v[4:5], v[12:13], v[4:5] neg_lo:[0,1] neg_hi:[0,1]
	v_pk_add_f32 v[12:13], v[92:93], v[84:85]
	v_pk_add_f32 v[84:85], v[92:93], v[84:85] neg_lo:[0,1] neg_hi:[0,1]
	v_pk_mul_f32 v[92:93], v[62:63], s[70:71] op_sel:[1,0] op_sel_hi:[0,0] neg_lo:[1,0]
	v_mov_b32_e32 v101, v24
	v_pk_fma_f32 v[62:63], v[62:63], s[70:71], v[92:93] op_sel_hi:[1,0,1]
	s_nop 0
	v_pk_add_f32 v[92:93], v[2:3], v[62:63]
	v_pk_add_f32 v[2:3], v[2:3], v[62:63] neg_lo:[0,1] neg_hi:[0,1]
	v_xor_b32_e32 v62, 0x80000000, v65
	v_mov_b32_e32 v63, v64
	v_pk_add_f32 v[64:65], v[22:23], v[62:63]
	v_pk_add_f32 v[22:23], v[22:23], v[62:63] neg_lo:[0,1] neg_hi:[0,1]
	v_pk_mul_f32 v[62:63], v[24:25], s[70:71] op_sel_hi:[1,0]
	s_nop 0
	v_pk_fma_f32 v[24:25], v[100:101], s[70:71], v[62:63] op_sel_hi:[1,0,1] neg_lo:[0,0,1] neg_hi:[0,0,1]
	v_xor_b32_e32 v100, 0x80000000, v21
	v_pk_add_f32 v[62:63], v[68:69], v[24:25]
	v_pk_add_f32 v[24:25], v[68:69], v[24:25] neg_lo:[0,1] neg_hi:[0,1]
	v_pk_add_f32 v[68:69], v[80:81], v[96:97]
	v_pk_add_f32 v[80:81], v[80:81], v[96:97] neg_lo:[0,1] neg_hi:[0,1]
	v_pk_mul_f32 v[96:97], v[66:67], s[70:71] op_sel:[1,0] op_sel_hi:[0,0] neg_lo:[1,0]
	v_mov_b32_e32 v101, v20
	v_pk_fma_f32 v[66:67], v[66:67], s[70:71], v[96:97] op_sel_hi:[1,0,1]
	s_nop 0
	v_pk_add_f32 v[96:97], v[70:71], v[66:67]
	v_pk_add_f32 v[66:67], v[70:71], v[66:67] neg_lo:[0,1] neg_hi:[0,1]
	v_xor_b32_e32 v70, 0x80000000, v89
	v_mov_b32_e32 v71, v88
	v_pk_add_f32 v[88:89], v[90:91], v[70:71]
	v_pk_add_f32 v[70:71], v[90:91], v[70:71] neg_lo:[0,1] neg_hi:[0,1]
	v_pk_mul_f32 v[90:91], v[20:21], s[70:71] op_sel_hi:[1,0]
	s_nop 0
	v_pk_fma_f32 v[20:21], v[100:101], s[70:71], v[90:91] op_sel_hi:[1,0,1] neg_lo:[0,0,1] neg_hi:[0,0,1]
	s_nop 0
	v_pk_add_f32 v[90:91], v[72:73], v[20:21]
	v_pk_add_f32 v[20:21], v[72:73], v[20:21] neg_lo:[0,1] neg_hi:[0,1]
	v_pk_add_f32 v[72:73], v[94:95], v[8:9]
	v_pk_add_f32 v[8:9], v[94:95], v[8:9] neg_lo:[0,1] neg_hi:[0,1]
	v_pk_mul_f32 v[94:95], v[82:83], s[62:63] op_sel:[1,0] op_sel_hi:[0,0] neg_lo:[1,0]
	s_nop 0
	v_pk_fma_f32 v[82:83], v[82:83], s[60:61], v[94:95] op_sel_hi:[1,0,1]
	s_nop 0
	v_pk_add_f32 v[94:95], v[98:99], v[82:83]
	v_pk_add_f32 v[82:83], v[98:99], v[82:83] neg_lo:[0,1] neg_hi:[0,1]
	v_pk_mul_f32 v[98:99], v[86:87], s[70:71] op_sel:[1,0] op_sel_hi:[0,0] neg_lo:[1,0]
	s_nop 0
	v_pk_fma_f32 v[86:87], v[86:87], s[70:71], v[98:99] op_sel_hi:[1,0,1]
	s_nop 0
	v_pk_add_f32 v[98:99], v[76:77], v[86:87]
	v_pk_add_f32 v[86:87], v[76:77], v[86:87] neg_lo:[0,1] neg_hi:[0,1]
	v_pk_mul_f32 v[76:77], v[26:27], s[60:61] op_sel:[1,0] op_sel_hi:[0,0] neg_lo:[1,0]
	s_nop 0
	v_pk_fma_f32 v[26:27], v[26:27], s[62:63], v[76:77] op_sel_hi:[1,0,1]
	v_xor_b32_e32 v76, 0x80000000, v67
	v_pk_add_f32 v[100:101], v[18:19], v[26:27]
	v_pk_add_f32 v[26:27], v[18:19], v[26:27] neg_lo:[0,1] neg_hi:[0,1]
	v_pk_add_f32 v[102:103], v[74:75], v[78:79] op_sel:[0,1] op_sel_hi:[1,0] neg_lo:[0,1]
	v_pk_add_f32 v[104:105], v[74:75], v[78:79] op_sel:[0,1] op_sel_hi:[1,0] neg_hi:[0,1]
	v_pk_mul_f32 v[18:19], v[6:7], s[62:63] op_sel_hi:[1,0]
	v_xor_b32_e32 v74, 0x80000000, v7
	v_mov_b32_e32 v75, v6
	v_pk_fma_f32 v[6:7], v[74:75], s[60:61], v[18:19] op_sel_hi:[1,0,1] neg_lo:[0,0,1] neg_hi:[0,0,1]
	v_xor_b32_e32 v74, 0x80000000, v15
	v_pk_add_f32 v[18:19], v[10:11], v[6:7]
	v_pk_add_f32 v[6:7], v[10:11], v[6:7] neg_lo:[0,1] neg_hi:[0,1]
	v_pk_mul_f32 v[10:11], v[14:15], s[70:71] op_sel_hi:[1,0]
	v_mov_b32_e32 v75, v14
	v_pk_fma_f32 v[10:11], v[74:75], s[70:71], v[10:11] op_sel_hi:[1,0,1] neg_lo:[0,0,1] neg_hi:[0,0,1]
	v_xor_b32_e32 v74, 0x80000000, v5
	v_pk_add_f32 v[14:15], v[16:17], v[10:11]
	v_pk_add_f32 v[10:11], v[16:17], v[10:11] neg_lo:[0,1] neg_hi:[0,1]
	v_pk_mul_f32 v[16:17], v[4:5], s[60:61] op_sel_hi:[1,0]
	v_mov_b32_e32 v75, v4
	v_pk_fma_f32 v[4:5], v[74:75], s[62:63], v[16:17] op_sel_hi:[1,0,1] neg_lo:[0,0,1] neg_hi:[0,0,1]
	v_xor_b32_e32 v74, 0x80000000, v89
	v_pk_add_f32 v[16:17], v[0:1], v[4:5]
	v_pk_add_f32 v[106:107], v[0:1], v[4:5] neg_lo:[0,1] neg_hi:[0,1]
	v_pk_add_f32 v[0:1], v[12:13], v[68:69]
	v_pk_add_f32 v[4:5], v[12:13], v[68:69] neg_lo:[0,1] neg_hi:[0,1]
	v_mov_b32_e32 v75, v88
	v_pk_mul_f32 v[12:13], v[96:97], s[62:63] op_sel:[1,0] op_sel_hi:[0,0] neg_lo:[1,0]
	v_pk_mul_f32 v[74:75], v[74:75], s[70:71] op_sel_hi:[1,0]
	v_pk_fma_f32 v[12:13], v[96:97], s[60:61], v[12:13] op_sel_hi:[1,0,1]
	v_pk_fma_f32 v[74:75], v[88:89], s[70:71], v[74:75] op_sel_hi:[1,0,1]
	v_pk_add_f32 v[68:69], v[92:93], v[12:13]
	v_pk_add_f32 v[12:13], v[92:93], v[12:13] neg_lo:[0,1] neg_hi:[0,1]
	v_pk_add_f32 v[88:89], v[64:65], v[74:75]
	v_pk_add_f32 v[92:93], v[64:65], v[74:75] neg_lo:[0,1] neg_hi:[0,1]
	v_pk_mul_f32 v[64:65], v[90:91], s[60:61] op_sel:[1,0] op_sel_hi:[0,0] neg_lo:[1,0]
	v_pk_add_f32 v[78:79], v[72:73], v[0:1]
	v_pk_fma_f32 v[64:65], v[90:91], s[62:63], v[64:65] op_sel_hi:[1,0,1]
	s_nop 0
	v_pk_add_f32 v[74:75], v[62:63], v[64:65]
	v_pk_add_f32 v[90:91], v[62:63], v[64:65] neg_lo:[0,1] neg_hi:[0,1]
	v_pk_mul_f32 v[0:1], v[68:69], s[58:59] op_sel:[1,0] op_sel_hi:[0,0] neg_lo:[1,0]
	v_pk_add_f32 v[64:65], v[84:85], v[80:81] op_sel:[0,1] op_sel_hi:[1,0] neg_lo:[0,1]
	v_pk_add_f32 v[80:81], v[84:85], v[80:81] op_sel:[0,1] op_sel_hi:[1,0] neg_hi:[0,1]
	v_pk_mul_f32 v[62:63], v[66:67], s[62:63] op_sel_hi:[1,0]
	v_mov_b32_e32 v77, v66
	v_pk_fma_f32 v[0:1], v[68:69], s[46:47], v[0:1] op_sel_hi:[1,0,1]
	v_pk_fma_f32 v[62:63], v[76:77], s[60:61], v[62:63] op_sel_hi:[1,0,1] neg_lo:[0,0,1] neg_hi:[0,0,1]
	v_pk_add_f32 v[76:77], v[94:95], v[0:1]
	v_pk_mul_f32 v[0:1], v[88:89], s[62:63] op_sel:[1,0] op_sel_hi:[0,0] neg_lo:[1,0]
	v_pk_add_f32 v[84:85], v[2:3], v[62:63]
	v_pk_fma_f32 v[0:1], v[88:89], s[60:61], v[0:1] op_sel_hi:[1,0,1]
	v_pk_add_f32 v[2:3], v[2:3], v[62:63] neg_lo:[0,1] neg_hi:[0,1]
	v_pk_add_f32 v[72:73], v[98:99], v[0:1]
	v_pk_mul_f32 v[0:1], v[74:75], s[66:67] op_sel:[1,0] op_sel_hi:[0,0] neg_lo:[1,0]
	v_pk_mul_f32 v[62:63], v[70:71], s[70:71] op_sel_hi:[1,0]
	v_pk_fma_f32 v[0:1], v[74:75], s[64:65], v[0:1] op_sel_hi:[1,0,1]
	v_xor_b32_e32 v66, 0x80000000, v71
	v_pk_add_f32 v[74:75], v[100:101], v[0:1]
	v_pk_mul_f32 v[0:1], v[64:65], s[70:71] op_sel:[1,0] op_sel_hi:[0,0] neg_lo:[1,0]
	v_mov_b32_e32 v67, v70
	v_pk_fma_f32 v[0:1], v[64:65], s[70:71], v[0:1] op_sel_hi:[1,0,1]
	v_pk_fma_f32 v[62:63], v[66:67], s[70:71], v[62:63] op_sel_hi:[1,0,1] neg_lo:[0,0,1] neg_hi:[0,0,1]
	v_pk_add_f32 v[66:67], v[102:103], v[0:1]
	v_pk_mul_f32 v[0:1], v[84:85], s[64:65] op_sel:[1,0] op_sel_hi:[0,0] neg_lo:[1,0]
	v_pk_add_f32 v[70:71], v[22:23], v[62:63]
	v_pk_fma_f32 v[0:1], v[84:85], s[66:67], v[0:1] op_sel_hi:[1,0,1]
	v_pk_add_f32 v[96:97], v[22:23], v[62:63] neg_lo:[0,1] neg_hi:[0,1]
	v_pk_mul_f32 v[22:23], v[20:21], s[60:61] op_sel_hi:[1,0]
	v_pk_add_f32 v[68:69], v[18:19], v[0:1]
	v_pk_fma_f32 v[20:21], v[20:21], s[62:63], v[22:23] op_sel:[1,0,0] op_sel_hi:[0,0,1] neg_lo:[1,0,1] neg_hi:[0,0,1]
	v_pk_mul_f32 v[0:1], v[70:71], s[60:61] op_sel:[1,0] op_sel_hi:[0,0] neg_lo:[1,0]
	v_pk_add_f32 v[22:23], v[24:25], v[20:21]
	v_pk_fma_f32 v[0:1], v[70:71], s[62:63], v[0:1] op_sel_hi:[1,0,1]
	v_pk_add_f32 v[108:109], v[24:25], v[20:21] neg_lo:[0,1] neg_hi:[0,1]
	v_pk_add_f32 v[62:63], v[14:15], v[0:1]
	v_pk_mul_f32 v[0:1], v[22:23], s[46:47] op_sel:[1,0] op_sel_hi:[0,0] neg_lo:[1,0]
	s_nop 0
	v_pk_fma_f32 v[0:1], v[22:23], s[58:59], v[0:1] op_sel_hi:[1,0,1]
	s_nop 0
	v_pk_add_f32 v[64:65], v[16:17], v[0:1]
	v_pk_add_f32 v[22:23], v[8:9], v[4:5] op_sel:[0,1] op_sel_hi:[1,0] neg_lo:[0,1]
	v_pk_mul_f32 v[0:1], v[12:13], s[58:59] op_sel_hi:[1,0]
	v_xor_b32_e32 v4, 0x80000000, v13
	v_mov_b32_e32 v5, v12
	v_pk_fma_f32 v[0:1], v[4:5], s[46:47], v[0:1] op_sel_hi:[1,0,1] neg_lo:[0,0,1] neg_hi:[0,0,1]
	v_xor_b32_e32 v4, 0x80000000, v93
	v_pk_add_f32 v[24:25], v[82:83], v[0:1]
	v_pk_mul_f32 v[0:1], v[92:93], s[62:63] op_sel_hi:[1,0]
	v_mov_b32_e32 v5, v92
	v_pk_fma_f32 v[0:1], v[4:5], s[60:61], v[0:1] op_sel_hi:[1,0,1] neg_lo:[0,0,1] neg_hi:[0,0,1]
	v_xor_b32_e32 v4, 0x80000000, v91
	v_pk_add_f32 v[18:19], v[86:87], v[0:1]
	v_pk_mul_f32 v[0:1], v[90:91], s[66:67] op_sel_hi:[1,0]
	v_mov_b32_e32 v5, v90
	v_pk_fma_f32 v[0:1], v[4:5], s[64:65], v[0:1] op_sel_hi:[1,0,1] neg_lo:[0,0,1] neg_hi:[0,0,1]
	s_nop 0
	v_pk_add_f32 v[20:21], v[26:27], v[0:1]
	v_pk_mul_f32 v[0:1], v[80:81], s[70:71] op_sel_hi:[1,0]
	s_nop 0
	v_pk_fma_f32 v[0:1], v[80:81], s[70:71], v[0:1] op_sel:[1,0,0] op_sel_hi:[0,0,1] neg_lo:[1,0,1] neg_hi:[0,0,1]
	v_xor_b32_e32 v8, 0x80000000, v3
	v_pk_add_f32 v[4:5], v[104:105], v[0:1]
	v_pk_mul_f32 v[0:1], v[2:3], s[64:65] op_sel_hi:[1,0]
	v_mov_b32_e32 v9, v2
	v_pk_fma_f32 v[0:1], v[8:9], s[66:67], v[0:1] op_sel_hi:[1,0,1] neg_lo:[0,0,1] neg_hi:[0,0,1]
	s_nop 0
	v_pk_add_f32 v[6:7], v[6:7], v[0:1]
	v_pk_mul_f32 v[0:1], v[96:97], s[60:61] op_sel_hi:[1,0]
	s_nop 0
	v_pk_fma_f32 v[0:1], v[96:97], s[62:63], v[0:1] op_sel:[1,0,0] op_sel_hi:[0,0,1] neg_lo:[1,0,1] neg_hi:[0,0,1]
	v_pk_mul_f32 v[2:3], v[108:109], s[46:47] op_sel_hi:[1,0]
	v_pk_add_f32 v[0:1], v[10:11], v[0:1]
	v_xor_b32_e32 v8, 0x80000000, v109
	v_mov_b32_e32 v9, v108
	v_mov_b32_e32 v10, v146
	v_pk_fma_f32 v[2:3], v[8:9], s[58:59], v[2:3] op_sel_hi:[1,0,1] neg_lo:[0,0,1] neg_hi:[0,0,1]
	global_load_dword v8, v145, s[0:1]
	s_movk_i32 s0, 0x200
	s_cselect_b32 s4, s0, 0x400
	s_add_i32 s0, s4, s68
	s_ashr_i32 s1, s0, 31
	s_lshl_b32 s6, s4, 2
	s_add_u32 s4, s90, s6
	s_addc_u32 s5, s91, 0
	s_lshl_b64 s[0:1], s[0:1], 14
	v_min_i32_e32 v70, 0x1ffe, v10
	v_mov_b32_e32 v9, s6
	s_add_u32 s36, s26, s0
	v_ashrrev_i32_e32 v11, 31, v10
	v_ashrrev_i32_e32 v71, 31, v70
	global_load_dword v16, v9, s[90:91]
	global_load_dword v14, v153, s[4:5] offset:2048
	global_load_dword v17, v154, s[4:5]
	global_load_dword v12, v9, s[94:95]
	s_addc_u32 s37, s27, s1
	v_max_i32_e32 v9, 1, v10
	v_lshlrev_b64 v[82:83], 1, v[10:11]
	v_lshlrev_b64 v[84:85], 1, v[70:71]
	v_lshl_add_u64 v[26:27], s[36:37], 0, v[82:83]
	v_lshlrev_b32_e32 v9, 1, v9
	v_lshl_add_u64 v[70:71], s[36:37], 0, v[84:85]
	global_load_ushort v13, v[26:27], off
	s_add_u32 s88, s30, s0
	global_load_ushort v70, v[70:71], off offset:2
	s_addc_u32 s89, s31, s1
	global_load_ushort v15, v9, s[36:37] offset:-2
	v_cmp_lt_i32_e64 s[0:1], 0, v10
	v_cmp_gt_i32_e64 s[4:5], s74, v10
	v_pk_add_f32 v[2:3], v[106:107], v[2:3]
	v_cndmask_b32_e64 v81, 0, 1.0, s[0:1]
	v_cndmask_b32_e64 v86, 0, 1.0, s[4:5]
	v_add_u32_e32 v92, 0x200, v10
	v_cmp_lt_i32_e64 s[20:21], s25, v10
	v_cmp_gt_i32_e64 s[18:19], s42, v10
	v_add_u32_e32 v90, 0x400, v10
	v_cmp_lt_i32_e64 s[16:17], s33, v10
	v_cmp_gt_i32_e64 s[0:1], s51, v10
	v_add_u32_e32 v88, 0x600, v10
	v_cmp_lt_i32_e64 s[12:13], s43, v10
	v_cmp_gt_i32_e64 s[10:11], s50, v10
	v_cmp_lt_i32_e64 s[8:9], s2, v10
	v_cmp_gt_i32_e64 s[6:7], s38, v10
	v_cmp_lt_i32_e64 s[4:5], s65, v10
	v_cmp_gt_i32_e64 s[22:23], s34, v10
	s_waitcnt vmcnt(2)
	v_lshlrev_b32_e32 v13, 16, v13
	s_waitcnt vmcnt(1)
	v_lshlrev_b32_e32 v70, 16, v70
	v_mul_f32_e32 v70, v86, v70
	s_waitcnt vmcnt(0)
	v_lshlrev_b32_e32 v15, 16, v15
	v_mul_f32_e32 v15, v81, v15
	v_mul_f32_e32 v15, v16, v15
	v_fmac_f32_e32 v15, v14, v13
	v_fmac_f32_e32 v15, v17, v70
	v_lshl_add_u64 v[70:71], s[88:89], 0, v[82:83]
	v_lshl_add_u64 v[82:83], s[88:89], 0, v[84:85]
	v_add_f32_e32 v80, v12, v15
	global_load_ushort v13, v[70:71], off
	global_load_ushort v15, v[82:83], off offset:2
	v_add_u32_e32 v84, 0x800, v10
	global_load_ushort v9, v9, s[88:89] offset:-2
	v_add_u32_e32 v82, 0xa00, v10
	s_waitcnt vmcnt(2)
	v_lshlrev_b32_e32 v13, 16, v13
	s_waitcnt vmcnt(1)
	v_lshlrev_b32_e32 v15, 16, v15
	v_mul_f32_e32 v15, v86, v15
	s_waitcnt vmcnt(0)
	v_lshlrev_b32_e32 v9, 16, v9
	v_mul_f32_e32 v9, v81, v9
	v_mul_f32_e32 v9, v16, v9
	v_fmac_f32_e32 v9, v14, v13
	v_fmac_f32_e32 v9, v17, v15
	v_add_f32_e32 v86, v12, v9
	s_cbranch_vccnz .LBB0_540
	v_readlane_b32 s98, v252, 56
	s_lshl_b64 s[0:1], s[92:93], 1
	s_add_u32 s4, s0, s30
	s_addc_u32 s5, s1, s31
	s_add_u32 s0, s0, s26
	s_addc_u32 s1, s1, s27
	s_add_u32 s18, s96, 0x800000
	s_addc_u32 s19, s97, 0
	s_cmpk_gt_i32 s98, 0xff
	s_cbranch_scc1 .Lhy_ep1_comb_L0
	v_lshlrev_b32_e32 v109, 1, v10
	global_load_ushort v9, v109, s[0:1]
	global_load_ushort v11, v109, s[4:5]
	global_load_ushort v13, v109, s[36:37] offset:1022
	global_load_ushort v15, v109, s[36:37] offset:1024
	global_load_ushort v81, v109, s[36:37] offset:1026
	global_load_ushort v83, v109, s[88:89] offset:1022
	global_load_ushort v85, v109, s[88:89] offset:1024
	global_load_ushort v87, v109, s[88:89] offset:1026
	global_load_ushort v89, v109, s[0:1] offset:1024
	global_load_ushort v91, v109, s[4:5] offset:1024
	global_load_ushort v93, v109, s[36:37] offset:2046
	global_load_ushort v94, v109, s[36:37] offset:2048
	global_load_ushort v95, v109, s[36:37] offset:2050
	global_load_ushort v96, v109, s[88:89] offset:2046
	global_load_ushort v97, v109, s[88:89] offset:2048
	global_load_ushort v98, v109, s[88:89] offset:2050
	global_load_ushort v99, v109, s[0:1] offset:2048
	global_load_ushort v100, v109, s[4:5] offset:2048
	global_load_ushort v101, v109, s[36:37] offset:3070
	global_load_ushort v102, v109, s[36:37] offset:3072
	global_load_ushort v103, v109, s[36:37] offset:3074
	global_load_ushort v104, v109, s[88:89] offset:3070
	global_load_ushort v105, v109, s[88:89] offset:3072
	global_load_ushort v106, v109, s[88:89] offset:3074
	global_load_ushort v107, v109, s[0:1] offset:3072
	global_load_ushort v108, v109, s[4:5] offset:3072
	s_waitcnt vmcnt(0)
	v_fma_f32 v27, v32, v8, v78
	v_mul_f32_e32 v70, v80, v27
	v_lshlrev_b32_e32 v9, 16, v9
	v_mul_f32_e32 v84, 0xbfb8aa3b, v9
	v_exp_f32_e32 v84, v84
	s_nop 0
	v_add_f32_e32 v84, 1.0, v84
	v_div_scale_f32 v71, s[28:29], v84, v84, v9
	v_rcp_f32_e32 v82, v71
	s_nop 0
	v_fma_f32 v92, -v71, v82, 1.0
	v_fmac_f32_e32 v82, v92, v82
	v_div_scale_f32 v88, vcc, v9, v84, v9
	v_mul_f32_e32 v90, v88, v82
	v_fma_f32 v92, -v71, v90, v88
	v_fmac_f32_e32 v90, v92, v82
	v_fma_f32 v71, -v71, v90, v88
	v_div_fmas_f32 v71, v71, v82, v90
	v_div_fixup_f32 v9, v71, v84, v9
	v_mul_f32_e32 v70, v70, v9
	v_fma_f32 v27, v34, v8, v79
	v_mul_f32_e32 v110, v86, v27
	v_lshlrev_b32_e32 v11, 16, v11
	v_mul_f32_e32 v84, 0xbfb8aa3b, v11
	v_exp_f32_e32 v84, v84
	s_nop 0
	v_add_f32_e32 v84, 1.0, v84
	v_div_scale_f32 v71, s[28:29], v84, v84, v11
	v_rcp_f32_e32 v82, v71
	s_nop 0
	v_fma_f32 v92, -v71, v82, 1.0
	v_fmac_f32_e32 v82, v92, v82
	v_div_scale_f32 v88, vcc, v11, v84, v11
	v_mul_f32_e32 v90, v88, v82
	v_fma_f32 v92, -v71, v90, v88
	v_fmac_f32_e32 v90, v92, v82
	v_fma_f32 v71, -v71, v90, v88
	v_div_fmas_f32 v71, v71, v82, v90
	v_div_fixup_f32 v11, v71, v84, v11
	v_mul_f32_e32 v110, v110, v11
	v_cvt_pk_bf16_f32 v198, v70, v110
	v_lshlrev_b32_e32 v15, 16, v15
	v_lshlrev_b32_e32 v81, 16, v81
	v_lshlrev_b32_e32 v13, 16, v13
	v_mul_f32_e32 v13, v16, v13
	v_fmac_f32_e32 v13, v14, v15
	v_fmac_f32_e32 v13, v17, v81
	v_add_f32_e32 v13, v12, v13
	v_fma_f32 v27, v33, v8, v76
	v_mul_f32_e32 v70, v27, v13
	v_lshlrev_b32_e32 v89, 16, v89
	v_mul_f32_e32 v84, 0xbfb8aa3b, v89
	v_exp_f32_e32 v84, v84
	s_nop 0
	v_add_f32_e32 v84, 1.0, v84
	v_div_scale_f32 v71, s[28:29], v84, v84, v89
	v_rcp_f32_e32 v82, v71
	s_nop 0
	v_fma_f32 v92, -v71, v82, 1.0
	v_fmac_f32_e32 v82, v92, v82
	v_div_scale_f32 v88, vcc, v89, v84, v89
	v_mul_f32_e32 v90, v88, v82
	v_fma_f32 v92, -v71, v90, v88
	v_fmac_f32_e32 v90, v92, v82
	v_fma_f32 v71, -v71, v90, v88
	v_div_fmas_f32 v71, v71, v82, v90
	v_div_fixup_f32 v89, v71, v84, v89
	v_mul_f32_e32 v70, v70, v89
	v_lshlrev_b32_e32 v85, 16, v85
	v_lshlrev_b32_e32 v87, 16, v87
	v_lshlrev_b32_e32 v83, 16, v83
	v_mul_f32_e32 v83, v16, v83
	v_fmac_f32_e32 v83, v14, v85
	v_fmac_f32_e32 v83, v17, v87
	v_add_f32_e32 v83, v12, v83
	v_fma_f32 v27, v35, v8, v77
	v_mul_f32_e32 v110, v27, v83
	v_lshlrev_b32_e32 v91, 16, v91
	v_mul_f32_e32 v84, 0xbfb8aa3b, v91
	v_exp_f32_e32 v84, v84
	s_nop 0
	v_add_f32_e32 v84, 1.0, v84
	v_div_scale_f32 v71, s[28:29], v84, v84, v91
	v_rcp_f32_e32 v82, v71
	s_nop 0
	v_fma_f32 v92, -v71, v82, 1.0
	v_fmac_f32_e32 v82, v92, v82
	v_div_scale_f32 v88, vcc, v91, v84, v91
	v_mul_f32_e32 v90, v88, v82
	v_fma_f32 v92, -v71, v90, v88
	v_fmac_f32_e32 v90, v92, v82
	v_fma_f32 v71, -v71, v90, v88
	v_div_fmas_f32 v71, v71, v82, v90
	v_div_fixup_f32 v91, v71, v84, v91
	v_mul_f32_e32 v110, v110, v91
	v_cvt_pk_bf16_f32 v199, v70, v110
	v_lshlrev_b32_e32 v94, 16, v94
	v_lshlrev_b32_e32 v95, 16, v95
	v_lshlrev_b32_e32 v93, 16, v93
	v_mul_f32_e32 v93, v16, v93
	v_fmac_f32_e32 v93, v14, v94
	v_fmac_f32_e32 v93, v17, v95
	v_add_f32_e32 v93, v12, v93
	v_fma_f32 v27, v37, v8, v72
	v_mul_f32_e32 v70, v27, v93
	v_lshlrev_b32_e32 v99, 16, v99
	v_mul_f32_e32 v84, 0xbfb8aa3b, v99
	v_exp_f32_e32 v84, v84
	s_nop 0
	v_add_f32_e32 v84, 1.0, v84
	v_div_scale_f32 v71, s[28:29], v84, v84, v99
	v_rcp_f32_e32 v82, v71
	s_nop 0
	v_fma_f32 v92, -v71, v82, 1.0
	v_fmac_f32_e32 v82, v92, v82
	v_div_scale_f32 v88, vcc, v99, v84, v99
	v_mul_f32_e32 v90, v88, v82
	v_fma_f32 v92, -v71, v90, v88
	v_fmac_f32_e32 v90, v92, v82
	v_fma_f32 v71, -v71, v90, v88
	v_div_fmas_f32 v71, v71, v82, v90
	v_div_fixup_f32 v99, v71, v84, v99
	v_mul_f32_e32 v70, v70, v99
	v_lshlrev_b32_e32 v97, 16, v97
	v_lshlrev_b32_e32 v98, 16, v98
	v_lshlrev_b32_e32 v96, 16, v96
	v_mul_f32_e32 v96, v16, v96
	v_fmac_f32_e32 v96, v14, v97
	v_fmac_f32_e32 v96, v17, v98
	v_add_f32_e32 v96, v12, v96
	v_fma_f32 v27, v31, v8, v73
	v_mul_f32_e32 v110, v27, v96
	v_lshlrev_b32_e32 v100, 16, v100
	v_mul_f32_e32 v84, 0xbfb8aa3b, v100
	v_exp_f32_e32 v84, v84
	s_nop 0
	v_add_f32_e32 v84, 1.0, v84
	v_div_scale_f32 v71, s[28:29], v84, v84, v100
	v_rcp_f32_e32 v82, v71
	s_nop 0
	v_fma_f32 v92, -v71, v82, 1.0
	v_fmac_f32_e32 v82, v92, v82
	v_div_scale_f32 v88, vcc, v100, v84, v100
	v_mul_f32_e32 v90, v88, v82
	v_fma_f32 v92, -v71, v90, v88
	v_fmac_f32_e32 v90, v92, v82
	v_fma_f32 v71, -v71, v90, v88
	v_div_fmas_f32 v71, v71, v82, v90
	v_div_fixup_f32 v100, v71, v84, v100
	v_mul_f32_e32 v110, v110, v100
	v_cvt_pk_bf16_f32 v200, v70, v110
	v_lshlrev_b32_e32 v102, 16, v102
	v_lshlrev_b32_e32 v103, 16, v103
	v_lshlrev_b32_e32 v101, 16, v101
	v_mul_f32_e32 v101, v16, v101
	v_fmac_f32_e32 v101, v14, v102
	v_fmac_f32_e32 v101, v17, v103
	v_add_f32_e32 v101, v12, v101
	v_fma_f32 v27, v36, v8, v74
	v_mul_f32_e32 v70, v27, v101
	v_lshlrev_b32_e32 v107, 16, v107
	v_mul_f32_e32 v84, 0xbfb8aa3b, v107
	v_exp_f32_e32 v84, v84
	s_nop 0
	v_add_f32_e32 v84, 1.0, v84
	v_div_scale_f32 v71, s[28:29], v84, v84, v107
	v_rcp_f32_e32 v82, v71
	s_nop 0
	v_fma_f32 v92, -v71, v82, 1.0
	v_fmac_f32_e32 v82, v92, v82
	v_div_scale_f32 v88, vcc, v107, v84, v107
	v_mul_f32_e32 v90, v88, v82
	v_fma_f32 v92, -v71, v90, v88
	v_fmac_f32_e32 v90, v92, v82
	v_fma_f32 v71, -v71, v90, v88
	v_div_fmas_f32 v71, v71, v82, v90
	v_div_fixup_f32 v107, v71, v84, v107
	v_mul_f32_e32 v70, v70, v107
	v_lshlrev_b32_e32 v105, 16, v105
	v_lshlrev_b32_e32 v106, 16, v106
	v_lshlrev_b32_e32 v104, 16, v104
	v_mul_f32_e32 v104, v16, v104
	v_fmac_f32_e32 v104, v14, v105
	v_fmac_f32_e32 v104, v17, v106
	v_add_f32_e32 v104, v12, v104
	v_fma_f32 v27, v30, v8, v75
	v_mul_f32_e32 v110, v27, v104
	v_lshlrev_b32_e32 v108, 16, v108
	v_mul_f32_e32 v84, 0xbfb8aa3b, v108
	v_exp_f32_e32 v84, v84
	s_nop 0
	v_add_f32_e32 v84, 1.0, v84
	v_div_scale_f32 v71, s[28:29], v84, v84, v108
	v_rcp_f32_e32 v82, v71
	s_nop 0
	v_fma_f32 v92, -v71, v82, 1.0
	v_fmac_f32_e32 v82, v92, v82
	v_div_scale_f32 v88, vcc, v108, v84, v108
	v_mul_f32_e32 v90, v88, v82
	v_fma_f32 v92, -v71, v90, v88
	v_fmac_f32_e32 v90, v92, v82
	v_fma_f32 v71, -v71, v90, v88
	v_div_fmas_f32 v71, v71, v82, v90
	v_div_fixup_f32 v108, v71, v84, v108
	v_mul_f32_e32 v110, v110, v108
	v_cvt_pk_bf16_f32 v201, v70, v110
	v_add_u32_e32 v109, 0x1000, v109
	global_load_ushort v9, v109, s[36:37] offset:-2
	global_load_ushort v11, v109, s[36:37]
	global_load_ushort v13, v109, s[36:37] offset:2
	global_load_ushort v15, v109, s[88:89] offset:-2
	global_load_ushort v81, v109, s[88:89]
	global_load_ushort v83, v109, s[88:89] offset:2
	global_load_ushort v85, v109, s[0:1]
	global_load_ushort v87, v109, s[4:5]
	global_load_ushort v89, v109, s[36:37] offset:1022
	global_load_ushort v91, v109, s[36:37] offset:1024
	global_load_ushort v93, v109, s[36:37] offset:1026
	global_load_ushort v94, v109, s[88:89] offset:1022
	global_load_ushort v95, v109, s[88:89] offset:1024
	global_load_ushort v96, v109, s[88:89] offset:1026
	global_load_ushort v97, v109, s[0:1] offset:1024
	global_load_ushort v98, v109, s[4:5] offset:1024
	global_load_ushort v99, v109, s[36:37] offset:2046
	global_load_ushort v100, v109, s[36:37] offset:2048
	global_load_ushort v101, v109, s[36:37] offset:2050
	global_load_ushort v102, v109, s[88:89] offset:2046
	global_load_ushort v103, v109, s[88:89] offset:2048
	global_load_ushort v104, v109, s[88:89] offset:2050
	global_load_ushort v105, v109, s[0:1] offset:2048
	global_load_ushort v106, v109, s[4:5] offset:2048
	global_load_ushort v107, v109, s[36:37] offset:3070
	global_load_ushort v108, v109, s[36:37] offset:3072
	global_load_ushort v32, v109, s[36:37] offset:3074
	global_load_ushort v78, v109, s[88:89] offset:3070
	global_load_ushort v34, v109, s[88:89] offset:3072
	global_load_ushort v79, v109, s[88:89] offset:3074
	global_load_ushort v33, v109, s[0:1] offset:3072
	global_load_ushort v76, v109, s[4:5] offset:3072
	s_waitcnt vmcnt(0)
	v_lshlrev_b32_e32 v11, 16, v11
	v_lshlrev_b32_e32 v13, 16, v13
	v_lshlrev_b32_e32 v9, 16, v9
	v_mul_f32_e32 v9, v16, v9
	v_fmac_f32_e32 v9, v14, v11
	v_fmac_f32_e32 v9, v17, v13
	v_add_f32_e32 v9, v12, v9
	v_fma_f32 v27, v39, v8, v66
	v_mul_f32_e32 v70, v27, v9
	v_lshlrev_b32_e32 v85, 16, v85
	v_mul_f32_e32 v84, 0xbfb8aa3b, v85
	v_exp_f32_e32 v84, v84
	s_nop 0
	v_add_f32_e32 v84, 1.0, v84
	v_div_scale_f32 v71, s[28:29], v84, v84, v85
	v_rcp_f32_e32 v82, v71
	s_nop 0
	v_fma_f32 v92, -v71, v82, 1.0
	v_fmac_f32_e32 v82, v92, v82
	v_div_scale_f32 v88, vcc, v85, v84, v85
	v_mul_f32_e32 v90, v88, v82
	v_fma_f32 v92, -v71, v90, v88
	v_fmac_f32_e32 v90, v92, v82
	v_fma_f32 v71, -v71, v90, v88
	v_div_fmas_f32 v71, v71, v82, v90
	v_div_fixup_f32 v85, v71, v84, v85
	v_mul_f32_e32 v70, v70, v85
	v_lshlrev_b32_e32 v81, 16, v81
	v_lshlrev_b32_e32 v83, 16, v83
	v_lshlrev_b32_e32 v15, 16, v15
	v_mul_f32_e32 v15, v16, v15
	v_fmac_f32_e32 v15, v14, v81
	v_fmac_f32_e32 v15, v17, v83
	v_add_f32_e32 v15, v12, v15
	v_fma_f32 v27, v41, v8, v67
	v_mul_f32_e32 v110, v27, v15
	v_lshlrev_b32_e32 v87, 16, v87
	v_mul_f32_e32 v84, 0xbfb8aa3b, v87
	v_exp_f32_e32 v84, v84
	s_nop 0
	v_add_f32_e32 v84, 1.0, v84
	v_div_scale_f32 v71, s[28:29], v84, v84, v87
	v_rcp_f32_e32 v82, v71
	s_nop 0
	v_fma_f32 v92, -v71, v82, 1.0
	v_fmac_f32_e32 v82, v92, v82
	v_div_scale_f32 v88, vcc, v87, v84, v87
	v_mul_f32_e32 v90, v88, v82
	v_fma_f32 v92, -v71, v90, v88
	v_fmac_f32_e32 v90, v92, v82
	v_fma_f32 v71, -v71, v90, v88
	v_div_fmas_f32 v71, v71, v82, v90
	v_div_fixup_f32 v87, v71, v84, v87
	v_mul_f32_e32 v110, v110, v87
	v_cvt_pk_bf16_f32 v202, v70, v110
	v_lshlrev_b32_e32 v91, 16, v91
	v_lshlrev_b32_e32 v93, 16, v93
	v_lshlrev_b32_e32 v89, 16, v89
	v_mul_f32_e32 v89, v16, v89
	v_fmac_f32_e32 v89, v14, v91
	v_fmac_f32_e32 v89, v17, v93
	v_add_f32_e32 v89, v12, v89
	v_fma_f32 v27, v38, v8, v68
	v_mul_f32_e32 v70, v27, v89
	v_lshlrev_b32_e32 v97, 16, v97
	v_mul_f32_e32 v84, 0xbfb8aa3b, v97
	v_exp_f32_e32 v84, v84
	s_nop 0
	v_add_f32_e32 v84, 1.0, v84
	v_div_scale_f32 v71, s[28:29], v84, v84, v97
	v_rcp_f32_e32 v82, v71
	s_nop 0
	v_fma_f32 v92, -v71, v82, 1.0
	v_fmac_f32_e32 v82, v92, v82
	v_div_scale_f32 v88, vcc, v97, v84, v97
	v_mul_f32_e32 v90, v88, v82
	v_fma_f32 v92, -v71, v90, v88
	v_fmac_f32_e32 v90, v92, v82
	v_fma_f32 v71, -v71, v90, v88
	v_div_fmas_f32 v71, v71, v82, v90
	v_div_fixup_f32 v97, v71, v84, v97
	v_mul_f32_e32 v70, v70, v97
	v_lshlrev_b32_e32 v95, 16, v95
	v_lshlrev_b32_e32 v96, 16, v96
	v_lshlrev_b32_e32 v94, 16, v94
	v_mul_f32_e32 v94, v16, v94
	v_fmac_f32_e32 v94, v14, v95
	v_fmac_f32_e32 v94, v17, v96
	v_add_f32_e32 v94, v12, v94
	v_fma_f32 v27, v40, v8, v69
	v_mul_f32_e32 v110, v27, v94
	v_lshlrev_b32_e32 v98, 16, v98
	v_mul_f32_e32 v84, 0xbfb8aa3b, v98
	v_exp_f32_e32 v84, v84
	s_nop 0
	v_add_f32_e32 v84, 1.0, v84
	v_div_scale_f32 v71, s[28:29], v84, v84, v98
	v_rcp_f32_e32 v82, v71
	s_nop 0
	v_fma_f32 v92, -v71, v82, 1.0
	v_fmac_f32_e32 v82, v92, v82
	v_div_scale_f32 v88, vcc, v98, v84, v98
	v_mul_f32_e32 v90, v88, v82
	v_fma_f32 v92, -v71, v90, v88
	v_fmac_f32_e32 v90, v92, v82
	v_fma_f32 v71, -v71, v90, v88
	v_div_fmas_f32 v71, v71, v82, v90
	v_div_fixup_f32 v98, v71, v84, v98
	v_mul_f32_e32 v110, v110, v98
	v_cvt_pk_bf16_f32 v203, v70, v110
	v_lshlrev_b32_e32 v100, 16, v100
	v_lshlrev_b32_e32 v101, 16, v101
	v_lshlrev_b32_e32 v99, 16, v99
	v_mul_f32_e32 v99, v16, v99
	v_fmac_f32_e32 v99, v14, v100
	v_fmac_f32_e32 v99, v17, v101
	v_add_f32_e32 v99, v12, v99
	v_fma_f32 v27, v43, v8, v62
	v_mul_f32_e32 v70, v27, v99
	v_lshlrev_b32_e32 v105, 16, v105
	v_mul_f32_e32 v84, 0xbfb8aa3b, v105
	v_exp_f32_e32 v84, v84
	s_nop 0
	v_add_f32_e32 v84, 1.0, v84
	v_div_scale_f32 v71, s[28:29], v84, v84, v105
	v_rcp_f32_e32 v82, v71
	s_nop 0
	v_fma_f32 v92, -v71, v82, 1.0
	v_fmac_f32_e32 v82, v92, v82
	v_div_scale_f32 v88, vcc, v105, v84, v105
	v_mul_f32_e32 v90, v88, v82
	v_fma_f32 v92, -v71, v90, v88
	v_fmac_f32_e32 v90, v92, v82
	v_fma_f32 v71, -v71, v90, v88
	v_div_fmas_f32 v71, v71, v82, v90
	v_div_fixup_f32 v105, v71, v84, v105
	v_mul_f32_e32 v70, v70, v105
	v_lshlrev_b32_e32 v103, 16, v103
	v_lshlrev_b32_e32 v104, 16, v104
	v_lshlrev_b32_e32 v102, 16, v102
	v_mul_f32_e32 v102, v16, v102
	v_fmac_f32_e32 v102, v14, v103
	v_fmac_f32_e32 v102, v17, v104
	v_add_f32_e32 v102, v12, v102
	v_fma_f32 v27, v45, v8, v63
	v_mul_f32_e32 v110, v27, v102
	v_lshlrev_b32_e32 v106, 16, v106
	v_mul_f32_e32 v84, 0xbfb8aa3b, v106
	v_exp_f32_e32 v84, v84
	s_nop 0
	v_add_f32_e32 v84, 1.0, v84
	v_div_scale_f32 v71, s[28:29], v84, v84, v106
	v_rcp_f32_e32 v82, v71
	s_nop 0
	v_fma_f32 v92, -v71, v82, 1.0
	v_fmac_f32_e32 v82, v92, v82
	v_div_scale_f32 v88, vcc, v106, v84, v106
	v_mul_f32_e32 v90, v88, v82
	v_fma_f32 v92, -v71, v90, v88
	v_fmac_f32_e32 v90, v92, v82
	v_fma_f32 v71, -v71, v90, v88
	v_div_fmas_f32 v71, v71, v82, v90
	v_div_fixup_f32 v106, v71, v84, v106
	v_mul_f32_e32 v110, v110, v106
	v_cvt_pk_bf16_f32 v204, v70, v110
	v_lshlrev_b32_e32 v108, 16, v108
	v_lshlrev_b32_e32 v32, 16, v32
	v_lshlrev_b32_e32 v107, 16, v107
	v_mul_f32_e32 v107, v16, v107
	v_fmac_f32_e32 v107, v14, v108
	v_fmac_f32_e32 v107, v17, v32
	v_add_f32_e32 v107, v12, v107
	v_fma_f32 v27, v42, v8, v64
	v_mul_f32_e32 v70, v27, v107
	v_lshlrev_b32_e32 v33, 16, v33
	v_mul_f32_e32 v84, 0xbfb8aa3b, v33
	v_exp_f32_e32 v84, v84
	s_nop 0
	v_add_f32_e32 v84, 1.0, v84
	v_div_scale_f32 v71, s[28:29], v84, v84, v33
	v_rcp_f32_e32 v82, v71
	s_nop 0
	v_fma_f32 v92, -v71, v82, 1.0
	v_fmac_f32_e32 v82, v92, v82
	v_div_scale_f32 v88, vcc, v33, v84, v33
	v_mul_f32_e32 v90, v88, v82
	v_fma_f32 v92, -v71, v90, v88
	v_fmac_f32_e32 v90, v92, v82
	v_fma_f32 v71, -v71, v90, v88
	v_div_fmas_f32 v71, v71, v82, v90
	v_div_fixup_f32 v33, v71, v84, v33
	v_mul_f32_e32 v70, v70, v33
	v_lshlrev_b32_e32 v34, 16, v34
	v_lshlrev_b32_e32 v79, 16, v79
	v_lshlrev_b32_e32 v78, 16, v78
	v_mul_f32_e32 v78, v16, v78
	v_fmac_f32_e32 v78, v14, v34
	v_fmac_f32_e32 v78, v17, v79
	v_add_f32_e32 v78, v12, v78
	v_fma_f32 v27, v44, v8, v65
	v_mul_f32_e32 v110, v27, v78
	v_lshlrev_b32_e32 v76, 16, v76
	v_mul_f32_e32 v84, 0xbfb8aa3b, v76
	v_exp_f32_e32 v84, v84
	s_nop 0
	v_add_f32_e32 v84, 1.0, v84
	v_div_scale_f32 v71, s[28:29], v84, v84, v76
	v_rcp_f32_e32 v82, v71
	s_nop 0
	v_fma_f32 v92, -v71, v82, 1.0
	v_fmac_f32_e32 v82, v92, v82
	v_div_scale_f32 v88, vcc, v76, v84, v76
	v_mul_f32_e32 v90, v88, v82
	v_fma_f32 v92, -v71, v90, v88
	v_fmac_f32_e32 v90, v92, v82
	v_fma_f32 v71, -v71, v90, v88
	v_div_fmas_f32 v71, v71, v82, v90
	v_div_fixup_f32 v76, v71, v84, v76
	v_mul_f32_e32 v110, v110, v76
	v_cvt_pk_bf16_f32 v205, v70, v110
	v_add_u32_e32 v109, 0x1000, v109
	global_load_ushort v9, v109, s[36:37] offset:-2
	global_load_ushort v11, v109, s[36:37]
	global_load_ushort v13, v109, s[36:37] offset:2
	global_load_ushort v15, v109, s[88:89] offset:-2
	global_load_ushort v81, v109, s[88:89]
	global_load_ushort v83, v109, s[88:89] offset:2
	global_load_ushort v85, v109, s[0:1]
	global_load_ushort v87, v109, s[4:5]
	global_load_ushort v89, v109, s[36:37] offset:1022
	global_load_ushort v91, v109, s[36:37] offset:1024
	global_load_ushort v93, v109, s[36:37] offset:1026
	global_load_ushort v94, v109, s[88:89] offset:1022
	global_load_ushort v95, v109, s[88:89] offset:1024
	global_load_ushort v96, v109, s[88:89] offset:1026
	global_load_ushort v97, v109, s[0:1] offset:1024
	global_load_ushort v98, v109, s[4:5] offset:1024
	global_load_ushort v99, v109, s[36:37] offset:2046
	global_load_ushort v100, v109, s[36:37] offset:2048
	global_load_ushort v101, v109, s[36:37] offset:2050
	global_load_ushort v102, v109, s[88:89] offset:2046
	global_load_ushort v103, v109, s[88:89] offset:2048
	global_load_ushort v104, v109, s[88:89] offset:2050
	global_load_ushort v105, v109, s[0:1] offset:2048
	global_load_ushort v106, v109, s[4:5] offset:2048
	global_load_ushort v107, v109, s[36:37] offset:3070
	global_load_ushort v108, v109, s[36:37] offset:3072
	global_load_ushort v32, v109, s[36:37] offset:3074
	global_load_ushort v78, v109, s[88:89] offset:3070
	global_load_ushort v34, v109, s[88:89] offset:3072
	global_load_ushort v79, v109, s[88:89] offset:3074
	global_load_ushort v33, v109, s[0:1] offset:3072
	global_load_ushort v76, v109, s[4:5] offset:3072
	s_waitcnt vmcnt(0)
	v_lshlrev_b32_e32 v11, 16, v11
	v_lshlrev_b32_e32 v13, 16, v13
	v_lshlrev_b32_e32 v9, 16, v9
	v_mul_f32_e32 v9, v16, v9
	v_fmac_f32_e32 v9, v14, v11
	v_fmac_f32_e32 v9, v17, v13
	v_add_f32_e32 v9, v12, v9
	v_fma_f32 v27, v47, v8, v22
	v_mul_f32_e32 v70, v27, v9
	v_lshlrev_b32_e32 v85, 16, v85
	v_mul_f32_e32 v84, 0xbfb8aa3b, v85
	v_exp_f32_e32 v84, v84
	s_nop 0
	v_add_f32_e32 v84, 1.0, v84
	v_div_scale_f32 v71, s[28:29], v84, v84, v85
	v_rcp_f32_e32 v82, v71
	s_nop 0
	v_fma_f32 v92, -v71, v82, 1.0
	v_fmac_f32_e32 v82, v92, v82
	v_div_scale_f32 v88, vcc, v85, v84, v85
	v_mul_f32_e32 v90, v88, v82
	v_fma_f32 v92, -v71, v90, v88
	v_fmac_f32_e32 v90, v92, v82
	v_fma_f32 v71, -v71, v90, v88
	v_div_fmas_f32 v71, v71, v82, v90
	v_div_fixup_f32 v85, v71, v84, v85
	v_mul_f32_e32 v70, v70, v85
	v_lshlrev_b32_e32 v81, 16, v81
	v_lshlrev_b32_e32 v83, 16, v83
	v_lshlrev_b32_e32 v15, 16, v15
	v_mul_f32_e32 v15, v16, v15
	v_fmac_f32_e32 v15, v14, v81
	v_fmac_f32_e32 v15, v17, v83
	v_add_f32_e32 v15, v12, v15
	v_fma_f32 v27, v49, v8, v23
	v_mul_f32_e32 v110, v27, v15
	v_lshlrev_b32_e32 v87, 16, v87
	v_mul_f32_e32 v84, 0xbfb8aa3b, v87
	v_exp_f32_e32 v84, v84
	s_nop 0
	v_add_f32_e32 v84, 1.0, v84
	v_div_scale_f32 v71, s[28:29], v84, v84, v87
	v_rcp_f32_e32 v82, v71
	s_nop 0
	v_fma_f32 v92, -v71, v82, 1.0
	v_fmac_f32_e32 v82, v92, v82
	v_div_scale_f32 v88, vcc, v87, v84, v87
	v_mul_f32_e32 v90, v88, v82
	v_fma_f32 v92, -v71, v90, v88
	v_fmac_f32_e32 v90, v92, v82
	v_fma_f32 v71, -v71, v90, v88
	v_div_fmas_f32 v71, v71, v82, v90
	v_div_fixup_f32 v87, v71, v84, v87
	v_mul_f32_e32 v110, v110, v87
	v_cvt_pk_bf16_f32 v206, v70, v110
	v_lshlrev_b32_e32 v91, 16, v91
	v_lshlrev_b32_e32 v93, 16, v93
	v_lshlrev_b32_e32 v89, 16, v89
	v_mul_f32_e32 v89, v16, v89
	v_fmac_f32_e32 v89, v14, v91
	v_fmac_f32_e32 v89, v17, v93
	v_add_f32_e32 v89, v12, v89
	v_fma_f32 v27, v46, v8, v24
	v_mul_f32_e32 v70, v27, v89
	v_lshlrev_b32_e32 v97, 16, v97
	v_mul_f32_e32 v84, 0xbfb8aa3b, v97
	v_exp_f32_e32 v84, v84
	s_nop 0
	v_add_f32_e32 v84, 1.0, v84
	v_div_scale_f32 v71, s[28:29], v84, v84, v97
	v_rcp_f32_e32 v82, v71
	s_nop 0
	v_fma_f32 v92, -v71, v82, 1.0
	v_fmac_f32_e32 v82, v92, v82
	v_div_scale_f32 v88, vcc, v97, v84, v97
	v_mul_f32_e32 v90, v88, v82
	v_fma_f32 v92, -v71, v90, v88
	v_fmac_f32_e32 v90, v92, v82
	v_fma_f32 v71, -v71, v90, v88
	v_div_fmas_f32 v71, v71, v82, v90
	v_div_fixup_f32 v97, v71, v84, v97
	v_mul_f32_e32 v70, v70, v97
	v_lshlrev_b32_e32 v95, 16, v95
	v_lshlrev_b32_e32 v96, 16, v96
	v_lshlrev_b32_e32 v94, 16, v94
	v_mul_f32_e32 v94, v16, v94
	v_fmac_f32_e32 v94, v14, v95
	v_fmac_f32_e32 v94, v17, v96
	v_add_f32_e32 v94, v12, v94
	v_fma_f32 v27, v48, v8, v25
	v_mul_f32_e32 v110, v27, v94
	v_lshlrev_b32_e32 v98, 16, v98
	v_mul_f32_e32 v84, 0xbfb8aa3b, v98
	v_exp_f32_e32 v84, v84
	s_nop 0
	v_add_f32_e32 v84, 1.0, v84
	v_div_scale_f32 v71, s[28:29], v84, v84, v98
	v_rcp_f32_e32 v82, v71
	s_nop 0
	v_fma_f32 v92, -v71, v82, 1.0
	v_fmac_f32_e32 v82, v92, v82
	v_div_scale_f32 v88, vcc, v98, v84, v98
	v_mul_f32_e32 v90, v88, v82
	v_fma_f32 v92, -v71, v90, v88
	v_fmac_f32_e32 v90, v92, v82
	v_fma_f32 v71, -v71, v90, v88
	v_div_fmas_f32 v71, v71, v82, v90
	v_div_fixup_f32 v98, v71, v84, v98
	v_mul_f32_e32 v110, v110, v98
	v_cvt_pk_bf16_f32 v207, v70, v110
	v_lshlrev_b32_e32 v100, 16, v100
	v_lshlrev_b32_e32 v101, 16, v101
	v_lshlrev_b32_e32 v99, 16, v99
	v_mul_f32_e32 v99, v16, v99
	v_fmac_f32_e32 v99, v14, v100
	v_fmac_f32_e32 v99, v17, v101
	v_add_f32_e32 v99, v12, v99
	v_fma_f32 v27, v51, v8, v18
	v_mul_f32_e32 v70, v27, v99
	v_lshlrev_b32_e32 v105, 16, v105
	v_mul_f32_e32 v84, 0xbfb8aa3b, v105
	v_exp_f32_e32 v84, v84
	s_nop 0
	v_add_f32_e32 v84, 1.0, v84
	v_div_scale_f32 v71, s[28:29], v84, v84, v105
	v_rcp_f32_e32 v82, v71
	s_nop 0
	v_fma_f32 v92, -v71, v82, 1.0
	v_fmac_f32_e32 v82, v92, v82
	v_div_scale_f32 v88, vcc, v105, v84, v105
	v_mul_f32_e32 v90, v88, v82
	v_fma_f32 v92, -v71, v90, v88
	v_fmac_f32_e32 v90, v92, v82
	v_fma_f32 v71, -v71, v90, v88
	v_div_fmas_f32 v71, v71, v82, v90
	v_div_fixup_f32 v105, v71, v84, v105
	v_mul_f32_e32 v70, v70, v105
	v_lshlrev_b32_e32 v103, 16, v103
	v_lshlrev_b32_e32 v104, 16, v104
	v_lshlrev_b32_e32 v102, 16, v102
	v_mul_f32_e32 v102, v16, v102
	v_fmac_f32_e32 v102, v14, v103
	v_fmac_f32_e32 v102, v17, v104
	v_add_f32_e32 v102, v12, v102
	v_fma_f32 v27, v53, v8, v19
	v_mul_f32_e32 v110, v27, v102
	v_lshlrev_b32_e32 v106, 16, v106
	v_mul_f32_e32 v84, 0xbfb8aa3b, v106
	v_exp_f32_e32 v84, v84
	s_nop 0
	v_add_f32_e32 v84, 1.0, v84
	v_div_scale_f32 v71, s[28:29], v84, v84, v106
	v_rcp_f32_e32 v82, v71
	s_nop 0
	v_fma_f32 v92, -v71, v82, 1.0
	v_fmac_f32_e32 v82, v92, v82
	v_div_scale_f32 v88, vcc, v106, v84, v106
	v_mul_f32_e32 v90, v88, v82
	v_fma_f32 v92, -v71, v90, v88
	v_fmac_f32_e32 v90, v92, v82
	v_fma_f32 v71, -v71, v90, v88
	v_div_fmas_f32 v71, v71, v82, v90
	v_div_fixup_f32 v106, v71, v84, v106
	v_mul_f32_e32 v110, v110, v106
	v_cvt_pk_bf16_f32 v208, v70, v110
	v_lshlrev_b32_e32 v108, 16, v108
	v_lshlrev_b32_e32 v32, 16, v32
	v_lshlrev_b32_e32 v107, 16, v107
	v_mul_f32_e32 v107, v16, v107
	v_fmac_f32_e32 v107, v14, v108
	v_fmac_f32_e32 v107, v17, v32
	v_add_f32_e32 v107, v12, v107
	v_fma_f32 v27, v50, v8, v20
	v_mul_f32_e32 v70, v27, v107
	v_lshlrev_b32_e32 v33, 16, v33
	v_mul_f32_e32 v84, 0xbfb8aa3b, v33
	v_exp_f32_e32 v84, v84
	s_nop 0
	v_add_f32_e32 v84, 1.0, v84
	v_div_scale_f32 v71, s[28:29], v84, v84, v33
	v_rcp_f32_e32 v82, v71
	s_nop 0
	v_fma_f32 v92, -v71, v82, 1.0
	v_fmac_f32_e32 v82, v92, v82
	v_div_scale_f32 v88, vcc, v33, v84, v33
	v_mul_f32_e32 v90, v88, v82
	v_fma_f32 v92, -v71, v90, v88
	v_fmac_f32_e32 v90, v92, v82
	v_fma_f32 v71, -v71, v90, v88
	v_div_fmas_f32 v71, v71, v82, v90
	v_div_fixup_f32 v33, v71, v84, v33
	v_mul_f32_e32 v70, v70, v33
	v_lshlrev_b32_e32 v34, 16, v34
	v_lshlrev_b32_e32 v79, 16, v79
	v_lshlrev_b32_e32 v78, 16, v78
	v_mul_f32_e32 v78, v16, v78
	v_fmac_f32_e32 v78, v14, v34
	v_fmac_f32_e32 v78, v17, v79
	v_add_f32_e32 v78, v12, v78
	v_fma_f32 v27, v52, v8, v21
	v_mul_f32_e32 v110, v27, v78
	v_lshlrev_b32_e32 v76, 16, v76
	v_mul_f32_e32 v84, 0xbfb8aa3b, v76
	v_exp_f32_e32 v84, v84
	s_nop 0
	v_add_f32_e32 v84, 1.0, v84
	v_div_scale_f32 v71, s[28:29], v84, v84, v76
	v_rcp_f32_e32 v82, v71
	s_nop 0
	v_fma_f32 v92, -v71, v82, 1.0
	v_fmac_f32_e32 v82, v92, v82
	v_div_scale_f32 v88, vcc, v76, v84, v76
	v_mul_f32_e32 v90, v88, v82
	v_fma_f32 v92, -v71, v90, v88
	v_fmac_f32_e32 v90, v92, v82
	v_fma_f32 v71, -v71, v90, v88
	v_div_fmas_f32 v71, v71, v82, v90
	v_div_fixup_f32 v76, v71, v84, v76
	v_mul_f32_e32 v110, v110, v76
	v_cvt_pk_bf16_f32 v209, v70, v110
	v_add_u32_e32 v52, 0x1e00, v10
	v_cmp_gt_i32_e32 vcc, 0x1fff, v52
	v_min_i32_e32 v52, 0x1ffe, v52
	v_lshlrev_b32_e32 v52, 1, v52
	s_nop 0
	v_cndmask_b32_e64 v21, 0, 1.0, vcc
	v_add_u32_e32 v109, 0x1000, v109
	global_load_ushort v9, v109, s[36:37] offset:-2
	global_load_ushort v11, v109, s[36:37]
	global_load_ushort v13, v109, s[36:37] offset:2
	global_load_ushort v15, v109, s[88:89] offset:-2
	global_load_ushort v81, v109, s[88:89]
	global_load_ushort v83, v109, s[88:89] offset:2
	global_load_ushort v85, v109, s[0:1]
	global_load_ushort v87, v109, s[4:5]
	global_load_ushort v89, v109, s[36:37] offset:1022
	global_load_ushort v91, v109, s[36:37] offset:1024
	global_load_ushort v93, v109, s[36:37] offset:1026
	global_load_ushort v94, v109, s[88:89] offset:1022
	global_load_ushort v95, v109, s[88:89] offset:1024
	global_load_ushort v96, v109, s[88:89] offset:1026
	global_load_ushort v97, v109, s[0:1] offset:1024
	global_load_ushort v98, v109, s[4:5] offset:1024
	global_load_ushort v99, v109, s[36:37] offset:2046
	global_load_ushort v100, v109, s[36:37] offset:2048
	global_load_ushort v101, v109, s[36:37] offset:2050
	global_load_ushort v102, v109, s[88:89] offset:2046
	global_load_ushort v103, v109, s[88:89] offset:2048
	global_load_ushort v104, v109, s[88:89] offset:2050
	global_load_ushort v105, v109, s[0:1] offset:2048
	global_load_ushort v106, v109, s[4:5] offset:2048
	global_load_ushort v107, v109, s[36:37] offset:3070
	global_load_ushort v108, v109, s[36:37] offset:3072
	global_load_ushort v32, v52, s[36:37] offset:2
	global_load_ushort v78, v109, s[88:89] offset:3070
	global_load_ushort v34, v109, s[88:89] offset:3072
	global_load_ushort v79, v52, s[88:89] offset:2
	global_load_ushort v33, v109, s[0:1] offset:3072
	global_load_ushort v76, v109, s[4:5] offset:3072
	s_waitcnt vmcnt(0)
	v_lshlrev_b32_e32 v11, 16, v11
	v_lshlrev_b32_e32 v13, 16, v13
	v_lshlrev_b32_e32 v9, 16, v9
	v_mul_f32_e32 v9, v16, v9
	v_fmac_f32_e32 v9, v14, v11
	v_fmac_f32_e32 v9, v17, v13
	v_add_f32_e32 v9, v12, v9
	v_fma_f32 v27, v55, v8, v4
	v_mul_f32_e32 v70, v27, v9
	v_lshlrev_b32_e32 v85, 16, v85
	v_mul_f32_e32 v84, 0xbfb8aa3b, v85
	v_exp_f32_e32 v84, v84
	s_nop 0
	v_add_f32_e32 v84, 1.0, v84
	v_div_scale_f32 v71, s[28:29], v84, v84, v85
	v_rcp_f32_e32 v82, v71
	s_nop 0
	v_fma_f32 v92, -v71, v82, 1.0
	v_fmac_f32_e32 v82, v92, v82
	v_div_scale_f32 v88, vcc, v85, v84, v85
	v_mul_f32_e32 v90, v88, v82
	v_fma_f32 v92, -v71, v90, v88
	v_fmac_f32_e32 v90, v92, v82
	v_fma_f32 v71, -v71, v90, v88
	v_div_fmas_f32 v71, v71, v82, v90
	v_div_fixup_f32 v85, v71, v84, v85
	v_mul_f32_e32 v70, v70, v85
	v_lshlrev_b32_e32 v81, 16, v81
	v_lshlrev_b32_e32 v83, 16, v83
	v_lshlrev_b32_e32 v15, 16, v15
	v_mul_f32_e32 v15, v16, v15
	v_fmac_f32_e32 v15, v14, v81
	v_fmac_f32_e32 v15, v17, v83
	v_add_f32_e32 v15, v12, v15
	v_fma_f32 v27, v57, v8, v5
	v_mul_f32_e32 v110, v27, v15
	v_lshlrev_b32_e32 v87, 16, v87
	v_mul_f32_e32 v84, 0xbfb8aa3b, v87
	v_exp_f32_e32 v84, v84
	s_nop 0
	v_add_f32_e32 v84, 1.0, v84
	v_div_scale_f32 v71, s[28:29], v84, v84, v87
	v_rcp_f32_e32 v82, v71
	s_nop 0
	v_fma_f32 v92, -v71, v82, 1.0
	v_fmac_f32_e32 v82, v92, v82
	v_div_scale_f32 v88, vcc, v87, v84, v87
	v_mul_f32_e32 v90, v88, v82
	v_fma_f32 v92, -v71, v90, v88
	v_fmac_f32_e32 v90, v92, v82
	v_fma_f32 v71, -v71, v90, v88
	v_div_fmas_f32 v71, v71, v82, v90
	v_div_fixup_f32 v87, v71, v84, v87
	v_mul_f32_e32 v110, v110, v87
	v_cvt_pk_bf16_f32 v210, v70, v110
	v_lshlrev_b32_e32 v91, 16, v91
	v_lshlrev_b32_e32 v93, 16, v93
	v_lshlrev_b32_e32 v89, 16, v89
	v_mul_f32_e32 v89, v16, v89
	v_fmac_f32_e32 v89, v14, v91
	v_fmac_f32_e32 v89, v17, v93
	v_add_f32_e32 v89, v12, v89
	v_fma_f32 v27, v54, v8, v6
	v_mul_f32_e32 v70, v27, v89
	v_lshlrev_b32_e32 v97, 16, v97
	v_mul_f32_e32 v84, 0xbfb8aa3b, v97
	v_exp_f32_e32 v84, v84
	s_nop 0
	v_add_f32_e32 v84, 1.0, v84
	v_div_scale_f32 v71, s[28:29], v84, v84, v97
	v_rcp_f32_e32 v82, v71
	s_nop 0
	v_fma_f32 v92, -v71, v82, 1.0
	v_fmac_f32_e32 v82, v92, v82
	v_div_scale_f32 v88, vcc, v97, v84, v97
	v_mul_f32_e32 v90, v88, v82
	v_fma_f32 v92, -v71, v90, v88
	v_fmac_f32_e32 v90, v92, v82
	v_fma_f32 v71, -v71, v90, v88
	v_div_fmas_f32 v71, v71, v82, v90
	v_div_fixup_f32 v97, v71, v84, v97
	v_mul_f32_e32 v70, v70, v97
	v_lshlrev_b32_e32 v95, 16, v95
	v_lshlrev_b32_e32 v96, 16, v96
	v_lshlrev_b32_e32 v94, 16, v94
	v_mul_f32_e32 v94, v16, v94
	v_fmac_f32_e32 v94, v14, v95
	v_fmac_f32_e32 v94, v17, v96
	v_add_f32_e32 v94, v12, v94
	v_fma_f32 v27, v56, v8, v7
	v_mul_f32_e32 v110, v27, v94
	v_lshlrev_b32_e32 v98, 16, v98
	v_mul_f32_e32 v84, 0xbfb8aa3b, v98
	v_exp_f32_e32 v84, v84
	s_nop 0
	v_add_f32_e32 v84, 1.0, v84
	v_div_scale_f32 v71, s[28:29], v84, v84, v98
	v_rcp_f32_e32 v82, v71
	s_nop 0
	v_fma_f32 v92, -v71, v82, 1.0
	v_fmac_f32_e32 v82, v92, v82
	v_div_scale_f32 v88, vcc, v98, v84, v98
	v_mul_f32_e32 v90, v88, v82
	v_fma_f32 v92, -v71, v90, v88
	v_fmac_f32_e32 v90, v92, v82
	v_fma_f32 v71, -v71, v90, v88
	v_div_fmas_f32 v71, v71, v82, v90
	v_div_fixup_f32 v98, v71, v84, v98
	v_mul_f32_e32 v110, v110, v98
	v_cvt_pk_bf16_f32 v211, v70, v110
	v_lshlrev_b32_e32 v100, 16, v100
	v_lshlrev_b32_e32 v101, 16, v101
	v_lshlrev_b32_e32 v99, 16, v99
	v_mul_f32_e32 v99, v16, v99
	v_fmac_f32_e32 v99, v14, v100
	v_fmac_f32_e32 v99, v17, v101
	v_add_f32_e32 v99, v12, v99
	v_fma_f32 v27, v59, v8, v0
	v_mul_f32_e32 v70, v27, v99
	v_lshlrev_b32_e32 v105, 16, v105
	v_mul_f32_e32 v84, 0xbfb8aa3b, v105
	v_exp_f32_e32 v84, v84
	s_nop 0
	v_add_f32_e32 v84, 1.0, v84
	v_div_scale_f32 v71, s[28:29], v84, v84, v105
	v_rcp_f32_e32 v82, v71
	s_nop 0
	v_fma_f32 v92, -v71, v82, 1.0
	v_fmac_f32_e32 v82, v92, v82
	v_div_scale_f32 v88, vcc, v105, v84, v105
	v_mul_f32_e32 v90, v88, v82
	v_fma_f32 v92, -v71, v90, v88
	v_fmac_f32_e32 v90, v92, v82
	v_fma_f32 v71, -v71, v90, v88
	v_div_fmas_f32 v71, v71, v82, v90
	v_div_fixup_f32 v105, v71, v84, v105
	v_mul_f32_e32 v70, v70, v105
	v_lshlrev_b32_e32 v103, 16, v103
	v_lshlrev_b32_e32 v104, 16, v104
	v_lshlrev_b32_e32 v102, 16, v102
	v_mul_f32_e32 v102, v16, v102
	v_fmac_f32_e32 v102, v14, v103
	v_fmac_f32_e32 v102, v17, v104
	v_add_f32_e32 v102, v12, v102
	v_fma_f32 v27, v61, v8, v1
	v_mul_f32_e32 v110, v27, v102
	v_lshlrev_b32_e32 v106, 16, v106
	v_mul_f32_e32 v84, 0xbfb8aa3b, v106
	v_exp_f32_e32 v84, v84
	s_nop 0
	v_add_f32_e32 v84, 1.0, v84
	v_div_scale_f32 v71, s[28:29], v84, v84, v106
	v_rcp_f32_e32 v82, v71
	s_nop 0
	v_fma_f32 v92, -v71, v82, 1.0
	v_fmac_f32_e32 v82, v92, v82
	v_div_scale_f32 v88, vcc, v106, v84, v106
	v_mul_f32_e32 v90, v88, v82
	v_fma_f32 v92, -v71, v90, v88
	v_fmac_f32_e32 v90, v92, v82
	v_fma_f32 v71, -v71, v90, v88
	v_div_fmas_f32 v71, v71, v82, v90
	v_div_fixup_f32 v106, v71, v84, v106
	v_mul_f32_e32 v110, v110, v106
	v_cvt_pk_bf16_f32 v212, v70, v110
	v_lshlrev_b32_e32 v108, 16, v108
	v_lshlrev_b32_e32 v32, 16, v32
	v_lshlrev_b32_e32 v107, 16, v107
	v_mul_f32_e32 v107, v16, v107
	v_mul_f32_e32 v32, v21, v32
	v_fmac_f32_e32 v107, v14, v108
	v_fmac_f32_e32 v107, v17, v32
	v_add_f32_e32 v107, v12, v107
	v_fma_f32 v27, v58, v8, v2
	v_mul_f32_e32 v70, v27, v107
	v_lshlrev_b32_e32 v33, 16, v33
	v_mul_f32_e32 v84, 0xbfb8aa3b, v33
	v_exp_f32_e32 v84, v84
	s_nop 0
	v_add_f32_e32 v84, 1.0, v84
	v_div_scale_f32 v71, s[28:29], v84, v84, v33
	v_rcp_f32_e32 v82, v71
	s_nop 0
	v_fma_f32 v92, -v71, v82, 1.0
	v_fmac_f32_e32 v82, v92, v82
	v_div_scale_f32 v88, vcc, v33, v84, v33
	v_mul_f32_e32 v90, v88, v82
	v_fma_f32 v92, -v71, v90, v88
	v_fmac_f32_e32 v90, v92, v82
	v_fma_f32 v71, -v71, v90, v88
	v_div_fmas_f32 v71, v71, v82, v90
	v_div_fixup_f32 v33, v71, v84, v33
	v_mul_f32_e32 v70, v70, v33
	v_lshlrev_b32_e32 v34, 16, v34
	v_lshlrev_b32_e32 v79, 16, v79
	v_lshlrev_b32_e32 v78, 16, v78
	v_mul_f32_e32 v78, v16, v78
	v_mul_f32_e32 v79, v21, v79
	v_fmac_f32_e32 v78, v14, v34
	v_fmac_f32_e32 v78, v17, v79
	v_add_f32_e32 v78, v12, v78
	v_fma_f32 v27, v60, v8, v3
	v_mul_f32_e32 v110, v27, v78
	v_lshlrev_b32_e32 v76, 16, v76
	v_mul_f32_e32 v84, 0xbfb8aa3b, v76
	v_exp_f32_e32 v84, v84
	s_nop 0
	v_add_f32_e32 v84, 1.0, v84
	v_div_scale_f32 v71, s[28:29], v84, v84, v76
	v_rcp_f32_e32 v82, v71
	s_nop 0
	v_fma_f32 v92, -v71, v82, 1.0
	v_fmac_f32_e32 v82, v92, v82
	v_div_scale_f32 v88, vcc, v76, v84, v76
	v_mul_f32_e32 v90, v88, v82
	v_fma_f32 v92, -v71, v90, v88
	v_fmac_f32_e32 v90, v92, v82
	v_fma_f32 v71, -v71, v90, v88
	v_div_fmas_f32 v71, v71, v82, v90
	v_div_fixup_f32 v76, v71, v84, v76
	v_mul_f32_e32 v110, v110, v76
	v_cvt_pk_bf16_f32 v213, v70, v110
	s_branch .Lhy_ep1_done_L0
.Lhy_ep1_comb_L0:
	s_mov_b32 s98, 0x5040100
	s_mov_b32 s99, 0x7060302
	v_lshlrev_b32_e32 v109, 1, v10
	global_load_ushort v9, v109, s[0:1]
	global_load_ushort v11, v109, s[4:5]
	global_load_ushort v13, v109, s[36:37] offset:1022
	global_load_ushort v15, v109, s[36:37] offset:1024
	global_load_ushort v81, v109, s[36:37] offset:1026
	global_load_ushort v83, v109, s[88:89] offset:1022
	global_load_ushort v85, v109, s[88:89] offset:1024
	global_load_ushort v87, v109, s[88:89] offset:1026
	global_load_ushort v89, v109, s[0:1] offset:1024
	global_load_ushort v91, v109, s[4:5] offset:1024
	global_load_ushort v93, v109, s[36:37] offset:2046
	global_load_ushort v94, v109, s[36:37] offset:2048
	global_load_ushort v95, v109, s[36:37] offset:2050
	global_load_ushort v96, v109, s[88:89] offset:2046
	global_load_ushort v97, v109, s[88:89] offset:2048
	global_load_ushort v98, v109, s[88:89] offset:2050
	global_load_ushort v99, v109, s[0:1] offset:2048
	global_load_ushort v100, v109, s[4:5] offset:2048
	global_load_ushort v101, v109, s[36:37] offset:3070
	global_load_ushort v102, v109, s[36:37] offset:3072
	global_load_ushort v103, v109, s[36:37] offset:3074
	global_load_ushort v104, v109, s[88:89] offset:3070
	global_load_ushort v105, v109, s[88:89] offset:3072
	global_load_ushort v106, v109, s[88:89] offset:3074
	global_load_ushort v107, v109, s[0:1] offset:3072
	global_load_ushort v108, v109, s[4:5] offset:3072
	s_waitcnt vmcnt(0)
	v_lshlrev_b32_e32 v26, 10, v10
	v_fma_f32 v27, v32, v8, v78
	v_mul_f32_e32 v70, v80, v27
	v_lshlrev_b32_e32 v9, 16, v9
	v_mul_f32_e32 v84, 0xbfb8aa3b, v9
	v_exp_f32_e32 v84, v84
	s_nop 0
	v_add_f32_e32 v84, 1.0, v84
	v_div_scale_f32 v71, s[28:29], v84, v84, v9
	v_rcp_f32_e32 v82, v71
	s_nop 0
	v_fma_f32 v92, -v71, v82, 1.0
	v_fmac_f32_e32 v82, v92, v82
	v_div_scale_f32 v88, vcc, v9, v84, v9
	v_mul_f32_e32 v90, v88, v82
	v_fma_f32 v92, -v71, v90, v88
	v_fmac_f32_e32 v90, v92, v82
	v_fma_f32 v71, -v71, v90, v88
	v_div_fmas_f32 v71, v71, v82, v90
	v_div_fixup_f32 v9, v71, v84, v9
	v_mul_f32_e32 v70, v70, v9
	v_fma_f32 v27, v34, v8, v79
	v_mul_f32_e32 v110, v86, v27
	v_lshlrev_b32_e32 v11, 16, v11
	v_mul_f32_e32 v84, 0xbfb8aa3b, v11
	v_exp_f32_e32 v84, v84
	s_nop 0
	v_add_f32_e32 v84, 1.0, v84
	v_div_scale_f32 v71, s[28:29], v84, v84, v11
	v_rcp_f32_e32 v82, v71
	s_nop 0
	v_fma_f32 v92, -v71, v82, 1.0
	v_fmac_f32_e32 v82, v92, v82
	v_div_scale_f32 v88, vcc, v11, v84, v11
	v_mul_f32_e32 v90, v88, v82
	v_fma_f32 v92, -v71, v90, v88
	v_fmac_f32_e32 v90, v92, v82
	v_fma_f32 v71, -v71, v90, v88
	v_div_fmas_f32 v71, v71, v82, v90
	v_div_fixup_f32 v11, v71, v84, v11
	v_mul_f32_e32 v110, v110, v11
	v_cvt_pk_bf16_f32 v70, v70, v110
	v_perm_b32 v110, v70, v198, s98
	v_perm_b32 v70, v70, v198, s99
	global_store_dword v26, v110, s[96:97] offset:-2
	global_store_dword v26, v70, s[18:19] offset:-2
	v_add_u32_e32 v26, 0x80000, v26
	v_lshlrev_b32_e32 v15, 16, v15
	v_lshlrev_b32_e32 v81, 16, v81
	v_lshlrev_b32_e32 v13, 16, v13
	v_mul_f32_e32 v13, v16, v13
	v_fmac_f32_e32 v13, v14, v15
	v_fmac_f32_e32 v13, v17, v81
	v_add_f32_e32 v13, v12, v13
	v_fma_f32 v27, v33, v8, v76
	v_mul_f32_e32 v70, v27, v13
	v_lshlrev_b32_e32 v89, 16, v89
	v_mul_f32_e32 v84, 0xbfb8aa3b, v89
	v_exp_f32_e32 v84, v84
	s_nop 0
	v_add_f32_e32 v84, 1.0, v84
	v_div_scale_f32 v71, s[28:29], v84, v84, v89
	v_rcp_f32_e32 v82, v71
	s_nop 0
	v_fma_f32 v92, -v71, v82, 1.0
	v_fmac_f32_e32 v82, v92, v82
	v_div_scale_f32 v88, vcc, v89, v84, v89
	v_mul_f32_e32 v90, v88, v82
	v_fma_f32 v92, -v71, v90, v88
	v_fmac_f32_e32 v90, v92, v82
	v_fma_f32 v71, -v71, v90, v88
	v_div_fmas_f32 v71, v71, v82, v90
	v_div_fixup_f32 v89, v71, v84, v89
	v_mul_f32_e32 v70, v70, v89
	v_lshlrev_b32_e32 v85, 16, v85
	v_lshlrev_b32_e32 v87, 16, v87
	v_lshlrev_b32_e32 v83, 16, v83
	v_mul_f32_e32 v83, v16, v83
	v_fmac_f32_e32 v83, v14, v85
	v_fmac_f32_e32 v83, v17, v87
	v_add_f32_e32 v83, v12, v83
	v_fma_f32 v27, v35, v8, v77
	v_mul_f32_e32 v110, v27, v83
	v_lshlrev_b32_e32 v91, 16, v91
	v_mul_f32_e32 v84, 0xbfb8aa3b, v91
	v_exp_f32_e32 v84, v84
	s_nop 0
	v_add_f32_e32 v84, 1.0, v84
	v_div_scale_f32 v71, s[28:29], v84, v84, v91
	v_rcp_f32_e32 v82, v71
	s_nop 0
	v_fma_f32 v92, -v71, v82, 1.0
	v_fmac_f32_e32 v82, v92, v82
	v_div_scale_f32 v88, vcc, v91, v84, v91
	v_mul_f32_e32 v90, v88, v82
	v_fma_f32 v92, -v71, v90, v88
	v_fmac_f32_e32 v90, v92, v82
	v_fma_f32 v71, -v71, v90, v88
	v_div_fmas_f32 v71, v71, v82, v90
	v_div_fixup_f32 v91, v71, v84, v91
	v_mul_f32_e32 v110, v110, v91
	v_cvt_pk_bf16_f32 v70, v70, v110
	v_perm_b32 v110, v70, v199, s98
	v_perm_b32 v70, v70, v199, s99
	global_store_dword v26, v110, s[96:97] offset:-2
	global_store_dword v26, v70, s[18:19] offset:-2
	v_add_u32_e32 v26, 0x80000, v26
	v_lshlrev_b32_e32 v94, 16, v94
	v_lshlrev_b32_e32 v95, 16, v95
	v_lshlrev_b32_e32 v93, 16, v93
	v_mul_f32_e32 v93, v16, v93
	v_fmac_f32_e32 v93, v14, v94
	v_fmac_f32_e32 v93, v17, v95
	v_add_f32_e32 v93, v12, v93
	v_fma_f32 v27, v37, v8, v72
	v_mul_f32_e32 v70, v27, v93
	v_lshlrev_b32_e32 v99, 16, v99
	v_mul_f32_e32 v84, 0xbfb8aa3b, v99
	v_exp_f32_e32 v84, v84
	s_nop 0
	v_add_f32_e32 v84, 1.0, v84
	v_div_scale_f32 v71, s[28:29], v84, v84, v99
	v_rcp_f32_e32 v82, v71
	s_nop 0
	v_fma_f32 v92, -v71, v82, 1.0
	v_fmac_f32_e32 v82, v92, v82
	v_div_scale_f32 v88, vcc, v99, v84, v99
	v_mul_f32_e32 v90, v88, v82
	v_fma_f32 v92, -v71, v90, v88
	v_fmac_f32_e32 v90, v92, v82
	v_fma_f32 v71, -v71, v90, v88
	v_div_fmas_f32 v71, v71, v82, v90
	v_div_fixup_f32 v99, v71, v84, v99
	v_mul_f32_e32 v70, v70, v99
	v_lshlrev_b32_e32 v97, 16, v97
	v_lshlrev_b32_e32 v98, 16, v98
	v_lshlrev_b32_e32 v96, 16, v96
	v_mul_f32_e32 v96, v16, v96
	v_fmac_f32_e32 v96, v14, v97
	v_fmac_f32_e32 v96, v17, v98
	v_add_f32_e32 v96, v12, v96
	v_fma_f32 v27, v31, v8, v73
	v_mul_f32_e32 v110, v27, v96
	v_lshlrev_b32_e32 v100, 16, v100
	v_mul_f32_e32 v84, 0xbfb8aa3b, v100
	v_exp_f32_e32 v84, v84
	s_nop 0
	v_add_f32_e32 v84, 1.0, v84
	v_div_scale_f32 v71, s[28:29], v84, v84, v100
	v_rcp_f32_e32 v82, v71
	s_nop 0
	v_fma_f32 v92, -v71, v82, 1.0
	v_fmac_f32_e32 v82, v92, v82
	v_div_scale_f32 v88, vcc, v100, v84, v100
	v_mul_f32_e32 v90, v88, v82
	v_fma_f32 v92, -v71, v90, v88
	v_fmac_f32_e32 v90, v92, v82
	v_fma_f32 v71, -v71, v90, v88
	v_div_fmas_f32 v71, v71, v82, v90
	v_div_fixup_f32 v100, v71, v84, v100
	v_mul_f32_e32 v110, v110, v100
	v_cvt_pk_bf16_f32 v70, v70, v110
	v_perm_b32 v110, v70, v200, s98
	v_perm_b32 v70, v70, v200, s99
	global_store_dword v26, v110, s[96:97] offset:-2
	global_store_dword v26, v70, s[18:19] offset:-2
	v_add_u32_e32 v26, 0x80000, v26
	v_lshlrev_b32_e32 v102, 16, v102
	v_lshlrev_b32_e32 v103, 16, v103
	v_lshlrev_b32_e32 v101, 16, v101
	v_mul_f32_e32 v101, v16, v101
	v_fmac_f32_e32 v101, v14, v102
	v_fmac_f32_e32 v101, v17, v103
	v_add_f32_e32 v101, v12, v101
	v_fma_f32 v27, v36, v8, v74
	v_mul_f32_e32 v70, v27, v101
	v_lshlrev_b32_e32 v107, 16, v107
	v_mul_f32_e32 v84, 0xbfb8aa3b, v107
	v_exp_f32_e32 v84, v84
	s_nop 0
	v_add_f32_e32 v84, 1.0, v84
	v_div_scale_f32 v71, s[28:29], v84, v84, v107
	v_rcp_f32_e32 v82, v71
	s_nop 0
	v_fma_f32 v92, -v71, v82, 1.0
	v_fmac_f32_e32 v82, v92, v82
	v_div_scale_f32 v88, vcc, v107, v84, v107
	v_mul_f32_e32 v90, v88, v82
	v_fma_f32 v92, -v71, v90, v88
	v_fmac_f32_e32 v90, v92, v82
	v_fma_f32 v71, -v71, v90, v88
	v_div_fmas_f32 v71, v71, v82, v90
	v_div_fixup_f32 v107, v71, v84, v107
	v_mul_f32_e32 v70, v70, v107
	v_lshlrev_b32_e32 v105, 16, v105
	v_lshlrev_b32_e32 v106, 16, v106
	v_lshlrev_b32_e32 v104, 16, v104
	v_mul_f32_e32 v104, v16, v104
	v_fmac_f32_e32 v104, v14, v105
	v_fmac_f32_e32 v104, v17, v106
	v_add_f32_e32 v104, v12, v104
	v_fma_f32 v27, v30, v8, v75
	v_mul_f32_e32 v110, v27, v104
	v_lshlrev_b32_e32 v108, 16, v108
	v_mul_f32_e32 v84, 0xbfb8aa3b, v108
	v_exp_f32_e32 v84, v84
	s_nop 0
	v_add_f32_e32 v84, 1.0, v84
	v_div_scale_f32 v71, s[28:29], v84, v84, v108
	v_rcp_f32_e32 v82, v71
	s_nop 0
	v_fma_f32 v92, -v71, v82, 1.0
	v_fmac_f32_e32 v82, v92, v82
	v_div_scale_f32 v88, vcc, v108, v84, v108
	v_mul_f32_e32 v90, v88, v82
	v_fma_f32 v92, -v71, v90, v88
	v_fmac_f32_e32 v90, v92, v82
	v_fma_f32 v71, -v71, v90, v88
	v_div_fmas_f32 v71, v71, v82, v90
	v_div_fixup_f32 v108, v71, v84, v108
	v_mul_f32_e32 v110, v110, v108
	v_cvt_pk_bf16_f32 v70, v70, v110
	v_perm_b32 v110, v70, v201, s98
	v_perm_b32 v70, v70, v201, s99
	global_store_dword v26, v110, s[96:97] offset:-2
	global_store_dword v26, v70, s[18:19] offset:-2
	v_add_u32_e32 v109, 0x1000, v109
	global_load_ushort v9, v109, s[36:37] offset:-2
	global_load_ushort v11, v109, s[36:37]
	global_load_ushort v13, v109, s[36:37] offset:2
	global_load_ushort v15, v109, s[88:89] offset:-2
	global_load_ushort v81, v109, s[88:89]
	global_load_ushort v83, v109, s[88:89] offset:2
	global_load_ushort v85, v109, s[0:1]
	global_load_ushort v87, v109, s[4:5]
	global_load_ushort v89, v109, s[36:37] offset:1022
	global_load_ushort v91, v109, s[36:37] offset:1024
	global_load_ushort v93, v109, s[36:37] offset:1026
	global_load_ushort v94, v109, s[88:89] offset:1022
	global_load_ushort v95, v109, s[88:89] offset:1024
	global_load_ushort v96, v109, s[88:89] offset:1026
	global_load_ushort v97, v109, s[0:1] offset:1024
	global_load_ushort v98, v109, s[4:5] offset:1024
	global_load_ushort v99, v109, s[36:37] offset:2046
	global_load_ushort v100, v109, s[36:37] offset:2048
	global_load_ushort v101, v109, s[36:37] offset:2050
	global_load_ushort v102, v109, s[88:89] offset:2046
	global_load_ushort v103, v109, s[88:89] offset:2048
	global_load_ushort v104, v109, s[88:89] offset:2050
	global_load_ushort v105, v109, s[0:1] offset:2048
	global_load_ushort v106, v109, s[4:5] offset:2048
	global_load_ushort v107, v109, s[36:37] offset:3070
	global_load_ushort v108, v109, s[36:37] offset:3072
	global_load_ushort v32, v109, s[36:37] offset:3074
	global_load_ushort v78, v109, s[88:89] offset:3070
	global_load_ushort v34, v109, s[88:89] offset:3072
	global_load_ushort v79, v109, s[88:89] offset:3074
	global_load_ushort v33, v109, s[0:1] offset:3072
	global_load_ushort v76, v109, s[4:5] offset:3072
	s_waitcnt vmcnt(0)
	v_add_u32_e32 v26, 0x80000, v26
	v_lshlrev_b32_e32 v11, 16, v11
	v_lshlrev_b32_e32 v13, 16, v13
	v_lshlrev_b32_e32 v9, 16, v9
	v_mul_f32_e32 v9, v16, v9
	v_fmac_f32_e32 v9, v14, v11
	v_fmac_f32_e32 v9, v17, v13
	v_add_f32_e32 v9, v12, v9
	v_fma_f32 v27, v39, v8, v66
	v_mul_f32_e32 v70, v27, v9
	v_lshlrev_b32_e32 v85, 16, v85
	v_mul_f32_e32 v84, 0xbfb8aa3b, v85
	v_exp_f32_e32 v84, v84
	s_nop 0
	v_add_f32_e32 v84, 1.0, v84
	v_div_scale_f32 v71, s[28:29], v84, v84, v85
	v_rcp_f32_e32 v82, v71
	s_nop 0
	v_fma_f32 v92, -v71, v82, 1.0
	v_fmac_f32_e32 v82, v92, v82
	v_div_scale_f32 v88, vcc, v85, v84, v85
	v_mul_f32_e32 v90, v88, v82
	v_fma_f32 v92, -v71, v90, v88
	v_fmac_f32_e32 v90, v92, v82
	v_fma_f32 v71, -v71, v90, v88
	v_div_fmas_f32 v71, v71, v82, v90
	v_div_fixup_f32 v85, v71, v84, v85
	v_mul_f32_e32 v70, v70, v85
	v_lshlrev_b32_e32 v81, 16, v81
	v_lshlrev_b32_e32 v83, 16, v83
	v_lshlrev_b32_e32 v15, 16, v15
	v_mul_f32_e32 v15, v16, v15
	v_fmac_f32_e32 v15, v14, v81
	v_fmac_f32_e32 v15, v17, v83
	v_add_f32_e32 v15, v12, v15
	v_fma_f32 v27, v41, v8, v67
	v_mul_f32_e32 v110, v27, v15
	v_lshlrev_b32_e32 v87, 16, v87
	v_mul_f32_e32 v84, 0xbfb8aa3b, v87
	v_exp_f32_e32 v84, v84
	s_nop 0
	v_add_f32_e32 v84, 1.0, v84
	v_div_scale_f32 v71, s[28:29], v84, v84, v87
	v_rcp_f32_e32 v82, v71
	s_nop 0
	v_fma_f32 v92, -v71, v82, 1.0
	v_fmac_f32_e32 v82, v92, v82
	v_div_scale_f32 v88, vcc, v87, v84, v87
	v_mul_f32_e32 v90, v88, v82
	v_fma_f32 v92, -v71, v90, v88
	v_fmac_f32_e32 v90, v92, v82
	v_fma_f32 v71, -v71, v90, v88
	v_div_fmas_f32 v71, v71, v82, v90
	v_div_fixup_f32 v87, v71, v84, v87
	v_mul_f32_e32 v110, v110, v87
	v_cvt_pk_bf16_f32 v70, v70, v110
	v_perm_b32 v110, v70, v202, s98
	v_perm_b32 v70, v70, v202, s99
	global_store_dword v26, v110, s[96:97] offset:-2
	global_store_dword v26, v70, s[18:19] offset:-2
	v_add_u32_e32 v26, 0x80000, v26
	v_lshlrev_b32_e32 v91, 16, v91
	v_lshlrev_b32_e32 v93, 16, v93
	v_lshlrev_b32_e32 v89, 16, v89
	v_mul_f32_e32 v89, v16, v89
	v_fmac_f32_e32 v89, v14, v91
	v_fmac_f32_e32 v89, v17, v93
	v_add_f32_e32 v89, v12, v89
	v_fma_f32 v27, v38, v8, v68
	v_mul_f32_e32 v70, v27, v89
	v_lshlrev_b32_e32 v97, 16, v97
	v_mul_f32_e32 v84, 0xbfb8aa3b, v97
	v_exp_f32_e32 v84, v84
	s_nop 0
	v_add_f32_e32 v84, 1.0, v84
	v_div_scale_f32 v71, s[28:29], v84, v84, v97
	v_rcp_f32_e32 v82, v71
	s_nop 0
	v_fma_f32 v92, -v71, v82, 1.0
	v_fmac_f32_e32 v82, v92, v82
	v_div_scale_f32 v88, vcc, v97, v84, v97
	v_mul_f32_e32 v90, v88, v82
	v_fma_f32 v92, -v71, v90, v88
	v_fmac_f32_e32 v90, v92, v82
	v_fma_f32 v71, -v71, v90, v88
	v_div_fmas_f32 v71, v71, v82, v90
	v_div_fixup_f32 v97, v71, v84, v97
	v_mul_f32_e32 v70, v70, v97
	v_lshlrev_b32_e32 v95, 16, v95
	v_lshlrev_b32_e32 v96, 16, v96
	v_lshlrev_b32_e32 v94, 16, v94
	v_mul_f32_e32 v94, v16, v94
	v_fmac_f32_e32 v94, v14, v95
	v_fmac_f32_e32 v94, v17, v96
	v_add_f32_e32 v94, v12, v94
	v_fma_f32 v27, v40, v8, v69
	v_mul_f32_e32 v110, v27, v94
	v_lshlrev_b32_e32 v98, 16, v98
	v_mul_f32_e32 v84, 0xbfb8aa3b, v98
	v_exp_f32_e32 v84, v84
	s_nop 0
	v_add_f32_e32 v84, 1.0, v84
	v_div_scale_f32 v71, s[28:29], v84, v84, v98
	v_rcp_f32_e32 v82, v71
	s_nop 0
	v_fma_f32 v92, -v71, v82, 1.0
	v_fmac_f32_e32 v82, v92, v82
	v_div_scale_f32 v88, vcc, v98, v84, v98
	v_mul_f32_e32 v90, v88, v82
	v_fma_f32 v92, -v71, v90, v88
	v_fmac_f32_e32 v90, v92, v82
	v_fma_f32 v71, -v71, v90, v88
	v_div_fmas_f32 v71, v71, v82, v90
	v_div_fixup_f32 v98, v71, v84, v98
	v_mul_f32_e32 v110, v110, v98
	v_cvt_pk_bf16_f32 v70, v70, v110
	v_perm_b32 v110, v70, v203, s98
	v_perm_b32 v70, v70, v203, s99
	global_store_dword v26, v110, s[96:97] offset:-2
	global_store_dword v26, v70, s[18:19] offset:-2
	v_add_u32_e32 v26, 0x80000, v26
	v_lshlrev_b32_e32 v100, 16, v100
	v_lshlrev_b32_e32 v101, 16, v101
	v_lshlrev_b32_e32 v99, 16, v99
	v_mul_f32_e32 v99, v16, v99
	v_fmac_f32_e32 v99, v14, v100
	v_fmac_f32_e32 v99, v17, v101
	v_add_f32_e32 v99, v12, v99
	v_fma_f32 v27, v43, v8, v62
	v_mul_f32_e32 v70, v27, v99
	v_lshlrev_b32_e32 v105, 16, v105
	v_mul_f32_e32 v84, 0xbfb8aa3b, v105
	v_exp_f32_e32 v84, v84
	s_nop 0
	v_add_f32_e32 v84, 1.0, v84
	v_div_scale_f32 v71, s[28:29], v84, v84, v105
	v_rcp_f32_e32 v82, v71
	s_nop 0
	v_fma_f32 v92, -v71, v82, 1.0
	v_fmac_f32_e32 v82, v92, v82
	v_div_scale_f32 v88, vcc, v105, v84, v105
	v_mul_f32_e32 v90, v88, v82
	v_fma_f32 v92, -v71, v90, v88
	v_fmac_f32_e32 v90, v92, v82
	v_fma_f32 v71, -v71, v90, v88
	v_div_fmas_f32 v71, v71, v82, v90
	v_div_fixup_f32 v105, v71, v84, v105
	v_mul_f32_e32 v70, v70, v105
	v_lshlrev_b32_e32 v103, 16, v103
	v_lshlrev_b32_e32 v104, 16, v104
	v_lshlrev_b32_e32 v102, 16, v102
	v_mul_f32_e32 v102, v16, v102
	v_fmac_f32_e32 v102, v14, v103
	v_fmac_f32_e32 v102, v17, v104
	v_add_f32_e32 v102, v12, v102
	v_fma_f32 v27, v45, v8, v63
	v_mul_f32_e32 v110, v27, v102
	v_lshlrev_b32_e32 v106, 16, v106
	v_mul_f32_e32 v84, 0xbfb8aa3b, v106
	v_exp_f32_e32 v84, v84
	s_nop 0
	v_add_f32_e32 v84, 1.0, v84
	v_div_scale_f32 v71, s[28:29], v84, v84, v106
	v_rcp_f32_e32 v82, v71
	s_nop 0
	v_fma_f32 v92, -v71, v82, 1.0
	v_fmac_f32_e32 v82, v92, v82
	v_div_scale_f32 v88, vcc, v106, v84, v106
	v_mul_f32_e32 v90, v88, v82
	v_fma_f32 v92, -v71, v90, v88
	v_fmac_f32_e32 v90, v92, v82
	v_fma_f32 v71, -v71, v90, v88
	v_div_fmas_f32 v71, v71, v82, v90
	v_div_fixup_f32 v106, v71, v84, v106
	v_mul_f32_e32 v110, v110, v106
	v_cvt_pk_bf16_f32 v70, v70, v110
	v_perm_b32 v110, v70, v204, s98
	v_perm_b32 v70, v70, v204, s99
	global_store_dword v26, v110, s[96:97] offset:-2
	global_store_dword v26, v70, s[18:19] offset:-2
	v_add_u32_e32 v26, 0x80000, v26
	v_lshlrev_b32_e32 v108, 16, v108
	v_lshlrev_b32_e32 v32, 16, v32
	v_lshlrev_b32_e32 v107, 16, v107
	v_mul_f32_e32 v107, v16, v107
	v_fmac_f32_e32 v107, v14, v108
	v_fmac_f32_e32 v107, v17, v32
	v_add_f32_e32 v107, v12, v107
	v_fma_f32 v27, v42, v8, v64
	v_mul_f32_e32 v70, v27, v107
	v_lshlrev_b32_e32 v33, 16, v33
	v_mul_f32_e32 v84, 0xbfb8aa3b, v33
	v_exp_f32_e32 v84, v84
	s_nop 0
	v_add_f32_e32 v84, 1.0, v84
	v_div_scale_f32 v71, s[28:29], v84, v84, v33
	v_rcp_f32_e32 v82, v71
	s_nop 0
	v_fma_f32 v92, -v71, v82, 1.0
	v_fmac_f32_e32 v82, v92, v82
	v_div_scale_f32 v88, vcc, v33, v84, v33
	v_mul_f32_e32 v90, v88, v82
	v_fma_f32 v92, -v71, v90, v88
	v_fmac_f32_e32 v90, v92, v82
	v_fma_f32 v71, -v71, v90, v88
	v_div_fmas_f32 v71, v71, v82, v90
	v_div_fixup_f32 v33, v71, v84, v33
	v_mul_f32_e32 v70, v70, v33
	v_lshlrev_b32_e32 v34, 16, v34
	v_lshlrev_b32_e32 v79, 16, v79
	v_lshlrev_b32_e32 v78, 16, v78
	v_mul_f32_e32 v78, v16, v78
	v_fmac_f32_e32 v78, v14, v34
	v_fmac_f32_e32 v78, v17, v79
	v_add_f32_e32 v78, v12, v78
	v_fma_f32 v27, v44, v8, v65
	v_mul_f32_e32 v110, v27, v78
	v_lshlrev_b32_e32 v76, 16, v76
	v_mul_f32_e32 v84, 0xbfb8aa3b, v76
	v_exp_f32_e32 v84, v84
	s_nop 0
	v_add_f32_e32 v84, 1.0, v84
	v_div_scale_f32 v71, s[28:29], v84, v84, v76
	v_rcp_f32_e32 v82, v71
	s_nop 0
	v_fma_f32 v92, -v71, v82, 1.0
	v_fmac_f32_e32 v82, v92, v82
	v_div_scale_f32 v88, vcc, v76, v84, v76
	v_mul_f32_e32 v90, v88, v82
	v_fma_f32 v92, -v71, v90, v88
	v_fmac_f32_e32 v90, v92, v82
	v_fma_f32 v71, -v71, v90, v88
	v_div_fmas_f32 v71, v71, v82, v90
	v_div_fixup_f32 v76, v71, v84, v76
	v_mul_f32_e32 v110, v110, v76
	v_cvt_pk_bf16_f32 v70, v70, v110
	v_perm_b32 v110, v70, v205, s98
	v_perm_b32 v70, v70, v205, s99
	global_store_dword v26, v110, s[96:97] offset:-2
	global_store_dword v26, v70, s[18:19] offset:-2
	v_add_u32_e32 v109, 0x1000, v109
	global_load_ushort v9, v109, s[36:37] offset:-2
	global_load_ushort v11, v109, s[36:37]
	global_load_ushort v13, v109, s[36:37] offset:2
	global_load_ushort v15, v109, s[88:89] offset:-2
	global_load_ushort v81, v109, s[88:89]
	global_load_ushort v83, v109, s[88:89] offset:2
	global_load_ushort v85, v109, s[0:1]
	global_load_ushort v87, v109, s[4:5]
	global_load_ushort v89, v109, s[36:37] offset:1022
	global_load_ushort v91, v109, s[36:37] offset:1024
	global_load_ushort v93, v109, s[36:37] offset:1026
	global_load_ushort v94, v109, s[88:89] offset:1022
	global_load_ushort v95, v109, s[88:89] offset:1024
	global_load_ushort v96, v109, s[88:89] offset:1026
	global_load_ushort v97, v109, s[0:1] offset:1024
	global_load_ushort v98, v109, s[4:5] offset:1024
	global_load_ushort v99, v109, s[36:37] offset:2046
	global_load_ushort v100, v109, s[36:37] offset:2048
	global_load_ushort v101, v109, s[36:37] offset:2050
	global_load_ushort v102, v109, s[88:89] offset:2046
	global_load_ushort v103, v109, s[88:89] offset:2048
	global_load_ushort v104, v109, s[88:89] offset:2050
	global_load_ushort v105, v109, s[0:1] offset:2048
	global_load_ushort v106, v109, s[4:5] offset:2048
	global_load_ushort v107, v109, s[36:37] offset:3070
	global_load_ushort v108, v109, s[36:37] offset:3072
	global_load_ushort v32, v109, s[36:37] offset:3074
	global_load_ushort v78, v109, s[88:89] offset:3070
	global_load_ushort v34, v109, s[88:89] offset:3072
	global_load_ushort v79, v109, s[88:89] offset:3074
	global_load_ushort v33, v109, s[0:1] offset:3072
	global_load_ushort v76, v109, s[4:5] offset:3072
	s_waitcnt vmcnt(0)
	v_add_u32_e32 v26, 0x80000, v26
	v_lshlrev_b32_e32 v11, 16, v11
	v_lshlrev_b32_e32 v13, 16, v13
	v_lshlrev_b32_e32 v9, 16, v9
	v_mul_f32_e32 v9, v16, v9
	v_fmac_f32_e32 v9, v14, v11
	v_fmac_f32_e32 v9, v17, v13
	v_add_f32_e32 v9, v12, v9
	v_fma_f32 v27, v47, v8, v22
	v_mul_f32_e32 v70, v27, v9
	v_lshlrev_b32_e32 v85, 16, v85
	v_mul_f32_e32 v84, 0xbfb8aa3b, v85
	v_exp_f32_e32 v84, v84
	s_nop 0
	v_add_f32_e32 v84, 1.0, v84
	v_div_scale_f32 v71, s[28:29], v84, v84, v85
	v_rcp_f32_e32 v82, v71
	s_nop 0
	v_fma_f32 v92, -v71, v82, 1.0
	v_fmac_f32_e32 v82, v92, v82
	v_div_scale_f32 v88, vcc, v85, v84, v85
	v_mul_f32_e32 v90, v88, v82
	v_fma_f32 v92, -v71, v90, v88
	v_fmac_f32_e32 v90, v92, v82
	v_fma_f32 v71, -v71, v90, v88
	v_div_fmas_f32 v71, v71, v82, v90
	v_div_fixup_f32 v85, v71, v84, v85
	v_mul_f32_e32 v70, v70, v85
	v_lshlrev_b32_e32 v81, 16, v81
	v_lshlrev_b32_e32 v83, 16, v83
	v_lshlrev_b32_e32 v15, 16, v15
	v_mul_f32_e32 v15, v16, v15
	v_fmac_f32_e32 v15, v14, v81
	v_fmac_f32_e32 v15, v17, v83
	v_add_f32_e32 v15, v12, v15
	v_fma_f32 v27, v49, v8, v23
	v_mul_f32_e32 v110, v27, v15
	v_lshlrev_b32_e32 v87, 16, v87
	v_mul_f32_e32 v84, 0xbfb8aa3b, v87
	v_exp_f32_e32 v84, v84
	s_nop 0
	v_add_f32_e32 v84, 1.0, v84
	v_div_scale_f32 v71, s[28:29], v84, v84, v87
	v_rcp_f32_e32 v82, v71
	s_nop 0
	v_fma_f32 v92, -v71, v82, 1.0
	v_fmac_f32_e32 v82, v92, v82
	v_div_scale_f32 v88, vcc, v87, v84, v87
	v_mul_f32_e32 v90, v88, v82
	v_fma_f32 v92, -v71, v90, v88
	v_fmac_f32_e32 v90, v92, v82
	v_fma_f32 v71, -v71, v90, v88
	v_div_fmas_f32 v71, v71, v82, v90
	v_div_fixup_f32 v87, v71, v84, v87
	v_mul_f32_e32 v110, v110, v87
	v_cvt_pk_bf16_f32 v70, v70, v110
	v_perm_b32 v110, v70, v206, s98
	v_perm_b32 v70, v70, v206, s99
	global_store_dword v26, v110, s[96:97] offset:-2
	global_store_dword v26, v70, s[18:19] offset:-2
	v_add_u32_e32 v26, 0x80000, v26
	v_lshlrev_b32_e32 v91, 16, v91
	v_lshlrev_b32_e32 v93, 16, v93
	v_lshlrev_b32_e32 v89, 16, v89
	v_mul_f32_e32 v89, v16, v89
	v_fmac_f32_e32 v89, v14, v91
	v_fmac_f32_e32 v89, v17, v93
	v_add_f32_e32 v89, v12, v89
	v_fma_f32 v27, v46, v8, v24
	v_mul_f32_e32 v70, v27, v89
	v_lshlrev_b32_e32 v97, 16, v97
	v_mul_f32_e32 v84, 0xbfb8aa3b, v97
	v_exp_f32_e32 v84, v84
	s_nop 0
	v_add_f32_e32 v84, 1.0, v84
	v_div_scale_f32 v71, s[28:29], v84, v84, v97
	v_rcp_f32_e32 v82, v71
	s_nop 0
	v_fma_f32 v92, -v71, v82, 1.0
	v_fmac_f32_e32 v82, v92, v82
	v_div_scale_f32 v88, vcc, v97, v84, v97
	v_mul_f32_e32 v90, v88, v82
	v_fma_f32 v92, -v71, v90, v88
	v_fmac_f32_e32 v90, v92, v82
	v_fma_f32 v71, -v71, v90, v88
	v_div_fmas_f32 v71, v71, v82, v90
	v_div_fixup_f32 v97, v71, v84, v97
	v_mul_f32_e32 v70, v70, v97
	v_lshlrev_b32_e32 v95, 16, v95
	v_lshlrev_b32_e32 v96, 16, v96
	v_lshlrev_b32_e32 v94, 16, v94
	v_mul_f32_e32 v94, v16, v94
	v_fmac_f32_e32 v94, v14, v95
	v_fmac_f32_e32 v94, v17, v96
	v_add_f32_e32 v94, v12, v94
	v_fma_f32 v27, v48, v8, v25
	v_mul_f32_e32 v110, v27, v94
	v_lshlrev_b32_e32 v98, 16, v98
	v_mul_f32_e32 v84, 0xbfb8aa3b, v98
	v_exp_f32_e32 v84, v84
	s_nop 0
	v_add_f32_e32 v84, 1.0, v84
	v_div_scale_f32 v71, s[28:29], v84, v84, v98
	v_rcp_f32_e32 v82, v71
	s_nop 0
	v_fma_f32 v92, -v71, v82, 1.0
	v_fmac_f32_e32 v82, v92, v82
	v_div_scale_f32 v88, vcc, v98, v84, v98
	v_mul_f32_e32 v90, v88, v82
	v_fma_f32 v92, -v71, v90, v88
	v_fmac_f32_e32 v90, v92, v82
	v_fma_f32 v71, -v71, v90, v88
	v_div_fmas_f32 v71, v71, v82, v90
	v_div_fixup_f32 v98, v71, v84, v98
	v_mul_f32_e32 v110, v110, v98
	v_cvt_pk_bf16_f32 v70, v70, v110
	v_perm_b32 v110, v70, v207, s98
	v_perm_b32 v70, v70, v207, s99
	global_store_dword v26, v110, s[96:97] offset:-2
	global_store_dword v26, v70, s[18:19] offset:-2
	v_add_u32_e32 v26, 0x80000, v26
	v_lshlrev_b32_e32 v100, 16, v100
	v_lshlrev_b32_e32 v101, 16, v101
	v_lshlrev_b32_e32 v99, 16, v99
	v_mul_f32_e32 v99, v16, v99
	v_fmac_f32_e32 v99, v14, v100
	v_fmac_f32_e32 v99, v17, v101
	v_add_f32_e32 v99, v12, v99
	v_fma_f32 v27, v51, v8, v18
	v_mul_f32_e32 v70, v27, v99
	v_lshlrev_b32_e32 v105, 16, v105
	v_mul_f32_e32 v84, 0xbfb8aa3b, v105
	v_exp_f32_e32 v84, v84
	s_nop 0
	v_add_f32_e32 v84, 1.0, v84
	v_div_scale_f32 v71, s[28:29], v84, v84, v105
	v_rcp_f32_e32 v82, v71
	s_nop 0
	v_fma_f32 v92, -v71, v82, 1.0
	v_fmac_f32_e32 v82, v92, v82
	v_div_scale_f32 v88, vcc, v105, v84, v105
	v_mul_f32_e32 v90, v88, v82
	v_fma_f32 v92, -v71, v90, v88
	v_fmac_f32_e32 v90, v92, v82
	v_fma_f32 v71, -v71, v90, v88
	v_div_fmas_f32 v71, v71, v82, v90
	v_div_fixup_f32 v105, v71, v84, v105
	v_mul_f32_e32 v70, v70, v105
	v_lshlrev_b32_e32 v103, 16, v103
	v_lshlrev_b32_e32 v104, 16, v104
	v_lshlrev_b32_e32 v102, 16, v102
	v_mul_f32_e32 v102, v16, v102
	v_fmac_f32_e32 v102, v14, v103
	v_fmac_f32_e32 v102, v17, v104
	v_add_f32_e32 v102, v12, v102
	v_fma_f32 v27, v53, v8, v19
	v_mul_f32_e32 v110, v27, v102
	v_lshlrev_b32_e32 v106, 16, v106
	v_mul_f32_e32 v84, 0xbfb8aa3b, v106
	v_exp_f32_e32 v84, v84
	s_nop 0
	v_add_f32_e32 v84, 1.0, v84
	v_div_scale_f32 v71, s[28:29], v84, v84, v106
	v_rcp_f32_e32 v82, v71
	s_nop 0
	v_fma_f32 v92, -v71, v82, 1.0
	v_fmac_f32_e32 v82, v92, v82
	v_div_scale_f32 v88, vcc, v106, v84, v106
	v_mul_f32_e32 v90, v88, v82
	v_fma_f32 v92, -v71, v90, v88
	v_fmac_f32_e32 v90, v92, v82
	v_fma_f32 v71, -v71, v90, v88
	v_div_fmas_f32 v71, v71, v82, v90
	v_div_fixup_f32 v106, v71, v84, v106
	v_mul_f32_e32 v110, v110, v106
	v_cvt_pk_bf16_f32 v70, v70, v110
	v_perm_b32 v110, v70, v208, s98
	v_perm_b32 v70, v70, v208, s99
	global_store_dword v26, v110, s[96:97] offset:-2
	global_store_dword v26, v70, s[18:19] offset:-2
	v_add_u32_e32 v26, 0x80000, v26
	v_lshlrev_b32_e32 v108, 16, v108
	v_lshlrev_b32_e32 v32, 16, v32
	v_lshlrev_b32_e32 v107, 16, v107
	v_mul_f32_e32 v107, v16, v107
	v_fmac_f32_e32 v107, v14, v108
	v_fmac_f32_e32 v107, v17, v32
	v_add_f32_e32 v107, v12, v107
	v_fma_f32 v27, v50, v8, v20
	v_mul_f32_e32 v70, v27, v107
	v_lshlrev_b32_e32 v33, 16, v33
	v_mul_f32_e32 v84, 0xbfb8aa3b, v33
	v_exp_f32_e32 v84, v84
	s_nop 0
	v_add_f32_e32 v84, 1.0, v84
	v_div_scale_f32 v71, s[28:29], v84, v84, v33
	v_rcp_f32_e32 v82, v71
	s_nop 0
	v_fma_f32 v92, -v71, v82, 1.0
	v_fmac_f32_e32 v82, v92, v82
	v_div_scale_f32 v88, vcc, v33, v84, v33
	v_mul_f32_e32 v90, v88, v82
	v_fma_f32 v92, -v71, v90, v88
	v_fmac_f32_e32 v90, v92, v82
	v_fma_f32 v71, -v71, v90, v88
	v_div_fmas_f32 v71, v71, v82, v90
	v_div_fixup_f32 v33, v71, v84, v33
	v_mul_f32_e32 v70, v70, v33
	v_lshlrev_b32_e32 v34, 16, v34
	v_lshlrev_b32_e32 v79, 16, v79
	v_lshlrev_b32_e32 v78, 16, v78
	v_mul_f32_e32 v78, v16, v78
	v_fmac_f32_e32 v78, v14, v34
	v_fmac_f32_e32 v78, v17, v79
	v_add_f32_e32 v78, v12, v78
	v_fma_f32 v27, v52, v8, v21
	v_mul_f32_e32 v110, v27, v78
	v_lshlrev_b32_e32 v76, 16, v76
	v_mul_f32_e32 v84, 0xbfb8aa3b, v76
	v_exp_f32_e32 v84, v84
	s_nop 0
	v_add_f32_e32 v84, 1.0, v84
	v_div_scale_f32 v71, s[28:29], v84, v84, v76
	v_rcp_f32_e32 v82, v71
	s_nop 0
	v_fma_f32 v92, -v71, v82, 1.0
	v_fmac_f32_e32 v82, v92, v82
	v_div_scale_f32 v88, vcc, v76, v84, v76
	v_mul_f32_e32 v90, v88, v82
	v_fma_f32 v92, -v71, v90, v88
	v_fmac_f32_e32 v90, v92, v82
	v_fma_f32 v71, -v71, v90, v88
	v_div_fmas_f32 v71, v71, v82, v90
	v_div_fixup_f32 v76, v71, v84, v76
	v_mul_f32_e32 v110, v110, v76
	v_cvt_pk_bf16_f32 v70, v70, v110
	v_perm_b32 v110, v70, v209, s98
	v_perm_b32 v70, v70, v209, s99
	global_store_dword v26, v110, s[96:97] offset:-2
	global_store_dword v26, v70, s[18:19] offset:-2
	v_add_u32_e32 v52, 0x1e00, v10
	v_cmp_gt_i32_e32 vcc, 0x1fff, v52
	v_min_i32_e32 v52, 0x1ffe, v52
	v_lshlrev_b32_e32 v52, 1, v52
	s_nop 0
	v_cndmask_b32_e64 v21, 0, 1.0, vcc
	v_add_u32_e32 v109, 0x1000, v109
	global_load_ushort v9, v109, s[36:37] offset:-2
	global_load_ushort v11, v109, s[36:37]
	global_load_ushort v13, v109, s[36:37] offset:2
	global_load_ushort v15, v109, s[88:89] offset:-2
	global_load_ushort v81, v109, s[88:89]
	global_load_ushort v83, v109, s[88:89] offset:2
	global_load_ushort v85, v109, s[0:1]
	global_load_ushort v87, v109, s[4:5]
	global_load_ushort v89, v109, s[36:37] offset:1022
	global_load_ushort v91, v109, s[36:37] offset:1024
	global_load_ushort v93, v109, s[36:37] offset:1026
	global_load_ushort v94, v109, s[88:89] offset:1022
	global_load_ushort v95, v109, s[88:89] offset:1024
	global_load_ushort v96, v109, s[88:89] offset:1026
	global_load_ushort v97, v109, s[0:1] offset:1024
	global_load_ushort v98, v109, s[4:5] offset:1024
	global_load_ushort v99, v109, s[36:37] offset:2046
	global_load_ushort v100, v109, s[36:37] offset:2048
	global_load_ushort v101, v109, s[36:37] offset:2050
	global_load_ushort v102, v109, s[88:89] offset:2046
	global_load_ushort v103, v109, s[88:89] offset:2048
	global_load_ushort v104, v109, s[88:89] offset:2050
	global_load_ushort v105, v109, s[0:1] offset:2048
	global_load_ushort v106, v109, s[4:5] offset:2048
	global_load_ushort v107, v109, s[36:37] offset:3070
	global_load_ushort v108, v109, s[36:37] offset:3072
	global_load_ushort v32, v52, s[36:37] offset:2
	global_load_ushort v78, v109, s[88:89] offset:3070
	global_load_ushort v34, v109, s[88:89] offset:3072
	global_load_ushort v79, v52, s[88:89] offset:2
	global_load_ushort v33, v109, s[0:1] offset:3072
	global_load_ushort v76, v109, s[4:5] offset:3072
	s_waitcnt vmcnt(0)
	v_add_u32_e32 v26, 0x80000, v26
	v_lshlrev_b32_e32 v11, 16, v11
	v_lshlrev_b32_e32 v13, 16, v13
	v_lshlrev_b32_e32 v9, 16, v9
	v_mul_f32_e32 v9, v16, v9
	v_fmac_f32_e32 v9, v14, v11
	v_fmac_f32_e32 v9, v17, v13
	v_add_f32_e32 v9, v12, v9
	v_fma_f32 v27, v55, v8, v4
	v_mul_f32_e32 v70, v27, v9
	v_lshlrev_b32_e32 v85, 16, v85
	v_mul_f32_e32 v84, 0xbfb8aa3b, v85
	v_exp_f32_e32 v84, v84
	s_nop 0
	v_add_f32_e32 v84, 1.0, v84
	v_div_scale_f32 v71, s[28:29], v84, v84, v85
	v_rcp_f32_e32 v82, v71
	s_nop 0
	v_fma_f32 v92, -v71, v82, 1.0
	v_fmac_f32_e32 v82, v92, v82
	v_div_scale_f32 v88, vcc, v85, v84, v85
	v_mul_f32_e32 v90, v88, v82
	v_fma_f32 v92, -v71, v90, v88
	v_fmac_f32_e32 v90, v92, v82
	v_fma_f32 v71, -v71, v90, v88
	v_div_fmas_f32 v71, v71, v82, v90
	v_div_fixup_f32 v85, v71, v84, v85
	v_mul_f32_e32 v70, v70, v85
	v_lshlrev_b32_e32 v81, 16, v81
	v_lshlrev_b32_e32 v83, 16, v83
	v_lshlrev_b32_e32 v15, 16, v15
	v_mul_f32_e32 v15, v16, v15
	v_fmac_f32_e32 v15, v14, v81
	v_fmac_f32_e32 v15, v17, v83
	v_add_f32_e32 v15, v12, v15
	v_fma_f32 v27, v57, v8, v5
	v_mul_f32_e32 v110, v27, v15
	v_lshlrev_b32_e32 v87, 16, v87
	v_mul_f32_e32 v84, 0xbfb8aa3b, v87
	v_exp_f32_e32 v84, v84
	s_nop 0
	v_add_f32_e32 v84, 1.0, v84
	v_div_scale_f32 v71, s[28:29], v84, v84, v87
	v_rcp_f32_e32 v82, v71
	s_nop 0
	v_fma_f32 v92, -v71, v82, 1.0
	v_fmac_f32_e32 v82, v92, v82
	v_div_scale_f32 v88, vcc, v87, v84, v87
	v_mul_f32_e32 v90, v88, v82
	v_fma_f32 v92, -v71, v90, v88
	v_fmac_f32_e32 v90, v92, v82
	v_fma_f32 v71, -v71, v90, v88
	v_div_fmas_f32 v71, v71, v82, v90
	v_div_fixup_f32 v87, v71, v84, v87
	v_mul_f32_e32 v110, v110, v87
	v_cvt_pk_bf16_f32 v70, v70, v110
	v_perm_b32 v110, v70, v210, s98
	v_perm_b32 v70, v70, v210, s99
	global_store_dword v26, v110, s[96:97] offset:-2
	global_store_dword v26, v70, s[18:19] offset:-2
	v_add_u32_e32 v26, 0x80000, v26
	v_lshlrev_b32_e32 v91, 16, v91
	v_lshlrev_b32_e32 v93, 16, v93
	v_lshlrev_b32_e32 v89, 16, v89
	v_mul_f32_e32 v89, v16, v89
	v_fmac_f32_e32 v89, v14, v91
	v_fmac_f32_e32 v89, v17, v93
	v_add_f32_e32 v89, v12, v89
	v_fma_f32 v27, v54, v8, v6
	v_mul_f32_e32 v70, v27, v89
	v_lshlrev_b32_e32 v97, 16, v97
	v_mul_f32_e32 v84, 0xbfb8aa3b, v97
	v_exp_f32_e32 v84, v84
	s_nop 0
	v_add_f32_e32 v84, 1.0, v84
	v_div_scale_f32 v71, s[28:29], v84, v84, v97
	v_rcp_f32_e32 v82, v71
	s_nop 0
	v_fma_f32 v92, -v71, v82, 1.0
	v_fmac_f32_e32 v82, v92, v82
	v_div_scale_f32 v88, vcc, v97, v84, v97
	v_mul_f32_e32 v90, v88, v82
	v_fma_f32 v92, -v71, v90, v88
	v_fmac_f32_e32 v90, v92, v82
	v_fma_f32 v71, -v71, v90, v88
	v_div_fmas_f32 v71, v71, v82, v90
	v_div_fixup_f32 v97, v71, v84, v97
	v_mul_f32_e32 v70, v70, v97
	v_lshlrev_b32_e32 v95, 16, v95
	v_lshlrev_b32_e32 v96, 16, v96
	v_lshlrev_b32_e32 v94, 16, v94
	v_mul_f32_e32 v94, v16, v94
	v_fmac_f32_e32 v94, v14, v95
	v_fmac_f32_e32 v94, v17, v96
	v_add_f32_e32 v94, v12, v94
	v_fma_f32 v27, v56, v8, v7
	v_mul_f32_e32 v110, v27, v94
	v_lshlrev_b32_e32 v98, 16, v98
	v_mul_f32_e32 v84, 0xbfb8aa3b, v98
	v_exp_f32_e32 v84, v84
	s_nop 0
	v_add_f32_e32 v84, 1.0, v84
	v_div_scale_f32 v71, s[28:29], v84, v84, v98
	v_rcp_f32_e32 v82, v71
	s_nop 0
	v_fma_f32 v92, -v71, v82, 1.0
	v_fmac_f32_e32 v82, v92, v82
	v_div_scale_f32 v88, vcc, v98, v84, v98
	v_mul_f32_e32 v90, v88, v82
	v_fma_f32 v92, -v71, v90, v88
	v_fmac_f32_e32 v90, v92, v82
	v_fma_f32 v71, -v71, v90, v88
	v_div_fmas_f32 v71, v71, v82, v90
	v_div_fixup_f32 v98, v71, v84, v98
	v_mul_f32_e32 v110, v110, v98
	v_cvt_pk_bf16_f32 v70, v70, v110
	v_perm_b32 v110, v70, v211, s98
	v_perm_b32 v70, v70, v211, s99
	global_store_dword v26, v110, s[96:97] offset:-2
	global_store_dword v26, v70, s[18:19] offset:-2
	v_add_u32_e32 v26, 0x80000, v26
	v_lshlrev_b32_e32 v100, 16, v100
	v_lshlrev_b32_e32 v101, 16, v101
	v_lshlrev_b32_e32 v99, 16, v99
	v_mul_f32_e32 v99, v16, v99
	v_fmac_f32_e32 v99, v14, v100
	v_fmac_f32_e32 v99, v17, v101
	v_add_f32_e32 v99, v12, v99
	v_fma_f32 v27, v59, v8, v0
	v_mul_f32_e32 v70, v27, v99
	v_lshlrev_b32_e32 v105, 16, v105
	v_mul_f32_e32 v84, 0xbfb8aa3b, v105
	v_exp_f32_e32 v84, v84
	s_nop 0
	v_add_f32_e32 v84, 1.0, v84
	v_div_scale_f32 v71, s[28:29], v84, v84, v105
	v_rcp_f32_e32 v82, v71
	s_nop 0
	v_fma_f32 v92, -v71, v82, 1.0
	v_fmac_f32_e32 v82, v92, v82
	v_div_scale_f32 v88, vcc, v105, v84, v105
	v_mul_f32_e32 v90, v88, v82
	v_fma_f32 v92, -v71, v90, v88
	v_fmac_f32_e32 v90, v92, v82
	v_fma_f32 v71, -v71, v90, v88
	v_div_fmas_f32 v71, v71, v82, v90
	v_div_fixup_f32 v105, v71, v84, v105
	v_mul_f32_e32 v70, v70, v105
	v_lshlrev_b32_e32 v103, 16, v103
	v_lshlrev_b32_e32 v104, 16, v104
	v_lshlrev_b32_e32 v102, 16, v102
	v_mul_f32_e32 v102, v16, v102
	v_fmac_f32_e32 v102, v14, v103
	v_fmac_f32_e32 v102, v17, v104
	v_add_f32_e32 v102, v12, v102
	v_fma_f32 v27, v61, v8, v1
	v_mul_f32_e32 v110, v27, v102
	v_lshlrev_b32_e32 v106, 16, v106
	v_mul_f32_e32 v84, 0xbfb8aa3b, v106
	v_exp_f32_e32 v84, v84
	s_nop 0
	v_add_f32_e32 v84, 1.0, v84
	v_div_scale_f32 v71, s[28:29], v84, v84, v106
	v_rcp_f32_e32 v82, v71
	s_nop 0
	v_fma_f32 v92, -v71, v82, 1.0
	v_fmac_f32_e32 v82, v92, v82
	v_div_scale_f32 v88, vcc, v106, v84, v106
	v_mul_f32_e32 v90, v88, v82
	v_fma_f32 v92, -v71, v90, v88
	v_fmac_f32_e32 v90, v92, v82
	v_fma_f32 v71, -v71, v90, v88
	v_div_fmas_f32 v71, v71, v82, v90
	v_div_fixup_f32 v106, v71, v84, v106
	v_mul_f32_e32 v110, v110, v106
	v_cvt_pk_bf16_f32 v70, v70, v110
	v_perm_b32 v110, v70, v212, s98
	v_perm_b32 v70, v70, v212, s99
	global_store_dword v26, v110, s[96:97] offset:-2
	global_store_dword v26, v70, s[18:19] offset:-2
	v_add_u32_e32 v26, 0x80000, v26
	v_lshlrev_b32_e32 v108, 16, v108
	v_lshlrev_b32_e32 v32, 16, v32
	v_lshlrev_b32_e32 v107, 16, v107
	v_mul_f32_e32 v107, v16, v107
	v_mul_f32_e32 v32, v21, v32
	v_fmac_f32_e32 v107, v14, v108
	v_fmac_f32_e32 v107, v17, v32
	v_add_f32_e32 v107, v12, v107
	v_fma_f32 v27, v58, v8, v2
	v_mul_f32_e32 v70, v27, v107
	v_lshlrev_b32_e32 v33, 16, v33
	v_mul_f32_e32 v84, 0xbfb8aa3b, v33
	v_exp_f32_e32 v84, v84
	s_nop 0
	v_add_f32_e32 v84, 1.0, v84
	v_div_scale_f32 v71, s[28:29], v84, v84, v33
	v_rcp_f32_e32 v82, v71
	s_nop 0
	v_fma_f32 v92, -v71, v82, 1.0
	v_fmac_f32_e32 v82, v92, v82
	v_div_scale_f32 v88, vcc, v33, v84, v33
	v_mul_f32_e32 v90, v88, v82
	v_fma_f32 v92, -v71, v90, v88
	v_fmac_f32_e32 v90, v92, v82
	v_fma_f32 v71, -v71, v90, v88
	v_div_fmas_f32 v71, v71, v82, v90
	v_div_fixup_f32 v33, v71, v84, v33
	v_mul_f32_e32 v70, v70, v33
	v_lshlrev_b32_e32 v34, 16, v34
	v_lshlrev_b32_e32 v79, 16, v79
	v_lshlrev_b32_e32 v78, 16, v78
	v_mul_f32_e32 v78, v16, v78
	v_mul_f32_e32 v79, v21, v79
	v_fmac_f32_e32 v78, v14, v34
	v_fmac_f32_e32 v78, v17, v79
	v_add_f32_e32 v78, v12, v78
	v_fma_f32 v27, v60, v8, v3
	v_mul_f32_e32 v110, v27, v78
	v_lshlrev_b32_e32 v76, 16, v76
	v_mul_f32_e32 v84, 0xbfb8aa3b, v76
	v_exp_f32_e32 v84, v84
	s_nop 0
	v_add_f32_e32 v84, 1.0, v84
	v_div_scale_f32 v71, s[28:29], v84, v84, v76
	v_rcp_f32_e32 v82, v71
	s_nop 0
	v_fma_f32 v92, -v71, v82, 1.0
	v_fmac_f32_e32 v82, v92, v82
	v_div_scale_f32 v88, vcc, v76, v84, v76
	v_mul_f32_e32 v90, v88, v82
	v_fma_f32 v92, -v71, v90, v88
	v_fmac_f32_e32 v90, v92, v82
	v_fma_f32 v71, -v71, v90, v88
	v_div_fmas_f32 v71, v71, v82, v90
	v_div_fixup_f32 v76, v71, v84, v76
	v_mul_f32_e32 v110, v110, v76
	v_cvt_pk_bf16_f32 v70, v70, v110
	v_perm_b32 v110, v70, v213, s98
	v_perm_b32 v70, v70, v213, s99
	global_store_dword v26, v110, s[96:97] offset:-2
	global_store_dword v26, v70, s[18:19] offset:-2
.Lhy_ep1_done_L0:
	s_mov_b64 s[28:29], 0

.LBB0_908:
	s_nop 1
	v_lshlrev_b32_e32 v0, 2, v146
	s_add_i32 s79, 16, 0x10000
	v_add_u32_e32 v64, 16, v0
	v_add_u32_e32 v65, s79, v0
	s_waitcnt lgkmcnt(0)
	s_barrier
	ds_read2st64_b32 v[2:3], v64 offset1:8
	ds_read2st64_b32 v[4:5], v65 offset1:8
	ds_read2st64_b32 v[8:9], v64 offset0:16 offset1:24
	ds_read2st64_b32 v[10:11], v65 offset0:16 offset1:24
	ds_read2st64_b32 v[12:13], v64 offset0:32 offset1:40
	ds_read2st64_b32 v[14:15], v65 offset0:32 offset1:40
	s_mov_b32 s47, s40
	s_waitcnt lgkmcnt(5)
	v_mov_b32_e32 v6, v2
	s_waitcnt lgkmcnt(4)
	v_mov_b32_e32 v7, v4
	v_mov_b32_e32 v4, v3
	s_waitcnt lgkmcnt(3)
	v_mov_b32_e32 v2, v8
	s_waitcnt lgkmcnt(2)
	v_mov_b32_e32 v3, v10
	v_mov_b32_e32 v10, v9
	ds_read2st64_b32 v[8:9], v64 offset0:48 offset1:56
	ds_read2st64_b32 v[16:17], v65 offset0:48 offset1:56
	s_waitcnt lgkmcnt(3)
	v_mov_b32_e32 v18, v12
	s_waitcnt lgkmcnt(2)
	v_mov_b32_e32 v19, v14
	v_mov_b32_e32 v14, v13
	s_waitcnt lgkmcnt(1)
	v_mov_b32_e32 v12, v8
	s_waitcnt lgkmcnt(0)
	v_mov_b32_e32 v13, v16
	ds_read2st64_b32 v[20:21], v64 offset0:64 offset1:72
	ds_read2st64_b32 v[22:23], v65 offset0:64 offset1:72
	v_mov_b32_e32 v16, v9
	ds_read2st64_b32 v[8:9], v64 offset0:80 offset1:88
	ds_read2st64_b32 v[24:25], v65 offset0:80 offset1:88
	s_mov_b32 s41, s43
	s_waitcnt lgkmcnt(3)
	v_mov_b32_e32 v26, v20
	s_waitcnt lgkmcnt(2)
	v_mov_b32_e32 v27, v22
	v_mov_b32_e32 v22, v21
	s_waitcnt lgkmcnt(1)
	v_mov_b32_e32 v28, v8
	s_waitcnt lgkmcnt(0)
	v_mov_b32_e32 v29, v24
	ds_read2st64_b32 v[20:21], v64 offset0:96 offset1:104
	ds_read2st64_b32 v[30:31], v65 offset0:96 offset1:104
	v_mov_b32_e32 v24, v9
	ds_read2st64_b32 v[8:9], v64 offset0:112 offset1:120
	ds_read2st64_b32 v[32:33], v65 offset0:112 offset1:120
	v_and_b32_e32 v196, 63, v146
	v_lshlrev_b32_e32 v196, 2, v196
	v_and_b32_e32 v0, 0xffffffc0, v146
	v_lshl_add_u32 v0, v0, 5, v196
	v_add_u32_e32 v0, 0x400, v0
	s_waitcnt lgkmcnt(3)
	v_mov_b32_e32 v34, v20
	s_waitcnt lgkmcnt(2)
	v_mov_b32_e32 v35, v30
	v_mov_b32_e32 v30, v21
	s_waitcnt lgkmcnt(1)
	v_mov_b32_e32 v36, v8
	s_waitcnt lgkmcnt(0)
	v_mov_b32_e32 v37, v32
	ds_read2st64_b32 v[20:21], v64 offset0:128 offset1:136
	ds_read2st64_b32 v[38:39], v65 offset0:128 offset1:136
	v_mov_b32_e32 v32, v9
	ds_read2st64_b32 v[8:9], v64 offset0:144 offset1:152
	ds_read2st64_b32 v[40:41], v65 offset0:144 offset1:152
	v_readlane_b32 s0, v252, 48
	s_waitcnt lgkmcnt(3)
	v_mov_b32_e32 v42, v20
	s_waitcnt lgkmcnt(2)
	v_mov_b32_e32 v43, v38
	v_mov_b32_e32 v38, v21
	s_waitcnt lgkmcnt(1)
	v_mov_b32_e32 v44, v8
	s_waitcnt lgkmcnt(0)
	v_mov_b32_e32 v45, v40
	ds_read2st64_b32 v[20:21], v64 offset0:160 offset1:168
	ds_read2st64_b32 v[46:47], v65 offset0:160 offset1:168
	v_mov_b32_e32 v40, v9
	ds_read2st64_b32 v[8:9], v64 offset0:176 offset1:184
	ds_read2st64_b32 v[48:49], v65 offset0:176 offset1:184
	v_ashrrev_i32_e32 v1, 31, v0
	s_waitcnt lgkmcnt(3)
	v_mov_b32_e32 v50, v20
	s_waitcnt lgkmcnt(2)
	v_mov_b32_e32 v51, v46
	v_mov_b32_e32 v46, v21
	s_waitcnt lgkmcnt(1)
	v_mov_b32_e32 v52, v8
	s_waitcnt lgkmcnt(0)
	v_mov_b32_e32 v53, v48
	ds_read2st64_b32 v[20:21], v64 offset0:192 offset1:200
	ds_read2st64_b32 v[54:55], v65 offset0:192 offset1:200
	v_mov_b32_e32 v48, v9
	ds_read2st64_b32 v[8:9], v64 offset0:208 offset1:216
	ds_read2st64_b32 v[56:57], v65 offset0:208 offset1:216
	v_readlane_b32 s1, v252, 49
	s_waitcnt lgkmcnt(3)
	v_mov_b32_e32 v58, v20
	s_waitcnt lgkmcnt(2)
	v_mov_b32_e32 v59, v54
	v_mov_b32_e32 v54, v21
	s_waitcnt lgkmcnt(1)
	v_mov_b32_e32 v60, v8
	s_waitcnt lgkmcnt(0)
	v_mov_b32_e32 v61, v56
	ds_read2st64_b32 v[20:21], v64 offset0:224 offset1:232
	ds_read2st64_b32 v[62:63], v65 offset0:224 offset1:232
	v_mov_b32_e32 v56, v9
	ds_read2st64_b32 v[8:9], v64 offset0:240 offset1:248
	ds_read2st64_b32 v[64:65], v65 offset0:240 offset1:248
	s_waitcnt lgkmcnt(0)
	v_mov_b32_e32 v66, v20
	v_mov_b32_e32 v67, v62
	v_mov_b32_e32 v72, v8
	v_mov_b32_e32 v73, v64
	v_mov_b32_e32 v64, v9
	v_pk_add_f32 v[8:9], v[6:7], v[42:43]
	v_pk_add_f32 v[6:7], v[6:7], v[42:43] neg_lo:[0,1] neg_hi:[0,1]
	v_pk_add_f32 v[42:43], v[4:5], v[38:39]
	v_pk_add_f32 v[4:5], v[4:5], v[38:39] neg_lo:[0,1] neg_hi:[0,1]
	v_mov_b32_e32 v62, v21
	v_pk_mul_f32 v[38:39], v[4:5], s[48:49] op_sel:[1,0] op_sel_hi:[0,0] neg_hi:[1,0]
	v_mov_b32_e32 v21, v146
	v_pk_fma_f32 v[4:5], v[4:5], s[44:45], v[38:39] op_sel_hi:[1,0,1]
	v_pk_add_f32 v[38:39], v[2:3], v[44:45]
	v_pk_add_f32 v[2:3], v[2:3], v[44:45] neg_lo:[0,1] neg_hi:[0,1]
	s_barrier
	s_nop 0
	s_nop 0
	v_pk_mul_f32 v[44:45], v[2:3], s[54:55] op_sel:[1,0] op_sel_hi:[0,0] neg_hi:[1,0]
	s_nop 0
	v_pk_fma_f32 v[2:3], v[2:3], s[52:53], v[44:45] op_sel_hi:[1,0,1]
	v_pk_add_f32 v[44:45], v[10:11], v[40:41]
	v_pk_add_f32 v[10:11], v[10:11], v[40:41] neg_lo:[0,1] neg_hi:[0,1]
	s_lshl_b64 s[10:11], s[62:63], 2
	s_nop 0
	s_nop 0
	v_pk_mul_f32 v[40:41], v[10:11], s[58:59] op_sel:[1,0] op_sel_hi:[0,0] neg_hi:[1,0]
	v_add_u32_e32 v70, 0x200, v146
	v_pk_fma_f32 v[10:11], v[10:11], s[56:57], v[40:41] op_sel_hi:[1,0,1]
	v_pk_add_f32 v[40:41], v[18:19], v[50:51]
	v_pk_add_f32 v[18:19], v[18:19], v[50:51] neg_lo:[0,1] neg_hi:[0,1]
	v_ashrrev_i32_e32 v147, 31, v146
	s_nop 0
	s_nop 0
	v_pk_mul_f32 v[50:51], v[18:19], s[60:61] op_sel:[1,0] op_sel_hi:[0,0] neg_hi:[1,0]
	v_add_u32_e32 v69, 0x400, v146
	v_pk_fma_f32 v[18:19], v[18:19], s[60:61], v[50:51] op_sel_hi:[1,0,1]
	v_pk_add_f32 v[50:51], v[14:15], v[46:47]
	v_pk_add_f32 v[14:15], v[14:15], v[46:47] neg_lo:[0,1] neg_hi:[0,1]
	v_add_u32_e32 v68, 0x600, v146
	v_pk_mul_f32 v[46:47], v[14:15], s[56:57] op_sel:[1,0] op_sel_hi:[0,0] neg_hi:[1,0]
	s_mov_b32 s16, 0
	v_pk_fma_f32 v[14:15], v[14:15], s[58:59], v[46:47] op_sel_hi:[1,0,1]
	v_pk_add_f32 v[46:47], v[12:13], v[52:53]
	v_pk_add_f32 v[12:13], v[12:13], v[52:53] neg_lo:[0,1] neg_hi:[0,1]
	s_nop 0
	v_pk_mul_f32 v[52:53], v[12:13], s[52:53] op_sel:[1,0] op_sel_hi:[0,0] neg_hi:[1,0]
	s_nop 0
	v_pk_fma_f32 v[12:13], v[12:13], s[54:55], v[52:53] op_sel_hi:[1,0,1]
	v_pk_add_f32 v[52:53], v[16:17], v[48:49]
	v_pk_add_f32 v[16:17], v[16:17], v[48:49] neg_lo:[0,1] neg_hi:[0,1]
	s_nop 0
	v_pk_mul_f32 v[48:49], v[16:17], s[44:45] op_sel:[1,0] op_sel_hi:[0,0] neg_hi:[1,0]
	s_nop 0
	v_pk_fma_f32 v[16:17], v[16:17], s[48:49], v[48:49] op_sel_hi:[1,0,1]
	v_pk_add_f32 v[48:49], v[26:27], v[58:59]
	v_pk_add_f32 v[26:27], v[26:27], v[58:59] neg_lo:[0,1] neg_hi:[0,1]
	s_nop 0
	v_xor_b32_e32 v59, 0x80000000, v26
	v_mov_b32_e32 v58, v27
	v_pk_add_f32 v[26:27], v[22:23], v[54:55]
	v_pk_add_f32 v[22:23], v[22:23], v[54:55] neg_lo:[0,1] neg_hi:[0,1]
	s_nop 0
	v_pk_mul_f32 v[54:55], v[22:23], s[48:49] op_sel_hi:[1,0]
	v_xor_b32_e32 v75, 0x80000000, v22
	v_mov_b32_e32 v74, v23
	v_pk_fma_f32 v[22:23], v[74:75], s[44:45], v[54:55] op_sel_hi:[1,0,1] neg_lo:[0,0,1] neg_hi:[0,0,1]
	v_pk_add_f32 v[54:55], v[28:29], v[60:61]
	v_pk_add_f32 v[28:29], v[28:29], v[60:61] neg_lo:[0,1] neg_hi:[0,1]
	s_nop 0
	v_pk_mul_f32 v[60:61], v[28:29], s[54:55] op_sel_hi:[1,0]
	v_xor_b32_e32 v75, 0x80000000, v28
	v_mov_b32_e32 v74, v29
	v_pk_fma_f32 v[28:29], v[74:75], s[52:53], v[60:61] op_sel_hi:[1,0,1] neg_lo:[0,0,1] neg_hi:[0,0,1]
	v_pk_add_f32 v[60:61], v[24:25], v[56:57]
	v_pk_add_f32 v[24:25], v[24:25], v[56:57] neg_lo:[0,1] neg_hi:[0,1]
	s_nop 0
	v_pk_mul_f32 v[56:57], v[24:25], s[58:59] op_sel_hi:[1,0]
	v_xor_b32_e32 v75, 0x80000000, v24
	v_mov_b32_e32 v74, v25
	v_pk_fma_f32 v[24:25], v[74:75], s[56:57], v[56:57] op_sel_hi:[1,0,1] neg_lo:[0,0,1] neg_hi:[0,0,1]
	v_pk_add_f32 v[56:57], v[34:35], v[66:67]
	v_pk_add_f32 v[34:35], v[34:35], v[66:67] neg_lo:[0,1] neg_hi:[0,1]
	s_nop 0
	v_pk_mul_f32 v[66:67], v[34:35], s[60:61] op_sel_hi:[1,0]
	v_xor_b32_e32 v75, 0x80000000, v34
	v_mov_b32_e32 v74, v35
	v_pk_fma_f32 v[34:35], v[74:75], s[60:61], v[66:67] op_sel_hi:[1,0,1] neg_lo:[0,0,1] neg_hi:[0,0,1]
	v_pk_add_f32 v[66:67], v[30:31], v[62:63]
	v_pk_add_f32 v[30:31], v[30:31], v[62:63] neg_lo:[0,1] neg_hi:[0,1]
	s_nop 0
	v_pk_mul_f32 v[62:63], v[30:31], s[56:57] op_sel_hi:[1,0]
	v_xor_b32_e32 v75, 0x80000000, v30
	v_mov_b32_e32 v74, v31
	v_pk_fma_f32 v[30:31], v[74:75], s[58:59], v[62:63] op_sel_hi:[1,0,1] neg_lo:[0,0,1] neg_hi:[0,0,1]
	v_pk_add_f32 v[62:63], v[36:37], v[72:73]
	v_pk_add_f32 v[36:37], v[36:37], v[72:73] neg_lo:[0,1] neg_hi:[0,1]
	s_nop 0
	v_pk_mul_f32 v[72:73], v[36:37], s[52:53] op_sel_hi:[1,0]
	v_xor_b32_e32 v75, 0x80000000, v36
	v_mov_b32_e32 v74, v37
	v_pk_fma_f32 v[36:37], v[74:75], s[54:55], v[72:73] op_sel_hi:[1,0,1] neg_lo:[0,0,1] neg_hi:[0,0,1]
	v_pk_add_f32 v[72:73], v[32:33], v[64:65]
	v_pk_add_f32 v[32:33], v[32:33], v[64:65] neg_lo:[0,1] neg_hi:[0,1]
	s_nop 0
	v_pk_mul_f32 v[64:65], v[32:33], s[44:45] op_sel_hi:[1,0]
	v_xor_b32_e32 v75, 0x80000000, v32
	v_mov_b32_e32 v74, v33
	v_pk_fma_f32 v[32:33], v[74:75], s[48:49], v[64:65] op_sel_hi:[1,0,1] neg_lo:[0,0,1] neg_hi:[0,0,1]
	v_pk_add_f32 v[64:65], v[8:9], v[48:49]
	v_pk_add_f32 v[8:9], v[8:9], v[48:49] neg_lo:[0,1] neg_hi:[0,1]
	v_pk_add_f32 v[48:49], v[42:43], v[26:27]
	v_pk_add_f32 v[26:27], v[42:43], v[26:27] neg_lo:[0,1] neg_hi:[0,1]
	s_nop 0
	v_pk_mul_f32 v[42:43], v[26:27], s[54:55] op_sel:[1,0] op_sel_hi:[0,0] neg_hi:[1,0]
	s_nop 0
	v_pk_fma_f32 v[26:27], v[26:27], s[52:53], v[42:43] op_sel_hi:[1,0,1]
	v_pk_add_f32 v[42:43], v[38:39], v[54:55]
	v_pk_add_f32 v[38:39], v[38:39], v[54:55] neg_lo:[0,1] neg_hi:[0,1]
	s_nop 0
	v_pk_mul_f32 v[54:55], v[38:39], s[60:61] op_sel:[1,0] op_sel_hi:[0,0] neg_hi:[1,0]
	s_nop 0
	v_pk_fma_f32 v[38:39], v[38:39], s[60:61], v[54:55] op_sel_hi:[1,0,1]
	v_pk_add_f32 v[54:55], v[44:45], v[60:61]
	v_pk_add_f32 v[44:45], v[44:45], v[60:61] neg_lo:[0,1] neg_hi:[0,1]
	s_nop 0
	v_pk_mul_f32 v[60:61], v[44:45], s[52:53] op_sel:[1,0] op_sel_hi:[0,0] neg_hi:[1,0]
	s_nop 0
	v_pk_fma_f32 v[44:45], v[44:45], s[54:55], v[60:61] op_sel_hi:[1,0,1]
	v_pk_add_f32 v[60:61], v[40:41], v[56:57]
	v_pk_add_f32 v[40:41], v[40:41], v[56:57] neg_lo:[0,1] neg_hi:[0,1]
	s_nop 0
	v_xor_b32_e32 v57, 0x80000000, v40
	v_mov_b32_e32 v56, v41
	v_pk_add_f32 v[40:41], v[50:51], v[66:67]
	v_pk_add_f32 v[50:51], v[50:51], v[66:67] neg_lo:[0,1] neg_hi:[0,1]
	s_nop 0
	v_pk_mul_f32 v[66:67], v[50:51], s[54:55] op_sel_hi:[1,0]
	v_xor_b32_e32 v75, 0x80000000, v50
	v_mov_b32_e32 v74, v51
	v_pk_fma_f32 v[50:51], v[74:75], s[52:53], v[66:67] op_sel_hi:[1,0,1] neg_lo:[0,0,1] neg_hi:[0,0,1]
	v_pk_add_f32 v[66:67], v[46:47], v[62:63]
	v_pk_add_f32 v[46:47], v[46:47], v[62:63] neg_lo:[0,1] neg_hi:[0,1]
	s_nop 0
	v_pk_mul_f32 v[62:63], v[46:47], s[60:61] op_sel_hi:[1,0]
	v_xor_b32_e32 v75, 0x80000000, v46
	v_mov_b32_e32 v74, v47
	v_pk_fma_f32 v[46:47], v[74:75], s[60:61], v[62:63] op_sel_hi:[1,0,1] neg_lo:[0,0,1] neg_hi:[0,0,1]
	v_pk_add_f32 v[62:63], v[52:53], v[72:73]
	v_pk_add_f32 v[52:53], v[52:53], v[72:73] neg_lo:[0,1] neg_hi:[0,1]
	s_nop 0
	v_pk_mul_f32 v[72:73], v[52:53], s[52:53] op_sel_hi:[1,0]
	v_xor_b32_e32 v75, 0x80000000, v52
	v_mov_b32_e32 v74, v53
	v_pk_fma_f32 v[52:53], v[74:75], s[54:55], v[72:73] op_sel_hi:[1,0,1] neg_lo:[0,0,1] neg_hi:[0,0,1]
	v_pk_add_f32 v[72:73], v[6:7], v[58:59]
	v_pk_add_f32 v[6:7], v[6:7], v[58:59] neg_lo:[0,1] neg_hi:[0,1]
	v_pk_add_f32 v[58:59], v[4:5], v[22:23]
	v_pk_add_f32 v[4:5], v[4:5], v[22:23] neg_lo:[0,1] neg_hi:[0,1]
	s_nop 0
	v_pk_mul_f32 v[22:23], v[4:5], s[54:55] op_sel:[1,0] op_sel_hi:[0,0] neg_hi:[1,0]
	s_nop 0
	v_pk_fma_f32 v[4:5], v[4:5], s[52:53], v[22:23] op_sel_hi:[1,0,1]
	v_pk_add_f32 v[22:23], v[2:3], v[28:29]
	v_pk_add_f32 v[2:3], v[2:3], v[28:29] neg_lo:[0,1] neg_hi:[0,1]
	s_nop 0
	v_pk_mul_f32 v[28:29], v[2:3], s[60:61] op_sel:[1,0] op_sel_hi:[0,0] neg_hi:[1,0]
	s_nop 0
	v_pk_fma_f32 v[2:3], v[2:3], s[60:61], v[28:29] op_sel_hi:[1,0,1]
	v_pk_add_f32 v[28:29], v[10:11], v[24:25]
	v_pk_add_f32 v[10:11], v[10:11], v[24:25] neg_lo:[0,1] neg_hi:[0,1]
	s_nop 0
	v_pk_mul_f32 v[24:25], v[10:11], s[52:53] op_sel:[1,0] op_sel_hi:[0,0] neg_hi:[1,0]
	s_nop 0
	v_pk_fma_f32 v[10:11], v[10:11], s[54:55], v[24:25] op_sel_hi:[1,0,1]
	v_pk_add_f32 v[24:25], v[18:19], v[34:35]
	v_pk_add_f32 v[18:19], v[18:19], v[34:35] neg_lo:[0,1] neg_hi:[0,1]
	s_nop 0
	v_xor_b32_e32 v35, 0x80000000, v18
	v_mov_b32_e32 v34, v19
	v_pk_add_f32 v[18:19], v[14:15], v[30:31]
	v_pk_add_f32 v[14:15], v[14:15], v[30:31] neg_lo:[0,1] neg_hi:[0,1]
	s_nop 0
	v_pk_mul_f32 v[30:31], v[14:15], s[54:55] op_sel_hi:[1,0]
	v_xor_b32_e32 v75, 0x80000000, v14
	v_mov_b32_e32 v74, v15
	v_pk_fma_f32 v[14:15], v[74:75], s[52:53], v[30:31] op_sel_hi:[1,0,1] neg_lo:[0,0,1] neg_hi:[0,0,1]
	v_pk_add_f32 v[30:31], v[12:13], v[36:37]
	v_pk_add_f32 v[12:13], v[12:13], v[36:37] neg_lo:[0,1] neg_hi:[0,1]
	s_nop 0
	v_pk_mul_f32 v[36:37], v[12:13], s[60:61] op_sel_hi:[1,0]
	v_xor_b32_e32 v75, 0x80000000, v12
	v_mov_b32_e32 v74, v13
	v_pk_fma_f32 v[12:13], v[74:75], s[60:61], v[36:37] op_sel_hi:[1,0,1] neg_lo:[0,0,1] neg_hi:[0,0,1]
	v_pk_add_f32 v[36:37], v[16:17], v[32:33]
	v_pk_add_f32 v[16:17], v[16:17], v[32:33] neg_lo:[0,1] neg_hi:[0,1]
	s_nop 0
	v_pk_mul_f32 v[32:33], v[16:17], s[52:53] op_sel_hi:[1,0]
	v_xor_b32_e32 v75, 0x80000000, v16
	v_mov_b32_e32 v74, v17
	v_pk_fma_f32 v[16:17], v[74:75], s[54:55], v[32:33] op_sel_hi:[1,0,1] neg_lo:[0,0,1] neg_hi:[0,0,1]
	v_pk_add_f32 v[32:33], v[64:65], v[60:61]
	v_pk_add_f32 v[60:61], v[64:65], v[60:61] neg_lo:[0,1] neg_hi:[0,1]
	v_pk_add_f32 v[64:65], v[48:49], v[40:41]
	v_pk_add_f32 v[40:41], v[48:49], v[40:41] neg_lo:[0,1] neg_hi:[0,1]
	s_nop 0
	v_pk_mul_f32 v[48:49], v[40:41], s[60:61] op_sel:[1,0] op_sel_hi:[0,0] neg_hi:[1,0]
	s_nop 0
	v_pk_fma_f32 v[40:41], v[40:41], s[60:61], v[48:49] op_sel_hi:[1,0,1]
	v_pk_add_f32 v[48:49], v[42:43], v[66:67]
	v_pk_add_f32 v[42:43], v[42:43], v[66:67] neg_lo:[0,1] neg_hi:[0,1]
	s_nop 0
	v_xor_b32_e32 v67, 0x80000000, v42
	v_mov_b32_e32 v66, v43
	v_pk_add_f32 v[42:43], v[54:55], v[62:63]
	v_pk_add_f32 v[54:55], v[54:55], v[62:63] neg_lo:[0,1] neg_hi:[0,1]
	s_nop 0
	v_pk_mul_f32 v[62:63], v[54:55], s[60:61] op_sel_hi:[1,0]
	v_xor_b32_e32 v75, 0x80000000, v54
	v_mov_b32_e32 v74, v55
	v_pk_fma_f32 v[54:55], v[74:75], s[60:61], v[62:63] op_sel_hi:[1,0,1] neg_lo:[0,0,1] neg_hi:[0,0,1]
	v_pk_add_f32 v[62:63], v[8:9], v[56:57]
	v_pk_add_f32 v[8:9], v[8:9], v[56:57] neg_lo:[0,1] neg_hi:[0,1]
	v_pk_add_f32 v[56:57], v[26:27], v[50:51]
	v_pk_add_f32 v[26:27], v[26:27], v[50:51] neg_lo:[0,1] neg_hi:[0,1]
	s_nop 0
	v_pk_mul_f32 v[50:51], v[26:27], s[60:61] op_sel:[1,0] op_sel_hi:[0,0] neg_hi:[1,0]
	s_nop 0
	v_pk_fma_f32 v[26:27], v[26:27], s[60:61], v[50:51] op_sel_hi:[1,0,1]
	v_pk_add_f32 v[50:51], v[38:39], v[46:47]
	v_pk_add_f32 v[38:39], v[38:39], v[46:47] neg_lo:[0,1] neg_hi:[0,1]
	s_nop 0
	v_xor_b32_e32 v47, 0x80000000, v38
	v_mov_b32_e32 v46, v39
	v_pk_add_f32 v[38:39], v[44:45], v[52:53]
	v_pk_add_f32 v[44:45], v[44:45], v[52:53] neg_lo:[0,1] neg_hi:[0,1]
	s_nop 0
	v_pk_mul_f32 v[52:53], v[44:45], s[60:61] op_sel_hi:[1,0]
	v_xor_b32_e32 v75, 0x80000000, v44
	v_mov_b32_e32 v74, v45
	v_pk_fma_f32 v[44:45], v[74:75], s[60:61], v[52:53] op_sel_hi:[1,0,1] neg_lo:[0,0,1] neg_hi:[0,0,1]
	v_pk_add_f32 v[52:53], v[72:73], v[24:25]
	v_pk_add_f32 v[24:25], v[72:73], v[24:25] neg_lo:[0,1] neg_hi:[0,1]
	v_pk_add_f32 v[72:73], v[58:59], v[18:19]
	v_pk_add_f32 v[18:19], v[58:59], v[18:19] neg_lo:[0,1] neg_hi:[0,1]
	s_nop 0
	v_pk_mul_f32 v[58:59], v[18:19], s[60:61] op_sel:[1,0] op_sel_hi:[0,0] neg_hi:[1,0]
	s_nop 0
	v_pk_fma_f32 v[18:19], v[18:19], s[60:61], v[58:59] op_sel_hi:[1,0,1]
	v_pk_add_f32 v[58:59], v[22:23], v[30:31]
	v_pk_add_f32 v[22:23], v[22:23], v[30:31] neg_lo:[0,1] neg_hi:[0,1]
	s_nop 0
	v_xor_b32_e32 v31, 0x80000000, v22
	v_mov_b32_e32 v30, v23
	v_pk_add_f32 v[22:23], v[28:29], v[36:37]
	v_pk_add_f32 v[28:29], v[28:29], v[36:37] neg_lo:[0,1] neg_hi:[0,1]
	v_pk_add_f32 v[76:77], v[24:25], v[30:31]
	v_pk_mul_f32 v[36:37], v[28:29], s[60:61] op_sel_hi:[1,0]
	v_xor_b32_e32 v75, 0x80000000, v28
	v_mov_b32_e32 v74, v29
	v_pk_fma_f32 v[28:29], v[74:75], s[60:61], v[36:37] op_sel_hi:[1,0,1] neg_lo:[0,0,1] neg_hi:[0,0,1]
	v_pk_add_f32 v[36:37], v[6:7], v[34:35]
	v_pk_add_f32 v[6:7], v[6:7], v[34:35] neg_lo:[0,1] neg_hi:[0,1]
	v_pk_add_f32 v[34:35], v[4:5], v[14:15]
	v_pk_add_f32 v[4:5], v[4:5], v[14:15] neg_lo:[0,1] neg_hi:[0,1]
	v_pk_add_f32 v[78:79], v[18:19], v[28:29]
	v_pk_mul_f32 v[14:15], v[4:5], s[60:61] op_sel:[1,0] op_sel_hi:[0,0] neg_hi:[1,0]
	v_pk_add_f32 v[18:19], v[18:19], v[28:29] neg_lo:[0,1] neg_hi:[0,1]
	v_pk_fma_f32 v[4:5], v[4:5], s[60:61], v[14:15] op_sel_hi:[1,0,1]
	v_pk_add_f32 v[14:15], v[2:3], v[12:13]
	v_pk_add_f32 v[2:3], v[2:3], v[12:13] neg_lo:[0,1] neg_hi:[0,1]
	v_xor_b32_e32 v81, 0x80000000, v18
	v_xor_b32_e32 v13, 0x80000000, v2
	v_mov_b32_e32 v12, v3
	v_pk_add_f32 v[2:3], v[10:11], v[16:17]
	v_pk_add_f32 v[10:11], v[10:11], v[16:17] neg_lo:[0,1] neg_hi:[0,1]
	v_mov_b32_e32 v80, v19
	v_pk_mul_f32 v[16:17], v[10:11], s[60:61] op_sel_hi:[1,0]
	s_nop 0
	v_pk_fma_f32 v[10:11], v[10:11], s[60:61], v[16:17] op_sel:[1,0,0] op_sel_hi:[0,0,1] neg_lo:[0,0,1] neg_hi:[1,0,1]
	v_pk_add_f32 v[74:75], v[62:63], v[50:51]
	v_pk_add_f32 v[50:51], v[62:63], v[50:51] neg_lo:[0,1] neg_hi:[0,1]
	v_pk_add_f32 v[62:63], v[56:57], v[38:39]
	v_pk_add_f32 v[38:39], v[56:57], v[38:39] neg_lo:[0,1] neg_hi:[0,1]
	v_pk_add_f32 v[16:17], v[32:33], v[48:49]
	v_pk_add_f32 v[32:33], v[32:33], v[48:49] neg_lo:[0,1] neg_hi:[0,1]
	v_pk_add_f32 v[48:49], v[64:65], v[42:43]
	v_pk_add_f32 v[42:43], v[64:65], v[42:43] neg_lo:[0,1] neg_hi:[0,1]
	v_xor_b32_e32 v57, 0x80000000, v38
	v_mov_b32_e32 v56, v39
	v_pk_add_f32 v[38:39], v[8:9], v[46:47]
	v_pk_add_f32 v[8:9], v[8:9], v[46:47] neg_lo:[0,1] neg_hi:[0,1]
	v_pk_add_f32 v[46:47], v[26:27], v[44:45]
	v_pk_add_f32 v[26:27], v[26:27], v[44:45] neg_lo:[0,1] neg_hi:[0,1]
	v_xor_b32_e32 v65, 0x80000000, v42
	v_mov_b32_e32 v64, v43
	v_pk_add_f32 v[42:43], v[60:61], v[66:67]
	v_pk_add_f32 v[60:61], v[60:61], v[66:67] neg_lo:[0,1] neg_hi:[0,1]
	v_pk_add_f32 v[66:67], v[40:41], v[54:55]
	v_pk_add_f32 v[40:41], v[40:41], v[54:55] neg_lo:[0,1] neg_hi:[0,1]
	v_xor_b32_e32 v45, 0x80000000, v26
	v_mov_b32_e32 v44, v27
	v_pk_add_f32 v[26:27], v[52:53], v[58:59]
	v_pk_add_f32 v[52:53], v[52:53], v[58:59] neg_lo:[0,1] neg_hi:[0,1]
	v_pk_add_f32 v[58:59], v[72:73], v[22:23]
	v_pk_add_f32 v[22:23], v[72:73], v[22:23] neg_lo:[0,1] neg_hi:[0,1]
	v_pk_add_f32 v[18:19], v[36:37], v[14:15]
	v_pk_add_f32 v[14:15], v[36:37], v[14:15] neg_lo:[0,1] neg_hi:[0,1]
	v_pk_add_f32 v[36:37], v[34:35], v[2:3]
	v_pk_add_f32 v[2:3], v[34:35], v[2:3] neg_lo:[0,1] neg_hi:[0,1]
	v_xor_b32_e32 v73, 0x80000000, v22
	v_mov_b32_e32 v72, v23
	v_xor_b32_e32 v35, 0x80000000, v2
	v_mov_b32_e32 v34, v3
	v_pk_add_f32 v[2:3], v[4:5], v[10:11] neg_lo:[0,1] neg_hi:[0,1]
	v_pk_add_f32 v[24:25], v[24:25], v[30:31] neg_lo:[0,1] neg_hi:[0,1]
	v_pk_add_f32 v[82:83], v[6:7], v[12:13]
	v_pk_add_f32 v[12:13], v[6:7], v[12:13] neg_lo:[0,1] neg_hi:[0,1]
	v_xor_b32_e32 v87, 0x80000000, v2
	v_mov_b32_e32 v86, v3
	v_pk_add_f32 v[2:3], v[16:17], v[48:49]
	v_pk_add_f32 v[88:89], v[16:17], v[48:49] neg_lo:[0,1] neg_hi:[0,1]
	v_pk_add_f32 v[48:49], v[32:33], v[64:65]
	v_pk_add_f32 v[28:29], v[32:33], v[64:65] neg_lo:[0,1] neg_hi:[0,1]
	v_pk_add_f32 v[64:65], v[60:61], v[40:41] op_sel:[0,1] op_sel_hi:[1,0] neg_hi:[0,1]
	v_pk_add_f32 v[6:7], v[60:61], v[40:41] op_sel:[0,1] op_sel_hi:[1,0] neg_lo:[0,1]
	v_pk_add_f32 v[60:61], v[50:51], v[56:57]
	v_pk_add_f32 v[22:23], v[50:51], v[56:57] neg_lo:[0,1] neg_hi:[0,1]
	v_pk_add_f32 v[50:51], v[52:53], v[72:73]
	v_pk_add_f32 v[30:31], v[52:53], v[72:73] neg_lo:[0,1] neg_hi:[0,1]
	v_pk_add_f32 v[52:53], v[18:19], v[36:37]
	v_pk_add_f32 v[56:57], v[18:19], v[36:37] neg_lo:[0,1] neg_hi:[0,1]
	v_mov_b32_e32 v18, v21
	v_pk_add_f32 v[84:85], v[4:5], v[10:11]
	v_cvt_f32_i32_e32 v18, v18
	v_pk_add_f32 v[32:33], v[42:43], v[66:67]
	v_pk_add_f32 v[40:41], v[42:43], v[66:67] neg_lo:[0,1] neg_hi:[0,1]
	v_pk_add_f32 v[66:67], v[24:25], v[80:81]
	v_pk_add_f32 v[10:11], v[24:25], v[80:81] neg_lo:[0,1] neg_hi:[0,1]
	v_pk_add_f32 v[72:73], v[14:15], v[34:35]
	v_pk_add_f32 v[24:25], v[14:15], v[34:35] neg_lo:[0,1] neg_hi:[0,1]
	v_mul_f32_e32 v15, 0x38800000, v18
	v_cos_f32_e32 v14, v15
	v_sin_f32_e32 v15, v15
	v_pk_add_f32 v[16:17], v[74:75], v[62:63]
	v_pk_add_f32 v[54:55], v[74:75], v[62:63] neg_lo:[0,1] neg_hi:[0,1]
	v_pk_add_f32 v[62:63], v[8:9], v[44:45]
	v_pk_add_f32 v[4:5], v[8:9], v[44:45] neg_lo:[0,1] neg_hi:[0,1]
	v_pk_add_f32 v[8:9], v[26:27], v[58:59]
	v_add_f32_e32 v20, v14, v14
	v_pk_add_f32 v[42:43], v[38:39], v[46:47]
	v_pk_add_f32 v[38:39], v[38:39], v[46:47] neg_lo:[0,1] neg_hi:[0,1]
	v_pk_add_f32 v[58:59], v[26:27], v[58:59] neg_lo:[0,1] neg_hi:[0,1]
	v_pk_add_f32 v[26:27], v[76:77], v[78:79]
	v_pk_add_f32 v[46:47], v[76:77], v[78:79] neg_lo:[0,1] neg_hi:[0,1]
	v_pk_mul_f32 v[18:19], v[14:15], v[14:15]
	v_mul_f32_e32 v20, v15, v20
	v_mov_b32_e32 v78, v15
	v_pk_add_f32 v[18:19], v[18:19], v[18:19] op_sel:[0,1] op_sel_hi:[0,1] neg_lo:[0,1] neg_hi:[0,1]
	v_pk_mul_f32 v[34:35], v[14:15], v[20:21] op_sel:[1,0] op_sel_hi:[0,0] neg_lo:[1,0]
	v_pk_mul_f32 v[36:37], v[78:79], v[8:9] op_sel:[0,1] op_sel_hi:[0,0] neg_hi:[0,1]
	v_pk_fma_f32 v[34:35], v[14:15], v[18:19], v[34:35]
	v_pk_fma_f32 v[8:9], v[14:15], v[8:9], v[36:37] op_sel_hi:[0,1,1]
	v_pk_mul_f32 v[14:15], v[20:21], s[46:47] op_sel_hi:[0,1]
	v_pk_fma_f32 v[36:37], v[18:19], s[40:41], v[14:15]
	s_nop 0
	v_pk_mul_f32 v[14:15], v[16:17], v[36:37] op_sel:[1,1] op_sel_hi:[0,1] neg_hi:[1,0]
	v_pk_add_f32 v[74:75], v[82:83], v[84:85]
	v_pk_fma_f32 v[16:17], v[16:17], v[36:37], v[14:15] op_sel_hi:[1,0,1]
	v_pk_mul_f32 v[14:15], v[20:21], v[34:35] op_sel:[0,1] op_sel_hi:[0,0] neg_lo:[0,1]
	v_pk_fma_f32 v[78:79], v[18:19], v[34:35], v[14:15]
	v_pk_mul_f32 v[14:15], v[34:35], v[52:53] op_sel:[1,1] op_sel_hi:[1,0] neg_hi:[0,1]
	v_pk_add_f32 v[76:77], v[12:13], v[86:87]
	v_pk_fma_f32 v[14:15], v[34:35], v[52:53], v[14:15] op_sel_hi:[0,1,1]
	v_pk_mul_f32 v[34:35], v[20:21], v[36:37] op_sel:[0,1] op_sel_hi:[0,0] neg_lo:[0,1]
	s_nop 0
	v_pk_fma_f32 v[36:37], v[18:19], v[36:37], v[34:35]
	v_pk_mul_f32 v[52:53], v[26:27], v[78:79] op_sel:[1,1] op_sel_hi:[0,1] neg_hi:[1,0]
	v_pk_mul_f32 v[34:35], v[32:33], v[36:37] op_sel:[1,1] op_sel_hi:[0,1] neg_hi:[1,0]
	v_pk_fma_f32 v[26:27], v[26:27], v[78:79], v[52:53] op_sel_hi:[1,0,1]
	v_pk_fma_f32 v[34:35], v[32:33], v[36:37], v[34:35] op_sel_hi:[1,0,1]
	v_pk_mul_f32 v[52:53], v[20:21], v[36:37] op_sel:[0,1] op_sel_hi:[0,0] neg_lo:[0,1]
	v_pk_mul_f32 v[32:33], v[20:21], v[78:79] op_sel:[0,1] op_sel_hi:[0,0] neg_lo:[0,1]
	v_pk_fma_f32 v[52:53], v[18:19], v[36:37], v[52:53]
	v_pk_fma_f32 v[32:33], v[18:19], v[78:79], v[32:33]
	v_pk_mul_f32 v[36:37], v[42:43], v[52:53] op_sel:[1,1] op_sel_hi:[0,1] neg_hi:[1,0]
	s_nop 0
	v_pk_fma_f32 v[36:37], v[42:43], v[52:53], v[36:37] op_sel_hi:[1,0,1]
	v_pk_mul_f32 v[42:43], v[20:21], v[32:33] op_sel:[0,1] op_sel_hi:[0,0] neg_lo:[0,1]
	v_pk_mul_f32 v[78:79], v[74:75], v[32:33] op_sel:[1,1] op_sel_hi:[0,1] neg_hi:[1,0]
	v_pk_fma_f32 v[42:43], v[18:19], v[32:33], v[42:43]
	v_pk_fma_f32 v[32:33], v[74:75], v[32:33], v[78:79] op_sel_hi:[1,0,1]
	v_pk_mul_f32 v[74:75], v[20:21], v[52:53] op_sel:[0,1] op_sel_hi:[0,0] neg_lo:[0,1]
	v_pk_fma_f32 v[52:53], v[18:19], v[52:53], v[74:75]
	s_nop 0
	v_pk_mul_f32 v[74:75], v[48:49], v[52:53] op_sel:[1,1] op_sel_hi:[0,1] neg_hi:[1,0]
	s_nop 0
	v_pk_fma_f32 v[48:49], v[48:49], v[52:53], v[74:75] op_sel_hi:[1,0,1]
	v_pk_mul_f32 v[74:75], v[20:21], v[42:43] op_sel:[0,1] op_sel_hi:[0,0] neg_lo:[0,1]
	v_pk_mul_f32 v[78:79], v[50:51], v[42:43] op_sel:[1,1] op_sel_hi:[0,1] neg_hi:[1,0]
	v_pk_fma_f32 v[74:75], v[18:19], v[42:43], v[74:75]
	v_pk_fma_f32 v[42:43], v[50:51], v[42:43], v[78:79] op_sel_hi:[1,0,1]
	v_pk_mul_f32 v[50:51], v[20:21], v[52:53] op_sel:[0,1] op_sel_hi:[0,0] neg_lo:[0,1]
	v_pk_fma_f32 v[78:79], v[18:19], v[52:53], v[50:51]
	s_nop 0
	v_pk_mul_f32 v[50:51], v[60:61], v[78:79] op_sel:[1,1] op_sel_hi:[0,1] neg_hi:[1,0]
	v_xor_b32_e32 v81, 0x80000000, v58
	v_pk_fma_f32 v[52:53], v[60:61], v[78:79], v[50:51] op_sel_hi:[1,0,1]
	v_pk_mul_f32 v[50:51], v[20:21], v[74:75] op_sel:[0,1] op_sel_hi:[0,0] neg_lo:[0,1]
	v_pk_fma_f32 v[60:61], v[18:19], v[74:75], v[50:51]
	v_pk_mul_f32 v[50:51], v[72:73], v[74:75] op_sel:[1,1] op_sel_hi:[0,1] neg_hi:[1,0]
	v_mov_b32_e32 v80, v59
	v_pk_fma_f32 v[50:51], v[72:73], v[74:75], v[50:51] op_sel_hi:[1,0,1]
	v_pk_mul_f32 v[72:73], v[20:21], v[78:79] op_sel:[0,1] op_sel_hi:[0,0] neg_lo:[0,1]
	v_pk_fma_f32 v[72:73], v[18:19], v[78:79], v[72:73]
	s_nop 0
	v_pk_mul_f32 v[74:75], v[64:65], v[72:73] op_sel:[1,1] op_sel_hi:[0,1] neg_hi:[1,0]
	s_nop 0
	v_pk_fma_f32 v[64:65], v[64:65], v[72:73], v[74:75] op_sel_hi:[1,0,1]
	v_pk_mul_f32 v[74:75], v[20:21], v[60:61] op_sel:[0,1] op_sel_hi:[0,0] neg_lo:[0,1]
	v_pk_mul_f32 v[78:79], v[66:67], v[60:61] op_sel:[1,1] op_sel_hi:[0,1] neg_hi:[1,0]
	v_pk_fma_f32 v[74:75], v[18:19], v[60:61], v[74:75]
	v_pk_fma_f32 v[60:61], v[66:67], v[60:61], v[78:79] op_sel_hi:[1,0,1]
	v_pk_mul_f32 v[66:67], v[20:21], v[72:73] op_sel:[0,1] op_sel_hi:[0,0] neg_lo:[0,1]
	v_pk_fma_f32 v[66:67], v[18:19], v[72:73], v[66:67]
	s_nop 0
	v_pk_mul_f32 v[72:73], v[62:63], v[66:67] op_sel:[1,1] op_sel_hi:[0,1] neg_hi:[1,0]
	s_nop 0
	v_pk_fma_f32 v[62:63], v[62:63], v[66:67], v[72:73] op_sel_hi:[1,0,1]
	v_pk_mul_f32 v[72:73], v[20:21], v[74:75] op_sel:[0,1] op_sel_hi:[0,0] neg_lo:[0,1]
	v_pk_mul_f32 v[78:79], v[76:77], v[74:75] op_sel:[1,1] op_sel_hi:[0,1] neg_hi:[1,0]
	v_pk_fma_f32 v[72:73], v[18:19], v[74:75], v[72:73]
	v_pk_fma_f32 v[74:75], v[76:77], v[74:75], v[78:79] op_sel_hi:[1,0,1]
	v_pk_mul_f32 v[76:77], v[20:21], v[66:67] op_sel:[0,1] op_sel_hi:[0,0] neg_lo:[0,1]
	s_nop 0
	v_pk_fma_f32 v[66:67], v[18:19], v[66:67], v[76:77]
	v_pk_mul_f32 v[78:79], v[20:21], v[72:73] op_sel:[0,1] op_sel_hi:[0,0] neg_lo:[0,1]
	v_pk_mul_f32 v[80:81], v[80:81], v[72:73] op_sel:[0,1]
	v_pk_fma_f32 v[78:79], v[18:19], v[72:73], v[78:79]
	v_pk_fma_f32 v[58:59], v[58:59], v[72:73], v[80:81] op_sel_hi:[1,0,1]
	v_pk_mul_f32 v[76:77], v[88:89], v[66:67] op_sel:[1,1] op_sel_hi:[0,1] neg_hi:[1,0]
	v_pk_mul_f32 v[72:73], v[20:21], v[66:67] op_sel:[0,1] op_sel_hi:[0,0] neg_lo:[0,1]
	v_pk_fma_f32 v[76:77], v[88:89], v[66:67], v[76:77] op_sel_hi:[1,0,1]
	v_pk_fma_f32 v[66:67], v[18:19], v[66:67], v[72:73]
	s_nop 0
	v_pk_mul_f32 v[72:73], v[54:55], v[66:67] op_sel:[1,1] op_sel_hi:[0,1] neg_hi:[1,0]
	s_nop 0
	v_pk_fma_f32 v[54:55], v[54:55], v[66:67], v[72:73] op_sel_hi:[1,0,1]
	v_pk_mul_f32 v[72:73], v[20:21], v[78:79] op_sel:[0,1] op_sel_hi:[0,0] neg_lo:[0,1]
	v_pk_mul_f32 v[80:81], v[56:57], v[78:79] op_sel:[1,1] op_sel_hi:[0,1] neg_hi:[1,0]
	v_pk_fma_f32 v[72:73], v[18:19], v[78:79], v[72:73]
	v_pk_fma_f32 v[56:57], v[56:57], v[78:79], v[80:81] op_sel_hi:[1,0,1]
	v_pk_mul_f32 v[78:79], v[20:21], v[66:67] op_sel:[0,1] op_sel_hi:[0,0] neg_lo:[0,1]
	v_pk_fma_f32 v[66:67], v[18:19], v[66:67], v[78:79]
	s_nop 0
	v_pk_mul_f32 v[78:79], v[40:41], v[66:67] op_sel:[1,1] op_sel_hi:[0,1] neg_hi:[1,0]
	s_nop 0
	v_pk_fma_f32 v[40:41], v[40:41], v[66:67], v[78:79] op_sel_hi:[1,0,1]
	v_pk_mul_f32 v[78:79], v[20:21], v[72:73] op_sel:[0,1] op_sel_hi:[0,0] neg_lo:[0,1]
	v_pk_mul_f32 v[80:81], v[46:47], v[72:73] op_sel:[1,1] op_sel_hi:[0,1] neg_hi:[1,0]
	v_pk_fma_f32 v[78:79], v[18:19], v[72:73], v[78:79]
	v_pk_fma_f32 v[46:47], v[46:47], v[72:73], v[80:81] op_sel_hi:[1,0,1]
	v_pk_mul_f32 v[72:73], v[20:21], v[66:67] op_sel:[0,1] op_sel_hi:[0,0] neg_lo:[0,1]
	v_pk_fma_f32 v[66:67], v[18:19], v[66:67], v[72:73]
	v_pk_add_f32 v[44:45], v[82:83], v[84:85] neg_lo:[0,1] neg_hi:[0,1]
	v_pk_mul_f32 v[72:73], v[38:39], v[66:67] op_sel:[1,1] op_sel_hi:[0,1] neg_hi:[1,0]
	s_nop 0
	v_pk_fma_f32 v[38:39], v[38:39], v[66:67], v[72:73] op_sel_hi:[1,0,1]
	v_pk_mul_f32 v[72:73], v[20:21], v[78:79] op_sel:[0,1] op_sel_hi:[0,0] neg_lo:[0,1]
	v_pk_mul_f32 v[80:81], v[44:45], v[78:79] op_sel:[1,1] op_sel_hi:[0,1] neg_hi:[1,0]
	v_pk_fma_f32 v[72:73], v[18:19], v[78:79], v[72:73]
	v_pk_fma_f32 v[44:45], v[44:45], v[78:79], v[80:81] op_sel_hi:[1,0,1]
	v_pk_mul_f32 v[78:79], v[20:21], v[66:67] op_sel:[0,1] op_sel_hi:[0,0] neg_lo:[0,1]
	v_pk_fma_f32 v[66:67], v[18:19], v[66:67], v[78:79]
	s_nop 0
	v_pk_mul_f32 v[78:79], v[28:29], v[66:67] op_sel:[1,1] op_sel_hi:[0,1] neg_hi:[1,0]
	s_nop 0
	v_pk_fma_f32 v[28:29], v[28:29], v[66:67], v[78:79] op_sel_hi:[1,0,1]
	v_pk_mul_f32 v[78:79], v[20:21], v[72:73] op_sel:[0,1] op_sel_hi:[0,0] neg_lo:[0,1]
	v_pk_mul_f32 v[80:81], v[30:31], v[72:73] op_sel:[1,1] op_sel_hi:[0,1] neg_hi:[1,0]
	v_pk_fma_f32 v[78:79], v[18:19], v[72:73], v[78:79]
	v_pk_fma_f32 v[30:31], v[30:31], v[72:73], v[80:81] op_sel_hi:[1,0,1]
	v_pk_mul_f32 v[72:73], v[20:21], v[66:67] op_sel:[0,1] op_sel_hi:[0,0] neg_lo:[0,1]
	v_pk_fma_f32 v[66:67], v[18:19], v[66:67], v[72:73]
	s_nop 0
	v_pk_mul_f32 v[72:73], v[22:23], v[66:67] op_sel:[1,1] op_sel_hi:[0,1] neg_hi:[1,0]
	s_nop 0
	v_pk_fma_f32 v[22:23], v[22:23], v[66:67], v[72:73] op_sel_hi:[1,0,1]
	v_pk_mul_f32 v[72:73], v[20:21], v[78:79] op_sel:[0,1] op_sel_hi:[0,0] neg_lo:[0,1]
	v_pk_mul_f32 v[80:81], v[24:25], v[78:79] op_sel:[1,1] op_sel_hi:[0,1] neg_hi:[1,0]
	v_pk_fma_f32 v[72:73], v[18:19], v[78:79], v[72:73]
	v_pk_fma_f32 v[24:25], v[24:25], v[78:79], v[80:81] op_sel_hi:[1,0,1]
	v_pk_mul_f32 v[78:79], v[20:21], v[66:67] op_sel:[0,1] op_sel_hi:[0,0] neg_lo:[0,1]
	v_pk_fma_f32 v[66:67], v[18:19], v[66:67], v[78:79]
	s_nop 0
	v_pk_mul_f32 v[78:79], v[6:7], v[66:67] op_sel:[1,1] op_sel_hi:[0,1] neg_hi:[1,0]
	s_nop 0
	v_pk_fma_f32 v[6:7], v[6:7], v[66:67], v[78:79] op_sel_hi:[1,0,1]
	v_pk_mul_f32 v[78:79], v[20:21], v[72:73] op_sel:[0,1] op_sel_hi:[0,0] neg_lo:[0,1]
	v_pk_mul_f32 v[80:81], v[10:11], v[72:73] op_sel:[1,1] op_sel_hi:[0,1] neg_hi:[1,0]
	v_pk_fma_f32 v[78:79], v[18:19], v[72:73], v[78:79]
	v_pk_fma_f32 v[10:11], v[10:11], v[72:73], v[80:81] op_sel_hi:[1,0,1]
	v_pk_mul_f32 v[72:73], v[20:21], v[66:67] op_sel:[0,1] op_sel_hi:[0,0] neg_lo:[0,1]
	v_pk_fma_f32 v[18:19], v[18:19], v[66:67], v[72:73]
	v_pk_add_f32 v[12:13], v[12:13], v[86:87] neg_lo:[0,1] neg_hi:[0,1]
	v_pk_mul_f32 v[66:67], v[4:5], v[18:19] op_sel:[1,1] op_sel_hi:[0,1] neg_hi:[1,0]
	s_nop 0
	v_pk_fma_f32 v[4:5], v[4:5], v[18:19], v[66:67] op_sel_hi:[1,0,1]
	s_nop 0
	s_nop 0
	v_pk_mul_f32 v[18:19], v[12:13], v[78:79] op_sel:[1,1] op_sel_hi:[0,1] neg_hi:[1,0]
	s_nop 0
	v_pk_fma_f32 v[12:13], v[12:13], v[78:79], v[18:19] op_sel_hi:[1,0,1]
	v_lshrrev_b32_e32 v18, 5, v21
	v_bitop3_b32 v18, v18, v21, 15 bitop3:0x6c
	v_lshlrev_b32_e32 v18, 3, v18
	v_bfe_u32 v19, v21, 5, 4
	v_add_u32_e32 v20, 16, v18
	ds_write_b64 v20, v[2:3]
	v_bitop3_b32 v2, v19, v21, 16 bitop3:0x36
	v_lshl_add_u32 v2, v2, 3, 16
	v_add_u32_e32 v3, s79, v18
	ds_write_b64 v2, v[76:77] offset:4096
	ds_write_b64 v20, v[48:49] offset:8192
	ds_write_b64 v2, v[28:29] offset:12288
	ds_write_b64 v20, v[34:35] offset:16384
	ds_write_b64 v2, v[40:41] offset:20480
	ds_write_b64 v20, v[64:65] offset:24576
	ds_write_b64 v2, v[6:7] offset:28672
	ds_write_b64 v20, v[16:17] offset:32768
	ds_write_b64 v2, v[54:55] offset:36864
	ds_write_b64 v20, v[52:53] offset:40960
	ds_write_b64 v2, v[22:23] offset:45056
	ds_write_b64 v20, v[36:37] offset:49152
	ds_write_b64 v2, v[38:39] offset:53248
	ds_write_b64 v20, v[62:63] offset:57344
	ds_write_b64 v2, v[4:5] offset:61440
	ds_write_b64 v3, v[8:9]
	v_add_u32_e32 v3, 0x11000, v2
	ds_write_b64 v3, v[58:59]
	v_add_u32_e32 v3, 0x12000, v20
	ds_write_b64 v3, v[42:43]
	v_add_u32_e32 v3, 0x13000, v2
	ds_write_b64 v3, v[30:31]
	v_add_u32_e32 v3, 0x14000, v20
	ds_write_b64 v3, v[26:27]
	v_add_u32_e32 v3, 0x15000, v2
	ds_write_b64 v3, v[46:47]
	v_add_u32_e32 v3, 0x16000, v20
	ds_write_b64 v3, v[60:61]
	v_add_u32_e32 v3, 0x17000, v2
	ds_write_b64 v3, v[10:11]
	v_add_u32_e32 v3, 0x18000, v20
	ds_write_b64 v3, v[14:15]
	v_add_u32_e32 v3, 0x19000, v2
	ds_write_b64 v3, v[56:57]
	v_add_u32_e32 v3, 0x1a000, v20
	ds_write_b64 v3, v[50:51]
	v_add_u32_e32 v3, 0x1b000, v2
	ds_write_b64 v3, v[24:25]
	v_add_u32_e32 v3, 0x1c000, v20
	ds_write_b64 v3, v[32:33]
	v_add_u32_e32 v3, 0x1d000, v2
	ds_write_b64 v3, v[44:45]
	v_add_u32_e32 v3, 0x1e000, v20
	v_add_u32_e32 v2, 0x1f000, v2
	v_mov_b32_e32 v11, v146
	ds_write_b64 v3, v[74:75]
	ds_write_b64 v2, v[12:13]
	s_waitcnt lgkmcnt(0)
	s_barrier
	s_nop 0
	v_lshlrev_b32_e32 v2, 5, v11
	v_and_b32_e32 v2, 0xfffffe00, v2
	v_and_or_b32 v3, v11, 16, v2
	v_bitop3_b32 v2, v2, 16, v11 bitop3:0x34
	v_bitop3_b32 v12, v11, 2, 15 bitop3:0x6c
	v_bitop3_b32 v22, v11, 4, 15 bitop3:0x6c
	v_bitop3_b32 v30, v11, 6, 15 bitop3:0x6c
	v_bitop3_b32 v38, v11, 8, 15 bitop3:0x6c
	v_and_b32_e32 v10, 15, v11
	v_lshl_add_u32 v18, v3, 3, 16
	v_lshl_add_u32 v87, v2, 3, 16
	v_lshlrev_b32_e32 v12, 3, v12
	v_lshlrev_b32_e32 v22, 3, v22
	v_lshlrev_b32_e32 v30, 3, v30
	v_lshlrev_b32_e32 v38, 3, v38
	v_lshlrev_b32_e32 v3, 3, v10
	v_bitop3_b32 v2, v11, 1, 15 bitop3:0x6c
	v_add_u32_e32 v57, v18, v12
	v_add_u32_e32 v58, v87, v12
	v_bitop3_b32 v12, v11, 3, 15 bitop3:0x6c
	v_add_u32_e32 v61, v18, v22
	v_add_u32_e32 v62, v87, v22
	v_bitop3_b32 v22, v11, 5, 15 bitop3:0x6c
	v_add_u32_e32 v65, v18, v30
	v_add_u32_e32 v66, v87, v30
	v_bitop3_b32 v30, v11, 7, 15 bitop3:0x6c
	v_add_u32_e32 v72, v18, v38
	v_add_u32_e32 v73, v87, v38
	v_bitop3_b32 v38, v11, 9, 15 bitop3:0x6c
	v_add_u32_e32 v19, v18, v3
	v_lshlrev_b32_e32 v2, 3, v2
	v_lshlrev_b32_e32 v12, 3, v12
	v_lshlrev_b32_e32 v22, 3, v22
	v_lshlrev_b32_e32 v30, 3, v30
	v_lshlrev_b32_e32 v38, 3, v38
	v_add_u32_e32 v54, v87, v3
	v_add_u32_e32 v55, v18, v2
	v_add_u32_e32 v56, v87, v2
	ds_read_b64 v[2:3], v19
	ds_read_b64 v[4:5], v54
	ds_read_b64 v[6:7], v55 offset:256
	ds_read_b64 v[8:9], v56 offset:256
	v_add_u32_e32 v59, v18, v12
	v_add_u32_e32 v60, v87, v12
	ds_read_b64 v[12:13], v57 offset:512
	ds_read_b64 v[14:15], v58 offset:512
	ds_read_b64 v[16:17], v59 offset:768
	ds_read_b64 v[20:21], v60 offset:768
	v_add_u32_e32 v63, v18, v22
	v_add_u32_e32 v64, v87, v22
	ds_read_b64 v[22:23], v61 offset:1024
	ds_read_b64 v[24:25], v62 offset:1024
	ds_read_b64 v[26:27], v63 offset:1280
	ds_read_b64 v[28:29], v64 offset:1280
	v_add_u32_e32 v67, v18, v30
	v_add_u32_e32 v71, v87, v30
	ds_read_b64 v[30:31], v65 offset:1536
	ds_read_b64 v[32:33], v66 offset:1536
	ds_read_b64 v[34:35], v67 offset:1792
	ds_read_b64 v[36:37], v71 offset:1792
	v_add_u32_e32 v74, v18, v38
	v_add_u32_e32 v75, v87, v38
	ds_read_b64 v[38:39], v72 offset:2048
	ds_read_b64 v[40:41], v73 offset:2048
	ds_read_b64 v[42:43], v74 offset:2304
	ds_read_b64 v[44:45], v75 offset:2304
	v_bitop3_b32 v46, v11, 10, 15 bitop3:0x6c
	s_waitcnt lgkmcnt(3)
	v_pk_add_f32 v[104:105], v[2:3], v[38:39]
	v_pk_add_f32 v[2:3], v[2:3], v[38:39] neg_lo:[0,1] neg_hi:[0,1]
	s_waitcnt lgkmcnt(2)
	v_pk_add_f32 v[38:39], v[4:5], v[40:41]
	v_pk_add_f32 v[4:5], v[4:5], v[40:41] neg_lo:[0,1] neg_hi:[0,1]
	v_lshlrev_b32_e32 v46, 3, v46
	v_pk_mul_f32 v[40:41], v[4:5], s[48:49] op_sel:[1,0] op_sel_hi:[0,0] neg_hi:[1,0]
	v_add_u32_e32 v76, v18, v46
	v_pk_fma_f32 v[4:5], v[4:5], s[44:45], v[40:41] op_sel_hi:[1,0,1]
	s_waitcnt lgkmcnt(1)
	v_pk_add_f32 v[40:41], v[6:7], v[42:43]
	v_pk_add_f32 v[6:7], v[6:7], v[42:43] neg_lo:[0,1] neg_hi:[0,1]
	v_add_u32_e32 v77, v87, v46
	v_bitop3_b32 v46, v11, 11, 15 bitop3:0x6c
	v_pk_mul_f32 v[42:43], v[6:7], s[54:55] op_sel:[1,0] op_sel_hi:[0,0] neg_hi:[1,0]
	v_lshlrev_b32_e32 v46, 3, v46
	v_pk_fma_f32 v[6:7], v[6:7], s[52:53], v[42:43] op_sel_hi:[1,0,1]
	s_waitcnt lgkmcnt(0)
	v_pk_add_f32 v[42:43], v[8:9], v[44:45]
	v_pk_add_f32 v[8:9], v[8:9], v[44:45] neg_lo:[0,1] neg_hi:[0,1]
	v_add_u32_e32 v78, v18, v46
	v_add_u32_e32 v79, v87, v46
	ds_read_b64 v[46:47], v76 offset:2560
	ds_read_b64 v[48:49], v77 offset:2560
	ds_read_b64 v[50:51], v78 offset:2816
	ds_read_b64 v[52:53], v79 offset:2816
	v_pk_mul_f32 v[44:45], v[8:9], s[58:59] op_sel:[1,0] op_sel_hi:[0,0] neg_hi:[1,0]
	v_bitop3_b32 v80, v11, 12, 15 bitop3:0x6c
	v_pk_fma_f32 v[8:9], v[8:9], s[56:57], v[44:45] op_sel_hi:[1,0,1]
	s_waitcnt lgkmcnt(3)
	v_pk_add_f32 v[44:45], v[12:13], v[46:47]
	v_pk_add_f32 v[12:13], v[12:13], v[46:47] neg_lo:[0,1] neg_hi:[0,1]
	v_lshlrev_b32_e32 v81, 3, v80
	v_pk_mul_f32 v[46:47], v[12:13], s[60:61] op_sel:[1,0] op_sel_hi:[0,0] neg_hi:[1,0]
	v_bitop3_b32 v82, v11, 13, 15 bitop3:0x6c
	v_pk_fma_f32 v[12:13], v[12:13], s[60:61], v[46:47] op_sel_hi:[1,0,1]
	s_waitcnt lgkmcnt(2)
	v_pk_add_f32 v[46:47], v[14:15], v[48:49]
	v_pk_add_f32 v[14:15], v[14:15], v[48:49] neg_lo:[0,1] neg_hi:[0,1]
	v_add_u32_e32 v80, v18, v81
	v_pk_mul_f32 v[48:49], v[14:15], s[56:57] op_sel:[1,0] op_sel_hi:[0,0] neg_hi:[1,0]
	v_lshlrev_b32_e32 v83, 3, v82
	v_pk_fma_f32 v[14:15], v[14:15], s[58:59], v[48:49] op_sel_hi:[1,0,1]
	s_waitcnt lgkmcnt(1)
	v_pk_add_f32 v[48:49], v[16:17], v[50:51]
	v_pk_add_f32 v[16:17], v[16:17], v[50:51] neg_lo:[0,1] neg_hi:[0,1]
	v_add_u32_e32 v81, v87, v81
	v_pk_mul_f32 v[50:51], v[16:17], s[52:53] op_sel:[1,0] op_sel_hi:[0,0] neg_hi:[1,0]
	v_add_u32_e32 v82, v18, v83
	v_pk_fma_f32 v[16:17], v[16:17], s[54:55], v[50:51] op_sel_hi:[1,0,1]
	s_waitcnt lgkmcnt(0)
	v_pk_add_f32 v[50:51], v[20:21], v[52:53]
	v_pk_add_f32 v[20:21], v[20:21], v[52:53] neg_lo:[0,1] neg_hi:[0,1]
	v_add_u32_e32 v83, v87, v83
	ds_read_b64 v[88:89], v80 offset:3072
	ds_read_b64 v[90:91], v81 offset:3072
	ds_read_b64 v[92:93], v82 offset:3328
	ds_read_b64 v[94:95], v83 offset:3328
	v_pk_mul_f32 v[52:53], v[20:21], s[44:45] op_sel:[1,0] op_sel_hi:[0,0] neg_hi:[1,0]
	v_bitop3_b32 v84, v11, 14, 15 bitop3:0x6c
	v_pk_fma_f32 v[20:21], v[20:21], s[48:49], v[52:53] op_sel_hi:[1,0,1]
	s_waitcnt lgkmcnt(3)
	v_pk_add_f32 v[52:53], v[22:23], v[88:89]
	v_pk_add_f32 v[22:23], v[22:23], v[88:89] neg_lo:[0,1] neg_hi:[0,1]
	v_lshlrev_b32_e32 v85, 3, v84
	v_xor_b32_e32 v89, 0x80000000, v22
	v_mov_b32_e32 v88, v23
	s_waitcnt lgkmcnt(2)
	v_pk_add_f32 v[22:23], v[24:25], v[90:91]
	v_pk_add_f32 v[24:25], v[24:25], v[90:91] neg_lo:[0,1] neg_hi:[0,1]
	v_bitop3_b32 v11, v11, 15, v11 bitop3:0xc
	v_pk_mul_f32 v[90:91], v[24:25], s[48:49] op_sel_hi:[1,0]
	v_xor_b32_e32 v107, 0x80000000, v24
	v_mov_b32_e32 v106, v25
	v_pk_fma_f32 v[24:25], v[106:107], s[44:45], v[90:91] op_sel_hi:[1,0,1] neg_lo:[0,0,1] neg_hi:[0,0,1]
	s_waitcnt lgkmcnt(1)
	v_pk_add_f32 v[90:91], v[26:27], v[92:93]
	v_pk_add_f32 v[26:27], v[26:27], v[92:93] neg_lo:[0,1] neg_hi:[0,1]
	v_add_u32_e32 v84, v18, v85
	v_lshlrev_b32_e32 v11, 3, v11
	v_pk_mul_f32 v[92:93], v[26:27], s[54:55] op_sel_hi:[1,0]
	v_xor_b32_e32 v107, 0x80000000, v26
	v_mov_b32_e32 v106, v27
	v_add_u32_e32 v85, v87, v85
	v_add_u32_e32 v86, v18, v11
	v_add_u32_e32 v87, v87, v11
	ds_read_b64 v[96:97], v84 offset:3584
	ds_read_b64 v[98:99], v85 offset:3584
	ds_read_b64 v[100:101], v86 offset:3840
	ds_read_b64 v[102:103], v87 offset:3840
	v_pk_fma_f32 v[26:27], v[106:107], s[52:53], v[92:93] op_sel_hi:[1,0,1] neg_lo:[0,0,1] neg_hi:[0,0,1]
	s_waitcnt lgkmcnt(4)
	v_pk_add_f32 v[92:93], v[28:29], v[94:95]
	v_pk_add_f32 v[28:29], v[28:29], v[94:95] neg_lo:[0,1] neg_hi:[0,1]
	s_nop 0
	v_pk_mul_f32 v[94:95], v[28:29], s[58:59] op_sel_hi:[1,0]
	v_xor_b32_e32 v107, 0x80000000, v28
	v_mov_b32_e32 v106, v29
	v_pk_fma_f32 v[28:29], v[106:107], s[56:57], v[94:95] op_sel_hi:[1,0,1] neg_lo:[0,0,1] neg_hi:[0,0,1]
	s_waitcnt lgkmcnt(3)
	v_pk_add_f32 v[94:95], v[30:31], v[96:97]
	v_pk_add_f32 v[30:31], v[30:31], v[96:97] neg_lo:[0,1] neg_hi:[0,1]
	v_cvt_f32_i32_e32 v10, v10
	v_pk_mul_f32 v[96:97], v[30:31], s[60:61] op_sel_hi:[1,0]
	v_xor_b32_e32 v107, 0x80000000, v30
	v_mov_b32_e32 v106, v31
	v_pk_fma_f32 v[30:31], v[106:107], s[60:61], v[96:97] op_sel_hi:[1,0,1] neg_lo:[0,0,1] neg_hi:[0,0,1]
	s_waitcnt lgkmcnt(2)
	v_pk_add_f32 v[96:97], v[32:33], v[98:99]
	v_pk_add_f32 v[32:33], v[32:33], v[98:99] neg_lo:[0,1] neg_hi:[0,1]
	v_mul_f32_e32 v10, 0x3b000000, v10
	v_pk_mul_f32 v[98:99], v[32:33], s[56:57] op_sel_hi:[1,0]
	v_xor_b32_e32 v107, 0x80000000, v32
	v_mov_b32_e32 v106, v33
	v_pk_fma_f32 v[32:33], v[106:107], s[58:59], v[98:99] op_sel_hi:[1,0,1] neg_lo:[0,0,1] neg_hi:[0,0,1]
	s_waitcnt lgkmcnt(1)
	v_pk_add_f32 v[98:99], v[34:35], v[100:101]
	v_pk_add_f32 v[34:35], v[34:35], v[100:101] neg_lo:[0,1] neg_hi:[0,1]
	s_nop 0
	v_pk_mul_f32 v[100:101], v[34:35], s[52:53] op_sel_hi:[1,0]
	v_xor_b32_e32 v107, 0x80000000, v34
	v_mov_b32_e32 v106, v35
	v_pk_fma_f32 v[34:35], v[106:107], s[54:55], v[100:101] op_sel_hi:[1,0,1] neg_lo:[0,0,1] neg_hi:[0,0,1]
	s_waitcnt lgkmcnt(0)
	v_pk_add_f32 v[100:101], v[36:37], v[102:103]
	v_pk_add_f32 v[36:37], v[36:37], v[102:103] neg_lo:[0,1] neg_hi:[0,1]
	s_nop 0
	v_pk_mul_f32 v[102:103], v[36:37], s[44:45] op_sel_hi:[1,0]
	v_xor_b32_e32 v107, 0x80000000, v36
	v_mov_b32_e32 v106, v37
	v_pk_fma_f32 v[36:37], v[106:107], s[48:49], v[102:103] op_sel_hi:[1,0,1] neg_lo:[0,0,1] neg_hi:[0,0,1]
	v_pk_add_f32 v[102:103], v[104:105], v[52:53]
	v_pk_add_f32 v[52:53], v[104:105], v[52:53] neg_lo:[0,1] neg_hi:[0,1]
	v_pk_add_f32 v[104:105], v[38:39], v[22:23]
	v_pk_add_f32 v[22:23], v[38:39], v[22:23] neg_lo:[0,1] neg_hi:[0,1]
	s_nop 0
	v_pk_mul_f32 v[38:39], v[22:23], s[54:55] op_sel:[1,0] op_sel_hi:[0,0] neg_hi:[1,0]
	s_nop 0
	v_pk_fma_f32 v[22:23], v[22:23], s[52:53], v[38:39] op_sel_hi:[1,0,1]
	v_pk_add_f32 v[38:39], v[40:41], v[90:91]
	v_pk_add_f32 v[40:41], v[40:41], v[90:91] neg_lo:[0,1] neg_hi:[0,1]
	s_nop 0
	v_pk_mul_f32 v[90:91], v[40:41], s[60:61] op_sel:[1,0] op_sel_hi:[0,0] neg_hi:[1,0]
	s_nop 0
	v_pk_fma_f32 v[40:41], v[40:41], s[60:61], v[90:91] op_sel_hi:[1,0,1]
	v_pk_add_f32 v[90:91], v[42:43], v[92:93]
	v_pk_add_f32 v[42:43], v[42:43], v[92:93] neg_lo:[0,1] neg_hi:[0,1]
	s_nop 0
	v_pk_mul_f32 v[92:93], v[42:43], s[52:53] op_sel:[1,0] op_sel_hi:[0,0] neg_hi:[1,0]
	s_nop 0
	v_pk_fma_f32 v[42:43], v[42:43], s[54:55], v[92:93] op_sel_hi:[1,0,1]
	v_pk_add_f32 v[92:93], v[44:45], v[94:95]
	v_pk_add_f32 v[44:45], v[44:45], v[94:95] neg_lo:[0,1] neg_hi:[0,1]
	s_nop 0
	v_xor_b32_e32 v95, 0x80000000, v44
	v_mov_b32_e32 v94, v45
	v_pk_add_f32 v[44:45], v[46:47], v[96:97]
	v_pk_add_f32 v[46:47], v[46:47], v[96:97] neg_lo:[0,1] neg_hi:[0,1]
	s_nop 0
	v_pk_mul_f32 v[96:97], v[46:47], s[54:55] op_sel_hi:[1,0]
	v_xor_b32_e32 v107, 0x80000000, v46
	v_mov_b32_e32 v106, v47
	v_pk_fma_f32 v[46:47], v[106:107], s[52:53], v[96:97] op_sel_hi:[1,0,1] neg_lo:[0,0,1] neg_hi:[0,0,1]
	v_pk_add_f32 v[96:97], v[48:49], v[98:99]
	v_pk_add_f32 v[48:49], v[48:49], v[98:99] neg_lo:[0,1] neg_hi:[0,1]
	s_nop 0
	v_pk_mul_f32 v[98:99], v[48:49], s[60:61] op_sel_hi:[1,0]
	v_xor_b32_e32 v107, 0x80000000, v48
	v_mov_b32_e32 v106, v49
	v_pk_fma_f32 v[48:49], v[106:107], s[60:61], v[98:99] op_sel_hi:[1,0,1] neg_lo:[0,0,1] neg_hi:[0,0,1]
	v_pk_add_f32 v[98:99], v[50:51], v[100:101]
	v_pk_add_f32 v[50:51], v[50:51], v[100:101] neg_lo:[0,1] neg_hi:[0,1]
	s_nop 0
	v_pk_mul_f32 v[100:101], v[50:51], s[52:53] op_sel_hi:[1,0]
	v_xor_b32_e32 v107, 0x80000000, v50
	v_mov_b32_e32 v106, v51
	v_pk_fma_f32 v[50:51], v[106:107], s[54:55], v[100:101] op_sel_hi:[1,0,1] neg_lo:[0,0,1] neg_hi:[0,0,1]
	v_pk_add_f32 v[100:101], v[2:3], v[88:89]
	v_pk_add_f32 v[2:3], v[2:3], v[88:89] neg_lo:[0,1] neg_hi:[0,1]
	v_pk_add_f32 v[88:89], v[4:5], v[24:25]
	v_pk_add_f32 v[4:5], v[4:5], v[24:25] neg_lo:[0,1] neg_hi:[0,1]
	s_nop 0
	v_pk_mul_f32 v[24:25], v[4:5], s[54:55] op_sel:[1,0] op_sel_hi:[0,0] neg_hi:[1,0]
	s_nop 0
	v_pk_fma_f32 v[4:5], v[4:5], s[52:53], v[24:25] op_sel_hi:[1,0,1]
	v_pk_add_f32 v[24:25], v[6:7], v[26:27]
	v_pk_add_f32 v[6:7], v[6:7], v[26:27] neg_lo:[0,1] neg_hi:[0,1]
	s_nop 0
	v_pk_mul_f32 v[26:27], v[6:7], s[60:61] op_sel:[1,0] op_sel_hi:[0,0] neg_hi:[1,0]
	s_nop 0
	v_pk_fma_f32 v[6:7], v[6:7], s[60:61], v[26:27] op_sel_hi:[1,0,1]
	v_pk_add_f32 v[26:27], v[8:9], v[28:29]
	v_pk_add_f32 v[8:9], v[8:9], v[28:29] neg_lo:[0,1] neg_hi:[0,1]
	s_nop 0
	v_pk_mul_f32 v[28:29], v[8:9], s[52:53] op_sel:[1,0] op_sel_hi:[0,0] neg_hi:[1,0]
	s_nop 0
	v_pk_fma_f32 v[8:9], v[8:9], s[54:55], v[28:29] op_sel_hi:[1,0,1]
	v_pk_add_f32 v[28:29], v[12:13], v[30:31]
	v_pk_add_f32 v[12:13], v[12:13], v[30:31] neg_lo:[0,1] neg_hi:[0,1]
	s_nop 0
	v_xor_b32_e32 v31, 0x80000000, v12
	v_mov_b32_e32 v30, v13
	v_pk_add_f32 v[12:13], v[14:15], v[32:33]
	v_pk_add_f32 v[14:15], v[14:15], v[32:33] neg_lo:[0,1] neg_hi:[0,1]
	s_nop 0
	v_pk_mul_f32 v[32:33], v[14:15], s[54:55] op_sel_hi:[1,0]
	v_xor_b32_e32 v107, 0x80000000, v14
	v_mov_b32_e32 v106, v15
	v_pk_fma_f32 v[14:15], v[106:107], s[52:53], v[32:33] op_sel_hi:[1,0,1] neg_lo:[0,0,1] neg_hi:[0,0,1]
	v_pk_add_f32 v[32:33], v[16:17], v[34:35]
	v_pk_add_f32 v[16:17], v[16:17], v[34:35] neg_lo:[0,1] neg_hi:[0,1]
	s_nop 0
	v_pk_mul_f32 v[34:35], v[16:17], s[60:61] op_sel_hi:[1,0]
	v_xor_b32_e32 v107, 0x80000000, v16
	v_mov_b32_e32 v106, v17
	v_pk_fma_f32 v[16:17], v[106:107], s[60:61], v[34:35] op_sel_hi:[1,0,1] neg_lo:[0,0,1] neg_hi:[0,0,1]
	v_pk_add_f32 v[34:35], v[20:21], v[36:37]
	v_pk_add_f32 v[20:21], v[20:21], v[36:37] neg_lo:[0,1] neg_hi:[0,1]
	s_nop 0
	v_pk_mul_f32 v[36:37], v[20:21], s[52:53] op_sel_hi:[1,0]
	v_xor_b32_e32 v107, 0x80000000, v20
	v_mov_b32_e32 v106, v21
	v_pk_fma_f32 v[20:21], v[106:107], s[54:55], v[36:37] op_sel_hi:[1,0,1] neg_lo:[0,0,1] neg_hi:[0,0,1]
	v_pk_add_f32 v[36:37], v[102:103], v[92:93]
	v_pk_add_f32 v[92:93], v[102:103], v[92:93] neg_lo:[0,1] neg_hi:[0,1]
	v_pk_add_f32 v[102:103], v[104:105], v[44:45]
	v_pk_add_f32 v[44:45], v[104:105], v[44:45] neg_lo:[0,1] neg_hi:[0,1]
	s_nop 0
	v_pk_mul_f32 v[104:105], v[44:45], s[60:61] op_sel:[1,0] op_sel_hi:[0,0] neg_hi:[1,0]
	s_nop 0
	v_pk_fma_f32 v[44:45], v[44:45], s[60:61], v[104:105] op_sel_hi:[1,0,1]
	v_pk_add_f32 v[104:105], v[38:39], v[96:97]
	v_pk_add_f32 v[38:39], v[38:39], v[96:97] neg_lo:[0,1] neg_hi:[0,1]
	s_nop 0
	v_xor_b32_e32 v97, 0x80000000, v38
	v_mov_b32_e32 v96, v39
	v_pk_add_f32 v[38:39], v[90:91], v[98:99]
	v_pk_add_f32 v[90:91], v[90:91], v[98:99] neg_lo:[0,1] neg_hi:[0,1]
	s_nop 0
	v_pk_mul_f32 v[98:99], v[90:91], s[60:61] op_sel_hi:[1,0]
	v_xor_b32_e32 v107, 0x80000000, v90
	v_mov_b32_e32 v106, v91
	v_pk_fma_f32 v[90:91], v[106:107], s[60:61], v[98:99] op_sel_hi:[1,0,1] neg_lo:[0,0,1] neg_hi:[0,0,1]
	v_pk_add_f32 v[98:99], v[52:53], v[94:95]
	v_pk_add_f32 v[52:53], v[52:53], v[94:95] neg_lo:[0,1] neg_hi:[0,1]
	v_pk_add_f32 v[94:95], v[22:23], v[46:47]
	v_pk_add_f32 v[22:23], v[22:23], v[46:47] neg_lo:[0,1] neg_hi:[0,1]
	s_nop 0
	v_pk_mul_f32 v[46:47], v[22:23], s[60:61] op_sel:[1,0] op_sel_hi:[0,0] neg_hi:[1,0]
	s_nop 0
	v_pk_fma_f32 v[22:23], v[22:23], s[60:61], v[46:47] op_sel_hi:[1,0,1]
	v_pk_add_f32 v[46:47], v[40:41], v[48:49]
	v_pk_add_f32 v[40:41], v[40:41], v[48:49] neg_lo:[0,1] neg_hi:[0,1]
	s_nop 0
	v_xor_b32_e32 v49, 0x80000000, v40
	v_mov_b32_e32 v48, v41
	v_pk_add_f32 v[40:41], v[42:43], v[50:51]
	v_pk_add_f32 v[42:43], v[42:43], v[50:51] neg_lo:[0,1] neg_hi:[0,1]
	s_nop 0
	v_pk_mul_f32 v[50:51], v[42:43], s[60:61] op_sel_hi:[1,0]
	v_xor_b32_e32 v107, 0x80000000, v42
	v_mov_b32_e32 v106, v43
	v_pk_fma_f32 v[42:43], v[106:107], s[60:61], v[50:51] op_sel_hi:[1,0,1] neg_lo:[0,0,1] neg_hi:[0,0,1]
	v_pk_add_f32 v[50:51], v[100:101], v[28:29]
	v_pk_add_f32 v[28:29], v[100:101], v[28:29] neg_lo:[0,1] neg_hi:[0,1]
	v_pk_add_f32 v[100:101], v[88:89], v[12:13]
	v_pk_add_f32 v[12:13], v[88:89], v[12:13] neg_lo:[0,1] neg_hi:[0,1]
	s_nop 0
	v_pk_mul_f32 v[88:89], v[12:13], s[60:61] op_sel:[1,0] op_sel_hi:[0,0] neg_hi:[1,0]
	s_nop 0
	v_pk_fma_f32 v[12:13], v[12:13], s[60:61], v[88:89] op_sel_hi:[1,0,1]
	v_pk_add_f32 v[88:89], v[24:25], v[32:33]
	v_pk_add_f32 v[24:25], v[24:25], v[32:33] neg_lo:[0,1] neg_hi:[0,1]
	v_pk_add_f32 v[108:109], v[50:51], v[88:89]
	v_xor_b32_e32 v33, 0x80000000, v24
	v_mov_b32_e32 v32, v25
	v_pk_add_f32 v[24:25], v[26:27], v[34:35]
	v_pk_add_f32 v[26:27], v[26:27], v[34:35] neg_lo:[0,1] neg_hi:[0,1]
	v_pk_add_f32 v[50:51], v[50:51], v[88:89] neg_lo:[0,1] neg_hi:[0,1]
	v_pk_mul_f32 v[34:35], v[26:27], s[60:61] op_sel_hi:[1,0]
	v_xor_b32_e32 v107, 0x80000000, v26
	v_mov_b32_e32 v106, v27
	v_pk_fma_f32 v[26:27], v[106:107], s[60:61], v[34:35] op_sel_hi:[1,0,1] neg_lo:[0,0,1] neg_hi:[0,0,1]
	v_pk_add_f32 v[34:35], v[2:3], v[30:31]
	v_pk_add_f32 v[2:3], v[2:3], v[30:31] neg_lo:[0,1] neg_hi:[0,1]
	v_pk_add_f32 v[30:31], v[4:5], v[14:15]
	v_pk_add_f32 v[4:5], v[4:5], v[14:15] neg_lo:[0,1] neg_hi:[0,1]
	v_pk_add_f32 v[110:111], v[12:13], v[26:27]
	v_pk_mul_f32 v[14:15], v[4:5], s[60:61] op_sel:[1,0] op_sel_hi:[0,0] neg_hi:[1,0]
	v_pk_add_f32 v[12:13], v[12:13], v[26:27] neg_lo:[0,1] neg_hi:[0,1]
	v_pk_fma_f32 v[4:5], v[4:5], s[60:61], v[14:15] op_sel_hi:[1,0,1]
	v_pk_add_f32 v[14:15], v[6:7], v[16:17]
	v_pk_add_f32 v[6:7], v[6:7], v[16:17] neg_lo:[0,1] neg_hi:[0,1]
	v_pk_add_f32 v[88:89], v[100:101], v[24:25]
	v_xor_b32_e32 v17, 0x80000000, v6
	v_mov_b32_e32 v16, v7
	v_pk_add_f32 v[6:7], v[8:9], v[20:21]
	v_pk_add_f32 v[8:9], v[8:9], v[20:21] neg_lo:[0,1] neg_hi:[0,1]
	v_xor_b32_e32 v113, 0x80000000, v12
	v_pk_mul_f32 v[20:21], v[8:9], s[60:61] op_sel_hi:[1,0]
	s_nop 0
	v_pk_fma_f32 v[8:9], v[8:9], s[60:61], v[20:21] op_sel:[1,0,0] op_sel_hi:[0,0,1] neg_lo:[0,0,1] neg_hi:[1,0,1]
	v_pk_add_f32 v[20:21], v[36:37], v[104:105]
	v_pk_add_f32 v[36:37], v[36:37], v[104:105] neg_lo:[0,1] neg_hi:[0,1]
	v_pk_add_f32 v[104:105], v[102:103], v[38:39]
	v_pk_add_f32 v[38:39], v[102:103], v[38:39] neg_lo:[0,1] neg_hi:[0,1]
	v_pk_add_f32 v[106:107], v[52:53], v[48:49]
	v_xor_b32_e32 v103, 0x80000000, v38
	v_mov_b32_e32 v102, v39
	v_pk_add_f32 v[38:39], v[92:93], v[96:97]
	v_pk_add_f32 v[92:93], v[92:93], v[96:97] neg_lo:[0,1] neg_hi:[0,1]
	v_pk_add_f32 v[96:97], v[44:45], v[90:91]
	v_pk_add_f32 v[44:45], v[44:45], v[90:91] neg_lo:[0,1] neg_hi:[0,1]
	v_pk_add_f32 v[48:49], v[52:53], v[48:49] neg_lo:[0,1] neg_hi:[0,1]
	v_pk_add_f32 v[52:53], v[22:23], v[42:43]
	v_pk_add_f32 v[22:23], v[22:23], v[42:43] neg_lo:[0,1] neg_hi:[0,1]
	v_xor_b32_e32 v91, 0x80000000, v44
	v_mov_b32_e32 v90, v45
	v_pk_add_f32 v[44:45], v[98:99], v[46:47]
	v_pk_add_f32 v[46:47], v[98:99], v[46:47] neg_lo:[0,1] neg_hi:[0,1]
	v_pk_add_f32 v[98:99], v[94:95], v[40:41]
	v_pk_add_f32 v[40:41], v[94:95], v[40:41] neg_lo:[0,1] neg_hi:[0,1]
	v_xor_b32_e32 v43, 0x80000000, v22
	v_mov_b32_e32 v42, v23
	v_pk_add_f32 v[22:23], v[100:101], v[24:25] neg_lo:[0,1] neg_hi:[0,1]
	v_xor_b32_e32 v95, 0x80000000, v40
	v_mov_b32_e32 v94, v41
	v_xor_b32_e32 v25, 0x80000000, v22
	v_mov_b32_e32 v24, v23
	v_pk_add_f32 v[100:101], v[28:29], v[32:33]
	v_pk_add_f32 v[32:33], v[28:29], v[32:33] neg_lo:[0,1] neg_hi:[0,1]
	v_mov_b32_e32 v112, v13
	v_pk_add_f32 v[12:13], v[34:35], v[14:15]
	v_pk_add_f32 v[14:15], v[34:35], v[14:15] neg_lo:[0,1] neg_hi:[0,1]
	v_pk_add_f32 v[34:35], v[30:31], v[6:7]
	v_pk_add_f32 v[6:7], v[30:31], v[6:7] neg_lo:[0,1] neg_hi:[0,1]
	v_pk_add_f32 v[114:115], v[2:3], v[16:17]
	v_pk_add_f32 v[16:17], v[2:3], v[16:17] neg_lo:[0,1] neg_hi:[0,1]
	v_pk_add_f32 v[2:3], v[4:5], v[8:9] neg_lo:[0,1] neg_hi:[0,1]
	v_xor_b32_e32 v31, 0x80000000, v6
	v_mov_b32_e32 v30, v7
	v_pk_add_f32 v[116:117], v[4:5], v[8:9]
	v_xor_b32_e32 v119, 0x80000000, v2
	v_mov_b32_e32 v118, v3
	v_pk_add_f32 v[2:3], v[20:21], v[104:105]
	v_pk_add_f32 v[104:105], v[20:21], v[104:105] neg_lo:[0,1] neg_hi:[0,1]
	v_pk_add_f32 v[120:121], v[36:37], v[102:103]
	v_pk_add_f32 v[26:27], v[36:37], v[102:103] neg_lo:[0,1] neg_hi:[0,1]
	v_pk_add_f32 v[36:37], v[38:39], v[96:97]
	v_pk_add_f32 v[40:41], v[38:39], v[96:97] neg_lo:[0,1] neg_hi:[0,1]
	v_pk_add_f32 v[96:97], v[92:93], v[90:91]
	v_pk_add_f32 v[6:7], v[92:93], v[90:91] neg_lo:[0,1] neg_hi:[0,1]
	v_pk_add_f32 v[20:21], v[44:45], v[98:99]
	v_pk_add_f32 v[90:91], v[44:45], v[98:99] neg_lo:[0,1] neg_hi:[0,1]
	v_pk_add_f32 v[92:93], v[46:47], v[94:95]
	v_pk_add_f32 v[22:23], v[46:47], v[94:95] neg_lo:[0,1] neg_hi:[0,1]
	v_pk_add_f32 v[46:47], v[106:107], v[52:53]
	v_pk_add_f32 v[38:39], v[106:107], v[52:53] neg_lo:[0,1] neg_hi:[0,1]
	v_pk_add_f32 v[52:53], v[50:51], v[24:25]
	v_pk_add_f32 v[28:29], v[50:51], v[24:25] neg_lo:[0,1] neg_hi:[0,1]
	v_pk_add_f32 v[50:51], v[100:101], v[110:111]
	v_pk_add_f32 v[44:45], v[100:101], v[110:111] neg_lo:[0,1] neg_hi:[0,1]
	v_pk_add_f32 v[98:99], v[32:33], v[112:113]
	v_pk_add_f32 v[8:9], v[32:33], v[112:113] neg_lo:[0,1] neg_hi:[0,1]
	v_pk_add_f32 v[32:33], v[12:13], v[34:35]
	v_pk_add_f32 v[100:101], v[12:13], v[34:35] neg_lo:[0,1] neg_hi:[0,1]
	v_cos_f32_e32 v12, v10
	v_sin_f32_e32 v13, v10
	v_pk_add_f32 v[94:95], v[48:49], v[42:43]
	v_pk_add_f32 v[4:5], v[48:49], v[42:43] neg_lo:[0,1] neg_hi:[0,1]
	v_pk_add_f32 v[48:49], v[108:109], v[88:89]
	v_pk_add_f32 v[102:103], v[14:15], v[30:31]
	v_pk_add_f32 v[24:25], v[14:15], v[30:31] neg_lo:[0,1] neg_hi:[0,1]
	v_pk_add_f32 v[106:107], v[16:17], v[118:119]
	v_pk_add_f32 v[10:11], v[16:17], v[118:119] neg_lo:[0,1] neg_hi:[0,1]
	v_pk_mul_f32 v[14:15], v[12:13], v[12:13]
	v_add_f32_e32 v16, v12, v12
	v_pk_add_f32 v[88:89], v[108:109], v[88:89] neg_lo:[0,1] neg_hi:[0,1]
	v_mul_f32_e32 v18, v13, v16
	v_pk_add_f32 v[16:17], v[14:15], v[14:15] op_sel:[0,1] op_sel_hi:[0,1] neg_lo:[0,1] neg_hi:[0,1]
	v_mov_b32_e32 v108, v13
	v_pk_mul_f32 v[14:15], v[12:13], v[18:19] op_sel:[1,0] op_sel_hi:[0,0] neg_lo:[1,0]
	v_pk_mul_f32 v[30:31], v[108:109], v[48:49] op_sel:[0,1] op_sel_hi:[0,0] neg_hi:[0,1]
	v_pk_fma_f32 v[14:15], v[12:13], v[16:17], v[14:15]
	v_pk_fma_f32 v[12:13], v[12:13], v[48:49], v[30:31] op_sel_hi:[0,1,1]
	v_pk_mul_f32 v[30:31], v[18:19], s[46:47] op_sel_hi:[0,1]
	v_pk_fma_f32 v[30:31], v[16:17], s[40:41], v[30:31]
	s_nop 0
	v_pk_mul_f32 v[48:49], v[30:31], v[20:21] op_sel:[1,1] op_sel_hi:[1,0] neg_hi:[0,1]
	s_nop 0
	v_pk_fma_f32 v[20:21], v[20:21], v[30:31], v[48:49] op_sel_hi:[1,0,1]
	v_pk_mul_f32 v[48:49], v[18:19], v[14:15] op_sel:[0,1] op_sel_hi:[0,0] neg_lo:[0,1]
	v_pk_mul_f32 v[108:109], v[14:15], v[32:33] op_sel:[1,1] op_sel_hi:[1,0] neg_hi:[0,1]
	v_pk_fma_f32 v[48:49], v[16:17], v[14:15], v[48:49]
	v_pk_fma_f32 v[14:15], v[14:15], v[32:33], v[108:109] op_sel_hi:[0,1,1]
	v_pk_mul_f32 v[32:33], v[18:19], v[30:31] op_sel:[0,1] op_sel_hi:[0,0] neg_lo:[0,1]
	v_pk_fma_f32 v[108:109], v[16:17], v[30:31], v[32:33]
	s_nop 0
	v_pk_mul_f32 v[30:31], v[36:37], v[108:109] op_sel:[1,1] op_sel_hi:[0,1] neg_hi:[1,0]
	v_pk_add_f32 v[34:35], v[114:115], v[116:117]
	v_pk_fma_f32 v[32:33], v[36:37], v[108:109], v[30:31] op_sel_hi:[1,0,1]
	v_pk_mul_f32 v[30:31], v[18:19], v[48:49] op_sel:[0,1] op_sel_hi:[0,0] neg_lo:[0,1]
	v_pk_fma_f32 v[110:111], v[16:17], v[48:49], v[30:31]
	v_pk_mul_f32 v[30:31], v[48:49], v[50:51] op_sel:[1,1] op_sel_hi:[1,0] neg_hi:[0,1]
	v_pk_mul_f32 v[36:37], v[18:19], v[108:109] op_sel:[0,1] op_sel_hi:[0,0] neg_lo:[0,1]
	v_pk_fma_f32 v[30:31], v[50:51], v[48:49], v[30:31] op_sel_hi:[1,0,1]
	v_pk_fma_f32 v[48:49], v[16:17], v[108:109], v[36:37]
	s_nop 0
	v_pk_mul_f32 v[36:37], v[46:47], v[48:49] op_sel:[1,1] op_sel_hi:[0,1] neg_hi:[1,0]
	s_nop 0
	v_pk_fma_f32 v[36:37], v[46:47], v[48:49], v[36:37] op_sel_hi:[1,0,1]
	v_pk_mul_f32 v[46:47], v[18:19], v[110:111] op_sel:[0,1] op_sel_hi:[0,0] neg_lo:[0,1]
	v_pk_mul_f32 v[50:51], v[110:111], v[34:35] op_sel:[1,1] op_sel_hi:[1,0] neg_hi:[0,1]
	v_pk_fma_f32 v[46:47], v[16:17], v[110:111], v[46:47]
	v_pk_fma_f32 v[34:35], v[34:35], v[110:111], v[50:51] op_sel_hi:[1,0,1]
	v_pk_mul_f32 v[50:51], v[18:19], v[48:49] op_sel:[0,1] op_sel_hi:[0,0] neg_lo:[0,1]
	s_nop 0
	v_pk_fma_f32 v[50:51], v[16:17], v[48:49], v[50:51]
	v_pk_mul_f32 v[108:109], v[18:19], v[46:47] op_sel:[0,1] op_sel_hi:[0,0] neg_lo:[0,1]
	v_pk_mul_f32 v[110:111], v[52:53], v[46:47] op_sel:[1,1] op_sel_hi:[0,1] neg_hi:[1,0]
	v_pk_fma_f32 v[108:109], v[16:17], v[46:47], v[108:109]
	v_pk_fma_f32 v[46:47], v[52:53], v[46:47], v[110:111] op_sel_hi:[1,0,1]
	v_pk_mul_f32 v[48:49], v[120:121], v[50:51] op_sel:[1,1] op_sel_hi:[0,1] neg_hi:[1,0]
	v_pk_mul_f32 v[52:53], v[18:19], v[50:51] op_sel:[0,1] op_sel_hi:[0,0] neg_lo:[0,1]
	v_pk_fma_f32 v[48:49], v[120:121], v[50:51], v[48:49] op_sel_hi:[1,0,1]
	v_pk_fma_f32 v[110:111], v[16:17], v[50:51], v[52:53]
	s_nop 0
	v_pk_mul_f32 v[50:51], v[92:93], v[110:111] op_sel:[1,1] op_sel_hi:[0,1] neg_hi:[1,0]
	v_pk_add_f32 v[42:43], v[114:115], v[116:117] neg_lo:[0,1] neg_hi:[0,1]
	v_pk_fma_f32 v[52:53], v[92:93], v[110:111], v[50:51] op_sel_hi:[1,0,1]
	v_pk_mul_f32 v[50:51], v[18:19], v[108:109] op_sel:[0,1] op_sel_hi:[0,0] neg_lo:[0,1]
	v_pk_fma_f32 v[92:93], v[16:17], v[108:109], v[50:51]
	v_pk_mul_f32 v[50:51], v[102:103], v[108:109] op_sel:[1,1] op_sel_hi:[0,1] neg_hi:[1,0]
	s_nop 0
	v_pk_fma_f32 v[50:51], v[102:103], v[108:109], v[50:51] op_sel_hi:[1,0,1]
	v_pk_mul_f32 v[102:103], v[18:19], v[110:111] op_sel:[0,1] op_sel_hi:[0,0] neg_lo:[0,1]
	v_pk_fma_f32 v[102:103], v[16:17], v[110:111], v[102:103]
	s_nop 0
	v_pk_mul_f32 v[108:109], v[96:97], v[102:103] op_sel:[1,1] op_sel_hi:[0,1] neg_hi:[1,0]
	s_nop 0
	v_pk_fma_f32 v[96:97], v[96:97], v[102:103], v[108:109] op_sel_hi:[1,0,1]
	v_pk_mul_f32 v[108:109], v[18:19], v[92:93] op_sel:[0,1] op_sel_hi:[0,0] neg_lo:[0,1]
	v_pk_mul_f32 v[110:111], v[98:99], v[92:93] op_sel:[1,1] op_sel_hi:[0,1] neg_hi:[1,0]
	v_pk_fma_f32 v[108:109], v[16:17], v[92:93], v[108:109]
	v_pk_fma_f32 v[92:93], v[98:99], v[92:93], v[110:111] op_sel_hi:[1,0,1]
	v_pk_mul_f32 v[98:99], v[18:19], v[102:103] op_sel:[0,1] op_sel_hi:[0,0] neg_lo:[0,1]
	v_pk_fma_f32 v[98:99], v[16:17], v[102:103], v[98:99]
	s_nop 0
	v_pk_mul_f32 v[102:103], v[94:95], v[98:99] op_sel:[1,1] op_sel_hi:[0,1] neg_hi:[1,0]
	s_nop 0
	v_pk_fma_f32 v[94:95], v[94:95], v[98:99], v[102:103] op_sel_hi:[1,0,1]
	v_pk_mul_f32 v[102:103], v[18:19], v[108:109] op_sel:[0,1] op_sel_hi:[0,0] neg_lo:[0,1]
	v_pk_mul_f32 v[110:111], v[106:107], v[108:109] op_sel:[1,1] op_sel_hi:[0,1] neg_hi:[1,0]
	v_pk_fma_f32 v[102:103], v[16:17], v[108:109], v[102:103]
	v_pk_fma_f32 v[106:107], v[106:107], v[108:109], v[110:111] op_sel_hi:[1,0,1]
	v_pk_mul_f32 v[108:109], v[18:19], v[98:99] op_sel:[0,1] op_sel_hi:[0,0] neg_lo:[0,1]
	v_pk_fma_f32 v[98:99], v[16:17], v[98:99], v[108:109]
	s_nop 0
	v_pk_mul_f32 v[108:109], v[104:105], v[98:99] op_sel:[1,1] op_sel_hi:[0,1] neg_hi:[1,0]
	s_nop 0
	v_pk_fma_f32 v[104:105], v[104:105], v[98:99], v[108:109] op_sel_hi:[1,0,1]
	v_pk_mul_f32 v[108:109], v[18:19], v[102:103] op_sel:[0,1] op_sel_hi:[0,0] neg_lo:[0,1]
	v_pk_mul_f32 v[110:111], v[88:89], v[102:103] op_sel:[1,1] op_sel_hi:[0,1] neg_hi:[1,0]
	v_pk_fma_f32 v[108:109], v[16:17], v[102:103], v[108:109]
	v_pk_fma_f32 v[88:89], v[88:89], v[102:103], v[110:111] op_sel_hi:[1,0,1]
	v_pk_mul_f32 v[102:103], v[18:19], v[98:99] op_sel:[0,1] op_sel_hi:[0,0] neg_lo:[0,1]
	v_pk_fma_f32 v[98:99], v[16:17], v[98:99], v[102:103]
	s_nop 0
	v_pk_mul_f32 v[102:103], v[90:91], v[98:99] op_sel:[1,1] op_sel_hi:[0,1] neg_hi:[1,0]
	s_nop 0
	v_pk_fma_f32 v[90:91], v[90:91], v[98:99], v[102:103] op_sel_hi:[1,0,1]
	v_pk_mul_f32 v[102:103], v[18:19], v[108:109] op_sel:[0,1] op_sel_hi:[0,0] neg_lo:[0,1]
	v_pk_mul_f32 v[110:111], v[100:101], v[108:109] op_sel:[1,1] op_sel_hi:[0,1] neg_hi:[1,0]
	v_pk_fma_f32 v[102:103], v[16:17], v[108:109], v[102:103]
	v_pk_fma_f32 v[100:101], v[100:101], v[108:109], v[110:111] op_sel_hi:[1,0,1]
	v_pk_mul_f32 v[108:109], v[18:19], v[98:99] op_sel:[0,1] op_sel_hi:[0,0] neg_lo:[0,1]
	v_pk_fma_f32 v[98:99], v[16:17], v[98:99], v[108:109]
	s_nop 0
	v_pk_mul_f32 v[108:109], v[40:41], v[98:99] op_sel:[1,1] op_sel_hi:[0,1] neg_hi:[1,0]
	s_nop 0
	v_pk_fma_f32 v[40:41], v[40:41], v[98:99], v[108:109] op_sel_hi:[1,0,1]
	v_pk_mul_f32 v[108:109], v[18:19], v[102:103] op_sel:[0,1] op_sel_hi:[0,0] neg_lo:[0,1]
	v_pk_mul_f32 v[110:111], v[44:45], v[102:103] op_sel:[1,1] op_sel_hi:[0,1] neg_hi:[1,0]
	v_pk_fma_f32 v[108:109], v[16:17], v[102:103], v[108:109]
	v_pk_fma_f32 v[44:45], v[44:45], v[102:103], v[110:111] op_sel_hi:[1,0,1]
	v_pk_mul_f32 v[102:103], v[18:19], v[98:99] op_sel:[0,1] op_sel_hi:[0,0] neg_lo:[0,1]
	v_pk_fma_f32 v[98:99], v[16:17], v[98:99], v[102:103]
	s_nop 0
	v_pk_mul_f32 v[102:103], v[38:39], v[98:99] op_sel:[1,1] op_sel_hi:[0,1] neg_hi:[1,0]
	s_nop 0
	v_pk_fma_f32 v[38:39], v[38:39], v[98:99], v[102:103] op_sel_hi:[1,0,1]
	v_pk_mul_f32 v[102:103], v[18:19], v[108:109] op_sel:[0,1] op_sel_hi:[0,0] neg_lo:[0,1]
	v_pk_mul_f32 v[110:111], v[42:43], v[108:109] op_sel:[1,1] op_sel_hi:[0,1] neg_hi:[1,0]
	v_pk_fma_f32 v[102:103], v[16:17], v[108:109], v[102:103]
	v_pk_fma_f32 v[42:43], v[42:43], v[108:109], v[110:111] op_sel_hi:[1,0,1]
	v_pk_mul_f32 v[108:109], v[18:19], v[98:99] op_sel:[0,1] op_sel_hi:[0,0] neg_lo:[0,1]
	v_pk_fma_f32 v[98:99], v[16:17], v[98:99], v[108:109]
	s_nop 0
	v_pk_mul_f32 v[108:109], v[26:27], v[98:99] op_sel:[1,1] op_sel_hi:[0,1] neg_hi:[1,0]
	s_nop 0
	v_pk_fma_f32 v[26:27], v[26:27], v[98:99], v[108:109] op_sel_hi:[1,0,1]
	v_pk_mul_f32 v[108:109], v[18:19], v[102:103] op_sel:[0,1] op_sel_hi:[0,0] neg_lo:[0,1]
	v_pk_mul_f32 v[110:111], v[28:29], v[102:103] op_sel:[1,1] op_sel_hi:[0,1] neg_hi:[1,0]
	v_pk_fma_f32 v[108:109], v[16:17], v[102:103], v[108:109]
	v_pk_fma_f32 v[28:29], v[28:29], v[102:103], v[110:111] op_sel_hi:[1,0,1]
	v_pk_mul_f32 v[102:103], v[18:19], v[98:99] op_sel:[0,1] op_sel_hi:[0,0] neg_lo:[0,1]
	v_pk_fma_f32 v[98:99], v[16:17], v[98:99], v[102:103]
	s_nop 0
	v_pk_mul_f32 v[102:103], v[22:23], v[98:99] op_sel:[1,1] op_sel_hi:[0,1] neg_hi:[1,0]
	s_nop 0
	v_pk_fma_f32 v[22:23], v[22:23], v[98:99], v[102:103] op_sel_hi:[1,0,1]
	v_pk_mul_f32 v[102:103], v[18:19], v[108:109] op_sel:[0,1] op_sel_hi:[0,0] neg_lo:[0,1]
	v_pk_mul_f32 v[110:111], v[24:25], v[108:109] op_sel:[1,1] op_sel_hi:[0,1] neg_hi:[1,0]
	v_pk_fma_f32 v[102:103], v[16:17], v[108:109], v[102:103]
	v_pk_fma_f32 v[24:25], v[24:25], v[108:109], v[110:111] op_sel_hi:[1,0,1]
	v_pk_mul_f32 v[108:109], v[18:19], v[98:99] op_sel:[0,1] op_sel_hi:[0,0] neg_lo:[0,1]
	v_pk_fma_f32 v[98:99], v[16:17], v[98:99], v[108:109]
	s_nop 0
	v_pk_mul_f32 v[108:109], v[6:7], v[98:99] op_sel:[1,1] op_sel_hi:[0,1] neg_hi:[1,0]
	s_nop 0
	v_pk_fma_f32 v[6:7], v[6:7], v[98:99], v[108:109] op_sel_hi:[1,0,1]
	v_pk_mul_f32 v[108:109], v[18:19], v[102:103] op_sel:[0,1] op_sel_hi:[0,0] neg_lo:[0,1]
	v_pk_mul_f32 v[110:111], v[8:9], v[102:103] op_sel:[1,1] op_sel_hi:[0,1] neg_hi:[1,0]
	v_pk_fma_f32 v[108:109], v[16:17], v[102:103], v[108:109]
	v_pk_fma_f32 v[8:9], v[8:9], v[102:103], v[110:111] op_sel_hi:[1,0,1]
	v_pk_mul_f32 v[102:103], v[18:19], v[98:99] op_sel:[0,1] op_sel_hi:[0,0] neg_lo:[0,1]
	v_pk_fma_f32 v[16:17], v[16:17], v[98:99], v[102:103]
	s_nop 0
	v_pk_mul_f32 v[98:99], v[4:5], v[16:17] op_sel:[1,1] op_sel_hi:[0,1] neg_hi:[1,0]
	s_nop 0
	v_pk_fma_f32 v[4:5], v[4:5], v[16:17], v[98:99] op_sel_hi:[1,0,1]
	v_pk_mul_f32 v[16:17], v[10:11], v[108:109] op_sel:[1,1] op_sel_hi:[0,1] neg_hi:[1,0]
	s_nop 0
	v_pk_fma_f32 v[10:11], v[10:11], v[108:109], v[16:17] op_sel_hi:[1,0,1]
	ds_write_b64 v19, v[2:3]
	ds_write_b64 v54, v[104:105]
	ds_write_b64 v55, v[48:49] offset:256
	ds_write_b64 v56, v[26:27] offset:256
	ds_write_b64 v57, v[32:33] offset:512
	ds_write_b64 v58, v[40:41] offset:512
	ds_write_b64 v59, v[96:97] offset:768
	ds_write_b64 v60, v[6:7] offset:768
	ds_write_b64 v61, v[20:21] offset:1024
	ds_write_b64 v62, v[90:91] offset:1024
	ds_write_b64 v63, v[52:53] offset:1280
	ds_write_b64 v64, v[22:23] offset:1280
	ds_write_b64 v65, v[36:37] offset:1536
	ds_write_b64 v66, v[38:39] offset:1536
	ds_write_b64 v67, v[94:95] offset:1792
	ds_write_b64 v71, v[4:5] offset:1792
	ds_write_b64 v72, v[12:13] offset:2048
	ds_write_b64 v73, v[88:89] offset:2048
	ds_write_b64 v74, v[46:47] offset:2304
	ds_write_b64 v75, v[28:29] offset:2304
	ds_write_b64 v76, v[30:31] offset:2560
	ds_write_b64 v77, v[44:45] offset:2560
	ds_write_b64 v78, v[92:93] offset:2816
	ds_write_b64 v79, v[8:9] offset:2816
	ds_write_b64 v80, v[14:15] offset:3072
	ds_write_b64 v81, v[100:101] offset:3072
	ds_write_b64 v82, v[50:51] offset:3328
	ds_write_b64 v83, v[24:25] offset:3328
	ds_write_b64 v84, v[34:35] offset:3584
	ds_write_b64 v85, v[42:43] offset:3584
	ds_write_b64 v86, v[106:107] offset:3840
	ds_write_b64 v87, v[10:11] offset:3840
	v_mov_b32_e32 v2, v146
	s_waitcnt lgkmcnt(0)
	s_barrier
	s_nop 0
	v_lshlrev_b32_e32 v34, 4, v2
	v_lshrrev_b32_e32 v35, 1, v2
	v_bitop3_b32 v3, v35, v34, 16 bitop3:0x6c
	v_lshl_add_u32 v26, v3, 3, 16
	v_bitop3_b32 v3, v35, 1, 15 bitop3:0x6c
	v_bitop3_b32 v11, v35, 5, 15 bitop3:0x6c
	v_bitop3_b32 v19, v35, 9, 15 bitop3:0x6c
	v_lshlrev_b32_e32 v37, 3, v3
	v_bitop3_b32 v3, v35, 2, 15 bitop3:0x6c
	v_lshlrev_b32_e32 v45, 3, v11
	v_bitop3_b32 v11, v35, 6, 15 bitop3:0x6c
	v_lshlrev_b32_e32 v49, 3, v19
	v_bitop3_b32 v19, v35, 10, 15 bitop3:0x6c
	v_bitop3_b32 v29, v35, 14, 15 bitop3:0x6c
	v_add_u32_e32 v34, 0x2000, v34
	v_bfe_u32 v2, v2, 1, 4
	v_lshlrev_b32_e32 v38, 3, v3
	v_bitop3_b32 v3, v35, 3, 15 bitop3:0x6c
	v_bitop3_b32 v10, v35, 4, 15 bitop3:0x6c
	v_lshlrev_b32_e32 v46, 3, v11
	v_bitop3_b32 v11, v35, 7, 15 bitop3:0x6c
	v_bitop3_b32 v18, v35, 8, 15 bitop3:0x6c
	v_lshlrev_b32_e32 v50, 3, v19
	v_bitop3_b32 v19, v35, 11, 15 bitop3:0x6c
	v_bitop3_b32 v27, v35, 12, 15 bitop3:0x6c
	v_bitop3_b32 v28, v35, 13, 15 bitop3:0x6c
	v_lshlrev_b32_e32 v54, 3, v29
	v_bitop3_b32 v29, v35, 15, v35 bitop3:0xc
	v_bitop3_b32 v34, v34, v35, 16 bitop3:0x78
	v_lshlrev_b32_e32 v36, 3, v2
	v_lshlrev_b32_e32 v39, 3, v3
	v_lshlrev_b32_e32 v44, 3, v10
	v_lshlrev_b32_e32 v47, 3, v11
	v_lshlrev_b32_e32 v48, 3, v18
	v_lshlrev_b32_e32 v51, 3, v19
	v_lshlrev_b32_e32 v52, 3, v27
	v_lshlrev_b32_e32 v53, 3, v28
	v_lshlrev_b32_e32 v55, 3, v29
	v_lshl_add_u32 v34, v34, 3, 16
	v_add_u32_e32 v2, v26, v36
	v_add_u32_e32 v4, v26, v37
	v_add_u32_e32 v6, v26, v38
	v_add_u32_e32 v8, v26, v39
	v_add_u32_e32 v10, v26, v44
	v_add_u32_e32 v12, v26, v45
	v_add_u32_e32 v14, v26, v46
	v_add_u32_e32 v16, v26, v47
	v_add_u32_e32 v18, v26, v48
	v_add_u32_e32 v20, v26, v49
	v_add_u32_e32 v22, v26, v50
	v_add_u32_e32 v24, v26, v51
	v_add_u32_e32 v27, v26, v52
	v_add_u32_e32 v28, v26, v53
	v_add_u32_e32 v30, v26, v54
	v_add_u32_e32 v32, v26, v55
	v_add_u32_e32 v35, v34, v36
	v_add_u32_e32 v40, v34, v37
	v_add_u32_e32 v41, v34, v38
	v_add_u32_e32 v42, v34, v39
	ds_read_b64 v[2:3], v2
	ds_read_b64 v[4:5], v4
	ds_read_b64 v[6:7], v6
	ds_read_b64 v[8:9], v8
	ds_read_b64 v[10:11], v10
	ds_read_b64 v[12:13], v12
	ds_read_b64 v[14:15], v14
	ds_read_b64 v[16:17], v16
	ds_read_b64 v[18:19], v18
	ds_read_b64 v[20:21], v20
	ds_read_b64 v[22:23], v22
	ds_read_b64 v[24:25], v24
	ds_read_b64 v[26:27], v27
	ds_read_b64 v[28:29], v28
	ds_read_b64 v[30:31], v30
	ds_read_b64 v[32:33], v32
	ds_read_b64 v[36:37], v35
	ds_read_b64 v[38:39], v40
	ds_read_b64 v[40:41], v41
	ds_read_b64 v[42:43], v42
	v_add_u32_e32 v35, v34, v44
	v_add_u32_e32 v44, v34, v45
	v_add_u32_e32 v45, v34, v46
	v_add_u32_e32 v46, v34, v47
	ds_read_b64 v[72:73], v35
	ds_read_b64 v[74:75], v44
	ds_read_b64 v[76:77], v45
	ds_read_b64 v[78:79], v46
	v_add_u32_e32 v35, v34, v48
	v_add_u32_e32 v44, v34, v49
	v_add_u32_e32 v45, v34, v50
	v_add_u32_e32 v46, v34, v51
	ds_read_b64 v[80:81], v35
	ds_read_b64 v[82:83], v44
	ds_read_b64 v[84:85], v45
	ds_read_b64 v[86:87], v46
	v_add_u32_e32 v35, v34, v52
	v_add_u32_e32 v44, v34, v53
	v_add_u32_e32 v45, v34, v54
	v_add_u32_e32 v34, v34, v55
	ds_read_b64 v[88:89], v35
	ds_read_b64 v[90:91], v44
	ds_read_b64 v[92:93], v45
	ds_read_b64 v[94:95], v34
	s_waitcnt lgkmcnt(14)
	v_pk_add_f32 v[34:35], v[2:3], v[18:19]
	v_pk_add_f32 v[2:3], v[2:3], v[18:19] neg_lo:[0,1] neg_hi:[0,1]
	v_pk_add_f32 v[18:19], v[4:5], v[20:21]
	v_pk_add_f32 v[4:5], v[4:5], v[20:21] neg_lo:[0,1] neg_hi:[0,1]
	s_nop 0
	v_pk_mul_f32 v[20:21], v[4:5], s[54:55] op_sel:[1,0] op_sel_hi:[0,0] neg_hi:[1,0]
	s_nop 0
	v_pk_fma_f32 v[4:5], v[4:5], s[52:53], v[20:21] op_sel_hi:[1,0,1]
	v_pk_add_f32 v[20:21], v[6:7], v[22:23]
	v_pk_add_f32 v[6:7], v[6:7], v[22:23] neg_lo:[0,1] neg_hi:[0,1]
	s_nop 0
	v_pk_mul_f32 v[22:23], v[6:7], s[60:61] op_sel:[1,0] op_sel_hi:[0,0] neg_hi:[1,0]
	s_nop 0
	v_pk_fma_f32 v[6:7], v[6:7], s[60:61], v[22:23] op_sel_hi:[1,0,1]
	v_pk_add_f32 v[22:23], v[8:9], v[24:25]
	v_pk_add_f32 v[8:9], v[8:9], v[24:25] neg_lo:[0,1] neg_hi:[0,1]
	s_nop 0
	v_pk_mul_f32 v[24:25], v[8:9], s[52:53] op_sel:[1,0] op_sel_hi:[0,0] neg_hi:[1,0]
	s_nop 0
	v_pk_fma_f32 v[8:9], v[8:9], s[54:55], v[24:25] op_sel_hi:[1,0,1]
	v_pk_add_f32 v[24:25], v[10:11], v[26:27]
	v_pk_add_f32 v[10:11], v[10:11], v[26:27] neg_lo:[0,1] neg_hi:[0,1]
	s_nop 0
	v_xor_b32_e32 v27, 0x80000000, v10
	v_mov_b32_e32 v26, v11
	v_pk_add_f32 v[10:11], v[12:13], v[28:29]
	v_pk_add_f32 v[12:13], v[12:13], v[28:29] neg_lo:[0,1] neg_hi:[0,1]
	s_nop 0
	v_pk_mul_f32 v[28:29], v[12:13], s[54:55] op_sel_hi:[1,0]
	v_xor_b32_e32 v45, 0x80000000, v12
	v_mov_b32_e32 v44, v13
	v_pk_fma_f32 v[12:13], v[44:45], s[52:53], v[28:29] op_sel_hi:[1,0,1] neg_lo:[0,0,1] neg_hi:[0,0,1]
	v_pk_add_f32 v[28:29], v[14:15], v[30:31]
	v_pk_add_f32 v[14:15], v[14:15], v[30:31] neg_lo:[0,1] neg_hi:[0,1]
	s_nop 0
	v_pk_mul_f32 v[30:31], v[14:15], s[60:61] op_sel_hi:[1,0]
	v_xor_b32_e32 v45, 0x80000000, v14
	v_mov_b32_e32 v44, v15
	v_pk_fma_f32 v[14:15], v[44:45], s[60:61], v[30:31] op_sel_hi:[1,0,1] neg_lo:[0,0,1] neg_hi:[0,0,1]
	v_pk_add_f32 v[30:31], v[16:17], v[32:33]
	v_pk_add_f32 v[16:17], v[16:17], v[32:33] neg_lo:[0,1] neg_hi:[0,1]
	s_nop 0
	v_pk_mul_f32 v[32:33], v[16:17], s[52:53] op_sel_hi:[1,0]
	v_xor_b32_e32 v45, 0x80000000, v16
	v_mov_b32_e32 v44, v17
	v_pk_fma_f32 v[16:17], v[44:45], s[54:55], v[32:33] op_sel_hi:[1,0,1] neg_lo:[0,0,1] neg_hi:[0,0,1]
	v_pk_add_f32 v[32:33], v[34:35], v[24:25]
	v_pk_add_f32 v[24:25], v[34:35], v[24:25] neg_lo:[0,1] neg_hi:[0,1]
	v_pk_add_f32 v[34:35], v[18:19], v[10:11]
	v_pk_add_f32 v[10:11], v[18:19], v[10:11] neg_lo:[0,1] neg_hi:[0,1]
	s_nop 0
	v_pk_mul_f32 v[18:19], v[10:11], s[60:61] op_sel:[1,0] op_sel_hi:[0,0] neg_hi:[1,0]
	s_nop 0
	v_pk_fma_f32 v[10:11], v[10:11], s[60:61], v[18:19] op_sel_hi:[1,0,1]
	v_pk_add_f32 v[18:19], v[20:21], v[28:29]
	v_pk_add_f32 v[20:21], v[20:21], v[28:29] neg_lo:[0,1] neg_hi:[0,1]
	s_nop 0
	v_xor_b32_e32 v29, 0x80000000, v20
	v_mov_b32_e32 v28, v21
	v_pk_add_f32 v[20:21], v[22:23], v[30:31]
	v_pk_add_f32 v[22:23], v[22:23], v[30:31] neg_lo:[0,1] neg_hi:[0,1]
	s_nop 0
	v_pk_mul_f32 v[30:31], v[22:23], s[60:61] op_sel_hi:[1,0]
	v_xor_b32_e32 v45, 0x80000000, v22
	v_mov_b32_e32 v44, v23
	v_pk_fma_f32 v[22:23], v[44:45], s[60:61], v[30:31] op_sel_hi:[1,0,1] neg_lo:[0,0,1] neg_hi:[0,0,1]
	v_pk_add_f32 v[30:31], v[2:3], v[26:27]
	v_pk_add_f32 v[2:3], v[2:3], v[26:27] neg_lo:[0,1] neg_hi:[0,1]
	v_pk_add_f32 v[26:27], v[4:5], v[12:13]
	v_pk_add_f32 v[4:5], v[4:5], v[12:13] neg_lo:[0,1] neg_hi:[0,1]
	s_nop 0
	v_pk_mul_f32 v[12:13], v[4:5], s[60:61] op_sel:[1,0] op_sel_hi:[0,0] neg_hi:[1,0]
	s_nop 0
	v_pk_fma_f32 v[4:5], v[4:5], s[60:61], v[12:13] op_sel_hi:[1,0,1]
	v_pk_add_f32 v[12:13], v[6:7], v[14:15]
	v_pk_add_f32 v[6:7], v[6:7], v[14:15] neg_lo:[0,1] neg_hi:[0,1]
	s_nop 0
	v_xor_b32_e32 v15, 0x80000000, v6
	v_mov_b32_e32 v14, v7
	v_pk_add_f32 v[6:7], v[8:9], v[16:17]
	v_pk_add_f32 v[8:9], v[8:9], v[16:17] neg_lo:[0,1] neg_hi:[0,1]
	s_nop 0
	v_pk_mul_f32 v[16:17], v[8:9], s[60:61] op_sel_hi:[1,0]
	s_nop 0
	v_pk_fma_f32 v[8:9], v[8:9], s[60:61], v[16:17] op_sel:[1,0,0] op_sel_hi:[0,0,1] neg_lo:[0,0,1] neg_hi:[1,0,1]
	v_pk_add_f32 v[16:17], v[32:33], v[18:19]
	v_pk_add_f32 v[18:19], v[32:33], v[18:19] neg_lo:[0,1] neg_hi:[0,1]
	v_pk_add_f32 v[32:33], v[34:35], v[20:21]
	v_pk_add_f32 v[20:21], v[34:35], v[20:21] neg_lo:[0,1] neg_hi:[0,1]
	v_pk_add_f32 v[66:67], v[16:17], v[32:33]
	v_xor_b32_e32 v35, 0x80000000, v20
	v_mov_b32_e32 v34, v21
	v_pk_add_f32 v[20:21], v[24:25], v[28:29]
	v_pk_add_f32 v[24:25], v[24:25], v[28:29] neg_lo:[0,1] neg_hi:[0,1]
	v_pk_add_f32 v[28:29], v[10:11], v[22:23]
	v_pk_add_f32 v[10:11], v[10:11], v[22:23] neg_lo:[0,1] neg_hi:[0,1]
	v_pk_add_f32 v[58:59], v[20:21], v[28:29]
	v_xor_b32_e32 v23, 0x80000000, v10
	v_mov_b32_e32 v22, v11
	v_pk_add_f32 v[10:11], v[30:31], v[12:13]
	v_pk_add_f32 v[12:13], v[30:31], v[12:13] neg_lo:[0,1] neg_hi:[0,1]
	v_pk_add_f32 v[30:31], v[26:27], v[6:7]
	v_pk_add_f32 v[6:7], v[26:27], v[6:7] neg_lo:[0,1] neg_hi:[0,1]
	v_pk_add_f32 v[54:55], v[24:25], v[22:23]
	v_xor_b32_e32 v27, 0x80000000, v6
	v_mov_b32_e32 v26, v7
	v_pk_add_f32 v[6:7], v[2:3], v[14:15]
	v_pk_add_f32 v[2:3], v[2:3], v[14:15] neg_lo:[0,1] neg_hi:[0,1]
	v_pk_add_f32 v[14:15], v[4:5], v[8:9]
	v_pk_add_f32 v[4:5], v[4:5], v[8:9] neg_lo:[0,1] neg_hi:[0,1]
	v_pk_add_f32 v[52:53], v[24:25], v[22:23] neg_lo:[0,1] neg_hi:[0,1]
	v_pk_add_f32 v[50:51], v[10:11], v[30:31]
	v_pk_add_f32 v[48:49], v[10:11], v[30:31] neg_lo:[0,1] neg_hi:[0,1]
	v_pk_add_f32 v[46:47], v[12:13], v[26:27]
	v_pk_add_f32 v[44:45], v[12:13], v[26:27] neg_lo:[0,1] neg_hi:[0,1]
	v_pk_add_f32 v[30:31], v[2:3], v[4:5] op_sel:[0,1] op_sel_hi:[1,0] neg_hi:[0,1]
	v_pk_add_f32 v[26:27], v[2:3], v[4:5] op_sel:[0,1] op_sel_hi:[1,0] neg_lo:[0,1]
	s_waitcnt lgkmcnt(6)
	v_pk_add_f32 v[8:9], v[38:39], v[82:83] neg_lo:[0,1] neg_hi:[0,1]
	s_waitcnt lgkmcnt(2)
	v_pk_add_f32 v[24:25], v[74:75], v[90:91] neg_lo:[0,1] neg_hi:[0,1]
	v_pk_add_f32 v[56:57], v[20:21], v[28:29] neg_lo:[0,1] neg_hi:[0,1]
	v_pk_add_f32 v[2:3], v[36:37], v[80:81]
	v_pk_add_f32 v[4:5], v[36:37], v[80:81] neg_lo:[0,1] neg_hi:[0,1]
	v_pk_mul_f32 v[28:29], v[24:25], s[54:55] op_sel_hi:[1,0]
	v_pk_add_f32 v[64:65], v[16:17], v[32:33] neg_lo:[0,1] neg_hi:[0,1]
	v_pk_mul_f32 v[10:11], v[8:9], s[54:55] op_sel:[1,0] op_sel_hi:[0,0] neg_hi:[1,0]
	v_pk_add_f32 v[12:13], v[40:41], v[84:85] neg_lo:[0,1] neg_hi:[0,1]
	v_pk_add_f32 v[16:17], v[42:43], v[86:87] neg_lo:[0,1] neg_hi:[0,1]
	v_pk_fma_f32 v[24:25], v[24:25], s[52:53], v[28:29] op_sel:[1,0,0] op_sel_hi:[0,0,1] neg_lo:[0,0,1] neg_hi:[1,0,1]
	s_waitcnt lgkmcnt(1)
	v_pk_add_f32 v[36:37], v[76:77], v[92:93] neg_lo:[0,1] neg_hi:[0,1]
	v_pk_add_f32 v[62:63], v[18:19], v[34:35]
	v_pk_add_f32 v[60:61], v[18:19], v[34:35] neg_lo:[0,1] neg_hi:[0,1]
	v_pk_add_f32 v[34:35], v[6:7], v[14:15]
	v_pk_add_f32 v[32:33], v[6:7], v[14:15] neg_lo:[0,1] neg_hi:[0,1]
	v_pk_add_f32 v[6:7], v[38:39], v[82:83]
	v_pk_fma_f32 v[8:9], v[8:9], s[52:53], v[10:11] op_sel_hi:[1,0,1]
	v_pk_add_f32 v[10:11], v[40:41], v[84:85]
	v_pk_mul_f32 v[38:39], v[36:37], s[60:61] op_sel_hi:[1,0]
	v_pk_mul_f32 v[14:15], v[12:13], s[60:61] op_sel:[1,0] op_sel_hi:[0,0] neg_hi:[1,0]
	v_pk_mul_f32 v[18:19], v[16:17], s[52:53] op_sel:[1,0] op_sel_hi:[0,0] neg_hi:[1,0]
	v_pk_add_f32 v[20:21], v[72:73], v[88:89] neg_lo:[0,1] neg_hi:[0,1]
	v_pk_fma_f32 v[36:37], v[36:37], s[60:61], v[38:39] op_sel:[1,0,0] op_sel_hi:[0,0,1] neg_lo:[0,0,1] neg_hi:[1,0,1]
	s_waitcnt lgkmcnt(0)
	v_pk_add_f32 v[40:41], v[78:79], v[94:95] neg_lo:[0,1] neg_hi:[0,1]
	v_pk_fma_f32 v[12:13], v[12:13], s[60:61], v[14:15] op_sel_hi:[1,0,1]
	v_pk_add_f32 v[14:15], v[42:43], v[86:87]
	v_pk_fma_f32 v[16:17], v[16:17], s[54:55], v[18:19] op_sel_hi:[1,0,1]
	v_pk_add_f32 v[18:19], v[72:73], v[88:89]
	v_xor_b32_e32 v23, 0x80000000, v20
	v_mov_b32_e32 v22, v21
	v_pk_add_f32 v[20:21], v[74:75], v[90:91]
	v_pk_mul_f32 v[42:43], v[40:41], s[52:53] op_sel_hi:[1,0]
	v_xor_b32_e32 v73, 0x80000000, v40
	v_mov_b32_e32 v72, v41
	v_pk_fma_f32 v[40:41], v[72:73], s[54:55], v[42:43] op_sel_hi:[1,0,1] neg_lo:[0,0,1] neg_hi:[0,0,1]
	v_pk_add_f32 v[42:43], v[2:3], v[18:19]
	v_pk_add_f32 v[2:3], v[2:3], v[18:19] neg_lo:[0,1] neg_hi:[0,1]
	v_pk_add_f32 v[18:19], v[6:7], v[20:21]
	v_pk_add_f32 v[6:7], v[6:7], v[20:21] neg_lo:[0,1] neg_hi:[0,1]
	v_pk_add_f32 v[28:29], v[76:77], v[92:93]
	v_pk_mul_f32 v[20:21], v[6:7], s[60:61] op_sel:[1,0] op_sel_hi:[0,0] neg_hi:[1,0]
	v_pk_add_f32 v[38:39], v[78:79], v[94:95]
	v_pk_fma_f32 v[6:7], v[6:7], s[60:61], v[20:21] op_sel_hi:[1,0,1]
	v_pk_add_f32 v[20:21], v[10:11], v[28:29]
	v_pk_add_f32 v[10:11], v[10:11], v[28:29] neg_lo:[0,1] neg_hi:[0,1]
	s_nop 0
	v_xor_b32_e32 v29, 0x80000000, v10
	v_mov_b32_e32 v28, v11
	v_pk_add_f32 v[10:11], v[14:15], v[38:39]
	v_pk_add_f32 v[14:15], v[14:15], v[38:39] neg_lo:[0,1] neg_hi:[0,1]
	s_nop 0
	v_pk_mul_f32 v[38:39], v[14:15], s[60:61] op_sel_hi:[1,0]
	v_xor_b32_e32 v73, 0x80000000, v14
	v_mov_b32_e32 v72, v15
	v_pk_fma_f32 v[14:15], v[72:73], s[60:61], v[38:39] op_sel_hi:[1,0,1] neg_lo:[0,0,1] neg_hi:[0,0,1]
	v_pk_add_f32 v[38:39], v[4:5], v[22:23]
	v_pk_add_f32 v[4:5], v[4:5], v[22:23] neg_lo:[0,1] neg_hi:[0,1]
	v_pk_add_f32 v[22:23], v[8:9], v[24:25]
	v_pk_add_f32 v[8:9], v[8:9], v[24:25] neg_lo:[0,1] neg_hi:[0,1]
	s_nop 0
	v_pk_mul_f32 v[24:25], v[8:9], s[60:61] op_sel:[1,0] op_sel_hi:[0,0] neg_hi:[1,0]
	s_nop 0
	v_pk_fma_f32 v[8:9], v[8:9], s[60:61], v[24:25] op_sel_hi:[1,0,1]
	v_pk_add_f32 v[24:25], v[12:13], v[36:37]
	v_pk_add_f32 v[12:13], v[12:13], v[36:37] neg_lo:[0,1] neg_hi:[0,1]
	v_pk_add_f32 v[74:75], v[38:39], v[24:25] neg_lo:[0,1] neg_hi:[0,1]
	v_xor_b32_e32 v37, 0x80000000, v12
	v_mov_b32_e32 v36, v13
	v_pk_add_f32 v[12:13], v[16:17], v[40:41]
	v_pk_add_f32 v[16:17], v[16:17], v[40:41] neg_lo:[0,1] neg_hi:[0,1]
	v_pk_add_f32 v[76:77], v[22:23], v[12:13]
	v_pk_mul_f32 v[40:41], v[16:17], s[60:61] op_sel_hi:[1,0]
	s_nop 0
	v_pk_fma_f32 v[16:17], v[16:17], s[60:61], v[40:41] op_sel:[1,0,0] op_sel_hi:[0,0,1] neg_lo:[0,0,1] neg_hi:[1,0,1]
	v_pk_add_f32 v[72:73], v[18:19], v[10:11]
	v_pk_add_f32 v[10:11], v[18:19], v[10:11] neg_lo:[0,1] neg_hi:[0,1]
	v_pk_add_f32 v[12:13], v[22:23], v[12:13] neg_lo:[0,1] neg_hi:[0,1]
	v_xor_b32_e32 v19, 0x80000000, v10
	v_mov_b32_e32 v18, v11
	v_pk_add_f32 v[10:11], v[2:3], v[28:29]
	v_pk_add_f32 v[2:3], v[2:3], v[28:29] neg_lo:[0,1] neg_hi:[0,1]
	v_pk_add_f32 v[28:29], v[6:7], v[14:15]
	v_pk_add_f32 v[6:7], v[6:7], v[14:15] neg_lo:[0,1] neg_hi:[0,1]
	v_pk_add_f32 v[22:23], v[10:11], v[28:29] neg_lo:[0,1] neg_hi:[0,1]
	v_xor_b32_e32 v15, 0x80000000, v6
	v_mov_b32_e32 v14, v7
	v_pk_add_f32 v[6:7], v[38:39], v[24:25]
	v_pk_add_f32 v[24:25], v[10:11], v[28:29]
	v_mov_b32_e32 v28, v146
	v_pk_add_f32 v[40:41], v[42:43], v[20:21]
	v_pk_add_f32 v[20:21], v[42:43], v[20:21] neg_lo:[0,1] neg_hi:[0,1]
	v_lshlrev_b32_e32 v71, 4, v28
	v_lshrrev_b32_e32 v29, 1, v28
	v_pk_add_f32 v[42:43], v[40:41], v[72:73]
	v_pk_add_f32 v[40:41], v[40:41], v[72:73] neg_lo:[0,1] neg_hi:[0,1]
	v_bfe_u32 v28, v28, 1, 4
	v_bitop3_b32 v72, v29, v71, 16 bitop3:0x6c
	v_lshl_add_u32 v72, v72, 3, 16
	v_lshlrev_b32_e32 v28, 3, v28
	v_add_u32_e32 v73, v72, v28
	ds_write_b64 v73, v[66:67]
	v_bitop3_b32 v73, v29, 1, 15 bitop3:0x6c
	v_xor_b32_e32 v79, 0x80000000, v12
	v_mov_b32_e32 v78, v13
	v_lshlrev_b32_e32 v73, 3, v73
	v_pk_add_f32 v[12:13], v[74:75], v[78:79]
	v_pk_add_f32 v[10:11], v[74:75], v[78:79] neg_lo:[0,1] neg_hi:[0,1]
	v_add_u32_e32 v74, v72, v73
	ds_write_b64 v74, v[64:65]
	v_bitop3_b32 v74, v29, 2, 15 bitop3:0x6c
	v_lshlrev_b32_e32 v74, 3, v74
	v_add_u32_e32 v75, v72, v74
	ds_write_b64 v75, v[62:63]
	v_bitop3_b32 v75, v29, 3, 15 bitop3:0x6c
	v_lshlrev_b32_e32 v75, 3, v75
	v_pk_add_f32 v[80:81], v[4:5], v[36:37]
	v_pk_add_f32 v[82:83], v[4:5], v[36:37] neg_lo:[0,1] neg_hi:[0,1]
	v_pk_add_f32 v[4:5], v[8:9], v[16:17]
	v_pk_add_f32 v[8:9], v[8:9], v[16:17] neg_lo:[0,1] neg_hi:[0,1]
	v_pk_add_f32 v[38:39], v[20:21], v[18:19]
	v_pk_add_f32 v[36:37], v[20:21], v[18:19] neg_lo:[0,1] neg_hi:[0,1]
	v_pk_add_f32 v[20:21], v[2:3], v[14:15]
	v_pk_add_f32 v[18:19], v[2:3], v[14:15] neg_lo:[0,1] neg_hi:[0,1]
	v_pk_add_f32 v[16:17], v[6:7], v[76:77]
	v_pk_add_f32 v[14:15], v[6:7], v[76:77] neg_lo:[0,1] neg_hi:[0,1]
	v_add_u32_e32 v76, v72, v75
	ds_write_b64 v76, v[60:61]
	v_bitop3_b32 v76, v29, 4, 15 bitop3:0x6c
	v_lshlrev_b32_e32 v76, 3, v76
	v_add_u32_e32 v77, v72, v76
	ds_write_b64 v77, v[58:59]
	v_bitop3_b32 v77, v29, 5, 15 bitop3:0x6c
	v_lshlrev_b32_e32 v77, 3, v77
	v_add_u32_e32 v78, v72, v77
	ds_write_b64 v78, v[56:57]
	v_bitop3_b32 v78, v29, 6, 15 bitop3:0x6c
	v_lshlrev_b32_e32 v78, 3, v78
	v_add_u32_e32 v79, v72, v78
	ds_write_b64 v79, v[54:55]
	v_bitop3_b32 v79, v29, 7, 15 bitop3:0x6c
	v_lshlrev_b32_e32 v79, 3, v79
	v_xor_b32_e32 v85, 0x80000000, v8
	v_mov_b32_e32 v84, v9
	v_pk_add_f32 v[8:9], v[80:81], v[4:5]
	v_pk_add_f32 v[6:7], v[80:81], v[4:5] neg_lo:[0,1] neg_hi:[0,1]
	v_add_u32_e32 v80, v72, v79
	ds_write_b64 v80, v[52:53]
	v_bitop3_b32 v80, v29, 8, 15 bitop3:0x6c
	v_lshlrev_b32_e32 v80, 3, v80
	v_add_u32_e32 v81, v72, v80
	ds_write_b64 v81, v[50:51]
	v_bitop3_b32 v81, v29, 9, 15 bitop3:0x6c
	v_lshlrev_b32_e32 v81, 3, v81
	v_pk_add_f32 v[4:5], v[82:83], v[84:85]
	v_pk_add_f32 v[2:3], v[82:83], v[84:85] neg_lo:[0,1] neg_hi:[0,1]
	v_add_u32_e32 v82, v72, v81
	ds_write_b64 v82, v[48:49]
	v_bitop3_b32 v82, v29, 10, 15 bitop3:0x6c
	v_lshlrev_b32_e32 v82, 3, v82
	v_add_u32_e32 v83, v72, v82
	ds_write_b64 v83, v[46:47]
	v_bitop3_b32 v83, v29, 11, 15 bitop3:0x6c
	v_lshlrev_b32_e32 v83, 3, v83
	v_add_u32_e32 v84, v72, v83
	ds_write_b64 v84, v[44:45]
	v_bitop3_b32 v84, v29, 12, 15 bitop3:0x6c
	v_lshlrev_b32_e32 v84, 3, v84
	v_add_u32_e32 v85, v72, v84
	ds_write_b64 v85, v[34:35]
	v_bitop3_b32 v85, v29, 13, 15 bitop3:0x6c
	v_lshlrev_b32_e32 v85, 3, v85
	v_add_u32_e32 v86, v72, v85
	ds_write_b64 v86, v[32:33]
	v_bitop3_b32 v86, v29, 14, 15 bitop3:0x6c
	v_lshlrev_b32_e32 v86, 3, v86
	v_add_u32_e32 v87, v72, v86
	v_add_u32_e32 v88, 0x2000, v71
	ds_write_b64 v87, v[30:31]
	v_bitop3_b32 v87, v29, 15, v29 bitop3:0xc
	v_bitop3_b32 v29, v88, v29, 16 bitop3:0x78
	v_lshlrev_b32_e32 v87, 3, v87
	v_lshl_add_u32 v29, v29, 3, 16
	v_add_u32_e32 v72, v72, v87
	v_add_u32_e32 v28, v29, v28
	ds_write_b64 v72, v[26:27]
	ds_write_b64 v28, v[42:43]
	v_add_u32_e32 v28, v29, v73
	ds_write_b64 v28, v[40:41]
	v_add_u32_e32 v28, v29, v74
	ds_write_b64 v28, v[38:39]
	v_add_u32_e32 v28, v29, v75
	ds_write_b64 v28, v[36:37]
	v_add_u32_e32 v28, v29, v76
	ds_write_b64 v28, v[24:25]
	v_add_u32_e32 v28, v29, v77
	ds_write_b64 v28, v[22:23]
	v_add_u32_e32 v28, v29, v78
	ds_write_b64 v28, v[20:21]
	v_add_u32_e32 v28, v29, v79
	ds_write_b64 v28, v[18:19]
	v_add_u32_e32 v28, v29, v80
	ds_write_b64 v28, v[16:17]
	v_add_u32_e32 v28, v29, v81
	ds_write_b64 v28, v[14:15]
	v_add_u32_e32 v28, v29, v82
	v_or_b32_e32 v72, 1, v71
	ds_write_b64 v28, v[12:13]
	v_add_u32_e32 v28, v29, v83
	v_bfrev_b32_e32 v72, v72
	ds_write_b64 v28, v[10:11]
	v_add_u32_e32 v28, v29, v84
	v_lshrrev_b32_e32 v72, 18, v72
	ds_write_b64 v28, v[8:9]
	v_add_u32_e32 v28, v29, v85
	v_sub_u32_e32 v72, 0, v72
	ds_write_b64 v28, v[6:7]
	v_add_u32_e32 v28, v29, v86
	v_and_b32_e32 v72, 0x3fff, v72
	ds_write_b64 v28, v[4:5]
	v_add_u32_e32 v28, v29, v87
	v_bfrev_b32_e32 v72, v72
	ds_write_b64 v28, v[2:3]
	v_lshl_add_u64 v[28:29], v[0:1], 2, s[0:1]
	v_bfrev_b32_e32 v0, v71
	v_lshrrev_b32_e32 v73, 18, v72
	v_lshrrev_b32_e32 v72, 23, v72
	v_lshrrev_b32_e32 v0, 18, v0
	v_bitop3_b32 v72, v72, v73, 31 bitop3:0x6c
	v_or_b32_e32 v73, 2, v71
	v_sub_u32_e32 v0, 0, v0
	v_bfrev_b32_e32 v73, v73
	v_and_b32_e32 v0, 0x3fff, v0
	v_lshrrev_b32_e32 v73, 18, v73
	v_bfrev_b32_e32 v0, v0
	v_sub_u32_e32 v73, 0, v73
	v_lshrrev_b32_e32 v1, 18, v0
	v_lshrrev_b32_e32 v0, 23, v0
	v_and_b32_e32 v74, 0x3fff, v73
	v_bitop3_b32 v0, v0, v1, 31 bitop3:0x6c
	v_bfrev_b32_e32 v74, v74
	v_and_b32_e32 v73, 0x1fff, v73
	v_lshl_add_u32 v0, v0, 3, 16
	v_lshrrev_b32_e32 v75, 18, v74
	v_lshrrev_b32_e32 v74, 23, v74
	v_bfrev_b32_e32 v73, v73
	s_waitcnt lgkmcnt(0)
	s_barrier
	ds_read_b64 v[0:1], v0
	v_bitop3_b32 v74, v74, v75, 31 bitop3:0x6c
	v_lshrrev_b32_e32 v75, 18, v73
	v_lshrrev_b32_e32 v73, 23, v73
	v_bitop3_b32 v73, v73, v75, 31 bitop3:0x6c
	v_lshl_add_u32 v72, v72, 3, 16
	v_lshl_add_u32 v74, v74, 3, 16
	v_lshl_add_u32 v76, v73, 3, 16
	ds_read_b64 v[72:73], v72
	ds_read_b64 v[74:75], v74
	ds_read_b64 v[76:77], v76
	s_waitcnt lgkmcnt(3)
	v_pk_add_f32 v[78:79], v[66:67], v[0:1]
	v_sub_f32_e32 v1, v67, v1
	v_sub_f32_e32 v0, v0, v66
	v_mul_f32_e32 v67, 0.5, v1
	v_mul_f32_e32 v66, 0.5, v0
	s_waitcnt lgkmcnt(2)
	v_pk_add_f32 v[0:1], v[64:65], v[72:73]
	v_mul_f32_e32 v78, 0.5, v78
	v_mul_f32_e32 v80, 0.5, v0
	v_sub_f32_e32 v0, v65, v73
	v_mul_f32_e32 v65, 0.5, v0
	v_sub_f32_e32 v0, v72, v64
	v_mul_f32_e32 v73, 0.5, v1
	v_mul_f32_e32 v64, 0.5, v0
	s_waitcnt lgkmcnt(1)
	v_pk_add_f32 v[0:1], v[62:63], v[74:75]
	s_mov_b32 s0, 0x10000
	v_mul_f32_e32 v72, 0.5, v0
	v_sub_f32_e32 v0, v63, v75
	v_mul_f32_e32 v75, 0.5, v0
	v_sub_f32_e32 v0, v74, v62
	v_mul_f32_e32 v81, 0.5, v1
	v_mul_f32_e32 v74, 0.5, v0
	s_waitcnt lgkmcnt(0)
	v_pk_add_f32 v[0:1], v[60:61], v[76:77]
	v_sub_f32_e32 v61, v61, v77
	v_mul_f32_e32 v0, 0.5, v0
	v_mul_f32_e32 v61, 0.5, v61
	v_sub_f32_e32 v60, v76, v60
	v_mul_f32_e32 v79, 0.5, v79
	v_mul_f32_e32 v1, 0.5, v1
	v_mul_f32_e32 v76, 0.5, v60
	v_cvt_pk_f16_f32 v63, v0, v61
	v_cvt_pk_f16_f32 v62, v72, v75
	v_cvt_pk_f16_f32 v61, v80, v65
	v_cvt_pk_f16_f32 v60, v78, v67
	v_add_co_u32_e32 v0, vcc, s0, v28
	global_store_dwordx4 v[28:29], v[60:63], off offset:-4096
	v_readlane_b32 s0, v252, 50
	s_add_u32 s64, s0, s10
	v_cvt_pk_f16_f32 v63, v1, v76
	v_cvt_pk_f16_f32 v62, v81, v74
	v_cvt_pk_f16_f32 v61, v73, v64
	v_cvt_pk_f16_f32 v60, v79, v66
	v_addc_co_u32_e32 v1, vcc, 0, v29, vcc
	global_store_dwordx4 v[0:1], v[60:63], off offset:-4096
	v_readlane_b32 s0, v252, 51
	s_addc_u32 s65, s0, s11
	v_or_b32_e32 v60, 4, v71
	v_bfrev_b32_e32 v60, v60
	v_lshrrev_b32_e32 v60, 18, v60
	v_sub_u32_e32 v62, 0, v60
	v_and_b32_e32 v63, 0x1fff, v62
	v_bfrev_b32_e32 v63, v63
	v_lshrrev_b32_e32 v64, 18, v63
	v_lshrrev_b32_e32 v63, 23, v63
	v_bitop3_b32 v63, v63, v64, 31 bitop3:0x6c
	v_or_b32_e32 v64, 6, v71
	v_bfrev_b32_e32 v64, v64
	v_and_b32_e32 v60, 0x3fff, v62
	v_lshrrev_b32_e32 v64, 18, v64
	v_bfrev_b32_e32 v60, v60
	v_sub_u32_e32 v64, 0, v64
	v_lshrrev_b32_e32 v61, 18, v60
	v_lshrrev_b32_e32 v60, 23, v60
	v_and_b32_e32 v64, 0x2fff, v64
	v_bitop3_b32 v60, v60, v61, 31 bitop3:0x6c
	v_bfrev_b32_e32 v64, v64
	v_and_b32_e32 v62, 0xfff, v62
	v_lshl_add_u32 v60, v60, 3, 16
	v_lshrrev_b32_e32 v65, 18, v64
	v_lshrrev_b32_e32 v64, 23, v64
	v_bfrev_b32_e32 v62, v62
	ds_read_b64 v[60:61], v60
	v_bitop3_b32 v64, v64, v65, 31 bitop3:0x6c
	v_lshrrev_b32_e32 v65, 18, v62
	v_lshrrev_b32_e32 v62, 23, v62
	v_bitop3_b32 v62, v62, v65, 31 bitop3:0x6c
	v_lshl_add_u32 v63, v63, 3, 16
	v_lshl_add_u32 v64, v64, 3, 16
	v_lshl_add_u32 v66, v62, 3, 16
	ds_read_b64 v[62:63], v63
	ds_read_b64 v[64:65], v64
	ds_read_b64 v[66:67], v66
	s_waitcnt lgkmcnt(3)
	v_pk_add_f32 v[72:73], v[58:59], v[60:61]
	v_sub_f32_e32 v59, v59, v61
	v_sub_f32_e32 v58, v60, v58
	v_mul_f32_e32 v61, 0.5, v59
	v_mul_f32_e32 v60, 0.5, v58
	s_waitcnt lgkmcnt(2)
	v_pk_add_f32 v[58:59], v[56:57], v[62:63]
	v_sub_f32_e32 v57, v57, v63
	v_sub_f32_e32 v56, v62, v56
	v_mul_f32_e32 v63, 0.5, v57
	v_mul_f32_e32 v62, 0.5, v56
	s_waitcnt lgkmcnt(1)
	v_pk_add_f32 v[56:57], v[54:55], v[64:65]
	v_sub_f32_e32 v55, v55, v65
	v_sub_f32_e32 v54, v64, v54
	v_mul_f32_e32 v65, 0.5, v55
	v_mul_f32_e32 v64, 0.5, v54
	s_waitcnt lgkmcnt(0)
	v_pk_add_f32 v[54:55], v[52:53], v[66:67]
	v_sub_f32_e32 v53, v53, v67
	v_mul_f32_e32 v72, 0.5, v72
	v_mul_f32_e32 v58, 0.5, v58
	v_mul_f32_e32 v56, 0.5, v56
	v_mul_f32_e32 v54, 0.5, v54
	v_mul_f32_e32 v53, 0.5, v53
	v_sub_f32_e32 v52, v66, v52
	v_mul_f32_e32 v73, 0.5, v73
	v_mul_f32_e32 v59, 0.5, v59
	v_mul_f32_e32 v57, 0.5, v57
	v_mul_f32_e32 v67, 0.5, v55
	v_mul_f32_e32 v66, 0.5, v52
	v_cvt_pk_f16_f32 v55, v54, v53
	v_cvt_pk_f16_f32 v54, v56, v65
	v_cvt_pk_f16_f32 v53, v58, v63
	v_cvt_pk_f16_f32 v52, v72, v61
	global_store_dwordx4 v[28:29], v[52:55], off offset:-3072
	s_lshl_b64 s[0:1], s[62:63], 13
	s_add_u32 s66, s0, 0xc00000
	v_cvt_pk_f16_f32 v55, v67, v66
	v_cvt_pk_f16_f32 v54, v57, v64
	v_cvt_pk_f16_f32 v53, v59, v62
	v_cvt_pk_f16_f32 v52, v73, v60
	global_store_dwordx4 v[0:1], v[52:55], off offset:-3072
	s_addc_u32 s67, s1, 0
	v_readlane_b32 s0, v252, 6
	v_or_b32_e32 v52, 8, v71
	v_bfrev_b32_e32 v52, v52
	v_lshrrev_b32_e32 v52, 18, v52
	v_sub_u32_e32 v62, 0, v52
	v_and_b32_e32 v54, 0x1fff, v62
	v_bfrev_b32_e32 v54, v54
	v_lshrrev_b32_e32 v55, 18, v54
	v_lshrrev_b32_e32 v54, 23, v54
	v_bitop3_b32 v54, v54, v55, 31 bitop3:0x6c
	v_or_b32_e32 v55, 10, v71
	v_bfrev_b32_e32 v55, v55
	v_lshrrev_b32_e32 v55, 18, v55
	v_sub_u32_e32 v55, 0, v55
	v_and_b32_e32 v55, 0x2fff, v55
	v_and_b32_e32 v52, 0x3fff, v62
	v_bfrev_b32_e32 v55, v55
	v_bfrev_b32_e32 v52, v52
	v_lshrrev_b32_e32 v56, 18, v55
	v_lshrrev_b32_e32 v55, 23, v55
	v_lshrrev_b32_e32 v53, 18, v52
	v_lshrrev_b32_e32 v52, 23, v52
	v_bitop3_b32 v55, v55, v56, 31 bitop3:0x6c
	v_bitop3_b32 v52, v52, v53, 31 bitop3:0x6c
	v_lshl_add_u32 v56, v55, 3, 16
	v_and_b32_e32 v55, 0xfff, v62
	v_lshl_add_u32 v52, v52, 3, 16
	v_bfrev_b32_e32 v55, v55
	ds_read_b64 v[52:53], v52
	v_lshrrev_b32_e32 v57, 18, v55
	v_lshrrev_b32_e32 v55, 23, v55
	v_bitop3_b32 v55, v55, v57, 31 bitop3:0x6c
	v_lshl_add_u32 v54, v54, 3, 16
	v_lshl_add_u32 v58, v55, 3, 16
	ds_read_b64 v[54:55], v54
	ds_read_b64 v[56:57], v56
	ds_read_b64 v[58:59], v58
	s_waitcnt lgkmcnt(3)
	v_pk_add_f32 v[60:61], v[50:51], v[52:53]
	v_sub_f32_e32 v51, v51, v53
	v_sub_f32_e32 v50, v52, v50
	v_mul_f32_e32 v53, 0.5, v51
	v_mul_f32_e32 v52, 0.5, v50
	s_waitcnt lgkmcnt(2)
	v_pk_add_f32 v[50:51], v[48:49], v[54:55]
	v_sub_f32_e32 v49, v49, v55
	v_sub_f32_e32 v48, v54, v48
	v_mul_f32_e32 v55, 0.5, v49
	v_mul_f32_e32 v54, 0.5, v48
	s_waitcnt lgkmcnt(1)
	v_pk_add_f32 v[48:49], v[46:47], v[56:57]
	v_sub_f32_e32 v47, v47, v57
	v_sub_f32_e32 v46, v56, v46
	v_mul_f32_e32 v57, 0.5, v47
	v_mul_f32_e32 v56, 0.5, v46
	s_waitcnt lgkmcnt(0)
	v_pk_add_f32 v[46:47], v[44:45], v[58:59]
	v_sub_f32_e32 v45, v45, v59
	v_mul_f32_e32 v60, 0.5, v60
	v_mul_f32_e32 v50, 0.5, v50
	v_mul_f32_e32 v48, 0.5, v48
	v_mul_f32_e32 v46, 0.5, v46
	v_mul_f32_e32 v45, 0.5, v45
	v_sub_f32_e32 v44, v58, v44
	v_mul_f32_e32 v61, 0.5, v61
	v_mul_f32_e32 v51, 0.5, v51
	v_mul_f32_e32 v49, 0.5, v49
	v_mul_f32_e32 v59, 0.5, v47
	v_mul_f32_e32 v58, 0.5, v44
	v_cvt_pk_f16_f32 v47, v46, v45
	v_cvt_pk_f16_f32 v46, v48, v57
	v_cvt_pk_f16_f32 v45, v50, v55
	v_cvt_pk_f16_f32 v44, v60, v53
	global_store_dwordx4 v[28:29], v[44:47], off offset:-2048
	s_add_u32 s68, s0, s10
	v_readlane_b32 s0, v252, 47
	v_cvt_pk_f16_f32 v47, v59, v58
	v_cvt_pk_f16_f32 v46, v49, v56
	v_cvt_pk_f16_f32 v45, v51, v54
	v_cvt_pk_f16_f32 v44, v61, v52
	global_store_dwordx4 v[0:1], v[44:47], off offset:-2048
	s_addc_u32 s69, s0, s11
	s_lshl_b64 s[0:1], s[62:63], 14
	v_or_b32_e32 v44, 12, v71
	v_bfrev_b32_e32 v44, v44
	v_lshrrev_b32_e32 v44, 18, v44
	v_sub_u32_e32 v46, 0, v44
	v_and_b32_e32 v44, 0x37ff, v46
	v_and_b32_e32 v46, 0x17ff, v46
	v_bfrev_b32_e32 v46, v46
	v_lshrrev_b32_e32 v47, 18, v46
	v_lshrrev_b32_e32 v46, 23, v46
	v_bitop3_b32 v46, v46, v47, 31 bitop3:0x6c
	v_or_b32_e32 v47, 14, v71
	v_bfrev_b32_e32 v47, v47
	v_lshrrev_b32_e32 v47, 18, v47
	v_sub_u32_e32 v47, 0, v47
	v_and_b32_e32 v47, 0x27ff, v47
	v_bfrev_b32_e32 v47, v47
	v_bfrev_b32_e32 v44, v44
	v_lshrrev_b32_e32 v48, 18, v47
	v_lshrrev_b32_e32 v47, 23, v47
	v_lshrrev_b32_e32 v45, 18, v44
	v_lshrrev_b32_e32 v44, 23, v44
	v_bitop3_b32 v47, v47, v48, 31 bitop3:0x6c
	v_bitop3_b32 v44, v44, v45, 31 bitop3:0x6c
	v_lshl_add_u32 v48, v47, 3, 16
	v_and_b32_e32 v47, 0x7ff, v62
	v_lshl_add_u32 v44, v44, 3, 16
	v_bfrev_b32_e32 v47, v47
	ds_read_b64 v[44:45], v44
	v_lshrrev_b32_e32 v49, 18, v47
	v_lshrrev_b32_e32 v47, 23, v47
	v_bitop3_b32 v47, v47, v49, 31 bitop3:0x6c
	v_lshl_add_u32 v46, v46, 3, 16
	v_lshl_add_u32 v50, v47, 3, 16
	ds_read_b64 v[46:47], v46
	ds_read_b64 v[48:49], v48
	ds_read_b64 v[50:51], v50
	s_waitcnt lgkmcnt(3)
	v_pk_add_f32 v[52:53], v[34:35], v[44:45]
	v_sub_f32_e32 v35, v35, v45
	v_sub_f32_e32 v34, v44, v34
	v_mul_f32_e32 v45, 0.5, v35
	v_mul_f32_e32 v44, 0.5, v34
	s_waitcnt lgkmcnt(2)
	v_pk_add_f32 v[34:35], v[32:33], v[46:47]
	v_sub_f32_e32 v33, v33, v47
	v_sub_f32_e32 v32, v46, v32
	v_mul_f32_e32 v47, 0.5, v33
	v_mul_f32_e32 v46, 0.5, v32
	s_waitcnt lgkmcnt(1)
	v_pk_add_f32 v[32:33], v[30:31], v[48:49]
	v_sub_f32_e32 v31, v31, v49
	v_sub_f32_e32 v30, v48, v30
	v_mul_f32_e32 v49, 0.5, v31
	v_mul_f32_e32 v48, 0.5, v30
	s_waitcnt lgkmcnt(0)
	v_pk_add_f32 v[30:31], v[26:27], v[50:51]
	v_sub_f32_e32 v27, v27, v51
	v_mul_f32_e32 v52, 0.5, v52
	v_mul_f32_e32 v34, 0.5, v34
	v_mul_f32_e32 v32, 0.5, v32
	v_mul_f32_e32 v30, 0.5, v30
	v_mul_f32_e32 v27, 0.5, v27
	v_sub_f32_e32 v26, v50, v26
	v_mul_f32_e32 v53, 0.5, v53
	v_mul_f32_e32 v35, 0.5, v35
	v_mul_f32_e32 v54, 0.5, v33
	v_mul_f32_e32 v51, 0.5, v31
	v_mul_f32_e32 v26, 0.5, v26
	v_cvt_pk_f16_f32 v33, v30, v27
	v_cvt_pk_f16_f32 v32, v32, v49
	v_cvt_pk_f16_f32 v31, v34, v47
	v_cvt_pk_f16_f32 v30, v52, v45
	global_store_dwordx4 v[28:29], v[30:33], off offset:-1024
	s_add_u32 s12, s26, s0
	s_addc_u32 s13, s27, s1
	v_cvt_pk_f16_f32 v33, v51, v26
	v_cvt_pk_f16_f32 v32, v54, v48
	v_cvt_pk_f16_f32 v31, v35, v46
	v_cvt_pk_f16_f32 v30, v53, v44
	global_store_dwordx4 v[0:1], v[30:33], off offset:-1024
	v_bfrev_b32_e32 v26, v88
	v_lshrrev_b32_e32 v26, 18, v26
	v_add_u32_e32 v30, 0x2001, v71
	v_bfrev_b32_e32 v30, v30
	v_lshrrev_b32_e32 v30, 18, v30
	v_sub_u32_e32 v30, 0, v30
	v_and_b32_e32 v30, 0x3fff, v30
	v_bfrev_b32_e32 v30, v30
	v_lshrrev_b32_e32 v31, 18, v30
	v_lshrrev_b32_e32 v30, 23, v30
	v_bitop3_b32 v30, v30, v31, 31 bitop3:0x6c
	v_add_u32_e32 v31, 0x2002, v71
	v_bfrev_b32_e32 v31, v31
	v_lshrrev_b32_e32 v31, 18, v31
	v_sub_u32_e32 v31, 0, v31
	v_and_b32_e32 v31, 0x3fff, v31
	v_bfrev_b32_e32 v31, v31
	v_lshrrev_b32_e32 v32, 18, v31
	v_lshrrev_b32_e32 v31, 23, v31
	v_bitop3_b32 v31, v31, v32, 31 bitop3:0x6c
	v_sub_u32_e32 v26, 0, v26
	v_lshl_add_u32 v32, v31, 3, 16
	v_add_u32_e32 v31, 0x2003, v71
	v_and_b32_e32 v26, 0x3fff, v26
	v_bfrev_b32_e32 v31, v31
	v_bfrev_b32_e32 v26, v26
	v_lshrrev_b32_e32 v31, 18, v31
	v_lshrrev_b32_e32 v27, 18, v26
	v_lshrrev_b32_e32 v26, 23, v26
	v_sub_u32_e32 v31, 0, v31
	v_bitop3_b32 v26, v26, v27, 31 bitop3:0x6c
	v_and_b32_e32 v31, 0x1fff, v31
	v_lshl_add_u32 v26, v26, 3, 16
	v_bfrev_b32_e32 v31, v31
	ds_read_b64 v[26:27], v26
	v_lshrrev_b32_e32 v33, 18, v31
	v_lshrrev_b32_e32 v31, 23, v31
	v_bitop3_b32 v31, v31, v33, 31 bitop3:0x6c
	v_lshl_add_u32 v30, v30, 3, 16
	v_lshl_add_u32 v34, v31, 3, 16
	ds_read_b64 v[30:31], v30
	ds_read_b64 v[32:33], v32
	ds_read_b64 v[34:35], v34
	s_waitcnt lgkmcnt(3)
	v_pk_add_f32 v[44:45], v[42:43], v[26:27]
	v_sub_f32_e32 v27, v43, v27
	v_sub_f32_e32 v26, v26, v42
	v_mul_f32_e32 v43, 0.5, v27
	v_mul_f32_e32 v42, 0.5, v26
	s_waitcnt lgkmcnt(2)
	v_pk_add_f32 v[26:27], v[40:41], v[30:31]
	v_mul_f32_e32 v44, 0.5, v44
	v_mul_f32_e32 v46, 0.5, v26
	v_sub_f32_e32 v26, v41, v31
	v_mul_f32_e32 v31, 0.5, v26
	v_sub_f32_e32 v26, v30, v40
	v_mul_f32_e32 v41, 0.5, v27
	v_mul_f32_e32 v40, 0.5, v26
	s_waitcnt lgkmcnt(1)
	v_pk_add_f32 v[26:27], v[38:39], v[32:33]
	v_mul_f32_e32 v45, 0.5, v45
	v_mul_f32_e32 v30, 0.5, v26
	v_sub_f32_e32 v26, v39, v33
	v_mul_f32_e32 v39, 0.5, v26
	v_sub_f32_e32 v26, v32, v38
	v_mul_f32_e32 v47, 0.5, v27
	v_mul_f32_e32 v38, 0.5, v26
	s_waitcnt lgkmcnt(0)
	v_pk_add_f32 v[26:27], v[36:37], v[34:35]
	v_sub_f32_e32 v32, v37, v35
	v_mul_f32_e32 v26, 0.5, v26
	v_mul_f32_e32 v32, 0.5, v32
	v_sub_f32_e32 v33, v34, v36
	v_mul_f32_e32 v27, 0.5, v27
	v_mul_f32_e32 v34, 0.5, v33
	v_cvt_pk_f16_f32 v33, v26, v32
	v_cvt_pk_f16_f32 v32, v30, v39
	v_cvt_pk_f16_f32 v31, v46, v31
	v_cvt_pk_f16_f32 v30, v44, v43
	global_store_dwordx4 v[28:29], v[30:33], off
	v_add_u32_e32 v26, 0x2004, v71
	v_bfrev_b32_e32 v26, v26
	v_cvt_pk_f16_f32 v33, v27, v34
	v_cvt_pk_f16_f32 v32, v47, v38
	v_cvt_pk_f16_f32 v31, v41, v40
	v_cvt_pk_f16_f32 v30, v45, v42
	global_store_dwordx4 v[0:1], v[30:33], off
	v_lshrrev_b32_e32 v26, 18, v26
	v_sub_u32_e32 v26, 0, v26
	v_add_u32_e32 v30, 0x2005, v71
	v_bfrev_b32_e32 v30, v30
	v_lshrrev_b32_e32 v30, 18, v30
	v_sub_u32_e32 v30, 0, v30
	v_and_b32_e32 v30, 0x1fff, v30
	v_bfrev_b32_e32 v30, v30
	v_lshrrev_b32_e32 v31, 18, v30
	v_lshrrev_b32_e32 v30, 23, v30
	v_bitop3_b32 v30, v30, v31, 31 bitop3:0x6c
	v_add_u32_e32 v31, 0x2006, v71
	v_bfrev_b32_e32 v31, v31
	v_lshrrev_b32_e32 v31, 18, v31
	v_sub_u32_e32 v31, 0, v31
	v_and_b32_e32 v31, 0x2fff, v31
	v_bfrev_b32_e32 v31, v31
	v_lshrrev_b32_e32 v32, 18, v31
	v_lshrrev_b32_e32 v31, 23, v31
	v_bitop3_b32 v31, v31, v32, 31 bitop3:0x6c
	v_lshl_add_u32 v32, v31, 3, 16
	v_add_u32_e32 v31, 0x2007, v71
	v_and_b32_e32 v26, 0x3fff, v26
	v_bfrev_b32_e32 v31, v31
	v_bfrev_b32_e32 v26, v26
	v_lshrrev_b32_e32 v31, 18, v31
	v_lshrrev_b32_e32 v27, 18, v26
	v_lshrrev_b32_e32 v26, 23, v26
	v_sub_u32_e32 v31, 0, v31
	v_bitop3_b32 v26, v26, v27, 31 bitop3:0x6c
	v_and_b32_e32 v31, 0xfff, v31
	v_lshl_add_u32 v26, v26, 3, 16
	v_bfrev_b32_e32 v31, v31
	ds_read_b64 v[26:27], v26
	v_lshrrev_b32_e32 v33, 18, v31
	v_lshrrev_b32_e32 v31, 23, v31
	v_bitop3_b32 v31, v31, v33, 31 bitop3:0x6c
	v_lshl_add_u32 v30, v30, 3, 16
	v_lshl_add_u32 v34, v31, 3, 16
	ds_read_b64 v[30:31], v30
	ds_read_b64 v[32:33], v32
	ds_read_b64 v[34:35], v34
	s_waitcnt lgkmcnt(3)
	v_pk_add_f32 v[36:37], v[24:25], v[26:27]
	v_sub_f32_e32 v25, v25, v27
	v_sub_f32_e32 v24, v26, v24
	v_mul_f32_e32 v27, 0.5, v25
	v_mul_f32_e32 v26, 0.5, v24
	s_waitcnt lgkmcnt(2)
	v_pk_add_f32 v[24:25], v[22:23], v[30:31]
	v_sub_f32_e32 v23, v23, v31
	v_sub_f32_e32 v22, v30, v22
	v_mul_f32_e32 v31, 0.5, v23
	v_mul_f32_e32 v30, 0.5, v22
	s_waitcnt lgkmcnt(1)
	v_pk_add_f32 v[22:23], v[20:21], v[32:33]
	v_sub_f32_e32 v21, v21, v33
	v_sub_f32_e32 v20, v32, v20
	v_mul_f32_e32 v33, 0.5, v21
	v_mul_f32_e32 v32, 0.5, v20
	s_waitcnt lgkmcnt(0)
	v_pk_add_f32 v[20:21], v[18:19], v[34:35]
	v_sub_f32_e32 v19, v19, v35
	v_mul_f32_e32 v36, 0.5, v36
	v_mul_f32_e32 v24, 0.5, v24
	v_mul_f32_e32 v22, 0.5, v22
	v_mul_f32_e32 v20, 0.5, v20
	v_mul_f32_e32 v19, 0.5, v19
	v_sub_f32_e32 v18, v34, v18
	v_mul_f32_e32 v37, 0.5, v37
	v_mul_f32_e32 v25, 0.5, v25
	v_mul_f32_e32 v23, 0.5, v23
	v_mul_f32_e32 v35, 0.5, v21
	v_mul_f32_e32 v34, 0.5, v18
	v_cvt_pk_f16_f32 v21, v20, v19
	v_cvt_pk_f16_f32 v20, v22, v33
	v_cvt_pk_f16_f32 v19, v24, v31
	v_cvt_pk_f16_f32 v18, v36, v27
	global_store_dwordx4 v[28:29], v[18:21], off offset:1024
	s_add_u32 s14, s30, s0
	s_addc_u32 s15, s31, s1
	v_cvt_pk_f16_f32 v21, v35, v34
	v_cvt_pk_f16_f32 v20, v23, v32
	v_cvt_pk_f16_f32 v19, v25, v30
	v_cvt_pk_f16_f32 v18, v37, v26
	global_store_dwordx4 v[0:1], v[18:21], off offset:1024
	v_cmp_lt_i32_e32 vcc, s33, v146
	v_add_u32_e32 v52, 0x800, v146
	v_add_u32_e32 v20, 0x2009, v71
	v_bfrev_b32_e32 v20, v20
	v_lshrrev_b32_e32 v20, 18, v20
	v_sub_u32_e32 v20, 0, v20
	v_and_b32_e32 v20, 0x1fff, v20
	v_bfrev_b32_e32 v20, v20
	v_lshrrev_b32_e32 v21, 18, v20
	v_lshrrev_b32_e32 v20, 23, v20
	v_bitop3_b32 v20, v20, v21, 31 bitop3:0x6c
	v_add_u32_e32 v21, 0x200a, v71
	v_bfrev_b32_e32 v21, v21
	v_lshrrev_b32_e32 v21, 18, v21
	v_sub_u32_e32 v21, 0, v21
	v_and_b32_e32 v21, 0x2fff, v21
	v_add_u32_e32 v18, 0x2008, v71
	v_bfrev_b32_e32 v21, v21
	v_bfrev_b32_e32 v18, v18
	v_lshrrev_b32_e32 v22, 18, v21
	v_lshrrev_b32_e32 v21, 23, v21
	v_lshrrev_b32_e32 v18, 18, v18
	v_bitop3_b32 v21, v21, v22, 31 bitop3:0x6c
	v_sub_u32_e32 v18, 0, v18
	v_lshl_add_u32 v22, v21, 3, 16
	v_add_u32_e32 v21, 0x200b, v71
	v_and_b32_e32 v18, 0x3fff, v18
	v_bfrev_b32_e32 v21, v21
	v_bfrev_b32_e32 v18, v18
	v_lshrrev_b32_e32 v21, 18, v21
	v_lshrrev_b32_e32 v19, 18, v18
	v_lshrrev_b32_e32 v18, 23, v18
	v_sub_u32_e32 v21, 0, v21
	v_bitop3_b32 v18, v18, v19, 31 bitop3:0x6c
	v_and_b32_e32 v21, 0xfff, v21
	v_lshl_add_u32 v18, v18, 3, 16
	v_bfrev_b32_e32 v21, v21
	ds_read_b64 v[18:19], v18
	v_lshrrev_b32_e32 v23, 18, v21
	v_lshrrev_b32_e32 v21, 23, v21
	v_bitop3_b32 v21, v21, v23, 31 bitop3:0x6c
	v_lshl_add_u32 v20, v20, 3, 16
	v_lshl_add_u32 v24, v21, 3, 16
	ds_read_b64 v[20:21], v20
	ds_read_b64 v[22:23], v22
	ds_read_b64 v[24:25], v24
	s_waitcnt lgkmcnt(3)
	v_pk_add_f32 v[26:27], v[16:17], v[18:19]
	v_sub_f32_e32 v17, v17, v19
	v_sub_f32_e32 v16, v18, v16
	v_mul_f32_e32 v19, 0.5, v17
	v_mul_f32_e32 v18, 0.5, v16
	s_waitcnt lgkmcnt(2)
	v_pk_add_f32 v[16:17], v[14:15], v[20:21]
	v_sub_f32_e32 v15, v15, v21
	v_sub_f32_e32 v14, v20, v14
	v_mul_f32_e32 v21, 0.5, v15
	v_mul_f32_e32 v20, 0.5, v14
	s_waitcnt lgkmcnt(1)
	v_pk_add_f32 v[14:15], v[12:13], v[22:23]
	v_sub_f32_e32 v13, v13, v23
	v_sub_f32_e32 v12, v22, v12
	v_mul_f32_e32 v23, 0.5, v13
	v_mul_f32_e32 v22, 0.5, v12
	s_waitcnt lgkmcnt(0)
	v_pk_add_f32 v[12:13], v[10:11], v[24:25]
	v_sub_f32_e32 v11, v11, v25
	v_mul_f32_e32 v26, 0.5, v26
	v_mul_f32_e32 v16, 0.5, v16
	v_mul_f32_e32 v14, 0.5, v14
	v_mul_f32_e32 v12, 0.5, v12
	v_mul_f32_e32 v11, 0.5, v11
	v_sub_f32_e32 v10, v24, v10
	v_mul_f32_e32 v27, 0.5, v27
	v_mul_f32_e32 v17, 0.5, v17
	v_mul_f32_e32 v15, 0.5, v15
	v_mul_f32_e32 v25, 0.5, v13
	v_mul_f32_e32 v24, 0.5, v10
	v_cvt_pk_f16_f32 v13, v12, v11
	v_cvt_pk_f16_f32 v12, v14, v23
	v_cvt_pk_f16_f32 v11, v16, v21
	v_cvt_pk_f16_f32 v10, v26, v19
	global_store_dwordx4 v[28:29], v[10:13], off offset:2048
	v_add_u32_e32 v53, 0xa00, v146
	v_add_u32_e32 v54, 0xc00, v146
	v_cvt_pk_f16_f32 v13, v25, v24
	v_cvt_pk_f16_f32 v12, v15, v22
	v_cvt_pk_f16_f32 v11, v17, v20
	v_cvt_pk_f16_f32 v10, v27, v18
	global_store_dwordx4 v[0:1], v[10:13], off offset:2048
	v_add_u32_e32 v55, 0xe00, v146
	v_add_u32_e32 v47, 0x1000, v146
	v_add_u32_e32 v12, 0x200d, v71
	v_bfrev_b32_e32 v12, v12
	v_lshrrev_b32_e32 v12, 18, v12
	v_sub_u32_e32 v12, 0, v12
	v_and_b32_e32 v12, 0x17ff, v12
	v_bfrev_b32_e32 v12, v12
	v_lshrrev_b32_e32 v13, 18, v12
	v_lshrrev_b32_e32 v12, 23, v12
	v_bitop3_b32 v12, v12, v13, 31 bitop3:0x6c
	v_add_u32_e32 v13, 0x200e, v71
	v_bfrev_b32_e32 v13, v13
	v_lshrrev_b32_e32 v13, 18, v13
	v_sub_u32_e32 v13, 0, v13
	v_and_b32_e32 v13, 0x27ff, v13
	v_add_u32_e32 v10, 0x200c, v71
	v_bfrev_b32_e32 v13, v13
	v_bfrev_b32_e32 v10, v10
	v_lshrrev_b32_e32 v14, 18, v13
	v_lshrrev_b32_e32 v13, 23, v13
	v_lshrrev_b32_e32 v10, 18, v10
	v_bitop3_b32 v13, v13, v14, 31 bitop3:0x6c
	v_sub_u32_e32 v10, 0, v10
	v_lshl_add_u32 v14, v13, 3, 16
	v_add_u32_e32 v13, 0x200f, v71
	v_and_b32_e32 v10, 0x37ff, v10
	v_bfrev_b32_e32 v13, v13
	v_bfrev_b32_e32 v10, v10
	v_lshrrev_b32_e32 v13, 18, v13
	v_lshrrev_b32_e32 v11, 18, v10
	v_lshrrev_b32_e32 v10, 23, v10
	v_sub_u32_e32 v13, 0, v13
	v_bitop3_b32 v10, v10, v11, 31 bitop3:0x6c
	v_and_b32_e32 v13, 0x7ff, v13
	v_lshl_add_u32 v10, v10, 3, 16
	v_bfrev_b32_e32 v13, v13
	ds_read_b64 v[10:11], v10
	v_lshrrev_b32_e32 v15, 18, v13
	v_lshrrev_b32_e32 v13, 23, v13
	v_bitop3_b32 v13, v13, v15, 31 bitop3:0x6c
	v_lshl_add_u32 v12, v12, 3, 16
	v_lshl_add_u32 v16, v13, 3, 16
	ds_read_b64 v[12:13], v12
	ds_read_b64 v[14:15], v14
	ds_read_b64 v[16:17], v16
	s_waitcnt lgkmcnt(3)
	v_pk_add_f32 v[18:19], v[8:9], v[10:11]
	v_sub_f32_e32 v9, v9, v11
	v_sub_f32_e32 v8, v10, v8
	v_mul_f32_e32 v11, 0.5, v9
	v_mul_f32_e32 v10, 0.5, v8
	s_waitcnt lgkmcnt(2)
	v_pk_add_f32 v[8:9], v[6:7], v[12:13]
	v_sub_f32_e32 v7, v7, v13
	v_sub_f32_e32 v6, v12, v6
	v_mul_f32_e32 v13, 0.5, v7
	v_mul_f32_e32 v12, 0.5, v6
	s_waitcnt lgkmcnt(1)
	v_pk_add_f32 v[6:7], v[4:5], v[14:15]
	v_sub_f32_e32 v5, v5, v15
	v_sub_f32_e32 v4, v14, v4
	v_mul_f32_e32 v15, 0.5, v5
	v_mul_f32_e32 v14, 0.5, v4
	s_waitcnt lgkmcnt(0)
	v_pk_add_f32 v[4:5], v[2:3], v[16:17]
	v_sub_f32_e32 v3, v3, v17
	v_mul_f32_e32 v18, 0.5, v18
	v_mul_f32_e32 v8, 0.5, v8
	v_mul_f32_e32 v6, 0.5, v6
	v_mul_f32_e32 v4, 0.5, v4
	v_mul_f32_e32 v3, 0.5, v3
	v_sub_f32_e32 v2, v16, v2
	v_mul_f32_e32 v19, 0.5, v19
	v_mul_f32_e32 v9, 0.5, v9
	v_mul_f32_e32 v7, 0.5, v7
	v_mul_f32_e32 v17, 0.5, v5
	v_mul_f32_e32 v16, 0.5, v2
	v_cvt_pk_f16_f32 v5, v4, v3
	v_cvt_pk_f16_f32 v4, v6, v15
	v_cvt_pk_f16_f32 v3, v8, v13
	v_cvt_pk_f16_f32 v2, v18, v11
	global_store_dwordx4 v[28:29], v[2:5], off offset:3072
	v_add_u32_e32 v46, 0x1200, v146
	v_add_u32_e32 v27, 0x1400, v146
	v_cvt_pk_f16_f32 v5, v17, v16
	v_cvt_pk_f16_f32 v4, v7, v14
	v_cvt_pk_f16_f32 v3, v9, v12
	v_cvt_pk_f16_f32 v2, v19, v10
	global_store_dwordx4 v[0:1], v[2:5], off offset:3072
	global_load_dword v2, v151, s[64:65] offset:2048
	global_load_dword v0, v152, s[64:65]
	global_load_dword v6, v145, s[64:65]
	global_load_dword v4, v145, s[68:69]
	v_lshlrev_b32_e32 v8, 1, v146
	v_max_i32_e32 v12, 1, v146
	v_add_u32_e32 v13, 0x1e00, v146
	v_cmp_lt_i32_e32 vcc, 0, v146
	v_add_u32_e32 v9, 0x1000, v8
	v_add_u32_e32 v10, 0x2000, v8
	v_add_u32_e32 v11, 0x3000, v8
	v_lshlrev_b32_e32 v12, 1, v12
	v_cndmask_b32_e64 v14, 0, 1.0, vcc
	v_cmp_gt_i32_e32 vcc, 0x1fff, v13
	v_min_i32_e32 v13, 0x1ffe, v13
	v_lshlrev_b32_e32 v13, 1, v13
	s_nop 0
	v_cndmask_b32_e64 v15, 0, 1.0, vcc
	global_load_ushort v163, v12, s[12:13] offset:-2
	global_load_ushort v164, v8, s[12:13]
	global_load_ushort v165, v8, s[12:13] offset:2
	global_load_ushort v166, v12, s[14:15] offset:-2
	global_load_ushort v167, v8, s[14:15]
	global_load_ushort v168, v8, s[14:15] offset:2
	global_load_ushort v169, v8, s[12:13] offset:1022
	global_load_ushort v170, v8, s[12:13] offset:1024
	global_load_ushort v171, v8, s[12:13] offset:1026
	global_load_ushort v172, v8, s[14:15] offset:1022
	global_load_ushort v173, v8, s[14:15] offset:1024
	global_load_ushort v174, v8, s[14:15] offset:1026
	global_load_ushort v175, v8, s[12:13] offset:2046
	global_load_ushort v176, v8, s[12:13] offset:2048
	global_load_ushort v177, v8, s[12:13] offset:2050
	global_load_ushort v178, v8, s[14:15] offset:2046
	global_load_ushort v179, v8, s[14:15] offset:2048
	global_load_ushort v180, v8, s[14:15] offset:2050
	global_load_ushort v181, v8, s[12:13] offset:3070
	global_load_ushort v182, v8, s[12:13] offset:3072
	global_load_ushort v183, v8, s[12:13] offset:3074
	global_load_ushort v184, v8, s[14:15] offset:3070
	global_load_ushort v185, v8, s[14:15] offset:3072
	global_load_ushort v186, v8, s[14:15] offset:3074
	global_load_ushort v187, v9, s[12:13] offset:-2
	global_load_ushort v188, v9, s[12:13]
	global_load_ushort v189, v9, s[12:13] offset:2
	global_load_ushort v190, v9, s[14:15] offset:-2
	global_load_ushort v191, v9, s[14:15]
	global_load_ushort v192, v9, s[14:15] offset:2
	global_load_ushort v193, v9, s[12:13] offset:1022
	global_load_ushort v194, v9, s[12:13] offset:1024
	global_load_ushort v195, v9, s[12:13] offset:1026
	global_load_ushort v196, v9, s[14:15] offset:1022
	global_load_ushort v197, v9, s[14:15] offset:1024
	global_load_ushort v62, v9, s[14:15] offset:1026
	global_load_ushort v63, v9, s[12:13] offset:2046
	global_load_ushort v64, v9, s[12:13] offset:2048
	global_load_ushort v65, v9, s[12:13] offset:2050
	global_load_ushort v66, v9, s[14:15] offset:2046
	global_load_ushort v67, v9, s[14:15] offset:2048
	global_load_ushort v68, v9, s[14:15] offset:2050
	global_load_ushort v69, v9, s[12:13] offset:3070
	global_load_ushort v70, v9, s[12:13] offset:3072
	global_load_ushort v71, v9, s[12:13] offset:3074
	global_load_ushort v72, v9, s[14:15] offset:3070
	global_load_ushort v73, v9, s[14:15] offset:3072
	global_load_ushort v74, v9, s[14:15] offset:3074
	global_load_ushort v75, v10, s[12:13] offset:-2
	global_load_ushort v76, v10, s[12:13]
	global_load_ushort v77, v10, s[12:13] offset:2
	global_load_ushort v221, v10, s[14:15] offset:-2
	global_load_ushort v222, v10, s[14:15]
	global_load_ushort v223, v10, s[14:15] offset:2
	global_load_ushort v224, v10, s[12:13] offset:1022
	global_load_ushort v225, v10, s[12:13] offset:1024
	global_load_ushort v226, v10, s[12:13] offset:1026
	global_load_ushort v227, v10, s[14:15] offset:1022
	global_load_ushort v228, v10, s[14:15] offset:1024
	global_load_ushort v229, v10, s[14:15] offset:1026
	global_load_ushort v230, v10, s[12:13] offset:2046
	global_load_ushort v231, v10, s[12:13] offset:2048
	global_load_ushort v232, v10, s[12:13] offset:2050
	global_load_ushort v233, v10, s[14:15] offset:2046
	global_load_ushort v234, v10, s[14:15] offset:2048
	global_load_ushort v235, v10, s[14:15] offset:2050
	global_load_ushort v236, v10, s[12:13] offset:3070
	global_load_ushort v237, v10, s[12:13] offset:3072
	global_load_ushort v238, v10, s[12:13] offset:3074
	global_load_ushort v239, v10, s[14:15] offset:3070
	global_load_ushort v240, v10, s[14:15] offset:3072
	global_load_ushort v241, v10, s[14:15] offset:3074
	global_load_ushort v242, v11, s[12:13] offset:-2
	global_load_ushort v243, v11, s[12:13]
	global_load_ushort v244, v11, s[12:13] offset:2
	global_load_ushort v245, v11, s[14:15] offset:-2
	global_load_ushort v246, v11, s[14:15]
	global_load_ushort v247, v11, s[14:15] offset:2
	global_load_ushort v248, v11, s[12:13] offset:1022
	global_load_ushort v249, v11, s[12:13] offset:1024
	global_load_ushort v250, v11, s[12:13] offset:1026
	global_load_ushort v251, v11, s[14:15] offset:1022
	global_load_ushort v253, v11, s[14:15] offset:1024
	global_load_ushort v254, v11, s[14:15] offset:1026
	global_load_ushort v255, v11, s[12:13] offset:2046
	global_load_ushort v1, v11, s[12:13] offset:2048
	global_load_ushort v3, v11, s[12:13] offset:2050
	global_load_ushort v5, v11, s[14:15] offset:2046
	global_load_ushort v7, v11, s[14:15] offset:2048
	global_load_ushort v16, v11, s[14:15] offset:2050
	global_load_ushort v17, v11, s[12:13] offset:3070
	global_load_ushort v18, v11, s[12:13] offset:3072
	global_load_ushort v19, v13, s[12:13] offset:2
	global_load_ushort v20, v11, s[14:15] offset:3070
	global_load_ushort v21, v11, s[14:15] offset:3072
	global_load_ushort v22, v13, s[14:15] offset:2
	s_waitcnt vmcnt(48)
	v_lshlrev_b32_e32 v163, 16, v163
	v_lshlrev_b32_e32 v164, 16, v164
	v_lshlrev_b32_e32 v165, 16, v165
	v_mul_f32_e32 v163, v14, v163
	v_mul_f32_e32 v163, v6, v163
	v_fmac_f32_e32 v163, v2, v164
	v_fmac_f32_e32 v163, v0, v165
	v_add_f32_e32 v32, v4, v163
	v_lshlrev_b32_e32 v166, 16, v166
	v_lshlrev_b32_e32 v167, 16, v167
	v_lshlrev_b32_e32 v168, 16, v168
	v_mul_f32_e32 v166, v14, v166
	v_mul_f32_e32 v166, v6, v166
	v_fmac_f32_e32 v166, v2, v167
	v_fmac_f32_e32 v166, v0, v168
	v_add_f32_e32 v34, v4, v166
	v_lshlrev_b32_e32 v169, 16, v169
	v_lshlrev_b32_e32 v170, 16, v170
	v_lshlrev_b32_e32 v171, 16, v171
	v_mul_f32_e32 v169, v6, v169
	v_fmac_f32_e32 v169, v2, v170
	v_fmac_f32_e32 v169, v0, v171
	v_add_f32_e32 v33, v4, v169
	v_lshlrev_b32_e32 v172, 16, v172
	v_lshlrev_b32_e32 v173, 16, v173
	v_lshlrev_b32_e32 v174, 16, v174
	v_mul_f32_e32 v172, v6, v172
	v_fmac_f32_e32 v172, v2, v173
	v_fmac_f32_e32 v172, v0, v174
	v_add_f32_e32 v35, v4, v172
	v_lshlrev_b32_e32 v175, 16, v175
	v_lshlrev_b32_e32 v176, 16, v176
	v_lshlrev_b32_e32 v177, 16, v177
	v_mul_f32_e32 v175, v6, v175
	v_fmac_f32_e32 v175, v2, v176
	v_fmac_f32_e32 v175, v0, v177
	v_add_f32_e32 v37, v4, v175
	v_lshlrev_b32_e32 v178, 16, v178
	v_lshlrev_b32_e32 v179, 16, v179
	v_lshlrev_b32_e32 v180, 16, v180
	v_mul_f32_e32 v178, v6, v178
	v_fmac_f32_e32 v178, v2, v179
	v_fmac_f32_e32 v178, v0, v180
	v_add_f32_e32 v31, v4, v178
	v_lshlrev_b32_e32 v181, 16, v181
	v_lshlrev_b32_e32 v182, 16, v182
	v_lshlrev_b32_e32 v183, 16, v183
	v_mul_f32_e32 v181, v6, v181
	v_fmac_f32_e32 v181, v2, v182
	v_fmac_f32_e32 v181, v0, v183
	v_add_f32_e32 v36, v4, v181
	v_lshlrev_b32_e32 v184, 16, v184
	v_lshlrev_b32_e32 v185, 16, v185
	v_lshlrev_b32_e32 v186, 16, v186
	v_mul_f32_e32 v184, v6, v184
	v_fmac_f32_e32 v184, v2, v185
	v_fmac_f32_e32 v184, v0, v186
	v_add_f32_e32 v30, v4, v184
	v_lshlrev_b32_e32 v187, 16, v187
	v_lshlrev_b32_e32 v188, 16, v188
	v_lshlrev_b32_e32 v189, 16, v189
	v_mul_f32_e32 v187, v6, v187
	v_fmac_f32_e32 v187, v2, v188
	v_fmac_f32_e32 v187, v0, v189
	v_add_f32_e32 v39, v4, v187
	v_lshlrev_b32_e32 v190, 16, v190
	v_lshlrev_b32_e32 v191, 16, v191
	v_lshlrev_b32_e32 v192, 16, v192
	v_mul_f32_e32 v190, v6, v190
	v_fmac_f32_e32 v190, v2, v191
	v_fmac_f32_e32 v190, v0, v192
	v_add_f32_e32 v41, v4, v190
	v_lshlrev_b32_e32 v193, 16, v193
	v_lshlrev_b32_e32 v194, 16, v194
	v_lshlrev_b32_e32 v195, 16, v195
	v_mul_f32_e32 v193, v6, v193
	v_fmac_f32_e32 v193, v2, v194
	v_fmac_f32_e32 v193, v0, v195
	v_add_f32_e32 v38, v4, v193
	v_lshlrev_b32_e32 v196, 16, v196
	v_lshlrev_b32_e32 v197, 16, v197
	v_lshlrev_b32_e32 v62, 16, v62
	v_mul_f32_e32 v196, v6, v196
	v_fmac_f32_e32 v196, v2, v197
	v_fmac_f32_e32 v196, v0, v62
	v_add_f32_e32 v40, v4, v196
	v_lshlrev_b32_e32 v63, 16, v63
	v_lshlrev_b32_e32 v64, 16, v64
	v_lshlrev_b32_e32 v65, 16, v65
	v_mul_f32_e32 v63, v6, v63
	v_fmac_f32_e32 v63, v2, v64
	v_fmac_f32_e32 v63, v0, v65
	v_add_f32_e32 v43, v4, v63
	v_lshlrev_b32_e32 v66, 16, v66
	v_lshlrev_b32_e32 v67, 16, v67
	v_lshlrev_b32_e32 v68, 16, v68
	v_mul_f32_e32 v66, v6, v66
	v_fmac_f32_e32 v66, v2, v67
	v_fmac_f32_e32 v66, v0, v68
	v_add_f32_e32 v45, v4, v66
	v_lshlrev_b32_e32 v69, 16, v69
	v_lshlrev_b32_e32 v70, 16, v70
	v_lshlrev_b32_e32 v71, 16, v71
	v_mul_f32_e32 v69, v6, v69
	v_fmac_f32_e32 v69, v2, v70
	v_fmac_f32_e32 v69, v0, v71
	v_add_f32_e32 v42, v4, v69
	v_lshlrev_b32_e32 v72, 16, v72
	v_lshlrev_b32_e32 v73, 16, v73
	v_lshlrev_b32_e32 v74, 16, v74
	v_mul_f32_e32 v72, v6, v72
	v_fmac_f32_e32 v72, v2, v73
	v_fmac_f32_e32 v72, v0, v74
	v_add_f32_e32 v44, v4, v72
	s_waitcnt vmcnt(0)
	v_lshlrev_b32_e32 v75, 16, v75
	v_lshlrev_b32_e32 v76, 16, v76
	v_lshlrev_b32_e32 v77, 16, v77
	v_mul_f32_e32 v75, v6, v75
	v_fmac_f32_e32 v75, v2, v76
	v_fmac_f32_e32 v75, v0, v77
	v_add_f32_e32 v47, v4, v75
	v_lshlrev_b32_e32 v221, 16, v221
	v_lshlrev_b32_e32 v222, 16, v222
	v_lshlrev_b32_e32 v223, 16, v223
	v_mul_f32_e32 v221, v6, v221
	v_fmac_f32_e32 v221, v2, v222
	v_fmac_f32_e32 v221, v0, v223
	v_add_f32_e32 v49, v4, v221
	v_lshlrev_b32_e32 v224, 16, v224
	v_lshlrev_b32_e32 v225, 16, v225
	v_lshlrev_b32_e32 v226, 16, v226
	v_mul_f32_e32 v224, v6, v224
	v_fmac_f32_e32 v224, v2, v225
	v_fmac_f32_e32 v224, v0, v226
	v_add_f32_e32 v46, v4, v224
	v_lshlrev_b32_e32 v227, 16, v227
	v_lshlrev_b32_e32 v228, 16, v228
	v_lshlrev_b32_e32 v229, 16, v229
	v_mul_f32_e32 v227, v6, v227
	v_fmac_f32_e32 v227, v2, v228
	v_fmac_f32_e32 v227, v0, v229
	v_add_f32_e32 v48, v4, v227
	v_lshlrev_b32_e32 v230, 16, v230
	v_lshlrev_b32_e32 v231, 16, v231
	v_lshlrev_b32_e32 v232, 16, v232
	v_mul_f32_e32 v230, v6, v230
	v_fmac_f32_e32 v230, v2, v231
	v_fmac_f32_e32 v230, v0, v232
	v_add_f32_e32 v51, v4, v230
	v_lshlrev_b32_e32 v233, 16, v233
	v_lshlrev_b32_e32 v234, 16, v234
	v_lshlrev_b32_e32 v235, 16, v235
	v_mul_f32_e32 v233, v6, v233
	v_fmac_f32_e32 v233, v2, v234
	v_fmac_f32_e32 v233, v0, v235
	v_add_f32_e32 v53, v4, v233
	v_lshlrev_b32_e32 v236, 16, v236
	v_lshlrev_b32_e32 v237, 16, v237
	v_lshlrev_b32_e32 v238, 16, v238
	v_mul_f32_e32 v236, v6, v236
	v_fmac_f32_e32 v236, v2, v237
	v_fmac_f32_e32 v236, v0, v238
	v_add_f32_e32 v50, v4, v236
	v_lshlrev_b32_e32 v239, 16, v239
	v_lshlrev_b32_e32 v240, 16, v240
	v_lshlrev_b32_e32 v241, 16, v241
	v_mul_f32_e32 v239, v6, v239
	v_fmac_f32_e32 v239, v2, v240
	v_fmac_f32_e32 v239, v0, v241
	v_add_f32_e32 v52, v4, v239
	v_lshlrev_b32_e32 v242, 16, v242
	v_lshlrev_b32_e32 v243, 16, v243
	v_lshlrev_b32_e32 v244, 16, v244
	v_mul_f32_e32 v242, v6, v242
	v_fmac_f32_e32 v242, v2, v243
	v_fmac_f32_e32 v242, v0, v244
	v_add_f32_e32 v55, v4, v242
	v_lshlrev_b32_e32 v245, 16, v245
	v_lshlrev_b32_e32 v246, 16, v246
	v_lshlrev_b32_e32 v247, 16, v247
	v_mul_f32_e32 v245, v6, v245
	v_fmac_f32_e32 v245, v2, v246
	v_fmac_f32_e32 v245, v0, v247
	v_add_f32_e32 v57, v4, v245
	v_lshlrev_b32_e32 v248, 16, v248
	v_lshlrev_b32_e32 v249, 16, v249
	v_lshlrev_b32_e32 v250, 16, v250
	v_mul_f32_e32 v248, v6, v248
	v_fmac_f32_e32 v248, v2, v249
	v_fmac_f32_e32 v248, v0, v250
	v_add_f32_e32 v54, v4, v248
	v_lshlrev_b32_e32 v251, 16, v251
	v_lshlrev_b32_e32 v253, 16, v253
	v_lshlrev_b32_e32 v254, 16, v254
	v_mul_f32_e32 v251, v6, v251
	v_fmac_f32_e32 v251, v2, v253
	v_fmac_f32_e32 v251, v0, v254
	v_add_f32_e32 v56, v4, v251
	v_lshlrev_b32_e32 v255, 16, v255
	v_lshlrev_b32_e32 v1, 16, v1
	v_lshlrev_b32_e32 v3, 16, v3
	v_mul_f32_e32 v255, v6, v255
	v_fmac_f32_e32 v255, v2, v1
	v_fmac_f32_e32 v255, v0, v3
	v_add_f32_e32 v59, v4, v255
	v_lshlrev_b32_e32 v5, 16, v5
	v_lshlrev_b32_e32 v7, 16, v7
	v_lshlrev_b32_e32 v16, 16, v16
	v_mul_f32_e32 v5, v6, v5
	v_fmac_f32_e32 v5, v2, v7
	v_fmac_f32_e32 v5, v0, v16
	v_add_f32_e32 v61, v4, v5
	v_lshlrev_b32_e32 v17, 16, v17
	v_lshlrev_b32_e32 v18, 16, v18
	v_lshlrev_b32_e32 v19, 16, v19
	v_mul_f32_e32 v19, v15, v19
	v_mul_f32_e32 v17, v6, v17
	v_fmac_f32_e32 v17, v2, v18
	v_fmac_f32_e32 v17, v0, v19
	v_add_f32_e32 v58, v4, v17
	v_lshlrev_b32_e32 v20, 16, v20
	v_lshlrev_b32_e32 v21, 16, v21
	v_lshlrev_b32_e32 v22, 16, v22
	v_mul_f32_e32 v22, v15, v22
	v_mul_f32_e32 v20, v6, v20
	v_fmac_f32_e32 v20, v2, v21
	v_fmac_f32_e32 v20, v0, v22
	v_add_f32_e32 v60, v4, v20
	v_readlane_b32 s0, v252, 43
	s_add_u32 s45, s0, s10
	v_readlane_b32 s0, v252, 42
	s_addc_u32 s24, s0, s11
	s_lshl_b64 s[0:1], s[62:63], 1
	v_readlane_b32 s4, v252, 60
	s_add_u32 s70, s4, s0
	v_readlane_b32 s0, v252, 61
	s_addc_u32 s71, s0, s1
	s_mov_b64 s[14:15], -1
	s_branch .LBB0_910

.LBB0_910:
	s_lshl_b32 s98, s16, 16
	s_mov_b32 s99, 0
	v_lshl_add_u64 v[196:197], s[98:99], 0, v[28:29]
	global_load_dwordx4 v[164:167], v[196:197], off offset:-4096
	global_load_dwordx4 v[168:171], v[196:197], off offset:-3072
	global_load_dwordx4 v[172:175], v[196:197], off offset:-2048
	global_load_dwordx4 v[176:179], v[196:197], off offset:-1024
	global_load_dwordx4 v[180:183], v[196:197], off
	global_load_dwordx4 v[184:187], v[196:197], off offset:1024
	global_load_dwordx4 v[188:191], v[196:197], off offset:2048
	global_load_dwordx4 v[192:195], v[196:197], off offset:3072
	v_mov_b32_e32 v20, v46
	v_mov_b32_e32 v21, v48
	v_mov_b32_e32 v22, v51
	v_mov_b32_e32 v23, v53
	v_pk_add_f32 v[88:89], v[20:21], 0 op_sel_hi:[1,0]
	v_pk_mul_f32 v[20:21], v[20:21], s[48:49] op_sel_hi:[1,0]
	v_xor_b32_e32 v91, 0x80000000, v46
	v_mov_b32_e32 v90, v48
	v_pk_add_f32 v[92:93], v[50:51], 0 neg_lo:[1,1] neg_hi:[1,1]
	v_mov_b32_e32 v24, v50
	v_mov_b32_e32 v25, v52
	v_pk_fma_f32 v[20:21], v[90:91], s[44:45], v[20:21] op_sel_hi:[1,0,1] neg_lo:[0,0,1] neg_hi:[0,0,1]
	v_pk_add_f32 v[90:91], v[22:23], 0 op_sel_hi:[1,0]
	v_pk_mul_f32 v[22:23], v[22:23], s[54:55] op_sel_hi:[1,0]
	v_mov_b32_e32 v92, v53
	v_mov_b32_e32 v26, v55
	v_mov_b32_e32 v27, v57
	v_pk_fma_f32 v[22:23], v[92:93], s[52:53], v[22:23] op_sel_hi:[1,0,1] neg_lo:[0,0,1] neg_hi:[0,0,1]
	v_pk_add_f32 v[92:93], v[24:25], 0 op_sel_hi:[1,0]
	v_pk_mul_f32 v[24:25], v[24:25], s[58:59] op_sel_hi:[1,0]
	v_xor_b32_e32 v95, 0x80000000, v50
	v_mov_b32_e32 v94, v52
	v_pk_add_f32 v[96:97], v[54:55], 0 neg_lo:[1,1] neg_hi:[1,1]
	v_mov_b32_e32 v64, v54
	v_mov_b32_e32 v65, v56
	v_pk_fma_f32 v[24:25], v[94:95], s[56:57], v[24:25] op_sel_hi:[1,0,1] neg_lo:[0,0,1] neg_hi:[0,0,1]
	v_pk_add_f32 v[94:95], v[26:27], 0 op_sel_hi:[1,0]
	v_pk_mul_f32 v[26:27], v[26:27], s[60:61] op_sel_hi:[1,0]
	v_mov_b32_e32 v96, v57
	v_mov_b32_e32 v66, v59
	v_mov_b32_e32 v67, v61
	v_pk_fma_f32 v[26:27], v[96:97], s[60:61], v[26:27] op_sel_hi:[1,0,1] neg_lo:[0,0,1] neg_hi:[0,0,1]
	v_pk_add_f32 v[96:97], v[64:65], 0 op_sel_hi:[1,0]
	v_pk_mul_f32 v[64:65], v[64:65], s[56:57] op_sel_hi:[1,0]
	v_xor_b32_e32 v99, 0x80000000, v54
	v_mov_b32_e32 v98, v56
	v_pk_add_f32 v[100:101], v[58:59], 0 neg_lo:[1,1] neg_hi:[1,1]
	v_mov_b32_e32 v2, v32
	v_mov_b32_e32 v3, v34
	v_mov_b32_e32 v4, v33
	v_mov_b32_e32 v5, v35
	v_mov_b32_e32 v18, v47
	v_mov_b32_e32 v19, v49
	v_mov_b32_e32 v68, v58
	v_mov_b32_e32 v69, v60
	v_pk_fma_f32 v[64:65], v[98:99], s[58:59], v[64:65] op_sel_hi:[1,0,1] neg_lo:[0,0,1] neg_hi:[0,0,1]
	v_pk_add_f32 v[98:99], v[66:67], 0 op_sel_hi:[1,0]
	v_pk_mul_f32 v[66:67], v[66:67], s[52:53] op_sel_hi:[1,0]
	v_mov_b32_e32 v100, v61
	v_pk_add_f32 v[70:71], v[2:3], 0 op_sel_hi:[1,0]
	v_pk_add_f32 v[72:73], v[4:5], 0 op_sel_hi:[1,0]
	v_pk_add_f32 v[74:75], v[32:33], 0 neg_lo:[1,1] neg_hi:[1,1]
	v_pk_add_f32 v[18:19], v[18:19], 0 op_sel_hi:[1,0]
	v_pk_fma_f32 v[66:67], v[100:101], s[54:55], v[66:67] op_sel_hi:[1,0,1] neg_lo:[0,0,1] neg_hi:[0,0,1]
	v_pk_add_f32 v[100:101], v[68:69], 0 op_sel_hi:[1,0]
	v_pk_mul_f32 v[68:69], v[68:69], s[44:45] op_sel_hi:[1,0]
	v_xor_b32_e32 v103, 0x80000000, v58
	v_mov_b32_e32 v102, v60
	v_mov_b32_e32 v74, v35
	v_pk_fma_f32 v[68:69], v[102:103], s[48:49], v[68:69] op_sel_hi:[1,0,1] neg_lo:[0,0,1] neg_hi:[0,0,1]
	v_pk_add_f32 v[102:103], v[18:19], v[70:71]
	v_pk_add_f32 v[18:19], v[70:71], v[18:19] neg_lo:[0,1] neg_hi:[0,1]
	v_pk_add_f32 v[70:71], v[88:89], v[72:73]
	v_pk_add_f32 v[72:73], v[72:73], v[88:89] neg_lo:[0,1] neg_hi:[0,1]
	v_mov_b32_e32 v6, v37
	v_mov_b32_e32 v7, v31
	v_pk_mul_f32 v[74:75], v[74:75], s[48:49] op_sel_hi:[1,0]
	s_nop 0
	v_pk_fma_f32 v[4:5], v[4:5], s[44:45], v[74:75] op_sel_hi:[1,0,1]
	v_pk_add_f32 v[74:75], v[6:7], 0 op_sel_hi:[1,0]
	v_pk_add_f32 v[76:77], v[36:37], 0 neg_lo:[1,1] neg_hi:[1,1]
	v_pk_mul_f32 v[88:89], v[72:73], s[54:55] op_sel:[1,0] op_sel_hi:[0,0] neg_hi:[1,0]
	v_mov_b32_e32 v76, v31
	v_pk_fma_f32 v[72:73], v[72:73], s[52:53], v[88:89] op_sel_hi:[1,0,1]
	v_pk_add_f32 v[88:89], v[90:91], v[74:75]
	v_pk_add_f32 v[74:75], v[74:75], v[90:91] neg_lo:[0,1] neg_hi:[0,1]
	v_mov_b32_e32 v8, v36
	v_mov_b32_e32 v9, v30
	v_pk_mul_f32 v[76:77], v[76:77], s[54:55] op_sel_hi:[1,0]
	s_nop 0
	v_pk_fma_f32 v[6:7], v[6:7], s[52:53], v[76:77] op_sel_hi:[1,0,1]
	v_pk_add_f32 v[76:77], v[8:9], 0 op_sel_hi:[1,0]
	v_pk_mul_f32 v[90:91], v[74:75], s[60:61] op_sel:[1,0] op_sel_hi:[0,0] neg_hi:[1,0]
	v_xor_b32_e32 v79, 0x80000000, v36
	v_mov_b32_e32 v78, v30
	v_pk_add_f32 v[80:81], v[38:39], 0 neg_lo:[1,1] neg_hi:[1,1]
	v_pk_fma_f32 v[74:75], v[74:75], s[60:61], v[90:91] op_sel_hi:[1,0,1]
	v_pk_add_f32 v[90:91], v[92:93], v[76:77]
	v_pk_add_f32 v[76:77], v[76:77], v[92:93] neg_lo:[0,1] neg_hi:[0,1]
	v_mov_b32_e32 v10, v39
	v_mov_b32_e32 v11, v41
	v_pk_mul_f32 v[78:79], v[78:79], s[58:59] op_sel_hi:[1,0]
	v_mov_b32_e32 v80, v41
	v_mov_b32_e32 v12, v38
	v_mov_b32_e32 v13, v40
	v_pk_fma_f32 v[8:9], v[8:9], s[56:57], v[78:79] op_sel_hi:[1,0,1]
	v_pk_add_f32 v[78:79], v[10:11], 0 op_sel_hi:[1,0]
	v_pk_mul_f32 v[80:81], v[80:81], s[60:61] op_sel_hi:[1,0]
	v_pk_mul_f32 v[92:93], v[76:77], s[52:53] op_sel:[1,0] op_sel_hi:[0,0] neg_hi:[1,0]
	v_pk_fma_f32 v[10:11], v[10:11], s[60:61], v[80:81] op_sel_hi:[1,0,1]
	v_pk_add_f32 v[80:81], v[12:13], 0 op_sel_hi:[1,0]
	v_xor_b32_e32 v83, 0x80000000, v38
	v_mov_b32_e32 v82, v40
	v_pk_fma_f32 v[76:77], v[76:77], s[54:55], v[92:93] op_sel_hi:[1,0,1]
	v_pk_add_f32 v[92:93], v[94:95], v[78:79]
	v_pk_add_f32 v[78:79], v[78:79], v[94:95] neg_lo:[0,1] neg_hi:[0,1]
	v_mov_b32_e32 v14, v43
	v_mov_b32_e32 v15, v45
	v_pk_mul_f32 v[82:83], v[82:83], s[56:57] op_sel_hi:[1,0]
	v_pk_add_f32 v[84:85], v[42:43], 0 neg_lo:[1,1] neg_hi:[1,1]
	v_xor_b32_e32 v95, 0x80000000, v78
	v_mov_b32_e32 v94, v79
	v_pk_add_f32 v[78:79], v[96:97], v[80:81]
	v_pk_add_f32 v[80:81], v[80:81], v[96:97] neg_lo:[0,1] neg_hi:[0,1]
	v_pk_fma_f32 v[12:13], v[12:13], s[58:59], v[82:83] op_sel_hi:[1,0,1]
	v_pk_add_f32 v[82:83], v[14:15], 0 op_sel_hi:[1,0]
	v_mov_b32_e32 v84, v45
	v_pk_mul_f32 v[96:97], v[80:81], s[54:55] op_sel_hi:[1,0]
	v_xor_b32_e32 v105, 0x80000000, v80
	v_mov_b32_e32 v104, v81
	v_mov_b32_e32 v16, v42
	v_mov_b32_e32 v17, v44
	v_pk_mul_f32 v[84:85], v[84:85], s[52:53] op_sel_hi:[1,0]
	v_xor_b32_e32 v87, 0x80000000, v42
	v_mov_b32_e32 v86, v44
	v_pk_fma_f32 v[80:81], v[104:105], s[52:53], v[96:97] op_sel_hi:[1,0,1] neg_lo:[0,0,1] neg_hi:[0,0,1]
	v_pk_add_f32 v[96:97], v[98:99], v[82:83]
	v_pk_add_f32 v[82:83], v[82:83], v[98:99] neg_lo:[0,1] neg_hi:[0,1]
	v_pk_fma_f32 v[14:15], v[14:15], s[54:55], v[84:85] op_sel_hi:[1,0,1]
	v_pk_add_f32 v[84:85], v[16:17], 0 op_sel_hi:[1,0]
	v_pk_mul_f32 v[86:87], v[86:87], s[44:45] op_sel_hi:[1,0]
	v_pk_mul_f32 v[98:99], v[82:83], s[60:61] op_sel_hi:[1,0]
	v_xor_b32_e32 v105, 0x80000000, v82
	v_mov_b32_e32 v104, v83
	v_pk_fma_f32 v[16:17], v[16:17], s[48:49], v[86:87] op_sel_hi:[1,0,1]
	v_pk_add_f32 v[86:87], v[46:47], 0 neg_lo:[1,1] neg_hi:[1,1]
	v_pk_fma_f32 v[82:83], v[104:105], s[60:61], v[98:99] op_sel_hi:[1,0,1] neg_lo:[0,0,1] neg_hi:[0,0,1]
	v_pk_add_f32 v[98:99], v[100:101], v[84:85]
	v_pk_add_f32 v[84:85], v[84:85], v[100:101] neg_lo:[0,1] neg_hi:[0,1]
	v_mov_b32_e32 v86, v49
	v_pk_mul_f32 v[100:101], v[84:85], s[52:53] op_sel_hi:[1,0]
	v_xor_b32_e32 v105, 0x80000000, v84
	v_mov_b32_e32 v104, v85
	v_pk_fma_f32 v[84:85], v[104:105], s[54:55], v[100:101] op_sel_hi:[1,0,1] neg_lo:[0,0,1] neg_hi:[0,0,1]
	v_pk_add_f32 v[100:101], v[86:87], v[2:3]
	v_pk_add_f32 v[2:3], v[2:3], v[86:87] neg_lo:[0,1] neg_hi:[0,1]
	v_pk_add_f32 v[86:87], v[20:21], v[4:5]
	v_pk_add_f32 v[4:5], v[4:5], v[20:21] neg_lo:[0,1] neg_hi:[0,1]
	v_mov_b32_e32 v63, v146
	v_pk_mul_f32 v[20:21], v[4:5], s[54:55] op_sel:[1,0] op_sel_hi:[0,0] neg_hi:[1,0]
	s_nop 0
	v_pk_fma_f32 v[4:5], v[4:5], s[52:53], v[20:21] op_sel_hi:[1,0,1]
	v_pk_add_f32 v[20:21], v[22:23], v[6:7]
	v_pk_add_f32 v[6:7], v[6:7], v[22:23] neg_lo:[0,1] neg_hi:[0,1]
	s_barrier
	v_pk_mul_f32 v[22:23], v[6:7], s[60:61] op_sel:[1,0] op_sel_hi:[0,0] neg_hi:[1,0]
	s_nop 0
	v_pk_fma_f32 v[6:7], v[6:7], s[60:61], v[22:23] op_sel_hi:[1,0,1]
	v_pk_add_f32 v[22:23], v[24:25], v[8:9]
	v_pk_add_f32 v[8:9], v[8:9], v[24:25] neg_lo:[0,1] neg_hi:[0,1]
	s_add_i32 s19, 16, 0x11000
	v_pk_mul_f32 v[24:25], v[8:9], s[52:53] op_sel:[1,0] op_sel_hi:[0,0] neg_hi:[1,0]
	s_add_i32 s18, 16, 0x12000
	v_pk_fma_f32 v[8:9], v[8:9], s[54:55], v[24:25] op_sel_hi:[1,0,1]
	v_pk_add_f32 v[24:25], v[26:27], v[10:11]
	v_pk_add_f32 v[10:11], v[10:11], v[26:27] neg_lo:[0,1] neg_hi:[0,1]
	s_add_i32 s17, 16, 0x13000
	v_xor_b32_e32 v27, 0x80000000, v10
	v_mov_b32_e32 v26, v11
	v_pk_add_f32 v[10:11], v[64:65], v[12:13]
	v_pk_add_f32 v[12:13], v[12:13], v[64:65] neg_lo:[0,1] neg_hi:[0,1]
	s_add_i32 s13, 16, 0x14000
	v_pk_mul_f32 v[64:65], v[12:13], s[54:55] op_sel_hi:[1,0]
	v_xor_b32_e32 v105, 0x80000000, v12
	v_mov_b32_e32 v104, v13
	v_pk_fma_f32 v[12:13], v[104:105], s[52:53], v[64:65] op_sel_hi:[1,0,1] neg_lo:[0,0,1] neg_hi:[0,0,1]
	v_pk_add_f32 v[64:65], v[66:67], v[14:15]
	v_pk_add_f32 v[14:15], v[14:15], v[66:67] neg_lo:[0,1] neg_hi:[0,1]
	s_add_i32 s12, 16, 0x15000
	v_pk_mul_f32 v[66:67], v[14:15], s[60:61] op_sel_hi:[1,0]
	v_xor_b32_e32 v105, 0x80000000, v14
	v_mov_b32_e32 v104, v15
	v_pk_fma_f32 v[14:15], v[104:105], s[60:61], v[66:67] op_sel_hi:[1,0,1] neg_lo:[0,0,1] neg_hi:[0,0,1]
	v_pk_add_f32 v[66:67], v[68:69], v[16:17]
	v_pk_add_f32 v[16:17], v[16:17], v[68:69] neg_lo:[0,1] neg_hi:[0,1]
	s_add_i32 s11, 16, 0x16000
	v_pk_mul_f32 v[68:69], v[16:17], s[52:53] op_sel_hi:[1,0]
	v_xor_b32_e32 v105, 0x80000000, v16
	v_mov_b32_e32 v104, v17
	v_pk_fma_f32 v[16:17], v[104:105], s[54:55], v[68:69] op_sel_hi:[1,0,1] neg_lo:[0,0,1] neg_hi:[0,0,1]
	v_pk_add_f32 v[68:69], v[92:93], v[102:103]
	v_pk_add_f32 v[92:93], v[102:103], v[92:93] neg_lo:[0,1] neg_hi:[0,1]
	v_pk_add_f32 v[102:103], v[78:79], v[70:71]
	v_pk_add_f32 v[70:71], v[70:71], v[78:79] neg_lo:[0,1] neg_hi:[0,1]
	s_add_i32 s10, 16, 0x17000
	v_pk_mul_f32 v[78:79], v[70:71], s[60:61] op_sel:[1,0] op_sel_hi:[0,0] neg_hi:[1,0]
	s_add_i32 s9, 16, 0x18000
	v_pk_fma_f32 v[70:71], v[70:71], s[60:61], v[78:79] op_sel_hi:[1,0,1]
	v_pk_add_f32 v[78:79], v[96:97], v[88:89]
	v_pk_add_f32 v[88:89], v[88:89], v[96:97] neg_lo:[0,1] neg_hi:[0,1]
	s_add_i32 s8, 16, 0x19000
	v_xor_b32_e32 v97, 0x80000000, v88
	v_mov_b32_e32 v96, v89
	v_pk_add_f32 v[88:89], v[98:99], v[90:91]
	v_pk_add_f32 v[90:91], v[90:91], v[98:99] neg_lo:[0,1] neg_hi:[0,1]
	s_add_i32 s7, 16, 0x1a000
	v_pk_mul_f32 v[98:99], v[90:91], s[60:61] op_sel_hi:[1,0]
	v_xor_b32_e32 v105, 0x80000000, v90
	v_mov_b32_e32 v104, v91
	v_pk_fma_f32 v[90:91], v[104:105], s[60:61], v[98:99] op_sel_hi:[1,0,1] neg_lo:[0,0,1] neg_hi:[0,0,1]
	v_pk_add_f32 v[98:99], v[94:95], v[18:19]
	v_pk_add_f32 v[18:19], v[18:19], v[94:95] neg_lo:[0,1] neg_hi:[0,1]
	v_pk_add_f32 v[94:95], v[80:81], v[72:73]
	v_pk_add_f32 v[72:73], v[72:73], v[80:81] neg_lo:[0,1] neg_hi:[0,1]
	s_add_i32 s6, 16, 0x1b000
	v_pk_mul_f32 v[80:81], v[72:73], s[60:61] op_sel:[1,0] op_sel_hi:[0,0] neg_hi:[1,0]
	s_add_i32 s5, 16, 0x1c000
	v_pk_fma_f32 v[72:73], v[72:73], s[60:61], v[80:81] op_sel_hi:[1,0,1]
	v_pk_add_f32 v[80:81], v[82:83], v[74:75]
	v_pk_add_f32 v[74:75], v[74:75], v[82:83] neg_lo:[0,1] neg_hi:[0,1]
	s_add_i32 s4, 16, 0x1d000
	v_xor_b32_e32 v83, 0x80000000, v74
	v_mov_b32_e32 v82, v75
	v_pk_add_f32 v[74:75], v[84:85], v[76:77]
	v_pk_add_f32 v[76:77], v[76:77], v[84:85] neg_lo:[0,1] neg_hi:[0,1]
	v_pk_add_f32 v[106:107], v[18:19], v[82:83]
	v_pk_mul_f32 v[84:85], v[76:77], s[60:61] op_sel_hi:[1,0]
	v_xor_b32_e32 v105, 0x80000000, v76
	v_mov_b32_e32 v104, v77
	v_pk_fma_f32 v[76:77], v[104:105], s[60:61], v[84:85] op_sel_hi:[1,0,1] neg_lo:[0,0,1] neg_hi:[0,0,1]
	v_pk_add_f32 v[84:85], v[24:25], v[100:101]
	v_pk_add_f32 v[24:25], v[100:101], v[24:25] neg_lo:[0,1] neg_hi:[0,1]
	v_pk_add_f32 v[100:101], v[10:11], v[86:87]
	v_pk_add_f32 v[10:11], v[86:87], v[10:11] neg_lo:[0,1] neg_hi:[0,1]
	v_pk_add_f32 v[18:19], v[18:19], v[82:83] neg_lo:[0,1] neg_hi:[0,1]
	v_pk_mul_f32 v[86:87], v[10:11], s[60:61] op_sel:[1,0] op_sel_hi:[0,0] neg_hi:[1,0]
	v_pk_add_f32 v[82:83], v[76:77], v[72:73]
	v_pk_fma_f32 v[10:11], v[10:11], s[60:61], v[86:87] op_sel_hi:[1,0,1]
	v_pk_add_f32 v[86:87], v[64:65], v[20:21]
	v_pk_add_f32 v[20:21], v[20:21], v[64:65] neg_lo:[0,1] neg_hi:[0,1]
	v_pk_add_f32 v[72:73], v[72:73], v[76:77] neg_lo:[0,1] neg_hi:[0,1]
	v_xor_b32_e32 v65, 0x80000000, v20
	v_mov_b32_e32 v64, v21
	v_pk_add_f32 v[20:21], v[66:67], v[22:23]
	v_pk_add_f32 v[22:23], v[22:23], v[66:67] neg_lo:[0,1] neg_hi:[0,1]
	v_xor_b32_e32 v77, 0x80000000, v72
	v_pk_mul_f32 v[66:67], v[22:23], s[60:61] op_sel_hi:[1,0]
	v_xor_b32_e32 v105, 0x80000000, v22
	v_mov_b32_e32 v104, v23
	v_pk_fma_f32 v[22:23], v[104:105], s[60:61], v[66:67] op_sel_hi:[1,0,1] neg_lo:[0,0,1] neg_hi:[0,0,1]
	v_pk_add_f32 v[66:67], v[2:3], v[26:27]
	v_pk_add_f32 v[2:3], v[2:3], v[26:27] neg_lo:[0,1] neg_hi:[0,1]
	v_pk_add_f32 v[26:27], v[12:13], v[4:5]
	v_pk_add_f32 v[4:5], v[4:5], v[12:13] neg_lo:[0,1] neg_hi:[0,1]
	v_mov_b32_e32 v76, v73
	v_pk_mul_f32 v[12:13], v[4:5], s[60:61] op_sel:[1,0] op_sel_hi:[0,0] neg_hi:[1,0]
	v_pk_add_f32 v[72:73], v[84:85], v[86:87]
	v_pk_fma_f32 v[4:5], v[4:5], s[60:61], v[12:13] op_sel_hi:[1,0,1]
	v_pk_add_f32 v[12:13], v[14:15], v[6:7]
	v_pk_add_f32 v[6:7], v[6:7], v[14:15] neg_lo:[0,1] neg_hi:[0,1]
	v_pk_add_f32 v[84:85], v[84:85], v[86:87] neg_lo:[0,1] neg_hi:[0,1]
	v_xor_b32_e32 v15, 0x80000000, v6
	v_mov_b32_e32 v14, v7
	v_pk_add_f32 v[6:7], v[16:17], v[8:9]
	v_pk_add_f32 v[8:9], v[8:9], v[16:17] neg_lo:[0,1] neg_hi:[0,1]
	v_pk_add_f32 v[86:87], v[20:21], v[100:101]
	v_pk_mul_f32 v[16:17], v[8:9], s[60:61] op_sel_hi:[1,0]
	s_nop 0
	v_pk_fma_f32 v[8:9], v[8:9], s[60:61], v[16:17] op_sel:[1,0,0] op_sel_hi:[0,0,1] neg_lo:[0,0,1] neg_hi:[1,0,1]
	v_pk_add_f32 v[104:105], v[92:93], v[96:97]
	v_pk_add_f32 v[92:93], v[92:93], v[96:97] neg_lo:[0,1] neg_hi:[0,1]
	v_pk_add_f32 v[96:97], v[90:91], v[70:71]
	v_pk_add_f32 v[70:71], v[70:71], v[90:91] neg_lo:[0,1] neg_hi:[0,1]
	v_pk_add_f32 v[16:17], v[78:79], v[68:69]
	v_pk_add_f32 v[68:69], v[68:69], v[78:79] neg_lo:[0,1] neg_hi:[0,1]
	v_pk_add_f32 v[78:79], v[88:89], v[102:103]
	v_pk_add_f32 v[88:89], v[102:103], v[88:89] neg_lo:[0,1] neg_hi:[0,1]
	v_xor_b32_e32 v91, 0x80000000, v70
	v_mov_b32_e32 v90, v71
	v_pk_add_f32 v[70:71], v[98:99], v[80:81]
	v_pk_add_f32 v[98:99], v[98:99], v[80:81] neg_lo:[0,1] neg_hi:[0,1]
	v_pk_add_f32 v[80:81], v[74:75], v[94:95]
	v_pk_add_f32 v[74:75], v[94:95], v[74:75] neg_lo:[0,1] neg_hi:[0,1]
	v_pk_add_f32 v[20:21], v[100:101], v[20:21] neg_lo:[0,1] neg_hi:[0,1]
	v_pk_add_f32 v[108:109], v[24:25], v[64:65]
	v_pk_add_f32 v[24:25], v[24:25], v[64:65] neg_lo:[0,1] neg_hi:[0,1]
	v_pk_add_f32 v[64:65], v[22:23], v[10:11]
	v_pk_add_f32 v[10:11], v[10:11], v[22:23] neg_lo:[0,1] neg_hi:[0,1]
	v_pk_add_f32 v[114:115], v[6:7], v[26:27]
	v_pk_add_f32 v[6:7], v[26:27], v[6:7] neg_lo:[0,1] neg_hi:[0,1]
	v_xor_b32_e32 v103, 0x80000000, v88
	v_mov_b32_e32 v102, v89
	v_xor_b32_e32 v95, 0x80000000, v74
	v_mov_b32_e32 v94, v75
	v_xor_b32_e32 v101, 0x80000000, v20
	v_mov_b32_e32 v100, v21
	v_xor_b32_e32 v27, 0x80000000, v6
	v_mov_b32_e32 v26, v7
	v_pk_add_f32 v[6:7], v[2:3], v[14:15]
	v_pk_add_f32 v[116:117], v[2:3], v[14:15] neg_lo:[0,1] neg_hi:[0,1]
	v_pk_add_f32 v[2:3], v[4:5], v[8:9] neg_lo:[0,1] neg_hi:[0,1]
	v_pk_add_f32 v[112:113], v[66:67], v[12:13]
	v_pk_add_f32 v[66:67], v[66:67], v[12:13] neg_lo:[0,1] neg_hi:[0,1]
	v_pk_add_f32 v[118:119], v[8:9], v[4:5]
	v_xor_b32_e32 v121, 0x80000000, v2
	v_mov_b32_e32 v120, v3
	v_pk_add_f32 v[2:3], v[78:79], v[16:17]
	v_pk_add_f32 v[88:89], v[16:17], v[78:79] neg_lo:[0,1] neg_hi:[0,1]
	v_pk_add_f32 v[122:123], v[68:69], v[102:103]
	v_pk_add_f32 v[20:21], v[68:69], v[102:103] neg_lo:[0,1] neg_hi:[0,1]
	v_pk_add_f32 v[78:79], v[104:105], v[96:97]
	v_pk_add_f32 v[74:75], v[104:105], v[96:97] neg_lo:[0,1] neg_hi:[0,1]
	v_pk_add_f32 v[96:97], v[92:93], v[90:91]
	v_pk_add_f32 v[8:9], v[92:93], v[90:91] neg_lo:[0,1] neg_hi:[0,1]
	v_pk_add_f32 v[102:103], v[98:99], v[94:95]
	v_pk_add_f32 v[12:13], v[98:99], v[94:95] neg_lo:[0,1] neg_hi:[0,1]
	v_pk_add_f32 v[98:99], v[18:19], v[76:77]
	v_pk_add_f32 v[4:5], v[18:19], v[76:77] neg_lo:[0,1] neg_hi:[0,1]
	v_pk_add_f32 v[18:19], v[72:73], v[86:87]
	v_pk_add_f32 v[92:93], v[72:73], v[86:87] neg_lo:[0,1] neg_hi:[0,1]
	v_pk_add_f32 v[86:87], v[84:85], v[100:101]
	v_pk_add_f32 v[22:23], v[84:85], v[100:101] neg_lo:[0,1] neg_hi:[0,1]
	v_pk_add_f32 v[100:101], v[24:25], v[10:11] op_sel:[0,1] op_sel_hi:[1,0] neg_hi:[0,1]
	v_pk_add_f32 v[10:11], v[24:25], v[10:11] op_sel:[0,1] op_sel_hi:[1,0] neg_lo:[0,1]
	v_mov_b32_e32 v24, v63
	v_pk_add_f32 v[84:85], v[108:109], v[64:65]
	v_cvt_f32_i32_e32 v24, v24
	v_pk_add_f32 v[76:77], v[108:109], v[64:65] neg_lo:[0,1] neg_hi:[0,1]
	v_pk_add_f32 v[104:105], v[66:67], v[26:27]
	v_pk_add_f32 v[14:15], v[66:67], v[26:27] neg_lo:[0,1] neg_hi:[0,1]
	v_mul_f32_e32 v25, 0x38800000, v24
	v_cos_f32_e32 v24, v25
	v_sin_f32_e32 v25, v25
	s_nop 0
	s_nop 0
	v_add_f32_e32 v62, v24, v24
	v_pk_mul_f32 v[26:27], v[24:25], v[24:25]
	v_mul_f32_e32 v62, v25, v62
	s_nop 0
	s_nop 0
	v_mov_b32_e32 v108, v25
	v_pk_add_f32 v[26:27], v[26:27], v[26:27] op_sel:[0,1] op_sel_hi:[0,1] neg_lo:[0,1] neg_hi:[0,1]
	v_pk_mul_f32 v[72:73], v[24:25], v[62:63] op_sel:[1,0] op_sel_hi:[0,0] neg_lo:[1,0]
	v_pk_mul_f32 v[94:95], v[18:19], v[108:109] op_sel:[1,0] op_sel_hi:[0,0] neg_hi:[1,0]
	v_pk_add_f32 v[16:17], v[70:71], v[80:81]
	v_pk_fma_f32 v[72:73], v[24:25], v[26:27], v[72:73]
	v_pk_fma_f32 v[18:19], v[18:19], v[24:25], v[94:95] op_sel_hi:[1,0,1]
	v_pk_mul_f32 v[24:25], v[62:63], s[46:47] op_sel_hi:[0,1]
	v_pk_fma_f32 v[94:95], v[26:27], s[40:41], v[24:25]
	s_nop 0
	v_pk_mul_f32 v[24:25], v[16:17], v[94:95] op_sel:[1,1] op_sel_hi:[0,1] neg_hi:[1,0]
	v_pk_add_f32 v[64:65], v[112:113], v[114:115]
	v_pk_fma_f32 v[24:25], v[16:17], v[94:95], v[24:25] op_sel_hi:[1,0,1]
	v_pk_mul_f32 v[16:17], v[62:63], v[72:73] op_sel:[0,1] op_sel_hi:[0,0] neg_lo:[0,1]
	v_pk_fma_f32 v[108:109], v[26:27], v[72:73], v[16:17]
	v_pk_mul_f32 v[16:17], v[64:65], v[72:73] op_sel:[1,1] op_sel_hi:[0,1] neg_hi:[1,0]
	v_pk_add_f32 v[90:91], v[106:107], v[82:83]
	v_pk_fma_f32 v[16:17], v[64:65], v[72:73], v[16:17] op_sel_hi:[1,0,1]
	v_pk_mul_f32 v[64:65], v[62:63], v[94:95] op_sel:[0,1] op_sel_hi:[0,0] neg_lo:[0,1]
	v_pk_fma_f32 v[94:95], v[26:27], v[94:95], v[64:65]
	s_nop 0
	v_pk_mul_f32 v[64:65], v[78:79], v[94:95] op_sel:[1,1] op_sel_hi:[0,1] neg_hi:[1,0]
	v_pk_add_f32 v[66:67], v[6:7], v[118:119]
	v_pk_fma_f32 v[72:73], v[78:79], v[94:95], v[64:65] op_sel_hi:[1,0,1]
	v_pk_mul_f32 v[64:65], v[62:63], v[108:109] op_sel:[0,1] op_sel_hi:[0,0] neg_lo:[0,1]
	v_pk_fma_f32 v[110:111], v[26:27], v[108:109], v[64:65]
	v_pk_mul_f32 v[64:65], v[84:85], v[108:109] op_sel:[1,1] op_sel_hi:[0,1] neg_hi:[1,0]
	v_pk_mul_f32 v[78:79], v[62:63], v[94:95] op_sel:[0,1] op_sel_hi:[0,0] neg_lo:[0,1]
	v_pk_fma_f32 v[64:65], v[84:85], v[108:109], v[64:65] op_sel_hi:[1,0,1]
	v_pk_fma_f32 v[84:85], v[26:27], v[94:95], v[78:79]
	s_nop 0
	v_pk_mul_f32 v[78:79], v[90:91], v[84:85] op_sel:[1,1] op_sel_hi:[0,1] neg_hi:[1,0]
	v_pk_add_f32 v[68:69], v[106:107], v[82:83] neg_lo:[0,1] neg_hi:[0,1]
	v_pk_fma_f32 v[78:79], v[90:91], v[84:85], v[78:79] op_sel_hi:[1,0,1]
	v_pk_mul_f32 v[90:91], v[62:63], v[110:111] op_sel:[0,1] op_sel_hi:[0,0] neg_lo:[0,1]
	v_pk_fma_f32 v[94:95], v[26:27], v[110:111], v[90:91]
	v_pk_mul_f32 v[90:91], v[66:67], v[110:111] op_sel:[1,1] op_sel_hi:[0,1] neg_hi:[1,0]
	v_pk_add_f32 v[106:107], v[116:117], v[120:121]
	v_pk_fma_f32 v[66:67], v[66:67], v[110:111], v[90:91] op_sel_hi:[1,0,1]
	v_pk_mul_f32 v[90:91], v[62:63], v[84:85] op_sel:[0,1] op_sel_hi:[0,0] neg_lo:[0,1]
	v_pk_fma_f32 v[108:109], v[26:27], v[84:85], v[90:91]
	s_nop 0
	v_pk_mul_f32 v[84:85], v[122:123], v[108:109] op_sel:[1,1] op_sel_hi:[0,1] neg_hi:[1,0]
	v_pk_add_f32 v[80:81], v[70:71], v[80:81] neg_lo:[0,1] neg_hi:[0,1]
	v_pk_fma_f32 v[90:91], v[122:123], v[108:109], v[84:85] op_sel_hi:[1,0,1]
	v_pk_mul_f32 v[84:85], v[62:63], v[94:95] op_sel:[0,1] op_sel_hi:[0,0] neg_lo:[0,1]
	v_pk_fma_f32 v[110:111], v[26:27], v[94:95], v[84:85]
	v_pk_mul_f32 v[84:85], v[86:87], v[94:95] op_sel:[1,1] op_sel_hi:[0,1] neg_hi:[1,0]
	v_pk_add_f32 v[82:83], v[112:113], v[114:115] neg_lo:[0,1] neg_hi:[0,1]
	v_pk_fma_f32 v[84:85], v[86:87], v[94:95], v[84:85] op_sel_hi:[1,0,1]
	v_pk_mul_f32 v[86:87], v[62:63], v[108:109] op_sel:[0,1] op_sel_hi:[0,0] neg_lo:[0,1]
	v_pk_fma_f32 v[108:109], v[26:27], v[108:109], v[86:87]
	s_nop 0
	v_pk_mul_f32 v[86:87], v[102:103], v[108:109] op_sel:[1,1] op_sel_hi:[0,1] neg_hi:[1,0]
	v_pk_add_f32 v[70:71], v[6:7], v[118:119] neg_lo:[0,1] neg_hi:[0,1]
	v_pk_fma_f32 v[94:95], v[102:103], v[108:109], v[86:87] op_sel_hi:[1,0,1]
	v_pk_mul_f32 v[86:87], v[62:63], v[110:111] op_sel:[0,1] op_sel_hi:[0,0] neg_lo:[0,1]
	v_pk_fma_f32 v[102:103], v[26:27], v[110:111], v[86:87]
	v_pk_mul_f32 v[86:87], v[104:105], v[110:111] op_sel:[1,1] op_sel_hi:[0,1] neg_hi:[1,0]
	v_pk_add_f32 v[6:7], v[116:117], v[120:121] neg_lo:[0,1] neg_hi:[0,1]
	v_pk_fma_f32 v[86:87], v[104:105], v[110:111], v[86:87] op_sel_hi:[1,0,1]
	v_pk_mul_f32 v[104:105], v[62:63], v[108:109] op_sel:[0,1] op_sel_hi:[0,0] neg_lo:[0,1]
	v_pk_fma_f32 v[104:105], v[26:27], v[108:109], v[104:105]
	s_nop 0
	v_pk_mul_f32 v[108:109], v[96:97], v[104:105] op_sel:[1,1] op_sel_hi:[0,1] neg_hi:[1,0]
	s_nop 0
	v_pk_fma_f32 v[96:97], v[96:97], v[104:105], v[108:109] op_sel_hi:[1,0,1]
	v_pk_mul_f32 v[108:109], v[62:63], v[102:103] op_sel:[0,1] op_sel_hi:[0,0] neg_lo:[0,1]
	v_pk_mul_f32 v[110:111], v[100:101], v[102:103] op_sel:[1,1] op_sel_hi:[0,1] neg_hi:[1,0]
	v_pk_fma_f32 v[108:109], v[26:27], v[102:103], v[108:109]
	v_pk_fma_f32 v[100:101], v[100:101], v[102:103], v[110:111] op_sel_hi:[1,0,1]
	v_pk_mul_f32 v[102:103], v[62:63], v[104:105] op_sel:[0,1] op_sel_hi:[0,0] neg_lo:[0,1]
	v_pk_fma_f32 v[102:103], v[26:27], v[104:105], v[102:103]
	s_nop 0
	v_pk_mul_f32 v[104:105], v[98:99], v[102:103] op_sel:[1,1] op_sel_hi:[0,1] neg_hi:[1,0]
	s_nop 0
	v_pk_fma_f32 v[98:99], v[98:99], v[102:103], v[104:105] op_sel_hi:[1,0,1]
	v_pk_mul_f32 v[104:105], v[62:63], v[108:109] op_sel:[0,1] op_sel_hi:[0,0] neg_lo:[0,1]
	v_pk_mul_f32 v[110:111], v[106:107], v[108:109] op_sel:[1,1] op_sel_hi:[0,1] neg_hi:[1,0]
	v_pk_fma_f32 v[104:105], v[26:27], v[108:109], v[104:105]
	v_pk_fma_f32 v[106:107], v[106:107], v[108:109], v[110:111] op_sel_hi:[1,0,1]
	v_pk_mul_f32 v[108:109], v[62:63], v[102:103] op_sel:[0,1] op_sel_hi:[0,0] neg_lo:[0,1]
	v_pk_fma_f32 v[102:103], v[26:27], v[102:103], v[108:109]
	s_nop 0
	v_pk_mul_f32 v[108:109], v[88:89], v[102:103] op_sel:[1,1] op_sel_hi:[0,1] neg_hi:[1,0]
	s_nop 0
	v_pk_fma_f32 v[88:89], v[88:89], v[102:103], v[108:109] op_sel_hi:[1,0,1]
	v_pk_mul_f32 v[108:109], v[62:63], v[104:105] op_sel:[0,1] op_sel_hi:[0,0] neg_lo:[0,1]
	v_pk_mul_f32 v[110:111], v[92:93], v[104:105] op_sel:[1,1] op_sel_hi:[0,1] neg_hi:[1,0]
	v_pk_fma_f32 v[108:109], v[26:27], v[104:105], v[108:109]
	v_pk_fma_f32 v[92:93], v[92:93], v[104:105], v[110:111] op_sel_hi:[1,0,1]
	v_pk_mul_f32 v[104:105], v[62:63], v[102:103] op_sel:[0,1] op_sel_hi:[0,0] neg_lo:[0,1]
	v_pk_fma_f32 v[102:103], v[26:27], v[102:103], v[104:105]
	s_nop 0
	v_pk_mul_f32 v[104:105], v[80:81], v[102:103] op_sel:[1,1] op_sel_hi:[0,1] neg_hi:[1,0]
	s_nop 0
	v_pk_fma_f32 v[80:81], v[80:81], v[102:103], v[104:105] op_sel_hi:[1,0,1]
	v_pk_mul_f32 v[104:105], v[62:63], v[108:109] op_sel:[0,1] op_sel_hi:[0,0] neg_lo:[0,1]
	v_pk_mul_f32 v[110:111], v[82:83], v[108:109] op_sel:[1,1] op_sel_hi:[0,1] neg_hi:[1,0]
	v_pk_fma_f32 v[104:105], v[26:27], v[108:109], v[104:105]
	v_pk_fma_f32 v[82:83], v[82:83], v[108:109], v[110:111] op_sel_hi:[1,0,1]
	v_pk_mul_f32 v[108:109], v[62:63], v[102:103] op_sel:[0,1] op_sel_hi:[0,0] neg_lo:[0,1]
	v_pk_fma_f32 v[102:103], v[26:27], v[102:103], v[108:109]
	s_nop 0
	v_pk_mul_f32 v[108:109], v[74:75], v[102:103] op_sel:[1,1] op_sel_hi:[0,1] neg_hi:[1,0]
	s_nop 0
	v_pk_fma_f32 v[74:75], v[74:75], v[102:103], v[108:109] op_sel_hi:[1,0,1]
	v_pk_mul_f32 v[108:109], v[62:63], v[104:105] op_sel:[0,1] op_sel_hi:[0,0] neg_lo:[0,1]
	v_pk_mul_f32 v[110:111], v[76:77], v[104:105] op_sel:[1,1] op_sel_hi:[0,1] neg_hi:[1,0]
	v_pk_fma_f32 v[108:109], v[26:27], v[104:105], v[108:109]
	v_pk_fma_f32 v[76:77], v[76:77], v[104:105], v[110:111] op_sel_hi:[1,0,1]
	v_pk_mul_f32 v[104:105], v[62:63], v[102:103] op_sel:[0,1] op_sel_hi:[0,0] neg_lo:[0,1]
	v_pk_fma_f32 v[102:103], v[26:27], v[102:103], v[104:105]
	s_nop 0
	v_pk_mul_f32 v[104:105], v[68:69], v[102:103] op_sel:[1,1] op_sel_hi:[0,1] neg_hi:[1,0]
	s_nop 0
	v_pk_fma_f32 v[68:69], v[68:69], v[102:103], v[104:105] op_sel_hi:[1,0,1]
	v_pk_mul_f32 v[104:105], v[62:63], v[108:109] op_sel:[0,1] op_sel_hi:[0,0] neg_lo:[0,1]
	v_pk_mul_f32 v[110:111], v[70:71], v[108:109] op_sel:[1,1] op_sel_hi:[0,1] neg_hi:[1,0]
	v_pk_fma_f32 v[104:105], v[26:27], v[108:109], v[104:105]
	v_pk_fma_f32 v[70:71], v[70:71], v[108:109], v[110:111] op_sel_hi:[1,0,1]
	v_pk_mul_f32 v[108:109], v[62:63], v[102:103] op_sel:[0,1] op_sel_hi:[0,0] neg_lo:[0,1]
	v_pk_fma_f32 v[102:103], v[26:27], v[102:103], v[108:109]
	s_nop 0
	v_pk_mul_f32 v[108:109], v[20:21], v[102:103] op_sel:[1,1] op_sel_hi:[0,1] neg_hi:[1,0]
	s_nop 0
	v_pk_fma_f32 v[20:21], v[20:21], v[102:103], v[108:109] op_sel_hi:[1,0,1]
	v_pk_mul_f32 v[108:109], v[62:63], v[104:105] op_sel:[0,1] op_sel_hi:[0,0] neg_lo:[0,1]
	v_pk_mul_f32 v[110:111], v[22:23], v[104:105] op_sel:[1,1] op_sel_hi:[0,1] neg_hi:[1,0]
	v_pk_fma_f32 v[108:109], v[26:27], v[104:105], v[108:109]
	v_pk_fma_f32 v[22:23], v[22:23], v[104:105], v[110:111] op_sel_hi:[1,0,1]
	v_pk_mul_f32 v[104:105], v[62:63], v[102:103] op_sel:[0,1] op_sel_hi:[0,0] neg_lo:[0,1]
	v_pk_fma_f32 v[102:103], v[26:27], v[102:103], v[104:105]
	s_nop 0
	v_pk_mul_f32 v[104:105], v[12:13], v[102:103] op_sel:[1,1] op_sel_hi:[0,1] neg_hi:[1,0]
	s_nop 0
	v_pk_fma_f32 v[12:13], v[12:13], v[102:103], v[104:105] op_sel_hi:[1,0,1]
	v_pk_mul_f32 v[104:105], v[62:63], v[108:109] op_sel:[0,1] op_sel_hi:[0,0] neg_lo:[0,1]
	v_pk_mul_f32 v[110:111], v[14:15], v[108:109] op_sel:[1,1] op_sel_hi:[0,1] neg_hi:[1,0]
	v_pk_fma_f32 v[104:105], v[26:27], v[108:109], v[104:105]
	v_pk_fma_f32 v[14:15], v[14:15], v[108:109], v[110:111] op_sel_hi:[1,0,1]
	v_pk_mul_f32 v[108:109], v[62:63], v[102:103] op_sel:[0,1] op_sel_hi:[0,0] neg_lo:[0,1]
	v_pk_fma_f32 v[102:103], v[26:27], v[102:103], v[108:109]
	s_nop 0
	v_pk_mul_f32 v[108:109], v[8:9], v[102:103] op_sel:[1,1] op_sel_hi:[0,1] neg_hi:[1,0]
	s_nop 0
	v_pk_fma_f32 v[8:9], v[8:9], v[102:103], v[108:109] op_sel_hi:[1,0,1]
	v_pk_mul_f32 v[108:109], v[62:63], v[104:105] op_sel:[0,1] op_sel_hi:[0,0] neg_lo:[0,1]
	v_pk_mul_f32 v[110:111], v[10:11], v[104:105] op_sel:[1,1] op_sel_hi:[0,1] neg_hi:[1,0]
	v_pk_fma_f32 v[108:109], v[26:27], v[104:105], v[108:109]
	v_pk_fma_f32 v[10:11], v[10:11], v[104:105], v[110:111] op_sel_hi:[1,0,1]
	v_pk_mul_f32 v[104:105], v[62:63], v[102:103] op_sel:[0,1] op_sel_hi:[0,0] neg_lo:[0,1]
	v_pk_fma_f32 v[26:27], v[26:27], v[102:103], v[104:105]
	s_nop 0
	v_pk_mul_f32 v[102:103], v[4:5], v[26:27] op_sel:[1,1] op_sel_hi:[0,1] neg_hi:[1,0]
	s_add_i32 s1, 16, 0x1e000
	v_pk_fma_f32 v[4:5], v[4:5], v[26:27], v[102:103] op_sel_hi:[1,0,1]
	s_nop 0
	s_nop 0
	v_pk_mul_f32 v[26:27], v[6:7], v[108:109] op_sel:[1,1] op_sel_hi:[0,1] neg_hi:[1,0]
	s_add_i32 s0, 16, 0x1f000
	v_pk_fma_f32 v[6:7], v[6:7], v[108:109], v[26:27] op_sel_hi:[1,0,1]
	v_lshrrev_b32_e32 v26, 5, v63
	v_bitop3_b32 v26, v26, v63, 15 bitop3:0x6c
	v_lshlrev_b32_e32 v26, 3, v26
	v_bfe_u32 v27, v63, 5, 4
	v_add_u32_e32 v62, 16, v26
	ds_write_b64 v62, v[2:3]
	v_bitop3_b32 v2, v27, v63, 16 bitop3:0x36
	v_lshlrev_b32_e32 v2, 3, v2
	v_add_u32_e32 v3, 16, v2
	ds_write_b64 v3, v[88:89] offset:4096
	ds_write_b64 v62, v[90:91] offset:8192
	ds_write_b64 v3, v[20:21] offset:12288
	ds_write_b64 v62, v[72:73] offset:16384
	ds_write_b64 v3, v[74:75] offset:20480
	ds_write_b64 v62, v[96:97] offset:24576
	ds_write_b64 v3, v[8:9] offset:28672
	ds_write_b64 v62, v[24:25] offset:32768
	ds_write_b64 v3, v[80:81] offset:36864
	ds_write_b64 v62, v[94:95] offset:40960
	ds_write_b64 v3, v[12:13] offset:45056
	ds_write_b64 v62, v[78:79] offset:49152
	ds_write_b64 v3, v[68:69] offset:53248
	ds_write_b64 v62, v[98:99] offset:57344
	ds_write_b64 v3, v[4:5] offset:61440
	v_add_u32_e32 v3, s79, v26
	ds_write_b64 v3, v[18:19]
	v_add_u32_e32 v3, s19, v2
	ds_write_b64 v3, v[92:93]
	v_add_u32_e32 v3, s18, v26
	ds_write_b64 v3, v[84:85]
	v_add_u32_e32 v3, s17, v2
	ds_write_b64 v3, v[22:23]
	v_add_u32_e32 v3, s13, v26
	ds_write_b64 v3, v[64:65]
	v_add_u32_e32 v3, s12, v2
	ds_write_b64 v3, v[76:77]
	v_add_u32_e32 v3, s11, v26
	ds_write_b64 v3, v[100:101]
	v_add_u32_e32 v3, s10, v2
	ds_write_b64 v3, v[10:11]
	v_add_u32_e32 v3, s9, v26
	ds_write_b64 v3, v[16:17]
	v_add_u32_e32 v3, s8, v2
	ds_write_b64 v3, v[82:83]
	v_add_u32_e32 v3, s7, v26
	ds_write_b64 v3, v[86:87]
	v_add_u32_e32 v3, s6, v2
	ds_write_b64 v3, v[14:15]
	v_add_u32_e32 v3, s5, v26
	ds_write_b64 v3, v[66:67]
	v_add_u32_e32 v3, s4, v2
	ds_write_b64 v3, v[70:71]
	v_add_u32_e32 v3, s1, v26
	v_add_u32_e32 v2, s0, v2
	v_mov_b32_e32 v21, v146
	ds_write_b64 v3, v[106:107]
	ds_write_b64 v2, v[6:7]
	s_waitcnt lgkmcnt(0)
	s_barrier
	s_lshl_b32 s42, s16, 14
	v_lshlrev_b32_e32 v2, 5, v21
	v_and_b32_e32 v4, 0xfffffe00, v2
	v_and_b32_e32 v20, 15, v21
	v_and_or_b32 v2, v21, 16, v4
	v_bitop3_b32 v4, v4, 16, v21 bitop3:0x34
	v_bitop3_b32 v72, v21, 8, 15 bitop3:0x6c
	v_lshl_add_u32 v26, v2, 3, 16
	v_lshlrev_b32_e32 v5, 3, v20
	v_lshl_add_u32 v126, v4, 3, 16
	v_lshlrev_b32_e32 v74, 3, v72
	v_add_u32_e32 v27, v26, v5
	v_add_u32_e32 v96, v126, v5
	v_add_u32_e32 v111, v26, v74
	v_add_u32_e32 v112, v126, v74
	ds_read_b64 v[2:3], v27
	ds_read_b64 v[4:5], v96
	v_bitop3_b32 v6, v21, 1, 15 bitop3:0x6c
	ds_read_b64 v[72:73], v111 offset:2048
	ds_read_b64 v[74:75], v112 offset:2048
	v_bitop3_b32 v76, v21, 9, 15 bitop3:0x6c
	v_lshlrev_b32_e32 v8, 3, v6
	v_lshlrev_b32_e32 v78, 3, v76
	v_add_u32_e32 v97, v26, v8
	v_add_u32_e32 v113, v26, v78
	ds_read_b64 v[6:7], v97 offset:256
	ds_read_b64 v[76:77], v113 offset:2304
	v_add_u32_e32 v98, v126, v8
	v_add_u32_e32 v114, v126, v78
	ds_read_b64 v[8:9], v98 offset:256
	ds_read_b64 v[78:79], v114 offset:2304
	s_waitcnt lgkmcnt(5)
	v_pk_add_f32 v[136:137], v[2:3], v[72:73]
	v_pk_add_f32 v[2:3], v[2:3], v[72:73] neg_lo:[0,1] neg_hi:[0,1]
	s_waitcnt lgkmcnt(4)
	v_pk_add_f32 v[72:73], v[4:5], v[74:75]
	v_pk_add_f32 v[4:5], v[4:5], v[74:75] neg_lo:[0,1] neg_hi:[0,1]
	v_bitop3_b32 v10, v21, 2, 15 bitop3:0x6c
	v_bitop3_b32 v80, v21, 10, 15 bitop3:0x6c
	v_lshlrev_b32_e32 v12, 3, v10
	v_lshlrev_b32_e32 v82, 3, v80
	v_pk_mul_f32 v[74:75], v[4:5], s[48:49] op_sel:[1,0] op_sel_hi:[0,0] neg_hi:[1,0]
	v_add_u32_e32 v99, v26, v12
	v_add_u32_e32 v115, v26, v82
	v_pk_fma_f32 v[4:5], v[4:5], s[44:45], v[74:75] op_sel_hi:[1,0,1]
	s_waitcnt lgkmcnt(2)
	v_pk_add_f32 v[74:75], v[6:7], v[76:77]
	v_pk_add_f32 v[6:7], v[6:7], v[76:77] neg_lo:[0,1] neg_hi:[0,1]
	ds_read_b64 v[10:11], v99 offset:512
	ds_read_b64 v[80:81], v115 offset:2560
	v_pk_mul_f32 v[76:77], v[6:7], s[54:55] op_sel:[1,0] op_sel_hi:[0,0] neg_hi:[1,0]
	v_add_u32_e32 v100, v126, v12
	v_bitop3_b32 v14, v21, 3, 15 bitop3:0x6c
	v_add_u32_e32 v116, v126, v82
	v_bitop3_b32 v84, v21, 11, 15 bitop3:0x6c
	v_pk_fma_f32 v[6:7], v[6:7], s[52:53], v[76:77] op_sel_hi:[1,0,1]
	s_waitcnt lgkmcnt(2)
	v_pk_add_f32 v[76:77], v[8:9], v[78:79]
	v_pk_add_f32 v[8:9], v[8:9], v[78:79] neg_lo:[0,1] neg_hi:[0,1]
	ds_read_b64 v[12:13], v100 offset:512
	v_lshlrev_b32_e32 v16, 3, v14
	ds_read_b64 v[82:83], v116 offset:2560
	v_lshlrev_b32_e32 v86, 3, v84
	v_add_u32_e32 v101, v26, v16
	v_add_u32_e32 v102, v126, v16
	v_add_u32_e32 v117, v26, v86
	v_add_u32_e32 v118, v126, v86
	v_pk_mul_f32 v[78:79], v[8:9], s[58:59] op_sel:[1,0] op_sel_hi:[0,0] neg_hi:[1,0]
	ds_read_b64 v[14:15], v101 offset:768
	ds_read_b64 v[16:17], v102 offset:768
	ds_read_b64 v[84:85], v117 offset:2816
	ds_read_b64 v[86:87], v118 offset:2816
	v_pk_fma_f32 v[8:9], v[8:9], s[56:57], v[78:79] op_sel_hi:[1,0,1]
	s_waitcnt lgkmcnt(6)
	v_pk_add_f32 v[78:79], v[10:11], v[80:81]
	v_pk_add_f32 v[10:11], v[10:11], v[80:81] neg_lo:[0,1] neg_hi:[0,1]
	v_bitop3_b32 v18, v21, 4, 15 bitop3:0x6c
	v_pk_mul_f32 v[80:81], v[10:11], s[60:61] op_sel:[1,0] op_sel_hi:[0,0] neg_hi:[1,0]
	v_bitop3_b32 v88, v21, 12, 15 bitop3:0x6c
	v_pk_fma_f32 v[10:11], v[10:11], s[60:61], v[80:81] op_sel_hi:[1,0,1]
	s_waitcnt lgkmcnt(4)
	v_pk_add_f32 v[80:81], v[12:13], v[82:83]
	v_pk_add_f32 v[12:13], v[12:13], v[82:83] neg_lo:[0,1] neg_hi:[0,1]
	v_lshlrev_b32_e32 v22, 3, v18
	v_lshlrev_b32_e32 v90, 3, v88
	v_pk_mul_f32 v[82:83], v[12:13], s[56:57] op_sel:[1,0] op_sel_hi:[0,0] neg_hi:[1,0]
	v_add_u32_e32 v103, v26, v22
	v_add_u32_e32 v119, v26, v90
	v_pk_fma_f32 v[12:13], v[12:13], s[58:59], v[82:83] op_sel_hi:[1,0,1]
	s_waitcnt lgkmcnt(1)
	v_pk_add_f32 v[82:83], v[14:15], v[84:85]
	v_pk_add_f32 v[14:15], v[14:15], v[84:85] neg_lo:[0,1] neg_hi:[0,1]
	ds_read_b64 v[18:19], v103 offset:1024
	v_add_u32_e32 v104, v126, v22
	v_bitop3_b32 v24, v21, 5, 15 bitop3:0x6c
	ds_read_b64 v[88:89], v119 offset:3072
	v_add_u32_e32 v120, v126, v90
	v_bitop3_b32 v92, v21, 13, 15 bitop3:0x6c
	ds_read_b64 v[22:23], v104 offset:1024
	v_lshlrev_b32_e32 v62, 3, v24
	ds_read_b64 v[90:91], v120 offset:3072
	v_lshlrev_b32_e32 v94, 3, v92
	v_pk_mul_f32 v[84:85], v[14:15], s[52:53] op_sel:[1,0] op_sel_hi:[0,0] neg_hi:[1,0]
	v_add_u32_e32 v105, v26, v62
	v_add_u32_e32 v121, v26, v94
	v_pk_fma_f32 v[14:15], v[14:15], s[54:55], v[84:85] op_sel_hi:[1,0,1]
	s_waitcnt lgkmcnt(4)
	v_pk_add_f32 v[84:85], v[16:17], v[86:87]
	v_pk_add_f32 v[16:17], v[16:17], v[86:87] neg_lo:[0,1] neg_hi:[0,1]
	ds_read_b64 v[24:25], v105 offset:1280
	ds_read_b64 v[92:93], v121 offset:3328
	v_add_u32_e32 v106, v126, v62
	v_bitop3_b32 v64, v21, 6, 15 bitop3:0x6c
	v_add_u32_e32 v122, v126, v94
	v_bitop3_b32 v123, v21, 14, 15 bitop3:0x6c
	v_pk_mul_f32 v[86:87], v[16:17], s[44:45] op_sel:[1,0] op_sel_hi:[0,0] neg_hi:[1,0]
	ds_read_b64 v[62:63], v106 offset:1280
	v_lshlrev_b32_e32 v66, 3, v64
	ds_read_b64 v[94:95], v122 offset:3328
	v_lshlrev_b32_e32 v124, 3, v123
	v_pk_fma_f32 v[16:17], v[16:17], s[48:49], v[86:87] op_sel_hi:[1,0,1]
	s_waitcnt lgkmcnt(6)
	v_pk_add_f32 v[86:87], v[18:19], v[88:89]
	v_pk_add_f32 v[18:19], v[18:19], v[88:89] neg_lo:[0,1] neg_hi:[0,1]
	v_add_u32_e32 v107, v26, v66
	v_add_u32_e32 v123, v26, v124
	v_xor_b32_e32 v89, 0x80000000, v18
	v_mov_b32_e32 v88, v19
	s_waitcnt lgkmcnt(4)
	v_pk_add_f32 v[18:19], v[22:23], v[90:91]
	v_pk_add_f32 v[22:23], v[22:23], v[90:91] neg_lo:[0,1] neg_hi:[0,1]
	ds_read_b64 v[64:65], v107 offset:1536
	ds_read_b64 v[128:129], v123 offset:3584
	v_pk_mul_f32 v[90:91], v[22:23], s[48:49] op_sel_hi:[1,0]
	v_xor_b32_e32 v139, 0x80000000, v22
	v_mov_b32_e32 v138, v23
	v_add_u32_e32 v108, v126, v66
	v_bitop3_b32 v68, v21, 7, 15 bitop3:0x6c
	v_add_u32_e32 v124, v126, v124
	v_bitop3_b32 v21, v21, 15, v21 bitop3:0xc
	v_pk_fma_f32 v[22:23], v[138:139], s[44:45], v[90:91] op_sel_hi:[1,0,1] neg_lo:[0,0,1] neg_hi:[0,0,1]
	s_waitcnt lgkmcnt(4)
	v_pk_add_f32 v[90:91], v[24:25], v[92:93]
	v_pk_add_f32 v[24:25], v[24:25], v[92:93] neg_lo:[0,1] neg_hi:[0,1]
	ds_read_b64 v[66:67], v108 offset:1536
	v_lshlrev_b32_e32 v70, 3, v68
	ds_read_b64 v[130:131], v124 offset:3584
	v_lshlrev_b32_e32 v21, 3, v21
	v_pk_mul_f32 v[92:93], v[24:25], s[54:55] op_sel_hi:[1,0]
	v_xor_b32_e32 v139, 0x80000000, v24
	v_mov_b32_e32 v138, v25
	v_add_u32_e32 v109, v26, v70
	v_add_u32_e32 v125, v26, v21
	v_pk_fma_f32 v[24:25], v[138:139], s[52:53], v[92:93] op_sel_hi:[1,0,1] neg_lo:[0,0,1] neg_hi:[0,0,1]
	s_waitcnt lgkmcnt(4)
	v_pk_add_f32 v[92:93], v[62:63], v[94:95]
	v_pk_add_f32 v[62:63], v[62:63], v[94:95] neg_lo:[0,1] neg_hi:[0,1]
	ds_read_b64 v[68:69], v109 offset:1792
	v_add_u32_e32 v110, v126, v70
	ds_read_b64 v[132:133], v125 offset:3840
	v_add_u32_e32 v126, v126, v21
	v_pk_mul_f32 v[94:95], v[62:63], s[58:59] op_sel_hi:[1,0]
	v_xor_b32_e32 v139, 0x80000000, v62
	v_mov_b32_e32 v138, v63
	ds_read_b64 v[70:71], v110 offset:1792
	ds_read_b64 v[134:135], v126 offset:3840
	v_pk_fma_f32 v[62:63], v[138:139], s[56:57], v[94:95] op_sel_hi:[1,0,1] neg_lo:[0,0,1] neg_hi:[0,0,1]
	s_waitcnt lgkmcnt(6)
	v_pk_add_f32 v[94:95], v[64:65], v[128:129]
	v_pk_add_f32 v[64:65], v[64:65], v[128:129] neg_lo:[0,1] neg_hi:[0,1]
	v_lshl_add_u64 v[0:1], s[42:43], 2, v[28:29]
	v_pk_mul_f32 v[128:129], v[64:65], s[60:61] op_sel_hi:[1,0]
	v_xor_b32_e32 v139, 0x80000000, v64
	v_mov_b32_e32 v138, v65
	v_pk_fma_f32 v[64:65], v[138:139], s[60:61], v[128:129] op_sel_hi:[1,0,1] neg_lo:[0,0,1] neg_hi:[0,0,1]
	s_waitcnt lgkmcnt(4)
	v_pk_add_f32 v[128:129], v[66:67], v[130:131]
	v_pk_add_f32 v[66:67], v[66:67], v[130:131] neg_lo:[0,1] neg_hi:[0,1]
	v_cvt_f32_i32_e32 v20, v20
	v_pk_mul_f32 v[130:131], v[66:67], s[56:57] op_sel_hi:[1,0]
	v_xor_b32_e32 v139, 0x80000000, v66
	v_mov_b32_e32 v138, v67
	v_pk_fma_f32 v[66:67], v[138:139], s[58:59], v[130:131] op_sel_hi:[1,0,1] neg_lo:[0,0,1] neg_hi:[0,0,1]
	s_waitcnt lgkmcnt(2)
	v_pk_add_f32 v[130:131], v[68:69], v[132:133]
	v_pk_add_f32 v[68:69], v[68:69], v[132:133] neg_lo:[0,1] neg_hi:[0,1]
	v_mul_f32_e32 v21, 0x3b000000, v20
	v_pk_mul_f32 v[132:133], v[68:69], s[52:53] op_sel_hi:[1,0]
	v_xor_b32_e32 v139, 0x80000000, v68
	v_mov_b32_e32 v138, v69
	v_pk_fma_f32 v[68:69], v[138:139], s[54:55], v[132:133] op_sel_hi:[1,0,1] neg_lo:[0,0,1] neg_hi:[0,0,1]
	s_waitcnt lgkmcnt(0)
	v_pk_add_f32 v[132:133], v[70:71], v[134:135]
	v_pk_add_f32 v[70:71], v[70:71], v[134:135] neg_lo:[0,1] neg_hi:[0,1]
	v_cos_f32_e32 v20, v21
	v_pk_mul_f32 v[134:135], v[70:71], s[44:45] op_sel_hi:[1,0]
	v_xor_b32_e32 v139, 0x80000000, v70
	v_mov_b32_e32 v138, v71
	v_pk_fma_f32 v[70:71], v[138:139], s[48:49], v[134:135] op_sel_hi:[1,0,1] neg_lo:[0,0,1] neg_hi:[0,0,1]
	v_pk_add_f32 v[134:135], v[136:137], v[86:87]
	v_pk_add_f32 v[86:87], v[136:137], v[86:87] neg_lo:[0,1] neg_hi:[0,1]
	v_pk_add_f32 v[136:137], v[72:73], v[18:19]
	v_pk_add_f32 v[18:19], v[72:73], v[18:19] neg_lo:[0,1] neg_hi:[0,1]
	v_sin_f32_e32 v21, v21
	s_nop 0
	s_nop 0
	v_pk_mul_f32 v[72:73], v[18:19], s[54:55] op_sel:[1,0] op_sel_hi:[0,0] neg_hi:[1,0]
	v_add_f32_e32 v26, v20, v20
	v_pk_fma_f32 v[18:19], v[18:19], s[52:53], v[72:73] op_sel_hi:[1,0,1]
	v_pk_add_f32 v[72:73], v[74:75], v[90:91]
	v_pk_add_f32 v[74:75], v[74:75], v[90:91] neg_lo:[0,1] neg_hi:[0,1]
	v_mul_f32_e32 v26, v21, v26
	s_nop 0
	s_nop 0
	v_pk_mul_f32 v[90:91], v[74:75], s[60:61] op_sel:[1,0] op_sel_hi:[0,0] neg_hi:[1,0]
	s_lshl_b32 s42, s16, 9
	v_pk_fma_f32 v[74:75], v[74:75], s[60:61], v[90:91] op_sel_hi:[1,0,1]
	v_pk_add_f32 v[90:91], v[76:77], v[92:93]
	v_pk_add_f32 v[76:77], v[76:77], v[92:93] neg_lo:[0,1] neg_hi:[0,1]
	s_mov_b64 s[74:75], -1
	s_nop 0
	s_nop 0
	v_pk_mul_f32 v[92:93], v[76:77], s[52:53] op_sel:[1,0] op_sel_hi:[0,0] neg_hi:[1,0]
	s_nop 0
	v_pk_fma_f32 v[76:77], v[76:77], s[54:55], v[92:93] op_sel_hi:[1,0,1]
	v_pk_add_f32 v[92:93], v[78:79], v[94:95]
	v_pk_add_f32 v[78:79], v[78:79], v[94:95] neg_lo:[0,1] neg_hi:[0,1]
	s_nop 0
	v_xor_b32_e32 v95, 0x80000000, v78
	v_mov_b32_e32 v94, v79
	v_pk_add_f32 v[78:79], v[80:81], v[128:129]
	v_pk_add_f32 v[80:81], v[80:81], v[128:129] neg_lo:[0,1] neg_hi:[0,1]
	s_nop 0
	v_pk_mul_f32 v[128:129], v[80:81], s[54:55] op_sel_hi:[1,0]
	v_xor_b32_e32 v139, 0x80000000, v80
	v_mov_b32_e32 v138, v81
	v_pk_fma_f32 v[80:81], v[138:139], s[52:53], v[128:129] op_sel_hi:[1,0,1] neg_lo:[0,0,1] neg_hi:[0,0,1]
	v_pk_add_f32 v[128:129], v[82:83], v[130:131]
	v_pk_add_f32 v[82:83], v[82:83], v[130:131] neg_lo:[0,1] neg_hi:[0,1]
	s_nop 0
	v_pk_mul_f32 v[130:131], v[82:83], s[60:61] op_sel_hi:[1,0]
	v_xor_b32_e32 v139, 0x80000000, v82
	v_mov_b32_e32 v138, v83
	v_pk_fma_f32 v[82:83], v[138:139], s[60:61], v[130:131] op_sel_hi:[1,0,1] neg_lo:[0,0,1] neg_hi:[0,0,1]
	v_pk_add_f32 v[130:131], v[84:85], v[132:133]
	v_pk_add_f32 v[84:85], v[84:85], v[132:133] neg_lo:[0,1] neg_hi:[0,1]
	s_nop 0
	v_pk_mul_f32 v[132:133], v[84:85], s[52:53] op_sel_hi:[1,0]
	v_xor_b32_e32 v139, 0x80000000, v84
	v_mov_b32_e32 v138, v85
	v_pk_fma_f32 v[84:85], v[138:139], s[54:55], v[132:133] op_sel_hi:[1,0,1] neg_lo:[0,0,1] neg_hi:[0,0,1]
	v_pk_add_f32 v[132:133], v[2:3], v[88:89]
	v_pk_add_f32 v[2:3], v[2:3], v[88:89] neg_lo:[0,1] neg_hi:[0,1]
	v_pk_add_f32 v[88:89], v[4:5], v[22:23]
	v_pk_add_f32 v[4:5], v[4:5], v[22:23] neg_lo:[0,1] neg_hi:[0,1]
	s_nop 0
	v_pk_mul_f32 v[22:23], v[4:5], s[54:55] op_sel:[1,0] op_sel_hi:[0,0] neg_hi:[1,0]
	s_nop 0
	v_pk_fma_f32 v[4:5], v[4:5], s[52:53], v[22:23] op_sel_hi:[1,0,1]
	v_pk_add_f32 v[22:23], v[6:7], v[24:25]
	v_pk_add_f32 v[6:7], v[6:7], v[24:25] neg_lo:[0,1] neg_hi:[0,1]
	s_nop 0
	v_pk_mul_f32 v[24:25], v[6:7], s[60:61] op_sel:[1,0] op_sel_hi:[0,0] neg_hi:[1,0]
	s_nop 0
	v_pk_fma_f32 v[6:7], v[6:7], s[60:61], v[24:25] op_sel_hi:[1,0,1]
	v_pk_add_f32 v[24:25], v[8:9], v[62:63]
	v_pk_add_f32 v[8:9], v[8:9], v[62:63] neg_lo:[0,1] neg_hi:[0,1]
	s_nop 0
	v_pk_mul_f32 v[62:63], v[8:9], s[52:53] op_sel:[1,0] op_sel_hi:[0,0] neg_hi:[1,0]
	s_nop 0
	v_pk_fma_f32 v[8:9], v[8:9], s[54:55], v[62:63] op_sel_hi:[1,0,1]
	v_pk_add_f32 v[62:63], v[10:11], v[64:65]
	v_pk_add_f32 v[10:11], v[10:11], v[64:65] neg_lo:[0,1] neg_hi:[0,1]
	s_nop 0
	v_xor_b32_e32 v65, 0x80000000, v10
	v_mov_b32_e32 v64, v11
	v_pk_add_f32 v[10:11], v[12:13], v[66:67]
	v_pk_add_f32 v[12:13], v[12:13], v[66:67] neg_lo:[0,1] neg_hi:[0,1]
	s_nop 0
	v_pk_mul_f32 v[66:67], v[12:13], s[54:55] op_sel_hi:[1,0]
	v_xor_b32_e32 v139, 0x80000000, v12
	v_mov_b32_e32 v138, v13
	v_pk_fma_f32 v[12:13], v[138:139], s[52:53], v[66:67] op_sel_hi:[1,0,1] neg_lo:[0,0,1] neg_hi:[0,0,1]
	v_pk_add_f32 v[66:67], v[14:15], v[68:69]
	v_pk_add_f32 v[14:15], v[14:15], v[68:69] neg_lo:[0,1] neg_hi:[0,1]
	s_nop 0
	v_pk_mul_f32 v[68:69], v[14:15], s[60:61] op_sel_hi:[1,0]
	v_xor_b32_e32 v139, 0x80000000, v14
	v_mov_b32_e32 v138, v15
	v_pk_fma_f32 v[14:15], v[138:139], s[60:61], v[68:69] op_sel_hi:[1,0,1] neg_lo:[0,0,1] neg_hi:[0,0,1]
	v_pk_add_f32 v[68:69], v[16:17], v[70:71]
	v_pk_add_f32 v[16:17], v[16:17], v[70:71] neg_lo:[0,1] neg_hi:[0,1]
	s_nop 0
	v_pk_mul_f32 v[70:71], v[16:17], s[52:53] op_sel_hi:[1,0]
	v_xor_b32_e32 v139, 0x80000000, v16
	v_mov_b32_e32 v138, v17
	v_pk_fma_f32 v[16:17], v[138:139], s[54:55], v[70:71] op_sel_hi:[1,0,1] neg_lo:[0,0,1] neg_hi:[0,0,1]
	v_pk_add_f32 v[70:71], v[134:135], v[92:93]
	v_pk_add_f32 v[92:93], v[134:135], v[92:93] neg_lo:[0,1] neg_hi:[0,1]
	v_pk_add_f32 v[134:135], v[136:137], v[78:79]
	v_pk_add_f32 v[78:79], v[136:137], v[78:79] neg_lo:[0,1] neg_hi:[0,1]
	s_nop 0
	v_pk_mul_f32 v[136:137], v[78:79], s[60:61] op_sel:[1,0] op_sel_hi:[0,0] neg_hi:[1,0]
	s_nop 0
	v_pk_fma_f32 v[78:79], v[78:79], s[60:61], v[136:137] op_sel_hi:[1,0,1]
	v_pk_add_f32 v[136:137], v[72:73], v[128:129]
	v_pk_add_f32 v[72:73], v[72:73], v[128:129] neg_lo:[0,1] neg_hi:[0,1]
	s_nop 0
	v_xor_b32_e32 v129, 0x80000000, v72
	v_mov_b32_e32 v128, v73
	v_pk_add_f32 v[72:73], v[90:91], v[130:131]
	v_pk_add_f32 v[90:91], v[90:91], v[130:131] neg_lo:[0,1] neg_hi:[0,1]
	s_nop 0
	v_pk_mul_f32 v[130:131], v[90:91], s[60:61] op_sel_hi:[1,0]
	v_xor_b32_e32 v139, 0x80000000, v90
	v_mov_b32_e32 v138, v91
	v_pk_fma_f32 v[90:91], v[138:139], s[60:61], v[130:131] op_sel_hi:[1,0,1] neg_lo:[0,0,1] neg_hi:[0,0,1]
	v_pk_add_f32 v[130:131], v[86:87], v[94:95]
	v_pk_add_f32 v[86:87], v[86:87], v[94:95] neg_lo:[0,1] neg_hi:[0,1]
	v_pk_add_f32 v[94:95], v[18:19], v[80:81]
	v_pk_add_f32 v[18:19], v[18:19], v[80:81] neg_lo:[0,1] neg_hi:[0,1]
	s_nop 0
	v_pk_mul_f32 v[80:81], v[18:19], s[60:61] op_sel:[1,0] op_sel_hi:[0,0] neg_hi:[1,0]
	s_nop 0
	v_pk_fma_f32 v[18:19], v[18:19], s[60:61], v[80:81] op_sel_hi:[1,0,1]
	v_pk_add_f32 v[80:81], v[74:75], v[82:83]
	v_pk_add_f32 v[74:75], v[74:75], v[82:83] neg_lo:[0,1] neg_hi:[0,1]
	s_nop 0
	v_xor_b32_e32 v83, 0x80000000, v74
	v_mov_b32_e32 v82, v75
	v_pk_add_f32 v[74:75], v[76:77], v[84:85]
	v_pk_add_f32 v[76:77], v[76:77], v[84:85] neg_lo:[0,1] neg_hi:[0,1]
	s_nop 0
	v_pk_mul_f32 v[84:85], v[76:77], s[60:61] op_sel_hi:[1,0]
	v_xor_b32_e32 v139, 0x80000000, v76
	v_mov_b32_e32 v138, v77
	v_pk_fma_f32 v[76:77], v[138:139], s[60:61], v[84:85] op_sel_hi:[1,0,1] neg_lo:[0,0,1] neg_hi:[0,0,1]
	v_pk_add_f32 v[84:85], v[132:133], v[62:63]
	v_pk_add_f32 v[62:63], v[132:133], v[62:63] neg_lo:[0,1] neg_hi:[0,1]
	v_pk_add_f32 v[132:133], v[88:89], v[10:11]
	v_pk_add_f32 v[10:11], v[88:89], v[10:11] neg_lo:[0,1] neg_hi:[0,1]
	s_nop 0
	v_pk_mul_f32 v[88:89], v[10:11], s[60:61] op_sel:[1,0] op_sel_hi:[0,0] neg_hi:[1,0]
	s_nop 0
	v_pk_fma_f32 v[10:11], v[10:11], s[60:61], v[88:89] op_sel_hi:[1,0,1]
	v_pk_add_f32 v[88:89], v[22:23], v[66:67]
	v_pk_add_f32 v[22:23], v[22:23], v[66:67] neg_lo:[0,1] neg_hi:[0,1]
	s_nop 0
	v_xor_b32_e32 v67, 0x80000000, v22
	v_mov_b32_e32 v66, v23
	v_pk_add_f32 v[22:23], v[24:25], v[68:69]
	v_pk_add_f32 v[24:25], v[24:25], v[68:69] neg_lo:[0,1] neg_hi:[0,1]
	s_nop 0
	v_pk_mul_f32 v[68:69], v[24:25], s[60:61] op_sel_hi:[1,0]
	v_xor_b32_e32 v139, 0x80000000, v24
	v_mov_b32_e32 v138, v25
	v_pk_fma_f32 v[24:25], v[138:139], s[60:61], v[68:69] op_sel_hi:[1,0,1] neg_lo:[0,0,1] neg_hi:[0,0,1]
	v_pk_add_f32 v[68:69], v[2:3], v[64:65]
	v_pk_add_f32 v[2:3], v[2:3], v[64:65] neg_lo:[0,1] neg_hi:[0,1]
	v_pk_add_f32 v[64:65], v[4:5], v[12:13]
	v_pk_add_f32 v[4:5], v[4:5], v[12:13] neg_lo:[0,1] neg_hi:[0,1]
	s_nop 0
	v_pk_mul_f32 v[12:13], v[4:5], s[60:61] op_sel:[1,0] op_sel_hi:[0,0] neg_hi:[1,0]
	s_nop 0
	v_pk_fma_f32 v[4:5], v[4:5], s[60:61], v[12:13] op_sel_hi:[1,0,1]
	v_pk_add_f32 v[12:13], v[6:7], v[14:15]
	v_pk_add_f32 v[6:7], v[6:7], v[14:15] neg_lo:[0,1] neg_hi:[0,1]
	v_pk_add_f32 v[140:141], v[68:69], v[12:13]
	v_xor_b32_e32 v15, 0x80000000, v6
	v_mov_b32_e32 v14, v7
	v_pk_add_f32 v[6:7], v[8:9], v[16:17]
	v_pk_add_f32 v[8:9], v[8:9], v[16:17] neg_lo:[0,1] neg_hi:[0,1]
	v_pk_add_f32 v[142:143], v[64:65], v[6:7]
	v_pk_mul_f32 v[16:17], v[8:9], s[60:61] op_sel_hi:[1,0]
	s_nop 0
	v_pk_fma_f32 v[8:9], v[8:9], s[60:61], v[16:17] op_sel:[1,0,0] op_sel_hi:[0,0,1] neg_lo:[0,0,1] neg_hi:[1,0,1]
	v_pk_add_f32 v[16:17], v[70:71], v[136:137]
	v_pk_add_f32 v[70:71], v[70:71], v[136:137] neg_lo:[0,1] neg_hi:[0,1]
	v_pk_add_f32 v[136:137], v[134:135], v[72:73]
	v_pk_add_f32 v[72:73], v[134:135], v[72:73] neg_lo:[0,1] neg_hi:[0,1]
	v_pk_add_f32 v[138:139], v[84:85], v[88:89] neg_lo:[0,1] neg_hi:[0,1]
	v_xor_b32_e32 v135, 0x80000000, v72
	v_mov_b32_e32 v134, v73
	v_pk_add_f32 v[72:73], v[92:93], v[128:129]
	v_pk_add_f32 v[92:93], v[92:93], v[128:129] neg_lo:[0,1] neg_hi:[0,1]
	v_pk_add_f32 v[128:129], v[78:79], v[90:91]
	v_pk_add_f32 v[78:79], v[78:79], v[90:91] neg_lo:[0,1] neg_hi:[0,1]
	v_pk_add_f32 v[6:7], v[64:65], v[6:7] neg_lo:[0,1] neg_hi:[0,1]
	v_xor_b32_e32 v91, 0x80000000, v78
	v_mov_b32_e32 v90, v79
	v_pk_add_f32 v[78:79], v[130:131], v[80:81]
	v_pk_add_f32 v[130:131], v[130:131], v[80:81] neg_lo:[0,1] neg_hi:[0,1]
	v_pk_add_f32 v[80:81], v[94:95], v[74:75]
	v_pk_add_f32 v[74:75], v[94:95], v[74:75] neg_lo:[0,1] neg_hi:[0,1]
	v_xor_b32_e32 v149, 0x80000000, v6
	v_xor_b32_e32 v95, 0x80000000, v74
	v_mov_b32_e32 v94, v75
	v_pk_add_f32 v[74:75], v[86:87], v[82:83]
	v_pk_add_f32 v[82:83], v[86:87], v[82:83] neg_lo:[0,1] neg_hi:[0,1]
	v_pk_add_f32 v[86:87], v[18:19], v[76:77]
	v_pk_add_f32 v[18:19], v[18:19], v[76:77] neg_lo:[0,1] neg_hi:[0,1]
	v_mov_b32_e32 v148, v7
	v_xor_b32_e32 v77, 0x80000000, v18
	v_mov_b32_e32 v76, v19
	v_pk_add_f32 v[18:19], v[84:85], v[88:89]
	v_pk_add_f32 v[88:89], v[132:133], v[22:23]
	v_pk_add_f32 v[22:23], v[132:133], v[22:23] neg_lo:[0,1] neg_hi:[0,1]
	v_pk_add_f32 v[6:7], v[2:3], v[14:15]
	v_xor_b32_e32 v133, 0x80000000, v22
	v_mov_b32_e32 v132, v23
	v_pk_add_f32 v[22:23], v[62:63], v[66:67]
	v_pk_add_f32 v[62:63], v[62:63], v[66:67] neg_lo:[0,1] neg_hi:[0,1]
	v_pk_add_f32 v[66:67], v[10:11], v[24:25]
	v_pk_add_f32 v[10:11], v[10:11], v[24:25] neg_lo:[0,1] neg_hi:[0,1]
	v_pk_add_f32 v[154:155], v[2:3], v[14:15] neg_lo:[0,1] neg_hi:[0,1]
	v_pk_add_f32 v[2:3], v[4:5], v[8:9] neg_lo:[0,1] neg_hi:[0,1]
	v_pk_add_f32 v[68:69], v[68:69], v[12:13] neg_lo:[0,1] neg_hi:[0,1]
	v_pk_add_f32 v[156:157], v[4:5], v[8:9]
	v_xor_b32_e32 v159, 0x80000000, v2
	v_mov_b32_e32 v158, v3
	v_pk_add_f32 v[2:3], v[16:17], v[136:137]
	v_pk_add_f32 v[84:85], v[16:17], v[136:137] neg_lo:[0,1] neg_hi:[0,1]
	v_pk_add_f32 v[136:137], v[70:71], v[134:135]
	v_pk_add_f32 v[16:17], v[70:71], v[134:135] neg_lo:[0,1] neg_hi:[0,1]
	v_pk_add_f32 v[134:135], v[72:73], v[128:129]
	v_pk_add_f32 v[70:71], v[72:73], v[128:129] neg_lo:[0,1] neg_hi:[0,1]
	v_pk_add_f32 v[128:129], v[92:93], v[90:91]
	v_pk_add_f32 v[8:9], v[92:93], v[90:91] neg_lo:[0,1] neg_hi:[0,1]
	v_pk_add_f32 v[72:73], v[78:79], v[80:81]
	v_pk_add_f32 v[80:81], v[78:79], v[80:81] neg_lo:[0,1] neg_hi:[0,1]
	v_pk_add_f32 v[92:93], v[130:131], v[94:95]
	v_pk_add_f32 v[12:13], v[130:131], v[94:95] neg_lo:[0,1] neg_hi:[0,1]
	v_pk_add_f32 v[78:79], v[74:75], v[86:87]
	v_pk_add_f32 v[64:65], v[74:75], v[86:87] neg_lo:[0,1] neg_hi:[0,1]
	v_pk_add_f32 v[130:131], v[82:83], v[76:77]
	v_pk_add_f32 v[4:5], v[82:83], v[76:77] neg_lo:[0,1] neg_hi:[0,1]
	v_pk_add_f32 v[76:77], v[18:19], v[88:89]
	v_pk_add_f32 v[88:89], v[18:19], v[88:89] neg_lo:[0,1] neg_hi:[0,1]
	v_pk_add_f32 v[86:87], v[138:139], v[132:133]
	v_pk_add_f32 v[18:19], v[138:139], v[132:133] neg_lo:[0,1] neg_hi:[0,1]
	v_pk_add_f32 v[132:133], v[62:63], v[10:11] op_sel:[0,1] op_sel_hi:[1,0] neg_hi:[0,1]
	v_pk_add_f32 v[10:11], v[62:63], v[10:11] op_sel:[0,1] op_sel_hi:[1,0] neg_lo:[0,1]
	v_pk_mul_f32 v[24:25], v[20:21], v[20:21]
	s_nop 0
	v_pk_add_f32 v[24:25], v[24:25], v[24:25] op_sel:[0,1] op_sel_hi:[0,1] neg_lo:[0,1] neg_hi:[0,1]
	v_pk_mul_f32 v[62:63], v[20:21], v[26:27] op_sel:[1,0] op_sel_hi:[0,0] neg_lo:[1,0]
	v_pk_add_f32 v[90:91], v[22:23], v[66:67]
	v_pk_add_f32 v[74:75], v[22:23], v[66:67] neg_lo:[0,1] neg_hi:[0,1]
	v_pk_add_f32 v[22:23], v[140:141], v[142:143]
	v_pk_add_f32 v[82:83], v[140:141], v[142:143] neg_lo:[0,1] neg_hi:[0,1]
	v_pk_add_f32 v[138:139], v[68:69], v[148:149]
	v_pk_add_f32 v[14:15], v[68:69], v[148:149] neg_lo:[0,1] neg_hi:[0,1]
	v_pk_fma_f32 v[68:69], v[20:21], v[24:25], v[62:63]
	v_mov_b32_e32 v142, v21
	s_nop 0
	v_pk_mul_f32 v[62:63], v[142:143], v[76:77] op_sel:[0,1] op_sel_hi:[0,0] neg_hi:[0,1]
	v_pk_fma_f32 v[20:21], v[20:21], v[76:77], v[62:63] op_sel_hi:[0,1,1]
	v_pk_mul_f32 v[62:63], v[26:27], s[46:47] op_sel_hi:[0,1]
	v_pk_fma_f32 v[76:77], v[24:25], s[40:41], v[62:63]
	s_nop 0
	v_pk_mul_f32 v[62:63], v[76:77], v[72:73] op_sel:[1,1] op_sel_hi:[1,0] neg_hi:[0,1]
	v_pk_add_f32 v[94:95], v[6:7], v[156:157]
	v_pk_fma_f32 v[62:63], v[72:73], v[76:77], v[62:63] op_sel_hi:[1,0,1]
	v_pk_mul_f32 v[72:73], v[26:27], v[68:69] op_sel:[0,1] op_sel_hi:[0,0] neg_lo:[0,1]
	v_pk_fma_f32 v[142:143], v[24:25], v[68:69], v[72:73]
	v_pk_mul_f32 v[72:73], v[68:69], v[22:23] op_sel:[1,1] op_sel_hi:[1,0] neg_hi:[0,1]
	v_pk_add_f32 v[140:141], v[154:155], v[158:159]
	v_pk_fma_f32 v[22:23], v[68:69], v[22:23], v[72:73] op_sel_hi:[0,1,1]
	v_pk_mul_f32 v[68:69], v[26:27], v[76:77] op_sel:[0,1] op_sel_hi:[0,0] neg_lo:[0,1]
	v_pk_fma_f32 v[76:77], v[24:25], v[76:77], v[68:69]
	s_nop 0
	v_pk_mul_f32 v[68:69], v[134:135], v[76:77] op_sel:[1,1] op_sel_hi:[0,1] neg_hi:[1,0]
	v_pk_add_f32 v[66:67], v[6:7], v[156:157] neg_lo:[0,1] neg_hi:[0,1]
	v_pk_fma_f32 v[72:73], v[134:135], v[76:77], v[68:69] op_sel_hi:[1,0,1]
	v_pk_mul_f32 v[68:69], v[26:27], v[142:143] op_sel:[0,1] op_sel_hi:[0,0] neg_lo:[0,1]
	v_pk_fma_f32 v[134:135], v[24:25], v[142:143], v[68:69]
	v_pk_mul_f32 v[68:69], v[142:143], v[90:91] op_sel:[1,1] op_sel_hi:[1,0] neg_hi:[0,1]
	v_pk_add_f32 v[6:7], v[154:155], v[158:159] neg_lo:[0,1] neg_hi:[0,1]
	v_pk_fma_f32 v[68:69], v[90:91], v[142:143], v[68:69] op_sel_hi:[1,0,1]
	v_pk_mul_f32 v[90:91], v[26:27], v[76:77] op_sel:[0,1] op_sel_hi:[0,0] neg_lo:[0,1]
	v_pk_fma_f32 v[90:91], v[24:25], v[76:77], v[90:91]
	s_nop 0
	v_pk_mul_f32 v[76:77], v[78:79], v[90:91] op_sel:[1,1] op_sel_hi:[0,1] neg_hi:[1,0]
	s_nop 0
	v_pk_fma_f32 v[78:79], v[78:79], v[90:91], v[76:77] op_sel_hi:[1,0,1]
	v_pk_mul_f32 v[76:77], v[26:27], v[134:135] op_sel:[0,1] op_sel_hi:[0,0] neg_lo:[0,1]
	v_pk_fma_f32 v[142:143], v[24:25], v[134:135], v[76:77]
	v_pk_mul_f32 v[76:77], v[134:135], v[94:95] op_sel:[1,1] op_sel_hi:[1,0] neg_hi:[0,1]
	s_nop 0
	v_pk_fma_f32 v[76:77], v[94:95], v[134:135], v[76:77] op_sel_hi:[1,0,1]
	v_pk_mul_f32 v[94:95], v[26:27], v[90:91] op_sel:[0,1] op_sel_hi:[0,0] neg_lo:[0,1]
	v_pk_fma_f32 v[94:95], v[24:25], v[90:91], v[94:95]
	s_nop 0
	v_pk_mul_f32 v[90:91], v[136:137], v[94:95] op_sel:[1,1] op_sel_hi:[0,1] neg_hi:[1,0]
	v_xor_b32_e32 v134, 0x80000000, v143
	v_pk_fma_f32 v[90:91], v[136:137], v[94:95], v[90:91] op_sel_hi:[1,0,1]
	v_pk_mul_f32 v[136:137], v[86:87], v[142:143] op_sel:[1,1] op_sel_hi:[0,1] neg_hi:[1,0]
	v_mov_b32_e32 v135, v142
	v_pk_fma_f32 v[86:87], v[86:87], v[142:143], v[136:137] op_sel_hi:[1,0,1]
	v_pk_mul_f32 v[136:137], v[26:27], v[94:95] op_sel:[0,1] op_sel_hi:[0,0] neg_lo:[0,1]
	v_pk_mul_f32 v[134:135], v[26:27], v[134:135] op_sel_hi:[0,1]
	v_pk_fma_f32 v[136:137], v[24:25], v[94:95], v[136:137]
	v_pk_fma_f32 v[134:135], v[24:25], v[142:143], v[134:135]
	v_pk_mul_f32 v[94:95], v[92:93], v[136:137] op_sel:[1,1] op_sel_hi:[0,1] neg_hi:[1,0]
	s_nop 0
	v_pk_fma_f32 v[94:95], v[92:93], v[136:137], v[94:95] op_sel_hi:[1,0,1]
	v_pk_mul_f32 v[92:93], v[26:27], v[134:135] op_sel:[0,1] op_sel_hi:[0,0] neg_lo:[0,1]
	v_pk_fma_f32 v[142:143], v[24:25], v[134:135], v[92:93]
	v_pk_mul_f32 v[92:93], v[138:139], v[134:135] op_sel:[1,1] op_sel_hi:[0,1] neg_hi:[1,0]
	s_nop 0
	v_pk_fma_f32 v[92:93], v[138:139], v[134:135], v[92:93] op_sel_hi:[1,0,1]
	v_pk_mul_f32 v[134:135], v[26:27], v[136:137] op_sel:[0,1] op_sel_hi:[0,0] neg_lo:[0,1]
	s_nop 0
	v_pk_fma_f32 v[134:135], v[24:25], v[136:137], v[134:135]
	v_pk_mul_f32 v[138:139], v[132:133], v[142:143] op_sel:[1,1] op_sel_hi:[0,1] neg_hi:[1,0]
	v_pk_mul_f32 v[136:137], v[128:129], v[134:135] op_sel:[1,1] op_sel_hi:[0,1] neg_hi:[1,0]
	v_pk_fma_f32 v[132:133], v[132:133], v[142:143], v[138:139] op_sel_hi:[1,0,1]
	v_pk_fma_f32 v[128:129], v[128:129], v[134:135], v[136:137] op_sel_hi:[1,0,1]
	v_pk_mul_f32 v[138:139], v[26:27], v[134:135] op_sel:[0,1] op_sel_hi:[0,0] neg_lo:[0,1]
	v_pk_mul_f32 v[136:137], v[26:27], v[142:143] op_sel:[0,1] op_sel_hi:[0,0] neg_lo:[0,1]
	v_pk_fma_f32 v[134:135], v[24:25], v[134:135], v[138:139]
	v_pk_fma_f32 v[136:137], v[24:25], v[142:143], v[136:137]
	v_pk_mul_f32 v[138:139], v[130:131], v[134:135] op_sel:[1,1] op_sel_hi:[0,1] neg_hi:[1,0]
	s_nop 0
	v_pk_fma_f32 v[130:131], v[130:131], v[134:135], v[138:139] op_sel_hi:[1,0,1]
	v_pk_mul_f32 v[138:139], v[26:27], v[136:137] op_sel:[0,1] op_sel_hi:[0,0] neg_lo:[0,1]
	v_pk_mul_f32 v[142:143], v[140:141], v[136:137] op_sel:[1,1] op_sel_hi:[0,1] neg_hi:[1,0]
	v_pk_fma_f32 v[138:139], v[24:25], v[136:137], v[138:139]
	v_pk_fma_f32 v[136:137], v[140:141], v[136:137], v[142:143] op_sel_hi:[1,0,1]
	v_pk_mul_f32 v[140:141], v[26:27], v[134:135] op_sel:[0,1] op_sel_hi:[0,0] neg_lo:[0,1]
	v_pk_fma_f32 v[134:135], v[24:25], v[134:135], v[140:141]
	s_nop 0
	v_pk_mul_f32 v[140:141], v[84:85], v[134:135] op_sel:[1,1] op_sel_hi:[0,1] neg_hi:[1,0]
	s_nop 0
	v_pk_fma_f32 v[84:85], v[84:85], v[134:135], v[140:141] op_sel_hi:[1,0,1]
	v_pk_mul_f32 v[140:141], v[26:27], v[138:139] op_sel:[0,1] op_sel_hi:[0,0] neg_lo:[0,1]
	v_pk_mul_f32 v[142:143], v[88:89], v[138:139] op_sel:[1,1] op_sel_hi:[0,1] neg_hi:[1,0]
	v_pk_fma_f32 v[140:141], v[24:25], v[138:139], v[140:141]
	v_pk_fma_f32 v[88:89], v[88:89], v[138:139], v[142:143] op_sel_hi:[1,0,1]
	v_pk_mul_f32 v[138:139], v[26:27], v[134:135] op_sel:[0,1] op_sel_hi:[0,0] neg_lo:[0,1]
	v_pk_fma_f32 v[134:135], v[24:25], v[134:135], v[138:139]
	s_nop 0
	v_pk_mul_f32 v[138:139], v[80:81], v[134:135] op_sel:[1,1] op_sel_hi:[0,1] neg_hi:[1,0]
	s_nop 0
	v_pk_fma_f32 v[80:81], v[80:81], v[134:135], v[138:139] op_sel_hi:[1,0,1]
	v_pk_mul_f32 v[138:139], v[26:27], v[140:141] op_sel:[0,1] op_sel_hi:[0,0] neg_lo:[0,1]
	v_pk_mul_f32 v[142:143], v[82:83], v[140:141] op_sel:[1,1] op_sel_hi:[0,1] neg_hi:[1,0]
	v_pk_fma_f32 v[138:139], v[24:25], v[140:141], v[138:139]
	v_pk_fma_f32 v[82:83], v[82:83], v[140:141], v[142:143] op_sel_hi:[1,0,1]
	v_pk_mul_f32 v[140:141], v[26:27], v[134:135] op_sel:[0,1] op_sel_hi:[0,0] neg_lo:[0,1]
	v_pk_fma_f32 v[134:135], v[24:25], v[134:135], v[140:141]
	s_nop 0
	v_pk_mul_f32 v[140:141], v[70:71], v[134:135] op_sel:[1,1] op_sel_hi:[0,1] neg_hi:[1,0]
	s_nop 0
	v_pk_fma_f32 v[70:71], v[70:71], v[134:135], v[140:141] op_sel_hi:[1,0,1]
	v_pk_mul_f32 v[140:141], v[26:27], v[138:139] op_sel:[0,1] op_sel_hi:[0,0] neg_lo:[0,1]
	v_pk_mul_f32 v[142:143], v[74:75], v[138:139] op_sel:[1,1] op_sel_hi:[0,1] neg_hi:[1,0]
	v_pk_fma_f32 v[140:141], v[24:25], v[138:139], v[140:141]
	v_pk_fma_f32 v[74:75], v[74:75], v[138:139], v[142:143] op_sel_hi:[1,0,1]
	v_pk_mul_f32 v[138:139], v[26:27], v[134:135] op_sel:[0,1] op_sel_hi:[0,0] neg_lo:[0,1]
	v_pk_fma_f32 v[134:135], v[24:25], v[134:135], v[138:139]
	s_nop 0
	v_pk_mul_f32 v[138:139], v[64:65], v[134:135] op_sel:[1,1] op_sel_hi:[0,1] neg_hi:[1,0]
	s_nop 0
	v_pk_fma_f32 v[64:65], v[64:65], v[134:135], v[138:139] op_sel_hi:[1,0,1]
	v_pk_mul_f32 v[138:139], v[26:27], v[140:141] op_sel:[0,1] op_sel_hi:[0,0] neg_lo:[0,1]
	v_pk_mul_f32 v[142:143], v[66:67], v[140:141] op_sel:[1,1] op_sel_hi:[0,1] neg_hi:[1,0]
	v_pk_fma_f32 v[138:139], v[24:25], v[140:141], v[138:139]
	v_pk_fma_f32 v[66:67], v[66:67], v[140:141], v[142:143] op_sel_hi:[1,0,1]
	v_pk_mul_f32 v[140:141], v[26:27], v[134:135] op_sel:[0,1] op_sel_hi:[0,0] neg_lo:[0,1]
	v_pk_fma_f32 v[134:135], v[24:25], v[134:135], v[140:141]
	s_nop 0
	v_pk_mul_f32 v[140:141], v[16:17], v[134:135] op_sel:[1,1] op_sel_hi:[0,1] neg_hi:[1,0]
	s_nop 0
	v_pk_fma_f32 v[16:17], v[16:17], v[134:135], v[140:141] op_sel_hi:[1,0,1]
	v_pk_mul_f32 v[140:141], v[26:27], v[138:139] op_sel:[0,1] op_sel_hi:[0,0] neg_lo:[0,1]
	v_pk_mul_f32 v[142:143], v[18:19], v[138:139] op_sel:[1,1] op_sel_hi:[0,1] neg_hi:[1,0]
	v_pk_fma_f32 v[140:141], v[24:25], v[138:139], v[140:141]
	v_pk_fma_f32 v[18:19], v[18:19], v[138:139], v[142:143] op_sel_hi:[1,0,1]
	v_pk_mul_f32 v[138:139], v[26:27], v[134:135] op_sel:[0,1] op_sel_hi:[0,0] neg_lo:[0,1]
	v_pk_fma_f32 v[134:135], v[24:25], v[134:135], v[138:139]
	s_nop 0
	v_pk_mul_f32 v[138:139], v[12:13], v[134:135] op_sel:[1,1] op_sel_hi:[0,1] neg_hi:[1,0]
	s_nop 0
	v_pk_fma_f32 v[12:13], v[12:13], v[134:135], v[138:139] op_sel_hi:[1,0,1]
	v_pk_mul_f32 v[138:139], v[26:27], v[140:141] op_sel:[0,1] op_sel_hi:[0,0] neg_lo:[0,1]
	v_pk_mul_f32 v[142:143], v[14:15], v[140:141] op_sel:[1,1] op_sel_hi:[0,1] neg_hi:[1,0]
	v_pk_fma_f32 v[138:139], v[24:25], v[140:141], v[138:139]
	v_pk_fma_f32 v[14:15], v[14:15], v[140:141], v[142:143] op_sel_hi:[1,0,1]
	v_pk_mul_f32 v[140:141], v[26:27], v[134:135] op_sel:[0,1] op_sel_hi:[0,0] neg_lo:[0,1]
	v_pk_fma_f32 v[134:135], v[24:25], v[134:135], v[140:141]
	s_nop 0
	v_pk_mul_f32 v[140:141], v[8:9], v[134:135] op_sel:[1,1] op_sel_hi:[0,1] neg_hi:[1,0]
	s_nop 0
	v_pk_fma_f32 v[8:9], v[8:9], v[134:135], v[140:141] op_sel_hi:[1,0,1]
	v_pk_mul_f32 v[140:141], v[26:27], v[138:139] op_sel:[0,1] op_sel_hi:[0,0] neg_lo:[0,1]
	v_pk_mul_f32 v[142:143], v[10:11], v[138:139] op_sel:[1,1] op_sel_hi:[0,1] neg_hi:[1,0]
	v_pk_fma_f32 v[140:141], v[24:25], v[138:139], v[140:141]
	v_pk_fma_f32 v[10:11], v[10:11], v[138:139], v[142:143] op_sel_hi:[1,0,1]
	v_pk_mul_f32 v[138:139], v[26:27], v[134:135] op_sel:[0,1] op_sel_hi:[0,0] neg_lo:[0,1]
	v_pk_fma_f32 v[24:25], v[24:25], v[134:135], v[138:139]
	s_nop 0
	v_pk_mul_f32 v[134:135], v[4:5], v[24:25] op_sel:[1,1] op_sel_hi:[0,1] neg_hi:[1,0]
	s_nop 0
	v_pk_fma_f32 v[4:5], v[4:5], v[24:25], v[134:135] op_sel_hi:[1,0,1]
	v_pk_mul_f32 v[24:25], v[6:7], v[140:141] op_sel:[1,1] op_sel_hi:[0,1] neg_hi:[1,0]
	s_nop 0
	v_pk_fma_f32 v[6:7], v[6:7], v[140:141], v[24:25] op_sel_hi:[1,0,1]
	ds_write_b64 v27, v[2:3]
	ds_write_b64 v96, v[84:85]
	ds_write_b64 v97, v[90:91] offset:256
	ds_write_b64 v98, v[16:17] offset:256
	ds_write_b64 v99, v[72:73] offset:512
	ds_write_b64 v100, v[70:71] offset:512
	ds_write_b64 v101, v[128:129] offset:768
	ds_write_b64 v102, v[8:9] offset:768
	ds_write_b64 v103, v[62:63] offset:1024
	ds_write_b64 v104, v[80:81] offset:1024
	ds_write_b64 v105, v[94:95] offset:1280
	ds_write_b64 v106, v[12:13] offset:1280
	ds_write_b64 v107, v[78:79] offset:1536
	ds_write_b64 v108, v[64:65] offset:1536
	ds_write_b64 v109, v[130:131] offset:1792
	ds_write_b64 v110, v[4:5] offset:1792
	ds_write_b64 v111, v[20:21] offset:2048
	ds_write_b64 v112, v[88:89] offset:2048
	ds_write_b64 v113, v[86:87] offset:2304
	ds_write_b64 v114, v[18:19] offset:2304
	ds_write_b64 v115, v[68:69] offset:2560
	ds_write_b64 v116, v[74:75] offset:2560
	ds_write_b64 v117, v[132:133] offset:2816
	ds_write_b64 v118, v[10:11] offset:2816
	ds_write_b64 v119, v[22:23] offset:3072
	ds_write_b64 v120, v[82:83] offset:3072
	ds_write_b64 v121, v[92:93] offset:3328
	ds_write_b64 v122, v[14:15] offset:3328
	ds_write_b64 v123, v[76:77] offset:3584
	ds_write_b64 v124, v[66:67] offset:3584
	ds_write_b64 v125, v[136:137] offset:3840
	ds_write_b64 v126, v[6:7] offset:3840
	v_mov_b32_e32 v2, v146
	s_waitcnt lgkmcnt(0)
	s_barrier
	s_nop 0
	v_lshlrev_b32_e32 v3, 4, v2
	v_lshrrev_b32_e32 v4, 1, v2
	v_bfe_u32 v2, v2, 1, 4
	v_bitop3_b32 v5, v4, v3, 16 bitop3:0x6c
	v_lshl_add_u32 v5, v5, 3, 16
	v_lshlrev_b32_e32 v2, 3, v2
	v_add_u32_e32 v6, v5, v2
	ds_read_b64 v[12:13], v6
	v_bitop3_b32 v6, v4, 1, 15 bitop3:0x6c
	v_lshlrev_b32_e32 v8, 3, v6
	v_add_u32_e32 v6, v5, v8
	ds_read_b64 v[14:15], v6
	v_bitop3_b32 v6, v4, 2, 15 bitop3:0x6c
	v_lshlrev_b32_e32 v9, 3, v6
	v_add_u32_e32 v6, v5, v9
	ds_read_b64 v[16:17], v6
	v_bitop3_b32 v6, v4, 3, 15 bitop3:0x6c
	v_lshlrev_b32_e32 v10, 3, v6
	v_add_u32_e32 v6, v5, v10
	ds_read_b64 v[18:19], v6
	v_bitop3_b32 v6, v4, 4, 15 bitop3:0x6c
	v_lshlrev_b32_e32 v11, 3, v6
	v_add_u32_e32 v6, v5, v11
	ds_read_b64 v[20:21], v6
	v_bitop3_b32 v6, v4, 5, 15 bitop3:0x6c
	v_lshlrev_b32_e32 v82, 3, v6
	v_add_u32_e32 v6, v5, v82
	ds_read_b64 v[22:23], v6
	v_bitop3_b32 v6, v4, 6, 15 bitop3:0x6c
	v_lshlrev_b32_e32 v83, 3, v6
	v_add_u32_e32 v6, v5, v83
	ds_read_b64 v[24:25], v6
	v_bitop3_b32 v6, v4, 7, 15 bitop3:0x6c
	v_lshlrev_b32_e32 v84, 3, v6
	v_add_u32_e32 v6, v5, v84
	ds_read_b64 v[26:27], v6
	v_bitop3_b32 v6, v4, 8, 15 bitop3:0x6c
	v_lshlrev_b32_e32 v85, 3, v6
	v_add_u32_e32 v6, v5, v85
	ds_read_b64 v[62:63], v6
	v_bitop3_b32 v6, v4, 9, 15 bitop3:0x6c
	v_lshlrev_b32_e32 v86, 3, v6
	v_add_u32_e32 v6, v5, v86
	ds_read_b64 v[64:65], v6
	v_bitop3_b32 v6, v4, 10, 15 bitop3:0x6c
	v_lshlrev_b32_e32 v87, 3, v6
	v_add_u32_e32 v6, v5, v87
	ds_read_b64 v[66:67], v6
	v_bitop3_b32 v6, v4, 11, 15 bitop3:0x6c
	v_lshlrev_b32_e32 v88, 3, v6
	v_add_u32_e32 v6, v5, v88
	ds_read_b64 v[68:69], v6
	v_bitop3_b32 v6, v4, 12, 15 bitop3:0x6c
	v_lshlrev_b32_e32 v89, 3, v6
	v_add_u32_e32 v6, v5, v89
	ds_read_b64 v[70:71], v6
	v_bitop3_b32 v6, v4, 13, 15 bitop3:0x6c
	v_lshlrev_b32_e32 v90, 3, v6
	v_add_u32_e32 v6, v5, v90
	ds_read_b64 v[72:73], v6
	v_bitop3_b32 v6, v4, 14, 15 bitop3:0x6c
	v_lshlrev_b32_e32 v91, 3, v6
	v_add_u32_e32 v6, v5, v91
	v_add_u32_e32 v3, 0x2000, v3
	ds_read_b64 v[74:75], v6
	v_bitop3_b32 v6, v4, 15, v4 bitop3:0xc
	v_bitop3_b32 v3, v3, v4, 16 bitop3:0x78
	v_lshlrev_b32_e32 v106, 3, v6
	v_lshl_add_u32 v107, v3, 3, 16
	v_add_u32_e32 v5, v5, v106
	v_add_u32_e32 v2, v107, v2
	ds_read_b64 v[76:77], v5
	ds_read_b64 v[6:7], v2
	v_add_u32_e32 v2, v107, v8
	ds_read_b64 v[78:79], v2
	v_add_u32_e32 v2, v107, v9
	ds_read_b64 v[8:9], v2
	v_add_u32_e32 v2, v107, v10
	ds_read_b64 v[80:81], v2
	v_add_u32_e32 v2, v107, v11
	ds_read_b64 v[10:11], v2
	v_add_u32_e32 v2, v107, v82
	v_add_u32_e32 v82, v107, v84
	v_add_u32_e32 v84, v107, v85
	ds_read_b64 v[4:5], v2
	ds_read_b64 v[92:93], v84
	v_add_u32_e32 v2, v107, v83
	v_add_u32_e32 v84, v107, v86
	ds_read_b64 v[2:3], v2
	ds_read_b64 v[82:83], v82
	ds_read_b64 v[94:95], v84
	v_add_u32_e32 v84, v107, v87
	ds_read_b64 v[96:97], v84
	v_add_u32_e32 v84, v107, v88
	ds_read_b64 v[98:99], v84
	v_add_u32_e32 v84, v107, v89
	ds_read_b64 v[100:101], v84
	v_add_u32_e32 v84, v107, v90
	ds_read_b64 v[102:103], v84
	v_add_u32_e32 v84, v107, v91
	ds_read_b64 v[104:105], v84
	v_add_u32_e32 v84, v107, v106
	ds_read_b64 v[106:107], v84
	s_waitcnt lgkmcnt(14)
	v_pk_add_f32 v[84:85], v[12:13], v[62:63]
	v_pk_add_f32 v[12:13], v[12:13], v[62:63] neg_lo:[0,1] neg_hi:[0,1]
	v_pk_add_f32 v[62:63], v[14:15], v[64:65]
	v_pk_add_f32 v[14:15], v[14:15], v[64:65] neg_lo:[0,1] neg_hi:[0,1]
	s_nop 0
	v_pk_mul_f32 v[64:65], v[14:15], s[54:55] op_sel:[1,0] op_sel_hi:[0,0] neg_hi:[1,0]
	s_nop 0
	v_pk_fma_f32 v[14:15], v[14:15], s[52:53], v[64:65] op_sel_hi:[1,0,1]
	v_pk_add_f32 v[64:65], v[16:17], v[66:67]
	v_pk_add_f32 v[16:17], v[16:17], v[66:67] neg_lo:[0,1] neg_hi:[0,1]
	s_nop 0
	v_pk_mul_f32 v[66:67], v[16:17], s[60:61] op_sel:[1,0] op_sel_hi:[0,0] neg_hi:[1,0]
	s_nop 0
	v_pk_fma_f32 v[16:17], v[16:17], s[60:61], v[66:67] op_sel_hi:[1,0,1]
	v_pk_add_f32 v[66:67], v[18:19], v[68:69]
	v_pk_add_f32 v[18:19], v[18:19], v[68:69] neg_lo:[0,1] neg_hi:[0,1]
	s_nop 0
	v_pk_mul_f32 v[68:69], v[18:19], s[52:53] op_sel:[1,0] op_sel_hi:[0,0] neg_hi:[1,0]
	s_nop 0
	v_pk_fma_f32 v[18:19], v[18:19], s[54:55], v[68:69] op_sel_hi:[1,0,1]
	v_pk_add_f32 v[68:69], v[20:21], v[70:71]
	v_pk_add_f32 v[20:21], v[20:21], v[70:71] neg_lo:[0,1] neg_hi:[0,1]
	s_nop 0
	v_xor_b32_e32 v71, 0x80000000, v20
	v_mov_b32_e32 v70, v21
	v_pk_add_f32 v[20:21], v[22:23], v[72:73]
	v_pk_add_f32 v[22:23], v[22:23], v[72:73] neg_lo:[0,1] neg_hi:[0,1]
	s_nop 0
	v_pk_mul_f32 v[72:73], v[22:23], s[54:55] op_sel_hi:[1,0]
	v_xor_b32_e32 v87, 0x80000000, v22
	v_mov_b32_e32 v86, v23
	v_pk_fma_f32 v[22:23], v[86:87], s[52:53], v[72:73] op_sel_hi:[1,0,1] neg_lo:[0,0,1] neg_hi:[0,0,1]
	v_pk_add_f32 v[72:73], v[24:25], v[74:75]
	v_pk_add_f32 v[24:25], v[24:25], v[74:75] neg_lo:[0,1] neg_hi:[0,1]
	s_nop 0
	v_pk_mul_f32 v[74:75], v[24:25], s[60:61] op_sel_hi:[1,0]
	v_xor_b32_e32 v87, 0x80000000, v24
	v_mov_b32_e32 v86, v25
	v_pk_fma_f32 v[24:25], v[86:87], s[60:61], v[74:75] op_sel_hi:[1,0,1] neg_lo:[0,0,1] neg_hi:[0,0,1]
	v_pk_add_f32 v[74:75], v[26:27], v[76:77]
	v_pk_add_f32 v[26:27], v[26:27], v[76:77] neg_lo:[0,1] neg_hi:[0,1]
	s_nop 0
	v_pk_mul_f32 v[76:77], v[26:27], s[52:53] op_sel_hi:[1,0]
	v_xor_b32_e32 v87, 0x80000000, v26
	v_mov_b32_e32 v86, v27
	v_pk_fma_f32 v[26:27], v[86:87], s[54:55], v[76:77] op_sel_hi:[1,0,1] neg_lo:[0,0,1] neg_hi:[0,0,1]
	v_pk_add_f32 v[76:77], v[84:85], v[68:69]
	v_pk_add_f32 v[68:69], v[84:85], v[68:69] neg_lo:[0,1] neg_hi:[0,1]
	v_pk_add_f32 v[84:85], v[62:63], v[20:21]
	v_pk_add_f32 v[20:21], v[62:63], v[20:21] neg_lo:[0,1] neg_hi:[0,1]
	s_nop 0
	v_pk_mul_f32 v[62:63], v[20:21], s[60:61] op_sel:[1,0] op_sel_hi:[0,0] neg_hi:[1,0]
	s_nop 0
	v_pk_fma_f32 v[20:21], v[20:21], s[60:61], v[62:63] op_sel_hi:[1,0,1]
	v_pk_add_f32 v[62:63], v[64:65], v[72:73]
	v_pk_add_f32 v[64:65], v[64:65], v[72:73] neg_lo:[0,1] neg_hi:[0,1]
	s_nop 0
	v_xor_b32_e32 v73, 0x80000000, v64
	v_mov_b32_e32 v72, v65
	v_pk_add_f32 v[64:65], v[66:67], v[74:75]
	v_pk_add_f32 v[66:67], v[66:67], v[74:75] neg_lo:[0,1] neg_hi:[0,1]
	s_nop 0
	v_pk_mul_f32 v[74:75], v[66:67], s[60:61] op_sel_hi:[1,0]
	v_xor_b32_e32 v87, 0x80000000, v66
	v_mov_b32_e32 v86, v67
	v_pk_fma_f32 v[66:67], v[86:87], s[60:61], v[74:75] op_sel_hi:[1,0,1] neg_lo:[0,0,1] neg_hi:[0,0,1]
	v_pk_add_f32 v[74:75], v[12:13], v[70:71]
	v_pk_add_f32 v[12:13], v[12:13], v[70:71] neg_lo:[0,1] neg_hi:[0,1]
	v_pk_add_f32 v[70:71], v[14:15], v[22:23]
	v_pk_add_f32 v[14:15], v[14:15], v[22:23] neg_lo:[0,1] neg_hi:[0,1]
	s_nop 0
	v_pk_mul_f32 v[22:23], v[14:15], s[60:61] op_sel:[1,0] op_sel_hi:[0,0] neg_hi:[1,0]
	s_nop 0
	v_pk_fma_f32 v[14:15], v[14:15], s[60:61], v[22:23] op_sel_hi:[1,0,1]
	v_pk_add_f32 v[22:23], v[16:17], v[24:25]
	v_pk_add_f32 v[16:17], v[16:17], v[24:25] neg_lo:[0,1] neg_hi:[0,1]
	s_nop 0
	v_xor_b32_e32 v25, 0x80000000, v16
	v_mov_b32_e32 v24, v17
	v_pk_add_f32 v[16:17], v[18:19], v[26:27]
	v_pk_add_f32 v[18:19], v[18:19], v[26:27] neg_lo:[0,1] neg_hi:[0,1]
	v_pk_add_f32 v[108:109], v[12:13], v[24:25]
	v_pk_mul_f32 v[26:27], v[18:19], s[60:61] op_sel_hi:[1,0]
	s_nop 0
	v_pk_fma_f32 v[18:19], v[18:19], s[60:61], v[26:27] op_sel:[1,0,0] op_sel_hi:[0,0,1] neg_lo:[0,0,1] neg_hi:[1,0,1]
	v_pk_add_f32 v[26:27], v[76:77], v[62:63]
	v_pk_add_f32 v[62:63], v[76:77], v[62:63] neg_lo:[0,1] neg_hi:[0,1]
	v_pk_add_f32 v[76:77], v[84:85], v[64:65]
	v_pk_add_f32 v[64:65], v[84:85], v[64:65] neg_lo:[0,1] neg_hi:[0,1]
	v_pk_add_f32 v[110:111], v[12:13], v[24:25] neg_lo:[0,1] neg_hi:[0,1]
	v_xor_b32_e32 v85, 0x80000000, v64
	v_mov_b32_e32 v84, v65
	v_pk_add_f32 v[64:65], v[68:69], v[72:73]
	v_pk_add_f32 v[68:69], v[68:69], v[72:73] neg_lo:[0,1] neg_hi:[0,1]
	v_pk_add_f32 v[72:73], v[20:21], v[66:67]
	v_pk_add_f32 v[20:21], v[20:21], v[66:67] neg_lo:[0,1] neg_hi:[0,1]
	v_pk_add_f32 v[12:13], v[14:15], v[18:19] neg_lo:[0,1] neg_hi:[0,1]
	v_pk_add_f32 v[112:113], v[14:15], v[18:19]
	v_xor_b32_e32 v115, 0x80000000, v12
	v_mov_b32_e32 v114, v13
	v_pk_add_f32 v[12:13], v[26:27], v[76:77]
	v_pk_add_f32 v[14:15], v[26:27], v[76:77] neg_lo:[0,1] neg_hi:[0,1]
	v_pk_add_f32 v[24:25], v[68:69], v[20:21] op_sel:[0,1] op_sel_hi:[1,0] neg_hi:[0,1]
	v_pk_add_f32 v[26:27], v[68:69], v[20:21] op_sel:[0,1] op_sel_hi:[1,0] neg_lo:[0,1]
	s_waitcnt lgkmcnt(6)
	v_pk_add_f32 v[66:67], v[78:79], v[94:95] neg_lo:[0,1] neg_hi:[0,1]
	v_pk_add_f32 v[86:87], v[74:75], v[22:23]
	v_pk_mul_f32 v[76:77], v[66:67], s[54:55] op_sel:[1,0] op_sel_hi:[0,0] neg_hi:[1,0]
	v_pk_add_f32 v[74:75], v[74:75], v[22:23] neg_lo:[0,1] neg_hi:[0,1]
	v_pk_fma_f32 v[66:67], v[66:67], s[52:53], v[76:77] op_sel_hi:[1,0,1]
	s_waitcnt lgkmcnt(5)
	v_pk_add_f32 v[76:77], v[8:9], v[96:97]
	v_pk_add_f32 v[8:9], v[8:9], v[96:97] neg_lo:[0,1] neg_hi:[0,1]
	v_pk_add_f32 v[20:21], v[64:65], v[72:73]
	v_pk_add_f32 v[22:23], v[64:65], v[72:73] neg_lo:[0,1] neg_hi:[0,1]
	v_pk_add_f32 v[64:65], v[78:79], v[94:95]
	v_pk_mul_f32 v[78:79], v[8:9], s[60:61] op_sel:[1,0] op_sel_hi:[0,0] neg_hi:[1,0]
	v_pk_add_f32 v[88:89], v[70:71], v[16:17]
	v_pk_add_f32 v[16:17], v[70:71], v[16:17] neg_lo:[0,1] neg_hi:[0,1]
	v_pk_fma_f32 v[8:9], v[8:9], s[60:61], v[78:79] op_sel_hi:[1,0,1]
	s_waitcnt lgkmcnt(4)
	v_pk_add_f32 v[78:79], v[80:81], v[98:99]
	v_pk_add_f32 v[80:81], v[80:81], v[98:99] neg_lo:[0,1] neg_hi:[0,1]
	v_xor_b32_e32 v91, 0x80000000, v16
	v_mov_b32_e32 v90, v17
	v_pk_add_f32 v[16:17], v[62:63], v[84:85]
	v_pk_add_f32 v[18:19], v[62:63], v[84:85] neg_lo:[0,1] neg_hi:[0,1]
	v_pk_add_f32 v[62:63], v[6:7], v[92:93]
	v_pk_add_f32 v[6:7], v[6:7], v[92:93] neg_lo:[0,1] neg_hi:[0,1]
	v_pk_mul_f32 v[92:93], v[80:81], s[52:53] op_sel:[1,0] op_sel_hi:[0,0] neg_hi:[1,0]
	v_pk_add_f32 v[68:69], v[86:87], v[88:89]
	v_pk_fma_f32 v[80:81], v[80:81], s[54:55], v[92:93] op_sel_hi:[1,0,1]
	s_waitcnt lgkmcnt(3)
	v_pk_add_f32 v[92:93], v[10:11], v[100:101]
	v_pk_add_f32 v[10:11], v[10:11], v[100:101] neg_lo:[0,1] neg_hi:[0,1]
	v_pk_add_f32 v[70:71], v[86:87], v[88:89] neg_lo:[0,1] neg_hi:[0,1]
	v_xor_b32_e32 v95, 0x80000000, v10
	v_mov_b32_e32 v94, v11
	s_waitcnt lgkmcnt(2)
	v_pk_add_f32 v[10:11], v[4:5], v[102:103]
	v_pk_add_f32 v[4:5], v[4:5], v[102:103] neg_lo:[0,1] neg_hi:[0,1]
	v_pk_add_f32 v[84:85], v[108:109], v[112:113]
	v_pk_mul_f32 v[96:97], v[4:5], s[54:55] op_sel_hi:[1,0]
	s_nop 0
	v_pk_fma_f32 v[4:5], v[4:5], s[52:53], v[96:97] op_sel:[1,0,0] op_sel_hi:[0,0,1] neg_lo:[0,0,1] neg_hi:[1,0,1]
	s_waitcnt lgkmcnt(1)
	v_pk_add_f32 v[96:97], v[2:3], v[104:105]
	v_pk_add_f32 v[2:3], v[2:3], v[104:105] neg_lo:[0,1] neg_hi:[0,1]
	v_pk_add_f32 v[86:87], v[108:109], v[112:113] neg_lo:[0,1] neg_hi:[0,1]
	v_pk_mul_f32 v[98:99], v[2:3], s[60:61] op_sel_hi:[1,0]
	s_nop 0
	v_pk_fma_f32 v[2:3], v[2:3], s[60:61], v[98:99] op_sel:[1,0,0] op_sel_hi:[0,0,1] neg_lo:[0,0,1] neg_hi:[1,0,1]
	s_waitcnt lgkmcnt(0)
	v_pk_add_f32 v[98:99], v[82:83], v[106:107]
	v_pk_add_f32 v[82:83], v[82:83], v[106:107] neg_lo:[0,1] neg_hi:[0,1]
	v_pk_add_f32 v[72:73], v[74:75], v[90:91]
	v_pk_mul_f32 v[100:101], v[82:83], s[52:53] op_sel_hi:[1,0]
	v_xor_b32_e32 v103, 0x80000000, v82
	v_mov_b32_e32 v102, v83
	v_pk_fma_f32 v[82:83], v[102:103], s[54:55], v[100:101] op_sel_hi:[1,0,1] neg_lo:[0,0,1] neg_hi:[0,0,1]
	v_pk_add_f32 v[100:101], v[62:63], v[92:93]
	v_pk_add_f32 v[62:63], v[62:63], v[92:93] neg_lo:[0,1] neg_hi:[0,1]
	v_pk_add_f32 v[92:93], v[64:65], v[10:11]
	v_pk_add_f32 v[10:11], v[64:65], v[10:11] neg_lo:[0,1] neg_hi:[0,1]
	v_pk_add_f32 v[74:75], v[74:75], v[90:91] neg_lo:[0,1] neg_hi:[0,1]
	v_pk_mul_f32 v[64:65], v[10:11], s[60:61] op_sel:[1,0] op_sel_hi:[0,0] neg_hi:[1,0]
	v_pk_add_f32 v[88:89], v[110:111], v[114:115]
	v_pk_fma_f32 v[10:11], v[10:11], s[60:61], v[64:65] op_sel_hi:[1,0,1]
	v_pk_add_f32 v[64:65], v[76:77], v[96:97]
	v_pk_add_f32 v[76:77], v[76:77], v[96:97] neg_lo:[0,1] neg_hi:[0,1]
	v_pk_add_f32 v[90:91], v[110:111], v[114:115] neg_lo:[0,1] neg_hi:[0,1]
	v_xor_b32_e32 v97, 0x80000000, v76
	v_mov_b32_e32 v96, v77
	v_pk_add_f32 v[76:77], v[78:79], v[98:99]
	v_pk_add_f32 v[78:79], v[78:79], v[98:99] neg_lo:[0,1] neg_hi:[0,1]
	s_nop 0
	v_pk_mul_f32 v[98:99], v[78:79], s[60:61] op_sel_hi:[1,0]
	v_xor_b32_e32 v103, 0x80000000, v78
	v_mov_b32_e32 v102, v79
	v_pk_fma_f32 v[78:79], v[102:103], s[60:61], v[98:99] op_sel_hi:[1,0,1] neg_lo:[0,0,1] neg_hi:[0,0,1]
	v_pk_add_f32 v[98:99], v[6:7], v[94:95]
	v_pk_add_f32 v[6:7], v[6:7], v[94:95] neg_lo:[0,1] neg_hi:[0,1]
	v_pk_add_f32 v[94:95], v[66:67], v[4:5]
	v_pk_add_f32 v[4:5], v[66:67], v[4:5] neg_lo:[0,1] neg_hi:[0,1]
	s_nop 0
	v_pk_mul_f32 v[66:67], v[4:5], s[60:61] op_sel:[1,0] op_sel_hi:[0,0] neg_hi:[1,0]
	s_nop 0
	v_pk_fma_f32 v[4:5], v[4:5], s[60:61], v[66:67] op_sel_hi:[1,0,1]
	v_pk_add_f32 v[66:67], v[8:9], v[2:3]
	v_pk_add_f32 v[2:3], v[8:9], v[2:3] neg_lo:[0,1] neg_hi:[0,1]
	v_pk_add_f32 v[106:107], v[98:99], v[66:67] neg_lo:[0,1] neg_hi:[0,1]
	v_xor_b32_e32 v9, 0x80000000, v2
	v_mov_b32_e32 v8, v3
	v_pk_add_f32 v[2:3], v[80:81], v[82:83]
	v_pk_add_f32 v[80:81], v[80:81], v[82:83] neg_lo:[0,1] neg_hi:[0,1]
	v_pk_add_f32 v[108:109], v[94:95], v[2:3]
	v_pk_mul_f32 v[82:83], v[80:81], s[60:61] op_sel_hi:[1,0]
	s_nop 0
	v_pk_fma_f32 v[80:81], v[80:81], s[60:61], v[82:83] op_sel:[1,0,0] op_sel_hi:[0,0,1] neg_lo:[0,0,1] neg_hi:[1,0,1]
	v_pk_add_f32 v[82:83], v[100:101], v[64:65]
	v_pk_add_f32 v[64:65], v[100:101], v[64:65] neg_lo:[0,1] neg_hi:[0,1]
	v_pk_add_f32 v[100:101], v[92:93], v[76:77]
	v_pk_add_f32 v[76:77], v[92:93], v[76:77] neg_lo:[0,1] neg_hi:[0,1]
	v_pk_add_f32 v[102:103], v[10:11], v[78:79]
	v_xor_b32_e32 v93, 0x80000000, v76
	v_mov_b32_e32 v92, v77
	v_pk_add_f32 v[76:77], v[62:63], v[96:97]
	v_pk_add_f32 v[10:11], v[10:11], v[78:79] neg_lo:[0,1] neg_hi:[0,1]
	v_pk_add_f32 v[2:3], v[94:95], v[2:3] neg_lo:[0,1] neg_hi:[0,1]
	v_pk_add_f32 v[62:63], v[62:63], v[96:97] neg_lo:[0,1] neg_hi:[0,1]
	v_xor_b32_e32 v105, 0x80000000, v10
	v_mov_b32_e32 v104, v11
	v_pk_add_f32 v[10:11], v[98:99], v[66:67]
	v_xor_b32_e32 v111, 0x80000000, v2
	v_mov_b32_e32 v110, v3
	v_pk_add_f32 v[112:113], v[6:7], v[8:9]
	v_pk_add_f32 v[114:115], v[6:7], v[8:9] neg_lo:[0,1] neg_hi:[0,1]
	v_pk_add_f32 v[6:7], v[4:5], v[80:81]
	v_pk_add_f32 v[2:3], v[4:5], v[80:81] neg_lo:[0,1] neg_hi:[0,1]
	v_pk_add_f32 v[98:99], v[82:83], v[100:101]
	v_pk_add_f32 v[96:97], v[82:83], v[100:101] neg_lo:[0,1] neg_hi:[0,1]
	v_pk_add_f32 v[82:83], v[76:77], v[102:103]
	v_pk_add_f32 v[80:81], v[76:77], v[102:103] neg_lo:[0,1] neg_hi:[0,1]
	s_waitcnt vmcnt(7)
	v_mov_b64 v[100:101], v[164:165]
	v_mov_b64 v[102:103], v[166:167]
	v_pk_add_f32 v[78:79], v[62:63], v[104:105]
	v_pk_add_f32 v[76:77], v[62:63], v[104:105] neg_lo:[0,1] neg_hi:[0,1]
	v_xor_b32_e32 v5, 0x80000000, v2
	v_mov_b32_e32 v4, v3
	v_pk_add_f32 v[62:63], v[106:107], v[110:111]
	v_pk_add_f32 v[2:3], v[106:107], v[110:111] neg_lo:[0,1] neg_hi:[0,1]
	v_pk_add_f32 v[94:95], v[64:65], v[92:93]
	v_pk_add_f32 v[92:93], v[64:65], v[92:93] neg_lo:[0,1] neg_hi:[0,1]
	v_pk_add_f32 v[66:67], v[10:11], v[108:109]
	v_pk_add_f32 v[64:65], v[10:11], v[108:109] neg_lo:[0,1] neg_hi:[0,1]
	v_pk_add_f32 v[10:11], v[112:113], v[6:7]
	v_pk_add_f32 v[8:9], v[112:113], v[6:7] neg_lo:[0,1] neg_hi:[0,1]
	v_pk_add_f32 v[6:7], v[114:115], v[4:5]
	v_pk_add_f32 v[4:5], v[114:115], v[4:5] neg_lo:[0,1] neg_hi:[0,1]
	v_cvt_f32_f16_e32 v104, v100
	v_cvt_f32_f16_sdwa v100, v100 dst_sel:DWORD dst_unused:UNUSED_PAD src0_sel:WORD_1
	v_mul_f32_e32 v104, 0x38800000, v104
	v_mul_f32_e32 v100, 0x38800000, v100
	s_nop 0
	v_pk_mul_f32 v[106:107], v[12:13], v[100:101] op_sel:[1,0] op_sel_hi:[0,0] neg_lo:[1,0]
	v_cvt_f32_f16_e32 v100, v101
	v_cvt_f32_f16_sdwa v101, v101 dst_sel:DWORD dst_unused:UNUSED_PAD src0_sel:WORD_1
	v_pk_fma_f32 v[12:13], v[12:13], v[104:105], v[106:107] op_sel_hi:[1,0,1]
	v_xor_b32_e32 v106, 0x80000000, v15
	v_mov_b32_e32 v107, v14
	v_mul_f32_e32 v104, 0x38800000, v101
	v_mul_f32_e32 v100, 0x38800000, v100
	v_pk_mul_f32 v[104:105], v[106:107], v[104:105] op_sel_hi:[1,0]
	v_xor_b32_e32 v106, 0x80000000, v21
	v_pk_fma_f32 v[14:15], v[14:15], v[100:101], v[104:105] op_sel_hi:[1,0,1]
	v_cvt_f32_f16_sdwa v101, v102 dst_sel:DWORD dst_unused:UNUSED_PAD src0_sel:WORD_1
	v_cvt_f32_f16_e32 v100, v102
	s_nop 0
	s_nop 0
	v_mul_f32_e32 v102, 0x38800000, v101
	v_mul_f32_e32 v100, 0x38800000, v100
	v_pk_mul_f32 v[104:105], v[16:17], v[102:103] op_sel:[1,0] op_sel_hi:[0,0] neg_lo:[1,0]
	v_mov_b32_e32 v107, v20
	v_pk_fma_f32 v[16:17], v[16:17], v[100:101], v[104:105] op_sel_hi:[1,0,1]
	v_cvt_f32_f16_sdwa v101, v103 dst_sel:DWORD dst_unused:UNUSED_PAD src0_sel:WORD_1
	v_cvt_f32_f16_e32 v100, v103
	v_xor_b32_e32 v104, 0x80000000, v19
	v_mov_b32_e32 v105, v18
	v_mul_f32_e32 v102, 0x38800000, v101
	v_mul_f32_e32 v100, 0x38800000, v100
	v_pk_mul_f32 v[102:103], v[104:105], v[102:103] op_sel_hi:[1,0]
	s_nop 0
	v_pk_fma_f32 v[18:19], v[18:19], v[100:101], v[102:103] op_sel_hi:[1,0,1]
	s_waitcnt vmcnt(6)
	v_mov_b64 v[100:101], v[168:169]
	v_mov_b64 v[102:103], v[170:171]
	v_cvt_f32_f16_e32 v104, v100
	v_cvt_f32_f16_sdwa v100, v100 dst_sel:DWORD dst_unused:UNUSED_PAD src0_sel:WORD_1
	v_mul_f32_e32 v104, 0x38800000, v104
	v_mul_f32_e32 v100, 0x38800000, v100
	v_pk_mul_f32 v[106:107], v[106:107], v[100:101] op_sel_hi:[1,0]
	v_cvt_f32_f16_e32 v100, v101
	v_cvt_f32_f16_sdwa v101, v101 dst_sel:DWORD dst_unused:UNUSED_PAD src0_sel:WORD_1
	v_pk_fma_f32 v[20:21], v[20:21], v[104:105], v[106:107] op_sel_hi:[1,0,1]
	v_xor_b32_e32 v106, 0x80000000, v23
	v_mov_b32_e32 v107, v22
	v_mul_f32_e32 v104, 0x38800000, v101
	v_mul_f32_e32 v100, 0x38800000, v100
	v_pk_mul_f32 v[104:105], v[106:107], v[104:105] op_sel_hi:[1,0]
	v_xor_b32_e32 v106, 0x80000000, v69
	v_pk_fma_f32 v[22:23], v[22:23], v[100:101], v[104:105] op_sel_hi:[1,0,1]
	v_cvt_f32_f16_sdwa v101, v102 dst_sel:DWORD dst_unused:UNUSED_PAD src0_sel:WORD_1
	v_cvt_f32_f16_e32 v100, v102
	s_nop 0
	s_nop 0
	v_mul_f32_e32 v102, 0x38800000, v101
	v_mul_f32_e32 v100, 0x38800000, v100
	v_pk_mul_f32 v[104:105], v[24:25], v[102:103] op_sel:[1,0] op_sel_hi:[0,0] neg_lo:[1,0]
	v_mov_b32_e32 v107, v68
	v_pk_fma_f32 v[24:25], v[24:25], v[100:101], v[104:105] op_sel_hi:[1,0,1]
	v_cvt_f32_f16_sdwa v101, v103 dst_sel:DWORD dst_unused:UNUSED_PAD src0_sel:WORD_1
	v_cvt_f32_f16_e32 v100, v103
	v_xor_b32_e32 v104, 0x80000000, v27
	v_mov_b32_e32 v105, v26
	v_mul_f32_e32 v102, 0x38800000, v101
	v_mul_f32_e32 v100, 0x38800000, v100
	v_pk_mul_f32 v[102:103], v[104:105], v[102:103] op_sel_hi:[1,0]
	s_nop 0
	v_pk_fma_f32 v[26:27], v[26:27], v[100:101], v[102:103] op_sel_hi:[1,0,1]
	s_waitcnt vmcnt(5)
	v_mov_b64 v[100:101], v[172:173]
	v_mov_b64 v[102:103], v[174:175]
	v_cvt_f32_f16_e32 v104, v100
	v_cvt_f32_f16_sdwa v100, v100 dst_sel:DWORD dst_unused:UNUSED_PAD src0_sel:WORD_1
	v_mul_f32_e32 v104, 0x38800000, v104
	v_mul_f32_e32 v100, 0x38800000, v100
	v_pk_mul_f32 v[106:107], v[106:107], v[100:101] op_sel_hi:[1,0]
	v_cvt_f32_f16_e32 v100, v101
	v_cvt_f32_f16_sdwa v101, v101 dst_sel:DWORD dst_unused:UNUSED_PAD src0_sel:WORD_1
	v_pk_fma_f32 v[68:69], v[68:69], v[104:105], v[106:107] op_sel_hi:[1,0,1]
	v_xor_b32_e32 v106, 0x80000000, v71
	v_mov_b32_e32 v107, v70
	v_mul_f32_e32 v104, 0x38800000, v101
	v_mul_f32_e32 v100, 0x38800000, v100
	v_pk_mul_f32 v[104:105], v[106:107], v[104:105] op_sel_hi:[1,0]
	v_xor_b32_e32 v106, 0x80000000, v85
	v_pk_fma_f32 v[70:71], v[70:71], v[100:101], v[104:105] op_sel_hi:[1,0,1]
	v_cvt_f32_f16_sdwa v101, v102 dst_sel:DWORD dst_unused:UNUSED_PAD src0_sel:WORD_1
	v_cvt_f32_f16_e32 v100, v102
	s_nop 0
	s_nop 0
	v_mul_f32_e32 v102, 0x38800000, v101
	v_mul_f32_e32 v100, 0x38800000, v100
	v_pk_mul_f32 v[104:105], v[72:73], v[102:103] op_sel:[1,0] op_sel_hi:[0,0] neg_lo:[1,0]
	v_mov_b32_e32 v107, v84
	v_pk_fma_f32 v[72:73], v[72:73], v[100:101], v[104:105] op_sel_hi:[1,0,1]
	v_cvt_f32_f16_sdwa v101, v103 dst_sel:DWORD dst_unused:UNUSED_PAD src0_sel:WORD_1
	v_cvt_f32_f16_e32 v100, v103
	v_xor_b32_e32 v104, 0x80000000, v75
	v_mov_b32_e32 v105, v74
	v_mul_f32_e32 v102, 0x38800000, v101
	v_mul_f32_e32 v100, 0x38800000, v100
	v_pk_mul_f32 v[102:103], v[104:105], v[102:103] op_sel_hi:[1,0]
	s_nop 0
	v_pk_fma_f32 v[74:75], v[74:75], v[100:101], v[102:103] op_sel_hi:[1,0,1]
	s_waitcnt vmcnt(4)
	v_mov_b64 v[100:101], v[176:177]
	v_mov_b64 v[102:103], v[178:179]
	v_cvt_f32_f16_e32 v104, v100
	v_cvt_f32_f16_sdwa v100, v100 dst_sel:DWORD dst_unused:UNUSED_PAD src0_sel:WORD_1
	v_mul_f32_e32 v104, 0x38800000, v104
	v_mul_f32_e32 v100, 0x38800000, v100
	v_pk_mul_f32 v[106:107], v[106:107], v[100:101] op_sel_hi:[1,0]
	v_cvt_f32_f16_e32 v100, v101
	v_cvt_f32_f16_sdwa v101, v101 dst_sel:DWORD dst_unused:UNUSED_PAD src0_sel:WORD_1
	v_pk_fma_f32 v[84:85], v[84:85], v[104:105], v[106:107] op_sel_hi:[1,0,1]
	v_xor_b32_e32 v106, 0x80000000, v87
	v_mov_b32_e32 v107, v86
	v_mul_f32_e32 v104, 0x38800000, v101
	v_mul_f32_e32 v100, 0x38800000, v100
	v_pk_mul_f32 v[104:105], v[106:107], v[104:105] op_sel_hi:[1,0]
	v_xor_b32_e32 v106, 0x80000000, v99
	v_pk_fma_f32 v[86:87], v[86:87], v[100:101], v[104:105] op_sel_hi:[1,0,1]
	v_cvt_f32_f16_sdwa v101, v102 dst_sel:DWORD dst_unused:UNUSED_PAD src0_sel:WORD_1
	v_cvt_f32_f16_e32 v100, v102
	s_nop 0
	s_nop 0
	v_mul_f32_e32 v102, 0x38800000, v101
	v_mul_f32_e32 v100, 0x38800000, v100
	v_pk_mul_f32 v[104:105], v[88:89], v[102:103] op_sel:[1,0] op_sel_hi:[0,0] neg_lo:[1,0]
	v_mov_b32_e32 v107, v98
	v_pk_fma_f32 v[88:89], v[88:89], v[100:101], v[104:105] op_sel_hi:[1,0,1]
	v_cvt_f32_f16_sdwa v101, v103 dst_sel:DWORD dst_unused:UNUSED_PAD src0_sel:WORD_1
	v_cvt_f32_f16_e32 v100, v103
	v_xor_b32_e32 v104, 0x80000000, v91
	v_mov_b32_e32 v105, v90
	v_mul_f32_e32 v102, 0x38800000, v101
	v_mul_f32_e32 v100, 0x38800000, v100
	v_pk_mul_f32 v[102:103], v[104:105], v[102:103] op_sel_hi:[1,0]
	s_nop 0
	v_pk_fma_f32 v[90:91], v[90:91], v[100:101], v[102:103] op_sel_hi:[1,0,1]
	s_waitcnt vmcnt(3)
	v_mov_b64 v[100:101], v[180:181]
	v_mov_b64 v[102:103], v[182:183]
	v_cvt_f32_f16_e32 v104, v100
	v_cvt_f32_f16_sdwa v100, v100 dst_sel:DWORD dst_unused:UNUSED_PAD src0_sel:WORD_1
	v_mul_f32_e32 v104, 0x38800000, v104
	v_mul_f32_e32 v100, 0x38800000, v100
	v_pk_mul_f32 v[106:107], v[106:107], v[100:101] op_sel_hi:[1,0]
	v_cvt_f32_f16_e32 v100, v101
	v_cvt_f32_f16_sdwa v101, v101 dst_sel:DWORD dst_unused:UNUSED_PAD src0_sel:WORD_1
	v_pk_fma_f32 v[98:99], v[98:99], v[104:105], v[106:107] op_sel_hi:[1,0,1]
	v_xor_b32_e32 v106, 0x80000000, v97
	v_mov_b32_e32 v107, v96
	v_mul_f32_e32 v104, 0x38800000, v101
	v_mul_f32_e32 v100, 0x38800000, v100
	v_pk_mul_f32 v[104:105], v[106:107], v[104:105] op_sel_hi:[1,0]
	v_xor_b32_e32 v106, 0x80000000, v83
	v_pk_fma_f32 v[96:97], v[96:97], v[100:101], v[104:105] op_sel_hi:[1,0,1]
	v_cvt_f32_f16_sdwa v101, v102 dst_sel:DWORD dst_unused:UNUSED_PAD src0_sel:WORD_1
	v_cvt_f32_f16_e32 v100, v102
	s_nop 0
	s_nop 0
	v_mul_f32_e32 v102, 0x38800000, v101
	v_mul_f32_e32 v100, 0x38800000, v100
	v_pk_mul_f32 v[104:105], v[94:95], v[102:103] op_sel:[1,0] op_sel_hi:[0,0] neg_lo:[1,0]
	v_mov_b32_e32 v107, v82
	v_pk_fma_f32 v[94:95], v[94:95], v[100:101], v[104:105] op_sel_hi:[1,0,1]
	v_cvt_f32_f16_sdwa v101, v103 dst_sel:DWORD dst_unused:UNUSED_PAD src0_sel:WORD_1
	v_cvt_f32_f16_e32 v100, v103
	v_xor_b32_e32 v104, 0x80000000, v93
	v_mov_b32_e32 v105, v92
	v_mul_f32_e32 v102, 0x38800000, v101
	v_mul_f32_e32 v100, 0x38800000, v100
	v_pk_mul_f32 v[102:103], v[104:105], v[102:103] op_sel_hi:[1,0]
	s_nop 0
	v_pk_fma_f32 v[92:93], v[92:93], v[100:101], v[102:103] op_sel_hi:[1,0,1]
	s_waitcnt vmcnt(2)
	v_mov_b64 v[100:101], v[184:185]
	v_mov_b64 v[102:103], v[186:187]
	v_cvt_f32_f16_e32 v104, v100
	v_cvt_f32_f16_sdwa v100, v100 dst_sel:DWORD dst_unused:UNUSED_PAD src0_sel:WORD_1
	v_mul_f32_e32 v104, 0x38800000, v104
	v_mul_f32_e32 v100, 0x38800000, v100
	v_pk_mul_f32 v[106:107], v[106:107], v[100:101] op_sel_hi:[1,0]
	v_cvt_f32_f16_e32 v100, v101
	v_cvt_f32_f16_sdwa v101, v101 dst_sel:DWORD dst_unused:UNUSED_PAD src0_sel:WORD_1
	v_pk_fma_f32 v[82:83], v[82:83], v[104:105], v[106:107] op_sel_hi:[1,0,1]
	v_xor_b32_e32 v106, 0x80000000, v81
	v_mov_b32_e32 v107, v80
	v_mul_f32_e32 v104, 0x38800000, v101
	v_mul_f32_e32 v100, 0x38800000, v100
	v_pk_mul_f32 v[104:105], v[106:107], v[104:105] op_sel_hi:[1,0]
	v_xor_b32_e32 v106, 0x80000000, v67
	v_pk_fma_f32 v[80:81], v[80:81], v[100:101], v[104:105] op_sel_hi:[1,0,1]
	v_cvt_f32_f16_sdwa v101, v102 dst_sel:DWORD dst_unused:UNUSED_PAD src0_sel:WORD_1
	v_cvt_f32_f16_e32 v100, v102
	s_nop 0
	s_nop 0
	v_mul_f32_e32 v102, 0x38800000, v101
	v_mul_f32_e32 v100, 0x38800000, v100
	v_pk_mul_f32 v[104:105], v[78:79], v[102:103] op_sel:[1,0] op_sel_hi:[0,0] neg_lo:[1,0]
	v_mov_b32_e32 v107, v66
	v_pk_fma_f32 v[78:79], v[78:79], v[100:101], v[104:105] op_sel_hi:[1,0,1]
	v_cvt_f32_f16_sdwa v101, v103 dst_sel:DWORD dst_unused:UNUSED_PAD src0_sel:WORD_1
	v_cvt_f32_f16_e32 v100, v103
	v_xor_b32_e32 v104, 0x80000000, v77
	v_mov_b32_e32 v105, v76
	v_mul_f32_e32 v102, 0x38800000, v101
	v_mul_f32_e32 v100, 0x38800000, v100
	v_pk_mul_f32 v[102:103], v[104:105], v[102:103] op_sel_hi:[1,0]
	s_nop 0
	v_pk_fma_f32 v[76:77], v[76:77], v[100:101], v[102:103] op_sel_hi:[1,0,1]
	s_waitcnt vmcnt(1)
	v_mov_b64 v[100:101], v[188:189]
	v_mov_b64 v[102:103], v[190:191]
	v_cvt_f32_f16_e32 v104, v100
	v_cvt_f32_f16_sdwa v100, v100 dst_sel:DWORD dst_unused:UNUSED_PAD src0_sel:WORD_1
	v_mul_f32_e32 v104, 0x38800000, v104
	v_mul_f32_e32 v100, 0x38800000, v100
	v_pk_mul_f32 v[106:107], v[106:107], v[100:101] op_sel_hi:[1,0]
	v_cvt_f32_f16_e32 v100, v101
	v_cvt_f32_f16_sdwa v101, v101 dst_sel:DWORD dst_unused:UNUSED_PAD src0_sel:WORD_1
	v_pk_fma_f32 v[66:67], v[66:67], v[104:105], v[106:107] op_sel_hi:[1,0,1]
	v_xor_b32_e32 v106, 0x80000000, v65
	v_mov_b32_e32 v107, v64
	v_mul_f32_e32 v104, 0x38800000, v101
	v_mul_f32_e32 v100, 0x38800000, v100
	v_pk_mul_f32 v[104:105], v[106:107], v[104:105] op_sel_hi:[1,0]
	s_nop 0
	v_pk_fma_f32 v[64:65], v[64:65], v[100:101], v[104:105] op_sel_hi:[1,0,1]
	v_cvt_f32_f16_sdwa v101, v102 dst_sel:DWORD dst_unused:UNUSED_PAD src0_sel:WORD_1
	v_cvt_f32_f16_e32 v100, v102
	s_nop 0
	s_nop 0
	v_mul_f32_e32 v102, 0x38800000, v101
	v_mul_f32_e32 v100, 0x38800000, v100
	v_pk_mul_f32 v[104:105], v[62:63], v[102:103] op_sel:[1,0] op_sel_hi:[0,0] neg_lo:[1,0]
	s_nop 0
	v_pk_fma_f32 v[62:63], v[62:63], v[100:101], v[104:105] op_sel_hi:[1,0,1]
	v_cvt_f32_f16_sdwa v101, v103 dst_sel:DWORD dst_unused:UNUSED_PAD src0_sel:WORD_1
	v_cvt_f32_f16_e32 v100, v103
	v_xor_b32_e32 v104, 0x80000000, v3
	v_mov_b32_e32 v105, v2
	v_mul_f32_e32 v102, 0x38800000, v101
	v_mul_f32_e32 v100, 0x38800000, v100
	v_pk_mul_f32 v[102:103], v[104:105], v[102:103] op_sel_hi:[1,0]
	v_xor_b32_e32 v104, 0x80000000, v11
	v_pk_fma_f32 v[100:101], v[2:3], v[100:101], v[102:103] op_sel_hi:[1,0,1]
	s_waitcnt vmcnt(0)
	v_mov_b64 v[0:1], v[192:193]
	v_mov_b64 v[2:3], v[194:195]
	v_mov_b32_e32 v105, v10
	v_cvt_f32_f16_e32 v102, v0
	v_cvt_f32_f16_sdwa v0, v0 dst_sel:DWORD dst_unused:UNUSED_PAD src0_sel:WORD_1
	v_mul_f32_e32 v102, 0x38800000, v102
	v_mul_f32_e32 v0, 0x38800000, v0
	v_pk_mul_f32 v[104:105], v[104:105], v[0:1] op_sel_hi:[1,0]
	v_cvt_f32_f16_e32 v0, v1
	v_cvt_f32_f16_sdwa v1, v1 dst_sel:DWORD dst_unused:UNUSED_PAD src0_sel:WORD_1
	v_pk_fma_f32 v[10:11], v[10:11], v[102:103], v[104:105] op_sel_hi:[1,0,1]
	v_xor_b32_e32 v104, 0x80000000, v9
	v_mov_b32_e32 v105, v8
	v_mul_f32_e32 v102, 0x38800000, v1
	v_mul_f32_e32 v0, 0x38800000, v0
	v_pk_mul_f32 v[102:103], v[104:105], v[102:103] op_sel_hi:[1,0]
	s_nop 0
	v_pk_fma_f32 v[0:1], v[8:9], v[0:1], v[102:103] op_sel_hi:[1,0,1]
	v_cvt_f32_f16_e32 v8, v2
	v_cvt_f32_f16_sdwa v2, v2 dst_sel:DWORD dst_unused:UNUSED_PAD src0_sel:WORD_1
	s_nop 0
	s_nop 0
	v_mul_f32_e32 v8, 0x38800000, v8
	v_mul_f32_e32 v2, 0x38800000, v2
	s_nop 0
	v_pk_mul_f32 v[102:103], v[6:7], v[2:3] op_sel:[1,0] op_sel_hi:[0,0] neg_lo:[1,0]
	v_cvt_f32_f16_e32 v2, v3
	v_cvt_f32_f16_sdwa v3, v3 dst_sel:DWORD dst_unused:UNUSED_PAD src0_sel:WORD_1
	v_pk_fma_f32 v[6:7], v[6:7], v[8:9], v[102:103] op_sel_hi:[1,0,1]
	v_xor_b32_e32 v102, 0x80000000, v5
	v_mov_b32_e32 v103, v4
	v_mul_f32_e32 v8, 0x38800000, v3
	v_mul_f32_e32 v2, 0x38800000, v2
	v_pk_mul_f32 v[8:9], v[102:103], v[8:9] op_sel_hi:[1,0]
	v_mov_b32_e32 v102, v146
	v_pk_fma_f32 v[2:3], v[4:5], v[2:3], v[8:9] op_sel_hi:[1,0,1]
	v_pk_add_f32 v[4:5], v[12:13], v[14:15]
	v_pk_add_f32 v[8:9], v[12:13], v[14:15] neg_lo:[0,1] neg_hi:[0,1]
	v_pk_add_f32 v[12:13], v[16:17], v[18:19]
	v_pk_add_f32 v[14:15], v[16:17], v[18:19] neg_lo:[0,1] neg_hi:[0,1]
	v_pk_add_f32 v[16:17], v[20:21], v[22:23]
	v_pk_add_f32 v[18:19], v[20:21], v[22:23] neg_lo:[0,1] neg_hi:[0,1]
	v_pk_add_f32 v[20:21], v[24:25], v[26:27]
	v_pk_add_f32 v[22:23], v[24:25], v[26:27] neg_lo:[0,1] neg_hi:[0,1]
	v_pk_add_f32 v[24:25], v[68:69], v[70:71]
	v_pk_add_f32 v[26:27], v[68:69], v[70:71] neg_lo:[0,1] neg_hi:[0,1]
	v_pk_add_f32 v[68:69], v[72:73], v[74:75]
	v_pk_add_f32 v[70:71], v[72:73], v[74:75] neg_lo:[0,1] neg_hi:[0,1]
	v_pk_add_f32 v[72:73], v[84:85], v[86:87]
	v_pk_add_f32 v[74:75], v[84:85], v[86:87] neg_lo:[0,1] neg_hi:[0,1]
	v_pk_add_f32 v[84:85], v[88:89], v[90:91]
	v_pk_add_f32 v[86:87], v[88:89], v[90:91] neg_lo:[0,1] neg_hi:[0,1]
	v_pk_add_f32 v[88:89], v[4:5], v[12:13]
	v_pk_add_f32 v[4:5], v[4:5], v[12:13] neg_lo:[0,1] neg_hi:[0,1]
	v_xor_b32_e32 v12, 0x80000000, v15
	v_mov_b32_e32 v13, v14
	v_pk_add_f32 v[14:15], v[8:9], v[12:13]
	v_pk_add_f32 v[8:9], v[8:9], v[12:13] neg_lo:[0,1] neg_hi:[0,1]
	v_pk_add_f32 v[12:13], v[16:17], v[20:21]
	v_pk_add_f32 v[16:17], v[16:17], v[20:21] neg_lo:[0,1] neg_hi:[0,1]
	v_xor_b32_e32 v20, 0x80000000, v23
	v_mov_b32_e32 v21, v22
	v_pk_add_f32 v[22:23], v[18:19], v[20:21]
	v_pk_add_f32 v[18:19], v[18:19], v[20:21] neg_lo:[0,1] neg_hi:[0,1]
	v_pk_add_f32 v[20:21], v[24:25], v[68:69]
	v_pk_add_f32 v[24:25], v[24:25], v[68:69] neg_lo:[0,1] neg_hi:[0,1]
	v_xor_b32_e32 v68, 0x80000000, v71
	v_mov_b32_e32 v69, v70
	v_pk_add_f32 v[70:71], v[26:27], v[68:69]
	v_pk_add_f32 v[26:27], v[26:27], v[68:69] neg_lo:[0,1] neg_hi:[0,1]
	v_pk_add_f32 v[68:69], v[72:73], v[84:85]
	v_pk_add_f32 v[72:73], v[72:73], v[84:85] neg_lo:[0,1] neg_hi:[0,1]
	v_xor_b32_e32 v84, 0x80000000, v87
	v_mov_b32_e32 v85, v86
	v_pk_add_f32 v[86:87], v[74:75], v[84:85]
	v_pk_add_f32 v[74:75], v[74:75], v[84:85] neg_lo:[0,1] neg_hi:[0,1]
	v_pk_add_f32 v[84:85], v[88:89], v[12:13]
	v_pk_add_f32 v[12:13], v[88:89], v[12:13] neg_lo:[0,1] neg_hi:[0,1]
	v_pk_mul_f32 v[88:89], v[22:23], s[60:61] op_sel:[1,0] op_sel_hi:[0,0] neg_lo:[1,0]
	v_xor_b32_e32 v90, 0x80000000, v19
	v_pk_fma_f32 v[22:23], v[22:23], s[60:61], v[88:89] op_sel_hi:[1,0,1]
	v_mov_b32_e32 v91, v18
	v_pk_add_f32 v[88:89], v[14:15], v[22:23]
	v_pk_add_f32 v[14:15], v[14:15], v[22:23] neg_lo:[0,1] neg_hi:[0,1]
	v_xor_b32_e32 v22, 0x80000000, v17
	v_mov_b32_e32 v23, v16
	v_pk_add_f32 v[16:17], v[4:5], v[22:23]
	v_pk_add_f32 v[4:5], v[4:5], v[22:23] neg_lo:[0,1] neg_hi:[0,1]
	v_pk_mul_f32 v[22:23], v[18:19], s[60:61] op_sel_hi:[1,0]
	s_nop 0
	v_pk_fma_f32 v[18:19], v[90:91], s[60:61], v[22:23] op_sel_hi:[1,0,1] neg_lo:[0,0,1] neg_hi:[0,0,1]
	v_xor_b32_e32 v90, 0x80000000, v75
	v_pk_add_f32 v[22:23], v[8:9], v[18:19]
	v_pk_add_f32 v[8:9], v[8:9], v[18:19] neg_lo:[0,1] neg_hi:[0,1]
	v_pk_add_f32 v[18:19], v[20:21], v[68:69]
	v_pk_add_f32 v[20:21], v[20:21], v[68:69] neg_lo:[0,1] neg_hi:[0,1]
	v_pk_mul_f32 v[68:69], v[86:87], s[60:61] op_sel:[1,0] op_sel_hi:[0,0] neg_lo:[1,0]
	v_mov_b32_e32 v91, v74
	v_pk_fma_f32 v[68:69], v[86:87], s[60:61], v[68:69] op_sel_hi:[1,0,1]
	s_nop 0
	v_pk_add_f32 v[86:87], v[70:71], v[68:69]
	v_pk_add_f32 v[68:69], v[70:71], v[68:69] neg_lo:[0,1] neg_hi:[0,1]
	v_xor_b32_e32 v70, 0x80000000, v73
	v_mov_b32_e32 v71, v72
	v_pk_add_f32 v[72:73], v[24:25], v[70:71]
	v_pk_add_f32 v[24:25], v[24:25], v[70:71] neg_lo:[0,1] neg_hi:[0,1]
	v_pk_mul_f32 v[70:71], v[74:75], s[60:61] op_sel_hi:[1,0]
	s_nop 0
	v_pk_fma_f32 v[70:71], v[90:91], s[60:61], v[70:71] op_sel_hi:[1,0,1] neg_lo:[0,0,1] neg_hi:[0,0,1]
	v_xor_b32_e32 v90, 0x80000000, v69
	v_pk_add_f32 v[74:75], v[26:27], v[70:71]
	v_pk_add_f32 v[26:27], v[26:27], v[70:71] neg_lo:[0,1] neg_hi:[0,1]
	v_pk_add_f32 v[70:71], v[84:85], v[18:19]
	v_pk_add_f32 v[18:19], v[84:85], v[18:19] neg_lo:[0,1] neg_hi:[0,1]
	v_pk_mul_f32 v[84:85], v[86:87], s[54:55] op_sel:[1,0] op_sel_hi:[0,0] neg_lo:[1,0]
	v_mov_b32_e32 v91, v68
	v_pk_fma_f32 v[84:85], v[86:87], s[52:53], v[84:85] op_sel_hi:[1,0,1]
	s_nop 0
	v_pk_add_f32 v[86:87], v[88:89], v[84:85]
	v_pk_add_f32 v[84:85], v[88:89], v[84:85] neg_lo:[0,1] neg_hi:[0,1]
	v_pk_mul_f32 v[88:89], v[72:73], s[60:61] op_sel:[1,0] op_sel_hi:[0,0] neg_lo:[1,0]
	s_nop 0
	v_pk_fma_f32 v[72:73], v[72:73], s[60:61], v[88:89] op_sel_hi:[1,0,1]
	s_nop 0
	v_pk_add_f32 v[88:89], v[16:17], v[72:73]
	v_pk_add_f32 v[16:17], v[16:17], v[72:73] neg_lo:[0,1] neg_hi:[0,1]
	v_pk_mul_f32 v[72:73], v[74:75], s[52:53] op_sel:[1,0] op_sel_hi:[0,0] neg_lo:[1,0]
	s_nop 0
	v_pk_fma_f32 v[72:73], v[74:75], s[54:55], v[72:73] op_sel_hi:[1,0,1]
	s_nop 0
	v_pk_add_f32 v[74:75], v[22:23], v[72:73]
	v_pk_add_f32 v[22:23], v[22:23], v[72:73] neg_lo:[0,1] neg_hi:[0,1]
	v_xor_b32_e32 v72, 0x80000000, v21
	v_mov_b32_e32 v73, v20
	v_pk_add_f32 v[20:21], v[12:13], v[72:73]
	v_pk_add_f32 v[12:13], v[12:13], v[72:73] neg_lo:[0,1] neg_hi:[0,1]
	v_pk_mul_f32 v[72:73], v[68:69], s[54:55] op_sel_hi:[1,0]
	s_nop 0
	v_pk_fma_f32 v[68:69], v[90:91], s[52:53], v[72:73] op_sel_hi:[1,0,1] neg_lo:[0,0,1] neg_hi:[0,0,1]
	v_xor_b32_e32 v90, 0x80000000, v25
	v_pk_add_f32 v[72:73], v[14:15], v[68:69]
	v_pk_add_f32 v[14:15], v[14:15], v[68:69] neg_lo:[0,1] neg_hi:[0,1]
	v_pk_mul_f32 v[68:69], v[24:25], s[60:61] op_sel_hi:[1,0]
	v_mov_b32_e32 v91, v24
	v_pk_fma_f32 v[24:25], v[90:91], s[60:61], v[68:69] op_sel_hi:[1,0,1] neg_lo:[0,0,1] neg_hi:[0,0,1]
	s_nop 0
	v_pk_add_f32 v[68:69], v[4:5], v[24:25]
	v_pk_add_f32 v[4:5], v[4:5], v[24:25] neg_lo:[0,1] neg_hi:[0,1]
	v_pk_mul_f32 v[24:25], v[26:27], s[52:53] op_sel_hi:[1,0]
	s_nop 0
	v_pk_fma_f32 v[24:25], v[26:27], s[54:55], v[24:25] op_sel:[1,0,0] op_sel_hi:[0,0,1] neg_lo:[1,0,1] neg_hi:[0,0,1]
	v_pk_add_f32 v[90:91], v[98:99], v[96:97] neg_lo:[0,1] neg_hi:[0,1]
	v_pk_add_f32 v[26:27], v[8:9], v[24:25]
	v_pk_add_f32 v[8:9], v[8:9], v[24:25] neg_lo:[0,1] neg_hi:[0,1]
	v_pk_add_f32 v[24:25], v[98:99], v[96:97]
	v_pk_add_f32 v[96:97], v[94:95], v[92:93]
	v_pk_add_f32 v[92:93], v[94:95], v[92:93] neg_lo:[0,1] neg_hi:[0,1]
	v_pk_add_f32 v[94:95], v[82:83], v[80:81]
	v_pk_add_f32 v[80:81], v[82:83], v[80:81] neg_lo:[0,1] neg_hi:[0,1]
	v_pk_add_f32 v[82:83], v[78:79], v[76:77]
	v_pk_add_f32 v[76:77], v[78:79], v[76:77] neg_lo:[0,1] neg_hi:[0,1]
	v_pk_add_f32 v[98:99], v[10:11], v[0:1]
	v_pk_add_f32 v[0:1], v[10:11], v[0:1] neg_lo:[0,1] neg_hi:[0,1]
	v_pk_add_f32 v[10:11], v[6:7], v[2:3]
	v_pk_add_f32 v[2:3], v[6:7], v[2:3] neg_lo:[0,1] neg_hi:[0,1]
	v_pk_add_f32 v[6:7], v[24:25], v[96:97]
	v_pk_add_f32 v[24:25], v[24:25], v[96:97] neg_lo:[0,1] neg_hi:[0,1]
	v_xor_b32_e32 v96, 0x80000000, v93
	v_mov_b32_e32 v97, v92
	v_pk_add_f32 v[78:79], v[66:67], v[64:65]
	v_pk_add_f32 v[64:65], v[66:67], v[64:65] neg_lo:[0,1] neg_hi:[0,1]
	v_pk_add_f32 v[66:67], v[62:63], v[100:101]
	v_pk_add_f32 v[62:63], v[62:63], v[100:101] neg_lo:[0,1] neg_hi:[0,1]
	v_pk_add_f32 v[92:93], v[90:91], v[96:97]
	v_pk_add_f32 v[90:91], v[90:91], v[96:97] neg_lo:[0,1] neg_hi:[0,1]
	v_pk_add_f32 v[96:97], v[94:95], v[82:83]
	v_pk_add_f32 v[82:83], v[94:95], v[82:83] neg_lo:[0,1] neg_hi:[0,1]
	v_xor_b32_e32 v94, 0x80000000, v77
	v_mov_b32_e32 v95, v76
	v_pk_add_f32 v[76:77], v[80:81], v[94:95]
	v_pk_add_f32 v[80:81], v[80:81], v[94:95] neg_lo:[0,1] neg_hi:[0,1]
	v_pk_add_f32 v[94:95], v[78:79], v[66:67]
	v_pk_add_f32 v[66:67], v[78:79], v[66:67] neg_lo:[0,1] neg_hi:[0,1]
	v_xor_b32_e32 v78, 0x80000000, v63
	v_mov_b32_e32 v79, v62
	v_pk_add_f32 v[62:63], v[64:65], v[78:79]
	v_pk_add_f32 v[64:65], v[64:65], v[78:79] neg_lo:[0,1] neg_hi:[0,1]
	v_pk_add_f32 v[78:79], v[98:99], v[10:11]
	v_pk_add_f32 v[10:11], v[98:99], v[10:11] neg_lo:[0,1] neg_hi:[0,1]
	v_xor_b32_e32 v98, 0x80000000, v3
	v_mov_b32_e32 v99, v2
	v_pk_add_f32 v[2:3], v[0:1], v[98:99]
	v_pk_add_f32 v[0:1], v[0:1], v[98:99] neg_lo:[0,1] neg_hi:[0,1]
	v_pk_add_f32 v[98:99], v[6:7], v[96:97]
	v_pk_add_f32 v[6:7], v[6:7], v[96:97] neg_lo:[0,1] neg_hi:[0,1]
	v_pk_mul_f32 v[96:97], v[76:77], s[60:61] op_sel:[1,0] op_sel_hi:[0,0] neg_lo:[1,0]
	v_xor_b32_e32 v100, 0x80000000, v81
	v_pk_fma_f32 v[76:77], v[76:77], s[60:61], v[96:97] op_sel_hi:[1,0,1]
	v_mov_b32_e32 v101, v80
	v_pk_add_f32 v[96:97], v[92:93], v[76:77]
	v_pk_add_f32 v[76:77], v[92:93], v[76:77] neg_lo:[0,1] neg_hi:[0,1]
	v_xor_b32_e32 v92, 0x80000000, v83
	v_mov_b32_e32 v93, v82
	v_pk_add_f32 v[82:83], v[24:25], v[92:93]
	v_pk_add_f32 v[24:25], v[24:25], v[92:93] neg_lo:[0,1] neg_hi:[0,1]
	v_pk_mul_f32 v[92:93], v[80:81], s[60:61] op_sel_hi:[1,0]
	s_nop 0
	v_pk_fma_f32 v[80:81], v[100:101], s[60:61], v[92:93] op_sel_hi:[1,0,1] neg_lo:[0,0,1] neg_hi:[0,0,1]
	v_xor_b32_e32 v100, 0x80000000, v1
	v_pk_add_f32 v[92:93], v[90:91], v[80:81]
	v_pk_add_f32 v[80:81], v[90:91], v[80:81] neg_lo:[0,1] neg_hi:[0,1]
	v_pk_add_f32 v[90:91], v[94:95], v[78:79]
	v_pk_add_f32 v[78:79], v[94:95], v[78:79] neg_lo:[0,1] neg_hi:[0,1]
	v_pk_mul_f32 v[94:95], v[2:3], s[60:61] op_sel:[1,0] op_sel_hi:[0,0] neg_lo:[1,0]
	v_mov_b32_e32 v101, v0
	v_pk_fma_f32 v[2:3], v[2:3], s[60:61], v[94:95] op_sel_hi:[1,0,1]
	s_nop 0
	v_pk_add_f32 v[94:95], v[62:63], v[2:3]
	v_pk_add_f32 v[2:3], v[62:63], v[2:3] neg_lo:[0,1] neg_hi:[0,1]
	v_xor_b32_e32 v62, 0x80000000, v11
	v_mov_b32_e32 v63, v10
	v_pk_add_f32 v[10:11], v[66:67], v[62:63]
	v_pk_add_f32 v[62:63], v[66:67], v[62:63] neg_lo:[0,1] neg_hi:[0,1]
	v_pk_mul_f32 v[66:67], v[0:1], s[60:61] op_sel_hi:[1,0]
	s_nop 0
	v_pk_fma_f32 v[0:1], v[100:101], s[60:61], v[66:67] op_sel_hi:[1,0,1] neg_lo:[0,0,1] neg_hi:[0,0,1]
	v_xor_b32_e32 v100, 0x80000000, v3
	v_pk_add_f32 v[66:67], v[64:65], v[0:1]
	v_pk_add_f32 v[0:1], v[64:65], v[0:1] neg_lo:[0,1] neg_hi:[0,1]
	v_pk_add_f32 v[64:65], v[98:99], v[90:91]
	v_pk_add_f32 v[90:91], v[98:99], v[90:91] neg_lo:[0,1] neg_hi:[0,1]
	v_pk_mul_f32 v[98:99], v[94:95], s[54:55] op_sel:[1,0] op_sel_hi:[0,0] neg_lo:[1,0]
	v_mov_b32_e32 v101, v2
	v_pk_fma_f32 v[94:95], v[94:95], s[52:53], v[98:99] op_sel_hi:[1,0,1]
	s_nop 0
	v_pk_add_f32 v[98:99], v[96:97], v[94:95]
	v_pk_add_f32 v[94:95], v[96:97], v[94:95] neg_lo:[0,1] neg_hi:[0,1]
	v_pk_mul_f32 v[96:97], v[10:11], s[60:61] op_sel:[1,0] op_sel_hi:[0,0] neg_lo:[1,0]
	s_nop 0
	v_pk_fma_f32 v[10:11], v[10:11], s[60:61], v[96:97] op_sel_hi:[1,0,1]
	s_nop 0
	v_pk_add_f32 v[96:97], v[82:83], v[10:11]
	v_pk_add_f32 v[10:11], v[82:83], v[10:11] neg_lo:[0,1] neg_hi:[0,1]
	v_pk_mul_f32 v[82:83], v[66:67], s[52:53] op_sel:[1,0] op_sel_hi:[0,0] neg_lo:[1,0]
	s_nop 0
	v_pk_fma_f32 v[66:67], v[66:67], s[54:55], v[82:83] op_sel_hi:[1,0,1]
	s_nop 0
	v_pk_add_f32 v[82:83], v[92:93], v[66:67]
	v_pk_add_f32 v[66:67], v[92:93], v[66:67] neg_lo:[0,1] neg_hi:[0,1]
	v_xor_b32_e32 v92, 0x80000000, v79
	v_mov_b32_e32 v93, v78
	v_pk_add_f32 v[78:79], v[6:7], v[92:93]
	v_pk_add_f32 v[6:7], v[6:7], v[92:93] neg_lo:[0,1] neg_hi:[0,1]
	v_pk_mul_f32 v[92:93], v[2:3], s[54:55] op_sel_hi:[1,0]
	s_nop 0
	v_pk_fma_f32 v[2:3], v[100:101], s[52:53], v[92:93] op_sel_hi:[1,0,1] neg_lo:[0,0,1] neg_hi:[0,0,1]
	v_xor_b32_e32 v100, 0x80000000, v63
	v_pk_add_f32 v[92:93], v[76:77], v[2:3]
	v_pk_add_f32 v[2:3], v[76:77], v[2:3] neg_lo:[0,1] neg_hi:[0,1]
	v_pk_mul_f32 v[76:77], v[62:63], s[60:61] op_sel_hi:[1,0]
	v_mov_b32_e32 v101, v62
	v_pk_fma_f32 v[62:63], v[100:101], s[60:61], v[76:77] op_sel_hi:[1,0,1] neg_lo:[0,0,1] neg_hi:[0,0,1]
	v_xor_b32_e32 v100, 0x80000000, v1
	v_pk_add_f32 v[76:77], v[24:25], v[62:63]
	v_pk_add_f32 v[24:25], v[24:25], v[62:63] neg_lo:[0,1] neg_hi:[0,1]
	v_pk_mul_f32 v[62:63], v[0:1], s[52:53] op_sel_hi:[1,0]
	v_mov_b32_e32 v101, v0
	v_pk_fma_f32 v[0:1], v[100:101], s[54:55], v[62:63] op_sel_hi:[1,0,1] neg_lo:[0,0,1] neg_hi:[0,0,1]
	v_bfe_u32 v100, v102, 1, 4
	v_pk_add_f32 v[62:63], v[80:81], v[0:1]
	v_pk_add_f32 v[0:1], v[80:81], v[0:1] neg_lo:[0,1] neg_hi:[0,1]
	v_lshlrev_b32_e32 v80, 4, v102
	v_lshrrev_b32_e32 v81, 1, v102
	v_bitop3_b32 v101, v81, v80, 16 bitop3:0x6c
	v_lshl_add_u32 v101, v101, 3, 16
	v_lshlrev_b32_e32 v100, 3, v100
	v_add_u32_e32 v102, v101, v100
	ds_write_b64 v102, v[70:71]
	v_bitop3_b32 v70, v81, 1, 15 bitop3:0x6c
	v_lshlrev_b32_e32 v70, 3, v70
	v_add_u32_e32 v71, v101, v70
	ds_write_b64 v71, v[86:87]
	v_bitop3_b32 v71, v81, 2, 15 bitop3:0x6c
	v_lshlrev_b32_e32 v71, 3, v71
	v_add_u32_e32 v86, v101, v71
	ds_write_b64 v86, v[88:89]
	v_bitop3_b32 v86, v81, 3, 15 bitop3:0x6c
	v_lshlrev_b32_e32 v86, 3, v86
	v_add_u32_e32 v87, v101, v86
	ds_write_b64 v87, v[74:75]
	v_bitop3_b32 v74, v81, 4, 15 bitop3:0x6c
	v_lshlrev_b32_e32 v74, 3, v74
	v_add_u32_e32 v75, v101, v74
	ds_write_b64 v75, v[20:21]
	v_bitop3_b32 v20, v81, 5, 15 bitop3:0x6c
	v_lshlrev_b32_e32 v20, 3, v20
	v_add_u32_e32 v21, v101, v20
	ds_write_b64 v21, v[72:73]
	v_bitop3_b32 v21, v81, 6, 15 bitop3:0x6c
	v_lshlrev_b32_e32 v21, 3, v21
	v_add_u32_e32 v72, v101, v21
	ds_write_b64 v72, v[68:69]
	v_bitop3_b32 v68, v81, 7, 15 bitop3:0x6c
	v_lshlrev_b32_e32 v68, 3, v68
	v_add_u32_e32 v69, v101, v68
	ds_write_b64 v69, v[26:27]
	v_bitop3_b32 v26, v81, 8, 15 bitop3:0x6c
	v_lshlrev_b32_e32 v26, 3, v26
	v_add_u32_e32 v27, v101, v26
	ds_write_b64 v27, v[18:19]
	v_bitop3_b32 v18, v81, 9, 15 bitop3:0x6c
	v_lshlrev_b32_e32 v18, 3, v18
	v_add_u32_e32 v19, v101, v18
	ds_write_b64 v19, v[84:85]
	v_bitop3_b32 v19, v81, 10, 15 bitop3:0x6c
	v_lshlrev_b32_e32 v19, 3, v19
	v_add_u32_e32 v27, v101, v19
	ds_write_b64 v27, v[16:17]
	v_bitop3_b32 v16, v81, 11, 15 bitop3:0x6c
	v_lshlrev_b32_e32 v16, 3, v16
	v_add_u32_e32 v17, v101, v16
	ds_write_b64 v17, v[22:23]
	v_bitop3_b32 v17, v81, 12, 15 bitop3:0x6c
	v_lshlrev_b32_e32 v17, 3, v17
	v_add_u32_e32 v22, v101, v17
	ds_write_b64 v22, v[12:13]
	v_bitop3_b32 v12, v81, 13, 15 bitop3:0x6c
	v_lshlrev_b32_e32 v12, 3, v12
	v_add_u32_e32 v13, v101, v12
	ds_write_b64 v13, v[14:15]
	v_bitop3_b32 v13, v81, 14, 15 bitop3:0x6c
	v_lshlrev_b32_e32 v13, 3, v13
	v_add_u32_e32 v14, v101, v13
	ds_write_b64 v14, v[4:5]
	v_bitop3_b32 v4, v81, 15, v81 bitop3:0xc
	v_lshlrev_b32_e32 v4, 3, v4
	v_add_u32_e32 v5, v101, v4
	ds_write_b64 v5, v[8:9]
	v_add_u32_e32 v5, 0x2000, v80
	v_bitop3_b32 v5, v5, v81, 16 bitop3:0x78
	v_lshl_add_u32 v5, v5, 3, 16
	v_add_u32_e32 v8, v5, v100
	ds_write_b64 v8, v[64:65]
	v_add_u32_e32 v8, v5, v70
	ds_write_b64 v8, v[98:99]
	v_add_u32_e32 v8, v5, v71
	ds_write_b64 v8, v[96:97]
	v_add_u32_e32 v8, v5, v86
	ds_write_b64 v8, v[82:83]
	v_add_u32_e32 v8, v5, v74
	ds_write_b64 v8, v[78:79]
	v_add_u32_e32 v8, v5, v20
	ds_write_b64 v8, v[92:93]
	v_add_u32_e32 v8, v5, v21
	ds_write_b64 v8, v[76:77]
	v_add_u32_e32 v8, v5, v68
	ds_write_b64 v8, v[62:63]
	v_add_u32_e32 v8, v5, v26
	ds_write_b64 v8, v[90:91]
	v_add_u32_e32 v8, v5, v18
	ds_write_b64 v8, v[94:95]
	v_add_u32_e32 v8, v5, v19
	ds_write_b64 v8, v[10:11]
	v_add_u32_e32 v8, v5, v16
	ds_write_b64 v8, v[66:67]
	v_add_u32_e32 v8, v5, v17
	ds_write_b64 v8, v[6:7]
	v_add_u32_e32 v6, v5, v12
	ds_write_b64 v6, v[2:3]
	v_add_u32_e32 v2, v5, v13
	ds_write_b64 v2, v[24:25]
	v_add_u32_e32 v2, v5, v4
	v_mov_b32_e32 v22, v146
	ds_write_b64 v2, v[0:1]
	s_waitcnt lgkmcnt(0)
	s_barrier
	s_nop 0
	v_lshlrev_b32_e32 v0, 5, v22
	v_and_b32_e32 v2, 0xfffffe00, v0
	v_and_or_b32 v0, v22, 16, v2
	v_bitop3_b32 v2, v2, 16, v22 bitop3:0x34
	v_bitop3_b32 v6, v22, 4, 15 bitop3:0x6c
	v_bitop3_b32 v14, v22, 8, 15 bitop3:0x6c
	v_lshl_add_u32 v23, v0, 3, 16
	v_lshl_add_u32 v65, v2, 3, 16
	v_lshlrev_b32_e32 v6, 3, v6
	v_lshlrev_b32_e32 v14, 3, v14
	v_bitop3_b32 v2, v22, 1, 15 bitop3:0x6c
	v_add_u32_e32 v105, v23, v6
	v_add_u32_e32 v106, v65, v6
	v_bitop3_b32 v6, v22, 5, 15 bitop3:0x6c
	v_add_u32_e32 v113, v23, v14
	v_add_u32_e32 v114, v65, v14
	v_bitop3_b32 v14, v22, 9, 15 bitop3:0x6c
	v_lshlrev_b32_e32 v2, 3, v2
	v_lshlrev_b32_e32 v6, 3, v6
	v_lshlrev_b32_e32 v14, 3, v14
	v_add_u32_e32 v99, v23, v2
	v_add_u32_e32 v100, v65, v2
	v_bitop3_b32 v2, v22, 2, 15 bitop3:0x6c
	v_add_u32_e32 v107, v23, v6
	v_add_u32_e32 v108, v65, v6
	v_bitop3_b32 v6, v22, 6, 15 bitop3:0x6c
	v_add_u32_e32 v115, v23, v14
	v_add_u32_e32 v116, v65, v14
	v_bitop3_b32 v14, v22, 10, 15 bitop3:0x6c
	v_bitop3_b32 v26, v22, 12, 15 bitop3:0x6c
	v_lshlrev_b32_e32 v2, 3, v2
	v_lshlrev_b32_e32 v6, 3, v6
	v_lshlrev_b32_e32 v14, 3, v14
	v_lshlrev_b32_e32 v26, 3, v26
	v_and_b32_e32 v64, 15, v22
	v_add_u32_e32 v101, v23, v2
	v_add_u32_e32 v102, v65, v2
	v_bitop3_b32 v2, v22, 3, 15 bitop3:0x6c
	v_add_u32_e32 v109, v23, v6
	v_add_u32_e32 v110, v65, v6
	v_bitop3_b32 v6, v22, 7, 15 bitop3:0x6c
	v_add_u32_e32 v117, v23, v14
	v_add_u32_e32 v118, v65, v14
	v_bitop3_b32 v14, v22, 11, 15 bitop3:0x6c
	v_add_u32_e32 v121, v23, v26
	v_add_u32_e32 v122, v65, v26
	v_bitop3_b32 v26, v22, 13, 15 bitop3:0x6c
	v_bitop3_b32 v66, v22, 14, 15 bitop3:0x6c
	v_bitop3_b32 v22, v22, 15, v22 bitop3:0xc
	v_lshlrev_b32_e32 v3, 3, v64
	v_lshlrev_b32_e32 v2, 3, v2
	v_lshlrev_b32_e32 v6, 3, v6
	v_lshlrev_b32_e32 v14, 3, v14
	v_lshlrev_b32_e32 v26, 3, v26
	v_lshlrev_b32_e32 v66, 3, v66
	v_lshlrev_b32_e32 v22, 3, v22
	v_add_u32_e32 v67, v23, v3
	v_add_u32_e32 v98, v65, v3
	v_add_u32_e32 v103, v23, v2
	v_add_u32_e32 v104, v65, v2
	v_add_u32_e32 v111, v23, v6
	v_add_u32_e32 v112, v65, v6
	v_add_u32_e32 v119, v23, v14
	v_add_u32_e32 v120, v65, v14
	v_add_u32_e32 v123, v23, v26
	v_add_u32_e32 v124, v65, v26
	v_add_u32_e32 v125, v23, v66
	v_add_u32_e32 v126, v65, v66
	v_add_u32_e32 v127, v23, v22
	v_add_u32_e32 v128, v65, v22
	ds_read_b64 v[0:1], v67
	ds_read_b64 v[12:13], v98
	ds_read_b64 v[74:75], v99 offset:256
	ds_read_b64 v[4:5], v100 offset:256
	ds_read_b64 v[76:77], v101 offset:512
	ds_read_b64 v[10:11], v102 offset:512
	ds_read_b64 v[70:71], v103 offset:768
	ds_read_b64 v[2:3], v104 offset:768
	ds_read_b64 v[62:63], v105 offset:1024
	ds_read_b64 v[20:21], v106 offset:1024
	ds_read_b64 v[90:91], v107 offset:1280
	ds_read_b64 v[8:9], v108 offset:1280
	ds_read_b64 v[84:85], v109 offset:1536
	ds_read_b64 v[16:17], v110 offset:1536
	ds_read_b64 v[82:83], v111 offset:1792
	ds_read_b64 v[6:7], v112 offset:1792
	ds_read_b64 v[24:25], v113 offset:2048
	ds_read_b64 v[78:79], v114 offset:2048
	ds_read_b64 v[96:97], v115 offset:2304
	ds_read_b64 v[18:19], v116 offset:2304
	ds_read_b64 v[86:87], v117 offset:2560
	ds_read_b64 v[72:73], v118 offset:2560
	ds_read_b64 v[130:131], v119 offset:2816
	ds_read_b64 v[14:15], v120 offset:2816
	ds_read_b64 v[80:81], v121 offset:3072
	ds_read_b64 v[92:93], v122 offset:3072
	ds_read_b64 v[132:133], v123 offset:3328
	ds_read_b64 v[26:27], v124 offset:3328
	ds_read_b64 v[94:95], v125 offset:3584
	ds_read_b64 v[88:89], v126 offset:3584
	ds_read_b64 v[134:135], v127 offset:3840
	ds_read_b64 v[22:23], v128 offset:3840
	s_waitcnt lgkmcnt(14)
	s_nop 0
	v_cvt_f32_i32_e32 v64, v64
	s_nop 0
	v_mul_f32_e32 v64, 0x3b000000, v64
	v_cos_f32_e32 v68, v64
	v_sin_f32_e32 v69, v64
	v_add_f32_e32 v66, v68, v68
	v_pk_mul_f32 v[64:65], v[68:69], v[68:69]
	v_mul_f32_e32 v66, v69, v66
	s_nop 0
	s_nop 0
	v_mov_b32_e32 v140, v69
	v_pk_add_f32 v[64:65], v[64:65], v[64:65] op_sel:[0,1] op_sel_hi:[0,1] neg_lo:[0,1] neg_hi:[0,1]
	v_pk_mul_f32 v[136:137], v[68:69], v[66:67] op_sel:[1,0] op_sel_hi:[0,0] neg_lo:[1,0]
	v_pk_mul_f32 v[138:139], v[24:25], v[140:141] op_sel:[1,0] op_sel_hi:[0,0] neg_lo:[1,0]
	v_pk_fma_f32 v[136:137], v[68:69], v[64:65], v[136:137]
	v_pk_fma_f32 v[24:25], v[24:25], v[68:69], v[138:139] op_sel_hi:[1,0,1]
	v_pk_mul_f32 v[68:69], v[66:67], s[46:47] op_sel_hi:[0,1]
	v_pk_fma_f32 v[138:139], v[64:65], s[40:41], v[68:69]
	s_nop 0
	v_pk_mul_f32 v[68:69], v[62:63], v[138:139] op_sel:[1,1] op_sel_hi:[0,1] neg_lo:[1,0]
	s_nop 0
	v_pk_fma_f32 v[68:69], v[62:63], v[138:139], v[68:69] op_sel_hi:[1,0,1]
	v_pk_mul_f32 v[62:63], v[66:67], v[136:137] op_sel:[0,1] op_sel_hi:[0,0] neg_lo:[0,1]
	v_pk_fma_f32 v[140:141], v[64:65], v[136:137], v[62:63]
	s_waitcnt lgkmcnt(7)
	v_pk_mul_f32 v[62:63], v[80:81], v[136:137] op_sel:[1,1] op_sel_hi:[0,1] neg_lo:[1,0]
	s_nop 0
	v_pk_fma_f32 v[62:63], v[80:81], v[136:137], v[62:63] op_sel_hi:[1,0,1]
	v_pk_mul_f32 v[80:81], v[66:67], v[138:139] op_sel:[0,1] op_sel_hi:[0,0] neg_lo:[0,1]
	v_pk_fma_f32 v[136:137], v[64:65], v[138:139], v[80:81]
	s_nop 0
	v_pk_mul_f32 v[80:81], v[76:77], v[136:137] op_sel:[1,1] op_sel_hi:[0,1] neg_lo:[1,0]
	s_nop 0
	v_pk_fma_f32 v[80:81], v[76:77], v[136:137], v[80:81] op_sel_hi:[1,0,1]
	v_pk_mul_f32 v[76:77], v[66:67], v[140:141] op_sel:[0,1] op_sel_hi:[0,0] neg_lo:[0,1]
	v_pk_fma_f32 v[138:139], v[64:65], v[140:141], v[76:77]
	v_pk_mul_f32 v[76:77], v[86:87], v[140:141] op_sel:[1,1] op_sel_hi:[0,1] neg_lo:[1,0]
	s_nop 0
	v_pk_fma_f32 v[76:77], v[86:87], v[140:141], v[76:77] op_sel_hi:[1,0,1]
	v_pk_mul_f32 v[86:87], v[66:67], v[136:137] op_sel:[0,1] op_sel_hi:[0,0] neg_lo:[0,1]
	v_pk_fma_f32 v[136:137], v[64:65], v[136:137], v[86:87]
	s_nop 0
	v_pk_mul_f32 v[86:87], v[84:85], v[136:137] op_sel:[1,1] op_sel_hi:[0,1] neg_lo:[1,0]
	s_nop 0
	v_pk_fma_f32 v[86:87], v[84:85], v[136:137], v[86:87] op_sel_hi:[1,0,1]
	v_pk_mul_f32 v[84:85], v[66:67], v[138:139] op_sel:[0,1] op_sel_hi:[0,0] neg_lo:[0,1]
	v_pk_fma_f32 v[140:141], v[64:65], v[138:139], v[84:85]
	s_waitcnt lgkmcnt(3)
	v_pk_mul_f32 v[84:85], v[94:95], v[138:139] op_sel:[1,1] op_sel_hi:[0,1] neg_lo:[1,0]
	s_nop 0
	v_pk_fma_f32 v[84:85], v[94:95], v[138:139], v[84:85] op_sel_hi:[1,0,1]
	v_pk_mul_f32 v[94:95], v[66:67], v[136:137] op_sel:[0,1] op_sel_hi:[0,0] neg_lo:[0,1]
	v_pk_fma_f32 v[136:137], v[64:65], v[136:137], v[94:95]
	s_nop 0
	v_pk_mul_f32 v[94:95], v[74:75], v[136:137] op_sel:[1,1] op_sel_hi:[0,1] neg_lo:[1,0]
	s_nop 0
	v_pk_fma_f32 v[94:95], v[74:75], v[136:137], v[94:95] op_sel_hi:[1,0,1]
	v_pk_mul_f32 v[74:75], v[66:67], v[140:141] op_sel:[0,1] op_sel_hi:[0,0] neg_lo:[0,1]
	v_pk_fma_f32 v[138:139], v[64:65], v[140:141], v[74:75]
	v_pk_mul_f32 v[74:75], v[96:97], v[140:141] op_sel:[1,1] op_sel_hi:[0,1] neg_lo:[1,0]
	s_nop 0
	v_pk_fma_f32 v[74:75], v[96:97], v[140:141], v[74:75] op_sel_hi:[1,0,1]
	v_pk_mul_f32 v[96:97], v[66:67], v[136:137] op_sel:[0,1] op_sel_hi:[0,0] neg_lo:[0,1]
	v_pk_fma_f32 v[136:137], v[64:65], v[136:137], v[96:97]
	s_nop 0
	v_pk_mul_f32 v[96:97], v[90:91], v[136:137] op_sel:[1,1] op_sel_hi:[0,1] neg_lo:[1,0]
	s_nop 0
	v_pk_fma_f32 v[96:97], v[90:91], v[136:137], v[96:97] op_sel_hi:[1,0,1]
	v_pk_mul_f32 v[90:91], v[66:67], v[138:139] op_sel:[0,1] op_sel_hi:[0,0] neg_lo:[0,1]
	v_pk_fma_f32 v[140:141], v[64:65], v[138:139], v[90:91]
	v_pk_mul_f32 v[90:91], v[132:133], v[138:139] op_sel:[1,1] op_sel_hi:[0,1] neg_lo:[1,0]
	s_nop 0
	v_pk_fma_f32 v[90:91], v[132:133], v[138:139], v[90:91] op_sel_hi:[1,0,1]
	v_pk_mul_f32 v[132:133], v[66:67], v[136:137] op_sel:[0,1] op_sel_hi:[0,0] neg_lo:[0,1]
	s_nop 0
	v_pk_fma_f32 v[132:133], v[64:65], v[136:137], v[132:133]
	v_pk_mul_f32 v[138:139], v[130:131], v[140:141] op_sel:[1,1] op_sel_hi:[0,1] neg_lo:[1,0]
	v_pk_mul_f32 v[136:137], v[70:71], v[132:133] op_sel:[1,1] op_sel_hi:[0,1] neg_lo:[1,0]
	v_pk_fma_f32 v[130:131], v[130:131], v[140:141], v[138:139] op_sel_hi:[1,0,1]
	v_pk_fma_f32 v[70:71], v[70:71], v[132:133], v[136:137] op_sel_hi:[1,0,1]
	v_pk_mul_f32 v[138:139], v[66:67], v[132:133] op_sel:[0,1] op_sel_hi:[0,0] neg_lo:[0,1]
	v_pk_mul_f32 v[136:137], v[66:67], v[140:141] op_sel:[0,1] op_sel_hi:[0,0] neg_lo:[0,1]
	v_pk_fma_f32 v[132:133], v[64:65], v[132:133], v[138:139]
	v_pk_fma_f32 v[136:137], v[64:65], v[140:141], v[136:137]
	v_pk_mul_f32 v[138:139], v[82:83], v[132:133] op_sel:[1,1] op_sel_hi:[0,1] neg_lo:[1,0]
	s_waitcnt lgkmcnt(1)
	v_pk_fma_f32 v[82:83], v[82:83], v[132:133], v[138:139] op_sel_hi:[1,0,1]
	v_pk_mul_f32 v[138:139], v[66:67], v[136:137] op_sel:[0,1] op_sel_hi:[0,0] neg_lo:[0,1]
	v_pk_mul_f32 v[140:141], v[134:135], v[136:137] op_sel:[1,1] op_sel_hi:[0,1] neg_lo:[1,0]
	v_pk_fma_f32 v[138:139], v[64:65], v[136:137], v[138:139]
	v_pk_fma_f32 v[134:135], v[134:135], v[136:137], v[140:141] op_sel_hi:[1,0,1]
	v_pk_mul_f32 v[136:137], v[66:67], v[132:133] op_sel:[0,1] op_sel_hi:[0,0] neg_lo:[0,1]
	v_pk_fma_f32 v[132:133], v[64:65], v[132:133], v[136:137]
	s_nop 0
	v_pk_mul_f32 v[136:137], v[12:13], v[132:133] op_sel:[1,1] op_sel_hi:[0,1] neg_lo:[1,0]
	s_nop 0
	v_pk_fma_f32 v[12:13], v[12:13], v[132:133], v[136:137] op_sel_hi:[1,0,1]
	v_pk_mul_f32 v[136:137], v[66:67], v[138:139] op_sel:[0,1] op_sel_hi:[0,0] neg_lo:[0,1]
	v_pk_mul_f32 v[140:141], v[78:79], v[138:139] op_sel:[1,1] op_sel_hi:[0,1] neg_lo:[1,0]
	v_pk_fma_f32 v[136:137], v[64:65], v[138:139], v[136:137]
	v_pk_fma_f32 v[78:79], v[78:79], v[138:139], v[140:141] op_sel_hi:[1,0,1]
	v_pk_mul_f32 v[138:139], v[66:67], v[132:133] op_sel:[0,1] op_sel_hi:[0,0] neg_lo:[0,1]
	v_pk_fma_f32 v[132:133], v[64:65], v[132:133], v[138:139]
	s_nop 0
	v_pk_mul_f32 v[138:139], v[20:21], v[132:133] op_sel:[1,1] op_sel_hi:[0,1] neg_lo:[1,0]
	s_nop 0
	v_pk_fma_f32 v[20:21], v[20:21], v[132:133], v[138:139] op_sel_hi:[1,0,1]
	v_pk_mul_f32 v[138:139], v[66:67], v[136:137] op_sel:[0,1] op_sel_hi:[0,0] neg_lo:[0,1]
	v_pk_mul_f32 v[140:141], v[92:93], v[136:137] op_sel:[1,1] op_sel_hi:[0,1] neg_lo:[1,0]
	v_pk_fma_f32 v[138:139], v[64:65], v[136:137], v[138:139]
	v_pk_fma_f32 v[92:93], v[92:93], v[136:137], v[140:141] op_sel_hi:[1,0,1]
	v_pk_mul_f32 v[136:137], v[66:67], v[132:133] op_sel:[0,1] op_sel_hi:[0,0] neg_lo:[0,1]
	v_pk_fma_f32 v[132:133], v[64:65], v[132:133], v[136:137]
	s_nop 0
	v_pk_mul_f32 v[136:137], v[10:11], v[132:133] op_sel:[1,1] op_sel_hi:[0,1] neg_lo:[1,0]
	s_nop 0
	v_pk_fma_f32 v[10:11], v[10:11], v[132:133], v[136:137] op_sel_hi:[1,0,1]
	v_pk_mul_f32 v[136:137], v[66:67], v[138:139] op_sel:[0,1] op_sel_hi:[0,0] neg_lo:[0,1]
	v_pk_mul_f32 v[140:141], v[72:73], v[138:139] op_sel:[1,1] op_sel_hi:[0,1] neg_lo:[1,0]
	v_pk_fma_f32 v[136:137], v[64:65], v[138:139], v[136:137]
	v_pk_fma_f32 v[72:73], v[72:73], v[138:139], v[140:141] op_sel_hi:[1,0,1]
	v_pk_mul_f32 v[138:139], v[66:67], v[132:133] op_sel:[0,1] op_sel_hi:[0,0] neg_lo:[0,1]
	v_pk_fma_f32 v[132:133], v[64:65], v[132:133], v[138:139]
	s_nop 0
	v_pk_mul_f32 v[138:139], v[16:17], v[132:133] op_sel:[1,1] op_sel_hi:[0,1] neg_lo:[1,0]
	s_nop 0
	v_pk_fma_f32 v[16:17], v[16:17], v[132:133], v[138:139] op_sel_hi:[1,0,1]
	v_pk_mul_f32 v[138:139], v[66:67], v[136:137] op_sel:[0,1] op_sel_hi:[0,0] neg_lo:[0,1]
	v_pk_mul_f32 v[140:141], v[88:89], v[136:137] op_sel:[1,1] op_sel_hi:[0,1] neg_lo:[1,0]
	v_pk_fma_f32 v[138:139], v[64:65], v[136:137], v[138:139]
	v_pk_fma_f32 v[88:89], v[88:89], v[136:137], v[140:141] op_sel_hi:[1,0,1]
	v_pk_mul_f32 v[136:137], v[66:67], v[132:133] op_sel:[0,1] op_sel_hi:[0,0] neg_lo:[0,1]
	v_pk_fma_f32 v[132:133], v[64:65], v[132:133], v[136:137]
	s_nop 0
	v_pk_mul_f32 v[136:137], v[4:5], v[132:133] op_sel:[1,1] op_sel_hi:[0,1] neg_lo:[1,0]
	s_nop 0
	v_pk_fma_f32 v[4:5], v[4:5], v[132:133], v[136:137] op_sel_hi:[1,0,1]
	v_pk_mul_f32 v[136:137], v[66:67], v[138:139] op_sel:[0,1] op_sel_hi:[0,0] neg_lo:[0,1]
	v_pk_mul_f32 v[140:141], v[18:19], v[138:139] op_sel:[1,1] op_sel_hi:[0,1] neg_lo:[1,0]
	v_pk_fma_f32 v[136:137], v[64:65], v[138:139], v[136:137]
	v_pk_fma_f32 v[18:19], v[18:19], v[138:139], v[140:141] op_sel_hi:[1,0,1]
	v_pk_mul_f32 v[138:139], v[66:67], v[132:133] op_sel:[0,1] op_sel_hi:[0,0] neg_lo:[0,1]
	v_pk_fma_f32 v[132:133], v[64:65], v[132:133], v[138:139]
	s_nop 0
	v_pk_mul_f32 v[138:139], v[8:9], v[132:133] op_sel:[1,1] op_sel_hi:[0,1] neg_lo:[1,0]
	s_nop 0
	v_pk_fma_f32 v[8:9], v[8:9], v[132:133], v[138:139] op_sel_hi:[1,0,1]
	v_pk_mul_f32 v[138:139], v[66:67], v[136:137] op_sel:[0,1] op_sel_hi:[0,0] neg_lo:[0,1]
	v_pk_mul_f32 v[140:141], v[26:27], v[136:137] op_sel:[1,1] op_sel_hi:[0,1] neg_lo:[1,0]
	v_pk_fma_f32 v[138:139], v[64:65], v[136:137], v[138:139]
	v_pk_fma_f32 v[26:27], v[26:27], v[136:137], v[140:141] op_sel_hi:[1,0,1]
	v_pk_mul_f32 v[136:137], v[66:67], v[132:133] op_sel:[0,1] op_sel_hi:[0,0] neg_lo:[0,1]
	v_pk_fma_f32 v[132:133], v[64:65], v[132:133], v[136:137]
	s_nop 0
	v_pk_mul_f32 v[136:137], v[2:3], v[132:133] op_sel:[1,1] op_sel_hi:[0,1] neg_lo:[1,0]
	s_nop 0
	v_pk_fma_f32 v[2:3], v[2:3], v[132:133], v[136:137] op_sel_hi:[1,0,1]
	v_pk_mul_f32 v[136:137], v[66:67], v[138:139] op_sel:[0,1] op_sel_hi:[0,0] neg_lo:[0,1]
	v_pk_mul_f32 v[140:141], v[14:15], v[138:139] op_sel:[1,1] op_sel_hi:[0,1] neg_lo:[1,0]
	v_pk_fma_f32 v[136:137], v[64:65], v[138:139], v[136:137]
	v_pk_fma_f32 v[14:15], v[14:15], v[138:139], v[140:141] op_sel_hi:[1,0,1]
	v_pk_mul_f32 v[138:139], v[66:67], v[132:133] op_sel:[0,1] op_sel_hi:[0,0] neg_lo:[0,1]
	v_pk_fma_f32 v[64:65], v[64:65], v[132:133], v[138:139]
	s_nop 0
	v_pk_mul_f32 v[132:133], v[6:7], v[64:65] op_sel:[1,1] op_sel_hi:[0,1] neg_lo:[1,0]
	s_nop 0
	v_pk_fma_f32 v[6:7], v[6:7], v[64:65], v[132:133] op_sel_hi:[1,0,1]
	s_waitcnt lgkmcnt(0)
	v_pk_mul_f32 v[64:65], v[22:23], v[136:137] op_sel:[1,1] op_sel_hi:[0,1] neg_lo:[1,0]
	s_nop 0
	v_pk_fma_f32 v[22:23], v[22:23], v[136:137], v[64:65] op_sel_hi:[1,0,1]
	v_pk_add_f32 v[64:65], v[0:1], v[12:13]
	v_pk_add_f32 v[0:1], v[0:1], v[12:13] neg_lo:[0,1] neg_hi:[0,1]
	v_pk_add_f32 v[12:13], v[94:95], v[4:5]
	v_pk_add_f32 v[4:5], v[94:95], v[4:5] neg_lo:[0,1] neg_hi:[0,1]
	v_pk_add_f32 v[94:95], v[80:81], v[10:11]
	v_pk_add_f32 v[10:11], v[80:81], v[10:11] neg_lo:[0,1] neg_hi:[0,1]
	v_pk_add_f32 v[80:81], v[70:71], v[2:3]
	v_pk_add_f32 v[2:3], v[70:71], v[2:3] neg_lo:[0,1] neg_hi:[0,1]
	v_pk_add_f32 v[132:133], v[64:65], v[12:13]
	v_pk_add_f32 v[12:13], v[64:65], v[12:13] neg_lo:[0,1] neg_hi:[0,1]
	v_xor_b32_e32 v64, 0x80000000, v5
	v_mov_b32_e32 v65, v4
	v_pk_add_f32 v[70:71], v[68:69], v[20:21]
	v_pk_add_f32 v[20:21], v[68:69], v[20:21] neg_lo:[0,1] neg_hi:[0,1]
	v_pk_add_f32 v[68:69], v[96:97], v[8:9]
	v_pk_add_f32 v[8:9], v[96:97], v[8:9] neg_lo:[0,1] neg_hi:[0,1]
	v_pk_add_f32 v[4:5], v[0:1], v[64:65]
	v_pk_add_f32 v[0:1], v[0:1], v[64:65] neg_lo:[0,1] neg_hi:[0,1]
	v_pk_add_f32 v[64:65], v[94:95], v[80:81]
	v_pk_add_f32 v[80:81], v[94:95], v[80:81] neg_lo:[0,1] neg_hi:[0,1]
	v_xor_b32_e32 v94, 0x80000000, v3
	v_mov_b32_e32 v95, v2
	v_pk_add_f32 v[96:97], v[86:87], v[16:17]
	v_pk_add_f32 v[16:17], v[86:87], v[16:17] neg_lo:[0,1] neg_hi:[0,1]
	v_pk_add_f32 v[86:87], v[82:83], v[6:7]
	v_pk_add_f32 v[6:7], v[82:83], v[6:7] neg_lo:[0,1] neg_hi:[0,1]
	v_pk_add_f32 v[2:3], v[10:11], v[94:95]
	v_pk_add_f32 v[10:11], v[10:11], v[94:95] neg_lo:[0,1] neg_hi:[0,1]
	v_pk_add_f32 v[94:95], v[70:71], v[68:69]
	v_pk_add_f32 v[68:69], v[70:71], v[68:69] neg_lo:[0,1] neg_hi:[0,1]
	v_xor_b32_e32 v70, 0x80000000, v9
	v_mov_b32_e32 v71, v8
	v_pk_add_f32 v[82:83], v[24:25], v[78:79]
	v_pk_add_f32 v[24:25], v[24:25], v[78:79] neg_lo:[0,1] neg_hi:[0,1]
	v_pk_add_f32 v[78:79], v[74:75], v[18:19]
	v_pk_add_f32 v[18:19], v[74:75], v[18:19] neg_lo:[0,1] neg_hi:[0,1]
	v_pk_add_f32 v[8:9], v[20:21], v[70:71]
	v_pk_add_f32 v[20:21], v[20:21], v[70:71] neg_lo:[0,1] neg_hi:[0,1]
	v_pk_add_f32 v[70:71], v[96:97], v[86:87]
	v_pk_add_f32 v[86:87], v[96:97], v[86:87] neg_lo:[0,1] neg_hi:[0,1]
	v_xor_b32_e32 v96, 0x80000000, v7
	v_mov_b32_e32 v97, v6
	v_pk_add_f32 v[74:75], v[76:77], v[72:73]
	v_pk_add_f32 v[72:73], v[76:77], v[72:73] neg_lo:[0,1] neg_hi:[0,1]
	v_pk_add_f32 v[76:77], v[130:131], v[14:15]
	v_pk_add_f32 v[14:15], v[130:131], v[14:15] neg_lo:[0,1] neg_hi:[0,1]
	v_pk_add_f32 v[6:7], v[16:17], v[96:97]
	v_pk_add_f32 v[16:17], v[16:17], v[96:97] neg_lo:[0,1] neg_hi:[0,1]
	v_pk_add_f32 v[96:97], v[82:83], v[78:79]
	v_pk_add_f32 v[78:79], v[82:83], v[78:79] neg_lo:[0,1] neg_hi:[0,1]
	v_xor_b32_e32 v82, 0x80000000, v19
	v_mov_b32_e32 v83, v18
	v_pk_add_f32 v[130:131], v[62:63], v[92:93]
	v_pk_add_f32 v[62:63], v[62:63], v[92:93] neg_lo:[0,1] neg_hi:[0,1]
	v_pk_add_f32 v[92:93], v[90:91], v[26:27]
	v_pk_add_f32 v[26:27], v[90:91], v[26:27] neg_lo:[0,1] neg_hi:[0,1]
	v_pk_add_f32 v[18:19], v[24:25], v[82:83]
	v_pk_add_f32 v[24:25], v[24:25], v[82:83] neg_lo:[0,1] neg_hi:[0,1]
	v_pk_add_f32 v[82:83], v[74:75], v[76:77]
	v_pk_add_f32 v[74:75], v[74:75], v[76:77] neg_lo:[0,1] neg_hi:[0,1]
	v_xor_b32_e32 v76, 0x80000000, v15
	v_mov_b32_e32 v77, v14
	v_pk_add_f32 v[90:91], v[84:85], v[88:89]
	v_pk_add_f32 v[84:85], v[84:85], v[88:89] neg_lo:[0,1] neg_hi:[0,1]
	v_pk_add_f32 v[88:89], v[134:135], v[22:23]
	v_pk_add_f32 v[22:23], v[134:135], v[22:23] neg_lo:[0,1] neg_hi:[0,1]
	v_pk_add_f32 v[14:15], v[72:73], v[76:77]
	v_pk_add_f32 v[72:73], v[72:73], v[76:77] neg_lo:[0,1] neg_hi:[0,1]
	v_pk_add_f32 v[76:77], v[130:131], v[92:93]
	v_pk_add_f32 v[92:93], v[130:131], v[92:93] neg_lo:[0,1] neg_hi:[0,1]
	v_xor_b32_e32 v130, 0x80000000, v27
	v_mov_b32_e32 v131, v26
	v_pk_add_f32 v[26:27], v[62:63], v[130:131]
	v_pk_add_f32 v[62:63], v[62:63], v[130:131] neg_lo:[0,1] neg_hi:[0,1]
	v_pk_add_f32 v[130:131], v[90:91], v[88:89]
	v_pk_add_f32 v[88:89], v[90:91], v[88:89] neg_lo:[0,1] neg_hi:[0,1]
	v_xor_b32_e32 v90, 0x80000000, v23
	v_mov_b32_e32 v91, v22
	v_pk_add_f32 v[22:23], v[84:85], v[90:91]
	v_pk_add_f32 v[84:85], v[84:85], v[90:91] neg_lo:[0,1] neg_hi:[0,1]
	v_pk_add_f32 v[90:91], v[132:133], v[64:65]
	v_pk_add_f32 v[64:65], v[132:133], v[64:65] neg_lo:[0,1] neg_hi:[0,1]
	v_pk_mul_f32 v[132:133], v[2:3], s[60:61] op_sel:[1,0] op_sel_hi:[0,0] neg_lo:[1,0]
	v_xor_b32_e32 v134, 0x80000000, v11
	v_pk_fma_f32 v[2:3], v[2:3], s[60:61], v[132:133] op_sel_hi:[1,0,1]
	v_mov_b32_e32 v135, v10
	v_pk_add_f32 v[132:133], v[4:5], v[2:3]
	v_pk_add_f32 v[2:3], v[4:5], v[2:3] neg_lo:[0,1] neg_hi:[0,1]
	v_xor_b32_e32 v4, 0x80000000, v81
	v_mov_b32_e32 v5, v80
	v_pk_add_f32 v[80:81], v[12:13], v[4:5]
	v_pk_add_f32 v[4:5], v[12:13], v[4:5] neg_lo:[0,1] neg_hi:[0,1]
	v_pk_mul_f32 v[12:13], v[10:11], s[60:61] op_sel_hi:[1,0]
	s_nop 0
	v_pk_fma_f32 v[10:11], v[134:135], s[60:61], v[12:13] op_sel_hi:[1,0,1] neg_lo:[0,0,1] neg_hi:[0,0,1]
	v_xor_b32_e32 v134, 0x80000000, v17
	v_pk_add_f32 v[12:13], v[0:1], v[10:11]
	v_pk_add_f32 v[0:1], v[0:1], v[10:11] neg_lo:[0,1] neg_hi:[0,1]
	v_pk_add_f32 v[10:11], v[94:95], v[70:71]
	v_pk_add_f32 v[70:71], v[94:95], v[70:71] neg_lo:[0,1] neg_hi:[0,1]
	v_pk_mul_f32 v[94:95], v[6:7], s[60:61] op_sel:[1,0] op_sel_hi:[0,0] neg_lo:[1,0]
	v_mov_b32_e32 v135, v16
	v_pk_fma_f32 v[6:7], v[6:7], s[60:61], v[94:95] op_sel_hi:[1,0,1]
	s_nop 0
	v_pk_add_f32 v[94:95], v[8:9], v[6:7]
	v_pk_add_f32 v[6:7], v[8:9], v[6:7] neg_lo:[0,1] neg_hi:[0,1]
	v_xor_b32_e32 v8, 0x80000000, v87
	v_mov_b32_e32 v9, v86
	v_pk_add_f32 v[86:87], v[68:69], v[8:9]
	v_pk_add_f32 v[8:9], v[68:69], v[8:9] neg_lo:[0,1] neg_hi:[0,1]
	v_pk_mul_f32 v[68:69], v[16:17], s[60:61] op_sel_hi:[1,0]
	s_nop 0
	v_pk_fma_f32 v[16:17], v[134:135], s[60:61], v[68:69] op_sel_hi:[1,0,1] neg_lo:[0,0,1] neg_hi:[0,0,1]
	v_xor_b32_e32 v134, 0x80000000, v73
	v_pk_add_f32 v[68:69], v[20:21], v[16:17]
	v_pk_add_f32 v[16:17], v[20:21], v[16:17] neg_lo:[0,1] neg_hi:[0,1]
	v_pk_add_f32 v[20:21], v[96:97], v[82:83]
	v_pk_add_f32 v[82:83], v[96:97], v[82:83] neg_lo:[0,1] neg_hi:[0,1]
	v_pk_mul_f32 v[96:97], v[14:15], s[60:61] op_sel:[1,0] op_sel_hi:[0,0] neg_lo:[1,0]
	v_mov_b32_e32 v135, v72
	v_pk_fma_f32 v[14:15], v[14:15], s[60:61], v[96:97] op_sel_hi:[1,0,1]
	s_nop 0
	v_pk_add_f32 v[96:97], v[18:19], v[14:15]
	v_pk_add_f32 v[14:15], v[18:19], v[14:15] neg_lo:[0,1] neg_hi:[0,1]
	v_xor_b32_e32 v18, 0x80000000, v75
	v_mov_b32_e32 v19, v74
	v_pk_add_f32 v[74:75], v[78:79], v[18:19]
	v_pk_add_f32 v[18:19], v[78:79], v[18:19] neg_lo:[0,1] neg_hi:[0,1]
	v_pk_mul_f32 v[78:79], v[72:73], s[60:61] op_sel_hi:[1,0]
	s_nop 0
	v_pk_fma_f32 v[72:73], v[134:135], s[60:61], v[78:79] op_sel_hi:[1,0,1] neg_lo:[0,0,1] neg_hi:[0,0,1]
	v_xor_b32_e32 v134, 0x80000000, v85
	v_pk_add_f32 v[78:79], v[24:25], v[72:73]
	v_pk_add_f32 v[24:25], v[24:25], v[72:73] neg_lo:[0,1] neg_hi:[0,1]
	v_pk_add_f32 v[72:73], v[76:77], v[130:131]
	v_pk_add_f32 v[76:77], v[76:77], v[130:131] neg_lo:[0,1] neg_hi:[0,1]
	v_pk_mul_f32 v[130:131], v[22:23], s[60:61] op_sel:[1,0] op_sel_hi:[0,0] neg_lo:[1,0]
	v_mov_b32_e32 v135, v84
	v_pk_fma_f32 v[22:23], v[22:23], s[60:61], v[130:131] op_sel_hi:[1,0,1]
	s_nop 0
	v_pk_add_f32 v[130:131], v[26:27], v[22:23]
	v_pk_add_f32 v[22:23], v[26:27], v[22:23] neg_lo:[0,1] neg_hi:[0,1]
	v_xor_b32_e32 v26, 0x80000000, v89
	v_mov_b32_e32 v27, v88
	v_pk_add_f32 v[88:89], v[92:93], v[26:27]
	v_pk_add_f32 v[26:27], v[92:93], v[26:27] neg_lo:[0,1] neg_hi:[0,1]
	v_pk_mul_f32 v[92:93], v[84:85], s[60:61] op_sel_hi:[1,0]
	s_nop 0
	v_pk_fma_f32 v[84:85], v[134:135], s[60:61], v[92:93] op_sel_hi:[1,0,1] neg_lo:[0,0,1] neg_hi:[0,0,1]
	v_xor_b32_e32 v134, 0x80000000, v7
	v_pk_add_f32 v[92:93], v[62:63], v[84:85]
	v_pk_add_f32 v[62:63], v[62:63], v[84:85] neg_lo:[0,1] neg_hi:[0,1]
	v_pk_add_f32 v[84:85], v[90:91], v[10:11]
	v_pk_add_f32 v[10:11], v[90:91], v[10:11] neg_lo:[0,1] neg_hi:[0,1]
	v_pk_mul_f32 v[90:91], v[94:95], s[54:55] op_sel:[1,0] op_sel_hi:[0,0] neg_lo:[1,0]
	v_mov_b32_e32 v135, v6
	v_pk_fma_f32 v[90:91], v[94:95], s[52:53], v[90:91] op_sel_hi:[1,0,1]
	s_nop 0
	v_pk_add_f32 v[94:95], v[132:133], v[90:91]
	v_pk_add_f32 v[90:91], v[132:133], v[90:91] neg_lo:[0,1] neg_hi:[0,1]
	v_pk_mul_f32 v[132:133], v[86:87], s[60:61] op_sel:[1,0] op_sel_hi:[0,0] neg_lo:[1,0]
	s_nop 0
	v_pk_fma_f32 v[86:87], v[86:87], s[60:61], v[132:133] op_sel_hi:[1,0,1]
	s_nop 0
	v_pk_add_f32 v[132:133], v[80:81], v[86:87]
	v_pk_add_f32 v[80:81], v[80:81], v[86:87] neg_lo:[0,1] neg_hi:[0,1]
	v_pk_mul_f32 v[86:87], v[68:69], s[52:53] op_sel:[1,0] op_sel_hi:[0,0] neg_lo:[1,0]
	s_nop 0
	v_pk_fma_f32 v[68:69], v[68:69], s[54:55], v[86:87] op_sel_hi:[1,0,1]
	s_nop 0
	v_pk_add_f32 v[86:87], v[12:13], v[68:69]
	v_pk_add_f32 v[12:13], v[12:13], v[68:69] neg_lo:[0,1] neg_hi:[0,1]
	v_xor_b32_e32 v68, 0x80000000, v71
	v_mov_b32_e32 v69, v70
	v_pk_add_f32 v[70:71], v[64:65], v[68:69]
	v_pk_add_f32 v[64:65], v[64:65], v[68:69] neg_lo:[0,1] neg_hi:[0,1]
	v_pk_mul_f32 v[68:69], v[6:7], s[54:55] op_sel_hi:[1,0]
	s_nop 0
	v_pk_fma_f32 v[6:7], v[134:135], s[52:53], v[68:69] op_sel_hi:[1,0,1] neg_lo:[0,0,1] neg_hi:[0,0,1]
	v_xor_b32_e32 v134, 0x80000000, v9
	v_pk_add_f32 v[68:69], v[2:3], v[6:7]
	v_pk_add_f32 v[2:3], v[2:3], v[6:7] neg_lo:[0,1] neg_hi:[0,1]
	v_pk_mul_f32 v[6:7], v[8:9], s[60:61] op_sel_hi:[1,0]
	v_mov_b32_e32 v135, v8
	v_pk_fma_f32 v[6:7], v[134:135], s[60:61], v[6:7] op_sel_hi:[1,0,1] neg_lo:[0,0,1] neg_hi:[0,0,1]
	v_xor_b32_e32 v134, 0x80000000, v17
	v_pk_add_f32 v[8:9], v[4:5], v[6:7]
	v_pk_add_f32 v[4:5], v[4:5], v[6:7] neg_lo:[0,1] neg_hi:[0,1]
	v_pk_mul_f32 v[6:7], v[16:17], s[52:53] op_sel_hi:[1,0]
	v_mov_b32_e32 v135, v16
	v_pk_fma_f32 v[6:7], v[134:135], s[54:55], v[6:7] op_sel_hi:[1,0,1] neg_lo:[0,0,1] neg_hi:[0,0,1]
	v_xor_b32_e32 v134, 0x80000000, v23
	v_pk_add_f32 v[16:17], v[0:1], v[6:7]
	v_pk_add_f32 v[0:1], v[0:1], v[6:7] neg_lo:[0,1] neg_hi:[0,1]
	v_pk_add_f32 v[6:7], v[20:21], v[72:73]
	v_pk_add_f32 v[20:21], v[20:21], v[72:73] neg_lo:[0,1] neg_hi:[0,1]
	v_pk_mul_f32 v[72:73], v[130:131], s[54:55] op_sel:[1,0] op_sel_hi:[0,0] neg_lo:[1,0]
	v_mov_b32_e32 v135, v22
	v_pk_fma_f32 v[72:73], v[130:131], s[52:53], v[72:73] op_sel_hi:[1,0,1]
	s_nop 0
	v_pk_add_f32 v[130:131], v[96:97], v[72:73]
	v_pk_add_f32 v[72:73], v[96:97], v[72:73] neg_lo:[0,1] neg_hi:[0,1]
	v_pk_mul_f32 v[96:97], v[88:89], s[60:61] op_sel:[1,0] op_sel_hi:[0,0] neg_lo:[1,0]
	s_nop 0
	v_pk_fma_f32 v[88:89], v[88:89], s[60:61], v[96:97] op_sel_hi:[1,0,1]
	s_nop 0
	v_pk_add_f32 v[96:97], v[74:75], v[88:89]
	v_pk_add_f32 v[74:75], v[74:75], v[88:89] neg_lo:[0,1] neg_hi:[0,1]
	v_pk_mul_f32 v[88:89], v[92:93], s[52:53] op_sel:[1,0] op_sel_hi:[0,0] neg_lo:[1,0]
	s_nop 0
	v_pk_fma_f32 v[88:89], v[92:93], s[54:55], v[88:89] op_sel_hi:[1,0,1]
	s_nop 0
	v_pk_add_f32 v[92:93], v[78:79], v[88:89]
	v_pk_add_f32 v[78:79], v[78:79], v[88:89] neg_lo:[0,1] neg_hi:[0,1]
	v_xor_b32_e32 v88, 0x80000000, v77
	v_mov_b32_e32 v89, v76
	v_pk_add_f32 v[76:77], v[82:83], v[88:89]
	v_pk_add_f32 v[82:83], v[82:83], v[88:89] neg_lo:[0,1] neg_hi:[0,1]
	v_pk_mul_f32 v[88:89], v[22:23], s[54:55] op_sel_hi:[1,0]
	s_nop 0
	v_pk_fma_f32 v[22:23], v[134:135], s[52:53], v[88:89] op_sel_hi:[1,0,1] neg_lo:[0,0,1] neg_hi:[0,0,1]
	v_xor_b32_e32 v134, 0x80000000, v27
	v_pk_add_f32 v[88:89], v[14:15], v[22:23]
	v_pk_add_f32 v[14:15], v[14:15], v[22:23] neg_lo:[0,1] neg_hi:[0,1]
	v_pk_mul_f32 v[22:23], v[26:27], s[60:61] op_sel_hi:[1,0]
	v_mov_b32_e32 v135, v26
	v_pk_fma_f32 v[22:23], v[134:135], s[60:61], v[22:23] op_sel_hi:[1,0,1] neg_lo:[0,0,1] neg_hi:[0,0,1]
	v_xor_b32_e32 v134, 0x80000000, v63
	v_pk_add_f32 v[26:27], v[18:19], v[22:23]
	v_pk_add_f32 v[18:19], v[18:19], v[22:23] neg_lo:[0,1] neg_hi:[0,1]
	v_pk_mul_f32 v[22:23], v[62:63], s[52:53] op_sel_hi:[1,0]
	v_mov_b32_e32 v135, v62
	v_pk_fma_f32 v[22:23], v[134:135], s[54:55], v[22:23] op_sel_hi:[1,0,1] neg_lo:[0,0,1] neg_hi:[0,0,1]
	v_xor_b32_e32 v134, 0x80000000, v73
	v_pk_add_f32 v[62:63], v[24:25], v[22:23]
	v_pk_add_f32 v[22:23], v[24:25], v[22:23] neg_lo:[0,1] neg_hi:[0,1]
	v_pk_add_f32 v[24:25], v[84:85], v[6:7]
	v_pk_add_f32 v[6:7], v[84:85], v[6:7] neg_lo:[0,1] neg_hi:[0,1]
	v_pk_mul_f32 v[84:85], v[130:131], s[48:49] op_sel:[1,0] op_sel_hi:[0,0] neg_lo:[1,0]
	v_mov_b32_e32 v135, v72
	v_pk_fma_f32 v[84:85], v[130:131], s[44:45], v[84:85] op_sel_hi:[1,0,1]
	s_nop 0
	v_pk_add_f32 v[130:131], v[94:95], v[84:85]
	v_pk_add_f32 v[84:85], v[94:95], v[84:85] neg_lo:[0,1] neg_hi:[0,1]
	v_pk_mul_f32 v[94:95], v[96:97], s[54:55] op_sel:[1,0] op_sel_hi:[0,0] neg_lo:[1,0]
	s_nop 0
	v_pk_fma_f32 v[94:95], v[96:97], s[52:53], v[94:95] op_sel_hi:[1,0,1]
	s_nop 0
	v_pk_add_f32 v[96:97], v[132:133], v[94:95]
	v_pk_add_f32 v[94:95], v[132:133], v[94:95] neg_lo:[0,1] neg_hi:[0,1]
	v_pk_mul_f32 v[132:133], v[92:93], s[58:59] op_sel:[1,0] op_sel_hi:[0,0] neg_lo:[1,0]
	s_nop 0
	v_pk_fma_f32 v[92:93], v[92:93], s[56:57], v[132:133] op_sel_hi:[1,0,1]
	s_nop 0
	v_pk_add_f32 v[132:133], v[86:87], v[92:93]
	v_pk_add_f32 v[86:87], v[86:87], v[92:93] neg_lo:[0,1] neg_hi:[0,1]
	v_pk_mul_f32 v[92:93], v[76:77], s[60:61] op_sel:[1,0] op_sel_hi:[0,0] neg_lo:[1,0]
	s_nop 0
	v_pk_fma_f32 v[76:77], v[76:77], s[60:61], v[92:93] op_sel_hi:[1,0,1]
	s_nop 0
	v_pk_add_f32 v[92:93], v[70:71], v[76:77]
	v_pk_add_f32 v[70:71], v[70:71], v[76:77] neg_lo:[0,1] neg_hi:[0,1]
	v_pk_mul_f32 v[76:77], v[88:89], s[56:57] op_sel:[1,0] op_sel_hi:[0,0] neg_lo:[1,0]
	s_nop 0
	v_pk_fma_f32 v[76:77], v[88:89], s[58:59], v[76:77] op_sel_hi:[1,0,1]
	s_nop 0
	v_pk_add_f32 v[88:89], v[68:69], v[76:77]
	v_pk_add_f32 v[68:69], v[68:69], v[76:77] neg_lo:[0,1] neg_hi:[0,1]
	v_pk_mul_f32 v[76:77], v[26:27], s[52:53] op_sel:[1,0] op_sel_hi:[0,0] neg_lo:[1,0]
	s_nop 0
	v_pk_fma_f32 v[26:27], v[26:27], s[54:55], v[76:77] op_sel_hi:[1,0,1]
	s_nop 0
	v_pk_add_f32 v[76:77], v[8:9], v[26:27]
	v_pk_add_f32 v[8:9], v[8:9], v[26:27] neg_lo:[0,1] neg_hi:[0,1]
	v_pk_mul_f32 v[26:27], v[62:63], s[44:45] op_sel:[1,0] op_sel_hi:[0,0] neg_lo:[1,0]
	s_nop 0
	v_pk_fma_f32 v[26:27], v[62:63], s[48:49], v[26:27] op_sel_hi:[1,0,1]
	s_nop 0
	v_pk_add_f32 v[62:63], v[16:17], v[26:27]
	v_pk_add_f32 v[16:17], v[16:17], v[26:27] neg_lo:[0,1] neg_hi:[0,1]
	v_xor_b32_e32 v26, 0x80000000, v21
	v_mov_b32_e32 v27, v20
	v_pk_add_f32 v[20:21], v[10:11], v[26:27]
	v_pk_add_f32 v[10:11], v[10:11], v[26:27] neg_lo:[0,1] neg_hi:[0,1]
	v_pk_mul_f32 v[26:27], v[72:73], s[48:49] op_sel_hi:[1,0]
	s_nop 0
	v_pk_fma_f32 v[26:27], v[134:135], s[44:45], v[26:27] op_sel_hi:[1,0,1] neg_lo:[0,0,1] neg_hi:[0,0,1]
	v_xor_b32_e32 v134, 0x80000000, v75
	v_pk_add_f32 v[72:73], v[90:91], v[26:27]
	v_pk_add_f32 v[26:27], v[90:91], v[26:27] neg_lo:[0,1] neg_hi:[0,1]
	v_pk_mul_f32 v[90:91], v[74:75], s[54:55] op_sel_hi:[1,0]
	v_mov_b32_e32 v135, v74
	v_pk_fma_f32 v[74:75], v[134:135], s[52:53], v[90:91] op_sel_hi:[1,0,1] neg_lo:[0,0,1] neg_hi:[0,0,1]
	v_xor_b32_e32 v134, 0x80000000, v79
	v_pk_add_f32 v[90:91], v[80:81], v[74:75]
	v_pk_add_f32 v[74:75], v[80:81], v[74:75] neg_lo:[0,1] neg_hi:[0,1]
	v_pk_mul_f32 v[80:81], v[78:79], s[58:59] op_sel_hi:[1,0]
	v_mov_b32_e32 v135, v78
	v_pk_fma_f32 v[78:79], v[134:135], s[56:57], v[80:81] op_sel_hi:[1,0,1] neg_lo:[0,0,1] neg_hi:[0,0,1]
	v_xor_b32_e32 v134, 0x80000000, v83
	v_pk_add_f32 v[80:81], v[12:13], v[78:79]
	v_pk_add_f32 v[12:13], v[12:13], v[78:79] neg_lo:[0,1] neg_hi:[0,1]
	v_pk_mul_f32 v[78:79], v[82:83], s[60:61] op_sel_hi:[1,0]
	v_mov_b32_e32 v135, v82
	v_pk_fma_f32 v[78:79], v[134:135], s[60:61], v[78:79] op_sel_hi:[1,0,1] neg_lo:[0,0,1] neg_hi:[0,0,1]
	v_xor_b32_e32 v134, 0x80000000, v15
	v_pk_add_f32 v[82:83], v[64:65], v[78:79]
	v_pk_add_f32 v[64:65], v[64:65], v[78:79] neg_lo:[0,1] neg_hi:[0,1]
	v_pk_mul_f32 v[78:79], v[14:15], s[56:57] op_sel_hi:[1,0]
	v_mov_b32_e32 v135, v14
	v_pk_fma_f32 v[14:15], v[134:135], s[58:59], v[78:79] op_sel_hi:[1,0,1] neg_lo:[0,0,1] neg_hi:[0,0,1]
	v_xor_b32_e32 v134, 0x80000000, v19
	v_pk_add_f32 v[78:79], v[2:3], v[14:15]
	v_pk_add_f32 v[2:3], v[2:3], v[14:15] neg_lo:[0,1] neg_hi:[0,1]
	v_pk_mul_f32 v[14:15], v[18:19], s[52:53] op_sel_hi:[1,0]
	v_mov_b32_e32 v135, v18
	v_pk_fma_f32 v[14:15], v[134:135], s[54:55], v[14:15] op_sel_hi:[1,0,1] neg_lo:[0,0,1] neg_hi:[0,0,1]
	v_xor_b32_e32 v134, 0x80000000, v23
	v_pk_add_f32 v[18:19], v[4:5], v[14:15]
	v_pk_add_f32 v[4:5], v[4:5], v[14:15] neg_lo:[0,1] neg_hi:[0,1]
	v_pk_mul_f32 v[14:15], v[22:23], s[44:45] op_sel_hi:[1,0]
	v_mov_b32_e32 v135, v22
	v_pk_fma_f32 v[14:15], v[134:135], s[48:49], v[14:15] op_sel_hi:[1,0,1] neg_lo:[0,0,1] neg_hi:[0,0,1]
	s_nop 0
	v_pk_add_f32 v[22:23], v[0:1], v[14:15]
	v_pk_add_f32 v[0:1], v[0:1], v[14:15] neg_lo:[0,1] neg_hi:[0,1]
	ds_write_b64 v67, v[24:25]
	ds_write_b64 v98, v[130:131]
	ds_write_b64 v99, v[96:97] offset:256
	ds_write_b64 v100, v[132:133] offset:256
	ds_write_b64 v101, v[92:93] offset:512
	ds_write_b64 v102, v[88:89] offset:512
	ds_write_b64 v103, v[76:77] offset:768
	ds_write_b64 v104, v[62:63] offset:768
	ds_write_b64 v105, v[20:21] offset:1024
	ds_write_b64 v106, v[72:73] offset:1024
	ds_write_b64 v107, v[90:91] offset:1280
	ds_write_b64 v108, v[80:81] offset:1280
	ds_write_b64 v109, v[82:83] offset:1536
	ds_write_b64 v110, v[78:79] offset:1536
	ds_write_b64 v111, v[18:19] offset:1792
	ds_write_b64 v112, v[22:23] offset:1792
	ds_write_b64 v113, v[6:7] offset:2048
	ds_write_b64 v114, v[84:85] offset:2048
	ds_write_b64 v115, v[94:95] offset:2304
	ds_write_b64 v116, v[86:87] offset:2304
	ds_write_b64 v117, v[70:71] offset:2560
	ds_write_b64 v118, v[68:69] offset:2560
	ds_write_b64 v119, v[8:9] offset:2816
	ds_write_b64 v120, v[16:17] offset:2816
	ds_write_b64 v121, v[10:11] offset:3072
	ds_write_b64 v122, v[26:27] offset:3072
	ds_write_b64 v123, v[74:75] offset:3328
	ds_write_b64 v124, v[12:13] offset:3328
	ds_write_b64 v125, v[64:65] offset:3584
	ds_write_b64 v126, v[2:3] offset:3584
	ds_write_b64 v127, v[4:5] offset:3840
	ds_write_b64 v128, v[0:1] offset:3840
	v_mov_b32_e32 v74, v146
	s_waitcnt lgkmcnt(0)
	s_barrier
	s_nop 0
	v_lshrrev_b32_e32 v0, 5, v74
	v_bfe_u32 v4, v74, 5, 4
	v_bitop3_b32 v0, v0, v74, 15 bitop3:0x6c
	v_bitop3_b32 v4, v4, v74, 16 bitop3:0x36
	v_lshlrev_b32_e32 v66, 3, v0
	v_lshlrev_b32_e32 v67, 3, v4
	v_add_u32_e32 v5, 16, v66
	v_add_u32_e32 v4, 16, v67
	v_add_u32_e32 v62, s79, v66
	v_add_u32_e32 v70, s9, v66
	ds_read2st64_b64 v[0:3], v5 offset1:16
	ds_read2st64_b64 v[16:19], v4 offset0:8 offset1:24
	ds_read2st64_b64 v[24:27], v5 offset0:32 offset1:48
	ds_read2st64_b64 v[8:11], v4 offset0:40 offset1:56
	ds_read2st64_b64 v[92:95], v5 offset0:64 offset1:80
	ds_read2st64_b64 v[12:15], v4 offset0:72 offset1:88
	ds_read2st64_b64 v[20:23], v5 offset0:96 offset1:112
	ds_read2st64_b64 v[4:7], v4 offset0:104 offset1:120
	ds_read_b64 v[68:69], v62
	ds_read_b64 v[72:73], v70
	v_add_u32_e32 v62, s19, v67
	v_add_u32_e32 v70, s8, v67
	ds_read_b64 v[84:85], v62
	ds_read_b64 v[90:91], v70
	v_add_u32_e32 v62, s18, v66
	v_add_u32_e32 v70, s7, v66
	ds_read_b64 v[96:97], v62
	ds_read_b64 v[100:101], v70
	v_add_u32_e32 v62, s17, v67
	v_add_u32_e32 v70, s6, v67
	ds_read_b64 v[64:65], v62
	ds_read_b64 v[70:71], v70
	v_add_u32_e32 v62, s13, v66
	v_add_u32_e32 v75, s5, v66
	ds_read_b64 v[86:87], v62
	ds_read_b64 v[102:103], v75
	v_add_u32_e32 v62, s12, v67
	v_add_u32_e32 v75, s4, v67
	ds_read_b64 v[80:81], v62
	ds_read_b64 v[88:89], v75
	v_add_u32_e32 v62, s11, v66
	v_add_u32_e32 v66, s1, v66
	ds_read_b64 v[98:99], v62
	ds_read_b64 v[104:105], v66
	v_add_u32_e32 v62, s10, v67
	v_add_u32_e32 v66, s0, v67
	ds_read_b64 v[62:63], v62
	ds_read_b64 v[66:67], v66
	s_waitcnt lgkmcnt(14)
	s_nop 0
	v_cvt_f32_i32_e32 v74, v74
	s_nop 0
	s_lshl_b64 s[0:1], s[42:43], 2
	s_add_u32 s0, s45, s0
	v_mul_f32_e32 v74, 0x38800000, v74
	v_cos_f32_e32 v78, v74
	v_sin_f32_e32 v79, v74
	s_addc_u32 s1, s24, s1
	s_and_b64 vcc, s[14:15], exec
	v_add_f32_e32 v76, v78, v78
	v_pk_mul_f32 v[74:75], v[78:79], v[78:79]
	v_mul_f32_e32 v76, v79, v76
	s_nop 0
	s_nop 0
	v_mov_b32_e32 v108, v79
	v_pk_add_f32 v[74:75], v[74:75], v[74:75] op_sel:[0,1] op_sel_hi:[0,1] neg_lo:[0,1] neg_hi:[0,1]
	v_pk_mul_f32 v[82:83], v[78:79], v[76:77] op_sel:[1,0] op_sel_hi:[0,0] neg_lo:[1,0]
	v_pk_mul_f32 v[106:107], v[68:69], v[108:109] op_sel:[1,0] op_sel_hi:[0,0] neg_lo:[1,0]
	v_pk_fma_f32 v[82:83], v[78:79], v[74:75], v[82:83]
	v_pk_fma_f32 v[68:69], v[68:69], v[78:79], v[106:107] op_sel_hi:[1,0,1]
	v_pk_mul_f32 v[78:79], v[76:77], s[46:47] op_sel_hi:[0,1]
	v_pk_fma_f32 v[106:107], v[74:75], s[40:41], v[78:79]
	s_nop 0
	v_pk_mul_f32 v[78:79], v[92:93], v[106:107] op_sel:[1,1] op_sel_hi:[0,1] neg_lo:[1,0]
	s_nop 0
	v_pk_fma_f32 v[78:79], v[92:93], v[106:107], v[78:79] op_sel_hi:[1,0,1]
	v_pk_mul_f32 v[92:93], v[76:77], v[82:83] op_sel:[0,1] op_sel_hi:[0,0] neg_lo:[0,1]
	v_pk_mul_f32 v[108:109], v[72:73], v[82:83] op_sel:[1,1] op_sel_hi:[0,1] neg_lo:[1,0]
	v_pk_fma_f32 v[92:93], v[74:75], v[82:83], v[92:93]
	v_pk_fma_f32 v[72:73], v[72:73], v[82:83], v[108:109] op_sel_hi:[1,0,1]
	v_pk_mul_f32 v[82:83], v[76:77], v[106:107] op_sel:[0,1] op_sel_hi:[0,0] neg_lo:[0,1]
	v_pk_fma_f32 v[106:107], v[74:75], v[106:107], v[82:83]
	s_nop 0
	v_pk_mul_f32 v[82:83], v[24:25], v[106:107] op_sel:[1,1] op_sel_hi:[0,1] neg_lo:[1,0]
	s_nop 0
	v_pk_fma_f32 v[82:83], v[24:25], v[106:107], v[82:83] op_sel_hi:[1,0,1]
	v_pk_mul_f32 v[24:25], v[76:77], v[92:93] op_sel:[0,1] op_sel_hi:[0,0] neg_lo:[0,1]
	v_pk_fma_f32 v[108:109], v[74:75], v[92:93], v[24:25]
	s_waitcnt lgkmcnt(7)
	v_pk_mul_f32 v[24:25], v[86:87], v[92:93] op_sel:[1,1] op_sel_hi:[0,1] neg_lo:[1,0]
	s_nop 0
	v_pk_fma_f32 v[24:25], v[86:87], v[92:93], v[24:25] op_sel_hi:[1,0,1]
	v_pk_mul_f32 v[86:87], v[76:77], v[106:107] op_sel:[0,1] op_sel_hi:[0,0] neg_lo:[0,1]
	v_pk_fma_f32 v[92:93], v[74:75], v[106:107], v[86:87]
	s_nop 0
	v_pk_mul_f32 v[86:87], v[20:21], v[92:93] op_sel:[1,1] op_sel_hi:[0,1] neg_lo:[1,0]
	s_nop 0
	v_pk_fma_f32 v[86:87], v[20:21], v[92:93], v[86:87] op_sel_hi:[1,0,1]
	v_pk_mul_f32 v[20:21], v[76:77], v[108:109] op_sel:[0,1] op_sel_hi:[0,0] neg_lo:[0,1]
	v_pk_fma_f32 v[106:107], v[74:75], v[108:109], v[20:21]
	s_waitcnt lgkmcnt(6)
	v_pk_mul_f32 v[20:21], v[102:103], v[108:109] op_sel:[1,1] op_sel_hi:[0,1] neg_lo:[1,0]
	s_nop 0
	v_pk_fma_f32 v[20:21], v[102:103], v[108:109], v[20:21] op_sel_hi:[1,0,1]
	v_pk_mul_f32 v[102:103], v[76:77], v[92:93] op_sel:[0,1] op_sel_hi:[0,0] neg_lo:[0,1]
	v_pk_fma_f32 v[102:103], v[74:75], v[92:93], v[102:103]
	s_nop 0
	v_pk_mul_f32 v[92:93], v[2:3], v[102:103] op_sel:[1,1] op_sel_hi:[0,1] neg_lo:[1,0]
	s_nop 0
	v_pk_fma_f32 v[92:93], v[2:3], v[102:103], v[92:93] op_sel_hi:[1,0,1]
	v_pk_mul_f32 v[2:3], v[76:77], v[106:107] op_sel:[0,1] op_sel_hi:[0,0] neg_lo:[0,1]
	v_pk_fma_f32 v[108:109], v[74:75], v[106:107], v[2:3]
	v_pk_mul_f32 v[2:3], v[96:97], v[106:107] op_sel:[1,1] op_sel_hi:[0,1] neg_lo:[1,0]
	s_nop 0
	v_pk_fma_f32 v[2:3], v[96:97], v[106:107], v[2:3] op_sel_hi:[1,0,1]
	v_pk_mul_f32 v[96:97], v[76:77], v[102:103] op_sel:[0,1] op_sel_hi:[0,0] neg_lo:[0,1]
	v_pk_fma_f32 v[102:103], v[74:75], v[102:103], v[96:97]
	s_nop 0
	v_pk_mul_f32 v[96:97], v[94:95], v[102:103] op_sel:[1,1] op_sel_hi:[0,1] neg_lo:[1,0]
	s_nop 0
	v_pk_fma_f32 v[96:97], v[94:95], v[102:103], v[96:97] op_sel_hi:[1,0,1]
	v_pk_mul_f32 v[94:95], v[76:77], v[108:109] op_sel:[0,1] op_sel_hi:[0,0] neg_lo:[0,1]
	v_pk_fma_f32 v[106:107], v[74:75], v[108:109], v[94:95]
	v_pk_mul_f32 v[94:95], v[100:101], v[108:109] op_sel:[1,1] op_sel_hi:[0,1] neg_lo:[1,0]
	s_nop 0
	v_pk_fma_f32 v[94:95], v[100:101], v[108:109], v[94:95] op_sel_hi:[1,0,1]
	v_pk_mul_f32 v[100:101], v[76:77], v[102:103] op_sel:[0,1] op_sel_hi:[0,0] neg_lo:[0,1]
	v_pk_fma_f32 v[100:101], v[74:75], v[102:103], v[100:101]
	s_nop 0
	v_pk_mul_f32 v[102:103], v[26:27], v[100:101] op_sel:[1,1] op_sel_hi:[0,1] neg_lo:[1,0]
	s_waitcnt lgkmcnt(3)
	v_pk_fma_f32 v[26:27], v[26:27], v[100:101], v[102:103] op_sel_hi:[1,0,1]
	v_pk_mul_f32 v[102:103], v[76:77], v[106:107] op_sel:[0,1] op_sel_hi:[0,0] neg_lo:[0,1]
	v_pk_mul_f32 v[108:109], v[98:99], v[106:107] op_sel:[1,1] op_sel_hi:[0,1] neg_lo:[1,0]
	v_pk_fma_f32 v[102:103], v[74:75], v[106:107], v[102:103]
	v_pk_fma_f32 v[98:99], v[98:99], v[106:107], v[108:109] op_sel_hi:[1,0,1]
	v_pk_mul_f32 v[106:107], v[76:77], v[100:101] op_sel:[0,1] op_sel_hi:[0,0] neg_lo:[0,1]
	v_pk_fma_f32 v[100:101], v[74:75], v[100:101], v[106:107]
	s_nop 0
	v_pk_mul_f32 v[106:107], v[22:23], v[100:101] op_sel:[1,1] op_sel_hi:[0,1] neg_lo:[1,0]
	s_waitcnt lgkmcnt(2)
	v_pk_fma_f32 v[22:23], v[22:23], v[100:101], v[106:107] op_sel_hi:[1,0,1]
	v_pk_mul_f32 v[106:107], v[76:77], v[102:103] op_sel:[0,1] op_sel_hi:[0,0] neg_lo:[0,1]
	v_pk_mul_f32 v[108:109], v[104:105], v[102:103] op_sel:[1,1] op_sel_hi:[0,1] neg_lo:[1,0]
	v_pk_fma_f32 v[106:107], v[74:75], v[102:103], v[106:107]
	v_pk_fma_f32 v[102:103], v[104:105], v[102:103], v[108:109] op_sel_hi:[1,0,1]
	v_pk_mul_f32 v[104:105], v[76:77], v[100:101] op_sel:[0,1] op_sel_hi:[0,0] neg_lo:[0,1]
	v_pk_fma_f32 v[100:101], v[74:75], v[100:101], v[104:105]
	s_nop 0
	v_pk_mul_f32 v[104:105], v[16:17], v[100:101] op_sel:[1,1] op_sel_hi:[0,1] neg_lo:[1,0]
	s_nop 0
	v_pk_fma_f32 v[16:17], v[16:17], v[100:101], v[104:105] op_sel_hi:[1,0,1]
	v_pk_mul_f32 v[104:105], v[76:77], v[106:107] op_sel:[0,1] op_sel_hi:[0,0] neg_lo:[0,1]
	v_pk_mul_f32 v[108:109], v[84:85], v[106:107] op_sel:[1,1] op_sel_hi:[0,1] neg_lo:[1,0]
	v_pk_fma_f32 v[104:105], v[74:75], v[106:107], v[104:105]
	v_pk_fma_f32 v[84:85], v[84:85], v[106:107], v[108:109] op_sel_hi:[1,0,1]
	v_pk_mul_f32 v[106:107], v[76:77], v[100:101] op_sel:[0,1] op_sel_hi:[0,0] neg_lo:[0,1]
	v_pk_fma_f32 v[100:101], v[74:75], v[100:101], v[106:107]
	s_nop 0
	v_pk_mul_f32 v[106:107], v[12:13], v[100:101] op_sel:[1,1] op_sel_hi:[0,1] neg_lo:[1,0]
	s_nop 0
	v_pk_fma_f32 v[12:13], v[12:13], v[100:101], v[106:107] op_sel_hi:[1,0,1]
	v_pk_mul_f32 v[106:107], v[76:77], v[104:105] op_sel:[0,1] op_sel_hi:[0,0] neg_lo:[0,1]
	v_pk_mul_f32 v[108:109], v[90:91], v[104:105] op_sel:[1,1] op_sel_hi:[0,1] neg_lo:[1,0]
	v_pk_fma_f32 v[106:107], v[74:75], v[104:105], v[106:107]
	v_pk_fma_f32 v[90:91], v[90:91], v[104:105], v[108:109] op_sel_hi:[1,0,1]
	v_pk_mul_f32 v[104:105], v[76:77], v[100:101] op_sel:[0,1] op_sel_hi:[0,0] neg_lo:[0,1]
	v_pk_fma_f32 v[100:101], v[74:75], v[100:101], v[104:105]
	s_nop 0
	v_pk_mul_f32 v[104:105], v[8:9], v[100:101] op_sel:[1,1] op_sel_hi:[0,1] neg_lo:[1,0]
	s_nop 0
	v_pk_fma_f32 v[8:9], v[8:9], v[100:101], v[104:105] op_sel_hi:[1,0,1]
	v_pk_mul_f32 v[104:105], v[76:77], v[106:107] op_sel:[0,1] op_sel_hi:[0,0] neg_lo:[0,1]
	v_pk_mul_f32 v[108:109], v[80:81], v[106:107] op_sel:[1,1] op_sel_hi:[0,1] neg_lo:[1,0]
	v_pk_fma_f32 v[104:105], v[74:75], v[106:107], v[104:105]
	v_pk_fma_f32 v[80:81], v[80:81], v[106:107], v[108:109] op_sel_hi:[1,0,1]
	v_pk_mul_f32 v[106:107], v[76:77], v[100:101] op_sel:[0,1] op_sel_hi:[0,0] neg_lo:[0,1]
	v_pk_fma_f32 v[100:101], v[74:75], v[100:101], v[106:107]
	s_nop 0
	v_pk_mul_f32 v[106:107], v[4:5], v[100:101] op_sel:[1,1] op_sel_hi:[0,1] neg_lo:[1,0]
	s_nop 0
	v_pk_fma_f32 v[4:5], v[4:5], v[100:101], v[106:107] op_sel_hi:[1,0,1]
	v_pk_mul_f32 v[106:107], v[76:77], v[104:105] op_sel:[0,1] op_sel_hi:[0,0] neg_lo:[0,1]
	v_pk_mul_f32 v[108:109], v[88:89], v[104:105] op_sel:[1,1] op_sel_hi:[0,1] neg_lo:[1,0]
	v_pk_fma_f32 v[106:107], v[74:75], v[104:105], v[106:107]
	v_pk_fma_f32 v[88:89], v[88:89], v[104:105], v[108:109] op_sel_hi:[1,0,1]
	v_pk_mul_f32 v[104:105], v[76:77], v[100:101] op_sel:[0,1] op_sel_hi:[0,0] neg_lo:[0,1]
	v_pk_fma_f32 v[100:101], v[74:75], v[100:101], v[104:105]
	s_nop 0
	v_pk_mul_f32 v[104:105], v[18:19], v[100:101] op_sel:[1,1] op_sel_hi:[0,1] neg_lo:[1,0]
	s_nop 0
	v_pk_fma_f32 v[18:19], v[18:19], v[100:101], v[104:105] op_sel_hi:[1,0,1]
	v_pk_mul_f32 v[104:105], v[76:77], v[106:107] op_sel:[0,1] op_sel_hi:[0,0] neg_lo:[0,1]
	v_pk_mul_f32 v[108:109], v[64:65], v[106:107] op_sel:[1,1] op_sel_hi:[0,1] neg_lo:[1,0]
	v_pk_fma_f32 v[104:105], v[74:75], v[106:107], v[104:105]
	v_pk_fma_f32 v[64:65], v[64:65], v[106:107], v[108:109] op_sel_hi:[1,0,1]
	v_pk_mul_f32 v[106:107], v[76:77], v[100:101] op_sel:[0,1] op_sel_hi:[0,0] neg_lo:[0,1]
	v_pk_fma_f32 v[100:101], v[74:75], v[100:101], v[106:107]
	s_nop 0
	v_pk_mul_f32 v[106:107], v[14:15], v[100:101] op_sel:[1,1] op_sel_hi:[0,1] neg_lo:[1,0]
	s_nop 0
	v_pk_fma_f32 v[14:15], v[14:15], v[100:101], v[106:107] op_sel_hi:[1,0,1]
	v_pk_mul_f32 v[106:107], v[76:77], v[104:105] op_sel:[0,1] op_sel_hi:[0,0] neg_lo:[0,1]
	v_pk_mul_f32 v[108:109], v[70:71], v[104:105] op_sel:[1,1] op_sel_hi:[0,1] neg_lo:[1,0]
	v_pk_fma_f32 v[106:107], v[74:75], v[104:105], v[106:107]
	v_pk_fma_f32 v[70:71], v[70:71], v[104:105], v[108:109] op_sel_hi:[1,0,1]
	v_pk_mul_f32 v[104:105], v[76:77], v[100:101] op_sel:[0,1] op_sel_hi:[0,0] neg_lo:[0,1]
	v_pk_fma_f32 v[100:101], v[74:75], v[100:101], v[104:105]
	s_nop 0
	v_pk_mul_f32 v[104:105], v[10:11], v[100:101] op_sel:[1,1] op_sel_hi:[0,1] neg_lo:[1,0]
	s_waitcnt lgkmcnt(1)
	v_pk_fma_f32 v[10:11], v[10:11], v[100:101], v[104:105] op_sel_hi:[1,0,1]
	v_pk_mul_f32 v[104:105], v[76:77], v[106:107] op_sel:[0,1] op_sel_hi:[0,0] neg_lo:[0,1]
	v_pk_mul_f32 v[108:109], v[62:63], v[106:107] op_sel:[1,1] op_sel_hi:[0,1] neg_lo:[1,0]
	v_pk_fma_f32 v[104:105], v[74:75], v[106:107], v[104:105]
	v_pk_fma_f32 v[62:63], v[62:63], v[106:107], v[108:109] op_sel_hi:[1,0,1]
	v_pk_mul_f32 v[76:77], v[76:77], v[100:101] op_sel:[0,1] op_sel_hi:[0,0] neg_lo:[0,1]
	v_pk_fma_f32 v[74:75], v[74:75], v[100:101], v[76:77]
	s_nop 0
	v_pk_mul_f32 v[76:77], v[6:7], v[74:75] op_sel:[1,1] op_sel_hi:[0,1] neg_lo:[1,0]
	s_nop 0
	v_pk_fma_f32 v[6:7], v[6:7], v[74:75], v[76:77] op_sel_hi:[1,0,1]
	s_waitcnt lgkmcnt(0)
	v_pk_mul_f32 v[74:75], v[66:67], v[104:105] op_sel:[1,1] op_sel_hi:[0,1] neg_lo:[1,0]
	v_pk_add_f32 v[76:77], v[82:83], v[8:9]
	v_pk_fma_f32 v[66:67], v[66:67], v[104:105], v[74:75] op_sel_hi:[1,0,1]
	v_pk_add_f32 v[74:75], v[0:1], v[16:17]
	v_pk_add_f32 v[0:1], v[0:1], v[16:17] neg_lo:[0,1] neg_hi:[0,1]
	v_pk_add_f32 v[16:17], v[92:93], v[18:19]
	v_pk_add_f32 v[18:19], v[92:93], v[18:19] neg_lo:[0,1] neg_hi:[0,1]
	v_pk_add_f32 v[8:9], v[82:83], v[8:9] neg_lo:[0,1] neg_hi:[0,1]
	v_pk_add_f32 v[82:83], v[26:27], v[10:11]
	v_pk_add_f32 v[10:11], v[26:27], v[10:11] neg_lo:[0,1] neg_hi:[0,1]
	v_pk_add_f32 v[92:93], v[86:87], v[4:5]
	v_pk_add_f32 v[4:5], v[86:87], v[4:5] neg_lo:[0,1] neg_hi:[0,1]
	v_pk_add_f32 v[86:87], v[22:23], v[6:7]
	v_pk_add_f32 v[6:7], v[22:23], v[6:7] neg_lo:[0,1] neg_hi:[0,1]
	v_pk_add_f32 v[22:23], v[68:69], v[84:85]
	v_pk_add_f32 v[68:69], v[68:69], v[84:85] neg_lo:[0,1] neg_hi:[0,1]
	v_pk_add_f32 v[84:85], v[2:3], v[64:65]
	v_pk_add_f32 v[2:3], v[2:3], v[64:65] neg_lo:[0,1] neg_hi:[0,1]
	v_pk_add_f32 v[64:65], v[24:25], v[80:81]
	v_pk_add_f32 v[24:25], v[24:25], v[80:81] neg_lo:[0,1] neg_hi:[0,1]
	v_pk_add_f32 v[80:81], v[98:99], v[62:63]
	v_pk_add_f32 v[62:63], v[98:99], v[62:63] neg_lo:[0,1] neg_hi:[0,1]
	v_pk_add_f32 v[98:99], v[74:75], v[16:17]
	v_pk_add_f32 v[16:17], v[74:75], v[16:17] neg_lo:[0,1] neg_hi:[0,1]
	v_xor_b32_e32 v74, 0x80000000, v19
	v_mov_b32_e32 v75, v18
	v_pk_add_f32 v[26:27], v[78:79], v[12:13]
	v_pk_add_f32 v[12:13], v[78:79], v[12:13] neg_lo:[0,1] neg_hi:[0,1]
	v_pk_add_f32 v[78:79], v[96:97], v[14:15]
	v_pk_add_f32 v[14:15], v[96:97], v[14:15] neg_lo:[0,1] neg_hi:[0,1]
	v_pk_add_f32 v[18:19], v[0:1], v[74:75]
	v_pk_add_f32 v[0:1], v[0:1], v[74:75] neg_lo:[0,1] neg_hi:[0,1]
	v_pk_add_f32 v[74:75], v[76:77], v[82:83]
	v_pk_add_f32 v[76:77], v[76:77], v[82:83] neg_lo:[0,1] neg_hi:[0,1]
	v_xor_b32_e32 v82, 0x80000000, v11
	v_mov_b32_e32 v83, v10
	v_pk_add_f32 v[10:11], v[8:9], v[82:83]
	v_pk_add_f32 v[8:9], v[8:9], v[82:83] neg_lo:[0,1] neg_hi:[0,1]
	v_pk_add_f32 v[82:83], v[26:27], v[78:79]
	v_pk_add_f32 v[26:27], v[26:27], v[78:79] neg_lo:[0,1] neg_hi:[0,1]
	v_xor_b32_e32 v78, 0x80000000, v15
	v_mov_b32_e32 v79, v14
	v_pk_add_f32 v[14:15], v[12:13], v[78:79]
	v_pk_add_f32 v[12:13], v[12:13], v[78:79] neg_lo:[0,1] neg_hi:[0,1]
	v_pk_add_f32 v[78:79], v[92:93], v[86:87]
	v_pk_add_f32 v[86:87], v[92:93], v[86:87] neg_lo:[0,1] neg_hi:[0,1]
	v_xor_b32_e32 v92, 0x80000000, v7
	v_mov_b32_e32 v93, v6
	v_pk_add_f32 v[6:7], v[4:5], v[92:93]
	v_pk_add_f32 v[4:5], v[4:5], v[92:93] neg_lo:[0,1] neg_hi:[0,1]
	v_pk_add_f32 v[92:93], v[22:23], v[84:85]
	v_pk_add_f32 v[22:23], v[22:23], v[84:85] neg_lo:[0,1] neg_hi:[0,1]
	v_xor_b32_e32 v84, 0x80000000, v3
	v_mov_b32_e32 v85, v2
	v_pk_add_f32 v[96:97], v[72:73], v[90:91]
	v_pk_add_f32 v[72:73], v[72:73], v[90:91] neg_lo:[0,1] neg_hi:[0,1]
	v_pk_add_f32 v[90:91], v[94:95], v[70:71]
	v_pk_add_f32 v[70:71], v[94:95], v[70:71] neg_lo:[0,1] neg_hi:[0,1]
	v_pk_add_f32 v[2:3], v[68:69], v[84:85]
	v_pk_add_f32 v[68:69], v[68:69], v[84:85] neg_lo:[0,1] neg_hi:[0,1]
	v_pk_add_f32 v[84:85], v[64:65], v[80:81]
	v_pk_add_f32 v[64:65], v[64:65], v[80:81] neg_lo:[0,1] neg_hi:[0,1]
	v_xor_b32_e32 v80, 0x80000000, v63
	v_mov_b32_e32 v81, v62
	v_pk_add_f32 v[94:95], v[20:21], v[88:89]
	v_pk_add_f32 v[20:21], v[20:21], v[88:89] neg_lo:[0,1] neg_hi:[0,1]
	v_pk_add_f32 v[88:89], v[102:103], v[66:67]
	v_pk_add_f32 v[66:67], v[102:103], v[66:67] neg_lo:[0,1] neg_hi:[0,1]
	v_pk_add_f32 v[62:63], v[24:25], v[80:81]
	v_pk_add_f32 v[24:25], v[24:25], v[80:81] neg_lo:[0,1] neg_hi:[0,1]
	v_pk_add_f32 v[80:81], v[96:97], v[90:91]
	v_pk_add_f32 v[90:91], v[96:97], v[90:91] neg_lo:[0,1] neg_hi:[0,1]
	v_xor_b32_e32 v96, 0x80000000, v71
	v_mov_b32_e32 v97, v70
	v_pk_add_f32 v[70:71], v[72:73], v[96:97]
	v_pk_add_f32 v[72:73], v[72:73], v[96:97] neg_lo:[0,1] neg_hi:[0,1]
	v_pk_add_f32 v[96:97], v[94:95], v[88:89]
	v_pk_add_f32 v[88:89], v[94:95], v[88:89] neg_lo:[0,1] neg_hi:[0,1]
	v_xor_b32_e32 v94, 0x80000000, v67
	v_mov_b32_e32 v95, v66
	v_pk_add_f32 v[66:67], v[20:21], v[94:95]
	v_pk_add_f32 v[20:21], v[20:21], v[94:95] neg_lo:[0,1] neg_hi:[0,1]
	v_pk_add_f32 v[94:95], v[98:99], v[74:75]
	v_pk_add_f32 v[74:75], v[98:99], v[74:75] neg_lo:[0,1] neg_hi:[0,1]
	v_pk_mul_f32 v[98:99], v[10:11], s[60:61] op_sel:[1,0] op_sel_hi:[0,0] neg_lo:[1,0]
	v_xor_b32_e32 v100, 0x80000000, v9
	v_pk_fma_f32 v[10:11], v[10:11], s[60:61], v[98:99] op_sel_hi:[1,0,1]
	v_mov_b32_e32 v101, v8
	v_pk_add_f32 v[98:99], v[18:19], v[10:11]
	v_pk_add_f32 v[10:11], v[18:19], v[10:11] neg_lo:[0,1] neg_hi:[0,1]
	v_xor_b32_e32 v18, 0x80000000, v77
	v_mov_b32_e32 v19, v76
	v_pk_add_f32 v[76:77], v[16:17], v[18:19]
	v_pk_add_f32 v[16:17], v[16:17], v[18:19] neg_lo:[0,1] neg_hi:[0,1]
	v_pk_mul_f32 v[18:19], v[8:9], s[60:61] op_sel_hi:[1,0]
	s_nop 0
	v_pk_fma_f32 v[8:9], v[100:101], s[60:61], v[18:19] op_sel_hi:[1,0,1] neg_lo:[0,0,1] neg_hi:[0,0,1]
	v_xor_b32_e32 v100, 0x80000000, v5
	v_pk_add_f32 v[18:19], v[0:1], v[8:9]
	v_pk_add_f32 v[0:1], v[0:1], v[8:9] neg_lo:[0,1] neg_hi:[0,1]
	v_pk_add_f32 v[8:9], v[82:83], v[78:79]
	v_pk_add_f32 v[78:79], v[82:83], v[78:79] neg_lo:[0,1] neg_hi:[0,1]
	v_pk_mul_f32 v[82:83], v[6:7], s[60:61] op_sel:[1,0] op_sel_hi:[0,0] neg_lo:[1,0]
	v_mov_b32_e32 v101, v4
	v_pk_fma_f32 v[6:7], v[6:7], s[60:61], v[82:83] op_sel_hi:[1,0,1]
	s_nop 0
	v_pk_add_f32 v[82:83], v[14:15], v[6:7]
	v_pk_add_f32 v[6:7], v[14:15], v[6:7] neg_lo:[0,1] neg_hi:[0,1]
	v_xor_b32_e32 v14, 0x80000000, v87
	v_mov_b32_e32 v15, v86
	v_pk_add_f32 v[86:87], v[26:27], v[14:15]
	v_pk_add_f32 v[14:15], v[26:27], v[14:15] neg_lo:[0,1] neg_hi:[0,1]
	v_pk_mul_f32 v[26:27], v[4:5], s[60:61] op_sel_hi:[1,0]
	s_nop 0
	v_pk_fma_f32 v[4:5], v[100:101], s[60:61], v[26:27] op_sel_hi:[1,0,1] neg_lo:[0,0,1] neg_hi:[0,0,1]
	v_xor_b32_e32 v100, 0x80000000, v25
	v_pk_add_f32 v[26:27], v[12:13], v[4:5]
	v_pk_add_f32 v[4:5], v[12:13], v[4:5] neg_lo:[0,1] neg_hi:[0,1]
	v_pk_add_f32 v[12:13], v[92:93], v[84:85]
	v_pk_add_f32 v[84:85], v[92:93], v[84:85] neg_lo:[0,1] neg_hi:[0,1]
	v_pk_mul_f32 v[92:93], v[62:63], s[60:61] op_sel:[1,0] op_sel_hi:[0,0] neg_lo:[1,0]
	v_mov_b32_e32 v101, v24
	v_pk_fma_f32 v[62:63], v[62:63], s[60:61], v[92:93] op_sel_hi:[1,0,1]
	s_nop 0
	v_pk_add_f32 v[92:93], v[2:3], v[62:63]
	v_pk_add_f32 v[2:3], v[2:3], v[62:63] neg_lo:[0,1] neg_hi:[0,1]
	v_xor_b32_e32 v62, 0x80000000, v65
	v_mov_b32_e32 v63, v64
	v_pk_add_f32 v[64:65], v[22:23], v[62:63]
	v_pk_add_f32 v[22:23], v[22:23], v[62:63] neg_lo:[0,1] neg_hi:[0,1]
	v_pk_mul_f32 v[62:63], v[24:25], s[60:61] op_sel_hi:[1,0]
	s_nop 0
	v_pk_fma_f32 v[24:25], v[100:101], s[60:61], v[62:63] op_sel_hi:[1,0,1] neg_lo:[0,0,1] neg_hi:[0,0,1]
	v_xor_b32_e32 v100, 0x80000000, v21
	v_pk_add_f32 v[62:63], v[68:69], v[24:25]
	v_pk_add_f32 v[24:25], v[68:69], v[24:25] neg_lo:[0,1] neg_hi:[0,1]
	v_pk_add_f32 v[68:69], v[80:81], v[96:97]
	v_pk_add_f32 v[80:81], v[80:81], v[96:97] neg_lo:[0,1] neg_hi:[0,1]
	v_pk_mul_f32 v[96:97], v[66:67], s[60:61] op_sel:[1,0] op_sel_hi:[0,0] neg_lo:[1,0]
	v_mov_b32_e32 v101, v20
	v_pk_fma_f32 v[66:67], v[66:67], s[60:61], v[96:97] op_sel_hi:[1,0,1]
	s_nop 0
	v_pk_add_f32 v[96:97], v[70:71], v[66:67]
	v_pk_add_f32 v[66:67], v[70:71], v[66:67] neg_lo:[0,1] neg_hi:[0,1]
	v_xor_b32_e32 v70, 0x80000000, v89
	v_mov_b32_e32 v71, v88
	v_pk_add_f32 v[88:89], v[90:91], v[70:71]
	v_pk_add_f32 v[70:71], v[90:91], v[70:71] neg_lo:[0,1] neg_hi:[0,1]
	v_pk_mul_f32 v[90:91], v[20:21], s[60:61] op_sel_hi:[1,0]
	s_nop 0
	v_pk_fma_f32 v[20:21], v[100:101], s[60:61], v[90:91] op_sel_hi:[1,0,1] neg_lo:[0,0,1] neg_hi:[0,0,1]
	s_nop 0
	v_pk_add_f32 v[90:91], v[72:73], v[20:21]
	v_pk_add_f32 v[20:21], v[72:73], v[20:21] neg_lo:[0,1] neg_hi:[0,1]
	v_pk_add_f32 v[72:73], v[94:95], v[8:9]
	v_pk_add_f32 v[8:9], v[94:95], v[8:9] neg_lo:[0,1] neg_hi:[0,1]
	v_pk_mul_f32 v[94:95], v[82:83], s[54:55] op_sel:[1,0] op_sel_hi:[0,0] neg_lo:[1,0]
	s_nop 0
	v_pk_fma_f32 v[82:83], v[82:83], s[52:53], v[94:95] op_sel_hi:[1,0,1]
	s_nop 0
	v_pk_add_f32 v[94:95], v[98:99], v[82:83]
	v_pk_add_f32 v[82:83], v[98:99], v[82:83] neg_lo:[0,1] neg_hi:[0,1]
	v_pk_mul_f32 v[98:99], v[86:87], s[60:61] op_sel:[1,0] op_sel_hi:[0,0] neg_lo:[1,0]
	s_nop 0
	v_pk_fma_f32 v[86:87], v[86:87], s[60:61], v[98:99] op_sel_hi:[1,0,1]
	s_nop 0
	v_pk_add_f32 v[98:99], v[76:77], v[86:87]
	v_pk_add_f32 v[86:87], v[76:77], v[86:87] neg_lo:[0,1] neg_hi:[0,1]
	v_pk_mul_f32 v[76:77], v[26:27], s[52:53] op_sel:[1,0] op_sel_hi:[0,0] neg_lo:[1,0]
	s_nop 0
	v_pk_fma_f32 v[26:27], v[26:27], s[54:55], v[76:77] op_sel_hi:[1,0,1]
	v_xor_b32_e32 v76, 0x80000000, v67
	v_pk_add_f32 v[100:101], v[18:19], v[26:27]
	v_pk_add_f32 v[26:27], v[18:19], v[26:27] neg_lo:[0,1] neg_hi:[0,1]
	v_pk_add_f32 v[102:103], v[74:75], v[78:79] op_sel:[0,1] op_sel_hi:[1,0] neg_lo:[0,1]
	v_pk_add_f32 v[104:105], v[74:75], v[78:79] op_sel:[0,1] op_sel_hi:[1,0] neg_hi:[0,1]
	v_pk_mul_f32 v[18:19], v[6:7], s[54:55] op_sel_hi:[1,0]
	v_xor_b32_e32 v74, 0x80000000, v7
	v_mov_b32_e32 v75, v6
	v_pk_fma_f32 v[6:7], v[74:75], s[52:53], v[18:19] op_sel_hi:[1,0,1] neg_lo:[0,0,1] neg_hi:[0,0,1]
	v_xor_b32_e32 v74, 0x80000000, v15
	v_pk_add_f32 v[18:19], v[10:11], v[6:7]
	v_pk_add_f32 v[6:7], v[10:11], v[6:7] neg_lo:[0,1] neg_hi:[0,1]
	v_pk_mul_f32 v[10:11], v[14:15], s[60:61] op_sel_hi:[1,0]
	v_mov_b32_e32 v75, v14
	v_pk_fma_f32 v[10:11], v[74:75], s[60:61], v[10:11] op_sel_hi:[1,0,1] neg_lo:[0,0,1] neg_hi:[0,0,1]
	v_xor_b32_e32 v74, 0x80000000, v5
	v_pk_add_f32 v[14:15], v[16:17], v[10:11]
	v_pk_add_f32 v[10:11], v[16:17], v[10:11] neg_lo:[0,1] neg_hi:[0,1]
	v_pk_mul_f32 v[16:17], v[4:5], s[52:53] op_sel_hi:[1,0]
	v_mov_b32_e32 v75, v4
	v_pk_fma_f32 v[4:5], v[74:75], s[54:55], v[16:17] op_sel_hi:[1,0,1] neg_lo:[0,0,1] neg_hi:[0,0,1]
	v_xor_b32_e32 v74, 0x80000000, v89
	v_pk_add_f32 v[16:17], v[0:1], v[4:5]
	v_pk_add_f32 v[106:107], v[0:1], v[4:5] neg_lo:[0,1] neg_hi:[0,1]
	v_pk_add_f32 v[0:1], v[12:13], v[68:69]
	v_pk_add_f32 v[4:5], v[12:13], v[68:69] neg_lo:[0,1] neg_hi:[0,1]
	v_mov_b32_e32 v75, v88
	v_pk_mul_f32 v[12:13], v[96:97], s[54:55] op_sel:[1,0] op_sel_hi:[0,0] neg_lo:[1,0]
	v_pk_mul_f32 v[74:75], v[74:75], s[60:61] op_sel_hi:[1,0]
	v_pk_fma_f32 v[12:13], v[96:97], s[52:53], v[12:13] op_sel_hi:[1,0,1]
	v_pk_fma_f32 v[74:75], v[88:89], s[60:61], v[74:75] op_sel_hi:[1,0,1]
	v_pk_add_f32 v[68:69], v[92:93], v[12:13]
	v_pk_add_f32 v[12:13], v[92:93], v[12:13] neg_lo:[0,1] neg_hi:[0,1]
	v_pk_add_f32 v[88:89], v[64:65], v[74:75]
	v_pk_add_f32 v[92:93], v[64:65], v[74:75] neg_lo:[0,1] neg_hi:[0,1]
	v_pk_mul_f32 v[64:65], v[90:91], s[52:53] op_sel:[1,0] op_sel_hi:[0,0] neg_lo:[1,0]
	v_pk_add_f32 v[78:79], v[72:73], v[0:1]
	v_pk_fma_f32 v[64:65], v[90:91], s[54:55], v[64:65] op_sel_hi:[1,0,1]
	s_nop 0
	v_pk_add_f32 v[74:75], v[62:63], v[64:65]
	v_pk_add_f32 v[90:91], v[62:63], v[64:65] neg_lo:[0,1] neg_hi:[0,1]
	v_pk_mul_f32 v[0:1], v[68:69], s[48:49] op_sel:[1,0] op_sel_hi:[0,0] neg_lo:[1,0]
	v_pk_add_f32 v[64:65], v[84:85], v[80:81] op_sel:[0,1] op_sel_hi:[1,0] neg_lo:[0,1]
	v_pk_add_f32 v[80:81], v[84:85], v[80:81] op_sel:[0,1] op_sel_hi:[1,0] neg_hi:[0,1]
	v_pk_mul_f32 v[62:63], v[66:67], s[54:55] op_sel_hi:[1,0]
	v_mov_b32_e32 v77, v66
	v_pk_fma_f32 v[0:1], v[68:69], s[44:45], v[0:1] op_sel_hi:[1,0,1]
	v_pk_fma_f32 v[62:63], v[76:77], s[52:53], v[62:63] op_sel_hi:[1,0,1] neg_lo:[0,0,1] neg_hi:[0,0,1]
	v_pk_add_f32 v[76:77], v[94:95], v[0:1]
	v_pk_mul_f32 v[0:1], v[88:89], s[54:55] op_sel:[1,0] op_sel_hi:[0,0] neg_lo:[1,0]
	v_pk_add_f32 v[84:85], v[2:3], v[62:63]
	v_pk_fma_f32 v[0:1], v[88:89], s[52:53], v[0:1] op_sel_hi:[1,0,1]
	v_pk_add_f32 v[2:3], v[2:3], v[62:63] neg_lo:[0,1] neg_hi:[0,1]
	v_pk_add_f32 v[72:73], v[98:99], v[0:1]
	v_pk_mul_f32 v[0:1], v[74:75], s[58:59] op_sel:[1,0] op_sel_hi:[0,0] neg_lo:[1,0]
	v_pk_mul_f32 v[62:63], v[70:71], s[60:61] op_sel_hi:[1,0]
	v_pk_fma_f32 v[0:1], v[74:75], s[56:57], v[0:1] op_sel_hi:[1,0,1]
	v_xor_b32_e32 v66, 0x80000000, v71
	v_pk_add_f32 v[74:75], v[100:101], v[0:1]
	v_pk_mul_f32 v[0:1], v[64:65], s[60:61] op_sel:[1,0] op_sel_hi:[0,0] neg_lo:[1,0]
	v_mov_b32_e32 v67, v70
	v_pk_fma_f32 v[0:1], v[64:65], s[60:61], v[0:1] op_sel_hi:[1,0,1]
	v_pk_fma_f32 v[62:63], v[66:67], s[60:61], v[62:63] op_sel_hi:[1,0,1] neg_lo:[0,0,1] neg_hi:[0,0,1]
	v_pk_add_f32 v[66:67], v[102:103], v[0:1]
	v_pk_mul_f32 v[0:1], v[84:85], s[56:57] op_sel:[1,0] op_sel_hi:[0,0] neg_lo:[1,0]
	v_pk_add_f32 v[70:71], v[22:23], v[62:63]
	v_pk_fma_f32 v[0:1], v[84:85], s[58:59], v[0:1] op_sel_hi:[1,0,1]
	v_pk_add_f32 v[96:97], v[22:23], v[62:63] neg_lo:[0,1] neg_hi:[0,1]
	v_pk_mul_f32 v[22:23], v[20:21], s[52:53] op_sel_hi:[1,0]
	v_pk_add_f32 v[68:69], v[18:19], v[0:1]
	v_pk_fma_f32 v[20:21], v[20:21], s[54:55], v[22:23] op_sel:[1,0,0] op_sel_hi:[0,0,1] neg_lo:[1,0,1] neg_hi:[0,0,1]
	v_pk_mul_f32 v[0:1], v[70:71], s[52:53] op_sel:[1,0] op_sel_hi:[0,0] neg_lo:[1,0]
	v_pk_add_f32 v[22:23], v[24:25], v[20:21]
	v_pk_fma_f32 v[0:1], v[70:71], s[54:55], v[0:1] op_sel_hi:[1,0,1]
	v_pk_add_f32 v[108:109], v[24:25], v[20:21] neg_lo:[0,1] neg_hi:[0,1]
	v_pk_add_f32 v[62:63], v[14:15], v[0:1]
	v_pk_mul_f32 v[0:1], v[22:23], s[44:45] op_sel:[1,0] op_sel_hi:[0,0] neg_lo:[1,0]
	s_nop 0
	v_pk_fma_f32 v[0:1], v[22:23], s[48:49], v[0:1] op_sel_hi:[1,0,1]
	s_nop 0
	v_pk_add_f32 v[64:65], v[16:17], v[0:1]
	v_pk_add_f32 v[22:23], v[8:9], v[4:5] op_sel:[0,1] op_sel_hi:[1,0] neg_lo:[0,1]
	v_pk_mul_f32 v[0:1], v[12:13], s[48:49] op_sel_hi:[1,0]
	v_xor_b32_e32 v4, 0x80000000, v13
	v_mov_b32_e32 v5, v12
	v_pk_fma_f32 v[0:1], v[4:5], s[44:45], v[0:1] op_sel_hi:[1,0,1] neg_lo:[0,0,1] neg_hi:[0,0,1]
	v_xor_b32_e32 v4, 0x80000000, v93
	v_pk_add_f32 v[24:25], v[82:83], v[0:1]
	v_pk_mul_f32 v[0:1], v[92:93], s[54:55] op_sel_hi:[1,0]
	v_mov_b32_e32 v5, v92
	v_pk_fma_f32 v[0:1], v[4:5], s[52:53], v[0:1] op_sel_hi:[1,0,1] neg_lo:[0,0,1] neg_hi:[0,0,1]
	v_xor_b32_e32 v4, 0x80000000, v91
	v_pk_add_f32 v[18:19], v[86:87], v[0:1]
	v_pk_mul_f32 v[0:1], v[90:91], s[58:59] op_sel_hi:[1,0]
	v_mov_b32_e32 v5, v90
	v_pk_fma_f32 v[0:1], v[4:5], s[56:57], v[0:1] op_sel_hi:[1,0,1] neg_lo:[0,0,1] neg_hi:[0,0,1]
	s_nop 0
	v_pk_add_f32 v[20:21], v[26:27], v[0:1]
	v_pk_mul_f32 v[0:1], v[80:81], s[60:61] op_sel_hi:[1,0]
	s_nop 0
	v_pk_fma_f32 v[0:1], v[80:81], s[60:61], v[0:1] op_sel:[1,0,0] op_sel_hi:[0,0,1] neg_lo:[1,0,1] neg_hi:[0,0,1]
	v_xor_b32_e32 v8, 0x80000000, v3
	v_pk_add_f32 v[4:5], v[104:105], v[0:1]
	v_pk_mul_f32 v[0:1], v[2:3], s[56:57] op_sel_hi:[1,0]
	v_mov_b32_e32 v9, v2
	v_pk_fma_f32 v[0:1], v[8:9], s[58:59], v[0:1] op_sel_hi:[1,0,1] neg_lo:[0,0,1] neg_hi:[0,0,1]
	s_nop 0
	v_pk_add_f32 v[6:7], v[6:7], v[0:1]
	v_pk_mul_f32 v[0:1], v[96:97], s[52:53] op_sel_hi:[1,0]
	s_nop 0
	v_pk_fma_f32 v[0:1], v[96:97], s[54:55], v[0:1] op_sel:[1,0,0] op_sel_hi:[0,0,1] neg_lo:[1,0,1] neg_hi:[0,0,1]
	v_pk_mul_f32 v[2:3], v[108:109], s[44:45] op_sel_hi:[1,0]
	v_pk_add_f32 v[0:1], v[10:11], v[0:1]
	v_xor_b32_e32 v8, 0x80000000, v109
	v_mov_b32_e32 v9, v108
	v_mov_b32_e32 v10, v146
	v_pk_fma_f32 v[2:3], v[8:9], s[48:49], v[2:3] op_sel_hi:[1,0,1] neg_lo:[0,0,1] neg_hi:[0,0,1]
	global_load_dword v8, v145, s[0:1]
	s_movk_i32 s0, 0x200
	s_cselect_b32 s4, s0, 0x400
	s_add_i32 s0, s4, s62
	s_ashr_i32 s1, s0, 31
	s_lshl_b32 s6, s4, 2
	s_add_u32 s4, s64, s6
	s_addc_u32 s5, s65, 0
	s_lshl_b64 s[0:1], s[0:1], 14
	v_min_i32_e32 v70, 0x1ffe, v10
	v_mov_b32_e32 v9, s6
	s_add_u32 s36, s26, s0
	v_ashrrev_i32_e32 v11, 31, v10
	v_ashrrev_i32_e32 v71, 31, v70
	global_load_dword v16, v9, s[64:65]
	global_load_dword v14, v151, s[4:5] offset:2048
	global_load_dword v17, v152, s[4:5]
	global_load_dword v12, v9, s[68:69]
	s_addc_u32 s37, s27, s1
	v_max_i32_e32 v9, 1, v10
	v_lshlrev_b64 v[82:83], 1, v[10:11]
	v_lshlrev_b64 v[84:85], 1, v[70:71]
	v_lshl_add_u64 v[26:27], s[36:37], 0, v[82:83]
	v_lshlrev_b32_e32 v9, 1, v9
	v_lshl_add_u64 v[70:71], s[36:37], 0, v[84:85]
	global_load_ushort v13, v[26:27], off
	s_add_u32 s72, s30, s0
	global_load_ushort v70, v[70:71], off offset:2
	s_addc_u32 s73, s31, s1
	global_load_ushort v15, v9, s[36:37] offset:-2
	v_cmp_lt_i32_e64 s[0:1], 0, v10
	v_cmp_gt_i32_e64 s[4:5], s88, v10
	v_pk_add_f32 v[2:3], v[106:107], v[2:3]
	v_cndmask_b32_e64 v81, 0, 1.0, s[0:1]
	v_cndmask_b32_e64 v86, 0, 1.0, s[4:5]
	v_add_u32_e32 v92, 0x200, v10
	v_cmp_lt_i32_e64 s[20:21], s33, v10
	v_cmp_gt_i32_e64 s[18:19], s92, v10
	v_add_u32_e32 v90, 0x400, v10
	v_cmp_lt_i32_e64 s[16:17], s81, v10
	v_cmp_gt_i32_e64 s[0:1], s38, v10
	v_add_u32_e32 v88, 0x600, v10
	v_cmp_lt_i32_e64 s[12:13], s93, v10
	v_cmp_gt_i32_e64 s[10:11], s3, v10
	v_cmp_lt_i32_e64 s[8:9], s50, v10
	v_cmp_gt_i32_e64 s[6:7], s90, v10
	v_cmp_lt_i32_e64 s[4:5], s39, v10
	v_cmp_gt_i32_e64 s[22:23], s51, v10
	s_waitcnt vmcnt(2)
	v_lshlrev_b32_e32 v13, 16, v13
	s_waitcnt vmcnt(1)
	v_lshlrev_b32_e32 v70, 16, v70
	v_mul_f32_e32 v70, v86, v70
	s_waitcnt vmcnt(0)
	v_lshlrev_b32_e32 v15, 16, v15
	v_mul_f32_e32 v15, v81, v15
	v_mul_f32_e32 v15, v16, v15
	v_fmac_f32_e32 v15, v14, v13
	v_fmac_f32_e32 v15, v17, v70
	v_lshl_add_u64 v[70:71], s[72:73], 0, v[82:83]
	v_lshl_add_u64 v[82:83], s[72:73], 0, v[84:85]
	v_add_f32_e32 v80, v12, v15
	global_load_ushort v13, v[70:71], off
	global_load_ushort v15, v[82:83], off offset:2
	v_add_u32_e32 v84, 0x800, v10
	global_load_ushort v9, v9, s[72:73] offset:-2
	v_add_u32_e32 v82, 0xa00, v10
	s_waitcnt vmcnt(2)
	v_lshlrev_b32_e32 v13, 16, v13
	s_waitcnt vmcnt(1)
	v_lshlrev_b32_e32 v15, 16, v15
	v_mul_f32_e32 v15, v86, v15
	s_waitcnt vmcnt(0)
	v_lshlrev_b32_e32 v9, 16, v9
	v_mul_f32_e32 v9, v81, v9
	v_mul_f32_e32 v9, v16, v9
	v_fmac_f32_e32 v9, v14, v13
	v_fmac_f32_e32 v9, v17, v15
	v_add_f32_e32 v86, v12, v9
	s_cbranch_vccnz .LBB0_912
	s_mov_b32 s98, s29
	s_lshl_b64 s[0:1], s[66:67], 1
	s_add_u32 s4, s0, s30
	s_addc_u32 s5, s1, s31
	s_add_u32 s0, s0, s26
	s_addc_u32 s1, s1, s27
	s_add_u32 s18, s70, 0x800000
	s_addc_u32 s19, s71, 0
	s_cmpk_gt_i32 s98, 0xff
	s_cbranch_scc1 .Lhy_ep1_comb_L1
	v_lshlrev_b32_e32 v109, 1, v10
	global_load_ushort v9, v109, s[0:1]
	global_load_ushort v11, v109, s[4:5]
	global_load_ushort v13, v109, s[36:37] offset:1022
	global_load_ushort v15, v109, s[36:37] offset:1024
	global_load_ushort v81, v109, s[36:37] offset:1026
	global_load_ushort v83, v109, s[72:73] offset:1022
	global_load_ushort v85, v109, s[72:73] offset:1024
	global_load_ushort v87, v109, s[72:73] offset:1026
	global_load_ushort v89, v109, s[0:1] offset:1024
	global_load_ushort v91, v109, s[4:5] offset:1024
	global_load_ushort v93, v109, s[36:37] offset:2046
	global_load_ushort v94, v109, s[36:37] offset:2048
	global_load_ushort v95, v109, s[36:37] offset:2050
	global_load_ushort v96, v109, s[72:73] offset:2046
	global_load_ushort v97, v109, s[72:73] offset:2048
	global_load_ushort v98, v109, s[72:73] offset:2050
	global_load_ushort v99, v109, s[0:1] offset:2048
	global_load_ushort v100, v109, s[4:5] offset:2048
	global_load_ushort v101, v109, s[36:37] offset:3070
	global_load_ushort v102, v109, s[36:37] offset:3072
	global_load_ushort v103, v109, s[36:37] offset:3074
	global_load_ushort v104, v109, s[72:73] offset:3070
	global_load_ushort v105, v109, s[72:73] offset:3072
	global_load_ushort v106, v109, s[72:73] offset:3074
	global_load_ushort v107, v109, s[0:1] offset:3072
	global_load_ushort v108, v109, s[4:5] offset:3072
	s_waitcnt vmcnt(0)
	v_fma_f32 v27, v32, v8, v78
	v_mul_f32_e32 v70, v80, v27
	v_lshlrev_b32_e32 v9, 16, v9
	v_mul_f32_e32 v84, 0xbfb8aa3b, v9
	v_exp_f32_e32 v84, v84
	s_nop 0
	v_add_f32_e32 v84, 1.0, v84
	v_div_scale_f32 v71, s[74:75], v84, v84, v9
	v_rcp_f32_e32 v82, v71
	s_nop 0
	v_fma_f32 v92, -v71, v82, 1.0
	v_fmac_f32_e32 v82, v92, v82
	v_div_scale_f32 v88, vcc, v9, v84, v9
	v_mul_f32_e32 v90, v88, v82
	v_fma_f32 v92, -v71, v90, v88
	v_fmac_f32_e32 v90, v92, v82
	v_fma_f32 v71, -v71, v90, v88
	v_div_fmas_f32 v71, v71, v82, v90
	v_div_fixup_f32 v9, v71, v84, v9
	v_mul_f32_e32 v70, v70, v9
	v_fma_f32 v27, v34, v8, v79
	v_mul_f32_e32 v110, v86, v27
	v_lshlrev_b32_e32 v11, 16, v11
	v_mul_f32_e32 v84, 0xbfb8aa3b, v11
	v_exp_f32_e32 v84, v84
	s_nop 0
	v_add_f32_e32 v84, 1.0, v84
	v_div_scale_f32 v71, s[74:75], v84, v84, v11
	v_rcp_f32_e32 v82, v71
	s_nop 0
	v_fma_f32 v92, -v71, v82, 1.0
	v_fmac_f32_e32 v82, v92, v82
	v_div_scale_f32 v88, vcc, v11, v84, v11
	v_mul_f32_e32 v90, v88, v82
	v_fma_f32 v92, -v71, v90, v88
	v_fmac_f32_e32 v90, v92, v82
	v_fma_f32 v71, -v71, v90, v88
	v_div_fmas_f32 v71, v71, v82, v90
	v_div_fixup_f32 v11, v71, v84, v11
	v_mul_f32_e32 v110, v110, v11
	v_cvt_pk_bf16_f32 v198, v70, v110
	v_lshlrev_b32_e32 v15, 16, v15
	v_lshlrev_b32_e32 v81, 16, v81
	v_lshlrev_b32_e32 v13, 16, v13
	v_mul_f32_e32 v13, v16, v13
	v_fmac_f32_e32 v13, v14, v15
	v_fmac_f32_e32 v13, v17, v81
	v_add_f32_e32 v13, v12, v13
	v_fma_f32 v27, v33, v8, v76
	v_mul_f32_e32 v70, v27, v13
	v_lshlrev_b32_e32 v89, 16, v89
	v_mul_f32_e32 v84, 0xbfb8aa3b, v89
	v_exp_f32_e32 v84, v84
	s_nop 0
	v_add_f32_e32 v84, 1.0, v84
	v_div_scale_f32 v71, s[74:75], v84, v84, v89
	v_rcp_f32_e32 v82, v71
	s_nop 0
	v_fma_f32 v92, -v71, v82, 1.0
	v_fmac_f32_e32 v82, v92, v82
	v_div_scale_f32 v88, vcc, v89, v84, v89
	v_mul_f32_e32 v90, v88, v82
	v_fma_f32 v92, -v71, v90, v88
	v_fmac_f32_e32 v90, v92, v82
	v_fma_f32 v71, -v71, v90, v88
	v_div_fmas_f32 v71, v71, v82, v90
	v_div_fixup_f32 v89, v71, v84, v89
	v_mul_f32_e32 v70, v70, v89
	v_lshlrev_b32_e32 v85, 16, v85
	v_lshlrev_b32_e32 v87, 16, v87
	v_lshlrev_b32_e32 v83, 16, v83
	v_mul_f32_e32 v83, v16, v83
	v_fmac_f32_e32 v83, v14, v85
	v_fmac_f32_e32 v83, v17, v87
	v_add_f32_e32 v83, v12, v83
	v_fma_f32 v27, v35, v8, v77
	v_mul_f32_e32 v110, v27, v83
	v_lshlrev_b32_e32 v91, 16, v91
	v_mul_f32_e32 v84, 0xbfb8aa3b, v91
	v_exp_f32_e32 v84, v84
	s_nop 0
	v_add_f32_e32 v84, 1.0, v84
	v_div_scale_f32 v71, s[74:75], v84, v84, v91
	v_rcp_f32_e32 v82, v71
	s_nop 0
	v_fma_f32 v92, -v71, v82, 1.0
	v_fmac_f32_e32 v82, v92, v82
	v_div_scale_f32 v88, vcc, v91, v84, v91
	v_mul_f32_e32 v90, v88, v82
	v_fma_f32 v92, -v71, v90, v88
	v_fmac_f32_e32 v90, v92, v82
	v_fma_f32 v71, -v71, v90, v88
	v_div_fmas_f32 v71, v71, v82, v90
	v_div_fixup_f32 v91, v71, v84, v91
	v_mul_f32_e32 v110, v110, v91
	v_cvt_pk_bf16_f32 v199, v70, v110
	v_lshlrev_b32_e32 v94, 16, v94
	v_lshlrev_b32_e32 v95, 16, v95
	v_lshlrev_b32_e32 v93, 16, v93
	v_mul_f32_e32 v93, v16, v93
	v_fmac_f32_e32 v93, v14, v94
	v_fmac_f32_e32 v93, v17, v95
	v_add_f32_e32 v93, v12, v93
	v_fma_f32 v27, v37, v8, v72
	v_mul_f32_e32 v70, v27, v93
	v_lshlrev_b32_e32 v99, 16, v99
	v_mul_f32_e32 v84, 0xbfb8aa3b, v99
	v_exp_f32_e32 v84, v84
	s_nop 0
	v_add_f32_e32 v84, 1.0, v84
	v_div_scale_f32 v71, s[74:75], v84, v84, v99
	v_rcp_f32_e32 v82, v71
	s_nop 0
	v_fma_f32 v92, -v71, v82, 1.0
	v_fmac_f32_e32 v82, v92, v82
	v_div_scale_f32 v88, vcc, v99, v84, v99
	v_mul_f32_e32 v90, v88, v82
	v_fma_f32 v92, -v71, v90, v88
	v_fmac_f32_e32 v90, v92, v82
	v_fma_f32 v71, -v71, v90, v88
	v_div_fmas_f32 v71, v71, v82, v90
	v_div_fixup_f32 v99, v71, v84, v99
	v_mul_f32_e32 v70, v70, v99
	v_lshlrev_b32_e32 v97, 16, v97
	v_lshlrev_b32_e32 v98, 16, v98
	v_lshlrev_b32_e32 v96, 16, v96
	v_mul_f32_e32 v96, v16, v96
	v_fmac_f32_e32 v96, v14, v97
	v_fmac_f32_e32 v96, v17, v98
	v_add_f32_e32 v96, v12, v96
	v_fma_f32 v27, v31, v8, v73
	v_mul_f32_e32 v110, v27, v96
	v_lshlrev_b32_e32 v100, 16, v100
	v_mul_f32_e32 v84, 0xbfb8aa3b, v100
	v_exp_f32_e32 v84, v84
	s_nop 0
	v_add_f32_e32 v84, 1.0, v84
	v_div_scale_f32 v71, s[74:75], v84, v84, v100
	v_rcp_f32_e32 v82, v71
	s_nop 0
	v_fma_f32 v92, -v71, v82, 1.0
	v_fmac_f32_e32 v82, v92, v82
	v_div_scale_f32 v88, vcc, v100, v84, v100
	v_mul_f32_e32 v90, v88, v82
	v_fma_f32 v92, -v71, v90, v88
	v_fmac_f32_e32 v90, v92, v82
	v_fma_f32 v71, -v71, v90, v88
	v_div_fmas_f32 v71, v71, v82, v90
	v_div_fixup_f32 v100, v71, v84, v100
	v_mul_f32_e32 v110, v110, v100
	v_cvt_pk_bf16_f32 v200, v70, v110
	v_lshlrev_b32_e32 v102, 16, v102
	v_lshlrev_b32_e32 v103, 16, v103
	v_lshlrev_b32_e32 v101, 16, v101
	v_mul_f32_e32 v101, v16, v101
	v_fmac_f32_e32 v101, v14, v102
	v_fmac_f32_e32 v101, v17, v103
	v_add_f32_e32 v101, v12, v101
	v_fma_f32 v27, v36, v8, v74
	v_mul_f32_e32 v70, v27, v101
	v_lshlrev_b32_e32 v107, 16, v107
	v_mul_f32_e32 v84, 0xbfb8aa3b, v107
	v_exp_f32_e32 v84, v84
	s_nop 0
	v_add_f32_e32 v84, 1.0, v84
	v_div_scale_f32 v71, s[74:75], v84, v84, v107
	v_rcp_f32_e32 v82, v71
	s_nop 0
	v_fma_f32 v92, -v71, v82, 1.0
	v_fmac_f32_e32 v82, v92, v82
	v_div_scale_f32 v88, vcc, v107, v84, v107
	v_mul_f32_e32 v90, v88, v82
	v_fma_f32 v92, -v71, v90, v88
	v_fmac_f32_e32 v90, v92, v82
	v_fma_f32 v71, -v71, v90, v88
	v_div_fmas_f32 v71, v71, v82, v90
	v_div_fixup_f32 v107, v71, v84, v107
	v_mul_f32_e32 v70, v70, v107
	v_lshlrev_b32_e32 v105, 16, v105
	v_lshlrev_b32_e32 v106, 16, v106
	v_lshlrev_b32_e32 v104, 16, v104
	v_mul_f32_e32 v104, v16, v104
	v_fmac_f32_e32 v104, v14, v105
	v_fmac_f32_e32 v104, v17, v106
	v_add_f32_e32 v104, v12, v104
	v_fma_f32 v27, v30, v8, v75
	v_mul_f32_e32 v110, v27, v104
	v_lshlrev_b32_e32 v108, 16, v108
	v_mul_f32_e32 v84, 0xbfb8aa3b, v108
	v_exp_f32_e32 v84, v84
	s_nop 0
	v_add_f32_e32 v84, 1.0, v84
	v_div_scale_f32 v71, s[74:75], v84, v84, v108
	v_rcp_f32_e32 v82, v71
	s_nop 0
	v_fma_f32 v92, -v71, v82, 1.0
	v_fmac_f32_e32 v82, v92, v82
	v_div_scale_f32 v88, vcc, v108, v84, v108
	v_mul_f32_e32 v90, v88, v82
	v_fma_f32 v92, -v71, v90, v88
	v_fmac_f32_e32 v90, v92, v82
	v_fma_f32 v71, -v71, v90, v88
	v_div_fmas_f32 v71, v71, v82, v90
	v_div_fixup_f32 v108, v71, v84, v108
	v_mul_f32_e32 v110, v110, v108
	v_cvt_pk_bf16_f32 v201, v70, v110
	v_add_u32_e32 v109, 0x1000, v109
	global_load_ushort v9, v109, s[36:37] offset:-2
	global_load_ushort v11, v109, s[36:37]
	global_load_ushort v13, v109, s[36:37] offset:2
	global_load_ushort v15, v109, s[72:73] offset:-2
	global_load_ushort v81, v109, s[72:73]
	global_load_ushort v83, v109, s[72:73] offset:2
	global_load_ushort v85, v109, s[0:1]
	global_load_ushort v87, v109, s[4:5]
	global_load_ushort v89, v109, s[36:37] offset:1022
	global_load_ushort v91, v109, s[36:37] offset:1024
	global_load_ushort v93, v109, s[36:37] offset:1026
	global_load_ushort v94, v109, s[72:73] offset:1022
	global_load_ushort v95, v109, s[72:73] offset:1024
	global_load_ushort v96, v109, s[72:73] offset:1026
	global_load_ushort v97, v109, s[0:1] offset:1024
	global_load_ushort v98, v109, s[4:5] offset:1024
	global_load_ushort v99, v109, s[36:37] offset:2046
	global_load_ushort v100, v109, s[36:37] offset:2048
	global_load_ushort v101, v109, s[36:37] offset:2050
	global_load_ushort v102, v109, s[72:73] offset:2046
	global_load_ushort v103, v109, s[72:73] offset:2048
	global_load_ushort v104, v109, s[72:73] offset:2050
	global_load_ushort v105, v109, s[0:1] offset:2048
	global_load_ushort v106, v109, s[4:5] offset:2048
	global_load_ushort v107, v109, s[36:37] offset:3070
	global_load_ushort v108, v109, s[36:37] offset:3072
	global_load_ushort v32, v109, s[36:37] offset:3074
	global_load_ushort v78, v109, s[72:73] offset:3070
	global_load_ushort v34, v109, s[72:73] offset:3072
	global_load_ushort v79, v109, s[72:73] offset:3074
	global_load_ushort v33, v109, s[0:1] offset:3072
	global_load_ushort v76, v109, s[4:5] offset:3072
	s_waitcnt vmcnt(0)
	v_lshlrev_b32_e32 v11, 16, v11
	v_lshlrev_b32_e32 v13, 16, v13
	v_lshlrev_b32_e32 v9, 16, v9
	v_mul_f32_e32 v9, v16, v9
	v_fmac_f32_e32 v9, v14, v11
	v_fmac_f32_e32 v9, v17, v13
	v_add_f32_e32 v9, v12, v9
	v_fma_f32 v27, v39, v8, v66
	v_mul_f32_e32 v70, v27, v9
	v_lshlrev_b32_e32 v85, 16, v85
	v_mul_f32_e32 v84, 0xbfb8aa3b, v85
	v_exp_f32_e32 v84, v84
	s_nop 0
	v_add_f32_e32 v84, 1.0, v84
	v_div_scale_f32 v71, s[74:75], v84, v84, v85
	v_rcp_f32_e32 v82, v71
	s_nop 0
	v_fma_f32 v92, -v71, v82, 1.0
	v_fmac_f32_e32 v82, v92, v82
	v_div_scale_f32 v88, vcc, v85, v84, v85
	v_mul_f32_e32 v90, v88, v82
	v_fma_f32 v92, -v71, v90, v88
	v_fmac_f32_e32 v90, v92, v82
	v_fma_f32 v71, -v71, v90, v88
	v_div_fmas_f32 v71, v71, v82, v90
	v_div_fixup_f32 v85, v71, v84, v85
	v_mul_f32_e32 v70, v70, v85
	v_lshlrev_b32_e32 v81, 16, v81
	v_lshlrev_b32_e32 v83, 16, v83
	v_lshlrev_b32_e32 v15, 16, v15
	v_mul_f32_e32 v15, v16, v15
	v_fmac_f32_e32 v15, v14, v81
	v_fmac_f32_e32 v15, v17, v83
	v_add_f32_e32 v15, v12, v15
	v_fma_f32 v27, v41, v8, v67
	v_mul_f32_e32 v110, v27, v15
	v_lshlrev_b32_e32 v87, 16, v87
	v_mul_f32_e32 v84, 0xbfb8aa3b, v87
	v_exp_f32_e32 v84, v84
	s_nop 0
	v_add_f32_e32 v84, 1.0, v84
	v_div_scale_f32 v71, s[74:75], v84, v84, v87
	v_rcp_f32_e32 v82, v71
	s_nop 0
	v_fma_f32 v92, -v71, v82, 1.0
	v_fmac_f32_e32 v82, v92, v82
	v_div_scale_f32 v88, vcc, v87, v84, v87
	v_mul_f32_e32 v90, v88, v82
	v_fma_f32 v92, -v71, v90, v88
	v_fmac_f32_e32 v90, v92, v82
	v_fma_f32 v71, -v71, v90, v88
	v_div_fmas_f32 v71, v71, v82, v90
	v_div_fixup_f32 v87, v71, v84, v87
	v_mul_f32_e32 v110, v110, v87
	v_cvt_pk_bf16_f32 v202, v70, v110
	v_lshlrev_b32_e32 v91, 16, v91
	v_lshlrev_b32_e32 v93, 16, v93
	v_lshlrev_b32_e32 v89, 16, v89
	v_mul_f32_e32 v89, v16, v89
	v_fmac_f32_e32 v89, v14, v91
	v_fmac_f32_e32 v89, v17, v93
	v_add_f32_e32 v89, v12, v89
	v_fma_f32 v27, v38, v8, v68
	v_mul_f32_e32 v70, v27, v89
	v_lshlrev_b32_e32 v97, 16, v97
	v_mul_f32_e32 v84, 0xbfb8aa3b, v97
	v_exp_f32_e32 v84, v84
	s_nop 0
	v_add_f32_e32 v84, 1.0, v84
	v_div_scale_f32 v71, s[74:75], v84, v84, v97
	v_rcp_f32_e32 v82, v71
	s_nop 0
	v_fma_f32 v92, -v71, v82, 1.0
	v_fmac_f32_e32 v82, v92, v82
	v_div_scale_f32 v88, vcc, v97, v84, v97
	v_mul_f32_e32 v90, v88, v82
	v_fma_f32 v92, -v71, v90, v88
	v_fmac_f32_e32 v90, v92, v82
	v_fma_f32 v71, -v71, v90, v88
	v_div_fmas_f32 v71, v71, v82, v90
	v_div_fixup_f32 v97, v71, v84, v97
	v_mul_f32_e32 v70, v70, v97
	v_lshlrev_b32_e32 v95, 16, v95
	v_lshlrev_b32_e32 v96, 16, v96
	v_lshlrev_b32_e32 v94, 16, v94
	v_mul_f32_e32 v94, v16, v94
	v_fmac_f32_e32 v94, v14, v95
	v_fmac_f32_e32 v94, v17, v96
	v_add_f32_e32 v94, v12, v94
	v_fma_f32 v27, v40, v8, v69
	v_mul_f32_e32 v110, v27, v94
	v_lshlrev_b32_e32 v98, 16, v98
	v_mul_f32_e32 v84, 0xbfb8aa3b, v98
	v_exp_f32_e32 v84, v84
	s_nop 0
	v_add_f32_e32 v84, 1.0, v84
	v_div_scale_f32 v71, s[74:75], v84, v84, v98
	v_rcp_f32_e32 v82, v71
	s_nop 0
	v_fma_f32 v92, -v71, v82, 1.0
	v_fmac_f32_e32 v82, v92, v82
	v_div_scale_f32 v88, vcc, v98, v84, v98
	v_mul_f32_e32 v90, v88, v82
	v_fma_f32 v92, -v71, v90, v88
	v_fmac_f32_e32 v90, v92, v82
	v_fma_f32 v71, -v71, v90, v88
	v_div_fmas_f32 v71, v71, v82, v90
	v_div_fixup_f32 v98, v71, v84, v98
	v_mul_f32_e32 v110, v110, v98
	v_cvt_pk_bf16_f32 v203, v70, v110
	v_lshlrev_b32_e32 v100, 16, v100
	v_lshlrev_b32_e32 v101, 16, v101
	v_lshlrev_b32_e32 v99, 16, v99
	v_mul_f32_e32 v99, v16, v99
	v_fmac_f32_e32 v99, v14, v100
	v_fmac_f32_e32 v99, v17, v101
	v_add_f32_e32 v99, v12, v99
	v_fma_f32 v27, v43, v8, v62
	v_mul_f32_e32 v70, v27, v99
	v_lshlrev_b32_e32 v105, 16, v105
	v_mul_f32_e32 v84, 0xbfb8aa3b, v105
	v_exp_f32_e32 v84, v84
	s_nop 0
	v_add_f32_e32 v84, 1.0, v84
	v_div_scale_f32 v71, s[74:75], v84, v84, v105
	v_rcp_f32_e32 v82, v71
	s_nop 0
	v_fma_f32 v92, -v71, v82, 1.0
	v_fmac_f32_e32 v82, v92, v82
	v_div_scale_f32 v88, vcc, v105, v84, v105
	v_mul_f32_e32 v90, v88, v82
	v_fma_f32 v92, -v71, v90, v88
	v_fmac_f32_e32 v90, v92, v82
	v_fma_f32 v71, -v71, v90, v88
	v_div_fmas_f32 v71, v71, v82, v90
	v_div_fixup_f32 v105, v71, v84, v105
	v_mul_f32_e32 v70, v70, v105
	v_lshlrev_b32_e32 v103, 16, v103
	v_lshlrev_b32_e32 v104, 16, v104
	v_lshlrev_b32_e32 v102, 16, v102
	v_mul_f32_e32 v102, v16, v102
	v_fmac_f32_e32 v102, v14, v103
	v_fmac_f32_e32 v102, v17, v104
	v_add_f32_e32 v102, v12, v102
	v_fma_f32 v27, v45, v8, v63
	v_mul_f32_e32 v110, v27, v102
	v_lshlrev_b32_e32 v106, 16, v106
	v_mul_f32_e32 v84, 0xbfb8aa3b, v106
	v_exp_f32_e32 v84, v84
	s_nop 0
	v_add_f32_e32 v84, 1.0, v84
	v_div_scale_f32 v71, s[74:75], v84, v84, v106
	v_rcp_f32_e32 v82, v71
	s_nop 0
	v_fma_f32 v92, -v71, v82, 1.0
	v_fmac_f32_e32 v82, v92, v82
	v_div_scale_f32 v88, vcc, v106, v84, v106
	v_mul_f32_e32 v90, v88, v82
	v_fma_f32 v92, -v71, v90, v88
	v_fmac_f32_e32 v90, v92, v82
	v_fma_f32 v71, -v71, v90, v88
	v_div_fmas_f32 v71, v71, v82, v90
	v_div_fixup_f32 v106, v71, v84, v106
	v_mul_f32_e32 v110, v110, v106
	v_cvt_pk_bf16_f32 v204, v70, v110
	v_lshlrev_b32_e32 v108, 16, v108
	v_lshlrev_b32_e32 v32, 16, v32
	v_lshlrev_b32_e32 v107, 16, v107
	v_mul_f32_e32 v107, v16, v107
	v_fmac_f32_e32 v107, v14, v108
	v_fmac_f32_e32 v107, v17, v32
	v_add_f32_e32 v107, v12, v107
	v_fma_f32 v27, v42, v8, v64
	v_mul_f32_e32 v70, v27, v107
	v_lshlrev_b32_e32 v33, 16, v33
	v_mul_f32_e32 v84, 0xbfb8aa3b, v33
	v_exp_f32_e32 v84, v84
	s_nop 0
	v_add_f32_e32 v84, 1.0, v84
	v_div_scale_f32 v71, s[74:75], v84, v84, v33
	v_rcp_f32_e32 v82, v71
	s_nop 0
	v_fma_f32 v92, -v71, v82, 1.0
	v_fmac_f32_e32 v82, v92, v82
	v_div_scale_f32 v88, vcc, v33, v84, v33
	v_mul_f32_e32 v90, v88, v82
	v_fma_f32 v92, -v71, v90, v88
	v_fmac_f32_e32 v90, v92, v82
	v_fma_f32 v71, -v71, v90, v88
	v_div_fmas_f32 v71, v71, v82, v90
	v_div_fixup_f32 v33, v71, v84, v33
	v_mul_f32_e32 v70, v70, v33
	v_lshlrev_b32_e32 v34, 16, v34
	v_lshlrev_b32_e32 v79, 16, v79
	v_lshlrev_b32_e32 v78, 16, v78
	v_mul_f32_e32 v78, v16, v78
	v_fmac_f32_e32 v78, v14, v34
	v_fmac_f32_e32 v78, v17, v79
	v_add_f32_e32 v78, v12, v78
	v_fma_f32 v27, v44, v8, v65
	v_mul_f32_e32 v110, v27, v78
	v_lshlrev_b32_e32 v76, 16, v76
	v_mul_f32_e32 v84, 0xbfb8aa3b, v76
	v_exp_f32_e32 v84, v84
	s_nop 0
	v_add_f32_e32 v84, 1.0, v84
	v_div_scale_f32 v71, s[74:75], v84, v84, v76
	v_rcp_f32_e32 v82, v71
	s_nop 0
	v_fma_f32 v92, -v71, v82, 1.0
	v_fmac_f32_e32 v82, v92, v82
	v_div_scale_f32 v88, vcc, v76, v84, v76
	v_mul_f32_e32 v90, v88, v82
	v_fma_f32 v92, -v71, v90, v88
	v_fmac_f32_e32 v90, v92, v82
	v_fma_f32 v71, -v71, v90, v88
	v_div_fmas_f32 v71, v71, v82, v90
	v_div_fixup_f32 v76, v71, v84, v76
	v_mul_f32_e32 v110, v110, v76
	v_cvt_pk_bf16_f32 v205, v70, v110
	v_add_u32_e32 v109, 0x1000, v109
	global_load_ushort v9, v109, s[36:37] offset:-2
	global_load_ushort v11, v109, s[36:37]
	global_load_ushort v13, v109, s[36:37] offset:2
	global_load_ushort v15, v109, s[72:73] offset:-2
	global_load_ushort v81, v109, s[72:73]
	global_load_ushort v83, v109, s[72:73] offset:2
	global_load_ushort v85, v109, s[0:1]
	global_load_ushort v87, v109, s[4:5]
	global_load_ushort v89, v109, s[36:37] offset:1022
	global_load_ushort v91, v109, s[36:37] offset:1024
	global_load_ushort v93, v109, s[36:37] offset:1026
	global_load_ushort v94, v109, s[72:73] offset:1022
	global_load_ushort v95, v109, s[72:73] offset:1024
	global_load_ushort v96, v109, s[72:73] offset:1026
	global_load_ushort v97, v109, s[0:1] offset:1024
	global_load_ushort v98, v109, s[4:5] offset:1024
	global_load_ushort v99, v109, s[36:37] offset:2046
	global_load_ushort v100, v109, s[36:37] offset:2048
	global_load_ushort v101, v109, s[36:37] offset:2050
	global_load_ushort v102, v109, s[72:73] offset:2046
	global_load_ushort v103, v109, s[72:73] offset:2048
	global_load_ushort v104, v109, s[72:73] offset:2050
	global_load_ushort v105, v109, s[0:1] offset:2048
	global_load_ushort v106, v109, s[4:5] offset:2048
	global_load_ushort v107, v109, s[36:37] offset:3070
	global_load_ushort v108, v109, s[36:37] offset:3072
	global_load_ushort v32, v109, s[36:37] offset:3074
	global_load_ushort v78, v109, s[72:73] offset:3070
	global_load_ushort v34, v109, s[72:73] offset:3072
	global_load_ushort v79, v109, s[72:73] offset:3074
	global_load_ushort v33, v109, s[0:1] offset:3072
	global_load_ushort v76, v109, s[4:5] offset:3072
	s_waitcnt vmcnt(0)
	v_lshlrev_b32_e32 v11, 16, v11
	v_lshlrev_b32_e32 v13, 16, v13
	v_lshlrev_b32_e32 v9, 16, v9
	v_mul_f32_e32 v9, v16, v9
	v_fmac_f32_e32 v9, v14, v11
	v_fmac_f32_e32 v9, v17, v13
	v_add_f32_e32 v9, v12, v9
	v_fma_f32 v27, v47, v8, v22
	v_mul_f32_e32 v70, v27, v9
	v_lshlrev_b32_e32 v85, 16, v85
	v_mul_f32_e32 v84, 0xbfb8aa3b, v85
	v_exp_f32_e32 v84, v84
	s_nop 0
	v_add_f32_e32 v84, 1.0, v84
	v_div_scale_f32 v71, s[74:75], v84, v84, v85
	v_rcp_f32_e32 v82, v71
	s_nop 0
	v_fma_f32 v92, -v71, v82, 1.0
	v_fmac_f32_e32 v82, v92, v82
	v_div_scale_f32 v88, vcc, v85, v84, v85
	v_mul_f32_e32 v90, v88, v82
	v_fma_f32 v92, -v71, v90, v88
	v_fmac_f32_e32 v90, v92, v82
	v_fma_f32 v71, -v71, v90, v88
	v_div_fmas_f32 v71, v71, v82, v90
	v_div_fixup_f32 v85, v71, v84, v85
	v_mul_f32_e32 v70, v70, v85
	v_lshlrev_b32_e32 v81, 16, v81
	v_lshlrev_b32_e32 v83, 16, v83
	v_lshlrev_b32_e32 v15, 16, v15
	v_mul_f32_e32 v15, v16, v15
	v_fmac_f32_e32 v15, v14, v81
	v_fmac_f32_e32 v15, v17, v83
	v_add_f32_e32 v15, v12, v15
	v_fma_f32 v27, v49, v8, v23
	v_mul_f32_e32 v110, v27, v15
	v_lshlrev_b32_e32 v87, 16, v87
	v_mul_f32_e32 v84, 0xbfb8aa3b, v87
	v_exp_f32_e32 v84, v84
	s_nop 0
	v_add_f32_e32 v84, 1.0, v84
	v_div_scale_f32 v71, s[74:75], v84, v84, v87
	v_rcp_f32_e32 v82, v71
	s_nop 0
	v_fma_f32 v92, -v71, v82, 1.0
	v_fmac_f32_e32 v82, v92, v82
	v_div_scale_f32 v88, vcc, v87, v84, v87
	v_mul_f32_e32 v90, v88, v82
	v_fma_f32 v92, -v71, v90, v88
	v_fmac_f32_e32 v90, v92, v82
	v_fma_f32 v71, -v71, v90, v88
	v_div_fmas_f32 v71, v71, v82, v90
	v_div_fixup_f32 v87, v71, v84, v87
	v_mul_f32_e32 v110, v110, v87
	v_cvt_pk_bf16_f32 v206, v70, v110
	v_lshlrev_b32_e32 v91, 16, v91
	v_lshlrev_b32_e32 v93, 16, v93
	v_lshlrev_b32_e32 v89, 16, v89
	v_mul_f32_e32 v89, v16, v89
	v_fmac_f32_e32 v89, v14, v91
	v_fmac_f32_e32 v89, v17, v93
	v_add_f32_e32 v89, v12, v89
	v_fma_f32 v27, v46, v8, v24
	v_mul_f32_e32 v70, v27, v89
	v_lshlrev_b32_e32 v97, 16, v97
	v_mul_f32_e32 v84, 0xbfb8aa3b, v97
	v_exp_f32_e32 v84, v84
	s_nop 0
	v_add_f32_e32 v84, 1.0, v84
	v_div_scale_f32 v71, s[74:75], v84, v84, v97
	v_rcp_f32_e32 v82, v71
	s_nop 0
	v_fma_f32 v92, -v71, v82, 1.0
	v_fmac_f32_e32 v82, v92, v82
	v_div_scale_f32 v88, vcc, v97, v84, v97
	v_mul_f32_e32 v90, v88, v82
	v_fma_f32 v92, -v71, v90, v88
	v_fmac_f32_e32 v90, v92, v82
	v_fma_f32 v71, -v71, v90, v88
	v_div_fmas_f32 v71, v71, v82, v90
	v_div_fixup_f32 v97, v71, v84, v97
	v_mul_f32_e32 v70, v70, v97
	v_lshlrev_b32_e32 v95, 16, v95
	v_lshlrev_b32_e32 v96, 16, v96
	v_lshlrev_b32_e32 v94, 16, v94
	v_mul_f32_e32 v94, v16, v94
	v_fmac_f32_e32 v94, v14, v95
	v_fmac_f32_e32 v94, v17, v96
	v_add_f32_e32 v94, v12, v94
	v_fma_f32 v27, v48, v8, v25
	v_mul_f32_e32 v110, v27, v94
	v_lshlrev_b32_e32 v98, 16, v98
	v_mul_f32_e32 v84, 0xbfb8aa3b, v98
	v_exp_f32_e32 v84, v84
	s_nop 0
	v_add_f32_e32 v84, 1.0, v84
	v_div_scale_f32 v71, s[74:75], v84, v84, v98
	v_rcp_f32_e32 v82, v71
	s_nop 0
	v_fma_f32 v92, -v71, v82, 1.0
	v_fmac_f32_e32 v82, v92, v82
	v_div_scale_f32 v88, vcc, v98, v84, v98
	v_mul_f32_e32 v90, v88, v82
	v_fma_f32 v92, -v71, v90, v88
	v_fmac_f32_e32 v90, v92, v82
	v_fma_f32 v71, -v71, v90, v88
	v_div_fmas_f32 v71, v71, v82, v90
	v_div_fixup_f32 v98, v71, v84, v98
	v_mul_f32_e32 v110, v110, v98
	v_cvt_pk_bf16_f32 v207, v70, v110
	v_lshlrev_b32_e32 v100, 16, v100
	v_lshlrev_b32_e32 v101, 16, v101
	v_lshlrev_b32_e32 v99, 16, v99
	v_mul_f32_e32 v99, v16, v99
	v_fmac_f32_e32 v99, v14, v100
	v_fmac_f32_e32 v99, v17, v101
	v_add_f32_e32 v99, v12, v99
	v_fma_f32 v27, v51, v8, v18
	v_mul_f32_e32 v70, v27, v99
	v_lshlrev_b32_e32 v105, 16, v105
	v_mul_f32_e32 v84, 0xbfb8aa3b, v105
	v_exp_f32_e32 v84, v84
	s_nop 0
	v_add_f32_e32 v84, 1.0, v84
	v_div_scale_f32 v71, s[74:75], v84, v84, v105
	v_rcp_f32_e32 v82, v71
	s_nop 0
	v_fma_f32 v92, -v71, v82, 1.0
	v_fmac_f32_e32 v82, v92, v82
	v_div_scale_f32 v88, vcc, v105, v84, v105
	v_mul_f32_e32 v90, v88, v82
	v_fma_f32 v92, -v71, v90, v88
	v_fmac_f32_e32 v90, v92, v82
	v_fma_f32 v71, -v71, v90, v88
	v_div_fmas_f32 v71, v71, v82, v90
	v_div_fixup_f32 v105, v71, v84, v105
	v_mul_f32_e32 v70, v70, v105
	v_lshlrev_b32_e32 v103, 16, v103
	v_lshlrev_b32_e32 v104, 16, v104
	v_lshlrev_b32_e32 v102, 16, v102
	v_mul_f32_e32 v102, v16, v102
	v_fmac_f32_e32 v102, v14, v103
	v_fmac_f32_e32 v102, v17, v104
	v_add_f32_e32 v102, v12, v102
	v_fma_f32 v27, v53, v8, v19
	v_mul_f32_e32 v110, v27, v102
	v_lshlrev_b32_e32 v106, 16, v106
	v_mul_f32_e32 v84, 0xbfb8aa3b, v106
	v_exp_f32_e32 v84, v84
	s_nop 0
	v_add_f32_e32 v84, 1.0, v84
	v_div_scale_f32 v71, s[74:75], v84, v84, v106
	v_rcp_f32_e32 v82, v71
	s_nop 0
	v_fma_f32 v92, -v71, v82, 1.0
	v_fmac_f32_e32 v82, v92, v82
	v_div_scale_f32 v88, vcc, v106, v84, v106
	v_mul_f32_e32 v90, v88, v82
	v_fma_f32 v92, -v71, v90, v88
	v_fmac_f32_e32 v90, v92, v82
	v_fma_f32 v71, -v71, v90, v88
	v_div_fmas_f32 v71, v71, v82, v90
	v_div_fixup_f32 v106, v71, v84, v106
	v_mul_f32_e32 v110, v110, v106
	v_cvt_pk_bf16_f32 v208, v70, v110
	v_lshlrev_b32_e32 v108, 16, v108
	v_lshlrev_b32_e32 v32, 16, v32
	v_lshlrev_b32_e32 v107, 16, v107
	v_mul_f32_e32 v107, v16, v107
	v_fmac_f32_e32 v107, v14, v108
	v_fmac_f32_e32 v107, v17, v32
	v_add_f32_e32 v107, v12, v107
	v_fma_f32 v27, v50, v8, v20
	v_mul_f32_e32 v70, v27, v107
	v_lshlrev_b32_e32 v33, 16, v33
	v_mul_f32_e32 v84, 0xbfb8aa3b, v33
	v_exp_f32_e32 v84, v84
	s_nop 0
	v_add_f32_e32 v84, 1.0, v84
	v_div_scale_f32 v71, s[74:75], v84, v84, v33
	v_rcp_f32_e32 v82, v71
	s_nop 0
	v_fma_f32 v92, -v71, v82, 1.0
	v_fmac_f32_e32 v82, v92, v82
	v_div_scale_f32 v88, vcc, v33, v84, v33
	v_mul_f32_e32 v90, v88, v82
	v_fma_f32 v92, -v71, v90, v88
	v_fmac_f32_e32 v90, v92, v82
	v_fma_f32 v71, -v71, v90, v88
	v_div_fmas_f32 v71, v71, v82, v90
	v_div_fixup_f32 v33, v71, v84, v33
	v_mul_f32_e32 v70, v70, v33
	v_lshlrev_b32_e32 v34, 16, v34
	v_lshlrev_b32_e32 v79, 16, v79
	v_lshlrev_b32_e32 v78, 16, v78
	v_mul_f32_e32 v78, v16, v78
	v_fmac_f32_e32 v78, v14, v34
	v_fmac_f32_e32 v78, v17, v79
	v_add_f32_e32 v78, v12, v78
	v_fma_f32 v27, v52, v8, v21
	v_mul_f32_e32 v110, v27, v78
	v_lshlrev_b32_e32 v76, 16, v76
	v_mul_f32_e32 v84, 0xbfb8aa3b, v76
	v_exp_f32_e32 v84, v84
	s_nop 0
	v_add_f32_e32 v84, 1.0, v84
	v_div_scale_f32 v71, s[74:75], v84, v84, v76
	v_rcp_f32_e32 v82, v71
	s_nop 0
	v_fma_f32 v92, -v71, v82, 1.0
	v_fmac_f32_e32 v82, v92, v82
	v_div_scale_f32 v88, vcc, v76, v84, v76
	v_mul_f32_e32 v90, v88, v82
	v_fma_f32 v92, -v71, v90, v88
	v_fmac_f32_e32 v90, v92, v82
	v_fma_f32 v71, -v71, v90, v88
	v_div_fmas_f32 v71, v71, v82, v90
	v_div_fixup_f32 v76, v71, v84, v76
	v_mul_f32_e32 v110, v110, v76
	v_cvt_pk_bf16_f32 v209, v70, v110
	v_add_u32_e32 v52, 0x1e00, v10
	v_cmp_gt_i32_e32 vcc, 0x1fff, v52
	v_min_i32_e32 v52, 0x1ffe, v52
	v_lshlrev_b32_e32 v52, 1, v52
	s_nop 0
	v_cndmask_b32_e64 v21, 0, 1.0, vcc
	v_add_u32_e32 v109, 0x1000, v109
	global_load_ushort v9, v109, s[36:37] offset:-2
	global_load_ushort v11, v109, s[36:37]
	global_load_ushort v13, v109, s[36:37] offset:2
	global_load_ushort v15, v109, s[72:73] offset:-2
	global_load_ushort v81, v109, s[72:73]
	global_load_ushort v83, v109, s[72:73] offset:2
	global_load_ushort v85, v109, s[0:1]
	global_load_ushort v87, v109, s[4:5]
	global_load_ushort v89, v109, s[36:37] offset:1022
	global_load_ushort v91, v109, s[36:37] offset:1024
	global_load_ushort v93, v109, s[36:37] offset:1026
	global_load_ushort v94, v109, s[72:73] offset:1022
	global_load_ushort v95, v109, s[72:73] offset:1024
	global_load_ushort v96, v109, s[72:73] offset:1026
	global_load_ushort v97, v109, s[0:1] offset:1024
	global_load_ushort v98, v109, s[4:5] offset:1024
	global_load_ushort v99, v109, s[36:37] offset:2046
	global_load_ushort v100, v109, s[36:37] offset:2048
	global_load_ushort v101, v109, s[36:37] offset:2050
	global_load_ushort v102, v109, s[72:73] offset:2046
	global_load_ushort v103, v109, s[72:73] offset:2048
	global_load_ushort v104, v109, s[72:73] offset:2050
	global_load_ushort v105, v109, s[0:1] offset:2048
	global_load_ushort v106, v109, s[4:5] offset:2048
	global_load_ushort v107, v109, s[36:37] offset:3070
	global_load_ushort v108, v109, s[36:37] offset:3072
	global_load_ushort v32, v52, s[36:37] offset:2
	global_load_ushort v78, v109, s[72:73] offset:3070
	global_load_ushort v34, v109, s[72:73] offset:3072
	global_load_ushort v79, v52, s[72:73] offset:2
	global_load_ushort v33, v109, s[0:1] offset:3072
	global_load_ushort v76, v109, s[4:5] offset:3072
	s_waitcnt vmcnt(0)
	v_lshlrev_b32_e32 v11, 16, v11
	v_lshlrev_b32_e32 v13, 16, v13
	v_lshlrev_b32_e32 v9, 16, v9
	v_mul_f32_e32 v9, v16, v9
	v_fmac_f32_e32 v9, v14, v11
	v_fmac_f32_e32 v9, v17, v13
	v_add_f32_e32 v9, v12, v9
	v_fma_f32 v27, v55, v8, v4
	v_mul_f32_e32 v70, v27, v9
	v_lshlrev_b32_e32 v85, 16, v85
	v_mul_f32_e32 v84, 0xbfb8aa3b, v85
	v_exp_f32_e32 v84, v84
	s_nop 0
	v_add_f32_e32 v84, 1.0, v84
	v_div_scale_f32 v71, s[74:75], v84, v84, v85
	v_rcp_f32_e32 v82, v71
	s_nop 0
	v_fma_f32 v92, -v71, v82, 1.0
	v_fmac_f32_e32 v82, v92, v82
	v_div_scale_f32 v88, vcc, v85, v84, v85
	v_mul_f32_e32 v90, v88, v82
	v_fma_f32 v92, -v71, v90, v88
	v_fmac_f32_e32 v90, v92, v82
	v_fma_f32 v71, -v71, v90, v88
	v_div_fmas_f32 v71, v71, v82, v90
	v_div_fixup_f32 v85, v71, v84, v85
	v_mul_f32_e32 v70, v70, v85
	v_lshlrev_b32_e32 v81, 16, v81
	v_lshlrev_b32_e32 v83, 16, v83
	v_lshlrev_b32_e32 v15, 16, v15
	v_mul_f32_e32 v15, v16, v15
	v_fmac_f32_e32 v15, v14, v81
	v_fmac_f32_e32 v15, v17, v83
	v_add_f32_e32 v15, v12, v15
	v_fma_f32 v27, v57, v8, v5
	v_mul_f32_e32 v110, v27, v15
	v_lshlrev_b32_e32 v87, 16, v87
	v_mul_f32_e32 v84, 0xbfb8aa3b, v87
	v_exp_f32_e32 v84, v84
	s_nop 0
	v_add_f32_e32 v84, 1.0, v84
	v_div_scale_f32 v71, s[74:75], v84, v84, v87
	v_rcp_f32_e32 v82, v71
	s_nop 0
	v_fma_f32 v92, -v71, v82, 1.0
	v_fmac_f32_e32 v82, v92, v82
	v_div_scale_f32 v88, vcc, v87, v84, v87
	v_mul_f32_e32 v90, v88, v82
	v_fma_f32 v92, -v71, v90, v88
	v_fmac_f32_e32 v90, v92, v82
	v_fma_f32 v71, -v71, v90, v88
	v_div_fmas_f32 v71, v71, v82, v90
	v_div_fixup_f32 v87, v71, v84, v87
	v_mul_f32_e32 v110, v110, v87
	v_cvt_pk_bf16_f32 v210, v70, v110
	v_lshlrev_b32_e32 v91, 16, v91
	v_lshlrev_b32_e32 v93, 16, v93
	v_lshlrev_b32_e32 v89, 16, v89
	v_mul_f32_e32 v89, v16, v89
	v_fmac_f32_e32 v89, v14, v91
	v_fmac_f32_e32 v89, v17, v93
	v_add_f32_e32 v89, v12, v89
	v_fma_f32 v27, v54, v8, v6
	v_mul_f32_e32 v70, v27, v89
	v_lshlrev_b32_e32 v97, 16, v97
	v_mul_f32_e32 v84, 0xbfb8aa3b, v97
	v_exp_f32_e32 v84, v84
	s_nop 0
	v_add_f32_e32 v84, 1.0, v84
	v_div_scale_f32 v71, s[74:75], v84, v84, v97
	v_rcp_f32_e32 v82, v71
	s_nop 0
	v_fma_f32 v92, -v71, v82, 1.0
	v_fmac_f32_e32 v82, v92, v82
	v_div_scale_f32 v88, vcc, v97, v84, v97
	v_mul_f32_e32 v90, v88, v82
	v_fma_f32 v92, -v71, v90, v88
	v_fmac_f32_e32 v90, v92, v82
	v_fma_f32 v71, -v71, v90, v88
	v_div_fmas_f32 v71, v71, v82, v90
	v_div_fixup_f32 v97, v71, v84, v97
	v_mul_f32_e32 v70, v70, v97
	v_lshlrev_b32_e32 v95, 16, v95
	v_lshlrev_b32_e32 v96, 16, v96
	v_lshlrev_b32_e32 v94, 16, v94
	v_mul_f32_e32 v94, v16, v94
	v_fmac_f32_e32 v94, v14, v95
	v_fmac_f32_e32 v94, v17, v96
	v_add_f32_e32 v94, v12, v94
	v_fma_f32 v27, v56, v8, v7
	v_mul_f32_e32 v110, v27, v94
	v_lshlrev_b32_e32 v98, 16, v98
	v_mul_f32_e32 v84, 0xbfb8aa3b, v98
	v_exp_f32_e32 v84, v84
	s_nop 0
	v_add_f32_e32 v84, 1.0, v84
	v_div_scale_f32 v71, s[74:75], v84, v84, v98
	v_rcp_f32_e32 v82, v71
	s_nop 0
	v_fma_f32 v92, -v71, v82, 1.0
	v_fmac_f32_e32 v82, v92, v82
	v_div_scale_f32 v88, vcc, v98, v84, v98
	v_mul_f32_e32 v90, v88, v82
	v_fma_f32 v92, -v71, v90, v88
	v_fmac_f32_e32 v90, v92, v82
	v_fma_f32 v71, -v71, v90, v88
	v_div_fmas_f32 v71, v71, v82, v90
	v_div_fixup_f32 v98, v71, v84, v98
	v_mul_f32_e32 v110, v110, v98
	v_cvt_pk_bf16_f32 v211, v70, v110
	v_lshlrev_b32_e32 v100, 16, v100
	v_lshlrev_b32_e32 v101, 16, v101
	v_lshlrev_b32_e32 v99, 16, v99
	v_mul_f32_e32 v99, v16, v99
	v_fmac_f32_e32 v99, v14, v100
	v_fmac_f32_e32 v99, v17, v101
	v_add_f32_e32 v99, v12, v99
	v_fma_f32 v27, v59, v8, v0
	v_mul_f32_e32 v70, v27, v99
	v_lshlrev_b32_e32 v105, 16, v105
	v_mul_f32_e32 v84, 0xbfb8aa3b, v105
	v_exp_f32_e32 v84, v84
	s_nop 0
	v_add_f32_e32 v84, 1.0, v84
	v_div_scale_f32 v71, s[74:75], v84, v84, v105
	v_rcp_f32_e32 v82, v71
	s_nop 0
	v_fma_f32 v92, -v71, v82, 1.0
	v_fmac_f32_e32 v82, v92, v82
	v_div_scale_f32 v88, vcc, v105, v84, v105
	v_mul_f32_e32 v90, v88, v82
	v_fma_f32 v92, -v71, v90, v88
	v_fmac_f32_e32 v90, v92, v82
	v_fma_f32 v71, -v71, v90, v88
	v_div_fmas_f32 v71, v71, v82, v90
	v_div_fixup_f32 v105, v71, v84, v105
	v_mul_f32_e32 v70, v70, v105
	v_lshlrev_b32_e32 v103, 16, v103
	v_lshlrev_b32_e32 v104, 16, v104
	v_lshlrev_b32_e32 v102, 16, v102
	v_mul_f32_e32 v102, v16, v102
	v_fmac_f32_e32 v102, v14, v103
	v_fmac_f32_e32 v102, v17, v104
	v_add_f32_e32 v102, v12, v102
	v_fma_f32 v27, v61, v8, v1
	v_mul_f32_e32 v110, v27, v102
	v_lshlrev_b32_e32 v106, 16, v106
	v_mul_f32_e32 v84, 0xbfb8aa3b, v106
	v_exp_f32_e32 v84, v84
	s_nop 0
	v_add_f32_e32 v84, 1.0, v84
	v_div_scale_f32 v71, s[74:75], v84, v84, v106
	v_rcp_f32_e32 v82, v71
	s_nop 0
	v_fma_f32 v92, -v71, v82, 1.0
	v_fmac_f32_e32 v82, v92, v82
	v_div_scale_f32 v88, vcc, v106, v84, v106
	v_mul_f32_e32 v90, v88, v82
	v_fma_f32 v92, -v71, v90, v88
	v_fmac_f32_e32 v90, v92, v82
	v_fma_f32 v71, -v71, v90, v88
	v_div_fmas_f32 v71, v71, v82, v90
	v_div_fixup_f32 v106, v71, v84, v106
	v_mul_f32_e32 v110, v110, v106
	v_cvt_pk_bf16_f32 v212, v70, v110
	v_lshlrev_b32_e32 v108, 16, v108
	v_lshlrev_b32_e32 v32, 16, v32
	v_lshlrev_b32_e32 v107, 16, v107
	v_mul_f32_e32 v107, v16, v107
	v_mul_f32_e32 v32, v21, v32
	v_fmac_f32_e32 v107, v14, v108
	v_fmac_f32_e32 v107, v17, v32
	v_add_f32_e32 v107, v12, v107
	v_fma_f32 v27, v58, v8, v2
	v_mul_f32_e32 v70, v27, v107
	v_lshlrev_b32_e32 v33, 16, v33
	v_mul_f32_e32 v84, 0xbfb8aa3b, v33
	v_exp_f32_e32 v84, v84
	s_nop 0
	v_add_f32_e32 v84, 1.0, v84
	v_div_scale_f32 v71, s[74:75], v84, v84, v33
	v_rcp_f32_e32 v82, v71
	s_nop 0
	v_fma_f32 v92, -v71, v82, 1.0
	v_fmac_f32_e32 v82, v92, v82
	v_div_scale_f32 v88, vcc, v33, v84, v33
	v_mul_f32_e32 v90, v88, v82
	v_fma_f32 v92, -v71, v90, v88
	v_fmac_f32_e32 v90, v92, v82
	v_fma_f32 v71, -v71, v90, v88
	v_div_fmas_f32 v71, v71, v82, v90
	v_div_fixup_f32 v33, v71, v84, v33
	v_mul_f32_e32 v70, v70, v33
	v_lshlrev_b32_e32 v34, 16, v34
	v_lshlrev_b32_e32 v79, 16, v79
	v_lshlrev_b32_e32 v78, 16, v78
	v_mul_f32_e32 v78, v16, v78
	v_mul_f32_e32 v79, v21, v79
	v_fmac_f32_e32 v78, v14, v34
	v_fmac_f32_e32 v78, v17, v79
	v_add_f32_e32 v78, v12, v78
	v_fma_f32 v27, v60, v8, v3
	v_mul_f32_e32 v110, v27, v78
	v_lshlrev_b32_e32 v76, 16, v76
	v_mul_f32_e32 v84, 0xbfb8aa3b, v76
	v_exp_f32_e32 v84, v84
	s_nop 0
	v_add_f32_e32 v84, 1.0, v84
	v_div_scale_f32 v71, s[74:75], v84, v84, v76
	v_rcp_f32_e32 v82, v71
	s_nop 0
	v_fma_f32 v92, -v71, v82, 1.0
	v_fmac_f32_e32 v82, v92, v82
	v_div_scale_f32 v88, vcc, v76, v84, v76
	v_mul_f32_e32 v90, v88, v82
	v_fma_f32 v92, -v71, v90, v88
	v_fmac_f32_e32 v90, v92, v82
	v_fma_f32 v71, -v71, v90, v88
	v_div_fmas_f32 v71, v71, v82, v90
	v_div_fixup_f32 v76, v71, v84, v76
	v_mul_f32_e32 v110, v110, v76
	v_cvt_pk_bf16_f32 v213, v70, v110
	s_branch .Lhy_ep1_done_L1
.Lhy_ep1_comb_L1:
	s_mov_b32 s98, 0x5040100
	s_mov_b32 s99, 0x7060302
	v_lshlrev_b32_e32 v109, 1, v10
	global_load_ushort v9, v109, s[0:1]
	global_load_ushort v11, v109, s[4:5]
	global_load_ushort v13, v109, s[36:37] offset:1022
	global_load_ushort v15, v109, s[36:37] offset:1024
	global_load_ushort v81, v109, s[36:37] offset:1026
	global_load_ushort v83, v109, s[72:73] offset:1022
	global_load_ushort v85, v109, s[72:73] offset:1024
	global_load_ushort v87, v109, s[72:73] offset:1026
	global_load_ushort v89, v109, s[0:1] offset:1024
	global_load_ushort v91, v109, s[4:5] offset:1024
	global_load_ushort v93, v109, s[36:37] offset:2046
	global_load_ushort v94, v109, s[36:37] offset:2048
	global_load_ushort v95, v109, s[36:37] offset:2050
	global_load_ushort v96, v109, s[72:73] offset:2046
	global_load_ushort v97, v109, s[72:73] offset:2048
	global_load_ushort v98, v109, s[72:73] offset:2050
	global_load_ushort v99, v109, s[0:1] offset:2048
	global_load_ushort v100, v109, s[4:5] offset:2048
	global_load_ushort v101, v109, s[36:37] offset:3070
	global_load_ushort v102, v109, s[36:37] offset:3072
	global_load_ushort v103, v109, s[36:37] offset:3074
	global_load_ushort v104, v109, s[72:73] offset:3070
	global_load_ushort v105, v109, s[72:73] offset:3072
	global_load_ushort v106, v109, s[72:73] offset:3074
	global_load_ushort v107, v109, s[0:1] offset:3072
	global_load_ushort v108, v109, s[4:5] offset:3072
	s_waitcnt vmcnt(0)
	v_lshlrev_b32_e32 v26, 10, v10
	v_fma_f32 v27, v32, v8, v78
	v_mul_f32_e32 v70, v80, v27
	v_lshlrev_b32_e32 v9, 16, v9
	v_mul_f32_e32 v84, 0xbfb8aa3b, v9
	v_exp_f32_e32 v84, v84
	s_nop 0
	v_add_f32_e32 v84, 1.0, v84
	v_div_scale_f32 v71, s[74:75], v84, v84, v9
	v_rcp_f32_e32 v82, v71
	s_nop 0
	v_fma_f32 v92, -v71, v82, 1.0
	v_fmac_f32_e32 v82, v92, v82
	v_div_scale_f32 v88, vcc, v9, v84, v9
	v_mul_f32_e32 v90, v88, v82
	v_fma_f32 v92, -v71, v90, v88
	v_fmac_f32_e32 v90, v92, v82
	v_fma_f32 v71, -v71, v90, v88
	v_div_fmas_f32 v71, v71, v82, v90
	v_div_fixup_f32 v9, v71, v84, v9
	v_mul_f32_e32 v70, v70, v9
	v_fma_f32 v27, v34, v8, v79
	v_mul_f32_e32 v110, v86, v27
	v_lshlrev_b32_e32 v11, 16, v11
	v_mul_f32_e32 v84, 0xbfb8aa3b, v11
	v_exp_f32_e32 v84, v84
	s_nop 0
	v_add_f32_e32 v84, 1.0, v84
	v_div_scale_f32 v71, s[74:75], v84, v84, v11
	v_rcp_f32_e32 v82, v71
	s_nop 0
	v_fma_f32 v92, -v71, v82, 1.0
	v_fmac_f32_e32 v82, v92, v82
	v_div_scale_f32 v88, vcc, v11, v84, v11
	v_mul_f32_e32 v90, v88, v82
	v_fma_f32 v92, -v71, v90, v88
	v_fmac_f32_e32 v90, v92, v82
	v_fma_f32 v71, -v71, v90, v88
	v_div_fmas_f32 v71, v71, v82, v90
	v_div_fixup_f32 v11, v71, v84, v11
	v_mul_f32_e32 v110, v110, v11
	v_cvt_pk_bf16_f32 v70, v70, v110
	v_perm_b32 v110, v70, v198, s98
	v_perm_b32 v70, v70, v198, s99
	global_store_dword v26, v110, s[70:71] offset:-2
	global_store_dword v26, v70, s[18:19] offset:-2
	v_add_u32_e32 v26, 0x80000, v26
	v_lshlrev_b32_e32 v15, 16, v15
	v_lshlrev_b32_e32 v81, 16, v81
	v_lshlrev_b32_e32 v13, 16, v13
	v_mul_f32_e32 v13, v16, v13
	v_fmac_f32_e32 v13, v14, v15
	v_fmac_f32_e32 v13, v17, v81
	v_add_f32_e32 v13, v12, v13
	v_fma_f32 v27, v33, v8, v76
	v_mul_f32_e32 v70, v27, v13
	v_lshlrev_b32_e32 v89, 16, v89
	v_mul_f32_e32 v84, 0xbfb8aa3b, v89
	v_exp_f32_e32 v84, v84
	s_nop 0
	v_add_f32_e32 v84, 1.0, v84
	v_div_scale_f32 v71, s[74:75], v84, v84, v89
	v_rcp_f32_e32 v82, v71
	s_nop 0
	v_fma_f32 v92, -v71, v82, 1.0
	v_fmac_f32_e32 v82, v92, v82
	v_div_scale_f32 v88, vcc, v89, v84, v89
	v_mul_f32_e32 v90, v88, v82
	v_fma_f32 v92, -v71, v90, v88
	v_fmac_f32_e32 v90, v92, v82
	v_fma_f32 v71, -v71, v90, v88
	v_div_fmas_f32 v71, v71, v82, v90
	v_div_fixup_f32 v89, v71, v84, v89
	v_mul_f32_e32 v70, v70, v89
	v_lshlrev_b32_e32 v85, 16, v85
	v_lshlrev_b32_e32 v87, 16, v87
	v_lshlrev_b32_e32 v83, 16, v83
	v_mul_f32_e32 v83, v16, v83
	v_fmac_f32_e32 v83, v14, v85
	v_fmac_f32_e32 v83, v17, v87
	v_add_f32_e32 v83, v12, v83
	v_fma_f32 v27, v35, v8, v77
	v_mul_f32_e32 v110, v27, v83
	v_lshlrev_b32_e32 v91, 16, v91
	v_mul_f32_e32 v84, 0xbfb8aa3b, v91
	v_exp_f32_e32 v84, v84
	s_nop 0
	v_add_f32_e32 v84, 1.0, v84
	v_div_scale_f32 v71, s[74:75], v84, v84, v91
	v_rcp_f32_e32 v82, v71
	s_nop 0
	v_fma_f32 v92, -v71, v82, 1.0
	v_fmac_f32_e32 v82, v92, v82
	v_div_scale_f32 v88, vcc, v91, v84, v91
	v_mul_f32_e32 v90, v88, v82
	v_fma_f32 v92, -v71, v90, v88
	v_fmac_f32_e32 v90, v92, v82
	v_fma_f32 v71, -v71, v90, v88
	v_div_fmas_f32 v71, v71, v82, v90
	v_div_fixup_f32 v91, v71, v84, v91
	v_mul_f32_e32 v110, v110, v91
	v_cvt_pk_bf16_f32 v70, v70, v110
	v_perm_b32 v110, v70, v199, s98
	v_perm_b32 v70, v70, v199, s99
	global_store_dword v26, v110, s[70:71] offset:-2
	global_store_dword v26, v70, s[18:19] offset:-2
	v_add_u32_e32 v26, 0x80000, v26
	v_lshlrev_b32_e32 v94, 16, v94
	v_lshlrev_b32_e32 v95, 16, v95
	v_lshlrev_b32_e32 v93, 16, v93
	v_mul_f32_e32 v93, v16, v93
	v_fmac_f32_e32 v93, v14, v94
	v_fmac_f32_e32 v93, v17, v95
	v_add_f32_e32 v93, v12, v93
	v_fma_f32 v27, v37, v8, v72
	v_mul_f32_e32 v70, v27, v93
	v_lshlrev_b32_e32 v99, 16, v99
	v_mul_f32_e32 v84, 0xbfb8aa3b, v99
	v_exp_f32_e32 v84, v84
	s_nop 0
	v_add_f32_e32 v84, 1.0, v84
	v_div_scale_f32 v71, s[74:75], v84, v84, v99
	v_rcp_f32_e32 v82, v71
	s_nop 0
	v_fma_f32 v92, -v71, v82, 1.0
	v_fmac_f32_e32 v82, v92, v82
	v_div_scale_f32 v88, vcc, v99, v84, v99
	v_mul_f32_e32 v90, v88, v82
	v_fma_f32 v92, -v71, v90, v88
	v_fmac_f32_e32 v90, v92, v82
	v_fma_f32 v71, -v71, v90, v88
	v_div_fmas_f32 v71, v71, v82, v90
	v_div_fixup_f32 v99, v71, v84, v99
	v_mul_f32_e32 v70, v70, v99
	v_lshlrev_b32_e32 v97, 16, v97
	v_lshlrev_b32_e32 v98, 16, v98
	v_lshlrev_b32_e32 v96, 16, v96
	v_mul_f32_e32 v96, v16, v96
	v_fmac_f32_e32 v96, v14, v97
	v_fmac_f32_e32 v96, v17, v98
	v_add_f32_e32 v96, v12, v96
	v_fma_f32 v27, v31, v8, v73
	v_mul_f32_e32 v110, v27, v96
	v_lshlrev_b32_e32 v100, 16, v100
	v_mul_f32_e32 v84, 0xbfb8aa3b, v100
	v_exp_f32_e32 v84, v84
	s_nop 0
	v_add_f32_e32 v84, 1.0, v84
	v_div_scale_f32 v71, s[74:75], v84, v84, v100
	v_rcp_f32_e32 v82, v71
	s_nop 0
	v_fma_f32 v92, -v71, v82, 1.0
	v_fmac_f32_e32 v82, v92, v82
	v_div_scale_f32 v88, vcc, v100, v84, v100
	v_mul_f32_e32 v90, v88, v82
	v_fma_f32 v92, -v71, v90, v88
	v_fmac_f32_e32 v90, v92, v82
	v_fma_f32 v71, -v71, v90, v88
	v_div_fmas_f32 v71, v71, v82, v90
	v_div_fixup_f32 v100, v71, v84, v100
	v_mul_f32_e32 v110, v110, v100
	v_cvt_pk_bf16_f32 v70, v70, v110
	v_perm_b32 v110, v70, v200, s98
	v_perm_b32 v70, v70, v200, s99
	global_store_dword v26, v110, s[70:71] offset:-2
	global_store_dword v26, v70, s[18:19] offset:-2
	v_add_u32_e32 v26, 0x80000, v26
	v_lshlrev_b32_e32 v102, 16, v102
	v_lshlrev_b32_e32 v103, 16, v103
	v_lshlrev_b32_e32 v101, 16, v101
	v_mul_f32_e32 v101, v16, v101
	v_fmac_f32_e32 v101, v14, v102
	v_fmac_f32_e32 v101, v17, v103
	v_add_f32_e32 v101, v12, v101
	v_fma_f32 v27, v36, v8, v74
	v_mul_f32_e32 v70, v27, v101
	v_lshlrev_b32_e32 v107, 16, v107
	v_mul_f32_e32 v84, 0xbfb8aa3b, v107
	v_exp_f32_e32 v84, v84
	s_nop 0
	v_add_f32_e32 v84, 1.0, v84
	v_div_scale_f32 v71, s[74:75], v84, v84, v107
	v_rcp_f32_e32 v82, v71
	s_nop 0
	v_fma_f32 v92, -v71, v82, 1.0
	v_fmac_f32_e32 v82, v92, v82
	v_div_scale_f32 v88, vcc, v107, v84, v107
	v_mul_f32_e32 v90, v88, v82
	v_fma_f32 v92, -v71, v90, v88
	v_fmac_f32_e32 v90, v92, v82
	v_fma_f32 v71, -v71, v90, v88
	v_div_fmas_f32 v71, v71, v82, v90
	v_div_fixup_f32 v107, v71, v84, v107
	v_mul_f32_e32 v70, v70, v107
	v_lshlrev_b32_e32 v105, 16, v105
	v_lshlrev_b32_e32 v106, 16, v106
	v_lshlrev_b32_e32 v104, 16, v104
	v_mul_f32_e32 v104, v16, v104
	v_fmac_f32_e32 v104, v14, v105
	v_fmac_f32_e32 v104, v17, v106
	v_add_f32_e32 v104, v12, v104
	v_fma_f32 v27, v30, v8, v75
	v_mul_f32_e32 v110, v27, v104
	v_lshlrev_b32_e32 v108, 16, v108
	v_mul_f32_e32 v84, 0xbfb8aa3b, v108
	v_exp_f32_e32 v84, v84
	s_nop 0
	v_add_f32_e32 v84, 1.0, v84
	v_div_scale_f32 v71, s[74:75], v84, v84, v108
	v_rcp_f32_e32 v82, v71
	s_nop 0
	v_fma_f32 v92, -v71, v82, 1.0
	v_fmac_f32_e32 v82, v92, v82
	v_div_scale_f32 v88, vcc, v108, v84, v108
	v_mul_f32_e32 v90, v88, v82
	v_fma_f32 v92, -v71, v90, v88
	v_fmac_f32_e32 v90, v92, v82
	v_fma_f32 v71, -v71, v90, v88
	v_div_fmas_f32 v71, v71, v82, v90
	v_div_fixup_f32 v108, v71, v84, v108
	v_mul_f32_e32 v110, v110, v108
	v_cvt_pk_bf16_f32 v70, v70, v110
	v_perm_b32 v110, v70, v201, s98
	v_perm_b32 v70, v70, v201, s99
	global_store_dword v26, v110, s[70:71] offset:-2
	global_store_dword v26, v70, s[18:19] offset:-2
	v_add_u32_e32 v109, 0x1000, v109
	global_load_ushort v9, v109, s[36:37] offset:-2
	global_load_ushort v11, v109, s[36:37]
	global_load_ushort v13, v109, s[36:37] offset:2
	global_load_ushort v15, v109, s[72:73] offset:-2
	global_load_ushort v81, v109, s[72:73]
	global_load_ushort v83, v109, s[72:73] offset:2
	global_load_ushort v85, v109, s[0:1]
	global_load_ushort v87, v109, s[4:5]
	global_load_ushort v89, v109, s[36:37] offset:1022
	global_load_ushort v91, v109, s[36:37] offset:1024
	global_load_ushort v93, v109, s[36:37] offset:1026
	global_load_ushort v94, v109, s[72:73] offset:1022
	global_load_ushort v95, v109, s[72:73] offset:1024
	global_load_ushort v96, v109, s[72:73] offset:1026
	global_load_ushort v97, v109, s[0:1] offset:1024
	global_load_ushort v98, v109, s[4:5] offset:1024
	global_load_ushort v99, v109, s[36:37] offset:2046
	global_load_ushort v100, v109, s[36:37] offset:2048
	global_load_ushort v101, v109, s[36:37] offset:2050
	global_load_ushort v102, v109, s[72:73] offset:2046
	global_load_ushort v103, v109, s[72:73] offset:2048
	global_load_ushort v104, v109, s[72:73] offset:2050
	global_load_ushort v105, v109, s[0:1] offset:2048
	global_load_ushort v106, v109, s[4:5] offset:2048
	global_load_ushort v107, v109, s[36:37] offset:3070
	global_load_ushort v108, v109, s[36:37] offset:3072
	global_load_ushort v32, v109, s[36:37] offset:3074
	global_load_ushort v78, v109, s[72:73] offset:3070
	global_load_ushort v34, v109, s[72:73] offset:3072
	global_load_ushort v79, v109, s[72:73] offset:3074
	global_load_ushort v33, v109, s[0:1] offset:3072
	global_load_ushort v76, v109, s[4:5] offset:3072
	s_waitcnt vmcnt(0)
	v_add_u32_e32 v26, 0x80000, v26
	v_lshlrev_b32_e32 v11, 16, v11
	v_lshlrev_b32_e32 v13, 16, v13
	v_lshlrev_b32_e32 v9, 16, v9
	v_mul_f32_e32 v9, v16, v9
	v_fmac_f32_e32 v9, v14, v11
	v_fmac_f32_e32 v9, v17, v13
	v_add_f32_e32 v9, v12, v9
	v_fma_f32 v27, v39, v8, v66
	v_mul_f32_e32 v70, v27, v9
	v_lshlrev_b32_e32 v85, 16, v85
	v_mul_f32_e32 v84, 0xbfb8aa3b, v85
	v_exp_f32_e32 v84, v84
	s_nop 0
	v_add_f32_e32 v84, 1.0, v84
	v_div_scale_f32 v71, s[74:75], v84, v84, v85
	v_rcp_f32_e32 v82, v71
	s_nop 0
	v_fma_f32 v92, -v71, v82, 1.0
	v_fmac_f32_e32 v82, v92, v82
	v_div_scale_f32 v88, vcc, v85, v84, v85
	v_mul_f32_e32 v90, v88, v82
	v_fma_f32 v92, -v71, v90, v88
	v_fmac_f32_e32 v90, v92, v82
	v_fma_f32 v71, -v71, v90, v88
	v_div_fmas_f32 v71, v71, v82, v90
	v_div_fixup_f32 v85, v71, v84, v85
	v_mul_f32_e32 v70, v70, v85
	v_lshlrev_b32_e32 v81, 16, v81
	v_lshlrev_b32_e32 v83, 16, v83
	v_lshlrev_b32_e32 v15, 16, v15
	v_mul_f32_e32 v15, v16, v15
	v_fmac_f32_e32 v15, v14, v81
	v_fmac_f32_e32 v15, v17, v83
	v_add_f32_e32 v15, v12, v15
	v_fma_f32 v27, v41, v8, v67
	v_mul_f32_e32 v110, v27, v15
	v_lshlrev_b32_e32 v87, 16, v87
	v_mul_f32_e32 v84, 0xbfb8aa3b, v87
	v_exp_f32_e32 v84, v84
	s_nop 0
	v_add_f32_e32 v84, 1.0, v84
	v_div_scale_f32 v71, s[74:75], v84, v84, v87
	v_rcp_f32_e32 v82, v71
	s_nop 0
	v_fma_f32 v92, -v71, v82, 1.0
	v_fmac_f32_e32 v82, v92, v82
	v_div_scale_f32 v88, vcc, v87, v84, v87
	v_mul_f32_e32 v90, v88, v82
	v_fma_f32 v92, -v71, v90, v88
	v_fmac_f32_e32 v90, v92, v82
	v_fma_f32 v71, -v71, v90, v88
	v_div_fmas_f32 v71, v71, v82, v90
	v_div_fixup_f32 v87, v71, v84, v87
	v_mul_f32_e32 v110, v110, v87
	v_cvt_pk_bf16_f32 v70, v70, v110
	v_perm_b32 v110, v70, v202, s98
	v_perm_b32 v70, v70, v202, s99
	global_store_dword v26, v110, s[70:71] offset:-2
	global_store_dword v26, v70, s[18:19] offset:-2
	v_add_u32_e32 v26, 0x80000, v26
	v_lshlrev_b32_e32 v91, 16, v91
	v_lshlrev_b32_e32 v93, 16, v93
	v_lshlrev_b32_e32 v89, 16, v89
	v_mul_f32_e32 v89, v16, v89
	v_fmac_f32_e32 v89, v14, v91
	v_fmac_f32_e32 v89, v17, v93
	v_add_f32_e32 v89, v12, v89
	v_fma_f32 v27, v38, v8, v68
	v_mul_f32_e32 v70, v27, v89
	v_lshlrev_b32_e32 v97, 16, v97
	v_mul_f32_e32 v84, 0xbfb8aa3b, v97
	v_exp_f32_e32 v84, v84
	s_nop 0
	v_add_f32_e32 v84, 1.0, v84
	v_div_scale_f32 v71, s[74:75], v84, v84, v97
	v_rcp_f32_e32 v82, v71
	s_nop 0
	v_fma_f32 v92, -v71, v82, 1.0
	v_fmac_f32_e32 v82, v92, v82
	v_div_scale_f32 v88, vcc, v97, v84, v97
	v_mul_f32_e32 v90, v88, v82
	v_fma_f32 v92, -v71, v90, v88
	v_fmac_f32_e32 v90, v92, v82
	v_fma_f32 v71, -v71, v90, v88
	v_div_fmas_f32 v71, v71, v82, v90
	v_div_fixup_f32 v97, v71, v84, v97
	v_mul_f32_e32 v70, v70, v97
	v_lshlrev_b32_e32 v95, 16, v95
	v_lshlrev_b32_e32 v96, 16, v96
	v_lshlrev_b32_e32 v94, 16, v94
	v_mul_f32_e32 v94, v16, v94
	v_fmac_f32_e32 v94, v14, v95
	v_fmac_f32_e32 v94, v17, v96
	v_add_f32_e32 v94, v12, v94
	v_fma_f32 v27, v40, v8, v69
	v_mul_f32_e32 v110, v27, v94
	v_lshlrev_b32_e32 v98, 16, v98
	v_mul_f32_e32 v84, 0xbfb8aa3b, v98
	v_exp_f32_e32 v84, v84
	s_nop 0
	v_add_f32_e32 v84, 1.0, v84
	v_div_scale_f32 v71, s[74:75], v84, v84, v98
	v_rcp_f32_e32 v82, v71
	s_nop 0
	v_fma_f32 v92, -v71, v82, 1.0
	v_fmac_f32_e32 v82, v92, v82
	v_div_scale_f32 v88, vcc, v98, v84, v98
	v_mul_f32_e32 v90, v88, v82
	v_fma_f32 v92, -v71, v90, v88
	v_fmac_f32_e32 v90, v92, v82
	v_fma_f32 v71, -v71, v90, v88
	v_div_fmas_f32 v71, v71, v82, v90
	v_div_fixup_f32 v98, v71, v84, v98
	v_mul_f32_e32 v110, v110, v98
	v_cvt_pk_bf16_f32 v70, v70, v110
	v_perm_b32 v110, v70, v203, s98
	v_perm_b32 v70, v70, v203, s99
	global_store_dword v26, v110, s[70:71] offset:-2
	global_store_dword v26, v70, s[18:19] offset:-2
	v_add_u32_e32 v26, 0x80000, v26
	v_lshlrev_b32_e32 v100, 16, v100
	v_lshlrev_b32_e32 v101, 16, v101
	v_lshlrev_b32_e32 v99, 16, v99
	v_mul_f32_e32 v99, v16, v99
	v_fmac_f32_e32 v99, v14, v100
	v_fmac_f32_e32 v99, v17, v101
	v_add_f32_e32 v99, v12, v99
	v_fma_f32 v27, v43, v8, v62
	v_mul_f32_e32 v70, v27, v99
	v_lshlrev_b32_e32 v105, 16, v105
	v_mul_f32_e32 v84, 0xbfb8aa3b, v105
	v_exp_f32_e32 v84, v84
	s_nop 0
	v_add_f32_e32 v84, 1.0, v84
	v_div_scale_f32 v71, s[74:75], v84, v84, v105
	v_rcp_f32_e32 v82, v71
	s_nop 0
	v_fma_f32 v92, -v71, v82, 1.0
	v_fmac_f32_e32 v82, v92, v82
	v_div_scale_f32 v88, vcc, v105, v84, v105
	v_mul_f32_e32 v90, v88, v82
	v_fma_f32 v92, -v71, v90, v88
	v_fmac_f32_e32 v90, v92, v82
	v_fma_f32 v71, -v71, v90, v88
	v_div_fmas_f32 v71, v71, v82, v90
	v_div_fixup_f32 v105, v71, v84, v105
	v_mul_f32_e32 v70, v70, v105
	v_lshlrev_b32_e32 v103, 16, v103
	v_lshlrev_b32_e32 v104, 16, v104
	v_lshlrev_b32_e32 v102, 16, v102
	v_mul_f32_e32 v102, v16, v102
	v_fmac_f32_e32 v102, v14, v103
	v_fmac_f32_e32 v102, v17, v104
	v_add_f32_e32 v102, v12, v102
	v_fma_f32 v27, v45, v8, v63
	v_mul_f32_e32 v110, v27, v102
	v_lshlrev_b32_e32 v106, 16, v106
	v_mul_f32_e32 v84, 0xbfb8aa3b, v106
	v_exp_f32_e32 v84, v84
	s_nop 0
	v_add_f32_e32 v84, 1.0, v84
	v_div_scale_f32 v71, s[74:75], v84, v84, v106
	v_rcp_f32_e32 v82, v71
	s_nop 0
	v_fma_f32 v92, -v71, v82, 1.0
	v_fmac_f32_e32 v82, v92, v82
	v_div_scale_f32 v88, vcc, v106, v84, v106
	v_mul_f32_e32 v90, v88, v82
	v_fma_f32 v92, -v71, v90, v88
	v_fmac_f32_e32 v90, v92, v82
	v_fma_f32 v71, -v71, v90, v88
	v_div_fmas_f32 v71, v71, v82, v90
	v_div_fixup_f32 v106, v71, v84, v106
	v_mul_f32_e32 v110, v110, v106
	v_cvt_pk_bf16_f32 v70, v70, v110
	v_perm_b32 v110, v70, v204, s98
	v_perm_b32 v70, v70, v204, s99
	global_store_dword v26, v110, s[70:71] offset:-2
	global_store_dword v26, v70, s[18:19] offset:-2
	v_add_u32_e32 v26, 0x80000, v26
	v_lshlrev_b32_e32 v108, 16, v108
	v_lshlrev_b32_e32 v32, 16, v32
	v_lshlrev_b32_e32 v107, 16, v107
	v_mul_f32_e32 v107, v16, v107
	v_fmac_f32_e32 v107, v14, v108
	v_fmac_f32_e32 v107, v17, v32
	v_add_f32_e32 v107, v12, v107
	v_fma_f32 v27, v42, v8, v64
	v_mul_f32_e32 v70, v27, v107
	v_lshlrev_b32_e32 v33, 16, v33
	v_mul_f32_e32 v84, 0xbfb8aa3b, v33
	v_exp_f32_e32 v84, v84
	s_nop 0
	v_add_f32_e32 v84, 1.0, v84
	v_div_scale_f32 v71, s[74:75], v84, v84, v33
	v_rcp_f32_e32 v82, v71
	s_nop 0
	v_fma_f32 v92, -v71, v82, 1.0
	v_fmac_f32_e32 v82, v92, v82
	v_div_scale_f32 v88, vcc, v33, v84, v33
	v_mul_f32_e32 v90, v88, v82
	v_fma_f32 v92, -v71, v90, v88
	v_fmac_f32_e32 v90, v92, v82
	v_fma_f32 v71, -v71, v90, v88
	v_div_fmas_f32 v71, v71, v82, v90
	v_div_fixup_f32 v33, v71, v84, v33
	v_mul_f32_e32 v70, v70, v33
	v_lshlrev_b32_e32 v34, 16, v34
	v_lshlrev_b32_e32 v79, 16, v79
	v_lshlrev_b32_e32 v78, 16, v78
	v_mul_f32_e32 v78, v16, v78
	v_fmac_f32_e32 v78, v14, v34
	v_fmac_f32_e32 v78, v17, v79
	v_add_f32_e32 v78, v12, v78
	v_fma_f32 v27, v44, v8, v65
	v_mul_f32_e32 v110, v27, v78
	v_lshlrev_b32_e32 v76, 16, v76
	v_mul_f32_e32 v84, 0xbfb8aa3b, v76
	v_exp_f32_e32 v84, v84
	s_nop 0
	v_add_f32_e32 v84, 1.0, v84
	v_div_scale_f32 v71, s[74:75], v84, v84, v76
	v_rcp_f32_e32 v82, v71
	s_nop 0
	v_fma_f32 v92, -v71, v82, 1.0
	v_fmac_f32_e32 v82, v92, v82
	v_div_scale_f32 v88, vcc, v76, v84, v76
	v_mul_f32_e32 v90, v88, v82
	v_fma_f32 v92, -v71, v90, v88
	v_fmac_f32_e32 v90, v92, v82
	v_fma_f32 v71, -v71, v90, v88
	v_div_fmas_f32 v71, v71, v82, v90
	v_div_fixup_f32 v76, v71, v84, v76
	v_mul_f32_e32 v110, v110, v76
	v_cvt_pk_bf16_f32 v70, v70, v110
	v_perm_b32 v110, v70, v205, s98
	v_perm_b32 v70, v70, v205, s99
	global_store_dword v26, v110, s[70:71] offset:-2
	global_store_dword v26, v70, s[18:19] offset:-2
	v_add_u32_e32 v109, 0x1000, v109
	global_load_ushort v9, v109, s[36:37] offset:-2
	global_load_ushort v11, v109, s[36:37]
	global_load_ushort v13, v109, s[36:37] offset:2
	global_load_ushort v15, v109, s[72:73] offset:-2
	global_load_ushort v81, v109, s[72:73]
	global_load_ushort v83, v109, s[72:73] offset:2
	global_load_ushort v85, v109, s[0:1]
	global_load_ushort v87, v109, s[4:5]
	global_load_ushort v89, v109, s[36:37] offset:1022
	global_load_ushort v91, v109, s[36:37] offset:1024
	global_load_ushort v93, v109, s[36:37] offset:1026
	global_load_ushort v94, v109, s[72:73] offset:1022
	global_load_ushort v95, v109, s[72:73] offset:1024
	global_load_ushort v96, v109, s[72:73] offset:1026
	global_load_ushort v97, v109, s[0:1] offset:1024
	global_load_ushort v98, v109, s[4:5] offset:1024
	global_load_ushort v99, v109, s[36:37] offset:2046
	global_load_ushort v100, v109, s[36:37] offset:2048
	global_load_ushort v101, v109, s[36:37] offset:2050
	global_load_ushort v102, v109, s[72:73] offset:2046
	global_load_ushort v103, v109, s[72:73] offset:2048
	global_load_ushort v104, v109, s[72:73] offset:2050
	global_load_ushort v105, v109, s[0:1] offset:2048
	global_load_ushort v106, v109, s[4:5] offset:2048
	global_load_ushort v107, v109, s[36:37] offset:3070
	global_load_ushort v108, v109, s[36:37] offset:3072
	global_load_ushort v32, v109, s[36:37] offset:3074
	global_load_ushort v78, v109, s[72:73] offset:3070
	global_load_ushort v34, v109, s[72:73] offset:3072
	global_load_ushort v79, v109, s[72:73] offset:3074
	global_load_ushort v33, v109, s[0:1] offset:3072
	global_load_ushort v76, v109, s[4:5] offset:3072
	s_waitcnt vmcnt(0)
	v_add_u32_e32 v26, 0x80000, v26
	v_lshlrev_b32_e32 v11, 16, v11
	v_lshlrev_b32_e32 v13, 16, v13
	v_lshlrev_b32_e32 v9, 16, v9
	v_mul_f32_e32 v9, v16, v9
	v_fmac_f32_e32 v9, v14, v11
	v_fmac_f32_e32 v9, v17, v13
	v_add_f32_e32 v9, v12, v9
	v_fma_f32 v27, v47, v8, v22
	v_mul_f32_e32 v70, v27, v9
	v_lshlrev_b32_e32 v85, 16, v85
	v_mul_f32_e32 v84, 0xbfb8aa3b, v85
	v_exp_f32_e32 v84, v84
	s_nop 0
	v_add_f32_e32 v84, 1.0, v84
	v_div_scale_f32 v71, s[74:75], v84, v84, v85
	v_rcp_f32_e32 v82, v71
	s_nop 0
	v_fma_f32 v92, -v71, v82, 1.0
	v_fmac_f32_e32 v82, v92, v82
	v_div_scale_f32 v88, vcc, v85, v84, v85
	v_mul_f32_e32 v90, v88, v82
	v_fma_f32 v92, -v71, v90, v88
	v_fmac_f32_e32 v90, v92, v82
	v_fma_f32 v71, -v71, v90, v88
	v_div_fmas_f32 v71, v71, v82, v90
	v_div_fixup_f32 v85, v71, v84, v85
	v_mul_f32_e32 v70, v70, v85
	v_lshlrev_b32_e32 v81, 16, v81
	v_lshlrev_b32_e32 v83, 16, v83
	v_lshlrev_b32_e32 v15, 16, v15
	v_mul_f32_e32 v15, v16, v15
	v_fmac_f32_e32 v15, v14, v81
	v_fmac_f32_e32 v15, v17, v83
	v_add_f32_e32 v15, v12, v15
	v_fma_f32 v27, v49, v8, v23
	v_mul_f32_e32 v110, v27, v15
	v_lshlrev_b32_e32 v87, 16, v87
	v_mul_f32_e32 v84, 0xbfb8aa3b, v87
	v_exp_f32_e32 v84, v84
	s_nop 0
	v_add_f32_e32 v84, 1.0, v84
	v_div_scale_f32 v71, s[74:75], v84, v84, v87
	v_rcp_f32_e32 v82, v71
	s_nop 0
	v_fma_f32 v92, -v71, v82, 1.0
	v_fmac_f32_e32 v82, v92, v82
	v_div_scale_f32 v88, vcc, v87, v84, v87
	v_mul_f32_e32 v90, v88, v82
	v_fma_f32 v92, -v71, v90, v88
	v_fmac_f32_e32 v90, v92, v82
	v_fma_f32 v71, -v71, v90, v88
	v_div_fmas_f32 v71, v71, v82, v90
	v_div_fixup_f32 v87, v71, v84, v87
	v_mul_f32_e32 v110, v110, v87
	v_cvt_pk_bf16_f32 v70, v70, v110
	v_perm_b32 v110, v70, v206, s98
	v_perm_b32 v70, v70, v206, s99
	global_store_dword v26, v110, s[70:71] offset:-2
	global_store_dword v26, v70, s[18:19] offset:-2
	v_add_u32_e32 v26, 0x80000, v26
	v_lshlrev_b32_e32 v91, 16, v91
	v_lshlrev_b32_e32 v93, 16, v93
	v_lshlrev_b32_e32 v89, 16, v89
	v_mul_f32_e32 v89, v16, v89
	v_fmac_f32_e32 v89, v14, v91
	v_fmac_f32_e32 v89, v17, v93
	v_add_f32_e32 v89, v12, v89
	v_fma_f32 v27, v46, v8, v24
	v_mul_f32_e32 v70, v27, v89
	v_lshlrev_b32_e32 v97, 16, v97
	v_mul_f32_e32 v84, 0xbfb8aa3b, v97
	v_exp_f32_e32 v84, v84
	s_nop 0
	v_add_f32_e32 v84, 1.0, v84
	v_div_scale_f32 v71, s[74:75], v84, v84, v97
	v_rcp_f32_e32 v82, v71
	s_nop 0
	v_fma_f32 v92, -v71, v82, 1.0
	v_fmac_f32_e32 v82, v92, v82
	v_div_scale_f32 v88, vcc, v97, v84, v97
	v_mul_f32_e32 v90, v88, v82
	v_fma_f32 v92, -v71, v90, v88
	v_fmac_f32_e32 v90, v92, v82
	v_fma_f32 v71, -v71, v90, v88
	v_div_fmas_f32 v71, v71, v82, v90
	v_div_fixup_f32 v97, v71, v84, v97
	v_mul_f32_e32 v70, v70, v97
	v_lshlrev_b32_e32 v95, 16, v95
	v_lshlrev_b32_e32 v96, 16, v96
	v_lshlrev_b32_e32 v94, 16, v94
	v_mul_f32_e32 v94, v16, v94
	v_fmac_f32_e32 v94, v14, v95
	v_fmac_f32_e32 v94, v17, v96
	v_add_f32_e32 v94, v12, v94
	v_fma_f32 v27, v48, v8, v25
	v_mul_f32_e32 v110, v27, v94
	v_lshlrev_b32_e32 v98, 16, v98
	v_mul_f32_e32 v84, 0xbfb8aa3b, v98
	v_exp_f32_e32 v84, v84
	s_nop 0
	v_add_f32_e32 v84, 1.0, v84
	v_div_scale_f32 v71, s[74:75], v84, v84, v98
	v_rcp_f32_e32 v82, v71
	s_nop 0
	v_fma_f32 v92, -v71, v82, 1.0
	v_fmac_f32_e32 v82, v92, v82
	v_div_scale_f32 v88, vcc, v98, v84, v98
	v_mul_f32_e32 v90, v88, v82
	v_fma_f32 v92, -v71, v90, v88
	v_fmac_f32_e32 v90, v92, v82
	v_fma_f32 v71, -v71, v90, v88
	v_div_fmas_f32 v71, v71, v82, v90
	v_div_fixup_f32 v98, v71, v84, v98
	v_mul_f32_e32 v110, v110, v98
	v_cvt_pk_bf16_f32 v70, v70, v110
	v_perm_b32 v110, v70, v207, s98
	v_perm_b32 v70, v70, v207, s99
	global_store_dword v26, v110, s[70:71] offset:-2
	global_store_dword v26, v70, s[18:19] offset:-2
	v_add_u32_e32 v26, 0x80000, v26
	v_lshlrev_b32_e32 v100, 16, v100
	v_lshlrev_b32_e32 v101, 16, v101
	v_lshlrev_b32_e32 v99, 16, v99
	v_mul_f32_e32 v99, v16, v99
	v_fmac_f32_e32 v99, v14, v100
	v_fmac_f32_e32 v99, v17, v101
	v_add_f32_e32 v99, v12, v99
	v_fma_f32 v27, v51, v8, v18
	v_mul_f32_e32 v70, v27, v99
	v_lshlrev_b32_e32 v105, 16, v105
	v_mul_f32_e32 v84, 0xbfb8aa3b, v105
	v_exp_f32_e32 v84, v84
	s_nop 0
	v_add_f32_e32 v84, 1.0, v84
	v_div_scale_f32 v71, s[74:75], v84, v84, v105
	v_rcp_f32_e32 v82, v71
	s_nop 0
	v_fma_f32 v92, -v71, v82, 1.0
	v_fmac_f32_e32 v82, v92, v82
	v_div_scale_f32 v88, vcc, v105, v84, v105
	v_mul_f32_e32 v90, v88, v82
	v_fma_f32 v92, -v71, v90, v88
	v_fmac_f32_e32 v90, v92, v82
	v_fma_f32 v71, -v71, v90, v88
	v_div_fmas_f32 v71, v71, v82, v90
	v_div_fixup_f32 v105, v71, v84, v105
	v_mul_f32_e32 v70, v70, v105
	v_lshlrev_b32_e32 v103, 16, v103
	v_lshlrev_b32_e32 v104, 16, v104
	v_lshlrev_b32_e32 v102, 16, v102
	v_mul_f32_e32 v102, v16, v102
	v_fmac_f32_e32 v102, v14, v103
	v_fmac_f32_e32 v102, v17, v104
	v_add_f32_e32 v102, v12, v102
	v_fma_f32 v27, v53, v8, v19
	v_mul_f32_e32 v110, v27, v102
	v_lshlrev_b32_e32 v106, 16, v106
	v_mul_f32_e32 v84, 0xbfb8aa3b, v106
	v_exp_f32_e32 v84, v84
	s_nop 0
	v_add_f32_e32 v84, 1.0, v84
	v_div_scale_f32 v71, s[74:75], v84, v84, v106
	v_rcp_f32_e32 v82, v71
	s_nop 0
	v_fma_f32 v92, -v71, v82, 1.0
	v_fmac_f32_e32 v82, v92, v82
	v_div_scale_f32 v88, vcc, v106, v84, v106
	v_mul_f32_e32 v90, v88, v82
	v_fma_f32 v92, -v71, v90, v88
	v_fmac_f32_e32 v90, v92, v82
	v_fma_f32 v71, -v71, v90, v88
	v_div_fmas_f32 v71, v71, v82, v90
	v_div_fixup_f32 v106, v71, v84, v106
	v_mul_f32_e32 v110, v110, v106
	v_cvt_pk_bf16_f32 v70, v70, v110
	v_perm_b32 v110, v70, v208, s98
	v_perm_b32 v70, v70, v208, s99
	global_store_dword v26, v110, s[70:71] offset:-2
	global_store_dword v26, v70, s[18:19] offset:-2
	v_add_u32_e32 v26, 0x80000, v26
	v_lshlrev_b32_e32 v108, 16, v108
	v_lshlrev_b32_e32 v32, 16, v32
	v_lshlrev_b32_e32 v107, 16, v107
	v_mul_f32_e32 v107, v16, v107
	v_fmac_f32_e32 v107, v14, v108
	v_fmac_f32_e32 v107, v17, v32
	v_add_f32_e32 v107, v12, v107
	v_fma_f32 v27, v50, v8, v20
	v_mul_f32_e32 v70, v27, v107
	v_lshlrev_b32_e32 v33, 16, v33
	v_mul_f32_e32 v84, 0xbfb8aa3b, v33
	v_exp_f32_e32 v84, v84
	s_nop 0
	v_add_f32_e32 v84, 1.0, v84
	v_div_scale_f32 v71, s[74:75], v84, v84, v33
	v_rcp_f32_e32 v82, v71
	s_nop 0
	v_fma_f32 v92, -v71, v82, 1.0
	v_fmac_f32_e32 v82, v92, v82
	v_div_scale_f32 v88, vcc, v33, v84, v33
	v_mul_f32_e32 v90, v88, v82
	v_fma_f32 v92, -v71, v90, v88
	v_fmac_f32_e32 v90, v92, v82
	v_fma_f32 v71, -v71, v90, v88
	v_div_fmas_f32 v71, v71, v82, v90
	v_div_fixup_f32 v33, v71, v84, v33
	v_mul_f32_e32 v70, v70, v33
	v_lshlrev_b32_e32 v34, 16, v34
	v_lshlrev_b32_e32 v79, 16, v79
	v_lshlrev_b32_e32 v78, 16, v78
	v_mul_f32_e32 v78, v16, v78
	v_fmac_f32_e32 v78, v14, v34
	v_fmac_f32_e32 v78, v17, v79
	v_add_f32_e32 v78, v12, v78
	v_fma_f32 v27, v52, v8, v21
	v_mul_f32_e32 v110, v27, v78
	v_lshlrev_b32_e32 v76, 16, v76
	v_mul_f32_e32 v84, 0xbfb8aa3b, v76
	v_exp_f32_e32 v84, v84
	s_nop 0
	v_add_f32_e32 v84, 1.0, v84
	v_div_scale_f32 v71, s[74:75], v84, v84, v76
	v_rcp_f32_e32 v82, v71
	s_nop 0
	v_fma_f32 v92, -v71, v82, 1.0
	v_fmac_f32_e32 v82, v92, v82
	v_div_scale_f32 v88, vcc, v76, v84, v76
	v_mul_f32_e32 v90, v88, v82
	v_fma_f32 v92, -v71, v90, v88
	v_fmac_f32_e32 v90, v92, v82
	v_fma_f32 v71, -v71, v90, v88
	v_div_fmas_f32 v71, v71, v82, v90
	v_div_fixup_f32 v76, v71, v84, v76
	v_mul_f32_e32 v110, v110, v76
	v_cvt_pk_bf16_f32 v70, v70, v110
	v_perm_b32 v110, v70, v209, s98
	v_perm_b32 v70, v70, v209, s99
	global_store_dword v26, v110, s[70:71] offset:-2
	global_store_dword v26, v70, s[18:19] offset:-2
	v_add_u32_e32 v52, 0x1e00, v10
	v_cmp_gt_i32_e32 vcc, 0x1fff, v52
	v_min_i32_e32 v52, 0x1ffe, v52
	v_lshlrev_b32_e32 v52, 1, v52
	s_nop 0
	v_cndmask_b32_e64 v21, 0, 1.0, vcc
	v_add_u32_e32 v109, 0x1000, v109
	global_load_ushort v9, v109, s[36:37] offset:-2
	global_load_ushort v11, v109, s[36:37]
	global_load_ushort v13, v109, s[36:37] offset:2
	global_load_ushort v15, v109, s[72:73] offset:-2
	global_load_ushort v81, v109, s[72:73]
	global_load_ushort v83, v109, s[72:73] offset:2
	global_load_ushort v85, v109, s[0:1]
	global_load_ushort v87, v109, s[4:5]
	global_load_ushort v89, v109, s[36:37] offset:1022
	global_load_ushort v91, v109, s[36:37] offset:1024
	global_load_ushort v93, v109, s[36:37] offset:1026
	global_load_ushort v94, v109, s[72:73] offset:1022
	global_load_ushort v95, v109, s[72:73] offset:1024
	global_load_ushort v96, v109, s[72:73] offset:1026
	global_load_ushort v97, v109, s[0:1] offset:1024
	global_load_ushort v98, v109, s[4:5] offset:1024
	global_load_ushort v99, v109, s[36:37] offset:2046
	global_load_ushort v100, v109, s[36:37] offset:2048
	global_load_ushort v101, v109, s[36:37] offset:2050
	global_load_ushort v102, v109, s[72:73] offset:2046
	global_load_ushort v103, v109, s[72:73] offset:2048
	global_load_ushort v104, v109, s[72:73] offset:2050
	global_load_ushort v105, v109, s[0:1] offset:2048
	global_load_ushort v106, v109, s[4:5] offset:2048
	global_load_ushort v107, v109, s[36:37] offset:3070
	global_load_ushort v108, v109, s[36:37] offset:3072
	global_load_ushort v32, v52, s[36:37] offset:2
	global_load_ushort v78, v109, s[72:73] offset:3070
	global_load_ushort v34, v109, s[72:73] offset:3072
	global_load_ushort v79, v52, s[72:73] offset:2
	global_load_ushort v33, v109, s[0:1] offset:3072
	global_load_ushort v76, v109, s[4:5] offset:3072
	s_waitcnt vmcnt(0)
	v_add_u32_e32 v26, 0x80000, v26
	v_lshlrev_b32_e32 v11, 16, v11
	v_lshlrev_b32_e32 v13, 16, v13
	v_lshlrev_b32_e32 v9, 16, v9
	v_mul_f32_e32 v9, v16, v9
	v_fmac_f32_e32 v9, v14, v11
	v_fmac_f32_e32 v9, v17, v13
	v_add_f32_e32 v9, v12, v9
	v_fma_f32 v27, v55, v8, v4
	v_mul_f32_e32 v70, v27, v9
	v_lshlrev_b32_e32 v85, 16, v85
	v_mul_f32_e32 v84, 0xbfb8aa3b, v85
	v_exp_f32_e32 v84, v84
	s_nop 0
	v_add_f32_e32 v84, 1.0, v84
	v_div_scale_f32 v71, s[74:75], v84, v84, v85
	v_rcp_f32_e32 v82, v71
	s_nop 0
	v_fma_f32 v92, -v71, v82, 1.0
	v_fmac_f32_e32 v82, v92, v82
	v_div_scale_f32 v88, vcc, v85, v84, v85
	v_mul_f32_e32 v90, v88, v82
	v_fma_f32 v92, -v71, v90, v88
	v_fmac_f32_e32 v90, v92, v82
	v_fma_f32 v71, -v71, v90, v88
	v_div_fmas_f32 v71, v71, v82, v90
	v_div_fixup_f32 v85, v71, v84, v85
	v_mul_f32_e32 v70, v70, v85
	v_lshlrev_b32_e32 v81, 16, v81
	v_lshlrev_b32_e32 v83, 16, v83
	v_lshlrev_b32_e32 v15, 16, v15
	v_mul_f32_e32 v15, v16, v15
	v_fmac_f32_e32 v15, v14, v81
	v_fmac_f32_e32 v15, v17, v83
	v_add_f32_e32 v15, v12, v15
	v_fma_f32 v27, v57, v8, v5
	v_mul_f32_e32 v110, v27, v15
	v_lshlrev_b32_e32 v87, 16, v87
	v_mul_f32_e32 v84, 0xbfb8aa3b, v87
	v_exp_f32_e32 v84, v84
	s_nop 0
	v_add_f32_e32 v84, 1.0, v84
	v_div_scale_f32 v71, s[74:75], v84, v84, v87
	v_rcp_f32_e32 v82, v71
	s_nop 0
	v_fma_f32 v92, -v71, v82, 1.0
	v_fmac_f32_e32 v82, v92, v82
	v_div_scale_f32 v88, vcc, v87, v84, v87
	v_mul_f32_e32 v90, v88, v82
	v_fma_f32 v92, -v71, v90, v88
	v_fmac_f32_e32 v90, v92, v82
	v_fma_f32 v71, -v71, v90, v88
	v_div_fmas_f32 v71, v71, v82, v90
	v_div_fixup_f32 v87, v71, v84, v87
	v_mul_f32_e32 v110, v110, v87
	v_cvt_pk_bf16_f32 v70, v70, v110
	v_perm_b32 v110, v70, v210, s98
	v_perm_b32 v70, v70, v210, s99
	global_store_dword v26, v110, s[70:71] offset:-2
	global_store_dword v26, v70, s[18:19] offset:-2
	v_add_u32_e32 v26, 0x80000, v26
	v_lshlrev_b32_e32 v91, 16, v91
	v_lshlrev_b32_e32 v93, 16, v93
	v_lshlrev_b32_e32 v89, 16, v89
	v_mul_f32_e32 v89, v16, v89
	v_fmac_f32_e32 v89, v14, v91
	v_fmac_f32_e32 v89, v17, v93
	v_add_f32_e32 v89, v12, v89
	v_fma_f32 v27, v54, v8, v6
	v_mul_f32_e32 v70, v27, v89
	v_lshlrev_b32_e32 v97, 16, v97
	v_mul_f32_e32 v84, 0xbfb8aa3b, v97
	v_exp_f32_e32 v84, v84
	s_nop 0
	v_add_f32_e32 v84, 1.0, v84
	v_div_scale_f32 v71, s[74:75], v84, v84, v97
	v_rcp_f32_e32 v82, v71
	s_nop 0
	v_fma_f32 v92, -v71, v82, 1.0
	v_fmac_f32_e32 v82, v92, v82
	v_div_scale_f32 v88, vcc, v97, v84, v97
	v_mul_f32_e32 v90, v88, v82
	v_fma_f32 v92, -v71, v90, v88
	v_fmac_f32_e32 v90, v92, v82
	v_fma_f32 v71, -v71, v90, v88
	v_div_fmas_f32 v71, v71, v82, v90
	v_div_fixup_f32 v97, v71, v84, v97
	v_mul_f32_e32 v70, v70, v97
	v_lshlrev_b32_e32 v95, 16, v95
	v_lshlrev_b32_e32 v96, 16, v96
	v_lshlrev_b32_e32 v94, 16, v94
	v_mul_f32_e32 v94, v16, v94
	v_fmac_f32_e32 v94, v14, v95
	v_fmac_f32_e32 v94, v17, v96
	v_add_f32_e32 v94, v12, v94
	v_fma_f32 v27, v56, v8, v7
	v_mul_f32_e32 v110, v27, v94
	v_lshlrev_b32_e32 v98, 16, v98
	v_mul_f32_e32 v84, 0xbfb8aa3b, v98
	v_exp_f32_e32 v84, v84
	s_nop 0
	v_add_f32_e32 v84, 1.0, v84
	v_div_scale_f32 v71, s[74:75], v84, v84, v98
	v_rcp_f32_e32 v82, v71
	s_nop 0
	v_fma_f32 v92, -v71, v82, 1.0
	v_fmac_f32_e32 v82, v92, v82
	v_div_scale_f32 v88, vcc, v98, v84, v98
	v_mul_f32_e32 v90, v88, v82
	v_fma_f32 v92, -v71, v90, v88
	v_fmac_f32_e32 v90, v92, v82
	v_fma_f32 v71, -v71, v90, v88
	v_div_fmas_f32 v71, v71, v82, v90
	v_div_fixup_f32 v98, v71, v84, v98
	v_mul_f32_e32 v110, v110, v98
	v_cvt_pk_bf16_f32 v70, v70, v110
	v_perm_b32 v110, v70, v211, s98
	v_perm_b32 v70, v70, v211, s99
	global_store_dword v26, v110, s[70:71] offset:-2
	global_store_dword v26, v70, s[18:19] offset:-2
	v_add_u32_e32 v26, 0x80000, v26
	v_lshlrev_b32_e32 v100, 16, v100
	v_lshlrev_b32_e32 v101, 16, v101
	v_lshlrev_b32_e32 v99, 16, v99
	v_mul_f32_e32 v99, v16, v99
	v_fmac_f32_e32 v99, v14, v100
	v_fmac_f32_e32 v99, v17, v101
	v_add_f32_e32 v99, v12, v99
	v_fma_f32 v27, v59, v8, v0
	v_mul_f32_e32 v70, v27, v99
	v_lshlrev_b32_e32 v105, 16, v105
	v_mul_f32_e32 v84, 0xbfb8aa3b, v105
	v_exp_f32_e32 v84, v84
	s_nop 0
	v_add_f32_e32 v84, 1.0, v84
	v_div_scale_f32 v71, s[74:75], v84, v84, v105
	v_rcp_f32_e32 v82, v71
	s_nop 0
	v_fma_f32 v92, -v71, v82, 1.0
	v_fmac_f32_e32 v82, v92, v82
	v_div_scale_f32 v88, vcc, v105, v84, v105
	v_mul_f32_e32 v90, v88, v82
	v_fma_f32 v92, -v71, v90, v88
	v_fmac_f32_e32 v90, v92, v82
	v_fma_f32 v71, -v71, v90, v88
	v_div_fmas_f32 v71, v71, v82, v90
	v_div_fixup_f32 v105, v71, v84, v105
	v_mul_f32_e32 v70, v70, v105
	v_lshlrev_b32_e32 v103, 16, v103
	v_lshlrev_b32_e32 v104, 16, v104
	v_lshlrev_b32_e32 v102, 16, v102
	v_mul_f32_e32 v102, v16, v102
	v_fmac_f32_e32 v102, v14, v103
	v_fmac_f32_e32 v102, v17, v104
	v_add_f32_e32 v102, v12, v102
	v_fma_f32 v27, v61, v8, v1
	v_mul_f32_e32 v110, v27, v102
	v_lshlrev_b32_e32 v106, 16, v106
	v_mul_f32_e32 v84, 0xbfb8aa3b, v106
	v_exp_f32_e32 v84, v84
	s_nop 0
	v_add_f32_e32 v84, 1.0, v84
	v_div_scale_f32 v71, s[74:75], v84, v84, v106
	v_rcp_f32_e32 v82, v71
	s_nop 0
	v_fma_f32 v92, -v71, v82, 1.0
	v_fmac_f32_e32 v82, v92, v82
	v_div_scale_f32 v88, vcc, v106, v84, v106
	v_mul_f32_e32 v90, v88, v82
	v_fma_f32 v92, -v71, v90, v88
	v_fmac_f32_e32 v90, v92, v82
	v_fma_f32 v71, -v71, v90, v88
	v_div_fmas_f32 v71, v71, v82, v90
	v_div_fixup_f32 v106, v71, v84, v106
	v_mul_f32_e32 v110, v110, v106
	v_cvt_pk_bf16_f32 v70, v70, v110
	v_perm_b32 v110, v70, v212, s98
	v_perm_b32 v70, v70, v212, s99
	global_store_dword v26, v110, s[70:71] offset:-2
	global_store_dword v26, v70, s[18:19] offset:-2
	v_add_u32_e32 v26, 0x80000, v26
	v_lshlrev_b32_e32 v108, 16, v108
	v_lshlrev_b32_e32 v32, 16, v32
	v_lshlrev_b32_e32 v107, 16, v107
	v_mul_f32_e32 v107, v16, v107
	v_mul_f32_e32 v32, v21, v32
	v_fmac_f32_e32 v107, v14, v108
	v_fmac_f32_e32 v107, v17, v32
	v_add_f32_e32 v107, v12, v107
	v_fma_f32 v27, v58, v8, v2
	v_mul_f32_e32 v70, v27, v107
	v_lshlrev_b32_e32 v33, 16, v33
	v_mul_f32_e32 v84, 0xbfb8aa3b, v33
	v_exp_f32_e32 v84, v84
	s_nop 0
	v_add_f32_e32 v84, 1.0, v84
	v_div_scale_f32 v71, s[74:75], v84, v84, v33
	v_rcp_f32_e32 v82, v71
	s_nop 0
	v_fma_f32 v92, -v71, v82, 1.0
	v_fmac_f32_e32 v82, v92, v82
	v_div_scale_f32 v88, vcc, v33, v84, v33
	v_mul_f32_e32 v90, v88, v82
	v_fma_f32 v92, -v71, v90, v88
	v_fmac_f32_e32 v90, v92, v82
	v_fma_f32 v71, -v71, v90, v88
	v_div_fmas_f32 v71, v71, v82, v90
	v_div_fixup_f32 v33, v71, v84, v33
	v_mul_f32_e32 v70, v70, v33
	v_lshlrev_b32_e32 v34, 16, v34
	v_lshlrev_b32_e32 v79, 16, v79
	v_lshlrev_b32_e32 v78, 16, v78
	v_mul_f32_e32 v78, v16, v78
	v_mul_f32_e32 v79, v21, v79
	v_fmac_f32_e32 v78, v14, v34
	v_fmac_f32_e32 v78, v17, v79
	v_add_f32_e32 v78, v12, v78
	v_fma_f32 v27, v60, v8, v3
	v_mul_f32_e32 v110, v27, v78
	v_lshlrev_b32_e32 v76, 16, v76
	v_mul_f32_e32 v84, 0xbfb8aa3b, v76
	v_exp_f32_e32 v84, v84
	s_nop 0
	v_add_f32_e32 v84, 1.0, v84
	v_div_scale_f32 v71, s[74:75], v84, v84, v76
	v_rcp_f32_e32 v82, v71
	s_nop 0
	v_fma_f32 v92, -v71, v82, 1.0
	v_fmac_f32_e32 v82, v92, v82
	v_div_scale_f32 v88, vcc, v76, v84, v76
	v_mul_f32_e32 v90, v88, v82
	v_fma_f32 v92, -v71, v90, v88
	v_fmac_f32_e32 v90, v92, v82
	v_fma_f32 v71, -v71, v90, v88
	v_div_fmas_f32 v71, v71, v82, v90
	v_div_fixup_f32 v76, v71, v84, v76
	v_mul_f32_e32 v110, v110, v76
	v_cvt_pk_bf16_f32 v70, v70, v110
	v_perm_b32 v110, v70, v213, s98
	v_perm_b32 v70, v70, v213, s99
	global_store_dword v26, v110, s[70:71] offset:-2
	global_store_dword v26, v70, s[18:19] offset:-2
.Lhy_ep1_done_L1:
	s_mov_b64 s[74:75], 0
